# FFT twiddle code: (-s,s) pairs built by v_xor+v_mov folded into op_sel/neg modifiers of the packed-f32 consumers (160 sites)
# baseline (speedup 1.0000x reference)
.LBB0_134:
	global_load_dword v6, v[22:23], off
	v_lshrrev_b32_e32 v26, 2, v11
	v_add_u32_e32 v25, 0x200, v25
	v_and_b32_e32 v26, 0x3ffffff8, v26
	v_cmp_lt_u32_e32 vcc, s34, v25
	v_add_u32_e32 v11, 8, v11
	v_lshl_add_u64 v[22:23], v[22:23], 0, s[26:27]
	v_add_u32_e32 v26, v24, v26
	v_add_u32_e32 v24, 64, v24
	s_or_b64 s[62:63], vcc, s[62:63]
	s_waitcnt vmcnt(0)
	ds_write_b64 v26, v[6:7]
	s_andn2_b64 exec, exec, s[62:63]
	s_cbranch_execnz .LBB0_134
	s_or_b64 exec, exec, s[62:63]
	v_mov_b32_e32 v6, v62
	s_waitcnt lgkmcnt(0)
	s_barrier
	s_mov_b32 s43, s40
	v_and_b32_e32 v11, 15, v6
	v_cvt_f32_ubyte0_e32 v22, v11
	v_mul_f32_e32 v23, 0x3b800000, v22
	v_sin_f32_e32 v22, v23
	v_cos_f32_e32 v24, v23
	v_lshlrev_b32_e32 v6, 4, v6
	v_and_b32_e32 v6, 0xffffff00, v6
	v_xor_b32_e32 v25, 0x80000000, v22
	v_mov_b32_e32 v23, v25
	v_pk_mul_f32 v[26:27], v[24:25], v[22:23] op_sel:[1,0] op_sel_hi:[0,1]
	v_pk_fma_f32 v[26:27], v[24:25], v[24:25], v[26:27] op_sel_hi:[1,0,1]
	v_lshlrev_b32_e32 v11, 3, v11
	v_pk_mul_f32 v[30:31], v[26:27], v[26:27] op_sel:[1,1] op_sel_hi:[0,1] neg_lo:[0,1]
	v_pk_fma_f32 v[30:31], v[26:27], v[26:27], v[30:31] op_sel_hi:[1,0,1]
	v_pk_mul_f32 v[28:29], v[22:23], v[26:27] op_sel:[0,1] op_sel_hi:[1,0]
	v_pk_mul_f32 v[50:51], v[30:31], v[30:31] op_sel:[1,1] op_sel_hi:[0,1] neg_lo:[0,1]
	v_pk_fma_f32 v[50:51], v[30:31], v[30:31], v[50:51] op_sel_hi:[1,0,1]
	v_pk_mul_f32 v[36:37], v[22:23], v[30:31] op_sel:[0,1] op_sel_hi:[1,0]
	v_pk_mul_f32 v[70:71], v[30:31], v[50:51] op_sel:[1,1] op_sel_hi:[1,0] neg_lo:[1,0]
	v_pk_mul_f32 v[54:55], v[22:23], v[50:51] op_sel:[0,1] op_sel_hi:[1,0]
	v_pk_fma_f32 v[70:71], v[30:31], v[50:51], v[70:71] op_sel_hi:[0,1,1]
	v_pk_mul_f32 v[74:75], v[22:23], v[70:71] op_sel:[0,1] op_sel_hi:[1,0]
	v_pk_fma_f32 v[28:29], v[24:25], v[26:27], v[28:29] op_sel_hi:[0,1,1]
	v_pk_fma_f32 v[36:37], v[24:25], v[30:31], v[36:37] op_sel_hi:[0,1,1]
	v_pk_fma_f32 v[54:55], v[24:25], v[50:51], v[54:55] op_sel_hi:[0,1,1]
	v_pk_fma_f32 v[74:75], v[24:25], v[70:71], v[74:75] op_sel_hi:[0,1,1]
	v_lshlrev_b32_e32 v25, 3, v6
	v_add3_u32 v11, 0, v11, v25
	v_ashrrev_i32_e32 v25, 2, v6
	v_add_u32_e32 v25, v11, v25
	ds_read2_b64 v[92:95], v25 offset1:16
	ds_read2_b64 v[96:99], v25 offset0:33 offset1:49
	ds_read2_b64 v[100:103], v25 offset0:66 offset1:82
	ds_read2_b64 v[104:107], v25 offset0:132 offset1:148
	ds_read2_b64 v[108:111], v25 offset0:99 offset1:115
	ds_read2_b64 v[112:115], v25 offset0:165 offset1:181
	ds_read2_b64 v[116:119], v25 offset0:198 offset1:214
	ds_read2_b64 v[120:123], v25 offset0:231 offset1:247
	s_waitcnt lgkmcnt(4)
	v_pk_add_f32 v[124:125], v[92:93], v[104:105]
	v_pk_add_f32 v[92:93], v[92:93], v[104:105] neg_lo:[0,1] neg_hi:[0,1]
	v_pk_add_f32 v[104:105], v[94:95], v[106:107]
	v_pk_add_f32 v[94:95], v[94:95], v[106:107] neg_lo:[0,1] neg_hi:[0,1]
	s_mov_b32 s45, s36
	v_pk_mul_f32 v[106:107], v[94:95], s[38:39]
	s_waitcnt lgkmcnt(1)
	v_pk_add_f32 v[126:127], v[102:103], v[118:119]
	v_pk_fma_f32 v[94:95], v[94:95], s[36:37], v[106:107] op_sel:[0,0,1] op_sel_hi:[1,0,0]
	v_pk_add_f32 v[106:107], v[96:97], v[112:113]
	v_pk_add_f32 v[96:97], v[96:97], v[112:113] neg_lo:[0,1] neg_hi:[0,1]
	v_pk_add_f32 v[102:103], v[102:103], v[118:119] neg_lo:[0,1] neg_hi:[0,1]
	v_pk_mul_f32 v[112:113], v[96:97], s[42:43]
	s_mov_b32 s62, s39
	v_pk_mul_f32 v[118:119], v[102:103], s[44:45]
	v_pk_fma_f32 v[96:97], v[96:97], s[40:41], v[112:113] op_sel:[0,0,1] op_sel_hi:[1,0,0]
	v_pk_add_f32 v[112:113], v[98:99], v[114:115]
	v_pk_add_f32 v[98:99], v[98:99], v[114:115] neg_lo:[0,1] neg_hi:[0,1]
	v_pk_fma_f32 v[102:103], v[102:103], s[62:63], v[118:119] op_sel:[0,0,1] op_sel_hi:[1,0,0] neg_lo:[1,0,0] neg_hi:[1,0,0]
	s_waitcnt lgkmcnt(0)
	v_pk_add_f32 v[118:119], v[108:109], v[120:121]
	v_pk_add_f32 v[108:109], v[108:109], v[120:121] neg_lo:[0,1] neg_hi:[0,1]
	v_pk_mul_f32 v[114:115], v[98:99], s[44:45]
	v_pk_mul_f32 v[120:121], v[108:109], s[42:43]
	v_pk_fma_f32 v[98:99], v[98:99], s[62:63], v[114:115] op_sel:[0,0,1] op_sel_hi:[1,0,0]
	v_pk_add_f32 v[114:115], v[100:101], v[116:117]
	v_pk_add_f32 v[116:117], v[100:101], v[116:117] neg_lo:[0,1] neg_hi:[0,1]
	v_pk_fma_f32 v[108:109], v[108:109], s[40:41], v[120:121] op_sel:[0,0,1] op_sel_hi:[1,0,0] neg_lo:[1,0,0] neg_hi:[1,0,0]
	v_pk_add_f32 v[120:121], v[110:111], v[122:123]
	v_pk_add_f32 v[110:111], v[110:111], v[122:123] neg_lo:[0,1] neg_hi:[0,1]
	v_pk_mul_f32 v[122:123], v[110:111], s[38:39]
	v_pk_fma_f32 v[110:111], v[110:111], s[36:37], v[122:123] op_sel:[0,0,1] op_sel_hi:[1,0,0] neg_lo:[1,0,0] neg_hi:[1,0,0]
	v_pk_add_f32 v[122:123], v[124:125], v[114:115]
	v_pk_add_f32 v[114:115], v[124:125], v[114:115] neg_lo:[0,1] neg_hi:[0,1]
	v_pk_add_f32 v[124:125], v[104:105], v[126:127]
	v_pk_add_f32 v[104:105], v[104:105], v[126:127] neg_lo:[0,1] neg_hi:[0,1]
	v_pk_add_f32 v[128:129], v[112:113], v[120:121]
	v_pk_add_f32 v[112:113], v[112:113], v[120:121] neg_lo:[0,1] neg_hi:[0,1]
	v_pk_add_f32 v[100:101], v[92:93], v[116:117] op_sel:[0,1] op_sel_hi:[1,0] neg_hi:[0,1]
	v_pk_add_f32 v[92:93], v[92:93], v[116:117] op_sel:[0,1] op_sel_hi:[1,0] neg_lo:[0,1]
	v_pk_add_f32 v[116:117], v[94:95], v[102:103]
	v_pk_add_f32 v[94:95], v[94:95], v[102:103] neg_lo:[0,1] neg_hi:[0,1]
	v_pk_mul_f32 v[126:127], v[104:105], s[42:43]
	v_pk_mul_f32 v[120:121], v[112:113], s[42:43]
	v_pk_mul_f32 v[102:103], v[94:95], s[42:43]
	v_pk_fma_f32 v[104:105], v[104:105], s[40:41], v[126:127] op_sel:[0,0,1] op_sel_hi:[1,0,0]
	v_pk_add_f32 v[126:127], v[106:107], v[118:119]
	v_pk_add_f32 v[118:119], v[106:107], v[118:119] neg_lo:[0,1] neg_hi:[0,1]
	v_pk_fma_f32 v[112:113], v[112:113], s[40:41], v[120:121] op_sel:[0,0,1] op_sel_hi:[1,0,0] neg_lo:[1,0,0] neg_hi:[1,0,0]
	v_pk_fma_f32 v[94:95], v[94:95], s[40:41], v[102:103] op_sel:[0,0,1] op_sel_hi:[1,0,0]
	v_pk_add_f32 v[102:103], v[96:97], v[108:109]
	v_pk_add_f32 v[120:121], v[98:99], v[110:111]
	v_pk_add_f32 v[98:99], v[98:99], v[110:111] neg_lo:[0,1] neg_hi:[0,1]
	v_pk_add_f32 v[96:97], v[96:97], v[108:109] neg_lo:[0,1] neg_hi:[0,1]
	v_pk_mul_f32 v[110:111], v[98:99], s[42:43]
	v_pk_add_f32 v[130:131], v[100:101], v[102:103]
	v_pk_add_f32 v[100:101], v[100:101], v[102:103] neg_lo:[0,1] neg_hi:[0,1]
	v_pk_add_f32 v[102:103], v[116:117], v[120:121]
	v_pk_add_f32 v[120:121], v[116:117], v[120:121] neg_lo:[0,1] neg_hi:[0,1]
	v_pk_mul_f32 v[42:43], v[26:27], v[30:31] op_sel:[1,1] op_sel_hi:[1,0] neg_lo:[1,0]
	v_xor_b32_e32 v109, 0x80000000, v96
	v_pk_fma_f32 v[98:99], v[98:99], s[40:41], v[110:111] op_sel:[0,0,1] op_sel_hi:[1,0,0] neg_lo:[1,0,0] neg_hi:[1,0,0]
	v_pk_add_f32 v[106:107], v[114:115], v[118:119] op_sel:[0,1] op_sel_hi:[1,0] neg_hi:[0,1]
	v_pk_add_f32 v[114:115], v[114:115], v[118:119] op_sel:[0,1] op_sel_hi:[1,0] neg_lo:[0,1]
	v_pk_add_f32 v[118:119], v[104:105], v[112:113]
	v_pk_add_f32 v[112:113], v[104:105], v[112:113] neg_lo:[0,1] neg_hi:[0,1]
	v_mov_b32_e32 v108, v97
	v_pk_fma_f32 v[42:43], v[26:27], v[30:31], v[42:43] op_sel_hi:[0,1,1]
	v_pk_mul_f32 v[46:47], v[30:31], v[28:29] op_sel:[1,1] op_sel_hi:[0,1] neg_lo:[0,1]
	v_pk_add_f32 v[96:97], v[92:93], v[108:109]
	v_pk_add_f32 v[92:93], v[92:93], v[108:109] neg_lo:[0,1] neg_hi:[0,1]
	v_pk_add_f32 v[108:109], v[94:95], v[98:99]
	v_pk_add_f32 v[98:99], v[94:95], v[98:99] neg_lo:[0,1] neg_hi:[0,1]
	v_pk_add_f32 v[116:117], v[100:101], v[120:121] op_sel:[0,1] op_sel_hi:[1,0] neg_hi:[0,1]
	v_pk_fma_f32 v[46:47], v[30:31], v[28:29], v[46:47] op_sel_hi:[1,0,1]
	v_pk_add_f32 v[104:105], v[114:115], v[112:113] op_sel:[0,1] op_sel_hi:[1,0] neg_hi:[0,1]
	v_pk_add_f32 v[100:101], v[100:101], v[120:121] op_sel:[0,1] op_sel_hi:[1,0] neg_lo:[0,1]
	v_pk_mul_f32 v[120:121], v[36:37], v[116:117] op_sel:[1,1] op_sel_hi:[1,0] neg_lo:[1,0]
	v_pk_add_f32 v[110:111], v[122:123], v[126:127]
	v_pk_add_f32 v[122:123], v[122:123], v[126:127] neg_lo:[0,1] neg_hi:[0,1]
	v_pk_add_f32 v[126:127], v[124:125], v[128:129]
	v_pk_add_f32 v[94:95], v[92:93], v[98:99] op_sel:[0,1] op_sel_hi:[1,0] neg_hi:[0,1]
	v_pk_fma_f32 v[116:117], v[36:37], v[116:117], v[120:121] op_sel_hi:[0,1,1]
	v_pk_mul_f32 v[120:121], v[42:43], v[104:105] op_sel:[1,1] op_sel_hi:[1,0] neg_lo:[1,0]
	v_pk_mul_f32 v[58:59], v[26:27], v[50:51] op_sel:[1,1] op_sel_hi:[1,0] neg_lo:[1,0]
	v_pk_add_f32 v[132:133], v[110:111], v[126:127]
	v_pk_add_f32 v[110:111], v[110:111], v[126:127] neg_lo:[0,1] neg_hi:[0,1]
	v_pk_fma_f32 v[104:105], v[42:43], v[104:105], v[120:121] op_sel_hi:[0,1,1]
	v_pk_mul_f32 v[120:121], v[46:47], v[94:95] op_sel:[1,1] op_sel_hi:[1,0] neg_lo:[1,0]
	v_pk_fma_f32 v[58:59], v[26:27], v[50:51], v[58:59] op_sel_hi:[0,1,1]
	v_pk_mul_f32 v[66:67], v[28:29], v[50:51] op_sel:[1,1] op_sel_hi:[1,0] neg_lo:[1,0]
	v_pk_add_f32 v[112:113], v[114:115], v[112:113] op_sel:[0,1] op_sel_hi:[1,0] neg_lo:[0,1]
	v_pk_add_f32 v[114:115], v[130:131], v[102:103]
	v_pk_add_f32 v[102:103], v[130:131], v[102:103] neg_lo:[0,1] neg_hi:[0,1]
	v_pk_fma_f32 v[94:95], v[46:47], v[94:95], v[120:121] op_sel_hi:[0,1,1]
	v_pk_mul_f32 v[120:121], v[50:51], v[110:111] op_sel:[1,1] op_sel_hi:[1,0] neg_lo:[1,0]
	v_pk_fma_f32 v[66:67], v[28:29], v[50:51], v[66:67] op_sel_hi:[0,1,1]
	v_pk_add_f32 v[128:129], v[124:125], v[128:129] neg_lo:[0,1] neg_hi:[0,1]
	v_pk_add_f32 v[126:127], v[106:107], v[118:119]
	v_pk_add_f32 v[106:107], v[106:107], v[118:119] neg_lo:[0,1] neg_hi:[0,1]
	v_pk_fma_f32 v[110:111], v[50:51], v[110:111], v[120:121] op_sel_hi:[0,1,1]
	v_pk_mul_f32 v[120:121], v[54:55], v[102:103] op_sel:[1,1] op_sel_hi:[1,0] neg_lo:[1,0]
	v_xor_b32_e32 v68, 0x80000000, v67
	v_mov_b32_e32 v69, v67
	v_pk_add_f32 v[118:119], v[96:97], v[108:109]
	v_pk_add_f32 v[96:97], v[96:97], v[108:109] neg_lo:[0,1] neg_hi:[0,1]
	v_pk_fma_f32 v[102:103], v[54:55], v[102:103], v[120:121] op_sel_hi:[0,1,1]
	v_pk_mul_f32 v[120:121], v[58:59], v[106:107] op_sel:[1,1] op_sel_hi:[1,0] neg_lo:[1,0]
	v_xor_b32_e32 v72, 0x80000000, v71
	v_mov_b32_e32 v73, v71
	v_pk_mul_f32 v[78:79], v[26:27], v[70:71] op_sel:[1,1] op_sel_hi:[1,0] neg_lo:[1,0]
	v_pk_add_f32 v[124:125], v[122:123], v[128:129] op_sel:[0,1] op_sel_hi:[1,0] neg_hi:[0,1]
	v_pk_add_f32 v[122:123], v[122:123], v[128:129] op_sel:[0,1] op_sel_hi:[1,0] neg_lo:[0,1]
	v_pk_fma_f32 v[106:107], v[58:59], v[106:107], v[120:121] op_sel_hi:[0,1,1]
	v_pk_mul_f32 v[120:121], v[68:69], v[96:97] op_sel:[0,1] op_sel_hi:[1,0]
	v_xor_b32_e32 v76, 0x80000000, v75
	v_mov_b32_e32 v77, v75
	v_pk_fma_f32 v[78:79], v[26:27], v[70:71], v[78:79] op_sel_hi:[0,1,1]
	v_pk_mul_f32 v[82:83], v[28:29], v[70:71] op_sel:[1,1] op_sel_hi:[1,0] neg_lo:[1,0]
	v_pk_fma_f32 v[96:97], v[66:67], v[96:97], v[120:121] op_sel_hi:[0,1,1]
	v_pk_mul_f32 v[120:121], v[72:73], v[122:123] op_sel:[0,1] op_sel_hi:[1,0]
	v_xor_b32_e32 v80, 0x80000000, v79
	v_mov_b32_e32 v81, v79
	v_pk_fma_f32 v[82:83], v[28:29], v[70:71], v[82:83] op_sel_hi:[0,1,1]
	v_pk_add_f32 v[92:93], v[92:93], v[98:99] op_sel:[0,1] op_sel_hi:[1,0] neg_lo:[0,1]
	v_pk_mul_f32 v[98:99], v[22:23], v[114:115] op_sel:[0,1] op_sel_hi:[1,0]
	v_pk_fma_f32 v[120:121], v[70:71], v[122:123], v[120:121] op_sel_hi:[0,1,1]
	v_pk_mul_f32 v[122:123], v[76:77], v[100:101] op_sel:[0,1] op_sel_hi:[1,0]
	v_xor_b32_e32 v84, 0x80000000, v83
	v_mov_b32_e32 v85, v83
	v_pk_fma_f32 v[98:99], v[24:25], v[114:115], v[98:99] op_sel_hi:[0,1,1]
	v_pk_mul_f32 v[114:115], v[28:29], v[118:119] op_sel:[1,1] op_sel_hi:[1,0] neg_lo:[1,0]
	v_pk_fma_f32 v[100:101], v[74:75], v[100:101], v[122:123] op_sel_hi:[0,1,1]
	v_pk_mul_f32 v[122:123], v[80:81], v[112:113] op_sel:[0,1] op_sel_hi:[1,0]
	v_add_u32_e32 v6, 0x2000, v6
	v_pk_mul_f32 v[108:109], v[26:27], v[126:127] op_sel:[1,1] op_sel_hi:[1,0] neg_lo:[1,0]
	v_pk_fma_f32 v[114:115], v[28:29], v[118:119], v[114:115] op_sel_hi:[0,1,1]
	v_pk_mul_f32 v[118:119], v[30:31], v[124:125] op_sel:[1,1] op_sel_hi:[1,0] neg_lo:[1,0]
	v_pk_fma_f32 v[112:113], v[78:79], v[112:113], v[122:123] op_sel_hi:[0,1,1]
	v_pk_mul_f32 v[122:123], v[84:85], v[92:93] op_sel:[0,1] op_sel_hi:[1,0]
	v_ashrrev_i32_e32 v6, 2, v6
	v_pk_fma_f32 v[108:109], v[26:27], v[126:127], v[108:109] op_sel_hi:[0,1,1]
	v_pk_fma_f32 v[118:119], v[30:31], v[124:125], v[118:119] op_sel_hi:[0,1,1]
	v_pk_fma_f32 v[92:93], v[82:83], v[92:93], v[122:123] op_sel_hi:[0,1,1]
	ds_write2_b64 v25, v[132:133], v[110:111] offset1:16
	ds_write2_b64 v25, v[118:119], v[120:121] offset0:33 offset1:49
	ds_write2_b64 v25, v[108:109], v[106:107] offset0:66 offset1:82
	ds_write2_b64 v25, v[104:105], v[112:113] offset0:99 offset1:115
	ds_write2_b64 v25, v[98:99], v[102:103] offset0:132 offset1:148
	ds_write2_b64 v25, v[116:117], v[100:101] offset0:165 offset1:181
	ds_write2_b64 v25, v[114:115], v[96:97] offset0:198 offset1:214
	ds_write2_b64 v25, v[94:95], v[92:93] offset0:231 offset1:247
	v_add3_u32 v6, v11, v6, s35
	ds_read2_b64 v[92:95], v6 offset1:16
	ds_read2_b64 v[96:99], v6 offset0:33 offset1:49
	ds_read2_b64 v[100:103], v6 offset0:66 offset1:82
	ds_read2_b64 v[104:107], v6 offset0:132 offset1:148
	ds_read2_b64 v[108:111], v6 offset0:99 offset1:115
	ds_read2_b64 v[112:115], v6 offset0:165 offset1:181
	ds_read2_b64 v[116:119], v6 offset0:198 offset1:214
	ds_read2_b64 v[120:123], v6 offset0:231 offset1:247
	s_waitcnt lgkmcnt(4)
	v_pk_add_f32 v[124:125], v[92:93], v[104:105]
	v_pk_add_f32 v[92:93], v[92:93], v[104:105] neg_lo:[0,1] neg_hi:[0,1]
	v_pk_add_f32 v[104:105], v[94:95], v[106:107]
	v_pk_add_f32 v[94:95], v[94:95], v[106:107] neg_lo:[0,1] neg_hi:[0,1]
	s_waitcnt lgkmcnt(1)
	v_pk_add_f32 v[126:127], v[102:103], v[118:119]
	v_pk_mul_f32 v[106:107], v[94:95], s[38:39]
	v_pk_add_f32 v[102:103], v[102:103], v[118:119] neg_lo:[0,1] neg_hi:[0,1]
	v_pk_fma_f32 v[94:95], v[94:95], s[36:37], v[106:107] op_sel:[0,0,1] op_sel_hi:[1,0,0]
	v_pk_add_f32 v[106:107], v[96:97], v[112:113]
	v_pk_add_f32 v[96:97], v[96:97], v[112:113] neg_lo:[0,1] neg_hi:[0,1]
	v_pk_mul_f32 v[118:119], v[102:103], s[44:45]
	v_pk_mul_f32 v[112:113], v[96:97], s[42:43]
	v_pk_fma_f32 v[102:103], v[102:103], s[62:63], v[118:119] op_sel:[0,0,1] op_sel_hi:[1,0,0] neg_lo:[1,0,0] neg_hi:[1,0,0]
	s_waitcnt lgkmcnt(0)
	v_pk_add_f32 v[118:119], v[108:109], v[120:121]
	v_pk_add_f32 v[108:109], v[108:109], v[120:121] neg_lo:[0,1] neg_hi:[0,1]
	v_pk_fma_f32 v[96:97], v[96:97], s[40:41], v[112:113] op_sel:[0,0,1] op_sel_hi:[1,0,0]
	v_pk_add_f32 v[112:113], v[98:99], v[114:115]
	v_pk_add_f32 v[98:99], v[98:99], v[114:115] neg_lo:[0,1] neg_hi:[0,1]
	v_pk_mul_f32 v[120:121], v[108:109], s[42:43]
	v_pk_mul_f32 v[114:115], v[98:99], s[44:45]
	v_pk_fma_f32 v[108:109], v[108:109], s[40:41], v[120:121] op_sel:[0,0,1] op_sel_hi:[1,0,0] neg_lo:[1,0,0] neg_hi:[1,0,0]
	v_pk_add_f32 v[120:121], v[110:111], v[122:123]
	v_pk_add_f32 v[110:111], v[110:111], v[122:123] neg_lo:[0,1] neg_hi:[0,1]
	v_pk_fma_f32 v[98:99], v[98:99], s[62:63], v[114:115] op_sel:[0,0,1] op_sel_hi:[1,0,0]
	v_pk_add_f32 v[114:115], v[100:101], v[116:117]
	v_pk_mul_f32 v[122:123], v[110:111], s[38:39]
	v_pk_add_f32 v[116:117], v[100:101], v[116:117] neg_lo:[0,1] neg_hi:[0,1]
	v_pk_fma_f32 v[110:111], v[110:111], s[36:37], v[122:123] op_sel:[0,0,1] op_sel_hi:[1,0,0] neg_lo:[1,0,0] neg_hi:[1,0,0]
	v_pk_add_f32 v[122:123], v[124:125], v[114:115]
	v_pk_add_f32 v[114:115], v[124:125], v[114:115] neg_lo:[0,1] neg_hi:[0,1]
	v_pk_add_f32 v[124:125], v[104:105], v[126:127]
	v_pk_add_f32 v[104:105], v[104:105], v[126:127] neg_lo:[0,1] neg_hi:[0,1]
	v_pk_mul_f32 v[126:127], v[104:105], s[42:43]
	v_pk_add_f32 v[128:129], v[112:113], v[120:121]
	v_pk_add_f32 v[112:113], v[112:113], v[120:121] neg_lo:[0,1] neg_hi:[0,1]
	v_pk_fma_f32 v[104:105], v[104:105], s[40:41], v[126:127] op_sel:[0,0,1] op_sel_hi:[1,0,0]
	v_pk_add_f32 v[126:127], v[106:107], v[118:119]
	v_pk_add_f32 v[118:119], v[106:107], v[118:119] neg_lo:[0,1] neg_hi:[0,1]
	v_pk_mul_f32 v[120:121], v[112:113], s[42:43]
	v_pk_add_f32 v[100:101], v[92:93], v[116:117] op_sel:[0,1] op_sel_hi:[1,0] neg_hi:[0,1]
	v_pk_add_f32 v[92:93], v[92:93], v[116:117] op_sel:[0,1] op_sel_hi:[1,0] neg_lo:[0,1]
	v_pk_add_f32 v[116:117], v[94:95], v[102:103]
	v_pk_add_f32 v[94:95], v[94:95], v[102:103] neg_lo:[0,1] neg_hi:[0,1]
	v_pk_fma_f32 v[112:113], v[112:113], s[40:41], v[120:121] op_sel:[0,0,1] op_sel_hi:[1,0,0] neg_lo:[1,0,0] neg_hi:[1,0,0]
	v_pk_mul_f32 v[102:103], v[94:95], s[42:43]
	v_pk_fma_f32 v[94:95], v[94:95], s[40:41], v[102:103] op_sel:[0,0,1] op_sel_hi:[1,0,0]
	v_pk_add_f32 v[102:103], v[96:97], v[108:109]
	v_pk_add_f32 v[120:121], v[98:99], v[110:111]
	v_pk_add_f32 v[98:99], v[98:99], v[110:111] neg_lo:[0,1] neg_hi:[0,1]
	v_pk_add_f32 v[106:107], v[114:115], v[118:119] op_sel:[0,1] op_sel_hi:[1,0] neg_hi:[0,1]
	v_pk_add_f32 v[114:115], v[114:115], v[118:119] op_sel:[0,1] op_sel_hi:[1,0] neg_lo:[0,1]
	v_pk_add_f32 v[118:119], v[104:105], v[112:113]
	v_pk_add_f32 v[112:113], v[104:105], v[112:113] neg_lo:[0,1] neg_hi:[0,1]
	v_pk_add_f32 v[108:109], v[96:97], v[108:109] neg_lo:[0,1] neg_hi:[0,1]
	v_pk_mul_f32 v[110:111], v[98:99], s[42:43]
	v_pk_add_f32 v[130:131], v[100:101], v[102:103]
	v_pk_add_f32 v[100:101], v[100:101], v[102:103] neg_lo:[0,1] neg_hi:[0,1]
	v_pk_add_f32 v[102:103], v[116:117], v[120:121]
	v_pk_fma_f32 v[98:99], v[98:99], s[40:41], v[110:111] op_sel:[0,0,1] op_sel_hi:[1,0,0] neg_lo:[1,0,0] neg_hi:[1,0,0]
	v_pk_add_f32 v[110:111], v[122:123], v[126:127]
	v_pk_add_f32 v[122:123], v[122:123], v[126:127] neg_lo:[0,1] neg_hi:[0,1]
	v_pk_add_f32 v[126:127], v[124:125], v[128:129]
	v_pk_add_f32 v[104:105], v[114:115], v[112:113] op_sel:[0,1] op_sel_hi:[1,0] neg_hi:[0,1]
	v_pk_add_f32 v[112:113], v[114:115], v[112:113] op_sel:[0,1] op_sel_hi:[1,0] neg_lo:[0,1]
	v_pk_add_f32 v[114:115], v[130:131], v[102:103]
	v_pk_add_f32 v[124:125], v[124:125], v[128:129] neg_lo:[0,1] neg_hi:[0,1]
	v_pk_add_f32 v[96:97], v[92:93], v[108:109] op_sel:[0,1] op_sel_hi:[1,0] neg_hi:[0,1]
	v_pk_add_f32 v[92:93], v[92:93], v[108:109] op_sel:[0,1] op_sel_hi:[1,0] neg_lo:[0,1]
	v_pk_add_f32 v[108:109], v[94:95], v[98:99]
	v_pk_add_f32 v[132:133], v[110:111], v[126:127]
	v_pk_add_f32 v[110:111], v[110:111], v[126:127] neg_lo:[0,1] neg_hi:[0,1]
	v_pk_add_f32 v[126:127], v[106:107], v[118:119]
	v_pk_mul_f32 v[22:23], v[22:23], v[114:115] op_sel:[0,1] op_sel_hi:[1,0]
	v_xor_b32_e32 v129, 0x80000000, v124
	v_pk_add_f32 v[116:117], v[116:117], v[120:121] neg_lo:[0,1] neg_hi:[0,1]
	v_mov_b32_e32 v128, v125
	v_pk_add_f32 v[106:107], v[106:107], v[118:119] neg_lo:[0,1] neg_hi:[0,1]
	v_pk_add_f32 v[118:119], v[96:97], v[108:109]
	v_pk_fma_f32 v[22:23], v[24:25], v[114:115], v[22:23] op_sel_hi:[0,1,1]
	v_pk_mul_f32 v[24:25], v[26:27], v[126:127] op_sel:[1,1] op_sel_hi:[1,0] neg_lo:[1,0]
	v_xor_b32_e32 v121, 0x80000000, v116
	v_pk_add_f32 v[94:95], v[94:95], v[98:99] neg_lo:[0,1] neg_hi:[0,1]
	v_pk_add_f32 v[124:125], v[122:123], v[128:129]
	v_mov_b32_e32 v120, v117
	v_pk_fma_f32 v[24:25], v[26:27], v[126:127], v[24:25] op_sel_hi:[0,1,1]
	v_pk_mul_f32 v[26:27], v[28:29], v[118:119] op_sel:[1,1] op_sel_hi:[1,0] neg_lo:[1,0]
	v_xor_b32_e32 v99, 0x80000000, v94
	v_pk_add_f32 v[116:117], v[100:101], v[120:121]
	v_mov_b32_e32 v98, v95
	v_pk_fma_f32 v[26:27], v[28:29], v[118:119], v[26:27] op_sel_hi:[0,1,1]
	v_pk_mul_f32 v[28:29], v[30:31], v[124:125] op_sel:[1,1] op_sel_hi:[1,0] neg_lo:[1,0]
	v_pk_add_f32 v[94:95], v[92:93], v[98:99]
	v_pk_fma_f32 v[28:29], v[30:31], v[124:125], v[28:29] op_sel_hi:[0,1,1]
	v_pk_mul_f32 v[30:31], v[36:37], v[116:117] op_sel:[1,1] op_sel_hi:[1,0] neg_lo:[1,0]
	v_pk_add_f32 v[122:123], v[122:123], v[128:129] neg_lo:[0,1] neg_hi:[0,1]
	v_pk_add_f32 v[102:103], v[130:131], v[102:103] neg_lo:[0,1] neg_hi:[0,1]
	v_pk_add_f32 v[100:101], v[100:101], v[120:121] neg_lo:[0,1] neg_hi:[0,1]
	v_pk_add_f32 v[96:97], v[96:97], v[108:109] neg_lo:[0,1] neg_hi:[0,1]
	v_pk_add_f32 v[92:93], v[92:93], v[98:99] neg_lo:[0,1] neg_hi:[0,1]
	v_pk_fma_f32 v[30:31], v[36:37], v[116:117], v[30:31] op_sel_hi:[0,1,1]
	v_pk_mul_f32 v[32:33], v[42:43], v[104:105] op_sel:[1,1] op_sel_hi:[1,0] neg_lo:[1,0]
	v_pk_mul_f32 v[34:35], v[46:47], v[94:95] op_sel:[1,1] op_sel_hi:[1,0] neg_lo:[1,0]
	v_pk_mul_f32 v[36:37], v[50:51], v[110:111] op_sel:[1,1] op_sel_hi:[1,0] neg_lo:[1,0]
	v_pk_fma_f32 v[32:33], v[42:43], v[104:105], v[32:33] op_sel_hi:[0,1,1]
	v_pk_fma_f32 v[34:35], v[46:47], v[94:95], v[34:35] op_sel_hi:[0,1,1]
	v_pk_fma_f32 v[36:37], v[50:51], v[110:111], v[36:37] op_sel_hi:[0,1,1]
	v_pk_mul_f32 v[38:39], v[54:55], v[102:103] op_sel:[1,1] op_sel_hi:[1,0] neg_lo:[1,0]
	v_pk_mul_f32 v[40:41], v[58:59], v[106:107] op_sel:[1,1] op_sel_hi:[1,0] neg_lo:[1,0]
	v_pk_mul_f32 v[42:43], v[68:69], v[96:97] op_sel:[0,1] op_sel_hi:[1,0]
	v_pk_mul_f32 v[44:45], v[72:73], v[122:123] op_sel:[0,1] op_sel_hi:[1,0]
	v_pk_mul_f32 v[46:47], v[76:77], v[100:101] op_sel:[0,1] op_sel_hi:[1,0]
	v_pk_mul_f32 v[48:49], v[80:81], v[112:113] op_sel:[0,1] op_sel_hi:[1,0]
	v_pk_mul_f32 v[50:51], v[84:85], v[92:93] op_sel:[0,1] op_sel_hi:[1,0]
	v_pk_fma_f32 v[38:39], v[54:55], v[102:103], v[38:39] op_sel_hi:[0,1,1]
	v_pk_fma_f32 v[40:41], v[58:59], v[106:107], v[40:41] op_sel_hi:[0,1,1]
	v_pk_fma_f32 v[42:43], v[66:67], v[96:97], v[42:43] op_sel_hi:[0,1,1]
	v_pk_fma_f32 v[44:45], v[70:71], v[122:123], v[44:45] op_sel_hi:[0,1,1]
	v_pk_fma_f32 v[46:47], v[74:75], v[100:101], v[46:47] op_sel_hi:[0,1,1]
	v_pk_fma_f32 v[48:49], v[78:79], v[112:113], v[48:49] op_sel_hi:[0,1,1]
	v_pk_fma_f32 v[50:51], v[82:83], v[92:93], v[50:51] op_sel_hi:[0,1,1]
	ds_write2_b64 v6, v[132:133], v[36:37] offset1:16
	ds_write2_b64 v6, v[28:29], v[44:45] offset0:33 offset1:49
	ds_write2_b64 v6, v[24:25], v[40:41] offset0:66 offset1:82
	ds_write2_b64 v6, v[32:33], v[48:49] offset0:99 offset1:115
	ds_write2_b64 v6, v[22:23], v[38:39] offset0:132 offset1:148
	ds_write2_b64 v6, v[30:31], v[46:47] offset0:165 offset1:181
	ds_write2_b64 v6, v[26:27], v[42:43] offset0:198 offset1:214
	ds_write2_b64 v6, v[34:35], v[50:51] offset0:231 offset1:247
	v_mov_b32_e32 v6, v62
	s_waitcnt lgkmcnt(0)
	s_barrier
	s_lshl_b32 s24, s71, 6
	v_bfe_i32 v11, v6, 1, 27
	v_lshl_add_u32 v68, v6, 7, 0
	v_lshl_add_u32 v11, v11, 3, v68
	ds_read2_b64 v[22:25], v11 offset1:1
	ds_read2_b64 v[26:29], v11 offset0:2 offset1:3
	ds_read2_b64 v[30:33], v11 offset0:8 offset1:9
	ds_read2_b64 v[34:37], v11 offset0:4 offset1:5
	ds_read2_b64 v[38:41], v11 offset0:6 offset1:7
	ds_read2_b64 v[42:45], v11 offset0:10 offset1:11
	ds_read2_b64 v[46:49], v11 offset0:12 offset1:13
	ds_read2_b64 v[50:53], v11 offset0:14 offset1:15
	s_waitcnt lgkmcnt(5)
	v_pk_add_f32 v[54:55], v[22:23], v[30:31]
	v_pk_add_f32 v[22:23], v[22:23], v[30:31] neg_lo:[0,1] neg_hi:[0,1]
	v_pk_add_f32 v[30:31], v[24:25], v[32:33]
	v_pk_add_f32 v[24:25], v[24:25], v[32:33] neg_lo:[0,1] neg_hi:[0,1]
	s_waitcnt lgkmcnt(1)
	v_pk_add_f32 v[56:57], v[36:37], v[48:49]
	v_pk_mul_f32 v[32:33], v[24:25], s[38:39]
	v_pk_add_f32 v[36:37], v[36:37], v[48:49] neg_lo:[0,1] neg_hi:[0,1]
	v_pk_fma_f32 v[24:25], v[24:25], s[36:37], v[32:33] op_sel:[0,0,1] op_sel_hi:[1,0,0]
	v_pk_add_f32 v[32:33], v[26:27], v[42:43]
	v_pk_add_f32 v[26:27], v[26:27], v[42:43] neg_lo:[0,1] neg_hi:[0,1]
	v_pk_mul_f32 v[48:49], v[36:37], s[44:45]
	v_pk_mul_f32 v[42:43], v[26:27], s[42:43]
	v_pk_fma_f32 v[36:37], v[36:37], s[62:63], v[48:49] op_sel:[0,0,1] op_sel_hi:[1,0,0] neg_lo:[1,0,0] neg_hi:[1,0,0]
	v_pk_fma_f32 v[26:27], v[26:27], s[40:41], v[42:43] op_sel:[0,0,1] op_sel_hi:[1,0,0]
	v_pk_add_f32 v[42:43], v[28:29], v[44:45]
	v_pk_add_f32 v[28:29], v[28:29], v[44:45] neg_lo:[0,1] neg_hi:[0,1]
	s_waitcnt lgkmcnt(0)
	v_pk_add_f32 v[48:49], v[38:39], v[50:51]
	v_pk_add_f32 v[38:39], v[38:39], v[50:51] neg_lo:[0,1] neg_hi:[0,1]
	v_pk_mul_f32 v[44:45], v[28:29], s[44:45]
	v_pk_mul_f32 v[50:51], v[38:39], s[42:43]
	v_pk_fma_f32 v[28:29], v[28:29], s[62:63], v[44:45] op_sel:[0,0,1] op_sel_hi:[1,0,0]
	v_pk_add_f32 v[44:45], v[34:35], v[46:47]
	v_pk_add_f32 v[46:47], v[34:35], v[46:47] neg_lo:[0,1] neg_hi:[0,1]
	v_pk_fma_f32 v[38:39], v[38:39], s[40:41], v[50:51] op_sel:[0,0,1] op_sel_hi:[1,0,0] neg_lo:[1,0,0] neg_hi:[1,0,0]
	v_pk_add_f32 v[50:51], v[40:41], v[52:53]
	v_pk_add_f32 v[40:41], v[40:41], v[52:53] neg_lo:[0,1] neg_hi:[0,1]
	v_pk_mul_f32 v[52:53], v[40:41], s[38:39]
	v_pk_add_f32 v[58:59], v[42:43], v[50:51]
	v_pk_add_f32 v[42:43], v[42:43], v[50:51] neg_lo:[0,1] neg_hi:[0,1]
	v_pk_fma_f32 v[40:41], v[40:41], s[36:37], v[52:53] op_sel:[0,0,1] op_sel_hi:[1,0,0] neg_lo:[1,0,0] neg_hi:[1,0,0]
	v_pk_add_f32 v[52:53], v[54:55], v[44:45]
	v_pk_add_f32 v[44:45], v[54:55], v[44:45] neg_lo:[0,1] neg_hi:[0,1]
	v_pk_add_f32 v[54:55], v[30:31], v[56:57]
	v_pk_add_f32 v[30:31], v[30:31], v[56:57] neg_lo:[0,1] neg_hi:[0,1]
	v_pk_mul_f32 v[50:51], v[42:43], s[42:43]
	v_pk_add_f32 v[34:35], v[22:23], v[46:47] op_sel:[0,1] op_sel_hi:[1,0] neg_hi:[0,1]
	v_pk_add_f32 v[22:23], v[22:23], v[46:47] op_sel:[0,1] op_sel_hi:[1,0] neg_lo:[0,1]
	v_pk_add_f32 v[46:47], v[24:25], v[36:37]
	v_pk_add_f32 v[24:25], v[24:25], v[36:37] neg_lo:[0,1] neg_hi:[0,1]
	v_pk_mul_f32 v[56:57], v[30:31], s[42:43]
	v_pk_fma_f32 v[42:43], v[42:43], s[40:41], v[50:51] op_sel:[0,0,1] op_sel_hi:[1,0,0] neg_lo:[1,0,0] neg_hi:[1,0,0]
	v_pk_mul_f32 v[36:37], v[24:25], s[42:43]
	v_pk_add_f32 v[50:51], v[28:29], v[40:41]
	v_pk_add_f32 v[28:29], v[28:29], v[40:41] neg_lo:[0,1] neg_hi:[0,1]
	v_pk_fma_f32 v[30:31], v[30:31], s[40:41], v[56:57] op_sel:[0,0,1] op_sel_hi:[1,0,0]
	v_pk_add_f32 v[56:57], v[32:33], v[48:49]
	v_pk_add_f32 v[48:49], v[32:33], v[48:49] neg_lo:[0,1] neg_hi:[0,1]
	v_pk_fma_f32 v[24:25], v[24:25], s[40:41], v[36:37] op_sel:[0,0,1] op_sel_hi:[1,0,0]
	v_pk_add_f32 v[36:37], v[26:27], v[38:39]
	v_pk_add_f32 v[38:39], v[26:27], v[38:39] neg_lo:[0,1] neg_hi:[0,1]
	v_pk_mul_f32 v[40:41], v[28:29], s[42:43]
	v_pk_fma_f32 v[28:29], v[28:29], s[40:41], v[40:41] op_sel:[0,0,1] op_sel_hi:[1,0,0] neg_lo:[1,0,0] neg_hi:[1,0,0]
	v_lshl_add_u32 v6, v6, 4, v90
	v_pk_add_f32 v[40:41], v[52:53], v[56:57]
	v_pk_add_f32 v[52:53], v[52:53], v[56:57] neg_lo:[0,1] neg_hi:[0,1]
	v_pk_add_f32 v[56:57], v[54:55], v[58:59]
	v_pk_add_f32 v[58:59], v[54:55], v[58:59] neg_lo:[0,1] neg_hi:[0,1]
	v_pk_add_f32 v[32:33], v[44:45], v[48:49] op_sel:[0,1] op_sel_hi:[1,0] neg_hi:[0,1]
	v_pk_add_f32 v[44:45], v[44:45], v[48:49] op_sel:[0,1] op_sel_hi:[1,0] neg_lo:[0,1]
	v_pk_add_f32 v[48:49], v[30:31], v[42:43]
	v_pk_add_f32 v[42:43], v[30:31], v[42:43] neg_lo:[0,1] neg_hi:[0,1]
	v_pk_add_f32 v[60:61], v[34:35], v[36:37]
	v_pk_add_f32 v[34:35], v[34:35], v[36:37] neg_lo:[0,1] neg_hi:[0,1]
	v_pk_add_f32 v[36:37], v[46:47], v[50:51]
	v_pk_add_f32 v[50:51], v[46:47], v[50:51] neg_lo:[0,1] neg_hi:[0,1]
	v_pk_add_f32 v[26:27], v[22:23], v[38:39] op_sel:[0,1] op_sel_hi:[1,0] neg_hi:[0,1]
	v_pk_add_f32 v[22:23], v[22:23], v[38:39] op_sel:[0,1] op_sel_hi:[1,0] neg_lo:[0,1]
	v_pk_add_f32 v[38:39], v[24:25], v[28:29]
	v_pk_add_f32 v[28:29], v[24:25], v[28:29] neg_lo:[0,1] neg_hi:[0,1]
	v_ashrrev_i32_e32 v6, 5, v6
	v_pk_add_f32 v[66:67], v[40:41], v[56:57]
	v_pk_add_f32 v[40:41], v[40:41], v[56:57] neg_lo:[0,1] neg_hi:[0,1]
	v_lshlrev_b32_e32 v6, 3, v6
	v_pk_add_f32 v[54:55], v[52:53], v[58:59] op_sel:[0,1] op_sel_hi:[1,0] neg_hi:[0,1]
	v_pk_add_f32 v[52:53], v[52:53], v[58:59] op_sel:[0,1] op_sel_hi:[1,0] neg_lo:[0,1]
	v_pk_add_f32 v[56:57], v[32:33], v[48:49]
	v_pk_add_f32 v[32:33], v[32:33], v[48:49] neg_lo:[0,1] neg_hi:[0,1]
	v_pk_add_f32 v[30:31], v[44:45], v[42:43] op_sel:[0,1] op_sel_hi:[1,0] neg_hi:[0,1]
	v_pk_add_f32 v[42:43], v[44:45], v[42:43] op_sel:[0,1] op_sel_hi:[1,0] neg_lo:[0,1]
	v_pk_add_f32 v[44:45], v[60:61], v[36:37]
	v_pk_add_f32 v[36:37], v[60:61], v[36:37] neg_lo:[0,1] neg_hi:[0,1]
	v_pk_add_f32 v[46:47], v[34:35], v[50:51] op_sel:[0,1] op_sel_hi:[1,0] neg_hi:[0,1]
	v_pk_add_f32 v[34:35], v[34:35], v[50:51] op_sel:[0,1] op_sel_hi:[1,0] neg_lo:[0,1]
	v_pk_add_f32 v[48:49], v[26:27], v[38:39]
	v_pk_add_f32 v[26:27], v[26:27], v[38:39] neg_lo:[0,1] neg_hi:[0,1]
	v_pk_add_f32 v[24:25], v[22:23], v[28:29] op_sel:[0,1] op_sel_hi:[1,0] neg_hi:[0,1]
	v_pk_add_f32 v[22:23], v[22:23], v[28:29] op_sel:[0,1] op_sel_hi:[1,0] neg_lo:[0,1]
	ds_write2_b64 v11, v[66:67], v[40:41] offset1:1
	ds_write2_b64 v11, v[54:55], v[52:53] offset0:2 offset1:3
	ds_write2_b64 v11, v[56:57], v[32:33] offset0:4 offset1:5
	ds_write2_b64 v11, v[30:31], v[42:43] offset0:6 offset1:7
	ds_write2_b64 v11, v[44:45], v[36:37] offset0:8 offset1:9
	ds_write2_b64 v11, v[46:47], v[34:35] offset0:10 offset1:11
	ds_write2_b64 v11, v[48:49], v[26:27] offset0:12 offset1:13
	ds_write2_b64 v11, v[24:25], v[22:23] offset0:14 offset1:15
	v_add3_u32 v6, v68, v6, s35
	ds_read2_b64 v[22:25], v6 offset1:1
	ds_read2_b64 v[26:29], v6 offset0:2 offset1:3
	ds_read2_b64 v[30:33], v6 offset0:8 offset1:9
	ds_read2_b64 v[34:37], v6 offset0:4 offset1:5
	ds_read2_b64 v[38:41], v6 offset0:6 offset1:7
	ds_read2_b64 v[42:45], v6 offset0:10 offset1:11
	ds_read2_b64 v[46:49], v6 offset0:12 offset1:13
	ds_read2_b64 v[50:53], v6 offset0:14 offset1:15
	s_waitcnt lgkmcnt(5)
	v_pk_add_f32 v[54:55], v[22:23], v[30:31]
	v_pk_add_f32 v[22:23], v[22:23], v[30:31] neg_lo:[0,1] neg_hi:[0,1]
	v_pk_add_f32 v[30:31], v[24:25], v[32:33]
	v_pk_add_f32 v[24:25], v[24:25], v[32:33] neg_lo:[0,1] neg_hi:[0,1]
	s_waitcnt lgkmcnt(1)
	v_pk_add_f32 v[56:57], v[36:37], v[48:49]
	v_pk_mul_f32 v[32:33], v[24:25], s[38:39]
	v_pk_add_f32 v[36:37], v[36:37], v[48:49] neg_lo:[0,1] neg_hi:[0,1]
	v_pk_fma_f32 v[24:25], v[24:25], s[36:37], v[32:33] op_sel:[0,0,1] op_sel_hi:[1,0,0]
	v_pk_add_f32 v[32:33], v[26:27], v[42:43]
	v_pk_add_f32 v[26:27], v[26:27], v[42:43] neg_lo:[0,1] neg_hi:[0,1]
	v_pk_mul_f32 v[48:49], v[36:37], s[44:45]
	v_pk_mul_f32 v[42:43], v[26:27], s[42:43]
	v_pk_fma_f32 v[36:37], v[36:37], s[62:63], v[48:49] op_sel:[0,0,1] op_sel_hi:[1,0,0] neg_lo:[1,0,0] neg_hi:[1,0,0]
	v_pk_fma_f32 v[26:27], v[26:27], s[40:41], v[42:43] op_sel:[0,0,1] op_sel_hi:[1,0,0]
	v_pk_add_f32 v[42:43], v[28:29], v[44:45]
	v_pk_add_f32 v[28:29], v[28:29], v[44:45] neg_lo:[0,1] neg_hi:[0,1]
	s_waitcnt lgkmcnt(0)
	v_pk_add_f32 v[48:49], v[38:39], v[50:51]
	v_pk_add_f32 v[38:39], v[38:39], v[50:51] neg_lo:[0,1] neg_hi:[0,1]
	v_pk_mul_f32 v[44:45], v[28:29], s[44:45]
	v_pk_mul_f32 v[50:51], v[38:39], s[42:43]
	v_pk_fma_f32 v[28:29], v[28:29], s[62:63], v[44:45] op_sel:[0,0,1] op_sel_hi:[1,0,0]
	v_pk_add_f32 v[44:45], v[34:35], v[46:47]
	v_pk_add_f32 v[46:47], v[34:35], v[46:47] neg_lo:[0,1] neg_hi:[0,1]
	v_pk_fma_f32 v[38:39], v[38:39], s[40:41], v[50:51] op_sel:[0,0,1] op_sel_hi:[1,0,0] neg_lo:[1,0,0] neg_hi:[1,0,0]
	v_pk_add_f32 v[50:51], v[40:41], v[52:53]
	v_pk_add_f32 v[40:41], v[40:41], v[52:53] neg_lo:[0,1] neg_hi:[0,1]
	v_pk_mul_f32 v[52:53], v[40:41], s[38:39]
	v_pk_add_f32 v[58:59], v[42:43], v[50:51]
	v_pk_add_f32 v[42:43], v[42:43], v[50:51] neg_lo:[0,1] neg_hi:[0,1]
	v_pk_fma_f32 v[40:41], v[40:41], s[36:37], v[52:53] op_sel:[0,0,1] op_sel_hi:[1,0,0] neg_lo:[1,0,0] neg_hi:[1,0,0]
	v_pk_mul_f32 v[50:51], v[42:43], s[42:43]
	v_pk_add_f32 v[34:35], v[22:23], v[46:47] op_sel:[0,1] op_sel_hi:[1,0] neg_hi:[0,1]
	v_pk_add_f32 v[22:23], v[22:23], v[46:47] op_sel:[0,1] op_sel_hi:[1,0] neg_lo:[0,1]
	v_pk_add_f32 v[46:47], v[24:25], v[36:37]
	v_pk_add_f32 v[24:25], v[24:25], v[36:37] neg_lo:[0,1] neg_hi:[0,1]
	v_pk_add_f32 v[52:53], v[54:55], v[44:45]
	v_pk_add_f32 v[44:45], v[54:55], v[44:45] neg_lo:[0,1] neg_hi:[0,1]
	v_pk_add_f32 v[54:55], v[30:31], v[56:57]
	v_pk_add_f32 v[30:31], v[30:31], v[56:57] neg_lo:[0,1] neg_hi:[0,1]
	v_pk_fma_f32 v[42:43], v[42:43], s[40:41], v[50:51] op_sel:[0,0,1] op_sel_hi:[1,0,0] neg_lo:[1,0,0] neg_hi:[1,0,0]
	v_pk_mul_f32 v[36:37], v[24:25], s[42:43]
	v_pk_add_f32 v[50:51], v[28:29], v[40:41]
	v_pk_add_f32 v[28:29], v[28:29], v[40:41] neg_lo:[0,1] neg_hi:[0,1]
	s_and_b32 s24, s24, 0xc0
	v_pk_mul_f32 v[56:57], v[30:31], s[42:43]
	v_pk_fma_f32 v[24:25], v[24:25], s[40:41], v[36:37] op_sel:[0,0,1] op_sel_hi:[1,0,0]
	v_pk_add_f32 v[36:37], v[26:27], v[38:39]
	v_pk_add_f32 v[38:39], v[26:27], v[38:39] neg_lo:[0,1] neg_hi:[0,1]
	v_pk_mul_f32 v[40:41], v[28:29], s[42:43]
	s_lshl_b64 s[62:63], s[50:51], 19
	v_pk_fma_f32 v[30:31], v[30:31], s[40:41], v[56:57] op_sel:[0,0,1] op_sel_hi:[1,0,0]
	v_pk_add_f32 v[56:57], v[32:33], v[48:49]
	v_pk_add_f32 v[48:49], v[32:33], v[48:49] neg_lo:[0,1] neg_hi:[0,1]
	s_nop 0
	v_pk_fma_f32 v[28:29], v[28:29], s[40:41], v[40:41] op_sel:[0,0,1] op_sel_hi:[1,0,0] neg_lo:[1,0,0] neg_hi:[1,0,0]
	s_add_u32 s43, s3, s62
	s_nop 0
	s_nop 0
	v_pk_add_f32 v[26:27], v[22:23], v[38:39] op_sel:[0,1] op_sel_hi:[1,0] neg_hi:[0,1]
	v_pk_add_f32 v[22:23], v[22:23], v[38:39] op_sel:[0,1] op_sel_hi:[1,0] neg_lo:[0,1]
	v_pk_add_f32 v[38:39], v[24:25], v[28:29]
	v_pk_add_f32 v[24:25], v[24:25], v[28:29] neg_lo:[0,1] neg_hi:[0,1]
	s_addc_u32 s45, s29, s63
	s_lshl_b32 s64, s24, 2
	v_pk_add_f32 v[40:41], v[52:53], v[56:57]
	v_pk_add_f32 v[52:53], v[52:53], v[56:57] neg_lo:[0,1] neg_hi:[0,1]
	v_pk_add_f32 v[56:57], v[54:55], v[58:59]
	v_pk_add_f32 v[54:55], v[54:55], v[58:59] neg_lo:[0,1] neg_hi:[0,1]
	v_pk_add_f32 v[32:33], v[44:45], v[48:49] op_sel:[0,1] op_sel_hi:[1,0] neg_hi:[0,1]
	v_pk_add_f32 v[44:45], v[44:45], v[48:49] op_sel:[0,1] op_sel_hi:[1,0] neg_lo:[0,1]
	v_pk_add_f32 v[48:49], v[30:31], v[42:43]
	v_pk_add_f32 v[42:43], v[30:31], v[42:43] neg_lo:[0,1] neg_hi:[0,1]
	v_pk_add_f32 v[60:61], v[34:35], v[36:37]
	v_pk_add_f32 v[34:35], v[34:35], v[36:37] neg_lo:[0,1] neg_hi:[0,1]
	v_pk_add_f32 v[36:37], v[46:47], v[50:51]
	v_pk_add_f32 v[46:47], v[46:47], v[50:51] neg_lo:[0,1] neg_hi:[0,1]
	v_xor_b32_e32 v29, 0x80000000, v24
	v_mov_b32_e32 v28, v25
	s_add_u32 s64, s43, s64
	v_xor_b32_e32 v59, 0x80000000, v54
	s_nop 0
	v_xor_b32_e32 v51, 0x80000000, v46
	v_pk_add_f32 v[66:67], v[40:41], v[56:57]
	v_pk_add_f32 v[40:41], v[40:41], v[56:57] neg_lo:[0,1] neg_hi:[0,1]
	v_mov_b32_e32 v58, v55
	v_mov_b32_e32 v50, v47
	v_pk_add_f32 v[24:25], v[22:23], v[28:29]
	v_pk_add_f32 v[22:23], v[22:23], v[28:29] neg_lo:[0,1] neg_hi:[0,1]
	s_addc_u32 s65, s45, 0
	v_pk_add_f32 v[54:55], v[52:53], v[58:59]
	v_pk_add_f32 v[52:53], v[52:53], v[58:59] neg_lo:[0,1] neg_hi:[0,1]
	v_pk_add_f32 v[56:57], v[32:33], v[48:49]
	v_pk_add_f32 v[32:33], v[32:33], v[48:49] neg_lo:[0,1] neg_hi:[0,1]
	v_pk_add_f32 v[30:31], v[44:45], v[42:43] op_sel:[0,1] op_sel_hi:[1,0] neg_hi:[0,1]
	v_pk_add_f32 v[42:43], v[44:45], v[42:43] op_sel:[0,1] op_sel_hi:[1,0] neg_lo:[0,1]
	v_pk_add_f32 v[44:45], v[60:61], v[36:37]
	v_pk_add_f32 v[36:37], v[60:61], v[36:37] neg_lo:[0,1] neg_hi:[0,1]
	v_pk_add_f32 v[46:47], v[34:35], v[50:51]
	v_pk_add_f32 v[34:35], v[34:35], v[50:51] neg_lo:[0,1] neg_hi:[0,1]
	v_pk_add_f32 v[48:49], v[26:27], v[38:39]
	v_pk_add_f32 v[26:27], v[26:27], v[38:39] neg_lo:[0,1] neg_hi:[0,1]
	ds_write2_b64 v6, v[66:67], v[40:41] offset1:1
	ds_write2_b64 v6, v[54:55], v[52:53] offset0:2 offset1:3
	ds_write2_b64 v6, v[56:57], v[32:33] offset0:4 offset1:5
	ds_write2_b64 v6, v[30:31], v[42:43] offset0:6 offset1:7
	ds_write2_b64 v6, v[44:45], v[36:37] offset0:8 offset1:9
	ds_write2_b64 v6, v[46:47], v[34:35] offset0:10 offset1:11
	ds_write2_b64 v6, v[48:49], v[26:27] offset0:12 offset1:13
	ds_write2_b64 v6, v[24:25], v[22:23] offset0:14 offset1:15
	v_lshl_add_u64 v[22:23], s[64:65], 0, v[20:21]
	s_mov_b64 s[64:65], 0
	v_mov_b32_e32 v11, v9
	v_mov_b64_e32 v[24:25], v[62:63]
	s_waitcnt lgkmcnt(0)
	s_barrier

.LBB0_271:
	global_load_dword v40, v35, s[18:19]
	v_lshl_add_u64 v[44:45], s[18:19], 0, v[34:35]
	global_load_dword v42, v[44:45], off
	s_waitcnt vmcnt(9)
	v_cvt_f32_f16_e32 v62, v6
	v_cvt_f32_f16_sdwa v44, v6 dst_sel:DWORD dst_unused:UNUSED_PAD src0_sel:WORD_1
	v_cvt_f32_f16_e32 v45, v7
	v_cvt_f32_f16_e32 v47, v8
	v_cvt_f32_f16_sdwa v48, v8 dst_sel:DWORD dst_unused:UNUSED_PAD src0_sel:WORD_1
	v_cvt_f32_f16_e32 v49, v9
	v_cvt_f32_f16_sdwa v8, v9 dst_sel:DWORD dst_unused:UNUSED_PAD src0_sel:WORD_1
	s_waitcnt vmcnt(8)
	v_cvt_f32_f16_e32 v9, v30
	s_waitcnt vmcnt(7)
	v_cvt_f32_f16_sdwa v52, v26 dst_sel:DWORD dst_unused:UNUSED_PAD src0_sel:WORD_1
	v_cvt_f32_f16_e32 v53, v27
	v_cvt_f32_f16_sdwa v46, v7 dst_sel:DWORD dst_unused:UNUSED_PAD src0_sel:WORD_1
	v_cvt_f32_f16_sdwa v50, v30 dst_sel:DWORD dst_unused:UNUSED_PAD src0_sel:WORD_1
	v_cvt_f32_f16_e32 v51, v31
	v_cvt_f32_f16_sdwa v30, v31 dst_sel:DWORD dst_unused:UNUSED_PAD src0_sel:WORD_1
	v_cvt_f32_f16_e32 v31, v32
	v_cvt_f32_f16_sdwa v7, v33 dst_sel:DWORD dst_unused:UNUSED_PAD src0_sel:WORD_1
	v_cvt_f32_f16_sdwa v32, v32 dst_sel:DWORD dst_unused:UNUSED_PAD src0_sel:WORD_1
	v_cvt_f32_f16_e32 v33, v33
	v_cvt_f32_f16_sdwa v26, v27 dst_sel:DWORD dst_unused:UNUSED_PAD src0_sel:WORD_1
	v_cvt_f32_f16_e32 v27, v28
	v_cvt_f32_f16_sdwa v54, v28 dst_sel:DWORD dst_unused:UNUSED_PAD src0_sel:WORD_1
	v_cvt_f32_f16_e32 v55, v29
	s_waitcnt vmcnt(6)
	v_cvt_f32_f16_e32 v28, v18
	v_cvt_f32_f16_sdwa v56, v18 dst_sel:DWORD dst_unused:UNUSED_PAD src0_sel:WORD_1
	v_cvt_f32_f16_e32 v57, v19
	v_cvt_f32_f16_sdwa v18, v19 dst_sel:DWORD dst_unused:UNUSED_PAD src0_sel:WORD_1
	v_cvt_f32_f16_e32 v19, v20
	v_cvt_f32_f16_sdwa v58, v20 dst_sel:DWORD dst_unused:UNUSED_PAD src0_sel:WORD_1
	v_cvt_f32_f16_e32 v59, v21
	v_cvt_f32_f16_sdwa v29, v29 dst_sel:DWORD dst_unused:UNUSED_PAD src0_sel:WORD_1
	v_cvt_f32_f16_sdwa v21, v21 dst_sel:DWORD dst_unused:UNUSED_PAD src0_sel:WORD_1
	v_cvt_f32_f16_e32 v20, v120
	s_waitcnt vmcnt(5)
	v_cvt_f32_f16_e32 v63, v22
	v_mul_f32_e32 v62, 0x3b800000, v62
	v_pk_mul_f32 v[44:45], v[44:45], s[38:39] op_sel_hi:[1,0]
	v_pk_mul_f32 v[8:9], v[8:9], s[38:39] op_sel_hi:[1,0]
	v_pk_mul_f32 v[52:53], v[52:53], s[38:39] op_sel_hi:[1,0]
	v_pk_mul_f32 v[46:47], v[46:47], s[38:39] op_sel_hi:[1,0]
	v_pk_mul_f32 v[48:49], v[48:49], s[38:39] op_sel_hi:[1,0]
	v_pk_mul_f32 v[50:51], v[50:51], s[38:39] op_sel_hi:[1,0]
	v_pk_mul_f32 v[30:31], v[30:31], s[38:39] op_sel_hi:[1,0]
	v_mul_f32_e32 v7, 0x3b800000, v7
	v_pk_mul_f32 v[32:33], v[32:33], s[38:39] op_sel_hi:[1,0]
	v_pk_mul_f32 v[26:27], v[26:27], s[38:39] op_sel_hi:[1,0]
	v_pk_mul_f32 v[54:55], v[54:55], s[38:39] op_sel_hi:[1,0]
	v_pk_mul_f32 v[56:57], v[56:57], s[38:39] op_sel_hi:[1,0]
	v_pk_mul_f32 v[18:19], v[18:19], s[38:39] op_sel_hi:[1,0]
	v_pk_mul_f32 v[58:59], v[58:59], s[38:39] op_sel_hi:[1,0]
	ds_write2_b32 v135, v44, v45 offset0:1 offset1:2
	ds_write2_b32 v135, v46, v47 offset0:3 offset1:4
	ds_write2_b32 v135, v48, v49 offset0:5 offset1:6
	ds_write2_b32 v135, v8, v9 offset0:7 offset1:8
	ds_write2_b32 v135, v50, v51 offset0:9 offset1:10
	ds_write2_b32 v135, v30, v31 offset0:11 offset1:12
	ds_write2_b32 v135, v32, v33 offset0:13 offset1:14
	v_pk_mov_b32 v[8:9], v[52:53], v[52:53] op_sel:[1,0]
	v_pk_mul_f32 v[28:29], v[28:29], s[38:39] op_sel_hi:[1,0]
	v_pk_mul_f32 v[20:21], v[20:21], s[38:39] op_sel_hi:[1,0]
	v_mul_f32_e32 v63, 0x3b800000, v63
	v_pk_mov_b32 v[26:27], v[26:27], v[26:27] op_sel:[1,0]
	v_pk_mov_b32 v[30:31], v[54:55], v[54:55] op_sel:[1,0]
	v_pk_mov_b32 v[32:33], v[56:57], v[56:57] op_sel:[1,0]
	v_pk_mov_b32 v[18:19], v[18:19], v[18:19] op_sel:[1,0]
	v_pk_mov_b32 v[44:45], v[58:59], v[58:59] op_sel:[1,0]
	ds_write_b64 v136, v[8:9]
	ds_write_b64 v137, v[26:27]
	ds_write_b64 v138, v[30:31]
	ds_write_b64 v139, v[28:29]
	ds_write_b64 v140, v[32:33]
	ds_write_b64 v141, v[18:19]
	ds_write_b64 v142, v[44:45]
	ds_write_b64 v143, v[20:21]
	v_cvt_f32_f16_e32 v9, v25
	s_waitcnt vmcnt(4)
	v_cvt_f32_f16_sdwa v18, v14 dst_sel:DWORD dst_unused:UNUSED_PAD src0_sel:WORD_1
	v_cvt_f32_f16_e32 v19, v15
	v_cvt_f32_f16_sdwa v60, v22 dst_sel:DWORD dst_unused:UNUSED_PAD src0_sel:WORD_1
	v_cvt_f32_f16_e32 v61, v23
	s_mov_b32 s10, s69
	s_mov_b32 s71, s64
	s_mov_b32 s78, s67
	v_pk_mul_f32 v[60:61], v[60:61], s[38:39] op_sel_hi:[1,0]
	s_mov_b32 s73, s50
	s_mov_b32 s76, s63
	s_waitcnt vmcnt(1)
	v_fma_mix_f32 v6, v6, s38, v40 op_sel_hi:[1,0,0]
	s_nop 0
	v_cndmask_b32_e64 v6, v62, v6, s[6:7]
	s_waitcnt vmcnt(0)
	v_fma_mix_f32 v8, v22, s38, v42 op_sel_hi:[1,0,0]
	ds_write2_b32 v135, v6, v7 offset1:15
	v_cvt_f32_f16_sdwa v6, v23 dst_sel:DWORD dst_unused:UNUSED_PAD src0_sel:WORD_1
	v_cvt_f32_f16_e32 v7, v24
	v_cndmask_b32_e64 v20, v63, v8, s[8:9]
	v_cvt_f32_f16_sdwa v8, v24 dst_sel:DWORD dst_unused:UNUSED_PAD src0_sel:WORD_1
	ds_write2_b32 v144, v60, v61 offset0:1 offset1:2
	v_pk_mul_f32 v[6:7], v[6:7], s[38:39] op_sel_hi:[1,0]
	ds_write2_b32 v144, v6, v7 offset0:3 offset1:4
	v_pk_mul_f32 v[6:7], v[8:9], s[38:39] op_sel_hi:[1,0]
	v_cvt_f32_f16_sdwa v8, v25 dst_sel:DWORD dst_unused:UNUSED_PAD src0_sel:WORD_1
	v_cvt_f32_f16_e32 v9, v14
	ds_write2_b32 v144, v6, v7 offset0:5 offset1:6
	v_cvt_f32_f16_sdwa v14, v17 dst_sel:DWORD dst_unused:UNUSED_PAD src0_sel:WORD_1
	v_pk_mul_f32 v[6:7], v[8:9], s[38:39] op_sel_hi:[1,0]
	ds_write2_b32 v144, v6, v7 offset0:7 offset1:8
	v_pk_mul_f32 v[6:7], v[18:19], s[38:39] op_sel_hi:[1,0]
	ds_write2_b32 v144, v6, v7 offset0:9 offset1:10
	v_cvt_f32_f16_sdwa v6, v15 dst_sel:DWORD dst_unused:UNUSED_PAD src0_sel:WORD_1
	v_cvt_f32_f16_e32 v7, v16
	v_cvt_f32_f16_sdwa v8, v16 dst_sel:DWORD dst_unused:UNUSED_PAD src0_sel:WORD_1
	v_cvt_f32_f16_e32 v9, v17
	v_mul_f32_e32 v14, 0x3b800000, v14
	v_pk_mul_f32 v[6:7], v[6:7], s[38:39] op_sel_hi:[1,0]
	ds_write2_b32 v144, v6, v7 offset0:11 offset1:12
	v_pk_mul_f32 v[6:7], v[8:9], s[38:39] op_sel_hi:[1,0]
	ds_write2_b32 v144, v6, v7 offset0:13 offset1:14
	v_cvt_f32_f16_sdwa v6, v10 dst_sel:DWORD dst_unused:UNUSED_PAD src0_sel:WORD_1
	v_cvt_f32_f16_e32 v7, v11
	v_cvt_f32_f16_sdwa v8, v11 dst_sel:DWORD dst_unused:UNUSED_PAD src0_sel:WORD_1
	v_cvt_f32_f16_e32 v9, v12
	ds_write2_b32 v144, v20, v14 offset1:15
	v_pk_mul_f32 v[6:7], v[6:7], s[38:39] op_sel_hi:[1,0]
	s_nop 0
	v_pk_mov_b32 v[6:7], v[6:7], v[6:7] op_sel:[1,0]
	ds_write_b64 v145, v[6:7]
	v_pk_mul_f32 v[6:7], v[8:9], s[38:39] op_sel_hi:[1,0]
	v_cvt_f32_f16_sdwa v8, v12 dst_sel:DWORD dst_unused:UNUSED_PAD src0_sel:WORD_1
	v_cvt_f32_f16_e32 v9, v13
	v_pk_mov_b32 v[6:7], v[6:7], v[6:7] op_sel:[1,0]
	ds_write_b64 v147, v[6:7]
	v_cvt_f32_f16_sdwa v7, v13 dst_sel:DWORD dst_unused:UNUSED_PAD src0_sel:WORD_1
	v_pk_mul_f32 v[8:9], v[8:9], s[38:39] op_sel_hi:[1,0]
	v_cvt_f32_f16_e32 v6, v2
	v_pk_mov_b32 v[8:9], v[8:9], v[8:9] op_sel:[1,0]
	ds_write_b64 v148, v[8:9]
	v_cvt_f32_f16_sdwa v8, v2 dst_sel:DWORD dst_unused:UNUSED_PAD src0_sel:WORD_1
	v_cvt_f32_f16_e32 v9, v3
	v_cvt_f32_f16_sdwa v2, v3 dst_sel:DWORD dst_unused:UNUSED_PAD src0_sel:WORD_1
	v_cvt_f32_f16_e32 v3, v4
	v_pk_mul_f32 v[6:7], v[6:7], s[38:39] op_sel_hi:[1,0]
	ds_write_b64 v149, v[6:7]
	v_pk_mul_f32 v[6:7], v[8:9], s[38:39] op_sel_hi:[1,0]
	v_pk_mul_f32 v[2:3], v[2:3], s[38:39] op_sel_hi:[1,0]
	v_pk_mov_b32 v[6:7], v[6:7], v[6:7] op_sel:[1,0]
	ds_write_b64 v150, v[6:7]
	v_pk_mov_b32 v[2:3], v[2:3], v[2:3] op_sel:[1,0]
	v_cvt_f32_f16_sdwa v6, v4 dst_sel:DWORD dst_unused:UNUSED_PAD src0_sel:WORD_1
	v_cvt_f32_f16_e32 v7, v5
	ds_write_b64 v151, v[2:3]
	v_cvt_f32_f16_sdwa v3, v5 dst_sel:DWORD dst_unused:UNUSED_PAD src0_sel:WORD_1
	v_cvt_f32_f16_e32 v2, v43
	v_pk_mul_f32 v[4:5], v[6:7], s[38:39] op_sel_hi:[1,0]
	v_pk_mul_f32 v[2:3], v[2:3], s[38:39] op_sel_hi:[1,0]
	v_pk_mov_b32 v[4:5], v[4:5], v[4:5] op_sel:[1,0]
	ds_write_b64 v152, v[4:5]
	ds_write_b64 v153, v[2:3]
	v_mov_b32_e32 v2, v1
	s_waitcnt lgkmcnt(0)
	s_barrier
	s_nop 0
	v_and_b32_e32 v3, 0x1ff, v2
	v_lshlrev_b32_e32 v2, 5, v2
	v_and_or_b32 v2, v2, s3, v3
	v_cvt_f32_u32_e32 v4, v3
	v_ashrrev_i32_e32 v3, 5, v2
	v_lshlrev_b32_e32 v5, 3, v2
	v_lshlrev_b32_e32 v3, 3, v3
	v_add3_u32 v40, 0, v5, v3
	v_add_u32_e32 v155, 0x10800, v40
	ds_read_b64 v[156:157], v40
	ds_read_b64 v[158:159], v40 offset:4224
	ds_read_b64 v[160:161], v40 offset:8448
	ds_read_b64 v[162:163], v40 offset:12672
	ds_read_b64 v[164:165], v40 offset:16896
	ds_read_b64 v[166:167], v40 offset:21120
	ds_read_b64 v[168:169], v40 offset:25344
	ds_read_b64 v[170:171], v40 offset:29568
	ds_read_b64 v[172:173], v40 offset:33792
	ds_read_b64 v[174:175], v40 offset:38016
	ds_read_b64 v[176:177], v40 offset:42240
	ds_read_b64 v[178:179], v40 offset:46464
	ds_read_b64 v[180:181], v40 offset:50688
	ds_read_b64 v[182:183], v40 offset:54912
	ds_read_b64 v[184:185], v40 offset:59136
	ds_read_b64 v[186:187], v40 offset:63360
	v_add_u32_e32 v201, 0x11880, v40
	v_add_u32_e32 v224, 0x12900, v40
	v_add_u32_e32 v225, 0x13980, v40
	ds_read_b64 v[188:189], v155
	ds_read_b64 v[190:191], v201
	ds_read_b64 v[192:193], v224
	ds_read_b64 v[194:195], v225
	v_add_u32_e32 v226, 0x14a00, v40
	s_waitcnt lgkmcnt(3)
	v_pk_add_f32 v[222:223], v[156:157], v[188:189]
	v_pk_add_f32 v[156:157], v[156:157], v[188:189] neg_lo:[0,1] neg_hi:[0,1]
	s_waitcnt lgkmcnt(2)
	v_pk_add_f32 v[188:189], v[158:159], v[190:191]
	v_pk_add_f32 v[158:159], v[158:159], v[190:191] neg_lo:[0,1] neg_hi:[0,1]
	v_add_u32_e32 v227, 0x15a80, v40
	v_pk_mul_f32 v[190:191], v[158:159], s[46:47]
	v_add_u32_e32 v228, 0x16b00, v40
	v_pk_fma_f32 v[158:159], v[158:159], s[42:43], v[190:191] op_sel:[0,0,1] op_sel_hi:[1,0,0]
	s_waitcnt lgkmcnt(1)
	v_pk_add_f32 v[190:191], v[160:161], v[192:193]
	v_pk_add_f32 v[160:161], v[160:161], v[192:193] neg_lo:[0,1] neg_hi:[0,1]
	v_add_u32_e32 v229, 0x17b80, v40
	v_pk_mul_f32 v[192:193], v[160:161], s[62:63]
	ds_read_b64 v[196:197], v226
	ds_read_b64 v[198:199], v227
	ds_read_b64 v[202:203], v228
	ds_read_b64 v[204:205], v229
	v_pk_fma_f32 v[160:161], v[160:161], s[50:51], v[192:193] op_sel:[0,0,1] op_sel_hi:[1,0,0]
	s_waitcnt lgkmcnt(4)
	v_pk_add_f32 v[192:193], v[162:163], v[194:195]
	v_pk_add_f32 v[162:163], v[162:163], v[194:195] neg_lo:[0,1] neg_hi:[0,1]
	v_add_u32_e32 v230, 0x18c00, v40
	v_pk_mul_f32 v[194:195], v[162:163], s[66:67]
	v_add_u32_e32 v231, 0x19c80, v40
	v_pk_fma_f32 v[162:163], v[162:163], s[64:65], v[194:195] op_sel:[0,0,1] op_sel_hi:[1,0,0]
	s_waitcnt lgkmcnt(3)
	v_pk_add_f32 v[194:195], v[164:165], v[196:197]
	v_pk_add_f32 v[164:165], v[164:165], v[196:197] neg_lo:[0,1] neg_hi:[0,1]
	v_add_u32_e32 v232, 0x1ad00, v40
	v_pk_mul_f32 v[196:197], v[164:165], s[68:69]
	v_add_u32_e32 v233, 0x1bd80, v40
	v_pk_fma_f32 v[164:165], v[164:165], s[10:11], v[196:197] op_sel:[0,0,1] op_sel_hi:[1,0,0]
	s_waitcnt lgkmcnt(2)
	v_pk_add_f32 v[196:197], v[166:167], v[198:199]
	v_pk_add_f32 v[166:167], v[166:167], v[198:199] neg_lo:[0,1] neg_hi:[0,1]
	ds_read_b64 v[206:207], v230
	ds_read_b64 v[208:209], v231
	ds_read_b64 v[210:211], v232
	ds_read_b64 v[212:213], v233
	v_pk_mul_f32 v[198:199], v[166:167], s[70:71]
	v_add_u32_e32 v234, 0x1ce00, v40
	v_pk_fma_f32 v[166:167], v[166:167], s[78:79], v[198:199] op_sel:[0,0,1] op_sel_hi:[1,0,0]
	s_waitcnt lgkmcnt(5)
	v_pk_add_f32 v[198:199], v[168:169], v[202:203]
	v_pk_add_f32 v[168:169], v[168:169], v[202:203] neg_lo:[0,1] neg_hi:[0,1]
	v_add_u32_e32 v235, 0x1de80, v40
	v_pk_mul_f32 v[202:203], v[168:169], s[72:73]
	v_add_u32_e32 v236, 0x1ef00, v40
	v_pk_fma_f32 v[168:169], v[168:169], s[76:77], v[202:203] op_sel:[0,0,1] op_sel_hi:[1,0,0]
	s_waitcnt lgkmcnt(4)
	v_pk_add_f32 v[202:203], v[170:171], v[204:205]
	v_pk_add_f32 v[170:171], v[170:171], v[204:205] neg_lo:[0,1] neg_hi:[0,1]
	v_add_u32_e32 v237, 0x1ff80, v40
	v_pk_mul_f32 v[204:205], v[170:171], s[40:41]
	ds_read_b64 v[214:215], v234
	ds_read_b64 v[216:217], v235
	ds_read_b64 v[218:219], v236
	ds_read_b64 v[220:221], v237
	v_pk_fma_f32 v[170:171], v[170:171], s[44:45], v[204:205] op_sel:[0,0,1] op_sel_hi:[1,0,0]
	s_waitcnt lgkmcnt(7)
	v_pk_add_f32 v[204:205], v[172:173], v[206:207]
	v_pk_add_f32 v[206:207], v[172:173], v[206:207] neg_lo:[0,1] neg_hi:[0,1]
	v_mul_f32_e32 v4, 0x38800000, v4
	s_waitcnt lgkmcnt(6)
	v_pk_add_f32 v[172:173], v[174:175], v[208:209]
	v_pk_add_f32 v[174:175], v[174:175], v[208:209] neg_lo:[0,1] neg_hi:[0,1]
	v_sin_f32_e32 v2, v4
	v_pk_mul_f32 v[208:209], v[174:175], s[40:41]
	v_cos_f32_e32 v4, v4
	v_pk_fma_f32 v[174:175], v[174:175], s[44:45], v[208:209] op_sel:[0,0,1] op_sel_hi:[1,0,0] neg_lo:[1,0,0] neg_hi:[1,0,0]
	s_waitcnt lgkmcnt(5)
	v_pk_add_f32 v[208:209], v[176:177], v[210:211]
	v_pk_add_f32 v[176:177], v[176:177], v[210:211] neg_lo:[0,1] neg_hi:[0,1]
	v_xor_b32_e32 v5, 0x80000000, v2
	v_pk_mul_f32 v[210:211], v[176:177], s[72:73]
	v_mov_b32_e32 v3, v5
	v_pk_fma_f32 v[176:177], v[176:177], s[76:77], v[210:211] op_sel:[0,0,1] op_sel_hi:[1,0,0] neg_lo:[1,0,0] neg_hi:[1,0,0]
	s_waitcnt lgkmcnt(4)
	v_pk_add_f32 v[210:211], v[178:179], v[212:213]
	v_pk_add_f32 v[178:179], v[178:179], v[212:213] neg_lo:[0,1] neg_hi:[0,1]
	v_pk_mul_f32 v[6:7], v[4:5], v[2:3] op_sel:[1,0] op_sel_hi:[0,1]
	v_pk_mul_f32 v[212:213], v[178:179], s[70:71]
	v_pk_fma_f32 v[6:7], v[4:5], v[4:5], v[6:7] op_sel_hi:[1,0,1]
	v_pk_fma_f32 v[178:179], v[178:179], s[78:79], v[212:213] op_sel:[0,0,1] op_sel_hi:[1,0,0] neg_lo:[1,0,0] neg_hi:[1,0,0]
	s_waitcnt lgkmcnt(3)
	v_pk_add_f32 v[212:213], v[180:181], v[214:215]
	v_pk_add_f32 v[180:181], v[180:181], v[214:215] neg_lo:[0,1] neg_hi:[0,1]
	v_pk_mul_f32 v[214:215], v[180:181], s[68:69]
	v_pk_fma_f32 v[180:181], v[180:181], s[10:11], v[214:215] op_sel:[0,0,1] op_sel_hi:[1,0,0] neg_lo:[1,0,0] neg_hi:[1,0,0]
	s_waitcnt lgkmcnt(2)
	v_pk_add_f32 v[214:215], v[182:183], v[216:217]
	v_pk_add_f32 v[182:183], v[182:183], v[216:217] neg_lo:[0,1] neg_hi:[0,1]
	v_pk_mul_f32 v[10:11], v[6:7], v[6:7] op_sel:[1,1] op_sel_hi:[0,1] neg_lo:[0,1]
	v_pk_mul_f32 v[216:217], v[182:183], s[66:67]
	v_pk_fma_f32 v[10:11], v[6:7], v[6:7], v[10:11] op_sel_hi:[1,0,1]
	v_pk_fma_f32 v[182:183], v[182:183], s[64:65], v[216:217] op_sel:[0,0,1] op_sel_hi:[1,0,0] neg_lo:[1,0,0] neg_hi:[1,0,0]
	s_waitcnt lgkmcnt(1)
	v_pk_add_f32 v[216:217], v[184:185], v[218:219]
	v_pk_add_f32 v[184:185], v[184:185], v[218:219] neg_lo:[0,1] neg_hi:[0,1]
	v_pk_mul_f32 v[218:219], v[184:185], s[62:63]
	v_pk_fma_f32 v[184:185], v[184:185], s[50:51], v[218:219] op_sel:[0,0,1] op_sel_hi:[1,0,0] neg_lo:[1,0,0] neg_hi:[1,0,0]
	s_waitcnt lgkmcnt(0)
	v_pk_add_f32 v[218:219], v[186:187], v[220:221]
	v_pk_add_f32 v[186:187], v[186:187], v[220:221] neg_lo:[0,1] neg_hi:[0,1]
	v_pk_mul_f32 v[26:27], v[10:11], v[10:11] op_sel:[1,1] op_sel_hi:[0,1] neg_lo:[0,1]
	v_pk_mul_f32 v[220:221], v[186:187], s[46:47]
	v_pk_fma_f32 v[26:27], v[10:11], v[10:11], v[26:27] op_sel_hi:[1,0,1]
	v_pk_fma_f32 v[186:187], v[186:187], s[42:43], v[220:221] op_sel:[0,0,1] op_sel_hi:[1,0,0] neg_lo:[1,0,0] neg_hi:[1,0,0]
	v_pk_add_f32 v[220:221], v[222:223], v[204:205]
	v_pk_add_f32 v[204:205], v[222:223], v[204:205] neg_lo:[0,1] neg_hi:[0,1]
	v_pk_add_f32 v[222:223], v[188:189], v[172:173]
	v_pk_add_f32 v[172:173], v[188:189], v[172:173] neg_lo:[0,1] neg_hi:[0,1]
	v_pk_mul_f32 v[50:51], v[10:11], v[26:27] op_sel:[1,1] op_sel_hi:[1,0] neg_lo:[1,0]
	v_pk_mul_f32 v[188:189], v[172:173], s[62:63]
	v_pk_fma_f32 v[50:51], v[10:11], v[26:27], v[50:51] op_sel_hi:[0,1,1]
	v_pk_fma_f32 v[172:173], v[172:173], s[50:51], v[188:189] op_sel:[0,0,1] op_sel_hi:[1,0,0]
	v_pk_add_f32 v[188:189], v[190:191], v[208:209]
	v_pk_add_f32 v[190:191], v[190:191], v[208:209] neg_lo:[0,1] neg_hi:[0,1]
	v_pk_mul_f32 v[66:67], v[10:11], v[50:51] op_sel:[1,1] op_sel_hi:[1,0] neg_lo:[1,0]
	v_pk_mul_f32 v[208:209], v[190:191], s[68:69]
	v_pk_fma_f32 v[66:67], v[10:11], v[50:51], v[66:67] op_sel_hi:[0,1,1]
	v_pk_fma_f32 v[190:191], v[190:191], s[10:11], v[208:209] op_sel:[0,0,1] op_sel_hi:[1,0,0]
	v_pk_add_f32 v[208:209], v[192:193], v[210:211]
	v_pk_add_f32 v[192:193], v[192:193], v[210:211] neg_lo:[0,1] neg_hi:[0,1]
	v_pk_mul_f32 v[82:83], v[10:11], v[66:67] op_sel:[1,1] op_sel_hi:[1,0] neg_lo:[1,0]
	v_pk_mul_f32 v[210:211], v[192:193], s[72:73]
	v_pk_fma_f32 v[82:83], v[10:11], v[66:67], v[82:83] op_sel_hi:[0,1,1]
	v_pk_fma_f32 v[192:193], v[192:193], s[76:77], v[210:211] op_sel:[0,0,1] op_sel_hi:[1,0,0]
	v_pk_add_f32 v[210:211], v[194:195], v[212:213]
	v_pk_add_f32 v[212:213], v[194:195], v[212:213] neg_lo:[0,1] neg_hi:[0,1]
	v_pk_mul_f32 v[98:99], v[10:11], v[82:83] op_sel:[1,1] op_sel_hi:[1,0] neg_lo:[1,0]
	v_pk_add_f32 v[194:195], v[196:197], v[214:215]
	v_pk_add_f32 v[196:197], v[196:197], v[214:215] neg_lo:[0,1] neg_hi:[0,1]
	v_pk_fma_f32 v[98:99], v[10:11], v[82:83], v[98:99] op_sel_hi:[0,1,1]
	v_pk_mul_f32 v[214:215], v[196:197], s[72:73]
	v_pk_mul_f32 v[114:115], v[10:11], v[98:99] op_sel:[1,1] op_sel_hi:[1,0] neg_lo:[1,0]
	v_pk_fma_f32 v[196:197], v[196:197], s[76:77], v[214:215] op_sel:[0,0,1] op_sel_hi:[1,0,0] neg_lo:[1,0,0] neg_hi:[1,0,0]
	v_pk_add_f32 v[214:215], v[198:199], v[216:217]
	v_pk_add_f32 v[198:199], v[198:199], v[216:217] neg_lo:[0,1] neg_hi:[0,1]
	v_pk_mul_f32 v[8:9], v[2:3], v[6:7] op_sel:[0,1] op_sel_hi:[1,0]
	v_pk_mul_f32 v[216:217], v[198:199], s[68:69]
	v_pk_fma_f32 v[114:115], v[10:11], v[98:99], v[114:115] op_sel_hi:[0,1,1]
	v_pk_fma_f32 v[198:199], v[198:199], s[10:11], v[216:217] op_sel:[0,0,1] op_sel_hi:[1,0,0] neg_lo:[1,0,0] neg_hi:[1,0,0]
	v_pk_add_f32 v[216:217], v[202:203], v[218:219]
	v_pk_add_f32 v[202:203], v[202:203], v[218:219] neg_lo:[0,1] neg_hi:[0,1]
	v_pk_fma_f32 v[8:9], v[4:5], v[6:7], v[8:9] op_sel_hi:[0,1,1]
	v_pk_mul_f32 v[218:219], v[202:203], s[62:63]
	v_pk_mul_f32 v[16:17], v[2:3], v[10:11] op_sel:[0,1] op_sel_hi:[1,0]
	v_pk_fma_f32 v[202:203], v[202:203], s[50:51], v[218:219] op_sel:[0,0,1] op_sel_hi:[1,0,0] neg_lo:[1,0,0] neg_hi:[1,0,0]
	v_pk_add_f32 v[218:219], v[156:157], v[206:207] op_sel:[0,1] op_sel_hi:[1,0] neg_hi:[0,1]
	v_pk_add_f32 v[156:157], v[156:157], v[206:207] op_sel:[0,1] op_sel_hi:[1,0] neg_lo:[0,1]
	v_pk_add_f32 v[206:207], v[158:159], v[174:175]
	v_pk_add_f32 v[158:159], v[158:159], v[174:175] neg_lo:[0,1] neg_hi:[0,1]
	v_pk_mul_f32 v[30:31], v[2:3], v[26:27] op_sel:[0,1] op_sel_hi:[1,0]
	v_pk_mul_f32 v[174:175], v[158:159], s[62:63]
	v_pk_mul_f32 v[54:55], v[2:3], v[50:51] op_sel:[0,1] op_sel_hi:[1,0]
	v_pk_fma_f32 v[158:159], v[158:159], s[50:51], v[174:175] op_sel:[0,0,1] op_sel_hi:[1,0,0]
	v_pk_add_f32 v[174:175], v[160:161], v[176:177]
	v_pk_add_f32 v[160:161], v[160:161], v[176:177] neg_lo:[0,1] neg_hi:[0,1]
	v_pk_mul_f32 v[70:71], v[2:3], v[66:67] op_sel:[0,1] op_sel_hi:[1,0]
	v_pk_mul_f32 v[176:177], v[160:161], s[68:69]
	v_pk_mul_f32 v[86:87], v[2:3], v[82:83] op_sel:[0,1] op_sel_hi:[1,0]
	v_pk_fma_f32 v[160:161], v[160:161], s[10:11], v[176:177] op_sel:[0,0,1] op_sel_hi:[1,0,0]
	v_pk_add_f32 v[176:177], v[162:163], v[178:179]
	v_pk_add_f32 v[162:163], v[162:163], v[178:179] neg_lo:[0,1] neg_hi:[0,1]
	v_pk_mul_f32 v[102:103], v[2:3], v[98:99] op_sel:[0,1] op_sel_hi:[1,0]
	v_pk_mul_f32 v[178:179], v[162:163], s[72:73]
	v_pk_mul_f32 v[118:119], v[2:3], v[114:115] op_sel:[0,1] op_sel_hi:[1,0]
	v_pk_fma_f32 v[162:163], v[162:163], s[76:77], v[178:179] op_sel:[0,0,1] op_sel_hi:[1,0,0]
	v_pk_add_f32 v[178:179], v[164:165], v[180:181]
	v_pk_add_f32 v[180:181], v[164:165], v[180:181] neg_lo:[0,1] neg_hi:[0,1]
	v_pk_add_f32 v[164:165], v[166:167], v[182:183]
	v_pk_add_f32 v[166:167], v[166:167], v[182:183] neg_lo:[0,1] neg_hi:[0,1]
	v_pk_mul_f32 v[182:183], v[166:167], s[72:73]
	v_pk_fma_f32 v[16:17], v[4:5], v[10:11], v[16:17] op_sel_hi:[0,1,1]
	v_pk_fma_f32 v[166:167], v[166:167], s[76:77], v[182:183] op_sel:[0,0,1] op_sel_hi:[1,0,0] neg_lo:[1,0,0] neg_hi:[1,0,0]
	v_pk_add_f32 v[182:183], v[168:169], v[184:185]
	v_pk_add_f32 v[168:169], v[168:169], v[184:185] neg_lo:[0,1] neg_hi:[0,1]
	v_pk_mul_f32 v[18:19], v[6:7], v[10:11] op_sel:[1,1] op_sel_hi:[1,0] neg_lo:[1,0]
	v_pk_mul_f32 v[184:185], v[168:169], s[68:69]
	v_pk_fma_f32 v[30:31], v[4:5], v[26:27], v[30:31] op_sel_hi:[0,1,1]
	v_pk_fma_f32 v[168:169], v[168:169], s[10:11], v[184:185] op_sel:[0,0,1] op_sel_hi:[1,0,0] neg_lo:[1,0,0] neg_hi:[1,0,0]
	v_pk_add_f32 v[184:185], v[170:171], v[186:187]
	v_pk_add_f32 v[170:171], v[170:171], v[186:187] neg_lo:[0,1] neg_hi:[0,1]
	v_pk_mul_f32 v[42:43], v[6:7], v[26:27] op_sel:[1,1] op_sel_hi:[1,0] neg_lo:[1,0]
	v_pk_mul_f32 v[186:187], v[170:171], s[62:63]
	v_pk_fma_f32 v[54:55], v[4:5], v[50:51], v[54:55] op_sel_hi:[0,1,1]
	v_pk_fma_f32 v[170:171], v[170:171], s[50:51], v[186:187] op_sel:[0,0,1] op_sel_hi:[1,0,0] neg_lo:[1,0,0] neg_hi:[1,0,0]
	v_pk_add_f32 v[186:187], v[220:221], v[210:211]
	v_pk_add_f32 v[210:211], v[220:221], v[210:211] neg_lo:[0,1] neg_hi:[0,1]
	v_pk_add_f32 v[220:221], v[222:223], v[194:195]
	v_pk_add_f32 v[194:195], v[222:223], v[194:195] neg_lo:[0,1] neg_hi:[0,1]
	v_pk_mul_f32 v[58:59], v[6:7], v[50:51] op_sel:[1,1] op_sel_hi:[1,0] neg_lo:[1,0]
	v_pk_mul_f32 v[222:223], v[194:195], s[68:69]
	v_pk_fma_f32 v[70:71], v[4:5], v[66:67], v[70:71] op_sel_hi:[0,1,1]
	v_pk_fma_f32 v[194:195], v[194:195], s[10:11], v[222:223] op_sel:[0,0,1] op_sel_hi:[1,0,0]
	v_pk_add_f32 v[222:223], v[188:189], v[214:215]
	v_pk_add_f32 v[214:215], v[188:189], v[214:215] neg_lo:[0,1] neg_hi:[0,1]
	v_pk_mul_f32 v[74:75], v[6:7], v[66:67] op_sel:[1,1] op_sel_hi:[1,0] neg_lo:[1,0]
	v_pk_add_f32 v[188:189], v[208:209], v[216:217]
	v_pk_add_f32 v[208:209], v[208:209], v[216:217] neg_lo:[0,1] neg_hi:[0,1]
	v_pk_fma_f32 v[86:87], v[4:5], v[82:83], v[86:87] op_sel_hi:[0,1,1]
	v_pk_mul_f32 v[216:217], v[208:209], s[68:69]
	v_pk_mul_f32 v[90:91], v[6:7], v[82:83] op_sel:[1,1] op_sel_hi:[1,0] neg_lo:[1,0]
	v_pk_fma_f32 v[208:209], v[208:209], s[10:11], v[216:217] op_sel:[0,0,1] op_sel_hi:[1,0,0] neg_lo:[1,0,0] neg_hi:[1,0,0]
	v_pk_add_f32 v[216:217], v[204:205], v[212:213] op_sel:[0,1] op_sel_hi:[1,0] neg_hi:[0,1]
	v_pk_add_f32 v[204:205], v[204:205], v[212:213] op_sel:[0,1] op_sel_hi:[1,0] neg_lo:[0,1]
	v_pk_add_f32 v[212:213], v[172:173], v[196:197]
	v_pk_add_f32 v[172:173], v[172:173], v[196:197] neg_lo:[0,1] neg_hi:[0,1]
	v_pk_fma_f32 v[102:103], v[4:5], v[98:99], v[102:103] op_sel_hi:[0,1,1]
	v_pk_mul_f32 v[196:197], v[172:173], s[68:69]
	v_pk_mul_f32 v[106:107], v[6:7], v[98:99] op_sel:[1,1] op_sel_hi:[1,0] neg_lo:[1,0]
	v_pk_fma_f32 v[172:173], v[172:173], s[10:11], v[196:197] op_sel:[0,0,1] op_sel_hi:[1,0,0]
	v_pk_add_f32 v[196:197], v[190:191], v[198:199]
	v_pk_add_f32 v[198:199], v[190:191], v[198:199] neg_lo:[0,1] neg_hi:[0,1]
	v_pk_fma_f32 v[118:119], v[4:5], v[114:115], v[118:119] op_sel_hi:[0,1,1]
	v_pk_add_f32 v[190:191], v[192:193], v[202:203]
	v_pk_add_f32 v[192:193], v[192:193], v[202:203] neg_lo:[0,1] neg_hi:[0,1]
	v_pk_mul_f32 v[122:123], v[6:7], v[114:115] op_sel:[1,1] op_sel_hi:[1,0] neg_lo:[1,0]
	v_pk_mul_f32 v[202:203], v[192:193], s[68:69]
	v_pk_fma_f32 v[18:19], v[6:7], v[10:11], v[18:19] op_sel_hi:[0,1,1]
	v_pk_fma_f32 v[192:193], v[192:193], s[10:11], v[202:203] op_sel:[0,0,1] op_sel_hi:[1,0,0] neg_lo:[1,0,0] neg_hi:[1,0,0]
	v_pk_add_f32 v[202:203], v[218:219], v[178:179]
	v_pk_add_f32 v[178:179], v[218:219], v[178:179] neg_lo:[0,1] neg_hi:[0,1]
	v_pk_add_f32 v[218:219], v[206:207], v[164:165]
	v_pk_add_f32 v[164:165], v[206:207], v[164:165] neg_lo:[0,1] neg_hi:[0,1]
	v_pk_mul_f32 v[22:23], v[10:11], v[8:9] op_sel:[1,1] op_sel_hi:[0,1] neg_lo:[0,1]
	v_pk_mul_f32 v[206:207], v[164:165], s[68:69]
	v_pk_fma_f32 v[42:43], v[6:7], v[26:27], v[42:43] op_sel_hi:[0,1,1]
	v_pk_fma_f32 v[164:165], v[164:165], s[10:11], v[206:207] op_sel:[0,0,1] op_sel_hi:[1,0,0]
	v_pk_add_f32 v[206:207], v[174:175], v[182:183]
	v_pk_add_f32 v[182:183], v[174:175], v[182:183] neg_lo:[0,1] neg_hi:[0,1]
	v_pk_mul_f32 v[46:47], v[8:9], v[26:27] op_sel:[1,1] op_sel_hi:[1,0] neg_lo:[1,0]
	v_pk_add_f32 v[174:175], v[176:177], v[184:185]
	v_pk_add_f32 v[176:177], v[176:177], v[184:185] neg_lo:[0,1] neg_hi:[0,1]
	v_pk_fma_f32 v[58:59], v[6:7], v[50:51], v[58:59] op_sel_hi:[0,1,1]
	v_pk_mul_f32 v[184:185], v[176:177], s[68:69]
	v_pk_mul_f32 v[62:63], v[8:9], v[50:51] op_sel:[1,1] op_sel_hi:[1,0] neg_lo:[1,0]
	v_pk_fma_f32 v[176:177], v[176:177], s[10:11], v[184:185] op_sel:[0,0,1] op_sel_hi:[1,0,0] neg_lo:[1,0,0] neg_hi:[1,0,0]
	v_pk_add_f32 v[184:185], v[156:157], v[180:181] op_sel:[0,1] op_sel_hi:[1,0] neg_hi:[0,1]
	v_pk_add_f32 v[156:157], v[156:157], v[180:181] op_sel:[0,1] op_sel_hi:[1,0] neg_lo:[0,1]
	v_pk_add_f32 v[180:181], v[158:159], v[166:167]
	v_pk_add_f32 v[158:159], v[158:159], v[166:167] neg_lo:[0,1] neg_hi:[0,1]
	v_pk_fma_f32 v[74:75], v[6:7], v[66:67], v[74:75] op_sel_hi:[0,1,1]
	v_pk_mul_f32 v[166:167], v[158:159], s[68:69]
	v_pk_mul_f32 v[78:79], v[8:9], v[66:67] op_sel:[1,1] op_sel_hi:[1,0] neg_lo:[1,0]
	v_pk_fma_f32 v[158:159], v[158:159], s[10:11], v[166:167] op_sel:[0,0,1] op_sel_hi:[1,0,0]
	v_pk_add_f32 v[166:167], v[160:161], v[168:169]
	v_pk_add_f32 v[168:169], v[160:161], v[168:169] neg_lo:[0,1] neg_hi:[0,1]
	v_pk_fma_f32 v[90:91], v[6:7], v[82:83], v[90:91] op_sel_hi:[0,1,1]
	v_pk_add_f32 v[160:161], v[162:163], v[170:171]
	v_pk_add_f32 v[162:163], v[162:163], v[170:171] neg_lo:[0,1] neg_hi:[0,1]
	v_pk_mul_f32 v[94:95], v[8:9], v[82:83] op_sel:[1,1] op_sel_hi:[1,0] neg_lo:[1,0]
	v_pk_mul_f32 v[170:171], v[162:163], s[68:69]
	v_pk_fma_f32 v[106:107], v[6:7], v[98:99], v[106:107] op_sel_hi:[0,1,1]
	v_pk_fma_f32 v[162:163], v[162:163], s[10:11], v[170:171] op_sel:[0,0,1] op_sel_hi:[1,0,0] neg_lo:[1,0,0] neg_hi:[1,0,0]
	v_pk_add_f32 v[170:171], v[186:187], v[222:223]
	v_pk_add_f32 v[186:187], v[186:187], v[222:223] neg_lo:[0,1] neg_hi:[0,1]
	v_pk_add_f32 v[222:223], v[220:221], v[188:189]
	v_pk_add_f32 v[220:221], v[220:221], v[188:189] neg_lo:[0,1] neg_hi:[0,1]
	v_pk_mul_f32 v[110:111], v[8:9], v[98:99] op_sel:[1,1] op_sel_hi:[1,0] neg_lo:[1,0]
	v_pk_add_f32 v[188:189], v[210:211], v[214:215] op_sel:[0,1] op_sel_hi:[1,0] neg_hi:[0,1]
	v_pk_add_f32 v[210:211], v[210:211], v[214:215] op_sel:[0,1] op_sel_hi:[1,0] neg_lo:[0,1]
	v_pk_add_f32 v[214:215], v[194:195], v[208:209]
	v_pk_add_f32 v[208:209], v[194:195], v[208:209] neg_lo:[0,1] neg_hi:[0,1]
	v_pk_fma_f32 v[122:123], v[6:7], v[114:115], v[122:123] op_sel_hi:[0,1,1]
	v_pk_add_f32 v[194:195], v[216:217], v[196:197]
	v_pk_add_f32 v[196:197], v[216:217], v[196:197] neg_lo:[0,1] neg_hi:[0,1]
	v_pk_add_f32 v[216:217], v[212:213], v[190:191]
	v_pk_add_f32 v[212:213], v[212:213], v[190:191] neg_lo:[0,1] neg_hi:[0,1]
	v_pk_mul_f32 v[126:127], v[8:9], v[114:115] op_sel:[1,1] op_sel_hi:[1,0] neg_lo:[1,0]
	v_pk_add_f32 v[190:191], v[204:205], v[198:199] op_sel:[0,1] op_sel_hi:[1,0] neg_hi:[0,1]
	v_pk_add_f32 v[198:199], v[204:205], v[198:199] op_sel:[0,1] op_sel_hi:[1,0] neg_lo:[0,1]
	v_pk_add_f32 v[204:205], v[172:173], v[192:193]
	v_pk_add_f32 v[192:193], v[172:173], v[192:193] neg_lo:[0,1] neg_hi:[0,1]
	v_xor_b32_e32 v24, 0x80000000, v17
	v_pk_add_f32 v[172:173], v[202:203], v[206:207]
	v_pk_add_f32 v[202:203], v[202:203], v[206:207] neg_lo:[0,1] neg_hi:[0,1]
	v_pk_add_f32 v[206:207], v[218:219], v[174:175]
	v_pk_add_f32 v[218:219], v[218:219], v[174:175] neg_lo:[0,1] neg_hi:[0,1]
	v_xor_b32_e32 v28, 0x80000000, v19
	v_pk_add_f32 v[174:175], v[178:179], v[182:183] op_sel:[0,1] op_sel_hi:[1,0] neg_hi:[0,1]
	v_pk_add_f32 v[178:179], v[178:179], v[182:183] op_sel:[0,1] op_sel_hi:[1,0] neg_lo:[0,1]
	v_pk_add_f32 v[182:183], v[164:165], v[176:177]
	v_pk_add_f32 v[176:177], v[164:165], v[176:177] neg_lo:[0,1] neg_hi:[0,1]
	v_pk_fma_f32 v[22:23], v[10:11], v[8:9], v[22:23] op_sel_hi:[1,0,1]
	v_pk_add_f32 v[164:165], v[184:185], v[166:167]
	v_pk_add_f32 v[166:167], v[184:185], v[166:167] neg_lo:[0,1] neg_hi:[0,1]
	v_pk_add_f32 v[184:185], v[180:181], v[160:161]
	v_pk_add_f32 v[180:181], v[180:181], v[160:161] neg_lo:[0,1] neg_hi:[0,1]
	v_pk_fma_f32 v[46:47], v[8:9], v[26:27], v[46:47] op_sel_hi:[0,1,1]
	v_pk_add_f32 v[160:161], v[156:157], v[168:169] op_sel:[0,1] op_sel_hi:[1,0] neg_hi:[0,1]
	v_pk_add_f32 v[156:157], v[156:157], v[168:169] op_sel:[0,1] op_sel_hi:[1,0] neg_lo:[0,1]
	v_pk_add_f32 v[168:169], v[158:159], v[162:163]
	v_pk_add_f32 v[162:163], v[158:159], v[162:163] neg_lo:[0,1] neg_hi:[0,1]
	v_pk_fma_f32 v[62:63], v[8:9], v[50:51], v[62:63] op_sel_hi:[0,1,1]
	v_pk_add_f32 v[158:159], v[170:171], v[222:223]
	v_pk_add_f32 v[170:171], v[170:171], v[222:223] neg_lo:[0,1] neg_hi:[0,1]
	v_pk_add_f32 v[222:223], v[186:187], v[220:221] op_sel:[0,1] op_sel_hi:[1,0] neg_hi:[0,1]
	v_pk_add_f32 v[186:187], v[186:187], v[220:221] op_sel:[0,1] op_sel_hi:[1,0] neg_lo:[0,1]
	v_pk_add_f32 v[220:221], v[188:189], v[214:215]
	v_pk_add_f32 v[188:189], v[188:189], v[214:215] neg_lo:[0,1] neg_hi:[0,1]
	v_pk_add_f32 v[214:215], v[210:211], v[208:209] op_sel:[0,1] op_sel_hi:[1,0] neg_hi:[0,1]
	v_pk_add_f32 v[208:209], v[210:211], v[208:209] op_sel:[0,1] op_sel_hi:[1,0] neg_lo:[0,1]
	v_pk_add_f32 v[210:211], v[194:195], v[216:217]
	v_pk_add_f32 v[194:195], v[194:195], v[216:217] neg_lo:[0,1] neg_hi:[0,1]
	v_pk_add_f32 v[216:217], v[196:197], v[212:213] op_sel:[0,1] op_sel_hi:[1,0] neg_hi:[0,1]
	v_pk_add_f32 v[196:197], v[196:197], v[212:213] op_sel:[0,1] op_sel_hi:[1,0] neg_lo:[0,1]
	v_pk_add_f32 v[212:213], v[190:191], v[204:205]
	v_pk_add_f32 v[190:191], v[190:191], v[204:205] neg_lo:[0,1] neg_hi:[0,1]
	v_pk_add_f32 v[204:205], v[198:199], v[192:193] op_sel:[0,1] op_sel_hi:[1,0] neg_hi:[0,1]
	v_pk_add_f32 v[192:193], v[198:199], v[192:193] op_sel:[0,1] op_sel_hi:[1,0] neg_lo:[0,1]
	v_pk_add_f32 v[198:199], v[172:173], v[206:207]
	v_pk_add_f32 v[172:173], v[172:173], v[206:207] neg_lo:[0,1] neg_hi:[0,1]
	v_pk_mul_f32 v[2:3], v[2:3], v[198:199] op_sel:[0,1] op_sel_hi:[1,0]
	v_pk_add_f32 v[206:207], v[202:203], v[218:219] op_sel:[0,1] op_sel_hi:[1,0] neg_hi:[0,1]
	v_pk_add_f32 v[202:203], v[202:203], v[218:219] op_sel:[0,1] op_sel_hi:[1,0] neg_lo:[0,1]
	v_pk_add_f32 v[218:219], v[174:175], v[182:183]
	v_pk_add_f32 v[174:175], v[174:175], v[182:183] neg_lo:[0,1] neg_hi:[0,1]
	v_pk_add_f32 v[182:183], v[178:179], v[176:177] op_sel:[0,1] op_sel_hi:[1,0] neg_hi:[0,1]
	v_pk_add_f32 v[176:177], v[178:179], v[176:177] op_sel:[0,1] op_sel_hi:[1,0] neg_lo:[0,1]
	v_pk_add_f32 v[178:179], v[164:165], v[184:185]
	v_pk_fma_f32 v[2:3], v[4:5], v[198:199], v[2:3] op_sel_hi:[0,1,1]
	v_pk_mul_f32 v[4:5], v[6:7], v[210:211] op_sel:[1,1] op_sel_hi:[1,0] neg_lo:[1,0]
	v_pk_fma_f32 v[78:79], v[8:9], v[66:67], v[78:79] op_sel_hi:[0,1,1]
	v_pk_fma_f32 v[4:5], v[6:7], v[210:211], v[4:5] op_sel_hi:[0,1,1]
	v_pk_mul_f32 v[6:7], v[8:9], v[178:179] op_sel:[1,1] op_sel_hi:[1,0] neg_lo:[1,0]
	v_pk_fma_f32 v[94:95], v[8:9], v[82:83], v[94:95] op_sel_hi:[0,1,1]
	v_pk_fma_f32 v[110:111], v[8:9], v[98:99], v[110:111] op_sel_hi:[0,1,1]
	v_pk_fma_f32 v[126:127], v[8:9], v[114:115], v[126:127] op_sel_hi:[0,1,1]
	v_mov_b32_e32 v25, v17
	v_mov_b32_e32 v29, v19
	v_pk_fma_f32 v[6:7], v[8:9], v[178:179], v[6:7] op_sel_hi:[0,1,1]
	v_pk_mul_f32 v[8:9], v[10:11], v[220:221] op_sel:[1,1] op_sel_hi:[1,0] neg_lo:[1,0]
	v_pk_add_f32 v[164:165], v[164:165], v[184:185] neg_lo:[0,1] neg_hi:[0,1]
	v_pk_add_f32 v[184:185], v[166:167], v[180:181] op_sel:[0,1] op_sel_hi:[1,0] neg_hi:[0,1]
	v_pk_add_f32 v[166:167], v[166:167], v[180:181] op_sel:[0,1] op_sel_hi:[1,0] neg_lo:[0,1]
	v_pk_add_f32 v[180:181], v[160:161], v[168:169]
	v_pk_fma_f32 v[8:9], v[10:11], v[220:221], v[8:9] op_sel_hi:[0,1,1]
	v_pk_mul_f32 v[10:11], v[24:25], v[218:219] op_sel:[0,1] op_sel_hi:[1,0]
	v_pk_mul_f32 v[12:13], v[28:29], v[212:213] op_sel:[0,1] op_sel_hi:[1,0]
	v_pk_add_f32 v[160:161], v[160:161], v[168:169] neg_lo:[0,1] neg_hi:[0,1]
	v_pk_add_f32 v[168:169], v[156:157], v[162:163] op_sel:[0,1] op_sel_hi:[1,0] neg_hi:[0,1]
	v_pk_fma_f32 v[10:11], v[16:17], v[218:219], v[10:11] op_sel_hi:[0,1,1]
	v_pk_fma_f32 v[12:13], v[18:19], v[212:213], v[12:13] op_sel_hi:[0,1,1]
	v_pk_mul_f32 v[14:15], v[22:23], v[180:181] op_sel:[1,1] op_sel_hi:[1,0] neg_lo:[1,0]
	v_pk_mul_f32 v[16:17], v[26:27], v[222:223] op_sel:[1,1] op_sel_hi:[1,0] neg_lo:[1,0]
	v_pk_mul_f32 v[18:19], v[30:31], v[206:207] op_sel:[1,1] op_sel_hi:[1,0] neg_lo:[1,0]
	v_pk_mul_f32 v[20:21], v[42:43], v[216:217] op_sel:[1,1] op_sel_hi:[1,0] neg_lo:[1,0]
	v_xor_b32_e32 v84, 0x80000000, v75
	v_xor_b32_e32 v88, 0x80000000, v79
	v_xor_b32_e32 v92, 0x80000000, v83
	v_xor_b32_e32 v96, 0x80000000, v87
	v_xor_b32_e32 v100, 0x80000000, v91
	v_xor_b32_e32 v104, 0x80000000, v95
	v_xor_b32_e32 v108, 0x80000000, v99
	v_xor_b32_e32 v112, 0x80000000, v103
	v_xor_b32_e32 v116, 0x80000000, v107
	v_xor_b32_e32 v120, 0x80000000, v111
	v_xor_b32_e32 v124, 0x80000000, v115
	v_xor_b32_e32 v128, 0x80000000, v119
	v_xor_b32_e32 v130, 0x80000000, v123
	v_xor_b32_e32 v132, 0x80000000, v127
	v_mov_b32_e32 v85, v75
	v_mov_b32_e32 v89, v79
	v_mov_b32_e32 v93, v83
	v_mov_b32_e32 v97, v87
	v_mov_b32_e32 v101, v91
	v_mov_b32_e32 v105, v95
	v_mov_b32_e32 v109, v99
	v_mov_b32_e32 v113, v103
	v_mov_b32_e32 v117, v107
	v_mov_b32_e32 v121, v111
	v_mov_b32_e32 v125, v115
	v_mov_b32_e32 v129, v119
	v_mov_b32_e32 v131, v123
	v_mov_b32_e32 v133, v127
	v_pk_add_f32 v[156:157], v[156:157], v[162:163] op_sel:[0,1] op_sel_hi:[1,0] neg_lo:[0,1]
	v_pk_fma_f32 v[14:15], v[22:23], v[180:181], v[14:15] op_sel_hi:[0,1,1]
	v_pk_fma_f32 v[16:17], v[26:27], v[222:223], v[16:17] op_sel_hi:[0,1,1]
	v_pk_fma_f32 v[18:19], v[30:31], v[206:207], v[18:19] op_sel_hi:[0,1,1]
	v_pk_fma_f32 v[20:21], v[42:43], v[216:217], v[20:21] op_sel_hi:[0,1,1]
	v_pk_mul_f32 v[22:23], v[46:47], v[184:185] op_sel:[1,1] op_sel_hi:[1,0] neg_lo:[1,0]
	v_pk_mul_f32 v[24:25], v[50:51], v[214:215] op_sel:[1,1] op_sel_hi:[1,0] neg_lo:[1,0]
	v_pk_mul_f32 v[26:27], v[54:55], v[182:183] op_sel:[1,1] op_sel_hi:[1,0] neg_lo:[1,0]
	v_pk_mul_f32 v[28:29], v[58:59], v[204:205] op_sel:[1,1] op_sel_hi:[1,0] neg_lo:[1,0]
	v_pk_mul_f32 v[30:31], v[62:63], v[168:169] op_sel:[1,1] op_sel_hi:[1,0] neg_lo:[1,0]
	v_pk_mul_f32 v[32:33], v[66:67], v[170:171] op_sel:[1,1] op_sel_hi:[1,0] neg_lo:[1,0]
	v_pk_mul_f32 v[42:43], v[70:71], v[172:173] op_sel:[1,1] op_sel_hi:[1,0] neg_lo:[1,0]
	v_pk_fma_f32 v[22:23], v[46:47], v[184:185], v[22:23] op_sel_hi:[0,1,1]
	v_pk_fma_f32 v[24:25], v[50:51], v[214:215], v[24:25] op_sel_hi:[0,1,1]
	v_pk_fma_f32 v[26:27], v[54:55], v[182:183], v[26:27] op_sel_hi:[0,1,1]
	v_pk_fma_f32 v[28:29], v[58:59], v[204:205], v[28:29] op_sel_hi:[0,1,1]
	v_pk_fma_f32 v[30:31], v[62:63], v[168:169], v[30:31] op_sel_hi:[0,1,1]
	v_pk_fma_f32 v[32:33], v[66:67], v[170:171], v[32:33] op_sel_hi:[0,1,1]
	v_pk_fma_f32 v[42:43], v[70:71], v[172:173], v[42:43] op_sel_hi:[0,1,1]
	v_pk_mul_f32 v[44:45], v[84:85], v[194:195] op_sel:[0,1] op_sel_hi:[1,0]
	v_pk_mul_f32 v[46:47], v[88:89], v[164:165] op_sel:[0,1] op_sel_hi:[1,0]
	v_pk_mul_f32 v[48:49], v[92:93], v[188:189] op_sel:[0,1] op_sel_hi:[1,0]
	v_pk_mul_f32 v[50:51], v[96:97], v[174:175] op_sel:[0,1] op_sel_hi:[1,0]
	v_pk_mul_f32 v[52:53], v[100:101], v[190:191] op_sel:[0,1] op_sel_hi:[1,0]
	v_pk_mul_f32 v[54:55], v[104:105], v[160:161] op_sel:[0,1] op_sel_hi:[1,0]
	v_pk_mul_f32 v[56:57], v[108:109], v[186:187] op_sel:[0,1] op_sel_hi:[1,0]
	v_pk_mul_f32 v[58:59], v[112:113], v[202:203] op_sel:[0,1] op_sel_hi:[1,0]
	v_pk_mul_f32 v[60:61], v[116:117], v[196:197] op_sel:[0,1] op_sel_hi:[1,0]
	v_pk_mul_f32 v[62:63], v[120:121], v[166:167] op_sel:[0,1] op_sel_hi:[1,0]
	v_pk_mul_f32 v[64:65], v[124:125], v[208:209] op_sel:[0,1] op_sel_hi:[1,0]
	v_pk_mul_f32 v[66:67], v[128:129], v[176:177] op_sel:[0,1] op_sel_hi:[1,0]
	v_pk_mul_f32 v[68:69], v[130:131], v[192:193] op_sel:[0,1] op_sel_hi:[1,0]
	v_pk_mul_f32 v[70:71], v[132:133], v[156:157] op_sel:[0,1] op_sel_hi:[1,0]
	v_pk_fma_f32 v[44:45], v[74:75], v[194:195], v[44:45] op_sel_hi:[0,1,1]
	v_pk_fma_f32 v[46:47], v[78:79], v[164:165], v[46:47] op_sel_hi:[0,1,1]
	v_pk_fma_f32 v[48:49], v[82:83], v[188:189], v[48:49] op_sel_hi:[0,1,1]
	v_pk_fma_f32 v[50:51], v[86:87], v[174:175], v[50:51] op_sel_hi:[0,1,1]
	v_pk_fma_f32 v[52:53], v[90:91], v[190:191], v[52:53] op_sel_hi:[0,1,1]
	v_pk_fma_f32 v[54:55], v[94:95], v[160:161], v[54:55] op_sel_hi:[0,1,1]
	v_pk_fma_f32 v[56:57], v[98:99], v[186:187], v[56:57] op_sel_hi:[0,1,1]
	v_pk_fma_f32 v[58:59], v[102:103], v[202:203], v[58:59] op_sel_hi:[0,1,1]
	v_pk_fma_f32 v[60:61], v[106:107], v[196:197], v[60:61] op_sel_hi:[0,1,1]
	v_pk_fma_f32 v[62:63], v[110:111], v[166:167], v[62:63] op_sel_hi:[0,1,1]
	v_pk_fma_f32 v[64:65], v[114:115], v[208:209], v[64:65] op_sel_hi:[0,1,1]
	v_pk_fma_f32 v[66:67], v[118:119], v[176:177], v[66:67] op_sel_hi:[0,1,1]
	v_pk_fma_f32 v[68:69], v[122:123], v[192:193], v[68:69] op_sel_hi:[0,1,1]
	v_pk_fma_f32 v[70:71], v[126:127], v[156:157], v[70:71] op_sel_hi:[0,1,1]
	ds_write_b64 v40, v[158:159]
	ds_write_b64 v40, v[32:33] offset:4224
	ds_write_b64 v40, v[16:17] offset:8448
	ds_write_b64 v40, v[56:57] offset:12672
	ds_write_b64 v40, v[8:9] offset:16896
	ds_write_b64 v40, v[48:49] offset:21120
	ds_write_b64 v40, v[24:25] offset:25344
	ds_write_b64 v40, v[64:65] offset:29568
	ds_write_b64 v40, v[4:5] offset:33792
	ds_write_b64 v40, v[44:45] offset:38016
	ds_write_b64 v40, v[20:21] offset:42240
	ds_write_b64 v40, v[60:61] offset:46464
	ds_write_b64 v40, v[12:13] offset:50688
	ds_write_b64 v40, v[52:53] offset:54912
	ds_write_b64 v40, v[28:29] offset:59136
	ds_write_b64 v40, v[68:69] offset:63360
	ds_write_b64 v155, v[2:3]
	ds_write_b64 v201, v[42:43]
	ds_write_b64 v224, v[18:19]
	ds_write_b64 v225, v[58:59]
	ds_write_b64 v226, v[10:11]
	ds_write_b64 v227, v[50:51]
	ds_write_b64 v228, v[26:27]
	ds_write_b64 v229, v[66:67]
	ds_write_b64 v230, v[6:7]
	ds_write_b64 v231, v[46:47]
	ds_write_b64 v232, v[22:23]
	ds_write_b64 v233, v[62:63]
	ds_write_b64 v234, v[14:15]
	ds_write_b64 v235, v[54:55]
	ds_write_b64 v236, v[30:31]
	ds_write_b64 v237, v[70:71]
	v_mov_b32_e32 v2, v1
	s_waitcnt lgkmcnt(0)
	s_barrier
	s_nop 0
	v_and_b32_e32 v3, 15, v2
	v_lshlrev_b32_e32 v2, 5, v2
	v_and_b32_e32 v4, 0xfffffe00, v2
	v_lshl_add_u32 v5, v4, 3, 0
	v_lshlrev_b32_e32 v6, 3, v3
	v_ashrrev_i32_e32 v7, 2, v4
	v_add3_u32 v40, v5, v6, v7
	v_add_u32_e32 v155, 0x800, v40
	ds_read2_b64 v[156:159], v40 offset1:16
	ds_read2_b64 v[160:163], v40 offset0:33 offset1:49
	ds_read2_b64 v[164:167], v40 offset0:66 offset1:82
	ds_read2_b64 v[168:171], v40 offset0:99 offset1:115
	ds_read2_b64 v[172:175], v40 offset0:132 offset1:148
	ds_read2_b64 v[176:179], v40 offset0:165 offset1:181
	ds_read2_b64 v[180:183], v40 offset0:198 offset1:214
	ds_read2_b64 v[184:187], v40 offset0:231 offset1:247
	ds_read2_b64 v[188:191], v155 offset0:8 offset1:24
	ds_read2_b64 v[192:195], v155 offset0:41 offset1:57
	ds_read2_b64 v[196:199], v155 offset0:74 offset1:90
	ds_read2_b64 v[202:205], v155 offset0:107 offset1:123
	ds_read2_b64 v[206:209], v155 offset0:140 offset1:156
	ds_read2_b64 v[210:213], v155 offset0:173 offset1:189
	ds_read2_b64 v[214:217], v155 offset0:206 offset1:222
	ds_read2_b64 v[218:221], v155 offset0:239 offset1:255
	s_waitcnt lgkmcnt(7)
	v_pk_add_f32 v[222:223], v[156:157], v[188:189]
	v_pk_add_f32 v[156:157], v[156:157], v[188:189] neg_lo:[0,1] neg_hi:[0,1]
	v_pk_add_f32 v[188:189], v[158:159], v[190:191]
	v_pk_add_f32 v[158:159], v[158:159], v[190:191] neg_lo:[0,1] neg_hi:[0,1]
	v_cvt_f32_ubyte0_e32 v2, v3
	v_pk_mul_f32 v[190:191], v[158:159], s[46:47]
	v_mul_f32_e32 v3, 0x3b000000, v2
	v_pk_fma_f32 v[158:159], v[158:159], s[42:43], v[190:191] op_sel:[0,0,1] op_sel_hi:[1,0,0]
	s_waitcnt lgkmcnt(6)
	v_pk_add_f32 v[190:191], v[160:161], v[192:193]
	v_pk_add_f32 v[160:161], v[160:161], v[192:193] neg_lo:[0,1] neg_hi:[0,1]
	v_sin_f32_e32 v2, v3
	v_pk_mul_f32 v[192:193], v[160:161], s[62:63]
	v_cos_f32_e32 v4, v3
	v_pk_fma_f32 v[160:161], v[160:161], s[50:51], v[192:193] op_sel:[0,0,1] op_sel_hi:[1,0,0]
	v_pk_add_f32 v[192:193], v[162:163], v[194:195]
	v_pk_add_f32 v[162:163], v[162:163], v[194:195] neg_lo:[0,1] neg_hi:[0,1]
	v_xor_b32_e32 v5, 0x80000000, v2
	v_pk_mul_f32 v[194:195], v[162:163], s[66:67]
	v_mov_b32_e32 v3, v5
	v_pk_fma_f32 v[162:163], v[162:163], s[64:65], v[194:195] op_sel:[0,0,1] op_sel_hi:[1,0,0]
	s_waitcnt lgkmcnt(5)
	v_pk_add_f32 v[194:195], v[164:165], v[196:197]
	v_pk_add_f32 v[164:165], v[164:165], v[196:197] neg_lo:[0,1] neg_hi:[0,1]
	v_pk_mul_f32 v[6:7], v[4:5], v[2:3] op_sel:[1,0] op_sel_hi:[0,1]
	v_pk_mul_f32 v[196:197], v[164:165], s[68:69]
	v_pk_fma_f32 v[6:7], v[4:5], v[4:5], v[6:7] op_sel_hi:[1,0,1]
	v_pk_fma_f32 v[164:165], v[164:165], s[10:11], v[196:197] op_sel:[0,0,1] op_sel_hi:[1,0,0]
	v_pk_add_f32 v[196:197], v[166:167], v[198:199]
	v_pk_add_f32 v[166:167], v[166:167], v[198:199] neg_lo:[0,1] neg_hi:[0,1]
	v_pk_mul_f32 v[198:199], v[166:167], s[70:71]
	v_pk_fma_f32 v[166:167], v[166:167], s[78:79], v[198:199] op_sel:[0,0,1] op_sel_hi:[1,0,0]
	s_waitcnt lgkmcnt(4)
	v_pk_add_f32 v[198:199], v[168:169], v[202:203]
	v_pk_add_f32 v[168:169], v[168:169], v[202:203] neg_lo:[0,1] neg_hi:[0,1]
	v_pk_mul_f32 v[10:11], v[6:7], v[6:7] op_sel:[1,1] op_sel_hi:[0,1] neg_lo:[0,1]
	v_pk_mul_f32 v[202:203], v[168:169], s[72:73]
	v_pk_fma_f32 v[10:11], v[6:7], v[6:7], v[10:11] op_sel_hi:[1,0,1]
	v_pk_fma_f32 v[168:169], v[168:169], s[76:77], v[202:203] op_sel:[0,0,1] op_sel_hi:[1,0,0]
	v_pk_add_f32 v[202:203], v[170:171], v[204:205]
	v_pk_add_f32 v[170:171], v[170:171], v[204:205] neg_lo:[0,1] neg_hi:[0,1]
	v_pk_mul_f32 v[204:205], v[170:171], s[40:41]
	v_pk_fma_f32 v[170:171], v[170:171], s[44:45], v[204:205] op_sel:[0,0,1] op_sel_hi:[1,0,0]
	s_waitcnt lgkmcnt(3)
	v_pk_add_f32 v[204:205], v[172:173], v[206:207]
	v_pk_add_f32 v[206:207], v[172:173], v[206:207] neg_lo:[0,1] neg_hi:[0,1]
	v_pk_mul_f32 v[26:27], v[10:11], v[10:11] op_sel:[1,1] op_sel_hi:[0,1] neg_lo:[0,1]
	v_pk_add_f32 v[172:173], v[174:175], v[208:209]
	v_pk_add_f32 v[174:175], v[174:175], v[208:209] neg_lo:[0,1] neg_hi:[0,1]
	v_pk_fma_f32 v[26:27], v[10:11], v[10:11], v[26:27] op_sel_hi:[1,0,1]
	v_pk_mul_f32 v[208:209], v[174:175], s[40:41]
	v_pk_mul_f32 v[50:51], v[10:11], v[26:27] op_sel:[1,1] op_sel_hi:[1,0] neg_lo:[1,0]
	v_pk_fma_f32 v[174:175], v[174:175], s[44:45], v[208:209] op_sel:[0,0,1] op_sel_hi:[1,0,0] neg_lo:[1,0,0] neg_hi:[1,0,0]
	s_waitcnt lgkmcnt(2)
	v_pk_add_f32 v[208:209], v[176:177], v[210:211]
	v_pk_add_f32 v[176:177], v[176:177], v[210:211] neg_lo:[0,1] neg_hi:[0,1]
	v_pk_fma_f32 v[50:51], v[10:11], v[26:27], v[50:51] op_sel_hi:[0,1,1]
	v_pk_mul_f32 v[210:211], v[176:177], s[72:73]
	v_pk_mul_f32 v[66:67], v[10:11], v[50:51] op_sel:[1,1] op_sel_hi:[1,0] neg_lo:[1,0]
	v_pk_fma_f32 v[176:177], v[176:177], s[76:77], v[210:211] op_sel:[0,0,1] op_sel_hi:[1,0,0] neg_lo:[1,0,0] neg_hi:[1,0,0]
	v_pk_add_f32 v[210:211], v[178:179], v[212:213]
	v_pk_add_f32 v[178:179], v[178:179], v[212:213] neg_lo:[0,1] neg_hi:[0,1]
	v_pk_fma_f32 v[66:67], v[10:11], v[50:51], v[66:67] op_sel_hi:[0,1,1]
	v_pk_mul_f32 v[212:213], v[178:179], s[70:71]
	v_pk_mul_f32 v[82:83], v[10:11], v[66:67] op_sel:[1,1] op_sel_hi:[1,0] neg_lo:[1,0]
	v_pk_fma_f32 v[178:179], v[178:179], s[78:79], v[212:213] op_sel:[0,0,1] op_sel_hi:[1,0,0] neg_lo:[1,0,0] neg_hi:[1,0,0]
	s_waitcnt lgkmcnt(1)
	v_pk_add_f32 v[212:213], v[180:181], v[214:215]
	v_pk_add_f32 v[180:181], v[180:181], v[214:215] neg_lo:[0,1] neg_hi:[0,1]
	v_pk_fma_f32 v[82:83], v[10:11], v[66:67], v[82:83] op_sel_hi:[0,1,1]
	v_pk_mul_f32 v[214:215], v[180:181], s[68:69]
	v_pk_mul_f32 v[98:99], v[10:11], v[82:83] op_sel:[1,1] op_sel_hi:[1,0] neg_lo:[1,0]
	v_pk_fma_f32 v[180:181], v[180:181], s[10:11], v[214:215] op_sel:[0,0,1] op_sel_hi:[1,0,0] neg_lo:[1,0,0] neg_hi:[1,0,0]
	v_pk_add_f32 v[214:215], v[182:183], v[216:217]
	v_pk_add_f32 v[182:183], v[182:183], v[216:217] neg_lo:[0,1] neg_hi:[0,1]
	v_pk_fma_f32 v[98:99], v[10:11], v[82:83], v[98:99] op_sel_hi:[0,1,1]
	v_pk_mul_f32 v[216:217], v[182:183], s[66:67]
	v_pk_mul_f32 v[114:115], v[10:11], v[98:99] op_sel:[1,1] op_sel_hi:[1,0] neg_lo:[1,0]
	v_pk_fma_f32 v[182:183], v[182:183], s[64:65], v[216:217] op_sel:[0,0,1] op_sel_hi:[1,0,0] neg_lo:[1,0,0] neg_hi:[1,0,0]
	s_waitcnt lgkmcnt(0)
	v_pk_add_f32 v[216:217], v[184:185], v[218:219]
	v_pk_add_f32 v[184:185], v[184:185], v[218:219] neg_lo:[0,1] neg_hi:[0,1]
	v_pk_mul_f32 v[8:9], v[2:3], v[6:7] op_sel:[0,1] op_sel_hi:[1,0]
	v_pk_mul_f32 v[218:219], v[184:185], s[62:63]
	v_pk_fma_f32 v[114:115], v[10:11], v[98:99], v[114:115] op_sel_hi:[0,1,1]
	v_pk_fma_f32 v[184:185], v[184:185], s[50:51], v[218:219] op_sel:[0,0,1] op_sel_hi:[1,0,0] neg_lo:[1,0,0] neg_hi:[1,0,0]
	v_pk_add_f32 v[218:219], v[186:187], v[220:221]
	v_pk_add_f32 v[186:187], v[186:187], v[220:221] neg_lo:[0,1] neg_hi:[0,1]
	v_pk_fma_f32 v[8:9], v[4:5], v[6:7], v[8:9] op_sel_hi:[0,1,1]
	v_pk_mul_f32 v[220:221], v[186:187], s[46:47]
	v_pk_mul_f32 v[16:17], v[2:3], v[10:11] op_sel:[0,1] op_sel_hi:[1,0]
	v_pk_fma_f32 v[186:187], v[186:187], s[42:43], v[220:221] op_sel:[0,0,1] op_sel_hi:[1,0,0] neg_lo:[1,0,0] neg_hi:[1,0,0]
	v_pk_add_f32 v[220:221], v[222:223], v[204:205]
	v_pk_add_f32 v[204:205], v[222:223], v[204:205] neg_lo:[0,1] neg_hi:[0,1]
	v_pk_add_f32 v[222:223], v[188:189], v[172:173]
	v_pk_add_f32 v[172:173], v[188:189], v[172:173] neg_lo:[0,1] neg_hi:[0,1]
	v_pk_mul_f32 v[30:31], v[2:3], v[26:27] op_sel:[0,1] op_sel_hi:[1,0]
	v_pk_mul_f32 v[188:189], v[172:173], s[62:63]
	v_pk_mul_f32 v[54:55], v[2:3], v[50:51] op_sel:[0,1] op_sel_hi:[1,0]
	v_pk_fma_f32 v[172:173], v[172:173], s[50:51], v[188:189] op_sel:[0,0,1] op_sel_hi:[1,0,0]
	v_pk_add_f32 v[188:189], v[190:191], v[208:209]
	v_pk_add_f32 v[190:191], v[190:191], v[208:209] neg_lo:[0,1] neg_hi:[0,1]
	v_pk_mul_f32 v[70:71], v[2:3], v[66:67] op_sel:[0,1] op_sel_hi:[1,0]
	v_pk_mul_f32 v[208:209], v[190:191], s[68:69]
	v_pk_mul_f32 v[86:87], v[2:3], v[82:83] op_sel:[0,1] op_sel_hi:[1,0]
	v_pk_fma_f32 v[190:191], v[190:191], s[10:11], v[208:209] op_sel:[0,0,1] op_sel_hi:[1,0,0]
	v_pk_add_f32 v[208:209], v[192:193], v[210:211]
	v_pk_add_f32 v[192:193], v[192:193], v[210:211] neg_lo:[0,1] neg_hi:[0,1]
	v_pk_mul_f32 v[102:103], v[2:3], v[98:99] op_sel:[0,1] op_sel_hi:[1,0]
	v_pk_mul_f32 v[210:211], v[192:193], s[72:73]
	v_pk_mul_f32 v[118:119], v[2:3], v[114:115] op_sel:[0,1] op_sel_hi:[1,0]
	v_pk_fma_f32 v[192:193], v[192:193], s[76:77], v[210:211] op_sel:[0,0,1] op_sel_hi:[1,0,0]
	v_pk_add_f32 v[210:211], v[194:195], v[212:213]
	v_pk_add_f32 v[212:213], v[194:195], v[212:213] neg_lo:[0,1] neg_hi:[0,1]
	v_pk_add_f32 v[194:195], v[196:197], v[214:215]
	v_pk_add_f32 v[196:197], v[196:197], v[214:215] neg_lo:[0,1] neg_hi:[0,1]
	v_pk_mul_f32 v[214:215], v[196:197], s[72:73]
	v_pk_fma_f32 v[16:17], v[4:5], v[10:11], v[16:17] op_sel_hi:[0,1,1]
	v_pk_fma_f32 v[196:197], v[196:197], s[76:77], v[214:215] op_sel:[0,0,1] op_sel_hi:[1,0,0] neg_lo:[1,0,0] neg_hi:[1,0,0]
	v_pk_add_f32 v[214:215], v[198:199], v[216:217]
	v_pk_add_f32 v[198:199], v[198:199], v[216:217] neg_lo:[0,1] neg_hi:[0,1]
	v_pk_mul_f32 v[18:19], v[6:7], v[10:11] op_sel:[1,1] op_sel_hi:[1,0] neg_lo:[1,0]
	v_pk_mul_f32 v[216:217], v[198:199], s[68:69]
	v_pk_fma_f32 v[30:31], v[4:5], v[26:27], v[30:31] op_sel_hi:[0,1,1]
	v_pk_fma_f32 v[198:199], v[198:199], s[10:11], v[216:217] op_sel:[0,0,1] op_sel_hi:[1,0,0] neg_lo:[1,0,0] neg_hi:[1,0,0]
	v_pk_add_f32 v[216:217], v[202:203], v[218:219]
	v_pk_add_f32 v[202:203], v[202:203], v[218:219] neg_lo:[0,1] neg_hi:[0,1]
	v_pk_mul_f32 v[42:43], v[6:7], v[26:27] op_sel:[1,1] op_sel_hi:[1,0] neg_lo:[1,0]
	v_pk_mul_f32 v[218:219], v[202:203], s[62:63]
	v_pk_fma_f32 v[54:55], v[4:5], v[50:51], v[54:55] op_sel_hi:[0,1,1]
	v_pk_fma_f32 v[202:203], v[202:203], s[50:51], v[218:219] op_sel:[0,0,1] op_sel_hi:[1,0,0] neg_lo:[1,0,0] neg_hi:[1,0,0]
	v_pk_add_f32 v[218:219], v[156:157], v[206:207] op_sel:[0,1] op_sel_hi:[1,0] neg_hi:[0,1]
	v_pk_add_f32 v[156:157], v[156:157], v[206:207] op_sel:[0,1] op_sel_hi:[1,0] neg_lo:[0,1]
	v_pk_add_f32 v[206:207], v[158:159], v[174:175]
	v_pk_add_f32 v[158:159], v[158:159], v[174:175] neg_lo:[0,1] neg_hi:[0,1]
	v_pk_mul_f32 v[58:59], v[6:7], v[50:51] op_sel:[1,1] op_sel_hi:[1,0] neg_lo:[1,0]
	v_pk_mul_f32 v[174:175], v[158:159], s[62:63]
	v_pk_fma_f32 v[70:71], v[4:5], v[66:67], v[70:71] op_sel_hi:[0,1,1]
	v_pk_fma_f32 v[158:159], v[158:159], s[50:51], v[174:175] op_sel:[0,0,1] op_sel_hi:[1,0,0]
	v_pk_add_f32 v[174:175], v[160:161], v[176:177]
	v_pk_add_f32 v[160:161], v[160:161], v[176:177] neg_lo:[0,1] neg_hi:[0,1]
	v_pk_mul_f32 v[74:75], v[6:7], v[66:67] op_sel:[1,1] op_sel_hi:[1,0] neg_lo:[1,0]
	v_pk_mul_f32 v[176:177], v[160:161], s[68:69]
	v_pk_fma_f32 v[86:87], v[4:5], v[82:83], v[86:87] op_sel_hi:[0,1,1]
	v_pk_fma_f32 v[160:161], v[160:161], s[10:11], v[176:177] op_sel:[0,0,1] op_sel_hi:[1,0,0]
	v_pk_add_f32 v[176:177], v[162:163], v[178:179]
	v_pk_add_f32 v[162:163], v[162:163], v[178:179] neg_lo:[0,1] neg_hi:[0,1]
	v_pk_mul_f32 v[90:91], v[6:7], v[82:83] op_sel:[1,1] op_sel_hi:[1,0] neg_lo:[1,0]
	v_pk_mul_f32 v[178:179], v[162:163], s[72:73]
	v_pk_fma_f32 v[102:103], v[4:5], v[98:99], v[102:103] op_sel_hi:[0,1,1]
	v_pk_fma_f32 v[162:163], v[162:163], s[76:77], v[178:179] op_sel:[0,0,1] op_sel_hi:[1,0,0]
	v_pk_add_f32 v[178:179], v[164:165], v[180:181]
	v_pk_add_f32 v[180:181], v[164:165], v[180:181] neg_lo:[0,1] neg_hi:[0,1]
	v_pk_mul_f32 v[106:107], v[6:7], v[98:99] op_sel:[1,1] op_sel_hi:[1,0] neg_lo:[1,0]
	v_pk_add_f32 v[164:165], v[166:167], v[182:183]
	v_pk_add_f32 v[166:167], v[166:167], v[182:183] neg_lo:[0,1] neg_hi:[0,1]
	v_pk_fma_f32 v[118:119], v[4:5], v[114:115], v[118:119] op_sel_hi:[0,1,1]
	v_pk_mul_f32 v[182:183], v[166:167], s[72:73]
	v_pk_mul_f32 v[122:123], v[6:7], v[114:115] op_sel:[1,1] op_sel_hi:[1,0] neg_lo:[1,0]
	v_pk_fma_f32 v[166:167], v[166:167], s[76:77], v[182:183] op_sel:[0,0,1] op_sel_hi:[1,0,0] neg_lo:[1,0,0] neg_hi:[1,0,0]
	v_pk_add_f32 v[182:183], v[168:169], v[184:185]
	v_pk_add_f32 v[168:169], v[168:169], v[184:185] neg_lo:[0,1] neg_hi:[0,1]
	v_pk_fma_f32 v[18:19], v[6:7], v[10:11], v[18:19] op_sel_hi:[0,1,1]
	v_pk_mul_f32 v[184:185], v[168:169], s[68:69]
	v_pk_mul_f32 v[22:23], v[10:11], v[8:9] op_sel:[1,1] op_sel_hi:[0,1] neg_lo:[0,1]
	v_pk_fma_f32 v[168:169], v[168:169], s[10:11], v[184:185] op_sel:[0,0,1] op_sel_hi:[1,0,0] neg_lo:[1,0,0] neg_hi:[1,0,0]
	v_pk_add_f32 v[184:185], v[170:171], v[186:187]
	v_pk_add_f32 v[170:171], v[170:171], v[186:187] neg_lo:[0,1] neg_hi:[0,1]
	v_pk_fma_f32 v[42:43], v[6:7], v[26:27], v[42:43] op_sel_hi:[0,1,1]
	v_pk_mul_f32 v[186:187], v[170:171], s[62:63]
	v_pk_mul_f32 v[46:47], v[8:9], v[26:27] op_sel:[1,1] op_sel_hi:[1,0] neg_lo:[1,0]
	v_pk_fma_f32 v[170:171], v[170:171], s[50:51], v[186:187] op_sel:[0,0,1] op_sel_hi:[1,0,0] neg_lo:[1,0,0] neg_hi:[1,0,0]
	v_pk_add_f32 v[186:187], v[220:221], v[210:211]
	v_pk_add_f32 v[210:211], v[220:221], v[210:211] neg_lo:[0,1] neg_hi:[0,1]
	v_pk_add_f32 v[220:221], v[222:223], v[194:195]
	v_pk_add_f32 v[194:195], v[222:223], v[194:195] neg_lo:[0,1] neg_hi:[0,1]
	v_pk_fma_f32 v[58:59], v[6:7], v[50:51], v[58:59] op_sel_hi:[0,1,1]
	v_pk_mul_f32 v[222:223], v[194:195], s[68:69]
	v_pk_mul_f32 v[62:63], v[8:9], v[50:51] op_sel:[1,1] op_sel_hi:[1,0] neg_lo:[1,0]
	v_pk_fma_f32 v[194:195], v[194:195], s[10:11], v[222:223] op_sel:[0,0,1] op_sel_hi:[1,0,0]
	v_pk_add_f32 v[222:223], v[188:189], v[214:215]
	v_pk_add_f32 v[214:215], v[188:189], v[214:215] neg_lo:[0,1] neg_hi:[0,1]
	v_pk_fma_f32 v[74:75], v[6:7], v[66:67], v[74:75] op_sel_hi:[0,1,1]
	v_pk_add_f32 v[188:189], v[208:209], v[216:217]
	v_pk_add_f32 v[208:209], v[208:209], v[216:217] neg_lo:[0,1] neg_hi:[0,1]
	v_pk_mul_f32 v[78:79], v[8:9], v[66:67] op_sel:[1,1] op_sel_hi:[1,0] neg_lo:[1,0]
	v_pk_mul_f32 v[216:217], v[208:209], s[68:69]
	v_pk_fma_f32 v[90:91], v[6:7], v[82:83], v[90:91] op_sel_hi:[0,1,1]
	v_pk_fma_f32 v[208:209], v[208:209], s[10:11], v[216:217] op_sel:[0,0,1] op_sel_hi:[1,0,0] neg_lo:[1,0,0] neg_hi:[1,0,0]
	v_pk_add_f32 v[216:217], v[204:205], v[212:213] op_sel:[0,1] op_sel_hi:[1,0] neg_hi:[0,1]
	v_pk_add_f32 v[204:205], v[204:205], v[212:213] op_sel:[0,1] op_sel_hi:[1,0] neg_lo:[0,1]
	v_pk_add_f32 v[212:213], v[172:173], v[196:197]
	v_pk_add_f32 v[172:173], v[172:173], v[196:197] neg_lo:[0,1] neg_hi:[0,1]
	v_pk_mul_f32 v[94:95], v[8:9], v[82:83] op_sel:[1,1] op_sel_hi:[1,0] neg_lo:[1,0]
	v_pk_mul_f32 v[196:197], v[172:173], s[68:69]
	v_pk_fma_f32 v[106:107], v[6:7], v[98:99], v[106:107] op_sel_hi:[0,1,1]
	v_pk_fma_f32 v[172:173], v[172:173], s[10:11], v[196:197] op_sel:[0,0,1] op_sel_hi:[1,0,0]
	v_pk_add_f32 v[196:197], v[190:191], v[198:199]
	v_pk_add_f32 v[198:199], v[190:191], v[198:199] neg_lo:[0,1] neg_hi:[0,1]
	v_pk_mul_f32 v[110:111], v[8:9], v[98:99] op_sel:[1,1] op_sel_hi:[1,0] neg_lo:[1,0]
	v_pk_add_f32 v[190:191], v[192:193], v[202:203]
	v_pk_add_f32 v[192:193], v[192:193], v[202:203] neg_lo:[0,1] neg_hi:[0,1]
	v_pk_fma_f32 v[122:123], v[6:7], v[114:115], v[122:123] op_sel_hi:[0,1,1]
	v_pk_mul_f32 v[202:203], v[192:193], s[68:69]
	v_pk_mul_f32 v[126:127], v[8:9], v[114:115] op_sel:[1,1] op_sel_hi:[1,0] neg_lo:[1,0]
	v_pk_fma_f32 v[192:193], v[192:193], s[10:11], v[202:203] op_sel:[0,0,1] op_sel_hi:[1,0,0] neg_lo:[1,0,0] neg_hi:[1,0,0]
	v_pk_add_f32 v[202:203], v[218:219], v[178:179]
	v_pk_add_f32 v[178:179], v[218:219], v[178:179] neg_lo:[0,1] neg_hi:[0,1]
	v_pk_add_f32 v[218:219], v[206:207], v[164:165]
	v_pk_add_f32 v[164:165], v[206:207], v[164:165] neg_lo:[0,1] neg_hi:[0,1]
	v_xor_b32_e32 v24, 0x80000000, v17
	v_pk_mul_f32 v[206:207], v[164:165], s[68:69]
	v_xor_b32_e32 v28, 0x80000000, v19
	v_pk_fma_f32 v[164:165], v[164:165], s[10:11], v[206:207] op_sel:[0,0,1] op_sel_hi:[1,0,0]
	v_pk_add_f32 v[206:207], v[174:175], v[182:183]
	v_pk_add_f32 v[182:183], v[174:175], v[182:183] neg_lo:[0,1] neg_hi:[0,1]
	v_pk_fma_f32 v[22:23], v[10:11], v[8:9], v[22:23] op_sel_hi:[1,0,1]
	v_pk_add_f32 v[174:175], v[176:177], v[184:185]
	v_pk_add_f32 v[176:177], v[176:177], v[184:185] neg_lo:[0,1] neg_hi:[0,1]
	v_pk_fma_f32 v[46:47], v[8:9], v[26:27], v[46:47] op_sel_hi:[0,1,1]
	v_pk_mul_f32 v[184:185], v[176:177], s[68:69]
	v_pk_fma_f32 v[62:63], v[8:9], v[50:51], v[62:63] op_sel_hi:[0,1,1]
	v_pk_fma_f32 v[176:177], v[176:177], s[10:11], v[184:185] op_sel:[0,0,1] op_sel_hi:[1,0,0] neg_lo:[1,0,0] neg_hi:[1,0,0]
	v_pk_add_f32 v[184:185], v[156:157], v[180:181] op_sel:[0,1] op_sel_hi:[1,0] neg_hi:[0,1]
	v_pk_add_f32 v[156:157], v[156:157], v[180:181] op_sel:[0,1] op_sel_hi:[1,0] neg_lo:[0,1]
	v_pk_add_f32 v[180:181], v[158:159], v[166:167]
	v_pk_add_f32 v[158:159], v[158:159], v[166:167] neg_lo:[0,1] neg_hi:[0,1]
	v_pk_fma_f32 v[78:79], v[8:9], v[66:67], v[78:79] op_sel_hi:[0,1,1]
	v_pk_mul_f32 v[166:167], v[158:159], s[68:69]
	v_pk_fma_f32 v[94:95], v[8:9], v[82:83], v[94:95] op_sel_hi:[0,1,1]
	v_pk_fma_f32 v[158:159], v[158:159], s[10:11], v[166:167] op_sel:[0,0,1] op_sel_hi:[1,0,0]
	v_pk_add_f32 v[166:167], v[160:161], v[168:169]
	v_pk_add_f32 v[168:169], v[160:161], v[168:169] neg_lo:[0,1] neg_hi:[0,1]
	v_pk_fma_f32 v[110:111], v[8:9], v[98:99], v[110:111] op_sel_hi:[0,1,1]
	v_pk_add_f32 v[160:161], v[162:163], v[170:171]
	v_pk_add_f32 v[162:163], v[162:163], v[170:171] neg_lo:[0,1] neg_hi:[0,1]
	v_pk_fma_f32 v[126:127], v[8:9], v[114:115], v[126:127] op_sel_hi:[0,1,1]
	v_pk_mul_f32 v[170:171], v[162:163], s[68:69]
	v_mov_b32_e32 v25, v17
	v_pk_fma_f32 v[162:163], v[162:163], s[10:11], v[170:171] op_sel:[0,0,1] op_sel_hi:[1,0,0] neg_lo:[1,0,0] neg_hi:[1,0,0]
	v_pk_add_f32 v[170:171], v[186:187], v[222:223]
	v_pk_add_f32 v[186:187], v[186:187], v[222:223] neg_lo:[0,1] neg_hi:[0,1]
	v_pk_add_f32 v[222:223], v[220:221], v[188:189]
	v_pk_add_f32 v[220:221], v[220:221], v[188:189] neg_lo:[0,1] neg_hi:[0,1]
	s_mov_b32 s10, s60
	s_nop 0
	s_nop 0
	v_pk_add_f32 v[188:189], v[210:211], v[214:215] op_sel:[0,1] op_sel_hi:[1,0] neg_hi:[0,1]
	v_pk_add_f32 v[210:211], v[210:211], v[214:215] op_sel:[0,1] op_sel_hi:[1,0] neg_lo:[0,1]
	v_pk_add_f32 v[214:215], v[194:195], v[208:209]
	v_pk_add_f32 v[208:209], v[194:195], v[208:209] neg_lo:[0,1] neg_hi:[0,1]
	s_add_i32 s60, s60, s28
	s_nop 0
	s_nop 0
	v_pk_add_f32 v[194:195], v[216:217], v[196:197]
	v_pk_add_f32 v[196:197], v[216:217], v[196:197] neg_lo:[0,1] neg_hi:[0,1]
	v_pk_add_f32 v[216:217], v[212:213], v[190:191]
	v_pk_add_f32 v[212:213], v[212:213], v[190:191] neg_lo:[0,1] neg_hi:[0,1]
	s_cmpk_gt_i32 s60, 0x7ff
	s_nop 0
	s_nop 0
	v_pk_add_f32 v[190:191], v[204:205], v[198:199] op_sel:[0,1] op_sel_hi:[1,0] neg_hi:[0,1]
	v_pk_add_f32 v[198:199], v[204:205], v[198:199] op_sel:[0,1] op_sel_hi:[1,0] neg_lo:[0,1]
	v_pk_add_f32 v[204:205], v[172:173], v[192:193]
	v_pk_add_f32 v[192:193], v[172:173], v[192:193] neg_lo:[0,1] neg_hi:[0,1]
	s_cselect_b64 s[76:77], -1, 0
	s_nop 0
	s_nop 0
	v_pk_add_f32 v[172:173], v[202:203], v[206:207]
	v_pk_add_f32 v[202:203], v[202:203], v[206:207] neg_lo:[0,1] neg_hi:[0,1]
	v_pk_add_f32 v[206:207], v[218:219], v[174:175]
	v_pk_add_f32 v[218:219], v[218:219], v[174:175] neg_lo:[0,1] neg_hi:[0,1]
	s_cmpk_lt_i32 s60, 0x800
	s_nop 0
	s_nop 0
	v_pk_add_f32 v[174:175], v[178:179], v[182:183] op_sel:[0,1] op_sel_hi:[1,0] neg_hi:[0,1]
	v_pk_add_f32 v[178:179], v[178:179], v[182:183] op_sel:[0,1] op_sel_hi:[1,0] neg_lo:[0,1]
	v_pk_add_f32 v[182:183], v[164:165], v[176:177]
	v_pk_add_f32 v[176:177], v[164:165], v[176:177] neg_lo:[0,1] neg_hi:[0,1]
	s_cselect_b32 s45, s60, s10
	s_nop 0
	s_nop 0
	v_pk_add_f32 v[164:165], v[184:185], v[166:167]
	v_pk_add_f32 v[166:167], v[184:185], v[166:167] neg_lo:[0,1] neg_hi:[0,1]
	v_pk_add_f32 v[184:185], v[180:181], v[160:161]
	v_pk_add_f32 v[180:181], v[180:181], v[160:161] neg_lo:[0,1] neg_hi:[0,1]
	s_lshl_b32 s11, s45, 1
	s_nop 0
	s_nop 0
	v_pk_add_f32 v[160:161], v[156:157], v[168:169] op_sel:[0,1] op_sel_hi:[1,0] neg_hi:[0,1]
	v_pk_add_f32 v[156:157], v[156:157], v[168:169] op_sel:[0,1] op_sel_hi:[1,0] neg_lo:[0,1]
	v_pk_add_f32 v[168:169], v[158:159], v[162:163]
	v_pk_add_f32 v[158:159], v[158:159], v[162:163] neg_lo:[0,1] neg_hi:[0,1]
	v_mov_b32_e32 v29, v19
	v_xor_b32_e32 v163, 0x80000000, v158
	v_mov_b32_e32 v162, v159
	v_pk_add_f32 v[158:159], v[170:171], v[222:223]
	v_pk_add_f32 v[170:171], v[170:171], v[222:223] neg_lo:[0,1] neg_hi:[0,1]
	v_pk_add_f32 v[222:223], v[186:187], v[220:221] op_sel:[0,1] op_sel_hi:[1,0] neg_hi:[0,1]
	v_pk_add_f32 v[186:187], v[186:187], v[220:221] op_sel:[0,1] op_sel_hi:[1,0] neg_lo:[0,1]
	v_pk_add_f32 v[220:221], v[188:189], v[214:215]
	v_pk_add_f32 v[188:189], v[188:189], v[214:215] neg_lo:[0,1] neg_hi:[0,1]
	v_pk_add_f32 v[214:215], v[210:211], v[208:209] op_sel:[0,1] op_sel_hi:[1,0] neg_hi:[0,1]
	v_pk_add_f32 v[208:209], v[210:211], v[208:209] op_sel:[0,1] op_sel_hi:[1,0] neg_lo:[0,1]
	v_pk_add_f32 v[210:211], v[194:195], v[216:217]
	v_pk_add_f32 v[194:195], v[194:195], v[216:217] neg_lo:[0,1] neg_hi:[0,1]
	v_pk_add_f32 v[216:217], v[196:197], v[212:213] op_sel:[0,1] op_sel_hi:[1,0] neg_hi:[0,1]
	v_pk_add_f32 v[196:197], v[196:197], v[212:213] op_sel:[0,1] op_sel_hi:[1,0] neg_lo:[0,1]
	v_pk_add_f32 v[212:213], v[190:191], v[204:205]
	v_pk_add_f32 v[190:191], v[190:191], v[204:205] neg_lo:[0,1] neg_hi:[0,1]
	v_pk_add_f32 v[204:205], v[198:199], v[192:193] op_sel:[0,1] op_sel_hi:[1,0] neg_hi:[0,1]
	v_pk_add_f32 v[192:193], v[198:199], v[192:193] op_sel:[0,1] op_sel_hi:[1,0] neg_lo:[0,1]
	v_pk_add_f32 v[198:199], v[172:173], v[206:207]
	v_pk_add_f32 v[172:173], v[172:173], v[206:207] neg_lo:[0,1] neg_hi:[0,1]
	v_pk_mul_f32 v[2:3], v[2:3], v[198:199] op_sel:[0,1] op_sel_hi:[1,0]
	v_pk_add_f32 v[206:207], v[202:203], v[218:219] op_sel:[0,1] op_sel_hi:[1,0] neg_hi:[0,1]
	v_pk_add_f32 v[202:203], v[202:203], v[218:219] op_sel:[0,1] op_sel_hi:[1,0] neg_lo:[0,1]
	v_pk_add_f32 v[218:219], v[174:175], v[182:183]
	v_pk_add_f32 v[174:175], v[174:175], v[182:183] neg_lo:[0,1] neg_hi:[0,1]
	v_pk_add_f32 v[182:183], v[178:179], v[176:177] op_sel:[0,1] op_sel_hi:[1,0] neg_hi:[0,1]
	v_pk_add_f32 v[176:177], v[178:179], v[176:177] op_sel:[0,1] op_sel_hi:[1,0] neg_lo:[0,1]
	v_pk_add_f32 v[178:179], v[164:165], v[184:185]
	v_pk_fma_f32 v[2:3], v[4:5], v[198:199], v[2:3] op_sel_hi:[0,1,1]
	v_pk_mul_f32 v[4:5], v[6:7], v[210:211] op_sel:[1,1] op_sel_hi:[1,0] neg_lo:[1,0]
	s_and_b32 s10, s45, 0x3ff
	v_pk_fma_f32 v[4:5], v[6:7], v[210:211], v[4:5] op_sel_hi:[0,1,1]
	v_pk_mul_f32 v[6:7], v[8:9], v[178:179] op_sel:[1,1] op_sel_hi:[1,0] neg_lo:[1,0]
	s_and_b32 s11, s11, 0xfffff800
	v_pk_fma_f32 v[6:7], v[8:9], v[178:179], v[6:7] op_sel_hi:[0,1,1]
	v_pk_mul_f32 v[8:9], v[10:11], v[220:221] op_sel:[1,1] op_sel_hi:[1,0] neg_lo:[1,0]
	s_nop 0
	s_nop 0
	s_nop 0
	v_pk_add_f32 v[164:165], v[164:165], v[184:185] neg_lo:[0,1] neg_hi:[0,1]
	v_pk_add_f32 v[184:185], v[166:167], v[180:181] op_sel:[0,1] op_sel_hi:[1,0] neg_hi:[0,1]
	v_pk_add_f32 v[166:167], v[166:167], v[180:181] op_sel:[0,1] op_sel_hi:[1,0] neg_lo:[0,1]
	v_pk_add_f32 v[180:181], v[160:161], v[168:169]
	v_pk_fma_f32 v[8:9], v[10:11], v[220:221], v[8:9] op_sel_hi:[0,1,1]
	v_pk_mul_f32 v[10:11], v[24:25], v[218:219] op_sel:[0,1] op_sel_hi:[1,0]
	v_pk_mul_f32 v[12:13], v[28:29], v[212:213] op_sel:[0,1] op_sel_hi:[1,0]
	s_or_b32 s10, s11, s10
	s_nop 0
	s_nop 0
	s_nop 0
	s_nop 0
	v_xor_b32_e32 v72, 0x80000000, v63
	v_xor_b32_e32 v76, 0x80000000, v67
	v_xor_b32_e32 v80, 0x80000000, v71
	v_mov_b32_e32 v73, v63
	v_mov_b32_e32 v77, v67
	v_mov_b32_e32 v81, v71
	v_pk_add_f32 v[160:161], v[160:161], v[168:169] neg_lo:[0,1] neg_hi:[0,1]
	v_pk_add_f32 v[168:169], v[156:157], v[162:163]
	v_pk_fma_f32 v[10:11], v[16:17], v[218:219], v[10:11] op_sel_hi:[0,1,1]
	v_pk_fma_f32 v[12:13], v[18:19], v[212:213], v[12:13] op_sel_hi:[0,1,1]
	v_pk_mul_f32 v[14:15], v[22:23], v[180:181] op_sel:[1,1] op_sel_hi:[1,0] neg_lo:[1,0]
	v_pk_mul_f32 v[16:17], v[26:27], v[222:223] op_sel:[1,1] op_sel_hi:[1,0] neg_lo:[1,0]
	v_pk_mul_f32 v[18:19], v[30:31], v[206:207] op_sel:[1,1] op_sel_hi:[1,0] neg_lo:[1,0]
	v_pk_mul_f32 v[20:21], v[42:43], v[216:217] op_sel:[1,1] op_sel_hi:[1,0] neg_lo:[1,0]
	s_ashr_i32 s11, s10, 31
	v_xor_b32_e32 v84, 0x80000000, v75
	v_xor_b32_e32 v88, 0x80000000, v79
	v_xor_b32_e32 v92, 0x80000000, v83
	v_xor_b32_e32 v96, 0x80000000, v87
	v_xor_b32_e32 v100, 0x80000000, v91
	v_xor_b32_e32 v104, 0x80000000, v95
	v_xor_b32_e32 v108, 0x80000000, v99
	v_xor_b32_e32 v112, 0x80000000, v103
	v_xor_b32_e32 v116, 0x80000000, v107
	v_xor_b32_e32 v120, 0x80000000, v111
	v_xor_b32_e32 v124, 0x80000000, v115
	v_xor_b32_e32 v128, 0x80000000, v119
	v_xor_b32_e32 v130, 0x80000000, v123
	v_xor_b32_e32 v132, 0x80000000, v127
	v_mov_b32_e32 v85, v75
	v_mov_b32_e32 v89, v79
	v_mov_b32_e32 v93, v83
	v_mov_b32_e32 v97, v87
	v_mov_b32_e32 v101, v91
	v_mov_b32_e32 v105, v95
	v_mov_b32_e32 v109, v99
	v_mov_b32_e32 v113, v103
	v_mov_b32_e32 v117, v107
	v_mov_b32_e32 v121, v111
	v_mov_b32_e32 v125, v115
	v_mov_b32_e32 v129, v119
	v_mov_b32_e32 v131, v123
	v_mov_b32_e32 v133, v127
	v_pk_add_f32 v[156:157], v[156:157], v[162:163] neg_lo:[0,1] neg_hi:[0,1]
	v_pk_fma_f32 v[14:15], v[22:23], v[180:181], v[14:15] op_sel_hi:[0,1,1]
	v_pk_fma_f32 v[16:17], v[26:27], v[222:223], v[16:17] op_sel_hi:[0,1,1]
	v_pk_fma_f32 v[18:19], v[30:31], v[206:207], v[18:19] op_sel_hi:[0,1,1]
	v_pk_fma_f32 v[20:21], v[42:43], v[216:217], v[20:21] op_sel_hi:[0,1,1]
	v_pk_mul_f32 v[22:23], v[46:47], v[184:185] op_sel:[1,1] op_sel_hi:[1,0] neg_lo:[1,0]
	v_pk_mul_f32 v[24:25], v[50:51], v[214:215] op_sel:[1,1] op_sel_hi:[1,0] neg_lo:[1,0]
	v_pk_mul_f32 v[26:27], v[54:55], v[182:183] op_sel:[1,1] op_sel_hi:[1,0] neg_lo:[1,0]
	v_pk_mul_f32 v[28:29], v[58:59], v[204:205] op_sel:[1,1] op_sel_hi:[1,0] neg_lo:[1,0]
	v_pk_mul_f32 v[30:31], v[72:73], v[168:169] op_sel:[0,1] op_sel_hi:[1,0]
	v_pk_mul_f32 v[32:33], v[76:77], v[170:171] op_sel:[0,1] op_sel_hi:[1,0]
	v_pk_mul_f32 v[42:43], v[80:81], v[172:173] op_sel:[0,1] op_sel_hi:[1,0]
	s_lshl_b64 s[78:79], s[10:11], 15
	s_bitset1_b32 s10, 10
	v_pk_fma_f32 v[22:23], v[46:47], v[184:185], v[22:23] op_sel_hi:[0,1,1]
	v_pk_fma_f32 v[24:25], v[50:51], v[214:215], v[24:25] op_sel_hi:[0,1,1]
	v_pk_fma_f32 v[26:27], v[54:55], v[182:183], v[26:27] op_sel_hi:[0,1,1]
	v_pk_fma_f32 v[28:29], v[58:59], v[204:205], v[28:29] op_sel_hi:[0,1,1]
	v_pk_fma_f32 v[30:31], v[62:63], v[168:169], v[30:31] op_sel_hi:[0,1,1]
	v_pk_fma_f32 v[32:33], v[66:67], v[170:171], v[32:33] op_sel_hi:[0,1,1]
	v_pk_fma_f32 v[42:43], v[70:71], v[172:173], v[42:43] op_sel_hi:[0,1,1]
	v_pk_mul_f32 v[44:45], v[84:85], v[194:195] op_sel:[0,1] op_sel_hi:[1,0]
	v_pk_mul_f32 v[46:47], v[88:89], v[164:165] op_sel:[0,1] op_sel_hi:[1,0]
	v_pk_mul_f32 v[48:49], v[92:93], v[188:189] op_sel:[0,1] op_sel_hi:[1,0]
	v_pk_mul_f32 v[50:51], v[96:97], v[174:175] op_sel:[0,1] op_sel_hi:[1,0]
	v_pk_mul_f32 v[52:53], v[100:101], v[190:191] op_sel:[0,1] op_sel_hi:[1,0]
	v_pk_mul_f32 v[54:55], v[104:105], v[160:161] op_sel:[0,1] op_sel_hi:[1,0]
	v_pk_mul_f32 v[56:57], v[108:109], v[186:187] op_sel:[0,1] op_sel_hi:[1,0]
	v_pk_mul_f32 v[58:59], v[112:113], v[202:203] op_sel:[0,1] op_sel_hi:[1,0]
	v_pk_mul_f32 v[60:61], v[116:117], v[196:197] op_sel:[0,1] op_sel_hi:[1,0]
	v_pk_mul_f32 v[62:63], v[120:121], v[166:167] op_sel:[0,1] op_sel_hi:[1,0]
	v_pk_mul_f32 v[64:65], v[124:125], v[208:209] op_sel:[0,1] op_sel_hi:[1,0]
	v_pk_mul_f32 v[66:67], v[128:129], v[176:177] op_sel:[0,1] op_sel_hi:[1,0]
	v_pk_mul_f32 v[68:69], v[130:131], v[192:193] op_sel:[0,1] op_sel_hi:[1,0]
	v_pk_mul_f32 v[70:71], v[132:133], v[156:157] op_sel:[0,1] op_sel_hi:[1,0]
	s_ashr_i32 s11, s10, 31
	v_pk_fma_f32 v[44:45], v[74:75], v[194:195], v[44:45] op_sel_hi:[0,1,1]
	v_pk_fma_f32 v[46:47], v[78:79], v[164:165], v[46:47] op_sel_hi:[0,1,1]
	v_pk_fma_f32 v[48:49], v[82:83], v[188:189], v[48:49] op_sel_hi:[0,1,1]
	v_pk_fma_f32 v[50:51], v[86:87], v[174:175], v[50:51] op_sel_hi:[0,1,1]
	v_pk_fma_f32 v[52:53], v[90:91], v[190:191], v[52:53] op_sel_hi:[0,1,1]
	v_pk_fma_f32 v[54:55], v[94:95], v[160:161], v[54:55] op_sel_hi:[0,1,1]
	v_pk_fma_f32 v[56:57], v[98:99], v[186:187], v[56:57] op_sel_hi:[0,1,1]
	v_pk_fma_f32 v[58:59], v[102:103], v[202:203], v[58:59] op_sel_hi:[0,1,1]
	v_pk_fma_f32 v[60:61], v[106:107], v[196:197], v[60:61] op_sel_hi:[0,1,1]
	v_pk_fma_f32 v[62:63], v[110:111], v[166:167], v[62:63] op_sel_hi:[0,1,1]
	v_pk_fma_f32 v[64:65], v[114:115], v[208:209], v[64:65] op_sel_hi:[0,1,1]
	v_pk_fma_f32 v[66:67], v[118:119], v[176:177], v[66:67] op_sel_hi:[0,1,1]
	v_pk_fma_f32 v[68:69], v[122:123], v[192:193], v[68:69] op_sel_hi:[0,1,1]
	v_pk_fma_f32 v[70:71], v[126:127], v[156:157], v[70:71] op_sel_hi:[0,1,1]
	ds_write2_b64 v40, v[158:159], v[32:33] offset1:16
	ds_write2_b64 v40, v[16:17], v[56:57] offset0:33 offset1:49
	ds_write2_b64 v40, v[8:9], v[48:49] offset0:66 offset1:82
	ds_write2_b64 v40, v[24:25], v[64:65] offset0:99 offset1:115
	ds_write2_b64 v40, v[4:5], v[44:45] offset0:132 offset1:148
	ds_write2_b64 v40, v[20:21], v[60:61] offset0:165 offset1:181
	ds_write2_b64 v40, v[12:13], v[52:53] offset0:198 offset1:214
	ds_write2_b64 v40, v[28:29], v[68:69] offset0:231 offset1:247
	ds_write2_b64 v155, v[2:3], v[42:43] offset0:8 offset1:24
	ds_write2_b64 v155, v[18:19], v[58:59] offset0:41 offset1:57
	ds_write2_b64 v155, v[10:11], v[50:51] offset0:74 offset1:90
	ds_write2_b64 v155, v[26:27], v[66:67] offset0:107 offset1:123
	ds_write2_b64 v155, v[6:7], v[46:47] offset0:140 offset1:156
	ds_write2_b64 v155, v[22:23], v[62:63] offset0:173 offset1:189
	ds_write2_b64 v155, v[14:15], v[54:55] offset0:206 offset1:222
	ds_write2_b64 v155, v[30:31], v[70:71] offset0:239 offset1:255
	s_lshl_b64 s[10:11], s[10:11], 15
	v_lshl_add_u64 v[2:3], v[36:37], 0, s[78:79]
	s_waitcnt lgkmcnt(0)
	s_barrier
	global_load_dwordx4 v[6:9], v[2:3], off nt
	global_load_dwordx4 v[30:33], v[2:3], off offset:16 nt
	v_lshl_add_u64 v[2:3], v[36:37], 0, s[10:11]
	global_load_dwordx4 v[26:29], v[2:3], off nt
	global_load_dwordx4 v[18:21], v[2:3], off offset:16 nt
	v_mov_b32_e32 v120, 0
	s_and_saveexec_b64 s[10:11], s[0:1]
	s_cbranch_execz .LBB0_273
	global_load_ushort v120, v[2:3], off offset:32

.LBB0_428:
	s_ashr_i32 s17, s16, 31
	s_lshl_b64 s[6:7], s[16:17], 2
	s_add_u32 s6, s48, s6
	s_addc_u32 s7, s49, s7
	global_load_dwordx2 v[40:41], v151, s[6:7]
	s_waitcnt vmcnt(0)
	v_cvt_f32_f16_e32 v36, v10
	v_cvt_f32_f16_sdwa v42, v10 dst_sel:DWORD dst_unused:UNUSED_PAD src0_sel:WORD_1
	v_cvt_f32_f16_e32 v43, v11
	v_cvt_f32_f16_e32 v45, v12
	v_cvt_f32_f16_sdwa v46, v12 dst_sel:DWORD dst_unused:UNUSED_PAD src0_sel:WORD_1
	v_cvt_f32_f16_e32 v47, v13
	v_cvt_f32_f16_sdwa v12, v13 dst_sel:DWORD dst_unused:UNUSED_PAD src0_sel:WORD_1
	v_cvt_f32_f16_e32 v13, v30
	v_cvt_f32_f16_sdwa v50, v26 dst_sel:DWORD dst_unused:UNUSED_PAD src0_sel:WORD_1
	v_cvt_f32_f16_e32 v51, v27
	v_cvt_f32_f16_sdwa v44, v11 dst_sel:DWORD dst_unused:UNUSED_PAD src0_sel:WORD_1
	v_cvt_f32_f16_sdwa v48, v30 dst_sel:DWORD dst_unused:UNUSED_PAD src0_sel:WORD_1
	v_cvt_f32_f16_e32 v49, v31
	v_cvt_f32_f16_sdwa v30, v31 dst_sel:DWORD dst_unused:UNUSED_PAD src0_sel:WORD_1
	v_cvt_f32_f16_e32 v31, v32
	v_cvt_f32_f16_sdwa v11, v33 dst_sel:DWORD dst_unused:UNUSED_PAD src0_sel:WORD_1
	v_cvt_f32_f16_sdwa v32, v32 dst_sel:DWORD dst_unused:UNUSED_PAD src0_sel:WORD_1
	v_cvt_f32_f16_e32 v33, v33
	v_cvt_f32_f16_sdwa v26, v27 dst_sel:DWORD dst_unused:UNUSED_PAD src0_sel:WORD_1
	v_cvt_f32_f16_e32 v27, v28
	v_cvt_f32_f16_sdwa v52, v28 dst_sel:DWORD dst_unused:UNUSED_PAD src0_sel:WORD_1
	v_cvt_f32_f16_e32 v53, v29
	v_cvt_f32_f16_e32 v28, v22
	v_cvt_f32_f16_sdwa v54, v22 dst_sel:DWORD dst_unused:UNUSED_PAD src0_sel:WORD_1
	v_cvt_f32_f16_e32 v55, v23
	v_cvt_f32_f16_sdwa v22, v23 dst_sel:DWORD dst_unused:UNUSED_PAD src0_sel:WORD_1
	v_cvt_f32_f16_e32 v23, v24
	v_cvt_f32_f16_sdwa v56, v24 dst_sel:DWORD dst_unused:UNUSED_PAD src0_sel:WORD_1
	v_cvt_f32_f16_e32 v57, v25
	v_cvt_f32_f16_sdwa v29, v29 dst_sel:DWORD dst_unused:UNUSED_PAD src0_sel:WORD_1
	v_cvt_f32_f16_sdwa v25, v25 dst_sel:DWORD dst_unused:UNUSED_PAD src0_sel:WORD_1
	v_cvt_f32_f16_e32 v24, v38
	v_cvt_f32_f16_sdwa v60, v19 dst_sel:DWORD dst_unused:UNUSED_PAD src0_sel:WORD_1
	v_cvt_f32_f16_e32 v61, v20
	v_cvt_f32_f16_e32 v38, v18
	v_cvt_f32_f16_e32 v59, v19
	v_mul_f32_e32 v19, 0x3b800000, v36
	v_pk_mul_f32 v[42:43], v[42:43], s[24:25] op_sel_hi:[1,0]
	v_pk_mul_f32 v[12:13], v[12:13], s[24:25] op_sel_hi:[1,0]
	v_pk_mul_f32 v[50:51], v[50:51], s[24:25] op_sel_hi:[1,0]
	v_pk_mul_f32 v[44:45], v[44:45], s[24:25] op_sel_hi:[1,0]
	v_pk_mul_f32 v[46:47], v[46:47], s[24:25] op_sel_hi:[1,0]
	v_pk_mul_f32 v[48:49], v[48:49], s[24:25] op_sel_hi:[1,0]
	v_pk_mul_f32 v[30:31], v[30:31], s[24:25] op_sel_hi:[1,0]
	v_mul_f32_e32 v11, 0x3b800000, v11
	v_pk_mul_f32 v[32:33], v[32:33], s[24:25] op_sel_hi:[1,0]
	v_pk_mul_f32 v[26:27], v[26:27], s[24:25] op_sel_hi:[1,0]
	v_pk_mul_f32 v[52:53], v[52:53], s[24:25] op_sel_hi:[1,0]
	v_pk_mul_f32 v[54:55], v[54:55], s[24:25] op_sel_hi:[1,0]
	v_pk_mul_f32 v[22:23], v[22:23], s[24:25] op_sel_hi:[1,0]
	v_pk_mul_f32 v[56:57], v[56:57], s[24:25] op_sel_hi:[1,0]
	ds_write2_b32 v131, v42, v43 offset0:1 offset1:2
	ds_write2_b32 v131, v44, v45 offset0:3 offset1:4
	ds_write2_b32 v131, v46, v47 offset0:5 offset1:6
	ds_write2_b32 v131, v12, v13 offset0:7 offset1:8
	ds_write2_b32 v131, v48, v49 offset0:9 offset1:10
	ds_write2_b32 v131, v30, v31 offset0:11 offset1:12
	ds_write2_b32 v131, v32, v33 offset0:13 offset1:14
	v_pk_mov_b32 v[12:13], v[50:51], v[50:51] op_sel:[1,0]
	v_pk_mul_f32 v[28:29], v[28:29], s[24:25] op_sel_hi:[1,0]
	v_pk_mul_f32 v[24:25], v[24:25], s[24:25] op_sel_hi:[1,0]
	v_pk_mov_b32 v[26:27], v[26:27], v[26:27] op_sel:[1,0]
	v_pk_mov_b32 v[30:31], v[52:53], v[52:53] op_sel:[1,0]
	v_pk_mov_b32 v[32:33], v[54:55], v[54:55] op_sel:[1,0]
	v_pk_mov_b32 v[22:23], v[22:23], v[22:23] op_sel:[1,0]
	v_pk_mov_b32 v[42:43], v[56:57], v[56:57] op_sel:[1,0]
	v_cvt_f32_f16_sdwa v58, v18 dst_sel:DWORD dst_unused:UNUSED_PAD src0_sel:WORD_1
	v_mul_f32_e32 v36, 0x3b800000, v38
	s_mov_b32 s6, s65
	v_pk_mul_f32 v[58:59], v[58:59], s[24:25] op_sel_hi:[1,0]
	v_fma_mix_f32 v10, v10, s24, v40 op_sel_hi:[1,0,0]
	s_nop 0
	v_cndmask_b32_e64 v10, v19, v10, s[4:5]
	ds_write2_b32 v131, v10, v11 offset1:15
	ds_write_b64 v132, v[12:13] offset:32824
	ds_write_b64 v133, v[26:27] offset:32824
	ds_write_b64 v134, v[30:31] offset:32824
	ds_write_b64 v135, v[28:29] offset:32824
	ds_write_b64 v136, v[32:33] offset:32824
	ds_write_b64 v137, v[22:23] offset:32824
	ds_write_b64 v138, v[42:43] offset:32824
	ds_write_b64 v139, v[24:25] offset:32824
	v_cvt_f32_f16_sdwa v10, v20 dst_sel:DWORD dst_unused:UNUSED_PAD src0_sel:WORD_1
	v_cvt_f32_f16_e32 v11, v21
	v_pk_mul_f32 v[12:13], v[60:61], s[24:25] op_sel_hi:[1,0]
	v_fma_mix_f32 v18, v18, s24, v41 op_sel_hi:[1,0,0]
	ds_write2_b32 v140, v12, v13 offset0:3 offset1:4
	v_cvt_f32_f16_sdwa v12, v21 dst_sel:DWORD dst_unused:UNUSED_PAD src0_sel:WORD_1
	v_cvt_f32_f16_e32 v13, v14
	v_cndmask_b32_e64 v36, v36, v18, s[4:5]
	v_cvt_f32_f16_sdwa v18, v14 dst_sel:DWORD dst_unused:UNUSED_PAD src0_sel:WORD_1
	v_cvt_f32_f16_e32 v19, v15
	v_pk_mul_f32 v[10:11], v[10:11], s[24:25] op_sel_hi:[1,0]
	ds_write2_b32 v140, v10, v11 offset0:5 offset1:6
	v_pk_mul_f32 v[10:11], v[12:13], s[24:25] op_sel_hi:[1,0]
	ds_write2_b32 v140, v10, v11 offset0:7 offset1:8
	v_pk_mul_f32 v[10:11], v[18:19], s[24:25] op_sel_hi:[1,0]
	ds_write2_b32 v140, v10, v11 offset0:9 offset1:10
	v_cvt_f32_f16_sdwa v10, v15 dst_sel:DWORD dst_unused:UNUSED_PAD src0_sel:WORD_1
	v_cvt_f32_f16_e32 v11, v16
	v_cvt_f32_f16_sdwa v12, v16 dst_sel:DWORD dst_unused:UNUSED_PAD src0_sel:WORD_1
	v_cvt_f32_f16_e32 v13, v17
	v_cvt_f32_f16_sdwa v14, v17 dst_sel:DWORD dst_unused:UNUSED_PAD src0_sel:WORD_1
	v_pk_mul_f32 v[10:11], v[10:11], s[24:25] op_sel_hi:[1,0]
	ds_write2_b32 v140, v10, v11 offset0:11 offset1:12
	v_pk_mul_f32 v[10:11], v[12:13], s[24:25] op_sel_hi:[1,0]
	ds_write2_b32 v140, v10, v11 offset0:13 offset1:14
	v_cvt_f32_f16_sdwa v10, v6 dst_sel:DWORD dst_unused:UNUSED_PAD src0_sel:WORD_1
	v_cvt_f32_f16_e32 v11, v7
	v_cvt_f32_f16_sdwa v6, v7 dst_sel:DWORD dst_unused:UNUSED_PAD src0_sel:WORD_1
	v_cvt_f32_f16_e32 v7, v8
	v_mul_f32_e32 v14, 0x3b800000, v14
	v_pk_mul_f32 v[10:11], v[10:11], s[24:25] op_sel_hi:[1,0]
	ds_write2_b32 v140, v58, v59 offset0:1 offset1:2
	v_pk_mov_b32 v[10:11], v[10:11], v[10:11] op_sel:[1,0]
	ds_write2_b32 v140, v36, v14 offset1:15
	ds_write_b64 v141, v[10:11] offset:32824
	v_cvt_f32_f16_sdwa v10, v8 dst_sel:DWORD dst_unused:UNUSED_PAD src0_sel:WORD_1
	v_cvt_f32_f16_e32 v11, v9
	v_pk_mul_f32 v[6:7], v[6:7], s[24:25] op_sel_hi:[1,0]
	s_nop 0
	v_pk_mov_b32 v[6:7], v[6:7], v[6:7] op_sel:[1,0]
	ds_write_b64 v142, v[6:7] offset:32824
	v_cvt_f32_f16_sdwa v7, v9 dst_sel:DWORD dst_unused:UNUSED_PAD src0_sel:WORD_1
	v_pk_mul_f32 v[8:9], v[10:11], s[24:25] op_sel_hi:[1,0]
	v_cvt_f32_f16_e32 v6, v2
	v_pk_mov_b32 v[8:9], v[8:9], v[8:9] op_sel:[1,0]
	ds_write_b64 v143, v[8:9] offset:32824
	v_cvt_f32_f16_sdwa v8, v2 dst_sel:DWORD dst_unused:UNUSED_PAD src0_sel:WORD_1
	v_cvt_f32_f16_e32 v9, v3
	v_cvt_f32_f16_sdwa v2, v3 dst_sel:DWORD dst_unused:UNUSED_PAD src0_sel:WORD_1
	v_cvt_f32_f16_e32 v3, v4
	v_pk_mul_f32 v[6:7], v[6:7], s[24:25] op_sel_hi:[1,0]
	ds_write_b64 v144, v[6:7] offset:32824
	v_pk_mul_f32 v[6:7], v[8:9], s[24:25] op_sel_hi:[1,0]
	v_pk_mul_f32 v[2:3], v[2:3], s[24:25] op_sel_hi:[1,0]
	v_pk_mov_b32 v[6:7], v[6:7], v[6:7] op_sel:[1,0]
	ds_write_b64 v145, v[6:7] offset:32824
	v_pk_mov_b32 v[2:3], v[2:3], v[2:3] op_sel:[1,0]
	v_cvt_f32_f16_sdwa v6, v4 dst_sel:DWORD dst_unused:UNUSED_PAD src0_sel:WORD_1
	v_cvt_f32_f16_e32 v7, v5
	ds_write_b64 v148, v[2:3] offset:32824
	v_cvt_f32_f16_sdwa v3, v5 dst_sel:DWORD dst_unused:UNUSED_PAD src0_sel:WORD_1
	v_cvt_f32_f16_e32 v2, v39
	v_pk_mul_f32 v[4:5], v[6:7], s[24:25] op_sel_hi:[1,0]
	v_pk_mul_f32 v[2:3], v[2:3], s[24:25] op_sel_hi:[1,0]
	v_pk_mov_b32 v[4:5], v[4:5], v[4:5] op_sel:[1,0]
	ds_write_b64 v149, v[4:5] offset:32824
	ds_write_b64 v150, v[2:3] offset:32824
	v_mov_b32_e32 v2, v130
	s_waitcnt lgkmcnt(0)
	s_barrier
	s_nop 0
	v_and_b32_e32 v3, 0xff, v2
	v_lshlrev_b32_e32 v4, 5, v2
	v_and_or_b32 v3, v4, s29, v3
	v_ashrrev_i32_e32 v4, 5, v3
	v_lshlrev_b32_e32 v3, 3, v3
	v_lshlrev_b32_e32 v6, 3, v4
	v_add3_u32 v36, 0, v3, v6
	ds_read_b64 v[154:155], v36
	ds_read_b64 v[156:157], v36 offset:2112
	ds_read_b64 v[158:159], v36 offset:4224
	ds_read_b64 v[160:161], v36 offset:6336
	ds_read_b64 v[162:163], v36 offset:8448
	ds_read_b64 v[164:165], v36 offset:10560
	ds_read_b64 v[166:167], v36 offset:12672
	ds_read_b64 v[168:169], v36 offset:14784
	ds_read_b64 v[170:171], v36 offset:16896
	ds_read_b64 v[172:173], v36 offset:19008
	ds_read_b64 v[174:175], v36 offset:21120
	ds_read_b64 v[176:177], v36 offset:23232
	ds_read_b64 v[178:179], v36 offset:25344
	ds_read_b64 v[180:181], v36 offset:27456
	ds_read_b64 v[182:183], v36 offset:29568
	ds_read_b64 v[184:185], v36 offset:31680
	ds_read_b64 v[186:187], v36 offset:33792
	ds_read_b64 v[188:189], v36 offset:35904
	ds_read_b64 v[190:191], v36 offset:38016
	ds_read_b64 v[192:193], v36 offset:40128
	ds_read_b64 v[194:195], v36 offset:42240
	ds_read_b64 v[196:197], v36 offset:44352
	ds_read_b64 v[198:199], v36 offset:46464
	ds_read_b64 v[204:205], v36 offset:48576
	ds_read_b64 v[206:207], v36 offset:50688
	ds_read_b64 v[208:209], v36 offset:52800
	ds_read_b64 v[210:211], v36 offset:54912
	ds_read_b64 v[212:213], v36 offset:57024
	ds_read_b64 v[214:215], v36 offset:59136
	ds_read_b64 v[216:217], v36 offset:61248
	ds_read_b64 v[218:219], v36 offset:63360
	ds_read_b64 v[220:221], v36 offset:65472
	s_waitcnt lgkmcnt(14)
	v_pk_add_f32 v[222:223], v[154:155], v[186:187]
	v_pk_add_f32 v[154:155], v[154:155], v[186:187] neg_lo:[0,1] neg_hi:[0,1]
	v_pk_add_f32 v[186:187], v[156:157], v[188:189]
	v_pk_add_f32 v[156:157], v[156:157], v[188:189] neg_lo:[0,1] neg_hi:[0,1]
	v_cvt_f32_ubyte0_e32 v2, v2
	v_pk_mul_f32 v[188:189], v[156:157], s[40:41]
	v_mul_f32_e32 v5, 0x39000000, v2
	v_pk_fma_f32 v[156:157], v[156:157], s[36:37], v[188:189] op_sel:[0,0,1] op_sel_hi:[1,0,0]
	s_waitcnt lgkmcnt(13)
	v_pk_add_f32 v[188:189], v[158:159], v[190:191]
	v_pk_add_f32 v[158:159], v[158:159], v[190:191] neg_lo:[0,1] neg_hi:[0,1]
	v_sin_f32_e32 v2, v5
	v_pk_mul_f32 v[190:191], v[158:159], s[44:45]
	v_cos_f32_e32 v4, v5
	v_pk_fma_f32 v[158:159], v[158:159], s[42:43], v[190:191] op_sel:[0,0,1] op_sel_hi:[1,0,0]
	s_waitcnt lgkmcnt(12)
	v_pk_add_f32 v[190:191], v[160:161], v[192:193]
	v_pk_add_f32 v[160:161], v[160:161], v[192:193] neg_lo:[0,1] neg_hi:[0,1]
	v_xor_b32_e32 v5, 0x80000000, v2
	v_pk_mul_f32 v[192:193], v[160:161], s[62:63]
	v_mov_b32_e32 v3, v5
	v_pk_fma_f32 v[160:161], v[160:161], s[50:51], v[192:193] op_sel:[0,0,1] op_sel_hi:[1,0,0]
	s_waitcnt lgkmcnt(11)
	v_pk_add_f32 v[192:193], v[162:163], v[194:195]
	v_pk_add_f32 v[162:163], v[162:163], v[194:195] neg_lo:[0,1] neg_hi:[0,1]
	v_pk_mul_f32 v[6:7], v[4:5], v[2:3] op_sel:[1,0] op_sel_hi:[0,1]
	v_pk_mul_f32 v[194:195], v[162:163], s[68:69]
	v_pk_fma_f32 v[6:7], v[4:5], v[4:5], v[6:7] op_sel_hi:[1,0,1]
	v_pk_fma_f32 v[162:163], v[162:163], s[64:65], v[194:195] op_sel:[0,0,1] op_sel_hi:[1,0,0]
	s_waitcnt lgkmcnt(10)
	v_pk_add_f32 v[194:195], v[164:165], v[196:197]
	v_pk_add_f32 v[164:165], v[164:165], v[196:197] neg_lo:[0,1] neg_hi:[0,1]
	v_pk_mul_f32 v[196:197], v[164:165], s[70:71]
	v_pk_fma_f32 v[164:165], v[164:165], s[46:47], v[196:197] op_sel:[0,0,1] op_sel_hi:[1,0,0]
	s_waitcnt lgkmcnt(9)
	v_pk_add_f32 v[196:197], v[166:167], v[198:199]
	v_pk_add_f32 v[166:167], v[166:167], v[198:199] neg_lo:[0,1] neg_hi:[0,1]
	v_pk_mul_f32 v[10:11], v[6:7], v[6:7] op_sel:[1,1] op_sel_hi:[0,1] neg_lo:[0,1]
	v_pk_mul_f32 v[198:199], v[166:167], s[76:77]
	v_pk_fma_f32 v[10:11], v[6:7], v[6:7], v[10:11] op_sel_hi:[1,0,1]
	v_pk_fma_f32 v[166:167], v[166:167], s[72:73], v[198:199] op_sel:[0,0,1] op_sel_hi:[1,0,0]
	s_waitcnt lgkmcnt(8)
	v_pk_add_f32 v[198:199], v[168:169], v[204:205]
	v_pk_add_f32 v[168:169], v[168:169], v[204:205] neg_lo:[0,1] neg_hi:[0,1]
	v_pk_mul_f32 v[204:205], v[168:169], s[26:27]
	v_pk_fma_f32 v[168:169], v[168:169], s[38:39], v[204:205] op_sel:[0,0,1] op_sel_hi:[1,0,0]
	s_waitcnt lgkmcnt(7)
	v_pk_add_f32 v[204:205], v[170:171], v[206:207]
	v_pk_add_f32 v[206:207], v[170:171], v[206:207] neg_lo:[0,1] neg_hi:[0,1]
	v_pk_mul_f32 v[26:27], v[10:11], v[10:11] op_sel:[1,1] op_sel_hi:[0,1] neg_lo:[0,1]
	s_waitcnt lgkmcnt(6)
	v_pk_add_f32 v[170:171], v[172:173], v[208:209]
	v_pk_add_f32 v[172:173], v[172:173], v[208:209] neg_lo:[0,1] neg_hi:[0,1]
	v_pk_fma_f32 v[26:27], v[10:11], v[10:11], v[26:27] op_sel_hi:[1,0,1]
	v_pk_mul_f32 v[208:209], v[172:173], s[26:27]
	v_pk_mul_f32 v[46:47], v[10:11], v[26:27] op_sel:[1,1] op_sel_hi:[1,0] neg_lo:[1,0]
	v_pk_fma_f32 v[172:173], v[172:173], s[38:39], v[208:209] op_sel:[0,0,1] op_sel_hi:[1,0,0] neg_lo:[1,0,0] neg_hi:[1,0,0]
	s_waitcnt lgkmcnt(5)
	v_pk_add_f32 v[208:209], v[174:175], v[210:211]
	v_pk_add_f32 v[174:175], v[174:175], v[210:211] neg_lo:[0,1] neg_hi:[0,1]
	v_pk_fma_f32 v[46:47], v[10:11], v[26:27], v[46:47] op_sel_hi:[0,1,1]
	v_pk_mul_f32 v[210:211], v[174:175], s[76:77]
	v_pk_mul_f32 v[62:63], v[10:11], v[46:47] op_sel:[1,1] op_sel_hi:[1,0] neg_lo:[1,0]
	v_pk_fma_f32 v[174:175], v[174:175], s[72:73], v[210:211] op_sel:[0,0,1] op_sel_hi:[1,0,0] neg_lo:[1,0,0] neg_hi:[1,0,0]
	s_waitcnt lgkmcnt(4)
	v_pk_add_f32 v[210:211], v[176:177], v[212:213]
	v_pk_add_f32 v[176:177], v[176:177], v[212:213] neg_lo:[0,1] neg_hi:[0,1]
	v_pk_fma_f32 v[62:63], v[10:11], v[46:47], v[62:63] op_sel_hi:[0,1,1]
	v_pk_mul_f32 v[212:213], v[176:177], s[70:71]
	v_pk_mul_f32 v[78:79], v[10:11], v[62:63] op_sel:[1,1] op_sel_hi:[1,0] neg_lo:[1,0]
	v_pk_fma_f32 v[176:177], v[176:177], s[46:47], v[212:213] op_sel:[0,0,1] op_sel_hi:[1,0,0] neg_lo:[1,0,0] neg_hi:[1,0,0]
	s_waitcnt lgkmcnt(3)
	v_pk_add_f32 v[212:213], v[178:179], v[214:215]
	v_pk_add_f32 v[178:179], v[178:179], v[214:215] neg_lo:[0,1] neg_hi:[0,1]
	v_pk_fma_f32 v[78:79], v[10:11], v[62:63], v[78:79] op_sel_hi:[0,1,1]
	v_pk_mul_f32 v[214:215], v[178:179], s[68:69]
	v_pk_mul_f32 v[94:95], v[10:11], v[78:79] op_sel:[1,1] op_sel_hi:[1,0] neg_lo:[1,0]
	v_pk_fma_f32 v[178:179], v[178:179], s[64:65], v[214:215] op_sel:[0,0,1] op_sel_hi:[1,0,0] neg_lo:[1,0,0] neg_hi:[1,0,0]
	s_waitcnt lgkmcnt(2)
	v_pk_add_f32 v[214:215], v[180:181], v[216:217]
	v_pk_add_f32 v[180:181], v[180:181], v[216:217] neg_lo:[0,1] neg_hi:[0,1]
	v_pk_fma_f32 v[94:95], v[10:11], v[78:79], v[94:95] op_sel_hi:[0,1,1]
	v_pk_mul_f32 v[216:217], v[180:181], s[62:63]
	v_pk_mul_f32 v[110:111], v[10:11], v[94:95] op_sel:[1,1] op_sel_hi:[1,0] neg_lo:[1,0]
	v_pk_fma_f32 v[180:181], v[180:181], s[50:51], v[216:217] op_sel:[0,0,1] op_sel_hi:[1,0,0] neg_lo:[1,0,0] neg_hi:[1,0,0]
	s_waitcnt lgkmcnt(1)
	v_pk_add_f32 v[216:217], v[182:183], v[218:219]
	v_pk_add_f32 v[182:183], v[182:183], v[218:219] neg_lo:[0,1] neg_hi:[0,1]
	v_pk_mul_f32 v[8:9], v[2:3], v[6:7] op_sel:[0,1] op_sel_hi:[1,0]
	v_pk_mul_f32 v[218:219], v[182:183], s[44:45]
	v_pk_fma_f32 v[110:111], v[10:11], v[94:95], v[110:111] op_sel_hi:[0,1,1]
	v_pk_fma_f32 v[182:183], v[182:183], s[42:43], v[218:219] op_sel:[0,0,1] op_sel_hi:[1,0,0] neg_lo:[1,0,0] neg_hi:[1,0,0]
	s_waitcnt lgkmcnt(0)
	v_pk_add_f32 v[218:219], v[184:185], v[220:221]
	v_pk_add_f32 v[184:185], v[184:185], v[220:221] neg_lo:[0,1] neg_hi:[0,1]
	v_pk_fma_f32 v[8:9], v[4:5], v[6:7], v[8:9] op_sel_hi:[0,1,1]
	v_pk_mul_f32 v[220:221], v[184:185], s[40:41]
	v_pk_mul_f32 v[16:17], v[2:3], v[10:11] op_sel:[0,1] op_sel_hi:[1,0]
	v_pk_fma_f32 v[184:185], v[184:185], s[36:37], v[220:221] op_sel:[0,0,1] op_sel_hi:[1,0,0] neg_lo:[1,0,0] neg_hi:[1,0,0]
	v_pk_add_f32 v[220:221], v[222:223], v[204:205]
	v_pk_add_f32 v[204:205], v[222:223], v[204:205] neg_lo:[0,1] neg_hi:[0,1]
	v_pk_add_f32 v[222:223], v[186:187], v[170:171]
	v_pk_add_f32 v[170:171], v[186:187], v[170:171] neg_lo:[0,1] neg_hi:[0,1]
	v_pk_mul_f32 v[30:31], v[2:3], v[26:27] op_sel:[0,1] op_sel_hi:[1,0]
	v_pk_mul_f32 v[186:187], v[170:171], s[44:45]
	v_pk_mul_f32 v[50:51], v[2:3], v[46:47] op_sel:[0,1] op_sel_hi:[1,0]
	v_pk_fma_f32 v[170:171], v[170:171], s[42:43], v[186:187] op_sel:[0,0,1] op_sel_hi:[1,0,0]
	v_pk_add_f32 v[186:187], v[188:189], v[208:209]
	v_pk_add_f32 v[188:189], v[188:189], v[208:209] neg_lo:[0,1] neg_hi:[0,1]
	v_pk_mul_f32 v[66:67], v[2:3], v[62:63] op_sel:[0,1] op_sel_hi:[1,0]
	v_pk_mul_f32 v[208:209], v[188:189], s[68:69]
	v_pk_mul_f32 v[82:83], v[2:3], v[78:79] op_sel:[0,1] op_sel_hi:[1,0]
	v_pk_fma_f32 v[188:189], v[188:189], s[64:65], v[208:209] op_sel:[0,0,1] op_sel_hi:[1,0,0]
	v_pk_add_f32 v[208:209], v[190:191], v[210:211]
	v_pk_add_f32 v[190:191], v[190:191], v[210:211] neg_lo:[0,1] neg_hi:[0,1]
	v_pk_mul_f32 v[98:99], v[2:3], v[94:95] op_sel:[0,1] op_sel_hi:[1,0]
	v_pk_mul_f32 v[210:211], v[190:191], s[76:77]
	v_pk_mul_f32 v[114:115], v[2:3], v[110:111] op_sel:[0,1] op_sel_hi:[1,0]
	v_pk_fma_f32 v[190:191], v[190:191], s[72:73], v[210:211] op_sel:[0,0,1] op_sel_hi:[1,0,0]
	v_pk_add_f32 v[210:211], v[192:193], v[212:213]
	v_pk_add_f32 v[212:213], v[192:193], v[212:213] neg_lo:[0,1] neg_hi:[0,1]
	v_pk_add_f32 v[192:193], v[194:195], v[214:215]
	v_pk_add_f32 v[194:195], v[194:195], v[214:215] neg_lo:[0,1] neg_hi:[0,1]
	v_pk_mul_f32 v[214:215], v[194:195], s[76:77]
	v_pk_fma_f32 v[16:17], v[4:5], v[10:11], v[16:17] op_sel_hi:[0,1,1]
	v_pk_fma_f32 v[194:195], v[194:195], s[72:73], v[214:215] op_sel:[0,0,1] op_sel_hi:[1,0,0] neg_lo:[1,0,0] neg_hi:[1,0,0]
	v_pk_add_f32 v[214:215], v[196:197], v[216:217]
	v_pk_add_f32 v[196:197], v[196:197], v[216:217] neg_lo:[0,1] neg_hi:[0,1]
	v_pk_mul_f32 v[18:19], v[6:7], v[10:11] op_sel:[1,1] op_sel_hi:[1,0] neg_lo:[1,0]
	v_pk_mul_f32 v[216:217], v[196:197], s[68:69]
	v_pk_fma_f32 v[30:31], v[4:5], v[26:27], v[30:31] op_sel_hi:[0,1,1]
	v_pk_fma_f32 v[196:197], v[196:197], s[64:65], v[216:217] op_sel:[0,0,1] op_sel_hi:[1,0,0] neg_lo:[1,0,0] neg_hi:[1,0,0]
	v_pk_add_f32 v[216:217], v[198:199], v[218:219]
	v_pk_add_f32 v[198:199], v[198:199], v[218:219] neg_lo:[0,1] neg_hi:[0,1]
	v_pk_mul_f32 v[38:39], v[6:7], v[26:27] op_sel:[1,1] op_sel_hi:[1,0] neg_lo:[1,0]
	v_pk_mul_f32 v[218:219], v[198:199], s[44:45]
	v_pk_fma_f32 v[50:51], v[4:5], v[46:47], v[50:51] op_sel_hi:[0,1,1]
	v_pk_fma_f32 v[198:199], v[198:199], s[42:43], v[218:219] op_sel:[0,0,1] op_sel_hi:[1,0,0] neg_lo:[1,0,0] neg_hi:[1,0,0]
	v_pk_add_f32 v[218:219], v[154:155], v[206:207] op_sel:[0,1] op_sel_hi:[1,0] neg_hi:[0,1]
	v_pk_add_f32 v[154:155], v[154:155], v[206:207] op_sel:[0,1] op_sel_hi:[1,0] neg_lo:[0,1]
	v_pk_add_f32 v[206:207], v[156:157], v[172:173]
	v_pk_add_f32 v[156:157], v[156:157], v[172:173] neg_lo:[0,1] neg_hi:[0,1]
	v_pk_mul_f32 v[54:55], v[6:7], v[46:47] op_sel:[1,1] op_sel_hi:[1,0] neg_lo:[1,0]
	v_pk_mul_f32 v[172:173], v[156:157], s[44:45]
	v_pk_fma_f32 v[66:67], v[4:5], v[62:63], v[66:67] op_sel_hi:[0,1,1]
	v_pk_fma_f32 v[156:157], v[156:157], s[42:43], v[172:173] op_sel:[0,0,1] op_sel_hi:[1,0,0]
	v_pk_add_f32 v[172:173], v[158:159], v[174:175]
	v_pk_add_f32 v[158:159], v[158:159], v[174:175] neg_lo:[0,1] neg_hi:[0,1]
	v_pk_mul_f32 v[70:71], v[6:7], v[62:63] op_sel:[1,1] op_sel_hi:[1,0] neg_lo:[1,0]
	v_pk_mul_f32 v[174:175], v[158:159], s[68:69]
	v_pk_fma_f32 v[82:83], v[4:5], v[78:79], v[82:83] op_sel_hi:[0,1,1]
	v_pk_fma_f32 v[158:159], v[158:159], s[64:65], v[174:175] op_sel:[0,0,1] op_sel_hi:[1,0,0]
	v_pk_add_f32 v[174:175], v[160:161], v[176:177]
	v_pk_add_f32 v[160:161], v[160:161], v[176:177] neg_lo:[0,1] neg_hi:[0,1]
	v_pk_mul_f32 v[86:87], v[6:7], v[78:79] op_sel:[1,1] op_sel_hi:[1,0] neg_lo:[1,0]
	v_pk_mul_f32 v[176:177], v[160:161], s[76:77]
	v_pk_fma_f32 v[98:99], v[4:5], v[94:95], v[98:99] op_sel_hi:[0,1,1]
	v_pk_fma_f32 v[160:161], v[160:161], s[72:73], v[176:177] op_sel:[0,0,1] op_sel_hi:[1,0,0]
	v_pk_add_f32 v[176:177], v[162:163], v[178:179]
	v_pk_add_f32 v[178:179], v[162:163], v[178:179] neg_lo:[0,1] neg_hi:[0,1]
	v_pk_mul_f32 v[102:103], v[6:7], v[94:95] op_sel:[1,1] op_sel_hi:[1,0] neg_lo:[1,0]
	v_pk_add_f32 v[162:163], v[164:165], v[180:181]
	v_pk_add_f32 v[164:165], v[164:165], v[180:181] neg_lo:[0,1] neg_hi:[0,1]
	v_pk_fma_f32 v[114:115], v[4:5], v[110:111], v[114:115] op_sel_hi:[0,1,1]
	v_pk_mul_f32 v[180:181], v[164:165], s[76:77]
	v_pk_mul_f32 v[118:119], v[6:7], v[110:111] op_sel:[1,1] op_sel_hi:[1,0] neg_lo:[1,0]
	v_pk_fma_f32 v[164:165], v[164:165], s[72:73], v[180:181] op_sel:[0,0,1] op_sel_hi:[1,0,0] neg_lo:[1,0,0] neg_hi:[1,0,0]
	v_pk_add_f32 v[180:181], v[166:167], v[182:183]
	v_pk_add_f32 v[166:167], v[166:167], v[182:183] neg_lo:[0,1] neg_hi:[0,1]
	v_pk_fma_f32 v[18:19], v[6:7], v[10:11], v[18:19] op_sel_hi:[0,1,1]
	v_pk_mul_f32 v[182:183], v[166:167], s[68:69]
	v_pk_mul_f32 v[22:23], v[10:11], v[8:9] op_sel:[1,1] op_sel_hi:[0,1] neg_lo:[0,1]
	v_pk_fma_f32 v[166:167], v[166:167], s[64:65], v[182:183] op_sel:[0,0,1] op_sel_hi:[1,0,0] neg_lo:[1,0,0] neg_hi:[1,0,0]
	v_pk_add_f32 v[182:183], v[168:169], v[184:185]
	v_pk_add_f32 v[168:169], v[168:169], v[184:185] neg_lo:[0,1] neg_hi:[0,1]
	v_pk_fma_f32 v[38:39], v[6:7], v[26:27], v[38:39] op_sel_hi:[0,1,1]
	v_pk_mul_f32 v[184:185], v[168:169], s[44:45]
	v_pk_mul_f32 v[42:43], v[8:9], v[26:27] op_sel:[1,1] op_sel_hi:[1,0] neg_lo:[1,0]
	v_pk_fma_f32 v[168:169], v[168:169], s[42:43], v[184:185] op_sel:[0,0,1] op_sel_hi:[1,0,0] neg_lo:[1,0,0] neg_hi:[1,0,0]
	v_pk_add_f32 v[184:185], v[220:221], v[210:211]
	v_pk_add_f32 v[210:211], v[220:221], v[210:211] neg_lo:[0,1] neg_hi:[0,1]
	v_pk_add_f32 v[220:221], v[222:223], v[192:193]
	v_pk_add_f32 v[192:193], v[222:223], v[192:193] neg_lo:[0,1] neg_hi:[0,1]
	v_pk_fma_f32 v[54:55], v[6:7], v[46:47], v[54:55] op_sel_hi:[0,1,1]
	v_pk_mul_f32 v[222:223], v[192:193], s[68:69]
	v_pk_mul_f32 v[58:59], v[8:9], v[46:47] op_sel:[1,1] op_sel_hi:[1,0] neg_lo:[1,0]
	v_pk_fma_f32 v[192:193], v[192:193], s[64:65], v[222:223] op_sel:[0,0,1] op_sel_hi:[1,0,0]
	v_pk_add_f32 v[222:223], v[186:187], v[214:215]
	v_pk_add_f32 v[214:215], v[186:187], v[214:215] neg_lo:[0,1] neg_hi:[0,1]
	v_pk_fma_f32 v[70:71], v[6:7], v[62:63], v[70:71] op_sel_hi:[0,1,1]
	v_pk_add_f32 v[186:187], v[208:209], v[216:217]
	v_pk_add_f32 v[208:209], v[208:209], v[216:217] neg_lo:[0,1] neg_hi:[0,1]
	v_pk_mul_f32 v[74:75], v[8:9], v[62:63] op_sel:[1,1] op_sel_hi:[1,0] neg_lo:[1,0]
	v_pk_mul_f32 v[216:217], v[208:209], s[68:69]
	v_pk_fma_f32 v[86:87], v[6:7], v[78:79], v[86:87] op_sel_hi:[0,1,1]
	v_pk_fma_f32 v[208:209], v[208:209], s[64:65], v[216:217] op_sel:[0,0,1] op_sel_hi:[1,0,0] neg_lo:[1,0,0] neg_hi:[1,0,0]
	v_pk_add_f32 v[216:217], v[204:205], v[212:213] op_sel:[0,1] op_sel_hi:[1,0] neg_hi:[0,1]
	v_pk_add_f32 v[204:205], v[204:205], v[212:213] op_sel:[0,1] op_sel_hi:[1,0] neg_lo:[0,1]
	v_pk_add_f32 v[212:213], v[170:171], v[194:195]
	v_pk_add_f32 v[170:171], v[170:171], v[194:195] neg_lo:[0,1] neg_hi:[0,1]
	v_pk_mul_f32 v[90:91], v[8:9], v[78:79] op_sel:[1,1] op_sel_hi:[1,0] neg_lo:[1,0]
	v_pk_mul_f32 v[194:195], v[170:171], s[68:69]
	v_pk_fma_f32 v[102:103], v[6:7], v[94:95], v[102:103] op_sel_hi:[0,1,1]
	v_pk_fma_f32 v[170:171], v[170:171], s[64:65], v[194:195] op_sel:[0,0,1] op_sel_hi:[1,0,0]
	v_pk_add_f32 v[194:195], v[188:189], v[196:197]
	v_pk_add_f32 v[196:197], v[188:189], v[196:197] neg_lo:[0,1] neg_hi:[0,1]
	v_pk_mul_f32 v[106:107], v[8:9], v[94:95] op_sel:[1,1] op_sel_hi:[1,0] neg_lo:[1,0]
	v_pk_add_f32 v[188:189], v[190:191], v[198:199]
	v_pk_add_f32 v[190:191], v[190:191], v[198:199] neg_lo:[0,1] neg_hi:[0,1]
	v_pk_fma_f32 v[118:119], v[6:7], v[110:111], v[118:119] op_sel_hi:[0,1,1]
	v_pk_mul_f32 v[198:199], v[190:191], s[68:69]
	v_pk_mul_f32 v[122:123], v[8:9], v[110:111] op_sel:[1,1] op_sel_hi:[1,0] neg_lo:[1,0]
	v_pk_fma_f32 v[190:191], v[190:191], s[64:65], v[198:199] op_sel:[0,0,1] op_sel_hi:[1,0,0] neg_lo:[1,0,0] neg_hi:[1,0,0]
	v_pk_add_f32 v[198:199], v[218:219], v[176:177]
	v_pk_add_f32 v[176:177], v[218:219], v[176:177] neg_lo:[0,1] neg_hi:[0,1]
	v_pk_add_f32 v[218:219], v[206:207], v[162:163]
	v_pk_add_f32 v[162:163], v[206:207], v[162:163] neg_lo:[0,1] neg_hi:[0,1]
	v_xor_b32_e32 v24, 0x80000000, v17
	v_pk_mul_f32 v[206:207], v[162:163], s[68:69]
	v_xor_b32_e32 v28, 0x80000000, v19
	v_pk_fma_f32 v[162:163], v[162:163], s[64:65], v[206:207] op_sel:[0,0,1] op_sel_hi:[1,0,0]
	v_pk_add_f32 v[206:207], v[172:173], v[180:181]
	v_pk_add_f32 v[180:181], v[172:173], v[180:181] neg_lo:[0,1] neg_hi:[0,1]
	v_pk_fma_f32 v[22:23], v[10:11], v[8:9], v[22:23] op_sel_hi:[1,0,1]
	v_pk_add_f32 v[172:173], v[174:175], v[182:183]
	v_pk_add_f32 v[174:175], v[174:175], v[182:183] neg_lo:[0,1] neg_hi:[0,1]
	v_pk_fma_f32 v[42:43], v[8:9], v[26:27], v[42:43] op_sel_hi:[0,1,1]
	v_pk_mul_f32 v[182:183], v[174:175], s[68:69]
	v_pk_fma_f32 v[58:59], v[8:9], v[46:47], v[58:59] op_sel_hi:[0,1,1]
	v_pk_fma_f32 v[174:175], v[174:175], s[64:65], v[182:183] op_sel:[0,0,1] op_sel_hi:[1,0,0] neg_lo:[1,0,0] neg_hi:[1,0,0]
	v_pk_add_f32 v[182:183], v[154:155], v[178:179] op_sel:[0,1] op_sel_hi:[1,0] neg_hi:[0,1]
	v_pk_add_f32 v[154:155], v[154:155], v[178:179] op_sel:[0,1] op_sel_hi:[1,0] neg_lo:[0,1]
	v_pk_add_f32 v[178:179], v[156:157], v[164:165]
	v_pk_add_f32 v[156:157], v[156:157], v[164:165] neg_lo:[0,1] neg_hi:[0,1]
	v_pk_fma_f32 v[74:75], v[8:9], v[62:63], v[74:75] op_sel_hi:[0,1,1]
	v_pk_mul_f32 v[164:165], v[156:157], s[68:69]
	v_pk_fma_f32 v[90:91], v[8:9], v[78:79], v[90:91] op_sel_hi:[0,1,1]
	v_pk_fma_f32 v[156:157], v[156:157], s[64:65], v[164:165] op_sel:[0,0,1] op_sel_hi:[1,0,0]
	v_pk_add_f32 v[164:165], v[158:159], v[166:167]
	v_pk_add_f32 v[166:167], v[158:159], v[166:167] neg_lo:[0,1] neg_hi:[0,1]
	v_pk_fma_f32 v[106:107], v[8:9], v[94:95], v[106:107] op_sel_hi:[0,1,1]
	v_pk_add_f32 v[158:159], v[160:161], v[168:169]
	v_pk_add_f32 v[160:161], v[160:161], v[168:169] neg_lo:[0,1] neg_hi:[0,1]
	v_pk_fma_f32 v[122:123], v[8:9], v[110:111], v[122:123] op_sel_hi:[0,1,1]
	v_pk_mul_f32 v[168:169], v[160:161], s[68:69]
	v_mov_b32_e32 v25, v17
	v_pk_fma_f32 v[160:161], v[160:161], s[64:65], v[168:169] op_sel:[0,0,1] op_sel_hi:[1,0,0] neg_lo:[1,0,0] neg_hi:[1,0,0]
	v_pk_add_f32 v[168:169], v[184:185], v[222:223]
	v_pk_add_f32 v[184:185], v[184:185], v[222:223] neg_lo:[0,1] neg_hi:[0,1]
	v_pk_add_f32 v[222:223], v[220:221], v[186:187]
	v_pk_add_f32 v[220:221], v[220:221], v[186:187] neg_lo:[0,1] neg_hi:[0,1]
	v_mov_b32_e32 v29, v19
	v_pk_add_f32 v[186:187], v[210:211], v[214:215] op_sel:[0,1] op_sel_hi:[1,0] neg_hi:[0,1]
	v_pk_add_f32 v[210:211], v[210:211], v[214:215] op_sel:[0,1] op_sel_hi:[1,0] neg_lo:[0,1]
	v_pk_add_f32 v[214:215], v[192:193], v[208:209]
	v_pk_add_f32 v[208:209], v[192:193], v[208:209] neg_lo:[0,1] neg_hi:[0,1]
	v_xor_b32_e32 v32, 0x80000000, v23
	v_pk_add_f32 v[192:193], v[216:217], v[194:195]
	v_pk_add_f32 v[194:195], v[216:217], v[194:195] neg_lo:[0,1] neg_hi:[0,1]
	v_pk_add_f32 v[216:217], v[212:213], v[188:189]
	v_pk_add_f32 v[212:213], v[212:213], v[188:189] neg_lo:[0,1] neg_hi:[0,1]
	v_xor_b32_e32 v40, 0x80000000, v27
	v_pk_add_f32 v[188:189], v[204:205], v[196:197] op_sel:[0,1] op_sel_hi:[1,0] neg_hi:[0,1]
	v_pk_add_f32 v[196:197], v[204:205], v[196:197] op_sel:[0,1] op_sel_hi:[1,0] neg_lo:[0,1]
	v_pk_add_f32 v[204:205], v[170:171], v[190:191]
	v_pk_add_f32 v[190:191], v[170:171], v[190:191] neg_lo:[0,1] neg_hi:[0,1]
	v_xor_b32_e32 v44, 0x80000000, v31
	v_pk_add_f32 v[170:171], v[198:199], v[206:207]
	v_pk_add_f32 v[198:199], v[198:199], v[206:207] neg_lo:[0,1] neg_hi:[0,1]
	v_pk_add_f32 v[206:207], v[218:219], v[172:173]
	v_pk_add_f32 v[218:219], v[218:219], v[172:173] neg_lo:[0,1] neg_hi:[0,1]
	v_xor_b32_e32 v48, 0x80000000, v39
	v_pk_add_f32 v[172:173], v[176:177], v[180:181] op_sel:[0,1] op_sel_hi:[1,0] neg_hi:[0,1]
	v_pk_add_f32 v[176:177], v[176:177], v[180:181] op_sel:[0,1] op_sel_hi:[1,0] neg_lo:[0,1]
	v_pk_add_f32 v[180:181], v[162:163], v[174:175]
	v_pk_add_f32 v[174:175], v[162:163], v[174:175] neg_lo:[0,1] neg_hi:[0,1]
	v_mov_b32_e32 v33, v23
	v_pk_add_f32 v[162:163], v[182:183], v[164:165]
	v_pk_add_f32 v[164:165], v[182:183], v[164:165] neg_lo:[0,1] neg_hi:[0,1]
	v_pk_add_f32 v[182:183], v[178:179], v[158:159]
	v_pk_add_f32 v[178:179], v[178:179], v[158:159] neg_lo:[0,1] neg_hi:[0,1]
	v_mov_b32_e32 v41, v27
	v_pk_add_f32 v[158:159], v[154:155], v[166:167] op_sel:[0,1] op_sel_hi:[1,0] neg_hi:[0,1]
	v_pk_add_f32 v[154:155], v[154:155], v[166:167] op_sel:[0,1] op_sel_hi:[1,0] neg_lo:[0,1]
	v_pk_add_f32 v[166:167], v[156:157], v[160:161]
	v_pk_add_f32 v[156:157], v[156:157], v[160:161] neg_lo:[0,1] neg_hi:[0,1]
	v_mov_b32_e32 v45, v31
	v_xor_b32_e32 v161, 0x80000000, v156
	v_mov_b32_e32 v160, v157
	v_pk_add_f32 v[156:157], v[168:169], v[222:223]
	v_pk_add_f32 v[168:169], v[168:169], v[222:223] neg_lo:[0,1] neg_hi:[0,1]
	v_pk_add_f32 v[222:223], v[184:185], v[220:221] op_sel:[0,1] op_sel_hi:[1,0] neg_hi:[0,1]
	v_pk_add_f32 v[184:185], v[184:185], v[220:221] op_sel:[0,1] op_sel_hi:[1,0] neg_lo:[0,1]
	v_pk_add_f32 v[220:221], v[186:187], v[214:215]
	v_pk_add_f32 v[186:187], v[186:187], v[214:215] neg_lo:[0,1] neg_hi:[0,1]
	v_pk_add_f32 v[214:215], v[210:211], v[208:209] op_sel:[0,1] op_sel_hi:[1,0] neg_hi:[0,1]
	v_pk_add_f32 v[208:209], v[210:211], v[208:209] op_sel:[0,1] op_sel_hi:[1,0] neg_lo:[0,1]
	v_pk_add_f32 v[210:211], v[192:193], v[216:217]
	v_pk_add_f32 v[192:193], v[192:193], v[216:217] neg_lo:[0,1] neg_hi:[0,1]
	v_pk_add_f32 v[216:217], v[194:195], v[212:213] op_sel:[0,1] op_sel_hi:[1,0] neg_hi:[0,1]
	v_pk_add_f32 v[194:195], v[194:195], v[212:213] op_sel:[0,1] op_sel_hi:[1,0] neg_lo:[0,1]
	v_pk_add_f32 v[212:213], v[188:189], v[204:205]
	v_pk_add_f32 v[188:189], v[188:189], v[204:205] neg_lo:[0,1] neg_hi:[0,1]
	v_pk_add_f32 v[204:205], v[196:197], v[190:191] op_sel:[0,1] op_sel_hi:[1,0] neg_hi:[0,1]
	v_pk_add_f32 v[190:191], v[196:197], v[190:191] op_sel:[0,1] op_sel_hi:[1,0] neg_lo:[0,1]
	v_pk_add_f32 v[196:197], v[170:171], v[206:207]
	v_pk_add_f32 v[170:171], v[170:171], v[206:207] neg_lo:[0,1] neg_hi:[0,1]
	v_pk_mul_f32 v[2:3], v[2:3], v[196:197] op_sel:[0,1] op_sel_hi:[1,0]
	v_pk_add_f32 v[206:207], v[198:199], v[218:219] op_sel:[0,1] op_sel_hi:[1,0] neg_hi:[0,1]
	v_pk_add_f32 v[198:199], v[198:199], v[218:219] op_sel:[0,1] op_sel_hi:[1,0] neg_lo:[0,1]
	v_pk_add_f32 v[218:219], v[172:173], v[180:181]
	v_pk_add_f32 v[172:173], v[172:173], v[180:181] neg_lo:[0,1] neg_hi:[0,1]
	v_pk_add_f32 v[180:181], v[176:177], v[174:175] op_sel:[0,1] op_sel_hi:[1,0] neg_hi:[0,1]
	v_pk_add_f32 v[174:175], v[176:177], v[174:175] op_sel:[0,1] op_sel_hi:[1,0] neg_lo:[0,1]
	v_pk_add_f32 v[176:177], v[162:163], v[182:183]
	v_pk_fma_f32 v[2:3], v[4:5], v[196:197], v[2:3] op_sel_hi:[0,1,1]
	v_pk_mul_f32 v[4:5], v[6:7], v[210:211] op_sel:[1,1] op_sel_hi:[1,0] neg_lo:[1,0]
	v_mov_b32_e32 v49, v39
	v_pk_fma_f32 v[4:5], v[6:7], v[210:211], v[4:5] op_sel_hi:[0,1,1]
	v_pk_mul_f32 v[6:7], v[8:9], v[176:177] op_sel:[1,1] op_sel_hi:[1,0] neg_lo:[1,0]
	v_pk_add_f32 v[162:163], v[162:163], v[182:183] neg_lo:[0,1] neg_hi:[0,1]
	v_pk_fma_f32 v[6:7], v[8:9], v[176:177], v[6:7] op_sel_hi:[0,1,1]
	v_pk_mul_f32 v[8:9], v[10:11], v[220:221] op_sel:[1,1] op_sel_hi:[1,0] neg_lo:[1,0]
	v_pk_add_f32 v[182:183], v[164:165], v[178:179] op_sel:[0,1] op_sel_hi:[1,0] neg_hi:[0,1]
	v_pk_add_f32 v[164:165], v[164:165], v[178:179] op_sel:[0,1] op_sel_hi:[1,0] neg_lo:[0,1]
	v_pk_add_f32 v[178:179], v[158:159], v[166:167]
	v_pk_fma_f32 v[8:9], v[10:11], v[220:221], v[8:9] op_sel_hi:[0,1,1]
	v_pk_mul_f32 v[10:11], v[24:25], v[218:219] op_sel:[0,1] op_sel_hi:[1,0]
	v_pk_mul_f32 v[12:13], v[28:29], v[212:213] op_sel:[0,1] op_sel_hi:[1,0]
	v_pk_add_f32 v[158:159], v[158:159], v[166:167] neg_lo:[0,1] neg_hi:[0,1]
	v_pk_add_f32 v[166:167], v[154:155], v[160:161]
	v_pk_fma_f32 v[10:11], v[16:17], v[218:219], v[10:11] op_sel_hi:[0,1,1]
	v_pk_fma_f32 v[12:13], v[18:19], v[212:213], v[12:13] op_sel_hi:[0,1,1]
	v_pk_mul_f32 v[14:15], v[32:33], v[178:179] op_sel:[0,1] op_sel_hi:[1,0]
	v_pk_mul_f32 v[16:17], v[40:41], v[222:223] op_sel:[0,1] op_sel_hi:[1,0]
	v_pk_mul_f32 v[18:19], v[44:45], v[206:207] op_sel:[0,1] op_sel_hi:[1,0]
	v_pk_mul_f32 v[20:21], v[48:49], v[216:217] op_sel:[0,1] op_sel_hi:[1,0]
	v_xor_b32_e32 v80, 0x80000000, v71
	v_xor_b32_e32 v84, 0x80000000, v75
	v_xor_b32_e32 v88, 0x80000000, v79
	v_xor_b32_e32 v92, 0x80000000, v83
	v_xor_b32_e32 v96, 0x80000000, v87
	v_xor_b32_e32 v100, 0x80000000, v91
	v_xor_b32_e32 v104, 0x80000000, v95
	v_xor_b32_e32 v108, 0x80000000, v99
	v_xor_b32_e32 v112, 0x80000000, v103
	v_xor_b32_e32 v116, 0x80000000, v107
	v_xor_b32_e32 v120, 0x80000000, v111
	v_xor_b32_e32 v124, 0x80000000, v115
	v_xor_b32_e32 v126, 0x80000000, v119
	v_xor_b32_e32 v128, 0x80000000, v123
	v_mov_b32_e32 v81, v71
	v_mov_b32_e32 v85, v75
	v_mov_b32_e32 v89, v79
	v_mov_b32_e32 v93, v83
	v_mov_b32_e32 v97, v87
	v_mov_b32_e32 v101, v91
	v_mov_b32_e32 v105, v95
	v_mov_b32_e32 v109, v99
	v_mov_b32_e32 v113, v103
	v_mov_b32_e32 v117, v107
	v_mov_b32_e32 v121, v111
	v_mov_b32_e32 v125, v115
	v_mov_b32_e32 v127, v119
	v_mov_b32_e32 v129, v123
	v_pk_add_f32 v[154:155], v[154:155], v[160:161] neg_lo:[0,1] neg_hi:[0,1]
	v_pk_fma_f32 v[14:15], v[22:23], v[178:179], v[14:15] op_sel_hi:[0,1,1]
	v_pk_fma_f32 v[16:17], v[26:27], v[222:223], v[16:17] op_sel_hi:[0,1,1]
	v_pk_fma_f32 v[18:19], v[30:31], v[206:207], v[18:19] op_sel_hi:[0,1,1]
	v_pk_fma_f32 v[20:21], v[38:39], v[216:217], v[20:21] op_sel_hi:[0,1,1]
	v_pk_mul_f32 v[22:23], v[42:43], v[182:183] op_sel:[1,1] op_sel_hi:[1,0] neg_lo:[1,0]
	v_pk_mul_f32 v[24:25], v[46:47], v[214:215] op_sel:[1,1] op_sel_hi:[1,0] neg_lo:[1,0]
	v_pk_mul_f32 v[26:27], v[50:51], v[180:181] op_sel:[1,1] op_sel_hi:[1,0] neg_lo:[1,0]
	v_pk_mul_f32 v[28:29], v[54:55], v[204:205] op_sel:[1,1] op_sel_hi:[1,0] neg_lo:[1,0]
	v_pk_mul_f32 v[30:31], v[58:59], v[166:167] op_sel:[1,1] op_sel_hi:[1,0] neg_lo:[1,0]
	v_pk_mul_f32 v[32:33], v[62:63], v[168:169] op_sel:[1,1] op_sel_hi:[1,0] neg_lo:[1,0]
	v_pk_mul_f32 v[38:39], v[66:67], v[170:171] op_sel:[1,1] op_sel_hi:[1,0] neg_lo:[1,0]
	v_pk_fma_f32 v[22:23], v[42:43], v[182:183], v[22:23] op_sel_hi:[0,1,1]
	v_pk_fma_f32 v[24:25], v[46:47], v[214:215], v[24:25] op_sel_hi:[0,1,1]
	v_pk_fma_f32 v[26:27], v[50:51], v[180:181], v[26:27] op_sel_hi:[0,1,1]
	v_pk_fma_f32 v[28:29], v[54:55], v[204:205], v[28:29] op_sel_hi:[0,1,1]
	v_pk_fma_f32 v[30:31], v[58:59], v[166:167], v[30:31] op_sel_hi:[0,1,1]
	v_pk_fma_f32 v[32:33], v[62:63], v[168:169], v[32:33] op_sel_hi:[0,1,1]
	v_pk_fma_f32 v[38:39], v[66:67], v[170:171], v[38:39] op_sel_hi:[0,1,1]
	v_pk_mul_f32 v[40:41], v[80:81], v[192:193] op_sel:[0,1] op_sel_hi:[1,0]
	v_pk_mul_f32 v[42:43], v[84:85], v[162:163] op_sel:[0,1] op_sel_hi:[1,0]
	v_pk_mul_f32 v[44:45], v[88:89], v[186:187] op_sel:[0,1] op_sel_hi:[1,0]
	v_pk_mul_f32 v[46:47], v[92:93], v[172:173] op_sel:[0,1] op_sel_hi:[1,0]
	v_pk_mul_f32 v[48:49], v[96:97], v[188:189] op_sel:[0,1] op_sel_hi:[1,0]
	v_pk_mul_f32 v[50:51], v[100:101], v[158:159] op_sel:[0,1] op_sel_hi:[1,0]
	v_pk_mul_f32 v[52:53], v[104:105], v[184:185] op_sel:[0,1] op_sel_hi:[1,0]
	v_pk_mul_f32 v[54:55], v[108:109], v[198:199] op_sel:[0,1] op_sel_hi:[1,0]
	v_pk_mul_f32 v[56:57], v[112:113], v[194:195] op_sel:[0,1] op_sel_hi:[1,0]
	v_pk_mul_f32 v[58:59], v[116:117], v[164:165] op_sel:[0,1] op_sel_hi:[1,0]
	v_pk_mul_f32 v[60:61], v[120:121], v[208:209] op_sel:[0,1] op_sel_hi:[1,0]
	v_pk_mul_f32 v[62:63], v[124:125], v[174:175] op_sel:[0,1] op_sel_hi:[1,0]
	v_pk_mul_f32 v[64:65], v[126:127], v[190:191] op_sel:[0,1] op_sel_hi:[1,0]
	v_pk_mul_f32 v[66:67], v[128:129], v[154:155] op_sel:[0,1] op_sel_hi:[1,0]
	v_pk_fma_f32 v[40:41], v[70:71], v[192:193], v[40:41] op_sel_hi:[0,1,1]
	v_pk_fma_f32 v[42:43], v[74:75], v[162:163], v[42:43] op_sel_hi:[0,1,1]
	v_pk_fma_f32 v[44:45], v[78:79], v[186:187], v[44:45] op_sel_hi:[0,1,1]
	v_pk_fma_f32 v[46:47], v[82:83], v[172:173], v[46:47] op_sel_hi:[0,1,1]
	v_pk_fma_f32 v[48:49], v[86:87], v[188:189], v[48:49] op_sel_hi:[0,1,1]
	v_pk_fma_f32 v[50:51], v[90:91], v[158:159], v[50:51] op_sel_hi:[0,1,1]
	v_pk_fma_f32 v[52:53], v[94:95], v[184:185], v[52:53] op_sel_hi:[0,1,1]
	v_pk_fma_f32 v[54:55], v[98:99], v[198:199], v[54:55] op_sel_hi:[0,1,1]
	v_pk_fma_f32 v[56:57], v[102:103], v[194:195], v[56:57] op_sel_hi:[0,1,1]
	v_pk_fma_f32 v[58:59], v[106:107], v[164:165], v[58:59] op_sel_hi:[0,1,1]
	v_pk_fma_f32 v[60:61], v[110:111], v[208:209], v[60:61] op_sel_hi:[0,1,1]
	v_pk_fma_f32 v[62:63], v[114:115], v[174:175], v[62:63] op_sel_hi:[0,1,1]
	v_pk_fma_f32 v[64:65], v[118:119], v[190:191], v[64:65] op_sel_hi:[0,1,1]
	v_pk_fma_f32 v[66:67], v[122:123], v[154:155], v[66:67] op_sel_hi:[0,1,1]
	ds_write_b64 v36, v[156:157]
	ds_write_b64 v36, v[32:33] offset:2112
	ds_write_b64 v36, v[16:17] offset:4224
	ds_write_b64 v36, v[52:53] offset:6336
	ds_write_b64 v36, v[8:9] offset:8448
	ds_write_b64 v36, v[44:45] offset:10560
	ds_write_b64 v36, v[24:25] offset:12672
	ds_write_b64 v36, v[60:61] offset:14784
	ds_write_b64 v36, v[4:5] offset:16896
	ds_write_b64 v36, v[40:41] offset:19008
	ds_write_b64 v36, v[20:21] offset:21120
	ds_write_b64 v36, v[56:57] offset:23232
	ds_write_b64 v36, v[12:13] offset:25344
	ds_write_b64 v36, v[48:49] offset:27456
	ds_write_b64 v36, v[28:29] offset:29568
	ds_write_b64 v36, v[64:65] offset:31680
	ds_write_b64 v36, v[2:3] offset:33792
	ds_write_b64 v36, v[38:39] offset:35904
	ds_write_b64 v36, v[18:19] offset:38016
	ds_write_b64 v36, v[54:55] offset:40128
	ds_write_b64 v36, v[10:11] offset:42240
	ds_write_b64 v36, v[46:47] offset:44352
	ds_write_b64 v36, v[26:27] offset:46464
	ds_write_b64 v36, v[62:63] offset:48576
	ds_write_b64 v36, v[6:7] offset:50688
	ds_write_b64 v36, v[42:43] offset:52800
	ds_write_b64 v36, v[22:23] offset:54912
	ds_write_b64 v36, v[58:59] offset:57024
	ds_write_b64 v36, v[14:15] offset:59136
	ds_write_b64 v36, v[50:51] offset:61248
	ds_write_b64 v36, v[30:31] offset:63360
	ds_write_b64 v36, v[66:67] offset:65472
	v_mov_b32_e32 v3, v130
	s_waitcnt lgkmcnt(0)
	s_barrier
	s_nop 0
	v_and_b32_e32 v5, 15, v3
	v_cvt_f32_ubyte0_e32 v2, v5
	v_mul_f32_e32 v4, 0x3b800000, v2
	v_sin_f32_e32 v2, v4
	v_cos_f32_e32 v4, v4
	v_lshlrev_b32_e32 v66, 3, v5
	v_lshlrev_b32_e32 v36, 4, v3
	v_xor_b32_e32 v5, 0x80000000, v2
	v_mov_b32_e32 v3, v5
	v_pk_mul_f32 v[6:7], v[4:5], v[2:3] op_sel:[1,0] op_sel_hi:[0,1]
	v_pk_fma_f32 v[6:7], v[4:5], v[4:5], v[6:7] op_sel_hi:[1,0,1]
	s_nop 0
	v_pk_mul_f32 v[10:11], v[6:7], v[6:7] op_sel:[1,1] op_sel_hi:[0,1] neg_lo:[0,1]
	v_pk_fma_f32 v[10:11], v[6:7], v[6:7], v[10:11] op_sel_hi:[1,0,1]
	v_pk_mul_f32 v[8:9], v[2:3], v[6:7] op_sel:[0,1] op_sel_hi:[1,0]
	v_pk_mul_f32 v[30:31], v[10:11], v[10:11] op_sel:[1,1] op_sel_hi:[0,1] neg_lo:[0,1]
	v_pk_fma_f32 v[30:31], v[10:11], v[10:11], v[30:31] op_sel_hi:[1,0,1]
	v_pk_mul_f32 v[16:17], v[2:3], v[10:11] op_sel:[0,1] op_sel_hi:[1,0]
	v_pk_mul_f32 v[50:51], v[10:11], v[30:31] op_sel:[1,1] op_sel_hi:[1,0] neg_lo:[1,0]
	v_pk_mul_f32 v[38:39], v[2:3], v[30:31] op_sel:[0,1] op_sel_hi:[1,0]
	v_pk_fma_f32 v[50:51], v[10:11], v[30:31], v[50:51] op_sel_hi:[0,1,1]
	v_pk_mul_f32 v[54:55], v[2:3], v[50:51] op_sel:[0,1] op_sel_hi:[1,0]
	v_pk_fma_f32 v[8:9], v[4:5], v[6:7], v[8:9] op_sel_hi:[0,1,1]
	v_pk_fma_f32 v[16:17], v[4:5], v[10:11], v[16:17] op_sel_hi:[0,1,1]
	v_pk_fma_f32 v[38:39], v[4:5], v[30:31], v[38:39] op_sel_hi:[0,1,1]
	v_pk_fma_f32 v[54:55], v[4:5], v[50:51], v[54:55] op_sel_hi:[0,1,1]
	v_and_b32_e32 v5, 0xffffff00, v36
	v_lshlrev_b32_e32 v36, 3, v5
	v_add3_u32 v36, 0, v66, v36
	v_ashrrev_i32_e32 v66, 2, v5
	v_add_u32_e32 v108, v36, v66
	ds_read2_b64 v[66:69], v108 offset1:16
	ds_read2_b64 v[70:73], v108 offset0:33 offset1:49
	ds_read2_b64 v[74:77], v108 offset0:66 offset1:82
	ds_read2_b64 v[78:81], v108 offset0:132 offset1:148
	ds_read2_b64 v[82:85], v108 offset0:99 offset1:115
	ds_read2_b64 v[86:89], v108 offset0:165 offset1:181
	ds_read2_b64 v[90:93], v108 offset0:198 offset1:214
	ds_read2_b64 v[94:97], v108 offset0:231 offset1:247
	s_waitcnt lgkmcnt(4)
	v_pk_add_f32 v[98:99], v[66:67], v[78:79]
	v_pk_add_f32 v[66:67], v[66:67], v[78:79] neg_lo:[0,1] neg_hi:[0,1]
	v_pk_add_f32 v[78:79], v[68:69], v[80:81]
	v_pk_add_f32 v[68:69], v[68:69], v[80:81] neg_lo:[0,1] neg_hi:[0,1]
	s_waitcnt lgkmcnt(1)
	v_pk_add_f32 v[100:101], v[76:77], v[92:93]
	v_pk_mul_f32 v[80:81], v[68:69], s[44:45]
	v_pk_add_f32 v[76:77], v[76:77], v[92:93] neg_lo:[0,1] neg_hi:[0,1]
	v_pk_fma_f32 v[68:69], v[68:69], s[42:43], v[80:81] op_sel:[0,0,1] op_sel_hi:[1,0,0]
	v_pk_add_f32 v[80:81], v[70:71], v[86:87]
	v_pk_add_f32 v[70:71], v[70:71], v[86:87] neg_lo:[0,1] neg_hi:[0,1]
	v_pk_mul_f32 v[92:93], v[76:77], s[76:77]
	v_pk_mul_f32 v[86:87], v[70:71], s[68:69]
	v_pk_fma_f32 v[76:77], v[76:77], s[72:73], v[92:93] op_sel:[0,0,1] op_sel_hi:[1,0,0] neg_lo:[1,0,0] neg_hi:[1,0,0]
	v_pk_fma_f32 v[70:71], v[70:71], s[64:65], v[86:87] op_sel:[0,0,1] op_sel_hi:[1,0,0]
	v_pk_add_f32 v[86:87], v[72:73], v[88:89]
	v_pk_add_f32 v[72:73], v[72:73], v[88:89] neg_lo:[0,1] neg_hi:[0,1]
	s_waitcnt lgkmcnt(0)
	v_pk_add_f32 v[92:93], v[82:83], v[94:95]
	v_pk_add_f32 v[82:83], v[82:83], v[94:95] neg_lo:[0,1] neg_hi:[0,1]
	v_pk_mul_f32 v[88:89], v[72:73], s[76:77]
	v_pk_mul_f32 v[94:95], v[82:83], s[68:69]
	v_pk_fma_f32 v[72:73], v[72:73], s[72:73], v[88:89] op_sel:[0,0,1] op_sel_hi:[1,0,0]
	v_pk_add_f32 v[88:89], v[74:75], v[90:91]
	v_pk_add_f32 v[90:91], v[74:75], v[90:91] neg_lo:[0,1] neg_hi:[0,1]
	v_pk_fma_f32 v[82:83], v[82:83], s[64:65], v[94:95] op_sel:[0,0,1] op_sel_hi:[1,0,0] neg_lo:[1,0,0] neg_hi:[1,0,0]
	v_pk_add_f32 v[94:95], v[84:85], v[96:97]
	v_pk_add_f32 v[84:85], v[84:85], v[96:97] neg_lo:[0,1] neg_hi:[0,1]
	v_pk_mul_f32 v[96:97], v[84:85], s[44:45]
	v_pk_fma_f32 v[84:85], v[84:85], s[42:43], v[96:97] op_sel:[0,0,1] op_sel_hi:[1,0,0] neg_lo:[1,0,0] neg_hi:[1,0,0]
	v_pk_add_f32 v[96:97], v[98:99], v[88:89]
	v_pk_add_f32 v[88:89], v[98:99], v[88:89] neg_lo:[0,1] neg_hi:[0,1]
	v_pk_add_f32 v[98:99], v[78:79], v[100:101]
	v_pk_add_f32 v[78:79], v[78:79], v[100:101] neg_lo:[0,1] neg_hi:[0,1]
	v_pk_add_f32 v[102:103], v[86:87], v[94:95]
	v_pk_add_f32 v[86:87], v[86:87], v[94:95] neg_lo:[0,1] neg_hi:[0,1]
	v_pk_add_f32 v[74:75], v[66:67], v[90:91] op_sel:[0,1] op_sel_hi:[1,0] neg_hi:[0,1]
	v_pk_add_f32 v[66:67], v[66:67], v[90:91] op_sel:[0,1] op_sel_hi:[1,0] neg_lo:[0,1]
	v_pk_add_f32 v[90:91], v[68:69], v[76:77]
	v_pk_add_f32 v[68:69], v[68:69], v[76:77] neg_lo:[0,1] neg_hi:[0,1]
	v_pk_mul_f32 v[100:101], v[78:79], s[68:69]
	v_pk_mul_f32 v[94:95], v[86:87], s[68:69]
	v_pk_mul_f32 v[76:77], v[68:69], s[68:69]
	v_pk_fma_f32 v[78:79], v[78:79], s[64:65], v[100:101] op_sel:[0,0,1] op_sel_hi:[1,0,0]
	v_pk_add_f32 v[100:101], v[80:81], v[92:93]
	v_pk_add_f32 v[92:93], v[80:81], v[92:93] neg_lo:[0,1] neg_hi:[0,1]
	v_pk_fma_f32 v[86:87], v[86:87], s[64:65], v[94:95] op_sel:[0,0,1] op_sel_hi:[1,0,0] neg_lo:[1,0,0] neg_hi:[1,0,0]
	v_pk_fma_f32 v[68:69], v[68:69], s[64:65], v[76:77] op_sel:[0,0,1] op_sel_hi:[1,0,0]
	v_pk_add_f32 v[76:77], v[70:71], v[82:83]
	v_pk_add_f32 v[94:95], v[72:73], v[84:85]
	v_pk_add_f32 v[72:73], v[72:73], v[84:85] neg_lo:[0,1] neg_hi:[0,1]
	v_pk_add_f32 v[70:71], v[70:71], v[82:83] neg_lo:[0,1] neg_hi:[0,1]
	v_pk_mul_f32 v[84:85], v[72:73], s[68:69]
	v_pk_add_f32 v[104:105], v[74:75], v[76:77]
	v_pk_add_f32 v[74:75], v[74:75], v[76:77] neg_lo:[0,1] neg_hi:[0,1]
	v_pk_add_f32 v[76:77], v[90:91], v[94:95]
	v_pk_add_f32 v[94:95], v[90:91], v[94:95] neg_lo:[0,1] neg_hi:[0,1]
	v_pk_mul_f32 v[22:23], v[6:7], v[10:11] op_sel:[1,1] op_sel_hi:[1,0] neg_lo:[1,0]
	v_xor_b32_e32 v83, 0x80000000, v70
	v_pk_fma_f32 v[72:73], v[72:73], s[64:65], v[84:85] op_sel:[0,0,1] op_sel_hi:[1,0,0] neg_lo:[1,0,0] neg_hi:[1,0,0]
	v_pk_add_f32 v[80:81], v[88:89], v[92:93] op_sel:[0,1] op_sel_hi:[1,0] neg_hi:[0,1]
	v_pk_add_f32 v[88:89], v[88:89], v[92:93] op_sel:[0,1] op_sel_hi:[1,0] neg_lo:[0,1]
	v_pk_add_f32 v[92:93], v[78:79], v[86:87]
	v_pk_add_f32 v[86:87], v[78:79], v[86:87] neg_lo:[0,1] neg_hi:[0,1]
	v_mov_b32_e32 v82, v71
	v_pk_fma_f32 v[22:23], v[6:7], v[10:11], v[22:23] op_sel_hi:[0,1,1]
	v_pk_mul_f32 v[26:27], v[10:11], v[8:9] op_sel:[1,1] op_sel_hi:[0,1] neg_lo:[0,1]
	v_pk_add_f32 v[70:71], v[66:67], v[82:83]
	v_pk_add_f32 v[66:67], v[66:67], v[82:83] neg_lo:[0,1] neg_hi:[0,1]
	v_pk_add_f32 v[82:83], v[68:69], v[72:73]
	v_pk_add_f32 v[72:73], v[68:69], v[72:73] neg_lo:[0,1] neg_hi:[0,1]
	v_pk_add_f32 v[90:91], v[74:75], v[94:95] op_sel:[0,1] op_sel_hi:[1,0] neg_hi:[0,1]
	v_pk_fma_f32 v[26:27], v[10:11], v[8:9], v[26:27] op_sel_hi:[1,0,1]
	v_pk_add_f32 v[78:79], v[88:89], v[86:87] op_sel:[0,1] op_sel_hi:[1,0] neg_hi:[0,1]
	v_pk_add_f32 v[74:75], v[74:75], v[94:95] op_sel:[0,1] op_sel_hi:[1,0] neg_lo:[0,1]
	v_pk_mul_f32 v[94:95], v[16:17], v[90:91] op_sel:[1,1] op_sel_hi:[1,0] neg_lo:[1,0]
	v_pk_add_f32 v[84:85], v[96:97], v[100:101]
	v_pk_add_f32 v[96:97], v[96:97], v[100:101] neg_lo:[0,1] neg_hi:[0,1]
	v_pk_add_f32 v[100:101], v[98:99], v[102:103]
	v_pk_add_f32 v[68:69], v[66:67], v[72:73] op_sel:[0,1] op_sel_hi:[1,0] neg_hi:[0,1]
	v_pk_fma_f32 v[90:91], v[16:17], v[90:91], v[94:95] op_sel_hi:[0,1,1]
	v_pk_mul_f32 v[94:95], v[22:23], v[78:79] op_sel:[1,1] op_sel_hi:[1,0] neg_lo:[1,0]
	v_pk_mul_f32 v[42:43], v[6:7], v[30:31] op_sel:[1,1] op_sel_hi:[1,0] neg_lo:[1,0]
	v_pk_add_f32 v[106:107], v[84:85], v[100:101]
	v_pk_add_f32 v[84:85], v[84:85], v[100:101] neg_lo:[0,1] neg_hi:[0,1]
	v_pk_fma_f32 v[78:79], v[22:23], v[78:79], v[94:95] op_sel_hi:[0,1,1]
	v_pk_mul_f32 v[94:95], v[26:27], v[68:69] op_sel:[1,1] op_sel_hi:[1,0] neg_lo:[1,0]
	v_xor_b32_e32 v40, 0x80000000, v39
	v_mov_b32_e32 v41, v39
	v_pk_fma_f32 v[42:43], v[6:7], v[30:31], v[42:43] op_sel_hi:[0,1,1]
	v_pk_mul_f32 v[46:47], v[8:9], v[30:31] op_sel:[1,1] op_sel_hi:[1,0] neg_lo:[1,0]
	v_pk_add_f32 v[86:87], v[88:89], v[86:87] op_sel:[0,1] op_sel_hi:[1,0] neg_lo:[0,1]
	v_pk_add_f32 v[88:89], v[104:105], v[76:77]
	v_pk_add_f32 v[76:77], v[104:105], v[76:77] neg_lo:[0,1] neg_hi:[0,1]
	v_pk_fma_f32 v[68:69], v[26:27], v[68:69], v[94:95] op_sel_hi:[0,1,1]
	v_pk_mul_f32 v[94:95], v[30:31], v[84:85] op_sel:[1,1] op_sel_hi:[1,0] neg_lo:[1,0]
	v_xor_b32_e32 v44, 0x80000000, v43
	v_mov_b32_e32 v45, v43
	v_pk_fma_f32 v[46:47], v[8:9], v[30:31], v[46:47] op_sel_hi:[0,1,1]
	v_pk_add_f32 v[102:103], v[98:99], v[102:103] neg_lo:[0,1] neg_hi:[0,1]
	v_pk_add_f32 v[100:101], v[80:81], v[92:93]
	v_pk_add_f32 v[80:81], v[80:81], v[92:93] neg_lo:[0,1] neg_hi:[0,1]
	v_pk_fma_f32 v[84:85], v[30:31], v[84:85], v[94:95] op_sel_hi:[0,1,1]
	v_pk_mul_f32 v[94:95], v[40:41], v[76:77] op_sel:[0,1] op_sel_hi:[1,0]
	v_xor_b32_e32 v48, 0x80000000, v47
	v_mov_b32_e32 v49, v47
	v_pk_add_f32 v[92:93], v[70:71], v[82:83]
	v_pk_add_f32 v[70:71], v[70:71], v[82:83] neg_lo:[0,1] neg_hi:[0,1]
	v_pk_fma_f32 v[76:77], v[38:39], v[76:77], v[94:95] op_sel_hi:[0,1,1]
	v_pk_mul_f32 v[94:95], v[44:45], v[80:81] op_sel:[0,1] op_sel_hi:[1,0]
	v_xor_b32_e32 v52, 0x80000000, v51
	v_mov_b32_e32 v53, v51
	v_pk_mul_f32 v[58:59], v[6:7], v[50:51] op_sel:[1,1] op_sel_hi:[1,0] neg_lo:[1,0]
	v_pk_add_f32 v[98:99], v[96:97], v[102:103] op_sel:[0,1] op_sel_hi:[1,0] neg_hi:[0,1]
	v_pk_add_f32 v[96:97], v[96:97], v[102:103] op_sel:[0,1] op_sel_hi:[1,0] neg_lo:[0,1]
	v_pk_fma_f32 v[80:81], v[42:43], v[80:81], v[94:95] op_sel_hi:[0,1,1]
	v_pk_mul_f32 v[94:95], v[48:49], v[70:71] op_sel:[0,1] op_sel_hi:[1,0]
	v_xor_b32_e32 v56, 0x80000000, v55
	v_mov_b32_e32 v57, v55
	v_pk_fma_f32 v[58:59], v[6:7], v[50:51], v[58:59] op_sel_hi:[0,1,1]
	v_pk_mul_f32 v[62:63], v[8:9], v[50:51] op_sel:[1,1] op_sel_hi:[1,0] neg_lo:[1,0]
	v_pk_fma_f32 v[70:71], v[46:47], v[70:71], v[94:95] op_sel_hi:[0,1,1]
	v_pk_mul_f32 v[94:95], v[52:53], v[96:97] op_sel:[0,1] op_sel_hi:[1,0]
	v_xor_b32_e32 v60, 0x80000000, v59
	v_mov_b32_e32 v61, v59
	v_pk_fma_f32 v[62:63], v[8:9], v[50:51], v[62:63] op_sel_hi:[0,1,1]
	v_pk_add_f32 v[66:67], v[66:67], v[72:73] op_sel:[0,1] op_sel_hi:[1,0] neg_lo:[0,1]
	v_pk_mul_f32 v[72:73], v[2:3], v[88:89] op_sel:[0,1] op_sel_hi:[1,0]
	v_pk_fma_f32 v[94:95], v[50:51], v[96:97], v[94:95] op_sel_hi:[0,1,1]
	v_pk_mul_f32 v[96:97], v[56:57], v[74:75] op_sel:[0,1] op_sel_hi:[1,0]
	v_xor_b32_e32 v64, 0x80000000, v63
	v_mov_b32_e32 v65, v63
	v_pk_fma_f32 v[72:73], v[4:5], v[88:89], v[72:73] op_sel_hi:[0,1,1]
	v_pk_mul_f32 v[88:89], v[8:9], v[92:93] op_sel:[1,1] op_sel_hi:[1,0] neg_lo:[1,0]
	v_pk_fma_f32 v[74:75], v[54:55], v[74:75], v[96:97] op_sel_hi:[0,1,1]
	v_pk_mul_f32 v[96:97], v[60:61], v[86:87] op_sel:[0,1] op_sel_hi:[1,0]
	v_add_u32_e32 v5, 0x2000, v5
	v_pk_mul_f32 v[82:83], v[6:7], v[100:101] op_sel:[1,1] op_sel_hi:[1,0] neg_lo:[1,0]
	v_pk_fma_f32 v[88:89], v[8:9], v[92:93], v[88:89] op_sel_hi:[0,1,1]
	v_pk_mul_f32 v[92:93], v[10:11], v[98:99] op_sel:[1,1] op_sel_hi:[1,0] neg_lo:[1,0]
	v_pk_fma_f32 v[86:87], v[58:59], v[86:87], v[96:97] op_sel_hi:[0,1,1]
	v_pk_mul_f32 v[96:97], v[64:65], v[66:67] op_sel:[0,1] op_sel_hi:[1,0]
	v_ashrrev_i32_e32 v5, 2, v5
	v_pk_fma_f32 v[82:83], v[6:7], v[100:101], v[82:83] op_sel_hi:[0,1,1]
	v_pk_fma_f32 v[92:93], v[10:11], v[98:99], v[92:93] op_sel_hi:[0,1,1]
	v_pk_fma_f32 v[66:67], v[62:63], v[66:67], v[96:97] op_sel_hi:[0,1,1]
	ds_write2_b64 v108, v[106:107], v[84:85] offset1:16
	ds_write2_b64 v108, v[92:93], v[94:95] offset0:33 offset1:49
	ds_write2_b64 v108, v[82:83], v[80:81] offset0:66 offset1:82
	ds_write2_b64 v108, v[78:79], v[86:87] offset0:99 offset1:115
	ds_write2_b64 v108, v[72:73], v[76:77] offset0:132 offset1:148
	ds_write2_b64 v108, v[90:91], v[74:75] offset0:165 offset1:181
	ds_write2_b64 v108, v[88:89], v[70:71] offset0:198 offset1:214
	ds_write2_b64 v108, v[68:69], v[66:67] offset0:231 offset1:247
	v_add3_u32 v36, v36, v5, s30
	ds_read2_b64 v[66:69], v36 offset1:16
	ds_read2_b64 v[70:73], v36 offset0:33 offset1:49
	ds_read2_b64 v[74:77], v36 offset0:66 offset1:82
	ds_read2_b64 v[78:81], v36 offset0:132 offset1:148
	ds_read2_b64 v[82:85], v36 offset0:99 offset1:115
	ds_read2_b64 v[86:89], v36 offset0:165 offset1:181
	ds_read2_b64 v[90:93], v36 offset0:198 offset1:214
	ds_read2_b64 v[94:97], v36 offset0:231 offset1:247
	s_waitcnt lgkmcnt(4)
	v_pk_add_f32 v[98:99], v[66:67], v[78:79]
	v_pk_add_f32 v[66:67], v[66:67], v[78:79] neg_lo:[0,1] neg_hi:[0,1]
	v_pk_add_f32 v[78:79], v[68:69], v[80:81]
	v_pk_add_f32 v[68:69], v[68:69], v[80:81] neg_lo:[0,1] neg_hi:[0,1]
	s_waitcnt lgkmcnt(1)
	v_pk_add_f32 v[100:101], v[76:77], v[92:93]
	v_pk_mul_f32 v[80:81], v[68:69], s[44:45]
	v_pk_add_f32 v[76:77], v[76:77], v[92:93] neg_lo:[0,1] neg_hi:[0,1]
	v_pk_fma_f32 v[68:69], v[68:69], s[42:43], v[80:81] op_sel:[0,0,1] op_sel_hi:[1,0,0]
	v_pk_add_f32 v[80:81], v[70:71], v[86:87]
	v_pk_add_f32 v[70:71], v[70:71], v[86:87] neg_lo:[0,1] neg_hi:[0,1]
	v_pk_mul_f32 v[92:93], v[76:77], s[76:77]
	v_pk_mul_f32 v[86:87], v[70:71], s[68:69]
	v_pk_fma_f32 v[76:77], v[76:77], s[72:73], v[92:93] op_sel:[0,0,1] op_sel_hi:[1,0,0] neg_lo:[1,0,0] neg_hi:[1,0,0]
	s_waitcnt lgkmcnt(0)
	v_pk_add_f32 v[92:93], v[82:83], v[94:95]
	v_pk_add_f32 v[82:83], v[82:83], v[94:95] neg_lo:[0,1] neg_hi:[0,1]
	v_pk_fma_f32 v[70:71], v[70:71], s[64:65], v[86:87] op_sel:[0,0,1] op_sel_hi:[1,0,0]
	v_pk_add_f32 v[86:87], v[72:73], v[88:89]
	v_pk_add_f32 v[72:73], v[72:73], v[88:89] neg_lo:[0,1] neg_hi:[0,1]
	v_pk_mul_f32 v[94:95], v[82:83], s[68:69]
	v_pk_mul_f32 v[88:89], v[72:73], s[76:77]
	v_pk_fma_f32 v[82:83], v[82:83], s[64:65], v[94:95] op_sel:[0,0,1] op_sel_hi:[1,0,0] neg_lo:[1,0,0] neg_hi:[1,0,0]
	v_pk_add_f32 v[94:95], v[84:85], v[96:97]
	v_pk_add_f32 v[84:85], v[84:85], v[96:97] neg_lo:[0,1] neg_hi:[0,1]
	v_pk_fma_f32 v[72:73], v[72:73], s[72:73], v[88:89] op_sel:[0,0,1] op_sel_hi:[1,0,0]
	v_pk_add_f32 v[88:89], v[74:75], v[90:91]
	v_pk_mul_f32 v[96:97], v[84:85], s[44:45]
	v_pk_add_f32 v[90:91], v[74:75], v[90:91] neg_lo:[0,1] neg_hi:[0,1]
	v_pk_fma_f32 v[84:85], v[84:85], s[42:43], v[96:97] op_sel:[0,0,1] op_sel_hi:[1,0,0] neg_lo:[1,0,0] neg_hi:[1,0,0]
	v_pk_add_f32 v[96:97], v[98:99], v[88:89]
	v_pk_add_f32 v[88:89], v[98:99], v[88:89] neg_lo:[0,1] neg_hi:[0,1]
	v_pk_add_f32 v[98:99], v[78:79], v[100:101]
	v_pk_add_f32 v[78:79], v[78:79], v[100:101] neg_lo:[0,1] neg_hi:[0,1]
	v_pk_add_f32 v[102:103], v[86:87], v[94:95]
	v_pk_add_f32 v[86:87], v[86:87], v[94:95] neg_lo:[0,1] neg_hi:[0,1]
	v_pk_mul_f32 v[100:101], v[78:79], s[68:69]
	v_pk_mul_f32 v[94:95], v[86:87], s[68:69]
	v_pk_fma_f32 v[78:79], v[78:79], s[64:65], v[100:101] op_sel:[0,0,1] op_sel_hi:[1,0,0]
	v_pk_add_f32 v[100:101], v[80:81], v[92:93]
	v_pk_add_f32 v[92:93], v[80:81], v[92:93] neg_lo:[0,1] neg_hi:[0,1]
	v_pk_fma_f32 v[86:87], v[86:87], s[64:65], v[94:95] op_sel:[0,0,1] op_sel_hi:[1,0,0] neg_lo:[1,0,0] neg_hi:[1,0,0]
	v_pk_add_f32 v[74:75], v[66:67], v[90:91] op_sel:[0,1] op_sel_hi:[1,0] neg_hi:[0,1]
	v_pk_add_f32 v[66:67], v[66:67], v[90:91] op_sel:[0,1] op_sel_hi:[1,0] neg_lo:[0,1]
	v_pk_add_f32 v[90:91], v[68:69], v[76:77]
	v_pk_add_f32 v[68:69], v[68:69], v[76:77] neg_lo:[0,1] neg_hi:[0,1]
	v_pk_add_f32 v[94:95], v[72:73], v[84:85]
	v_pk_add_f32 v[72:73], v[72:73], v[84:85] neg_lo:[0,1] neg_hi:[0,1]
	v_pk_mul_f32 v[76:77], v[68:69], s[68:69]
	v_pk_mul_f32 v[84:85], v[72:73], s[68:69]
	v_pk_fma_f32 v[68:69], v[68:69], s[64:65], v[76:77] op_sel:[0,0,1] op_sel_hi:[1,0,0]
	v_pk_add_f32 v[76:77], v[70:71], v[82:83]
	v_pk_fma_f32 v[72:73], v[72:73], s[64:65], v[84:85] op_sel:[0,0,1] op_sel_hi:[1,0,0] neg_lo:[1,0,0] neg_hi:[1,0,0]
	v_pk_add_f32 v[80:81], v[88:89], v[92:93] op_sel:[0,1] op_sel_hi:[1,0] neg_hi:[0,1]
	v_pk_add_f32 v[88:89], v[88:89], v[92:93] op_sel:[0,1] op_sel_hi:[1,0] neg_lo:[0,1]
	v_pk_add_f32 v[92:93], v[78:79], v[86:87]
	v_pk_add_f32 v[86:87], v[78:79], v[86:87] neg_lo:[0,1] neg_hi:[0,1]
	s_add_i32 s65, s65, s28
	v_pk_add_f32 v[82:83], v[70:71], v[82:83] neg_lo:[0,1] neg_hi:[0,1]
	s_nop 0
	v_pk_add_f32 v[104:105], v[74:75], v[76:77]
	v_pk_add_f32 v[74:75], v[74:75], v[76:77] neg_lo:[0,1] neg_hi:[0,1]
	v_pk_add_f32 v[76:77], v[90:91], v[94:95]
	s_cmpk_gt_i32 s65, 0x3ff
	s_nop 0
	v_pk_add_f32 v[84:85], v[96:97], v[100:101]
	v_pk_add_f32 v[96:97], v[96:97], v[100:101] neg_lo:[0,1] neg_hi:[0,1]
	v_pk_add_f32 v[100:101], v[98:99], v[102:103]
	s_nop 0
	v_pk_add_f32 v[78:79], v[88:89], v[86:87] op_sel:[0,1] op_sel_hi:[1,0] neg_hi:[0,1]
	v_pk_add_f32 v[86:87], v[88:89], v[86:87] op_sel:[0,1] op_sel_hi:[1,0] neg_lo:[0,1]
	v_pk_add_f32 v[88:89], v[104:105], v[76:77]
	s_cselect_b64 s[80:81], -1, 0
	s_cmpk_lt_i32 s65, 0x400
	v_pk_add_f32 v[98:99], v[98:99], v[102:103] neg_lo:[0,1] neg_hi:[0,1]
	v_pk_add_f32 v[70:71], v[66:67], v[82:83] op_sel:[0,1] op_sel_hi:[1,0] neg_hi:[0,1]
	v_pk_add_f32 v[66:67], v[66:67], v[82:83] op_sel:[0,1] op_sel_hi:[1,0] neg_lo:[0,1]
	v_pk_add_f32 v[82:83], v[68:69], v[72:73]
	v_pk_add_f32 v[106:107], v[84:85], v[100:101]
	v_pk_add_f32 v[84:85], v[84:85], v[100:101] neg_lo:[0,1] neg_hi:[0,1]
	v_pk_add_f32 v[100:101], v[80:81], v[92:93]
	v_pk_mul_f32 v[2:3], v[2:3], v[88:89] op_sel:[0,1] op_sel_hi:[1,0]
	s_cselect_b32 s6, s65, s6
	v_xor_b32_e32 v103, 0x80000000, v98
	v_pk_add_f32 v[90:91], v[90:91], v[94:95] neg_lo:[0,1] neg_hi:[0,1]
	v_mov_b32_e32 v102, v99
	v_pk_add_f32 v[80:81], v[80:81], v[92:93] neg_lo:[0,1] neg_hi:[0,1]
	v_pk_add_f32 v[92:93], v[70:71], v[82:83]
	v_pk_fma_f32 v[2:3], v[4:5], v[88:89], v[2:3] op_sel_hi:[0,1,1]
	v_pk_mul_f32 v[4:5], v[6:7], v[100:101] op_sel:[1,1] op_sel_hi:[1,0] neg_lo:[1,0]
	s_lshl_b32 s8, s6, 1
	s_lshl_b32 s6, s6, 2
	v_xor_b32_e32 v95, 0x80000000, v90
	v_pk_add_f32 v[68:69], v[68:69], v[72:73] neg_lo:[0,1] neg_hi:[0,1]
	v_pk_add_f32 v[98:99], v[96:97], v[102:103]
	v_mov_b32_e32 v94, v91
	v_pk_fma_f32 v[4:5], v[6:7], v[100:101], v[4:5] op_sel_hi:[0,1,1]
	v_pk_mul_f32 v[6:7], v[8:9], v[92:93] op_sel:[1,1] op_sel_hi:[1,0] neg_lo:[1,0]
	s_and_b32 s7, s8, 0x3fe
	s_and_b32 s6, s6, 0xfffff800
	v_xor_b32_e32 v73, 0x80000000, v68
	v_pk_add_f32 v[90:91], v[74:75], v[94:95]
	v_mov_b32_e32 v72, v69
	v_pk_fma_f32 v[6:7], v[8:9], v[92:93], v[6:7] op_sel_hi:[0,1,1]
	v_pk_mul_f32 v[8:9], v[10:11], v[98:99] op_sel:[1,1] op_sel_hi:[1,0] neg_lo:[1,0]
	s_or_b32 s6, s7, s6
	v_pk_add_f32 v[68:69], v[66:67], v[72:73]
	v_pk_fma_f32 v[8:9], v[10:11], v[98:99], v[8:9] op_sel_hi:[0,1,1]
	v_pk_mul_f32 v[10:11], v[16:17], v[90:91] op_sel:[1,1] op_sel_hi:[1,0] neg_lo:[1,0]
	s_ashr_i32 s7, s6, 31
	v_pk_add_f32 v[96:97], v[96:97], v[102:103] neg_lo:[0,1] neg_hi:[0,1]
	v_pk_add_f32 v[76:77], v[104:105], v[76:77] neg_lo:[0,1] neg_hi:[0,1]
	v_pk_add_f32 v[74:75], v[74:75], v[94:95] neg_lo:[0,1] neg_hi:[0,1]
	v_pk_add_f32 v[70:71], v[70:71], v[82:83] neg_lo:[0,1] neg_hi:[0,1]
	v_pk_add_f32 v[66:67], v[66:67], v[72:73] neg_lo:[0,1] neg_hi:[0,1]
	v_pk_fma_f32 v[10:11], v[16:17], v[90:91], v[10:11] op_sel_hi:[0,1,1]
	v_pk_mul_f32 v[12:13], v[22:23], v[78:79] op_sel:[1,1] op_sel_hi:[1,0] neg_lo:[1,0]
	v_pk_mul_f32 v[14:15], v[26:27], v[68:69] op_sel:[1,1] op_sel_hi:[1,0] neg_lo:[1,0]
	v_pk_mul_f32 v[16:17], v[30:31], v[84:85] op_sel:[1,1] op_sel_hi:[1,0] neg_lo:[1,0]
	s_lshl_b64 s[82:83], s[6:7], 14
	s_bitset1_b32 s6, 10
	v_pk_fma_f32 v[12:13], v[22:23], v[78:79], v[12:13] op_sel_hi:[0,1,1]
	v_pk_fma_f32 v[14:15], v[26:27], v[68:69], v[14:15] op_sel_hi:[0,1,1]
	v_pk_fma_f32 v[16:17], v[30:31], v[84:85], v[16:17] op_sel_hi:[0,1,1]
	v_pk_mul_f32 v[18:19], v[40:41], v[76:77] op_sel:[0,1] op_sel_hi:[1,0]
	v_pk_mul_f32 v[20:21], v[44:45], v[80:81] op_sel:[0,1] op_sel_hi:[1,0]
	v_pk_mul_f32 v[22:23], v[48:49], v[70:71] op_sel:[0,1] op_sel_hi:[1,0]
	v_pk_mul_f32 v[24:25], v[52:53], v[96:97] op_sel:[0,1] op_sel_hi:[1,0]
	v_pk_mul_f32 v[26:27], v[56:57], v[74:75] op_sel:[0,1] op_sel_hi:[1,0]
	v_pk_mul_f32 v[28:29], v[60:61], v[86:87] op_sel:[0,1] op_sel_hi:[1,0]
	v_pk_mul_f32 v[30:31], v[64:65], v[66:67] op_sel:[0,1] op_sel_hi:[1,0]
	s_ashr_i32 s7, s6, 31
	v_pk_fma_f32 v[18:19], v[38:39], v[76:77], v[18:19] op_sel_hi:[0,1,1]
	v_pk_fma_f32 v[20:21], v[42:43], v[80:81], v[20:21] op_sel_hi:[0,1,1]
	v_pk_fma_f32 v[22:23], v[46:47], v[70:71], v[22:23] op_sel_hi:[0,1,1]
	v_pk_fma_f32 v[24:25], v[50:51], v[96:97], v[24:25] op_sel_hi:[0,1,1]
	v_pk_fma_f32 v[26:27], v[54:55], v[74:75], v[26:27] op_sel_hi:[0,1,1]
	v_pk_fma_f32 v[28:29], v[58:59], v[86:87], v[28:29] op_sel_hi:[0,1,1]
	v_pk_fma_f32 v[30:31], v[62:63], v[66:67], v[30:31] op_sel_hi:[0,1,1]
	ds_write2_b64 v36, v[106:107], v[16:17] offset1:16
	ds_write2_b64 v36, v[8:9], v[24:25] offset0:33 offset1:49
	ds_write2_b64 v36, v[4:5], v[20:21] offset0:66 offset1:82
	ds_write2_b64 v36, v[12:13], v[28:29] offset0:99 offset1:115
	ds_write2_b64 v36, v[2:3], v[18:19] offset0:132 offset1:148
	ds_write2_b64 v36, v[10:11], v[26:27] offset0:165 offset1:181
	ds_write2_b64 v36, v[6:7], v[22:23] offset0:198 offset1:214
	ds_write2_b64 v36, v[14:15], v[30:31] offset0:231 offset1:247
	s_lshl_b64 s[6:7], s[6:7], 14
	v_lshl_add_u64 v[2:3], v[34:35], 0, s[82:83]
	s_waitcnt lgkmcnt(0)
	s_barrier
	global_load_dwordx4 v[10:13], v[2:3], off nt
	global_load_dwordx4 v[30:33], v[2:3], off offset:16 nt
	v_lshl_add_u64 v[2:3], v[34:35], 0, s[6:7]
	global_load_dwordx4 v[26:29], v[2:3], off nt
	global_load_dwordx4 v[22:25], v[2:3], off offset:16 nt
	v_mov_b32_e32 v38, 0
	s_and_saveexec_b64 s[6:7], s[0:1]
	s_cbranch_execz .LBB0_430
	global_load_ushort v38, v[2:3], off offset:32

.LBB0_499:
	v_mov_b32_e32 v2, v210
	s_mov_b32 s43, s8
	v_and_b32_e32 v3, 0x1ff, v2
	v_lshlrev_b32_e32 v2, 5, v2
	v_and_or_b32 v2, v2, s94, v3
	v_ashrrev_i32_e32 v4, 5, v2
	v_lshlrev_b32_e32 v2, 3, v2
	v_lshlrev_b32_e32 v4, 3, v4
	v_add3_u32 v18, 0, v2, v4
	ds_read_b64 v[128:129], v18
	ds_read_b64 v[134:135], v18 offset:4224
	ds_read_b64 v[136:137], v18 offset:8448
	ds_read_b64 v[138:139], v18 offset:12672
	ds_read_b64 v[140:141], v18 offset:16896
	ds_read_b64 v[142:143], v18 offset:21120
	ds_read_b64 v[132:133], v18 offset:25344
	ds_read_b64 v[130:131], v18 offset:29568
	ds_read_b64 v[144:145], v18 offset:33792
	ds_read_b64 v[148:149], v18 offset:38016
	ds_read_b64 v[150:151], v18 offset:42240
	ds_read_b64 v[152:153], v18 offset:46464
	s_waitcnt lgkmcnt(10)
	v_pk_mul_f32 v[162:163], v[134:135], s[10:11]
	s_mov_b32 s74, s11
	v_pk_fma_f32 v[162:163], v[134:135], s[8:9], v[162:163] op_sel:[0,0,1] op_sel_hi:[1,0,0]
	s_waitcnt lgkmcnt(2)
	v_pk_mul_f32 v[178:179], v[148:149], s[42:43]
	v_pk_add_f32 v[194:195], v[134:135], v[148:149]
	v_pk_add_f32 v[134:135], v[134:135], v[148:149] neg_lo:[0,1] neg_hi:[0,1]
	v_pk_mul_f32 v[164:165], v[136:137], s[18:19]
	s_mov_b32 s41, s16
	v_pk_fma_f32 v[178:179], v[148:149], s[74:75], v[178:179] op_sel:[0,0,1] op_sel_hi:[1,0,0] neg_lo:[1,0,0] neg_hi:[1,0,0]
	v_pk_mul_f32 v[148:149], v[134:135], s[18:19]
	v_pk_fma_f32 v[164:165], v[136:137], s[16:17], v[164:165] op_sel:[0,0,1] op_sel_hi:[1,0,0]
	s_mov_b32 s80, s19
	s_waitcnt lgkmcnt(1)
	v_pk_mul_f32 v[180:181], v[150:151], s[40:41]
	v_pk_fma_f32 v[134:135], v[134:135], s[16:17], v[148:149] op_sel:[0,0,1] op_sel_hi:[1,0,0]
	v_pk_add_f32 v[148:149], v[136:137], v[150:151]
	v_pk_add_f32 v[136:137], v[136:137], v[150:151] neg_lo:[0,1] neg_hi:[0,1]
	v_pk_mul_f32 v[166:167], v[138:139], s[26:27]
	s_mov_b32 s78, s37
	s_mov_b32 s39, s24
	v_pk_fma_f32 v[180:181], v[150:151], s[80:81], v[180:181] op_sel:[0,0,1] op_sel_hi:[1,0,0] neg_lo:[1,0,0] neg_hi:[1,0,0]
	v_pk_mul_f32 v[150:151], v[136:137], s[36:37]
	ds_read_b64 v[154:155], v18 offset:50688
	ds_read_b64 v[156:157], v18 offset:54912
	ds_read_b64 v[158:159], v18 offset:59136
	ds_read_b64 v[160:161], v18 offset:63360
	v_pk_fma_f32 v[166:167], v[138:139], s[24:25], v[166:167] op_sel:[0,0,1] op_sel_hi:[1,0,0]
	s_mov_b32 s0, s27
	s_waitcnt lgkmcnt(4)
	v_pk_mul_f32 v[182:183], v[152:153], s[38:39]
	v_pk_fma_f32 v[136:137], v[136:137], s[78:79], v[150:151] op_sel:[0,0,1] op_sel_hi:[1,0,0]
	v_pk_add_f32 v[150:151], v[138:139], v[152:153]
	v_pk_add_f32 v[138:139], v[138:139], v[152:153] neg_lo:[0,1] neg_hi:[0,1]
	v_pk_mul_f32 v[168:169], v[140:141], s[36:37]
	v_pk_fma_f32 v[182:183], v[152:153], s[0:1], v[182:183] op_sel:[0,0,1] op_sel_hi:[1,0,0] neg_lo:[1,0,0] neg_hi:[1,0,0]
	v_pk_mul_f32 v[152:153], v[138:139], s[40:41]
	v_pk_fma_f32 v[168:169], v[140:141], s[78:79], v[168:169] op_sel:[0,0,1] op_sel_hi:[1,0,0]
	v_pk_mul_f32 v[170:171], v[142:143], s[38:39]
	s_waitcnt lgkmcnt(3)
	v_pk_mul_f32 v[184:185], v[154:155], s[36:37]
	v_pk_fma_f32 v[138:139], v[138:139], s[80:81], v[152:153] op_sel:[0,0,1] op_sel_hi:[1,0,0]
	v_pk_add_f32 v[152:153], v[140:141], v[154:155]
	v_pk_add_f32 v[140:141], v[140:141], v[154:155] neg_lo:[0,1] neg_hi:[0,1]
	v_pk_fma_f32 v[170:171], v[142:143], s[0:1], v[170:171] op_sel:[0,0,1] op_sel_hi:[1,0,0]
	v_pk_fma_f32 v[184:185], v[154:155], s[78:79], v[184:185] op_sel:[0,0,1] op_sel_hi:[1,0,0] neg_lo:[1,0,0] neg_hi:[1,0,0]
	s_waitcnt lgkmcnt(2)
	v_pk_mul_f32 v[186:187], v[156:157], s[26:27]
	v_xor_b32_e32 v155, 0x80000000, v140
	v_mov_b32_e32 v154, v141
	v_pk_add_f32 v[140:141], v[142:143], v[156:157]
	v_pk_add_f32 v[142:143], v[142:143], v[156:157] neg_lo:[0,1] neg_hi:[0,1]
	v_pk_mul_f32 v[172:173], v[132:133], s[40:41]
	v_pk_fma_f32 v[186:187], v[156:157], s[24:25], v[186:187] op_sel:[0,0,1] op_sel_hi:[1,0,0] neg_lo:[1,0,0] neg_hi:[1,0,0]
	v_pk_mul_f32 v[156:157], v[142:143], s[40:41]
	v_pk_fma_f32 v[172:173], v[132:133], s[80:81], v[172:173] op_sel:[0,0,1] op_sel_hi:[1,0,0]
	s_waitcnt lgkmcnt(1)
	v_pk_mul_f32 v[188:189], v[158:159], s[18:19]
	v_pk_fma_f32 v[142:143], v[142:143], s[80:81], v[156:157] op_sel:[0,0,1] op_sel_hi:[1,0,0] neg_lo:[1,0,0] neg_hi:[1,0,0]
	v_pk_add_f32 v[156:157], v[132:133], v[158:159]
	v_pk_add_f32 v[132:133], v[132:133], v[158:159] neg_lo:[0,1] neg_hi:[0,1]
	v_pk_mul_f32 v[174:175], v[130:131], s[42:43]
	v_pk_fma_f32 v[188:189], v[158:159], s[16:17], v[188:189] op_sel:[0,0,1] op_sel_hi:[1,0,0] neg_lo:[1,0,0] neg_hi:[1,0,0]
	v_pk_mul_f32 v[158:159], v[132:133], s[36:37]
	v_pk_fma_f32 v[174:175], v[130:131], s[74:75], v[174:175] op_sel:[0,0,1] op_sel_hi:[1,0,0]
	s_waitcnt lgkmcnt(0)
	v_pk_mul_f32 v[190:191], v[160:161], s[10:11]
	v_pk_fma_f32 v[132:133], v[132:133], s[78:79], v[158:159] op_sel:[0,0,1] op_sel_hi:[1,0,0] neg_lo:[1,0,0] neg_hi:[1,0,0]
	v_pk_add_f32 v[158:159], v[130:131], v[160:161]
	v_pk_add_f32 v[130:131], v[130:131], v[160:161] neg_lo:[0,1] neg_hi:[0,1]
	v_xor_b32_e32 v177, 0x80000000, v144
	v_mov_b32_e32 v176, v145
	v_pk_fma_f32 v[190:191], v[160:161], s[8:9], v[190:191] op_sel:[0,0,1] op_sel_hi:[1,0,0] neg_lo:[1,0,0] neg_hi:[1,0,0]
	v_pk_mul_f32 v[160:161], v[130:131], s[18:19]
	v_pk_add_f32 v[192:193], v[128:129], v[144:145]
	v_pk_add_f32 v[144:145], v[128:129], v[144:145] neg_lo:[0,1] neg_hi:[0,1]
	v_pk_fma_f32 v[130:131], v[130:131], s[16:17], v[160:161] op_sel:[0,0,1] op_sel_hi:[1,0,0] neg_lo:[1,0,0] neg_hi:[1,0,0]
	v_pk_add_f32 v[160:161], v[128:129], v[176:177]
	v_pk_add_f32 v[128:129], v[128:129], v[176:177] neg_lo:[0,1] neg_hi:[0,1]
	v_pk_add_f32 v[176:177], v[162:163], v[178:179]
	v_pk_add_f32 v[162:163], v[162:163], v[178:179] neg_lo:[0,1] neg_hi:[0,1]
	v_cvt_f32_u32_e32 v2, v3
	v_pk_mul_f32 v[178:179], v[162:163], s[18:19]
	s_add_i32 s76, s72, s48
	v_pk_fma_f32 v[162:163], v[162:163], s[16:17], v[178:179] op_sel:[0,0,1] op_sel_hi:[1,0,0]
	v_pk_add_f32 v[178:179], v[164:165], v[180:181]
	v_pk_add_f32 v[164:165], v[164:165], v[180:181] neg_lo:[0,1] neg_hi:[0,1]
	v_mul_f32_e32 v2, 0x38800000, v2
	v_pk_mul_f32 v[180:181], v[164:165], s[36:37]
	v_sin_f32_e32 v34, v2
	v_pk_fma_f32 v[164:165], v[164:165], s[78:79], v[180:181] op_sel:[0,0,1] op_sel_hi:[1,0,0]
	v_pk_add_f32 v[180:181], v[166:167], v[182:183]
	v_pk_add_f32 v[166:167], v[166:167], v[182:183] neg_lo:[0,1] neg_hi:[0,1]
	v_cos_f32_e32 v30, v2
	v_pk_mul_f32 v[182:183], v[166:167], s[40:41]
	v_xor_b32_e32 v31, 0x80000000, v34
	v_pk_fma_f32 v[166:167], v[166:167], s[80:81], v[182:183] op_sel:[0,0,1] op_sel_hi:[1,0,0]
	v_pk_add_f32 v[182:183], v[168:169], v[184:185]
	v_pk_add_f32 v[184:185], v[168:169], v[184:185] neg_lo:[0,1] neg_hi:[0,1]
	v_mov_b32_e32 v35, v31
	v_pk_add_f32 v[168:169], v[170:171], v[186:187]
	v_pk_add_f32 v[170:171], v[170:171], v[186:187] neg_lo:[0,1] neg_hi:[0,1]
	v_pk_mul_f32 v[2:3], v[30:31], v[34:35] op_sel:[1,0] op_sel_hi:[0,1]
	v_pk_mul_f32 v[186:187], v[170:171], s[40:41]
	v_pk_fma_f32 v[44:45], v[30:31], v[30:31], v[2:3] op_sel_hi:[1,0,1]
	v_pk_fma_f32 v[170:171], v[170:171], s[80:81], v[186:187] op_sel:[0,0,1] op_sel_hi:[1,0,0] neg_lo:[1,0,0] neg_hi:[1,0,0]
	v_pk_add_f32 v[186:187], v[172:173], v[188:189]
	v_pk_add_f32 v[172:173], v[172:173], v[188:189] neg_lo:[0,1] neg_hi:[0,1]
	v_pk_mul_f32 v[2:3], v[34:35], v[44:45] op_sel:[0,1] op_sel_hi:[1,0]
	v_pk_mul_f32 v[188:189], v[172:173], s[36:37]
	v_pk_fma_f32 v[172:173], v[172:173], s[78:79], v[188:189] op_sel:[0,0,1] op_sel_hi:[1,0,0] neg_lo:[1,0,0] neg_hi:[1,0,0]
	v_pk_add_f32 v[188:189], v[174:175], v[190:191]
	v_pk_add_f32 v[174:175], v[174:175], v[190:191] neg_lo:[0,1] neg_hi:[0,1]
	v_pk_mul_f32 v[190:191], v[174:175], s[18:19]
	v_pk_fma_f32 v[46:47], v[30:31], v[44:45], v[2:3] op_sel_hi:[0,1,1]
	v_pk_fma_f32 v[174:175], v[174:175], s[16:17], v[190:191] op_sel:[0,0,1] op_sel_hi:[1,0,0] neg_lo:[1,0,0] neg_hi:[1,0,0]
	v_pk_add_f32 v[190:191], v[192:193], v[152:153]
	v_pk_add_f32 v[152:153], v[192:193], v[152:153] neg_lo:[0,1] neg_hi:[0,1]
	v_pk_add_f32 v[192:193], v[194:195], v[140:141]
	v_pk_add_f32 v[140:141], v[194:195], v[140:141] neg_lo:[0,1] neg_hi:[0,1]
	v_pk_mul_f32 v[2:3], v[44:45], v[44:45] op_sel:[1,1] op_sel_hi:[0,1] neg_lo:[0,1]
	v_pk_mul_f32 v[194:195], v[140:141], s[36:37]
	v_pk_fma_f32 v[52:53], v[44:45], v[44:45], v[2:3] op_sel_hi:[1,0,1]
	v_pk_fma_f32 v[140:141], v[140:141], s[78:79], v[194:195] op_sel:[0,0,1] op_sel_hi:[1,0,0]
	v_pk_add_f32 v[194:195], v[148:149], v[156:157]
	v_pk_add_f32 v[156:157], v[148:149], v[156:157] neg_lo:[0,1] neg_hi:[0,1]
	v_pk_add_f32 v[148:149], v[150:151], v[158:159]
	v_pk_add_f32 v[150:151], v[150:151], v[158:159] neg_lo:[0,1] neg_hi:[0,1]
	v_pk_mul_f32 v[158:159], v[150:151], s[36:37]
	v_pk_mul_f32 v[2:3], v[52:53], v[52:53] op_sel:[1,1] op_sel_hi:[0,1] neg_lo:[0,1]
	v_pk_fma_f32 v[150:151], v[150:151], s[78:79], v[158:159] op_sel:[0,0,1] op_sel_hi:[1,0,0] neg_lo:[1,0,0] neg_hi:[1,0,0]
	v_pk_add_f32 v[158:159], v[144:145], v[154:155]
	v_pk_add_f32 v[144:145], v[144:145], v[154:155] neg_lo:[0,1] neg_hi:[0,1]
	v_pk_add_f32 v[154:155], v[134:135], v[142:143]
	v_pk_add_f32 v[134:135], v[134:135], v[142:143] neg_lo:[0,1] neg_hi:[0,1]
	v_pk_fma_f32 v[48:49], v[52:53], v[52:53], v[2:3] op_sel_hi:[1,0,1]
	v_pk_mul_f32 v[142:143], v[134:135], s[36:37]
	v_pk_mul_f32 v[2:3], v[52:53], v[48:49] op_sel:[1,1] op_sel_hi:[1,0] neg_lo:[1,0]
	v_pk_fma_f32 v[134:135], v[134:135], s[78:79], v[142:143] op_sel:[0,0,1] op_sel_hi:[1,0,0]
	v_pk_add_f32 v[142:143], v[136:137], v[132:133]
	v_pk_add_f32 v[136:137], v[136:137], v[132:133] neg_lo:[0,1] neg_hi:[0,1]
	v_pk_fma_f32 v[36:37], v[52:53], v[48:49], v[2:3] op_sel_hi:[0,1,1]
	v_pk_add_f32 v[132:133], v[138:139], v[130:131]
	v_pk_add_f32 v[130:131], v[138:139], v[130:131] neg_lo:[0,1] neg_hi:[0,1]
	v_pk_mul_f32 v[2:3], v[52:53], v[36:37] op_sel:[1,1] op_sel_hi:[1,0] neg_lo:[1,0]
	v_pk_mul_f32 v[138:139], v[130:131], s[36:37]
	v_pk_fma_f32 v[26:27], v[52:53], v[36:37], v[2:3] op_sel_hi:[0,1,1]
	v_pk_fma_f32 v[130:131], v[130:131], s[78:79], v[138:139] op_sel:[0,0,1] op_sel_hi:[1,0,0] neg_lo:[1,0,0] neg_hi:[1,0,0]
	v_pk_add_f32 v[138:139], v[160:161], v[182:183]
	v_pk_add_f32 v[160:161], v[160:161], v[182:183] neg_lo:[0,1] neg_hi:[0,1]
	v_pk_add_f32 v[182:183], v[176:177], v[168:169]
	v_pk_add_f32 v[168:169], v[176:177], v[168:169] neg_lo:[0,1] neg_hi:[0,1]
	v_pk_mul_f32 v[2:3], v[52:53], v[26:27] op_sel:[1,1] op_sel_hi:[1,0] neg_lo:[1,0]
	v_pk_mul_f32 v[176:177], v[168:169], s[36:37]
	v_pk_fma_f32 v[20:21], v[52:53], v[26:27], v[2:3] op_sel_hi:[0,1,1]
	v_pk_fma_f32 v[168:169], v[168:169], s[78:79], v[176:177] op_sel:[0,0,1] op_sel_hi:[1,0,0]
	v_pk_add_f32 v[176:177], v[178:179], v[186:187]
	v_pk_add_f32 v[186:187], v[178:179], v[186:187] neg_lo:[0,1] neg_hi:[0,1]
	v_pk_mul_f32 v[2:3], v[52:53], v[20:21] op_sel:[1,1] op_sel_hi:[1,0] neg_lo:[1,0]
	v_pk_add_f32 v[178:179], v[180:181], v[188:189]
	v_pk_add_f32 v[180:181], v[180:181], v[188:189] neg_lo:[0,1] neg_hi:[0,1]
	v_pk_fma_f32 v[10:11], v[52:53], v[20:21], v[2:3] op_sel_hi:[0,1,1]
	v_pk_mul_f32 v[188:189], v[180:181], s[36:37]
	v_pk_mul_f32 v[2:3], v[52:53], v[10:11] op_sel:[1,1] op_sel_hi:[1,0] neg_lo:[1,0]
	v_pk_fma_f32 v[180:181], v[180:181], s[78:79], v[188:189] op_sel:[0,0,1] op_sel_hi:[1,0,0] neg_lo:[1,0,0] neg_hi:[1,0,0]
	v_pk_add_f32 v[188:189], v[128:129], v[184:185] op_sel:[0,1] op_sel_hi:[1,0] neg_hi:[0,1]
	v_pk_add_f32 v[128:129], v[128:129], v[184:185] op_sel:[0,1] op_sel_hi:[1,0] neg_lo:[0,1]
	v_pk_add_f32 v[184:185], v[162:163], v[170:171]
	v_pk_add_f32 v[162:163], v[162:163], v[170:171] neg_lo:[0,1] neg_hi:[0,1]
	v_pk_fma_f32 v[4:5], v[52:53], v[10:11], v[2:3] op_sel_hi:[0,1,1]
	v_pk_mul_f32 v[170:171], v[162:163], s[36:37]
	v_pk_mul_f32 v[8:9], v[44:45], v[4:5] op_sel:[1,1] op_sel_hi:[1,0] neg_lo:[1,0]
	v_pk_fma_f32 v[162:163], v[162:163], s[78:79], v[170:171] op_sel:[0,0,1] op_sel_hi:[1,0,0]
	v_pk_add_f32 v[170:171], v[164:165], v[172:173]
	v_pk_add_f32 v[172:173], v[164:165], v[172:173] neg_lo:[0,1] neg_hi:[0,1]
	v_pk_mul_f32 v[14:15], v[34:35], v[4:5] op_sel:[0,1] op_sel_hi:[1,0]
	v_pk_add_f32 v[164:165], v[166:167], v[174:175]
	v_pk_add_f32 v[166:167], v[166:167], v[174:175] neg_lo:[0,1] neg_hi:[0,1]
	v_pk_mul_f32 v[32:33], v[44:45], v[10:11] op_sel:[1,1] op_sel_hi:[1,0] neg_lo:[1,0]
	v_pk_mul_f32 v[174:175], v[166:167], s[36:37]
	v_pk_mul_f32 v[40:41], v[34:35], v[10:11] op_sel:[0,1] op_sel_hi:[1,0]
	v_pk_fma_f32 v[166:167], v[166:167], s[78:79], v[174:175] op_sel:[0,0,1] op_sel_hi:[1,0,0] neg_lo:[1,0,0] neg_hi:[1,0,0]
	v_pk_add_f32 v[174:175], v[190:191], v[194:195]
	v_pk_add_f32 v[190:191], v[190:191], v[194:195] neg_lo:[0,1] neg_hi:[0,1]
	v_pk_add_f32 v[194:195], v[192:193], v[148:149]
	v_pk_add_f32 v[192:193], v[192:193], v[148:149] neg_lo:[0,1] neg_hi:[0,1]
	v_pk_mul_f32 v[62:63], v[44:45], v[20:21] op_sel:[1,1] op_sel_hi:[1,0] neg_lo:[1,0]
	v_pk_add_f32 v[148:149], v[152:153], v[156:157] op_sel:[0,1] op_sel_hi:[1,0] neg_hi:[0,1]
	v_pk_add_f32 v[152:153], v[152:153], v[156:157] op_sel:[0,1] op_sel_hi:[1,0] neg_lo:[0,1]
	v_pk_add_f32 v[156:157], v[140:141], v[150:151]
	v_pk_add_f32 v[150:151], v[140:141], v[150:151] neg_lo:[0,1] neg_hi:[0,1]
	v_pk_mul_f32 v[66:67], v[34:35], v[20:21] op_sel:[0,1] op_sel_hi:[1,0]
	v_pk_add_f32 v[140:141], v[158:159], v[142:143]
	v_pk_add_f32 v[142:143], v[158:159], v[142:143] neg_lo:[0,1] neg_hi:[0,1]
	v_pk_add_f32 v[158:159], v[154:155], v[132:133]
	v_pk_add_f32 v[154:155], v[154:155], v[132:133] neg_lo:[0,1] neg_hi:[0,1]
	v_pk_mul_f32 v[78:79], v[44:45], v[26:27] op_sel:[1,1] op_sel_hi:[1,0] neg_lo:[1,0]
	v_pk_add_f32 v[132:133], v[144:145], v[136:137] op_sel:[0,1] op_sel_hi:[1,0] neg_hi:[0,1]
	v_pk_add_f32 v[136:137], v[144:145], v[136:137] op_sel:[0,1] op_sel_hi:[1,0] neg_lo:[0,1]
	v_pk_add_f32 v[144:145], v[134:135], v[130:131]
	v_pk_add_f32 v[134:135], v[134:135], v[130:131] neg_lo:[0,1] neg_hi:[0,1]
	v_pk_mul_f32 v[82:83], v[34:35], v[26:27] op_sel:[0,1] op_sel_hi:[1,0]
	v_pk_add_f32 v[130:131], v[138:139], v[176:177]
	v_pk_add_f32 v[138:139], v[138:139], v[176:177] neg_lo:[0,1] neg_hi:[0,1]
	v_pk_add_f32 v[176:177], v[182:183], v[178:179]
	v_pk_add_f32 v[182:183], v[182:183], v[178:179] neg_lo:[0,1] neg_hi:[0,1]
	v_pk_mul_f32 v[92:93], v[44:45], v[36:37] op_sel:[1,1] op_sel_hi:[1,0] neg_lo:[1,0]
	v_pk_add_f32 v[178:179], v[160:161], v[186:187] op_sel:[0,1] op_sel_hi:[1,0] neg_hi:[0,1]
	v_pk_add_f32 v[160:161], v[160:161], v[186:187] op_sel:[0,1] op_sel_hi:[1,0] neg_lo:[0,1]
	v_pk_add_f32 v[186:187], v[168:169], v[180:181]
	v_pk_add_f32 v[180:181], v[168:169], v[180:181] neg_lo:[0,1] neg_hi:[0,1]
	v_pk_mul_f32 v[96:97], v[34:35], v[36:37] op_sel:[0,1] op_sel_hi:[1,0]
	v_pk_add_f32 v[168:169], v[188:189], v[170:171]
	v_pk_add_f32 v[170:171], v[188:189], v[170:171] neg_lo:[0,1] neg_hi:[0,1]
	v_pk_add_f32 v[188:189], v[184:185], v[164:165]
	v_pk_add_f32 v[184:185], v[184:185], v[164:165] neg_lo:[0,1] neg_hi:[0,1]
	v_pk_mul_f32 v[106:107], v[44:45], v[48:49] op_sel:[1,1] op_sel_hi:[1,0] neg_lo:[1,0]
	v_pk_add_f32 v[164:165], v[128:129], v[172:173] op_sel:[0,1] op_sel_hi:[1,0] neg_hi:[0,1]
	v_pk_add_f32 v[128:129], v[128:129], v[172:173] op_sel:[0,1] op_sel_hi:[1,0] neg_lo:[0,1]
	v_pk_add_f32 v[172:173], v[162:163], v[166:167]
	v_pk_add_f32 v[166:167], v[162:163], v[166:167] neg_lo:[0,1] neg_hi:[0,1]
	v_pk_mul_f32 v[110:111], v[34:35], v[48:49] op_sel:[0,1] op_sel_hi:[1,0]
	v_pk_add_f32 v[162:163], v[174:175], v[194:195]
	v_pk_add_f32 v[174:175], v[174:175], v[194:195] neg_lo:[0,1] neg_hi:[0,1]
	v_pk_add_f32 v[194:195], v[190:191], v[192:193] op_sel:[0,1] op_sel_hi:[1,0] neg_hi:[0,1]
	v_pk_add_f32 v[190:191], v[190:191], v[192:193] op_sel:[0,1] op_sel_hi:[1,0] neg_lo:[0,1]
	v_pk_add_f32 v[192:193], v[148:149], v[156:157]
	v_pk_add_f32 v[148:149], v[148:149], v[156:157] neg_lo:[0,1] neg_hi:[0,1]
	v_pk_add_f32 v[156:157], v[152:153], v[150:151] op_sel:[0,1] op_sel_hi:[1,0] neg_hi:[0,1]
	v_pk_add_f32 v[150:151], v[152:153], v[150:151] op_sel:[0,1] op_sel_hi:[1,0] neg_lo:[0,1]
	v_pk_add_f32 v[152:153], v[140:141], v[158:159]
	v_pk_add_f32 v[140:141], v[140:141], v[158:159] neg_lo:[0,1] neg_hi:[0,1]
	v_pk_add_f32 v[158:159], v[142:143], v[154:155] op_sel:[0,1] op_sel_hi:[1,0] neg_hi:[0,1]
	v_pk_add_f32 v[142:143], v[142:143], v[154:155] op_sel:[0,1] op_sel_hi:[1,0] neg_lo:[0,1]
	v_pk_add_f32 v[154:155], v[132:133], v[144:145]
	v_pk_add_f32 v[132:133], v[132:133], v[144:145] neg_lo:[0,1] neg_hi:[0,1]
	v_pk_add_f32 v[144:145], v[136:137], v[134:135] op_sel:[0,1] op_sel_hi:[1,0] neg_hi:[0,1]
	v_pk_add_f32 v[134:135], v[136:137], v[134:135] op_sel:[0,1] op_sel_hi:[1,0] neg_lo:[0,1]
	v_pk_add_f32 v[136:137], v[130:131], v[176:177]
	v_pk_mul_f32 v[120:121], v[44:45], v[52:53] op_sel:[1,1] op_sel_hi:[1,0] neg_lo:[1,0]
	v_pk_mul_f32 v[124:125], v[34:35], v[52:53] op_sel:[0,1] op_sel_hi:[1,0]
	v_pk_mul_f32 v[34:35], v[34:35], v[136:137] op_sel:[0,1] op_sel_hi:[1,0]
	v_pk_fma_f32 v[8:9], v[44:45], v[4:5], v[8:9] op_sel_hi:[0,1,1]
	v_pk_fma_f32 v[14:15], v[30:31], v[4:5], v[14:15] op_sel_hi:[0,1,1]
	v_xor_b32_e32 v22, 0x80000000, v5
	v_pk_fma_f32 v[32:33], v[44:45], v[10:11], v[32:33] op_sel_hi:[0,1,1]
	v_pk_fma_f32 v[40:41], v[30:31], v[10:11], v[40:41] op_sel_hi:[0,1,1]
	v_pk_fma_f32 v[62:63], v[44:45], v[20:21], v[62:63] op_sel_hi:[0,1,1]
	v_pk_fma_f32 v[66:67], v[30:31], v[20:21], v[66:67] op_sel_hi:[0,1,1]
	v_pk_fma_f32 v[78:79], v[44:45], v[26:27], v[78:79] op_sel_hi:[0,1,1]
	v_pk_fma_f32 v[82:83], v[30:31], v[26:27], v[82:83] op_sel_hi:[0,1,1]
	v_pk_fma_f32 v[92:93], v[44:45], v[36:37], v[92:93] op_sel_hi:[0,1,1]
	v_pk_fma_f32 v[96:97], v[30:31], v[36:37], v[96:97] op_sel_hi:[0,1,1]
	v_pk_fma_f32 v[106:107], v[44:45], v[48:49], v[106:107] op_sel_hi:[0,1,1]
	v_pk_fma_f32 v[110:111], v[30:31], v[48:49], v[110:111] op_sel_hi:[0,1,1]
	v_pk_fma_f32 v[120:121], v[44:45], v[52:53], v[120:121] op_sel_hi:[0,1,1]
	v_pk_fma_f32 v[124:125], v[30:31], v[52:53], v[124:125] op_sel_hi:[0,1,1]
	v_mov_b32_e32 v23, v5
	v_pk_add_f32 v[130:131], v[130:131], v[176:177] neg_lo:[0,1] neg_hi:[0,1]
	v_pk_add_f32 v[176:177], v[138:139], v[182:183] op_sel:[0,1] op_sel_hi:[1,0] neg_hi:[0,1]
	v_pk_add_f32 v[138:139], v[138:139], v[182:183] op_sel:[0,1] op_sel_hi:[1,0] neg_lo:[0,1]
	v_pk_add_f32 v[182:183], v[178:179], v[186:187]
	v_pk_add_f32 v[178:179], v[178:179], v[186:187] neg_lo:[0,1] neg_hi:[0,1]
	v_pk_add_f32 v[186:187], v[160:161], v[180:181] op_sel:[0,1] op_sel_hi:[1,0] neg_hi:[0,1]
	v_pk_add_f32 v[160:161], v[160:161], v[180:181] op_sel:[0,1] op_sel_hi:[1,0] neg_lo:[0,1]
	v_pk_add_f32 v[180:181], v[168:169], v[188:189]
	v_pk_fma_f32 v[30:31], v[30:31], v[136:137], v[34:35] op_sel_hi:[0,1,1]
	v_pk_mul_f32 v[34:35], v[44:45], v[152:153] op_sel:[1,1] op_sel_hi:[1,0] neg_lo:[1,0]
	v_pk_mul_f32 v[2:3], v[46:47], v[4:5] op_sel:[1,1] op_sel_hi:[1,0] neg_lo:[1,0]
	v_xor_b32_e32 v12, 0x80000000, v9
	v_pk_mul_f32 v[24:25], v[46:47], v[10:11] op_sel:[1,1] op_sel_hi:[1,0] neg_lo:[1,0]
	v_xor_b32_e32 v38, 0x80000000, v33
	v_xor_b32_e32 v50, 0x80000000, v11
	v_pk_mul_f32 v[56:57], v[46:47], v[20:21] op_sel:[1,1] op_sel_hi:[1,0] neg_lo:[1,0]
	v_xor_b32_e32 v64, 0x80000000, v63
	v_xor_b32_e32 v70, 0x80000000, v21
	v_pk_mul_f32 v[74:75], v[46:47], v[26:27] op_sel:[1,1] op_sel_hi:[1,0] neg_lo:[1,0]
	v_xor_b32_e32 v80, 0x80000000, v79
	v_xor_b32_e32 v86, 0x80000000, v27
	v_pk_mul_f32 v[88:89], v[46:47], v[36:37] op_sel:[1,1] op_sel_hi:[1,0] neg_lo:[1,0]
	v_xor_b32_e32 v94, 0x80000000, v93
	v_xor_b32_e32 v100, 0x80000000, v37
	v_pk_mul_f32 v[102:103], v[46:47], v[48:49] op_sel:[1,1] op_sel_hi:[1,0] neg_lo:[1,0]
	v_pk_mul_f32 v[116:117], v[52:53], v[46:47] op_sel:[1,1] op_sel_hi:[0,1] neg_lo:[0,1]
	v_mov_b32_e32 v101, v37
	v_mov_b32_e32 v95, v93
	v_mov_b32_e32 v87, v27
	v_mov_b32_e32 v81, v79
	v_mov_b32_e32 v71, v21
	v_mov_b32_e32 v65, v63
	v_mov_b32_e32 v51, v11
	v_mov_b32_e32 v39, v33
	v_mov_b32_e32 v13, v9
	v_pk_fma_f32 v[34:35], v[44:45], v[152:153], v[34:35] op_sel_hi:[0,1,1]
	v_pk_mul_f32 v[44:45], v[46:47], v[180:181] op_sel:[1,1] op_sel_hi:[1,0] neg_lo:[1,0]
	v_pk_mul_f32 v[22:23], v[150:151], v[22:23] op_sel:[1,0] op_sel_hi:[0,1]
	v_pk_fma_f32 v[2:3], v[46:47], v[4:5], v[2:3] op_sel_hi:[0,1,1]
	v_pk_fma_f32 v[24:25], v[46:47], v[10:11], v[24:25] op_sel_hi:[0,1,1]
	v_pk_fma_f32 v[56:57], v[46:47], v[20:21], v[56:57] op_sel_hi:[0,1,1]
	v_pk_fma_f32 v[74:75], v[46:47], v[26:27], v[74:75] op_sel_hi:[0,1,1]
	v_pk_fma_f32 v[88:89], v[46:47], v[36:37], v[88:89] op_sel_hi:[0,1,1]
	v_pk_fma_f32 v[102:103], v[46:47], v[48:49], v[102:103] op_sel_hi:[0,1,1]
	v_pk_fma_f32 v[116:117], v[52:53], v[46:47], v[116:117] op_sel_hi:[1,0,1]
	v_pk_fma_f32 v[44:45], v[46:47], v[180:181], v[44:45] op_sel_hi:[0,1,1]
	v_pk_mul_f32 v[46:47], v[52:53], v[192:193] op_sel:[1,1] op_sel_hi:[1,0] neg_lo:[1,0]
	v_pk_mul_f32 v[54:55], v[120:121], v[154:155] op_sel:[1,1] op_sel_hi:[1,0] neg_lo:[1,0]
	v_pk_mul_f32 v[72:73], v[48:49], v[194:195] op_sel:[1,1] op_sel_hi:[1,0] neg_lo:[1,0]
	v_pk_mul_f32 v[108:109], v[106:107], v[158:159] op_sel:[1,1] op_sel_hi:[1,0] neg_lo:[1,0]
	v_pk_mul_f32 v[100:101], v[100:101], v[156:157] op_sel:[0,1] op_sel_hi:[1,0]
	v_pk_mul_f32 v[94:95], v[94:95], v[144:145] op_sel:[0,1] op_sel_hi:[1,0]
	v_pk_mul_f32 v[86:87], v[174:175], v[86:87] op_sel:[1,0] op_sel_hi:[0,1]
	v_pk_mul_f32 v[80:81], v[140:141], v[80:81] op_sel:[1,0] op_sel_hi:[0,1]
	v_pk_mul_f32 v[70:71], v[148:149], v[70:71] op_sel:[1,0] op_sel_hi:[0,1]
	v_pk_mul_f32 v[64:65], v[132:133], v[64:65] op_sel:[1,0] op_sel_hi:[0,1]
	v_pk_mul_f32 v[50:51], v[190:191], v[50:51] op_sel:[1,0] op_sel_hi:[0,1]
	v_pk_mul_f32 v[38:39], v[142:143], v[38:39] op_sel:[1,0] op_sel_hi:[0,1]
	v_pk_fma_f32 v[4:5], v[150:151], v[4:5], v[22:23] op_sel_hi:[1,0,1]
	v_pk_mul_f32 v[12:13], v[134:135], v[12:13] op_sel:[1,0] op_sel_hi:[0,1]
	v_pk_fma_f32 v[46:47], v[52:53], v[192:193], v[46:47] op_sel_hi:[0,1,1]
	v_pk_fma_f32 v[54:55], v[120:121], v[154:155], v[54:55] op_sel_hi:[0,1,1]
	v_pk_fma_f32 v[48:49], v[48:49], v[194:195], v[72:73] op_sel_hi:[0,1,1]
	v_pk_fma_f32 v[106:107], v[106:107], v[158:159], v[108:109] op_sel_hi:[0,1,1]
	v_pk_fma_f32 v[36:37], v[36:37], v[156:157], v[100:101] op_sel_hi:[0,1,1]
	v_pk_fma_f32 v[92:93], v[92:93], v[144:145], v[94:95] op_sel_hi:[0,1,1]
	v_pk_fma_f32 v[26:27], v[174:175], v[26:27], v[86:87] op_sel_hi:[1,0,1]
	v_pk_mul_f32 v[84:85], v[130:131], v[82:83] op_sel:[1,1] op_sel_hi:[0,1] neg_lo:[0,1]
	v_pk_fma_f32 v[78:79], v[140:141], v[78:79], v[80:81] op_sel_hi:[1,0,1]
	v_pk_fma_f32 v[20:21], v[148:149], v[20:21], v[70:71] op_sel_hi:[1,0,1]
	v_pk_fma_f32 v[62:63], v[132:133], v[62:63], v[64:65] op_sel_hi:[1,0,1]
	v_pk_fma_f32 v[10:11], v[190:191], v[10:11], v[50:51] op_sel_hi:[1,0,1]
	v_pk_fma_f32 v[32:33], v[142:143], v[32:33], v[38:39] op_sel_hi:[1,0,1]
	v_pk_fma_f32 v[8:9], v[134:135], v[8:9], v[12:13] op_sel_hi:[1,0,1]
	ds_write_b64 v18, v[162:163]
	ds_write_b64 v18, v[26:27] offset:4224
	ds_write_b64 v18, v[48:49] offset:8448
	ds_write_b64 v18, v[10:11] offset:12672
	ds_write_b64 v18, v[46:47] offset:16896
	ds_write_b64 v18, v[20:21] offset:21120
	ds_write_b64 v18, v[36:37] offset:25344
	ds_write_b64 v18, v[4:5] offset:29568
	ds_write_b64 v18, v[34:35] offset:33792
	ds_write_b64 v18, v[78:79] offset:38016
	ds_write_b64 v18, v[106:107] offset:42240
	ds_write_b64 v18, v[32:33] offset:46464
	ds_write_b64 v18, v[54:55] offset:50688
	ds_write_b64 v18, v[62:63] offset:54912
	ds_write_b64 v18, v[92:93] offset:59136
	ds_write_b64 v18, v[8:9] offset:63360
	v_add_u32_e32 v4, 0x10800, v18
	v_pk_mul_f32 v[72:73], v[110:111], v[176:177] op_sel:[1,1] op_sel_hi:[1,0] neg_lo:[1,0]
	v_pk_fma_f32 v[82:83], v[130:131], v[82:83], v[84:85] op_sel_hi:[1,0,1]
	ds_write_b64 v4, v[30:31]
	v_add_u32_e32 v4, 0x11880, v18
	v_pk_fma_f32 v[72:73], v[110:111], v[176:177], v[72:73] op_sel_hi:[0,1,1]
	v_pk_mul_f32 v[42:43], v[138:139], v[40:41] op_sel:[1,1] op_sel_hi:[0,1] neg_lo:[0,1]
	ds_write_b64 v4, v[82:83]
	v_add_u32_e32 v4, 0x12900, v18
	v_pk_mul_f32 v[52:53], v[124:125], v[182:183] op_sel:[1,1] op_sel_hi:[1,0] neg_lo:[1,0]
	v_pk_fma_f32 v[40:41], v[138:139], v[40:41], v[42:43] op_sel_hi:[1,0,1]
	ds_write_b64 v4, v[72:73]
	v_add_u32_e32 v4, 0x13980, v18
	v_pk_fma_f32 v[52:53], v[124:125], v[182:183], v[52:53] op_sel_hi:[0,1,1]
	v_pk_mul_f32 v[68:69], v[178:179], v[66:67] op_sel:[1,1] op_sel_hi:[0,1] neg_lo:[0,1]
	ds_write_b64 v4, v[40:41]
	v_add_u32_e32 v4, 0x14a00, v18
	v_pk_mul_f32 v[98:99], v[96:97], v[186:187] op_sel:[1,1] op_sel_hi:[1,0] neg_lo:[1,0]
	v_pk_fma_f32 v[66:67], v[178:179], v[66:67], v[68:69] op_sel_hi:[1,0,1]
	ds_write_b64 v4, v[52:53]
	v_add_u32_e32 v4, 0x15a80, v18
	v_pk_fma_f32 v[96:97], v[96:97], v[186:187], v[98:99] op_sel_hi:[0,1,1]
	v_pk_mul_f32 v[16:17], v[160:161], v[14:15] op_sel:[1,1] op_sel_hi:[0,1] neg_lo:[0,1]
	ds_write_b64 v4, v[66:67]
	v_add_u32_e32 v4, 0x16b00, v18
	v_pk_add_f32 v[168:169], v[168:169], v[188:189] neg_lo:[0,1] neg_hi:[0,1]
	v_pk_fma_f32 v[14:15], v[160:161], v[14:15], v[16:17] op_sel_hi:[1,0,1]
	ds_write_b64 v4, v[96:97]
	v_add_u32_e32 v4, 0x17b80, v18
	v_pk_add_f32 v[188:189], v[170:171], v[184:185] op_sel:[0,1] op_sel_hi:[1,0] neg_hi:[0,1]
	v_pk_mul_f32 v[76:77], v[168:169], v[74:75] op_sel:[1,1] op_sel_hi:[0,1] neg_lo:[0,1]
	ds_write_b64 v4, v[14:15]
	v_add_u32_e32 v4, 0x18c00, v18
	v_pk_add_f32 v[170:171], v[170:171], v[184:185] op_sel:[0,1] op_sel_hi:[1,0] neg_lo:[0,1]
	v_pk_mul_f32 v[104:105], v[102:103], v[188:189] op_sel:[1,1] op_sel_hi:[1,0] neg_lo:[1,0]
	v_pk_fma_f32 v[74:75], v[168:169], v[74:75], v[76:77] op_sel_hi:[1,0,1]
	ds_write_b64 v4, v[44:45]
	v_add_u32_e32 v4, 0x19c80, v18
	v_pk_add_f32 v[184:185], v[164:165], v[172:173]
	v_pk_fma_f32 v[102:103], v[102:103], v[188:189], v[104:105] op_sel_hi:[0,1,1]
	v_pk_mul_f32 v[28:29], v[170:171], v[24:25] op_sel:[1,1] op_sel_hi:[0,1] neg_lo:[0,1]
	ds_write_b64 v4, v[74:75]
	v_add_u32_e32 v4, 0x1ad00, v18
	v_pk_add_f32 v[164:165], v[164:165], v[172:173] neg_lo:[0,1] neg_hi:[0,1]
	v_pk_mul_f32 v[58:59], v[116:117], v[184:185] op_sel:[1,1] op_sel_hi:[1,0] neg_lo:[1,0]
	v_pk_fma_f32 v[24:25], v[170:171], v[24:25], v[28:29] op_sel_hi:[1,0,1]
	ds_write_b64 v4, v[102:103]
	v_add_u32_e32 v4, 0x1bd80, v18
	v_pk_add_f32 v[172:173], v[128:129], v[166:167] op_sel:[0,1] op_sel_hi:[1,0] neg_hi:[0,1]
	v_pk_fma_f32 v[58:59], v[116:117], v[184:185], v[58:59] op_sel_hi:[0,1,1]
	v_pk_mul_f32 v[60:61], v[164:165], v[56:57] op_sel:[1,1] op_sel_hi:[0,1] neg_lo:[0,1]
	ds_write_b64 v4, v[24:25]
	v_add_u32_e32 v4, 0x1ce00, v18
	v_pk_add_f32 v[128:129], v[128:129], v[166:167] op_sel:[0,1] op_sel_hi:[1,0] neg_lo:[0,1]
	v_pk_mul_f32 v[90:91], v[88:89], v[172:173] op_sel:[1,1] op_sel_hi:[1,0] neg_lo:[1,0]
	v_pk_fma_f32 v[56:57], v[164:165], v[56:57], v[60:61] op_sel_hi:[1,0,1]
	ds_write_b64 v4, v[58:59]
	v_add_u32_e32 v4, 0x1de80, v18
	v_pk_fma_f32 v[88:89], v[88:89], v[172:173], v[90:91] op_sel_hi:[0,1,1]
	v_pk_mul_f32 v[6:7], v[128:129], v[2:3] op_sel:[1,1] op_sel_hi:[0,1] neg_lo:[0,1]
	ds_write_b64 v4, v[56:57]
	v_add_u32_e32 v4, 0x1ef00, v18
	v_pk_fma_f32 v[2:3], v[128:129], v[2:3], v[6:7] op_sel_hi:[1,0,1]
	ds_write_b64 v4, v[88:89]
	v_add_u32_e32 v4, 0x1ff80, v18
	ds_write_b64 v4, v[2:3]
	v_mov_b32_e32 v2, v210
	s_waitcnt lgkmcnt(0)
	s_barrier
	s_ashr_i32 s77, s76, 31
	v_and_b32_e32 v3, 15, v2
	v_lshlrev_b32_e32 v2, 5, v2
	v_and_b32_e32 v4, 0xfffffe00, v2
	v_lshl_add_u32 v5, v4, 3, 0
	v_lshlrev_b32_e32 v6, 3, v3
	v_ashrrev_i32_e32 v7, 2, v4
	v_add3_u32 v18, v5, v6, v7
	v_add_u32_e32 v196, 0x800, v18
	ds_read2_b64 v[128:131], v18 offset1:16
	ds_read2_b64 v[132:135], v18 offset0:33 offset1:49
	ds_read2_b64 v[136:139], v18 offset0:66 offset1:82
	ds_read2_b64 v[140:143], v18 offset0:99 offset1:115
	ds_read2_b64 v[148:151], v18 offset0:132 offset1:148
	ds_read2_b64 v[152:155], v18 offset0:165 offset1:181
	ds_read2_b64 v[156:159], v18 offset0:198 offset1:214
	ds_read2_b64 v[160:163], v18 offset0:231 offset1:247
	ds_read2_b64 v[164:167], v196 offset0:8 offset1:24
	ds_read2_b64 v[168:171], v196 offset0:41 offset1:57
	ds_read2_b64 v[172:175], v196 offset0:74 offset1:90
	ds_read2_b64 v[176:179], v196 offset0:107 offset1:123
	ds_read2_b64 v[180:183], v196 offset0:140 offset1:156
	ds_read2_b64 v[184:187], v196 offset0:173 offset1:189
	ds_read2_b64 v[188:191], v196 offset0:206 offset1:222
	ds_read2_b64 v[192:195], v196 offset0:239 offset1:255
	s_waitcnt lgkmcnt(7)
	v_pk_add_f32 v[144:145], v[128:129], v[164:165]
	v_pk_add_f32 v[128:129], v[128:129], v[164:165] neg_lo:[0,1] neg_hi:[0,1]
	v_pk_add_f32 v[164:165], v[130:131], v[166:167]
	v_pk_add_f32 v[130:131], v[130:131], v[166:167] neg_lo:[0,1] neg_hi:[0,1]
	v_cvt_f32_ubyte0_e32 v2, v3
	v_pk_mul_f32 v[166:167], v[130:131], s[10:11]
	v_mul_f32_e32 v3, 0x3b000000, v2
	v_pk_fma_f32 v[130:131], v[130:131], s[8:9], v[166:167] op_sel:[0,0,1] op_sel_hi:[1,0,0]
	s_waitcnt lgkmcnt(6)
	v_pk_add_f32 v[166:167], v[132:133], v[168:169]
	v_pk_add_f32 v[132:133], v[132:133], v[168:169] neg_lo:[0,1] neg_hi:[0,1]
	v_sin_f32_e32 v2, v3
	v_pk_mul_f32 v[168:169], v[132:133], s[18:19]
	v_cos_f32_e32 v4, v3
	v_pk_fma_f32 v[132:133], v[132:133], s[16:17], v[168:169] op_sel:[0,0,1] op_sel_hi:[1,0,0]
	v_pk_add_f32 v[168:169], v[134:135], v[170:171]
	v_pk_add_f32 v[134:135], v[134:135], v[170:171] neg_lo:[0,1] neg_hi:[0,1]
	v_xor_b32_e32 v5, 0x80000000, v2
	v_pk_mul_f32 v[170:171], v[134:135], s[26:27]
	v_mov_b32_e32 v3, v5
	v_pk_fma_f32 v[134:135], v[134:135], s[24:25], v[170:171] op_sel:[0,0,1] op_sel_hi:[1,0,0]
	s_waitcnt lgkmcnt(5)
	v_pk_add_f32 v[170:171], v[136:137], v[172:173]
	v_pk_add_f32 v[136:137], v[136:137], v[172:173] neg_lo:[0,1] neg_hi:[0,1]
	v_pk_mul_f32 v[6:7], v[4:5], v[2:3] op_sel:[1,0] op_sel_hi:[0,1]
	v_pk_mul_f32 v[172:173], v[136:137], s[36:37]
	v_pk_fma_f32 v[6:7], v[4:5], v[4:5], v[6:7] op_sel_hi:[1,0,1]
	v_pk_fma_f32 v[136:137], v[136:137], s[78:79], v[172:173] op_sel:[0,0,1] op_sel_hi:[1,0,0]
	v_pk_add_f32 v[172:173], v[138:139], v[174:175]
	v_pk_add_f32 v[138:139], v[138:139], v[174:175] neg_lo:[0,1] neg_hi:[0,1]
	v_pk_mul_f32 v[174:175], v[138:139], s[38:39]
	v_pk_fma_f32 v[138:139], v[138:139], s[0:1], v[174:175] op_sel:[0,0,1] op_sel_hi:[1,0,0]
	s_waitcnt lgkmcnt(4)
	v_pk_add_f32 v[174:175], v[140:141], v[176:177]
	v_pk_add_f32 v[140:141], v[140:141], v[176:177] neg_lo:[0,1] neg_hi:[0,1]
	v_pk_mul_f32 v[10:11], v[6:7], v[6:7] op_sel:[1,1] op_sel_hi:[0,1] neg_lo:[0,1]
	v_pk_mul_f32 v[176:177], v[140:141], s[40:41]
	v_pk_fma_f32 v[10:11], v[6:7], v[6:7], v[10:11] op_sel_hi:[1,0,1]
	v_pk_fma_f32 v[140:141], v[140:141], s[80:81], v[176:177] op_sel:[0,0,1] op_sel_hi:[1,0,0]
	v_pk_add_f32 v[176:177], v[142:143], v[178:179]
	v_pk_add_f32 v[142:143], v[142:143], v[178:179] neg_lo:[0,1] neg_hi:[0,1]
	v_pk_mul_f32 v[178:179], v[142:143], s[42:43]
	v_pk_fma_f32 v[142:143], v[142:143], s[74:75], v[178:179] op_sel:[0,0,1] op_sel_hi:[1,0,0]
	s_waitcnt lgkmcnt(3)
	v_pk_add_f32 v[178:179], v[148:149], v[180:181]
	v_pk_add_f32 v[180:181], v[148:149], v[180:181] neg_lo:[0,1] neg_hi:[0,1]
	v_pk_mul_f32 v[28:29], v[10:11], v[10:11] op_sel:[1,1] op_sel_hi:[0,1] neg_lo:[0,1]
	v_pk_add_f32 v[148:149], v[150:151], v[182:183]
	v_pk_add_f32 v[150:151], v[150:151], v[182:183] neg_lo:[0,1] neg_hi:[0,1]
	v_pk_fma_f32 v[28:29], v[10:11], v[10:11], v[28:29] op_sel_hi:[1,0,1]
	v_pk_mul_f32 v[182:183], v[150:151], s[42:43]
	v_pk_mul_f32 v[44:45], v[10:11], v[28:29] op_sel:[1,1] op_sel_hi:[1,0] neg_lo:[1,0]
	v_pk_fma_f32 v[150:151], v[150:151], s[74:75], v[182:183] op_sel:[0,0,1] op_sel_hi:[1,0,0] neg_lo:[1,0,0] neg_hi:[1,0,0]
	s_waitcnt lgkmcnt(2)
	v_pk_add_f32 v[182:183], v[152:153], v[184:185]
	v_pk_add_f32 v[152:153], v[152:153], v[184:185] neg_lo:[0,1] neg_hi:[0,1]
	v_pk_fma_f32 v[44:45], v[10:11], v[28:29], v[44:45] op_sel_hi:[0,1,1]
	v_pk_mul_f32 v[184:185], v[152:153], s[40:41]
	v_pk_mul_f32 v[60:61], v[10:11], v[44:45] op_sel:[1,1] op_sel_hi:[1,0] neg_lo:[1,0]
	v_pk_fma_f32 v[152:153], v[152:153], s[80:81], v[184:185] op_sel:[0,0,1] op_sel_hi:[1,0,0] neg_lo:[1,0,0] neg_hi:[1,0,0]
	v_pk_add_f32 v[184:185], v[154:155], v[186:187]
	v_pk_add_f32 v[154:155], v[154:155], v[186:187] neg_lo:[0,1] neg_hi:[0,1]
	v_pk_fma_f32 v[60:61], v[10:11], v[44:45], v[60:61] op_sel_hi:[0,1,1]
	v_pk_mul_f32 v[186:187], v[154:155], s[38:39]
	v_pk_mul_f32 v[76:77], v[10:11], v[60:61] op_sel:[1,1] op_sel_hi:[1,0] neg_lo:[1,0]
	v_pk_fma_f32 v[154:155], v[154:155], s[0:1], v[186:187] op_sel:[0,0,1] op_sel_hi:[1,0,0] neg_lo:[1,0,0] neg_hi:[1,0,0]
	s_waitcnt lgkmcnt(1)
	v_pk_add_f32 v[186:187], v[156:157], v[188:189]
	v_pk_add_f32 v[156:157], v[156:157], v[188:189] neg_lo:[0,1] neg_hi:[0,1]
	v_pk_fma_f32 v[76:77], v[10:11], v[60:61], v[76:77] op_sel_hi:[0,1,1]
	v_pk_mul_f32 v[188:189], v[156:157], s[36:37]
	v_pk_mul_f32 v[92:93], v[10:11], v[76:77] op_sel:[1,1] op_sel_hi:[1,0] neg_lo:[1,0]
	v_pk_fma_f32 v[156:157], v[156:157], s[78:79], v[188:189] op_sel:[0,0,1] op_sel_hi:[1,0,0] neg_lo:[1,0,0] neg_hi:[1,0,0]
	v_pk_add_f32 v[188:189], v[158:159], v[190:191]
	v_pk_add_f32 v[158:159], v[158:159], v[190:191] neg_lo:[0,1] neg_hi:[0,1]
	v_pk_fma_f32 v[92:93], v[10:11], v[76:77], v[92:93] op_sel_hi:[0,1,1]
	v_pk_mul_f32 v[190:191], v[158:159], s[26:27]
	v_pk_mul_f32 v[108:109], v[10:11], v[92:93] op_sel:[1,1] op_sel_hi:[1,0] neg_lo:[1,0]
	v_pk_fma_f32 v[158:159], v[158:159], s[24:25], v[190:191] op_sel:[0,0,1] op_sel_hi:[1,0,0] neg_lo:[1,0,0] neg_hi:[1,0,0]
	s_waitcnt lgkmcnt(0)
	v_pk_add_f32 v[190:191], v[160:161], v[192:193]
	v_pk_add_f32 v[160:161], v[160:161], v[192:193] neg_lo:[0,1] neg_hi:[0,1]
	v_pk_mul_f32 v[8:9], v[2:3], v[6:7] op_sel:[0,1] op_sel_hi:[1,0]
	v_pk_mul_f32 v[192:193], v[160:161], s[18:19]
	v_pk_fma_f32 v[108:109], v[10:11], v[92:93], v[108:109] op_sel_hi:[0,1,1]
	v_pk_fma_f32 v[160:161], v[160:161], s[16:17], v[192:193] op_sel:[0,0,1] op_sel_hi:[1,0,0] neg_lo:[1,0,0] neg_hi:[1,0,0]
	v_pk_add_f32 v[192:193], v[162:163], v[194:195]
	v_pk_add_f32 v[162:163], v[162:163], v[194:195] neg_lo:[0,1] neg_hi:[0,1]
	v_pk_fma_f32 v[8:9], v[4:5], v[6:7], v[8:9] op_sel_hi:[0,1,1]
	v_pk_mul_f32 v[194:195], v[162:163], s[10:11]
	v_pk_mul_f32 v[16:17], v[2:3], v[10:11] op_sel:[0,1] op_sel_hi:[1,0]
	v_pk_fma_f32 v[162:163], v[162:163], s[8:9], v[194:195] op_sel:[0,0,1] op_sel_hi:[1,0,0] neg_lo:[1,0,0] neg_hi:[1,0,0]
	v_pk_add_f32 v[194:195], v[144:145], v[178:179]
	v_pk_add_f32 v[144:145], v[144:145], v[178:179] neg_lo:[0,1] neg_hi:[0,1]
	v_pk_add_f32 v[178:179], v[164:165], v[148:149]
	v_pk_add_f32 v[148:149], v[164:165], v[148:149] neg_lo:[0,1] neg_hi:[0,1]
	v_pk_mul_f32 v[32:33], v[2:3], v[28:29] op_sel:[0,1] op_sel_hi:[1,0]
	v_pk_mul_f32 v[164:165], v[148:149], s[18:19]
	v_pk_mul_f32 v[48:49], v[2:3], v[44:45] op_sel:[0,1] op_sel_hi:[1,0]
	v_pk_fma_f32 v[148:149], v[148:149], s[16:17], v[164:165] op_sel:[0,0,1] op_sel_hi:[1,0,0]
	v_pk_add_f32 v[164:165], v[166:167], v[182:183]
	v_pk_add_f32 v[166:167], v[166:167], v[182:183] neg_lo:[0,1] neg_hi:[0,1]
	v_pk_mul_f32 v[64:65], v[2:3], v[60:61] op_sel:[0,1] op_sel_hi:[1,0]
	v_pk_mul_f32 v[182:183], v[166:167], s[36:37]
	v_pk_mul_f32 v[80:81], v[2:3], v[76:77] op_sel:[0,1] op_sel_hi:[1,0]
	v_pk_fma_f32 v[166:167], v[166:167], s[78:79], v[182:183] op_sel:[0,0,1] op_sel_hi:[1,0,0]
	v_pk_add_f32 v[182:183], v[168:169], v[184:185]
	v_pk_add_f32 v[168:169], v[168:169], v[184:185] neg_lo:[0,1] neg_hi:[0,1]
	v_pk_mul_f32 v[96:97], v[2:3], v[92:93] op_sel:[0,1] op_sel_hi:[1,0]
	v_pk_mul_f32 v[184:185], v[168:169], s[40:41]
	v_pk_mul_f32 v[112:113], v[2:3], v[108:109] op_sel:[0,1] op_sel_hi:[1,0]
	v_pk_fma_f32 v[168:169], v[168:169], s[80:81], v[184:185] op_sel:[0,0,1] op_sel_hi:[1,0,0]
	v_pk_add_f32 v[184:185], v[170:171], v[186:187]
	v_pk_add_f32 v[186:187], v[170:171], v[186:187] neg_lo:[0,1] neg_hi:[0,1]
	v_pk_add_f32 v[170:171], v[172:173], v[188:189]
	v_pk_add_f32 v[172:173], v[172:173], v[188:189] neg_lo:[0,1] neg_hi:[0,1]
	v_pk_mul_f32 v[188:189], v[172:173], s[40:41]
	v_pk_fma_f32 v[16:17], v[4:5], v[10:11], v[16:17] op_sel_hi:[0,1,1]
	v_pk_fma_f32 v[172:173], v[172:173], s[80:81], v[188:189] op_sel:[0,0,1] op_sel_hi:[1,0,0] neg_lo:[1,0,0] neg_hi:[1,0,0]
	v_pk_add_f32 v[188:189], v[174:175], v[190:191]
	v_pk_add_f32 v[174:175], v[174:175], v[190:191] neg_lo:[0,1] neg_hi:[0,1]
	v_pk_mul_f32 v[20:21], v[6:7], v[10:11] op_sel:[1,1] op_sel_hi:[1,0] neg_lo:[1,0]
	v_pk_mul_f32 v[190:191], v[174:175], s[36:37]
	v_pk_fma_f32 v[32:33], v[4:5], v[28:29], v[32:33] op_sel_hi:[0,1,1]
	v_pk_fma_f32 v[174:175], v[174:175], s[78:79], v[190:191] op_sel:[0,0,1] op_sel_hi:[1,0,0] neg_lo:[1,0,0] neg_hi:[1,0,0]
	v_pk_add_f32 v[190:191], v[176:177], v[192:193]
	v_pk_add_f32 v[176:177], v[176:177], v[192:193] neg_lo:[0,1] neg_hi:[0,1]
	v_pk_mul_f32 v[36:37], v[6:7], v[28:29] op_sel:[1,1] op_sel_hi:[1,0] neg_lo:[1,0]
	v_pk_mul_f32 v[192:193], v[176:177], s[18:19]
	v_pk_fma_f32 v[48:49], v[4:5], v[44:45], v[48:49] op_sel_hi:[0,1,1]
	v_pk_fma_f32 v[176:177], v[176:177], s[16:17], v[192:193] op_sel:[0,0,1] op_sel_hi:[1,0,0] neg_lo:[1,0,0] neg_hi:[1,0,0]
	v_pk_add_f32 v[192:193], v[128:129], v[180:181] op_sel:[0,1] op_sel_hi:[1,0] neg_hi:[0,1]
	v_pk_add_f32 v[128:129], v[128:129], v[180:181] op_sel:[0,1] op_sel_hi:[1,0] neg_lo:[0,1]
	v_pk_add_f32 v[180:181], v[130:131], v[150:151]
	v_pk_add_f32 v[130:131], v[130:131], v[150:151] neg_lo:[0,1] neg_hi:[0,1]
	v_pk_mul_f32 v[52:53], v[6:7], v[44:45] op_sel:[1,1] op_sel_hi:[1,0] neg_lo:[1,0]
	v_pk_mul_f32 v[150:151], v[130:131], s[18:19]
	v_pk_fma_f32 v[64:65], v[4:5], v[60:61], v[64:65] op_sel_hi:[0,1,1]
	v_pk_fma_f32 v[130:131], v[130:131], s[16:17], v[150:151] op_sel:[0,0,1] op_sel_hi:[1,0,0]
	v_pk_add_f32 v[150:151], v[132:133], v[152:153]
	v_pk_add_f32 v[132:133], v[132:133], v[152:153] neg_lo:[0,1] neg_hi:[0,1]
	v_pk_mul_f32 v[68:69], v[6:7], v[60:61] op_sel:[1,1] op_sel_hi:[1,0] neg_lo:[1,0]
	v_pk_mul_f32 v[152:153], v[132:133], s[36:37]
	v_pk_fma_f32 v[80:81], v[4:5], v[76:77], v[80:81] op_sel_hi:[0,1,1]
	v_pk_fma_f32 v[132:133], v[132:133], s[78:79], v[152:153] op_sel:[0,0,1] op_sel_hi:[1,0,0]
	v_pk_add_f32 v[152:153], v[134:135], v[154:155]
	v_pk_add_f32 v[134:135], v[134:135], v[154:155] neg_lo:[0,1] neg_hi:[0,1]
	v_pk_mul_f32 v[84:85], v[6:7], v[76:77] op_sel:[1,1] op_sel_hi:[1,0] neg_lo:[1,0]
	v_pk_mul_f32 v[154:155], v[134:135], s[40:41]
	v_pk_fma_f32 v[96:97], v[4:5], v[92:93], v[96:97] op_sel_hi:[0,1,1]
	v_pk_fma_f32 v[134:135], v[134:135], s[80:81], v[154:155] op_sel:[0,0,1] op_sel_hi:[1,0,0]
	v_pk_add_f32 v[154:155], v[136:137], v[156:157]
	v_pk_add_f32 v[156:157], v[136:137], v[156:157] neg_lo:[0,1] neg_hi:[0,1]
	v_pk_mul_f32 v[100:101], v[6:7], v[92:93] op_sel:[1,1] op_sel_hi:[1,0] neg_lo:[1,0]
	v_pk_add_f32 v[136:137], v[138:139], v[158:159]
	v_pk_add_f32 v[138:139], v[138:139], v[158:159] neg_lo:[0,1] neg_hi:[0,1]
	v_pk_fma_f32 v[112:113], v[4:5], v[108:109], v[112:113] op_sel_hi:[0,1,1]
	v_pk_mul_f32 v[158:159], v[138:139], s[40:41]
	v_pk_mul_f32 v[116:117], v[6:7], v[108:109] op_sel:[1,1] op_sel_hi:[1,0] neg_lo:[1,0]
	v_pk_fma_f32 v[138:139], v[138:139], s[80:81], v[158:159] op_sel:[0,0,1] op_sel_hi:[1,0,0] neg_lo:[1,0,0] neg_hi:[1,0,0]
	v_pk_add_f32 v[158:159], v[140:141], v[160:161]
	v_pk_add_f32 v[140:141], v[140:141], v[160:161] neg_lo:[0,1] neg_hi:[0,1]
	v_pk_fma_f32 v[20:21], v[6:7], v[10:11], v[20:21] op_sel_hi:[0,1,1]
	v_pk_mul_f32 v[160:161], v[140:141], s[36:37]
	v_pk_mul_f32 v[24:25], v[10:11], v[8:9] op_sel:[1,1] op_sel_hi:[0,1] neg_lo:[0,1]
	v_pk_fma_f32 v[140:141], v[140:141], s[78:79], v[160:161] op_sel:[0,0,1] op_sel_hi:[1,0,0] neg_lo:[1,0,0] neg_hi:[1,0,0]
	v_pk_add_f32 v[160:161], v[142:143], v[162:163]
	v_pk_add_f32 v[142:143], v[142:143], v[162:163] neg_lo:[0,1] neg_hi:[0,1]
	v_pk_fma_f32 v[36:37], v[6:7], v[28:29], v[36:37] op_sel_hi:[0,1,1]
	v_pk_mul_f32 v[162:163], v[142:143], s[18:19]
	v_pk_mul_f32 v[40:41], v[8:9], v[28:29] op_sel:[1,1] op_sel_hi:[1,0] neg_lo:[1,0]
	v_pk_fma_f32 v[142:143], v[142:143], s[16:17], v[162:163] op_sel:[0,0,1] op_sel_hi:[1,0,0] neg_lo:[1,0,0] neg_hi:[1,0,0]
	v_pk_add_f32 v[162:163], v[194:195], v[184:185]
	v_pk_add_f32 v[184:185], v[194:195], v[184:185] neg_lo:[0,1] neg_hi:[0,1]
	v_pk_add_f32 v[194:195], v[178:179], v[170:171]
	v_pk_add_f32 v[170:171], v[178:179], v[170:171] neg_lo:[0,1] neg_hi:[0,1]
	v_pk_fma_f32 v[52:53], v[6:7], v[44:45], v[52:53] op_sel_hi:[0,1,1]
	v_pk_mul_f32 v[178:179], v[170:171], s[36:37]
	v_pk_mul_f32 v[56:57], v[8:9], v[44:45] op_sel:[1,1] op_sel_hi:[1,0] neg_lo:[1,0]
	v_pk_fma_f32 v[170:171], v[170:171], s[78:79], v[178:179] op_sel:[0,0,1] op_sel_hi:[1,0,0]
	v_pk_add_f32 v[178:179], v[164:165], v[188:189]
	v_pk_add_f32 v[188:189], v[164:165], v[188:189] neg_lo:[0,1] neg_hi:[0,1]
	v_pk_fma_f32 v[68:69], v[6:7], v[60:61], v[68:69] op_sel_hi:[0,1,1]
	v_pk_add_f32 v[164:165], v[182:183], v[190:191]
	v_pk_add_f32 v[182:183], v[182:183], v[190:191] neg_lo:[0,1] neg_hi:[0,1]
	v_pk_mul_f32 v[72:73], v[8:9], v[60:61] op_sel:[1,1] op_sel_hi:[1,0] neg_lo:[1,0]
	v_pk_mul_f32 v[190:191], v[182:183], s[36:37]
	v_pk_fma_f32 v[84:85], v[6:7], v[76:77], v[84:85] op_sel_hi:[0,1,1]
	v_pk_fma_f32 v[182:183], v[182:183], s[78:79], v[190:191] op_sel:[0,0,1] op_sel_hi:[1,0,0] neg_lo:[1,0,0] neg_hi:[1,0,0]
	v_pk_add_f32 v[190:191], v[144:145], v[186:187] op_sel:[0,1] op_sel_hi:[1,0] neg_hi:[0,1]
	v_pk_add_f32 v[144:145], v[144:145], v[186:187] op_sel:[0,1] op_sel_hi:[1,0] neg_lo:[0,1]
	v_pk_add_f32 v[186:187], v[148:149], v[172:173]
	v_pk_add_f32 v[148:149], v[148:149], v[172:173] neg_lo:[0,1] neg_hi:[0,1]
	v_pk_mul_f32 v[88:89], v[8:9], v[76:77] op_sel:[1,1] op_sel_hi:[1,0] neg_lo:[1,0]
	v_pk_mul_f32 v[172:173], v[148:149], s[36:37]
	v_pk_fma_f32 v[100:101], v[6:7], v[92:93], v[100:101] op_sel_hi:[0,1,1]
	v_pk_fma_f32 v[148:149], v[148:149], s[78:79], v[172:173] op_sel:[0,0,1] op_sel_hi:[1,0,0]
	v_pk_add_f32 v[172:173], v[166:167], v[174:175]
	v_pk_add_f32 v[174:175], v[166:167], v[174:175] neg_lo:[0,1] neg_hi:[0,1]
	v_pk_mul_f32 v[104:105], v[8:9], v[92:93] op_sel:[1,1] op_sel_hi:[1,0] neg_lo:[1,0]
	v_pk_add_f32 v[166:167], v[168:169], v[176:177]
	v_pk_add_f32 v[168:169], v[168:169], v[176:177] neg_lo:[0,1] neg_hi:[0,1]
	v_pk_fma_f32 v[116:117], v[6:7], v[108:109], v[116:117] op_sel_hi:[0,1,1]
	v_pk_mul_f32 v[176:177], v[168:169], s[36:37]
	v_pk_mul_f32 v[120:121], v[8:9], v[108:109] op_sel:[1,1] op_sel_hi:[1,0] neg_lo:[1,0]
	v_pk_fma_f32 v[168:169], v[168:169], s[78:79], v[176:177] op_sel:[0,0,1] op_sel_hi:[1,0,0] neg_lo:[1,0,0] neg_hi:[1,0,0]
	v_pk_add_f32 v[176:177], v[192:193], v[154:155]
	v_pk_add_f32 v[154:155], v[192:193], v[154:155] neg_lo:[0,1] neg_hi:[0,1]
	v_pk_add_f32 v[192:193], v[180:181], v[136:137]
	v_pk_add_f32 v[136:137], v[180:181], v[136:137] neg_lo:[0,1] neg_hi:[0,1]
	v_xor_b32_e32 v26, 0x80000000, v17
	v_pk_mul_f32 v[180:181], v[136:137], s[36:37]
	v_xor_b32_e32 v30, 0x80000000, v21
	v_pk_fma_f32 v[136:137], v[136:137], s[78:79], v[180:181] op_sel:[0,0,1] op_sel_hi:[1,0,0]
	v_pk_add_f32 v[180:181], v[150:151], v[158:159]
	v_pk_add_f32 v[158:159], v[150:151], v[158:159] neg_lo:[0,1] neg_hi:[0,1]
	v_pk_fma_f32 v[24:25], v[10:11], v[8:9], v[24:25] op_sel_hi:[1,0,1]
	v_pk_add_f32 v[150:151], v[152:153], v[160:161]
	v_pk_add_f32 v[152:153], v[152:153], v[160:161] neg_lo:[0,1] neg_hi:[0,1]
	v_pk_fma_f32 v[40:41], v[8:9], v[28:29], v[40:41] op_sel_hi:[0,1,1]
	v_pk_mul_f32 v[160:161], v[152:153], s[36:37]
	v_pk_fma_f32 v[56:57], v[8:9], v[44:45], v[56:57] op_sel_hi:[0,1,1]
	v_pk_fma_f32 v[152:153], v[152:153], s[78:79], v[160:161] op_sel:[0,0,1] op_sel_hi:[1,0,0] neg_lo:[1,0,0] neg_hi:[1,0,0]
	v_pk_add_f32 v[160:161], v[128:129], v[156:157] op_sel:[0,1] op_sel_hi:[1,0] neg_hi:[0,1]
	v_pk_add_f32 v[128:129], v[128:129], v[156:157] op_sel:[0,1] op_sel_hi:[1,0] neg_lo:[0,1]
	v_pk_add_f32 v[156:157], v[130:131], v[138:139]
	v_pk_add_f32 v[130:131], v[130:131], v[138:139] neg_lo:[0,1] neg_hi:[0,1]
	v_pk_fma_f32 v[72:73], v[8:9], v[60:61], v[72:73] op_sel_hi:[0,1,1]
	v_pk_mul_f32 v[138:139], v[130:131], s[36:37]
	v_pk_fma_f32 v[88:89], v[8:9], v[76:77], v[88:89] op_sel_hi:[0,1,1]
	v_pk_fma_f32 v[130:131], v[130:131], s[78:79], v[138:139] op_sel:[0,0,1] op_sel_hi:[1,0,0]
	v_pk_add_f32 v[138:139], v[132:133], v[140:141]
	v_pk_add_f32 v[140:141], v[132:133], v[140:141] neg_lo:[0,1] neg_hi:[0,1]
	v_pk_fma_f32 v[104:105], v[8:9], v[92:93], v[104:105] op_sel_hi:[0,1,1]
	v_pk_add_f32 v[132:133], v[134:135], v[142:143]
	v_pk_add_f32 v[134:135], v[134:135], v[142:143] neg_lo:[0,1] neg_hi:[0,1]
	v_pk_fma_f32 v[120:121], v[8:9], v[108:109], v[120:121] op_sel_hi:[0,1,1]
	v_pk_mul_f32 v[142:143], v[134:135], s[36:37]
	v_mov_b32_e32 v27, v17
	v_pk_fma_f32 v[134:135], v[134:135], s[78:79], v[142:143] op_sel:[0,0,1] op_sel_hi:[1,0,0] neg_lo:[1,0,0] neg_hi:[1,0,0]
	v_pk_add_f32 v[142:143], v[162:163], v[178:179]
	v_pk_add_f32 v[162:163], v[162:163], v[178:179] neg_lo:[0,1] neg_hi:[0,1]
	v_pk_add_f32 v[178:179], v[194:195], v[164:165]
	v_pk_add_f32 v[194:195], v[194:195], v[164:165] neg_lo:[0,1] neg_hi:[0,1]
	v_mov_b32_e32 v31, v21
	v_pk_add_f32 v[164:165], v[184:185], v[188:189] op_sel:[0,1] op_sel_hi:[1,0] neg_hi:[0,1]
	v_pk_add_f32 v[184:185], v[184:185], v[188:189] op_sel:[0,1] op_sel_hi:[1,0] neg_lo:[0,1]
	v_pk_add_f32 v[188:189], v[170:171], v[182:183]
	v_pk_add_f32 v[182:183], v[170:171], v[182:183] neg_lo:[0,1] neg_hi:[0,1]
	v_xor_b32_e32 v34, 0x80000000, v25
	v_pk_add_f32 v[170:171], v[190:191], v[172:173]
	v_pk_add_f32 v[172:173], v[190:191], v[172:173] neg_lo:[0,1] neg_hi:[0,1]
	v_pk_add_f32 v[190:191], v[186:187], v[166:167]
	v_pk_add_f32 v[186:187], v[186:187], v[166:167] neg_lo:[0,1] neg_hi:[0,1]
	v_xor_b32_e32 v38, 0x80000000, v29
	v_pk_add_f32 v[166:167], v[144:145], v[174:175] op_sel:[0,1] op_sel_hi:[1,0] neg_hi:[0,1]
	v_pk_add_f32 v[144:145], v[144:145], v[174:175] op_sel:[0,1] op_sel_hi:[1,0] neg_lo:[0,1]
	v_pk_add_f32 v[174:175], v[148:149], v[168:169]
	v_pk_add_f32 v[168:169], v[148:149], v[168:169] neg_lo:[0,1] neg_hi:[0,1]
	v_xor_b32_e32 v42, 0x80000000, v33
	v_pk_add_f32 v[148:149], v[176:177], v[180:181]
	v_pk_add_f32 v[176:177], v[176:177], v[180:181] neg_lo:[0,1] neg_hi:[0,1]
	v_pk_add_f32 v[180:181], v[192:193], v[150:151]
	v_pk_add_f32 v[192:193], v[192:193], v[150:151] neg_lo:[0,1] neg_hi:[0,1]
	v_xor_b32_e32 v46, 0x80000000, v37
	v_pk_add_f32 v[150:151], v[154:155], v[158:159] op_sel:[0,1] op_sel_hi:[1,0] neg_hi:[0,1]
	v_pk_add_f32 v[154:155], v[154:155], v[158:159] op_sel:[0,1] op_sel_hi:[1,0] neg_lo:[0,1]
	v_pk_add_f32 v[158:159], v[136:137], v[152:153]
	v_pk_add_f32 v[152:153], v[136:137], v[152:153] neg_lo:[0,1] neg_hi:[0,1]
	v_mov_b32_e32 v35, v25
	v_pk_add_f32 v[136:137], v[160:161], v[138:139]
	v_pk_add_f32 v[138:139], v[160:161], v[138:139] neg_lo:[0,1] neg_hi:[0,1]
	v_pk_add_f32 v[160:161], v[156:157], v[132:133]
	v_pk_add_f32 v[156:157], v[156:157], v[132:133] neg_lo:[0,1] neg_hi:[0,1]
	v_mov_b32_e32 v39, v29
	v_pk_add_f32 v[132:133], v[128:129], v[140:141] op_sel:[0,1] op_sel_hi:[1,0] neg_hi:[0,1]
	v_pk_add_f32 v[128:129], v[128:129], v[140:141] op_sel:[0,1] op_sel_hi:[1,0] neg_lo:[0,1]
	v_pk_add_f32 v[140:141], v[130:131], v[134:135]
	v_pk_add_f32 v[134:135], v[130:131], v[134:135] neg_lo:[0,1] neg_hi:[0,1]
	v_mov_b32_e32 v43, v33
	v_pk_add_f32 v[130:131], v[142:143], v[178:179]
	v_pk_add_f32 v[142:143], v[142:143], v[178:179] neg_lo:[0,1] neg_hi:[0,1]
	v_pk_add_f32 v[178:179], v[162:163], v[194:195] op_sel:[0,1] op_sel_hi:[1,0] neg_hi:[0,1]
	v_pk_add_f32 v[162:163], v[162:163], v[194:195] op_sel:[0,1] op_sel_hi:[1,0] neg_lo:[0,1]
	v_pk_add_f32 v[194:195], v[164:165], v[188:189]
	v_pk_add_f32 v[164:165], v[164:165], v[188:189] neg_lo:[0,1] neg_hi:[0,1]
	v_pk_add_f32 v[188:189], v[184:185], v[182:183] op_sel:[0,1] op_sel_hi:[1,0] neg_hi:[0,1]
	v_pk_add_f32 v[182:183], v[184:185], v[182:183] op_sel:[0,1] op_sel_hi:[1,0] neg_lo:[0,1]
	v_pk_add_f32 v[184:185], v[170:171], v[190:191]
	v_pk_add_f32 v[170:171], v[170:171], v[190:191] neg_lo:[0,1] neg_hi:[0,1]
	v_pk_add_f32 v[190:191], v[172:173], v[186:187] op_sel:[0,1] op_sel_hi:[1,0] neg_hi:[0,1]
	v_pk_add_f32 v[172:173], v[172:173], v[186:187] op_sel:[0,1] op_sel_hi:[1,0] neg_lo:[0,1]
	v_pk_add_f32 v[186:187], v[166:167], v[174:175]
	v_pk_add_f32 v[166:167], v[166:167], v[174:175] neg_lo:[0,1] neg_hi:[0,1]
	v_pk_add_f32 v[174:175], v[144:145], v[168:169] op_sel:[0,1] op_sel_hi:[1,0] neg_hi:[0,1]
	v_pk_add_f32 v[144:145], v[144:145], v[168:169] op_sel:[0,1] op_sel_hi:[1,0] neg_lo:[0,1]
	v_pk_add_f32 v[168:169], v[148:149], v[180:181]
	v_pk_add_f32 v[148:149], v[148:149], v[180:181] neg_lo:[0,1] neg_hi:[0,1]
	v_pk_mul_f32 v[2:3], v[2:3], v[168:169] op_sel:[0,1] op_sel_hi:[1,0]
	v_pk_add_f32 v[180:181], v[176:177], v[192:193] op_sel:[0,1] op_sel_hi:[1,0] neg_hi:[0,1]
	v_pk_add_f32 v[176:177], v[176:177], v[192:193] op_sel:[0,1] op_sel_hi:[1,0] neg_lo:[0,1]
	v_pk_add_f32 v[192:193], v[150:151], v[158:159]
	v_pk_add_f32 v[150:151], v[150:151], v[158:159] neg_lo:[0,1] neg_hi:[0,1]
	v_pk_add_f32 v[158:159], v[154:155], v[152:153] op_sel:[0,1] op_sel_hi:[1,0] neg_hi:[0,1]
	v_pk_add_f32 v[152:153], v[154:155], v[152:153] op_sel:[0,1] op_sel_hi:[1,0] neg_lo:[0,1]
	v_pk_add_f32 v[154:155], v[136:137], v[160:161]
	v_pk_fma_f32 v[2:3], v[4:5], v[168:169], v[2:3] op_sel_hi:[0,1,1]
	v_pk_mul_f32 v[4:5], v[6:7], v[184:185] op_sel:[1,1] op_sel_hi:[1,0] neg_lo:[1,0]
	v_mov_b32_e32 v47, v37
	v_pk_fma_f32 v[4:5], v[6:7], v[184:185], v[4:5] op_sel_hi:[0,1,1]
	v_pk_mul_f32 v[6:7], v[8:9], v[154:155] op_sel:[1,1] op_sel_hi:[1,0] neg_lo:[1,0]
	v_pk_add_f32 v[136:137], v[136:137], v[160:161] neg_lo:[0,1] neg_hi:[0,1]
	v_pk_fma_f32 v[6:7], v[8:9], v[154:155], v[6:7] op_sel_hi:[0,1,1]
	v_pk_mul_f32 v[8:9], v[10:11], v[194:195] op_sel:[1,1] op_sel_hi:[1,0] neg_lo:[1,0]
	v_pk_add_f32 v[160:161], v[138:139], v[156:157] op_sel:[0,1] op_sel_hi:[1,0] neg_hi:[0,1]
	v_pk_add_f32 v[138:139], v[138:139], v[156:157] op_sel:[0,1] op_sel_hi:[1,0] neg_lo:[0,1]
	v_pk_add_f32 v[156:157], v[132:133], v[140:141]
	v_pk_fma_f32 v[8:9], v[10:11], v[194:195], v[8:9] op_sel_hi:[0,1,1]
	v_pk_mul_f32 v[10:11], v[26:27], v[192:193] op_sel:[0,1] op_sel_hi:[1,0]
	v_pk_mul_f32 v[12:13], v[30:31], v[186:187] op_sel:[0,1] op_sel_hi:[1,0]
	v_pk_add_f32 v[132:133], v[132:133], v[140:141] neg_lo:[0,1] neg_hi:[0,1]
	v_pk_add_f32 v[140:141], v[128:129], v[134:135] op_sel:[0,1] op_sel_hi:[1,0] neg_hi:[0,1]
	v_pk_fma_f32 v[10:11], v[16:17], v[192:193], v[10:11] op_sel_hi:[0,1,1]
	v_pk_fma_f32 v[12:13], v[20:21], v[186:187], v[12:13] op_sel_hi:[0,1,1]
	v_pk_mul_f32 v[14:15], v[34:35], v[156:157] op_sel:[0,1] op_sel_hi:[1,0]
	v_pk_mul_f32 v[16:17], v[38:39], v[178:179] op_sel:[0,1] op_sel_hi:[1,0]
	v_pk_mul_f32 v[20:21], v[42:43], v[180:181] op_sel:[0,1] op_sel_hi:[1,0]
	v_pk_mul_f32 v[22:23], v[46:47], v[190:191] op_sel:[0,1] op_sel_hi:[1,0]
	v_xor_b32_e32 v78, 0x80000000, v69
	v_xor_b32_e32 v82, 0x80000000, v73
	v_xor_b32_e32 v86, 0x80000000, v77
	v_xor_b32_e32 v90, 0x80000000, v81
	v_xor_b32_e32 v94, 0x80000000, v85
	v_xor_b32_e32 v98, 0x80000000, v89
	v_xor_b32_e32 v102, 0x80000000, v93
	v_xor_b32_e32 v106, 0x80000000, v97
	v_xor_b32_e32 v110, 0x80000000, v101
	v_xor_b32_e32 v114, 0x80000000, v105
	v_xor_b32_e32 v118, 0x80000000, v109
	v_xor_b32_e32 v122, 0x80000000, v113
	v_xor_b32_e32 v124, 0x80000000, v117
	v_xor_b32_e32 v126, 0x80000000, v121
	v_mov_b32_e32 v79, v69
	v_mov_b32_e32 v83, v73
	v_mov_b32_e32 v87, v77
	v_mov_b32_e32 v91, v81
	v_mov_b32_e32 v95, v85
	v_mov_b32_e32 v99, v89
	v_mov_b32_e32 v103, v93
	v_mov_b32_e32 v107, v97
	v_mov_b32_e32 v111, v101
	v_mov_b32_e32 v115, v105
	v_mov_b32_e32 v119, v109
	v_mov_b32_e32 v123, v113
	v_mov_b32_e32 v125, v117
	v_mov_b32_e32 v127, v121
	v_pk_add_f32 v[128:129], v[128:129], v[134:135] op_sel:[0,1] op_sel_hi:[1,0] neg_lo:[0,1]
	v_pk_fma_f32 v[14:15], v[24:25], v[156:157], v[14:15] op_sel_hi:[0,1,1]
	v_pk_fma_f32 v[16:17], v[28:29], v[178:179], v[16:17] op_sel_hi:[0,1,1]
	v_pk_fma_f32 v[20:21], v[32:33], v[180:181], v[20:21] op_sel_hi:[0,1,1]
	v_pk_fma_f32 v[22:23], v[36:37], v[190:191], v[22:23] op_sel_hi:[0,1,1]
	v_pk_mul_f32 v[24:25], v[40:41], v[160:161] op_sel:[1,1] op_sel_hi:[1,0] neg_lo:[1,0]
	v_pk_mul_f32 v[26:27], v[44:45], v[188:189] op_sel:[1,1] op_sel_hi:[1,0] neg_lo:[1,0]
	v_pk_mul_f32 v[28:29], v[48:49], v[158:159] op_sel:[1,1] op_sel_hi:[1,0] neg_lo:[1,0]
	v_pk_mul_f32 v[30:31], v[52:53], v[174:175] op_sel:[1,1] op_sel_hi:[1,0] neg_lo:[1,0]
	v_pk_mul_f32 v[32:33], v[56:57], v[140:141] op_sel:[1,1] op_sel_hi:[1,0] neg_lo:[1,0]
	v_pk_mul_f32 v[34:35], v[60:61], v[142:143] op_sel:[1,1] op_sel_hi:[1,0] neg_lo:[1,0]
	v_pk_mul_f32 v[36:37], v[64:65], v[148:149] op_sel:[1,1] op_sel_hi:[1,0] neg_lo:[1,0]
	v_pk_fma_f32 v[24:25], v[40:41], v[160:161], v[24:25] op_sel_hi:[0,1,1]
	v_pk_fma_f32 v[26:27], v[44:45], v[188:189], v[26:27] op_sel_hi:[0,1,1]
	v_pk_fma_f32 v[28:29], v[48:49], v[158:159], v[28:29] op_sel_hi:[0,1,1]
	v_pk_fma_f32 v[30:31], v[52:53], v[174:175], v[30:31] op_sel_hi:[0,1,1]
	v_pk_fma_f32 v[32:33], v[56:57], v[140:141], v[32:33] op_sel_hi:[0,1,1]
	v_pk_fma_f32 v[34:35], v[60:61], v[142:143], v[34:35] op_sel_hi:[0,1,1]
	v_pk_fma_f32 v[36:37], v[64:65], v[148:149], v[36:37] op_sel_hi:[0,1,1]
	v_pk_mul_f32 v[38:39], v[78:79], v[170:171] op_sel:[0,1] op_sel_hi:[1,0]
	v_pk_mul_f32 v[40:41], v[82:83], v[136:137] op_sel:[0,1] op_sel_hi:[1,0]
	v_pk_mul_f32 v[42:43], v[86:87], v[164:165] op_sel:[0,1] op_sel_hi:[1,0]
	v_pk_mul_f32 v[44:45], v[90:91], v[150:151] op_sel:[0,1] op_sel_hi:[1,0]
	v_pk_mul_f32 v[46:47], v[94:95], v[166:167] op_sel:[0,1] op_sel_hi:[1,0]
	v_pk_mul_f32 v[48:49], v[98:99], v[132:133] op_sel:[0,1] op_sel_hi:[1,0]
	v_pk_mul_f32 v[50:51], v[102:103], v[162:163] op_sel:[0,1] op_sel_hi:[1,0]
	v_pk_mul_f32 v[52:53], v[106:107], v[176:177] op_sel:[0,1] op_sel_hi:[1,0]
	v_pk_mul_f32 v[54:55], v[110:111], v[172:173] op_sel:[0,1] op_sel_hi:[1,0]
	v_pk_mul_f32 v[56:57], v[114:115], v[138:139] op_sel:[0,1] op_sel_hi:[1,0]
	v_pk_mul_f32 v[58:59], v[118:119], v[182:183] op_sel:[0,1] op_sel_hi:[1,0]
	v_pk_mul_f32 v[60:61], v[122:123], v[152:153] op_sel:[0,1] op_sel_hi:[1,0]
	v_pk_mul_f32 v[62:63], v[124:125], v[144:145] op_sel:[0,1] op_sel_hi:[1,0]
	v_pk_mul_f32 v[64:65], v[126:127], v[128:129] op_sel:[0,1] op_sel_hi:[1,0]
	v_pk_fma_f32 v[38:39], v[68:69], v[170:171], v[38:39] op_sel_hi:[0,1,1]
	v_pk_fma_f32 v[40:41], v[72:73], v[136:137], v[40:41] op_sel_hi:[0,1,1]
	v_pk_fma_f32 v[42:43], v[76:77], v[164:165], v[42:43] op_sel_hi:[0,1,1]
	v_pk_fma_f32 v[44:45], v[80:81], v[150:151], v[44:45] op_sel_hi:[0,1,1]
	v_pk_fma_f32 v[46:47], v[84:85], v[166:167], v[46:47] op_sel_hi:[0,1,1]
	v_pk_fma_f32 v[48:49], v[88:89], v[132:133], v[48:49] op_sel_hi:[0,1,1]
	v_pk_fma_f32 v[50:51], v[92:93], v[162:163], v[50:51] op_sel_hi:[0,1,1]
	v_pk_fma_f32 v[52:53], v[96:97], v[176:177], v[52:53] op_sel_hi:[0,1,1]
	v_pk_fma_f32 v[54:55], v[100:101], v[172:173], v[54:55] op_sel_hi:[0,1,1]
	v_pk_fma_f32 v[56:57], v[104:105], v[138:139], v[56:57] op_sel_hi:[0,1,1]
	v_pk_fma_f32 v[58:59], v[108:109], v[182:183], v[58:59] op_sel_hi:[0,1,1]
	v_pk_fma_f32 v[60:61], v[112:113], v[152:153], v[60:61] op_sel_hi:[0,1,1]
	v_pk_fma_f32 v[62:63], v[116:117], v[144:145], v[62:63] op_sel_hi:[0,1,1]
	v_pk_fma_f32 v[64:65], v[120:121], v[128:129], v[64:65] op_sel_hi:[0,1,1]
	ds_write2_b64 v18, v[130:131], v[34:35] offset1:16
	ds_write2_b64 v18, v[16:17], v[50:51] offset0:33 offset1:49
	ds_write2_b64 v18, v[8:9], v[42:43] offset0:66 offset1:82
	ds_write2_b64 v18, v[26:27], v[58:59] offset0:99 offset1:115
	ds_write2_b64 v18, v[4:5], v[38:39] offset0:132 offset1:148
	ds_write2_b64 v18, v[22:23], v[54:55] offset0:165 offset1:181
	ds_write2_b64 v18, v[12:13], v[46:47] offset0:198 offset1:214
	ds_write2_b64 v18, v[30:31], v[62:63] offset0:231 offset1:247
	ds_write2_b64 v196, v[2:3], v[36:37] offset0:8 offset1:24
	ds_write2_b64 v196, v[20:21], v[52:53] offset0:41 offset1:57
	ds_write2_b64 v196, v[10:11], v[44:45] offset0:74 offset1:90
	ds_write2_b64 v196, v[28:29], v[60:61] offset0:107 offset1:123
	ds_write2_b64 v196, v[6:7], v[40:41] offset0:140 offset1:156
	ds_write2_b64 v196, v[24:25], v[56:57] offset0:173 offset1:189
	ds_write2_b64 v196, v[14:15], v[48:49] offset0:206 offset1:222
	ds_write2_b64 v196, v[32:33], v[64:65] offset0:239 offset1:255
	v_ashrrev_i32_e32 v2, 31, v210
	v_lshrrev_b32_e32 v2, 23, v2
	v_add_u32_e32 v2, v210, v2
	s_lshl_b64 s[74:75], s[76:77], 16
	v_and_b32_e32 v2, 0xfffffe00, v2
	s_add_u32 s0, s54, s74
	v_sub_u32_e32 v2, v210, v2
	s_addc_u32 s1, s55, s75
	v_ashrrev_i32_e32 v3, 31, v2
	v_lshl_add_u64 v[14:15], v[2:3], 3, s[0:1]
	v_add_co_u32_e32 v2, vcc, s92, v14
	s_mov_b32 s0, 0x8000
	s_nop 0
	v_addc_co_u32_e32 v3, vcc, 0, v15, vcc
	v_add_co_u32_e32 v4, vcc, s95, v14
	s_waitcnt lgkmcnt(0)
	s_nop 0
	v_addc_co_u32_e32 v5, vcc, 0, v15, vcc
	v_add_co_u32_e32 v8, vcc, s96, v14
	s_barrier
	s_nop 0
	v_addc_co_u32_e32 v9, vcc, 0, v15, vcc
	global_load_dwordx2 v[24:25], v[4:5], off offset:-4096 nt
	global_load_dwordx2 v[12:13], v[4:5], off nt
	global_load_dwordx2 v[6:7], v[8:9], off offset:-4096 nt
	s_nop 0
	global_load_dwordx2 v[4:5], v[8:9], off nt
	v_add_co_u32_e32 v8, vcc, s0, v14
	s_waitcnt vmcnt(3)
	v_cvt_f32_f16_sdwa v174, v24 dst_sel:DWORD dst_unused:UNUSED_PAD src0_sel:WORD_1
	v_addc_co_u32_e32 v9, vcc, 0, v15, vcc
	v_add_co_u32_e32 v10, vcc, s34, v14
	v_cvt_f32_f16_e32 v175, v25
	s_nop 0
	v_addc_co_u32_e32 v11, vcc, 0, v15, vcc
	global_load_dwordx2 v[16:17], v[8:9], off offset:-4096 nt
	global_load_dwordx2 v[122:123], v[8:9], off nt
	global_load_dwordx2 v[46:47], v[10:11], off offset:-4096 nt
	global_load_dwordx2 v[36:37], v[10:11], off nt
	v_add_co_u32_e32 v8, vcc, s35, v14
	v_cvt_f32_f16_sdwa v177, v25 dst_sel:DWORD dst_unused:UNUSED_PAD src0_sel:WORD_1
	s_nop 0
	v_addc_co_u32_e32 v9, vcc, 0, v15, vcc
	v_add_co_u32_e32 v22, vcc, s30, v14
	v_cvt_f32_f16_e32 v176, v24
	s_nop 0
	v_addc_co_u32_e32 v23, vcc, 0, v15, vcc
	global_load_dwordx2 v[26:27], v[8:9], off offset:-4096 nt
	global_load_dwordx2 v[20:21], v[8:9], off nt
	global_load_dwordx2 v[10:11], v[22:23], off offset:-4096 nt
	s_nop 0
	global_load_dwordx2 v[8:9], v[22:23], off nt
	v_add_co_u32_e32 v22, vcc, s31, v14
	s_waitcnt vmcnt(10)
	v_cvt_f32_f16_sdwa v164, v12 dst_sel:DWORD dst_unused:UNUSED_PAD src0_sel:WORD_1
	v_addc_co_u32_e32 v23, vcc, 0, v15, vcc
	global_load_dwordx2 v[30:31], v[2:3], off offset:-4096 nt
	global_load_dwordx2 v[28:29], v[2:3], off nt
	s_nop 0
	global_load_dwordx2 v[2:3], v[22:23], off nt
	global_load_dwordx2 v[32:33], v[14:15], off nt
	v_mov_b32_e32 v14, v210
	v_cvt_f32_f16_e32 v165, v13
	v_ashrrev_i32_e32 v15, 31, v14
	v_lshrrev_b32_e32 v15, 23, v15
	v_add_u32_e32 v15, v14, v15
	v_ashrrev_i32_e32 v15, 9, v15
	v_mul_i32_i24_e32 v18, 0x200, v15
	v_sub_u32_e32 v18, v14, v18
	v_lshlrev_b32_e32 v14, 14, v15
	v_lshlrev_b32_e32 v15, 1, v18
	v_bfrev_b32_e32 v15, v15
	v_lshrrev_b32_e32 v15, 22, v15
	v_sub_u32_e32 v15, 0x400, v15
	v_bfrev_b32_e32 v15, v15
	v_lshrrev_b32_e32 v15, 18, v15
	v_and_b32_e32 v15, 0x3ff0, v15
	v_cmp_eq_u32_e64 s[0:1], 0, v18
	v_lshl_add_u32 v22, v18, 5, v14
	v_lshl_add_u32 v23, v22, 3, 0
	v_cndmask_b32_e64 v15, v15, 16, s[0:1]
	v_or_b32_e32 v14, v15, v14
	v_ashrrev_i32_e32 v22, 2, v22
	v_ashrrev_i32_e32 v15, 5, v14
	v_add_u32_e32 v211, v23, v22
	v_lshlrev_b32_e32 v14, 3, v14
	v_lshlrev_b32_e32 v15, 3, v15
	v_add3_u32 v212, 0, v14, v15
	ds_read2_b64 v[38:41], v211 offset1:1
	ds_read2_b64 v[42:45], v211 offset0:2 offset1:3
	ds_read2_b64 v[48:51], v212 offset1:1
	ds_read2_b64 v[52:55], v212 offset0:2 offset1:3
	ds_read2_b64 v[56:59], v211 offset0:4 offset1:5
	ds_read2_b64 v[60:63], v211 offset0:6 offset1:7
	ds_read2_b64 v[68:71], v212 offset0:4 offset1:5
	ds_read2_b64 v[72:75], v212 offset0:6 offset1:7
	ds_read2_b64 v[64:67], v211 offset0:8 offset1:9
	ds_read2_b64 v[76:79], v211 offset0:10 offset1:11
	ds_read2_b64 v[80:83], v212 offset0:8 offset1:9
	ds_read2_b64 v[98:101], v212 offset0:10 offset1:11
	ds_read2_b64 v[84:87], v211 offset0:12 offset1:13
	ds_read2_b64 v[88:91], v211 offset0:14 offset1:15
	ds_read2_b64 v[102:105], v212 offset0:12 offset1:13
	ds_read2_b64 v[106:109], v212 offset0:14 offset1:15
	s_waitcnt lgkmcnt(7)
	v_pk_add_f32 v[14:15], v[38:39], v[64:65]
	v_pk_add_f32 v[22:23], v[38:39], v[64:65] neg_lo:[0,1] neg_hi:[0,1]
	v_pk_add_f32 v[38:39], v[40:41], v[66:67] neg_lo:[0,1] neg_hi:[0,1]
	v_pk_add_f32 v[34:35], v[40:41], v[66:67]
	v_pk_mul_f32 v[40:41], v[38:39], s[18:19]
	v_cmp_ne_u32_e32 vcc, 0, v18
	v_pk_fma_f32 v[38:39], v[38:39], s[16:17], v[40:41] op_sel:[0,0,1] op_sel_hi:[1,0,0]
	s_waitcnt lgkmcnt(6)
	v_pk_add_f32 v[40:41], v[42:43], v[76:77]
	v_pk_add_f32 v[42:43], v[42:43], v[76:77] neg_lo:[0,1] neg_hi:[0,1]
	v_bfrev_b32_e32 v18, v18
	v_pk_mul_f32 v[64:65], v[42:43], s[36:37]
	v_lshrrev_b32_e32 v18, 23, v18
	v_pk_fma_f32 v[42:43], v[42:43], s[78:79], v[64:65] op_sel:[0,0,1] op_sel_hi:[1,0,0]
	v_pk_add_f32 v[64:65], v[44:45], v[78:79]
	v_pk_add_f32 v[44:45], v[44:45], v[78:79] neg_lo:[0,1] neg_hi:[0,1]
	s_waitcnt lgkmcnt(3)
	v_pk_add_f32 v[78:79], v[58:59], v[86:87]
	v_pk_mul_f32 v[66:67], v[44:45], s[40:41]
	v_pk_add_f32 v[58:59], v[58:59], v[86:87] neg_lo:[0,1] neg_hi:[0,1]
	v_pk_fma_f32 v[44:45], v[44:45], s[80:81], v[66:67] op_sel:[0,0,1] op_sel_hi:[1,0,0]
	v_pk_add_f32 v[66:67], v[56:57], v[84:85]
	v_pk_add_f32 v[76:77], v[56:57], v[84:85] neg_lo:[0,1] neg_hi:[0,1]
	v_pk_mul_f32 v[84:85], v[58:59], s[40:41]
	v_pk_fma_f32 v[58:59], v[58:59], s[80:81], v[84:85] op_sel:[0,0,1] op_sel_hi:[1,0,0] neg_lo:[1,0,0] neg_hi:[1,0,0]
	s_waitcnt lgkmcnt(2)
	v_pk_add_f32 v[84:85], v[60:61], v[88:89]
	v_pk_add_f32 v[60:61], v[60:61], v[88:89] neg_lo:[0,1] neg_hi:[0,1]
	v_pk_mul_f32 v[86:87], v[60:61], s[36:37]
	v_pk_add_f32 v[56:57], v[22:23], v[76:77] op_sel:[0,1] op_sel_hi:[1,0] neg_hi:[0,1]
	v_pk_fma_f32 v[60:61], v[60:61], s[78:79], v[86:87] op_sel:[0,0,1] op_sel_hi:[1,0,0] neg_lo:[1,0,0] neg_hi:[1,0,0]
	v_pk_add_f32 v[86:87], v[62:63], v[90:91]
	v_pk_add_f32 v[62:63], v[62:63], v[90:91] neg_lo:[0,1] neg_hi:[0,1]
	v_pk_add_f32 v[90:91], v[64:65], v[86:87]
	v_pk_mul_f32 v[88:89], v[62:63], s[18:19]
	v_pk_add_f32 v[64:65], v[64:65], v[86:87] neg_lo:[0,1] neg_hi:[0,1]
	v_pk_fma_f32 v[62:63], v[62:63], s[16:17], v[88:89] op_sel:[0,0,1] op_sel_hi:[1,0,0] neg_lo:[1,0,0] neg_hi:[1,0,0]
	v_pk_add_f32 v[88:89], v[14:15], v[66:67]
	v_pk_add_f32 v[14:15], v[14:15], v[66:67] neg_lo:[0,1] neg_hi:[0,1]
	v_pk_add_f32 v[66:67], v[34:35], v[78:79]
	v_pk_add_f32 v[34:35], v[34:35], v[78:79] neg_lo:[0,1] neg_hi:[0,1]
	v_pk_add_f32 v[22:23], v[22:23], v[76:77] op_sel:[0,1] op_sel_hi:[1,0] neg_lo:[0,1]
	v_pk_mul_f32 v[78:79], v[34:35], s[36:37]
	v_pk_add_f32 v[76:77], v[38:39], v[58:59]
	v_pk_add_f32 v[38:39], v[38:39], v[58:59] neg_lo:[0,1] neg_hi:[0,1]
	v_pk_fma_f32 v[34:35], v[34:35], s[78:79], v[78:79] op_sel:[0,0,1] op_sel_hi:[1,0,0]
	v_pk_add_f32 v[78:79], v[40:41], v[84:85]
	v_pk_add_f32 v[84:85], v[40:41], v[84:85] neg_lo:[0,1] neg_hi:[0,1]
	v_pk_mul_f32 v[86:87], v[64:65], s[36:37]
	v_pk_mul_f32 v[58:59], v[38:39], s[36:37]
	v_pk_fma_f32 v[64:65], v[64:65], s[78:79], v[86:87] op_sel:[0,0,1] op_sel_hi:[1,0,0] neg_lo:[1,0,0] neg_hi:[1,0,0]
	v_pk_fma_f32 v[38:39], v[38:39], s[78:79], v[58:59] op_sel:[0,0,1] op_sel_hi:[1,0,0]
	v_pk_add_f32 v[58:59], v[42:43], v[60:61]
	v_pk_add_f32 v[86:87], v[44:45], v[62:63]
	v_pk_add_f32 v[44:45], v[44:45], v[62:63] neg_lo:[0,1] neg_hi:[0,1]
	v_pk_mul_f32 v[62:63], v[44:45], s[36:37]
	v_pk_add_f32 v[40:41], v[14:15], v[84:85] op_sel:[0,1] op_sel_hi:[1,0] neg_hi:[0,1]
	v_pk_add_f32 v[14:15], v[14:15], v[84:85] op_sel:[0,1] op_sel_hi:[1,0] neg_lo:[0,1]
	v_pk_add_f32 v[84:85], v[34:35], v[64:65]
	v_pk_add_f32 v[64:65], v[34:35], v[64:65] neg_lo:[0,1] neg_hi:[0,1]
	v_pk_add_f32 v[94:95], v[56:57], v[58:59]
	v_pk_add_f32 v[56:57], v[56:57], v[58:59] neg_lo:[0,1] neg_hi:[0,1]
	v_pk_add_f32 v[58:59], v[76:77], v[86:87]
	v_pk_fma_f32 v[44:45], v[44:45], s[78:79], v[62:63] op_sel:[0,0,1] op_sel_hi:[1,0,0] neg_lo:[1,0,0] neg_hi:[1,0,0]
	v_pk_add_f32 v[62:63], v[88:89], v[78:79]
	v_pk_add_f32 v[78:79], v[88:89], v[78:79] neg_lo:[0,1] neg_hi:[0,1]
	v_pk_add_f32 v[88:89], v[66:67], v[90:91]
	v_pk_add_f32 v[110:111], v[76:77], v[86:87] neg_lo:[0,1] neg_hi:[0,1]
	v_pk_add_f32 v[86:87], v[94:95], v[58:59]
	v_pk_add_f32 v[34:35], v[94:95], v[58:59] neg_lo:[0,1] neg_hi:[0,1]
	v_pk_add_f32 v[58:59], v[50:51], v[82:83]
	v_pk_add_f32 v[50:51], v[50:51], v[82:83] neg_lo:[0,1] neg_hi:[0,1]
	v_pk_add_f32 v[60:61], v[42:43], v[60:61] neg_lo:[0,1] neg_hi:[0,1]
	v_pk_add_f32 v[148:149], v[62:63], v[88:89]
	v_pk_add_f32 v[138:139], v[62:63], v[88:89] neg_lo:[0,1] neg_hi:[0,1]
	v_pk_mul_f32 v[62:63], v[50:51], s[18:19]
	v_pk_add_f32 v[90:91], v[66:67], v[90:91] neg_lo:[0,1] neg_hi:[0,1]
	v_pk_fma_f32 v[50:51], v[50:51], s[16:17], v[62:63] op_sel:[0,0,1] op_sel_hi:[1,0,0]
	v_pk_add_f32 v[62:63], v[52:53], v[98:99]
	v_pk_add_f32 v[52:53], v[52:53], v[98:99] neg_lo:[0,1] neg_hi:[0,1]
	v_pk_add_f32 v[112:113], v[22:23], v[60:61] op_sel:[0,1] op_sel_hi:[1,0] neg_hi:[0,1]
	v_pk_add_f32 v[114:115], v[22:23], v[60:61] op_sel:[0,1] op_sel_hi:[1,0] neg_lo:[0,1]
	v_pk_add_f32 v[96:97], v[40:41], v[84:85]
	v_pk_add_f32 v[66:67], v[40:41], v[84:85] neg_lo:[0,1] neg_hi:[0,1]
	v_pk_add_f32 v[60:61], v[14:15], v[64:65] op_sel:[0,1] op_sel_hi:[1,0] neg_hi:[0,1]
	v_pk_add_f32 v[84:85], v[14:15], v[64:65] op_sel:[0,1] op_sel_hi:[1,0] neg_lo:[0,1]
	v_pk_mul_f32 v[64:65], v[52:53], s[36:37]
	v_pk_fma_f32 v[52:53], v[52:53], s[78:79], v[64:65] op_sel:[0,0,1] op_sel_hi:[1,0,0]
	v_pk_add_f32 v[64:65], v[54:55], v[100:101]
	v_pk_add_f32 v[54:55], v[54:55], v[100:101] neg_lo:[0,1] neg_hi:[0,1]
	v_pk_mul_f32 v[76:77], v[54:55], s[40:41]
	v_pk_add_f32 v[92:93], v[78:79], v[90:91] op_sel:[0,1] op_sel_hi:[1,0] neg_hi:[0,1]
	v_pk_fma_f32 v[54:55], v[54:55], s[80:81], v[76:77] op_sel:[0,0,1] op_sel_hi:[1,0,0]
	s_waitcnt lgkmcnt(1)
	v_pk_add_f32 v[76:77], v[68:69], v[102:103]
	v_pk_add_f32 v[68:69], v[68:69], v[102:103] neg_lo:[0,1] neg_hi:[0,1]
	v_pk_add_f32 v[88:89], v[78:79], v[90:91] op_sel:[0,1] op_sel_hi:[1,0] neg_lo:[0,1]
	v_xor_b32_e32 v79, 0x80000000, v68
	v_mov_b32_e32 v78, v69
	v_pk_add_f32 v[68:69], v[70:71], v[104:105]
	v_pk_add_f32 v[70:71], v[70:71], v[104:105] neg_lo:[0,1] neg_hi:[0,1]
	v_pk_add_f32 v[22:23], v[38:39], v[44:45]
	v_pk_add_f32 v[116:117], v[38:39], v[44:45] neg_lo:[0,1] neg_hi:[0,1]
	v_pk_add_f32 v[40:41], v[56:57], v[110:111] op_sel:[0,1] op_sel_hi:[1,0] neg_hi:[0,1]
	v_pk_add_f32 v[44:45], v[56:57], v[110:111] op_sel:[0,1] op_sel_hi:[1,0] neg_lo:[0,1]
	v_pk_add_f32 v[56:57], v[48:49], v[80:81]
	v_pk_add_f32 v[48:49], v[48:49], v[80:81] neg_lo:[0,1] neg_hi:[0,1]
	v_pk_mul_f32 v[80:81], v[70:71], s[40:41]
	v_cvt_f32_u32_e32 v18, v18
	v_pk_fma_f32 v[70:71], v[70:71], s[80:81], v[80:81] op_sel:[0,0,1] op_sel_hi:[1,0,0] neg_lo:[1,0,0] neg_hi:[1,0,0]
	s_waitcnt lgkmcnt(0)
	v_pk_add_f32 v[80:81], v[72:73], v[106:107]
	v_pk_add_f32 v[72:73], v[72:73], v[106:107] neg_lo:[0,1] neg_hi:[0,1]
	v_mul_f32_e32 v18, 0x38000000, v18
	v_pk_mul_f32 v[82:83], v[72:73], s[36:37]
	v_cndmask_b32_e64 v18, v18, v208, s[0:1]
	v_pk_fma_f32 v[72:73], v[72:73], s[78:79], v[82:83] op_sel:[0,0,1] op_sel_hi:[1,0,0] neg_lo:[1,0,0] neg_hi:[1,0,0]
	v_pk_add_f32 v[82:83], v[74:75], v[108:109]
	v_pk_add_f32 v[74:75], v[74:75], v[108:109] neg_lo:[0,1] neg_hi:[0,1]
	s_nop 0
	v_pk_mul_f32 v[90:91], v[74:75], s[18:19]
	v_pk_fma_f32 v[74:75], v[74:75], s[16:17], v[90:91] op_sel:[0,0,1] op_sel_hi:[1,0,0] neg_lo:[1,0,0] neg_hi:[1,0,0]
	v_pk_add_f32 v[90:91], v[56:57], v[76:77]
	v_pk_add_f32 v[56:57], v[56:57], v[76:77] neg_lo:[0,1] neg_hi:[0,1]
	v_pk_add_f32 v[76:77], v[58:59], v[68:69]
	v_pk_add_f32 v[58:59], v[58:59], v[68:69] neg_lo:[0,1] neg_hi:[0,1]
	v_pk_add_f32 v[14:15], v[114:115], v[116:117] op_sel:[0,1] op_sel_hi:[1,0] neg_hi:[0,1]
	v_pk_mul_f32 v[68:69], v[58:59], s[36:37]
	v_pk_add_f32 v[38:39], v[114:115], v[116:117] op_sel:[0,1] op_sel_hi:[1,0] neg_lo:[0,1]
	v_pk_fma_f32 v[58:59], v[58:59], s[78:79], v[68:69] op_sel:[0,0,1] op_sel_hi:[1,0,0]
	v_pk_add_f32 v[68:69], v[62:63], v[80:81]
	v_pk_add_f32 v[80:81], v[62:63], v[80:81] neg_lo:[0,1] neg_hi:[0,1]
	s_waitcnt vmcnt(0)
	v_cvt_f32_f16_e32 v193, v33
	s_nop 0
	s_nop 0
	v_pk_add_f32 v[62:63], v[64:65], v[82:83]
	v_pk_add_f32 v[64:65], v[64:65], v[82:83] neg_lo:[0,1] neg_hi:[0,1]
	v_cvt_f32_f16_sdwa v192, v32 dst_sel:DWORD dst_unused:UNUSED_PAD src0_sel:WORD_1
	v_pk_mul_f32 v[82:83], v[64:65], s[36:37]
	v_cvt_f32_f16_e32 v194, v32
	v_pk_fma_f32 v[64:65], v[64:65], s[78:79], v[82:83] op_sel:[0,0,1] op_sel_hi:[1,0,0] neg_lo:[1,0,0] neg_hi:[1,0,0]
	v_pk_add_f32 v[82:83], v[48:49], v[78:79]
	v_pk_add_f32 v[48:49], v[48:49], v[78:79] neg_lo:[0,1] neg_hi:[0,1]
	v_pk_add_f32 v[78:79], v[50:51], v[70:71]
	v_pk_add_f32 v[50:51], v[50:51], v[70:71] neg_lo:[0,1] neg_hi:[0,1]
	v_cvt_f32_f16_sdwa v195, v33 dst_sel:DWORD dst_unused:UNUSED_PAD src0_sel:WORD_1
	v_pk_mul_f32 v[70:71], v[50:51], s[36:37]
	v_cvt_f32_f16_sdwa v170, v30 dst_sel:DWORD dst_unused:UNUSED_PAD src0_sel:WORD_1
	v_pk_fma_f32 v[50:51], v[50:51], s[78:79], v[70:71] op_sel:[0,0,1] op_sel_hi:[1,0,0]
	v_pk_add_f32 v[70:71], v[52:53], v[72:73]
	v_pk_add_f32 v[72:73], v[52:53], v[72:73] neg_lo:[0,1] neg_hi:[0,1]
	v_cvt_f32_f16_e32 v171, v31
	s_nop 0
	s_nop 0
	v_pk_add_f32 v[52:53], v[54:55], v[74:75]
	v_pk_add_f32 v[54:55], v[54:55], v[74:75] neg_lo:[0,1] neg_hi:[0,1]
	v_cvt_f32_f16_sdwa v185, v31 dst_sel:DWORD dst_unused:UNUSED_PAD src0_sel:WORD_1
	v_pk_mul_f32 v[74:75], v[54:55], s[36:37]
	v_cvt_f32_f16_e32 v184, v30
	v_pk_fma_f32 v[54:55], v[54:55], s[78:79], v[74:75] op_sel:[0,0,1] op_sel_hi:[1,0,0] neg_lo:[1,0,0] neg_hi:[1,0,0]
	v_pk_add_f32 v[74:75], v[90:91], v[68:69]
	v_pk_add_f32 v[68:69], v[90:91], v[68:69] neg_lo:[0,1] neg_hi:[0,1]
	v_pk_add_f32 v[90:91], v[76:77], v[62:63]
	v_pk_add_f32 v[62:63], v[76:77], v[62:63] neg_lo:[0,1] neg_hi:[0,1]
	v_cvt_f32_f16_sdwa v172, v28 dst_sel:DWORD dst_unused:UNUSED_PAD src0_sel:WORD_1
	v_xor_b32_e32 v77, 0x80000000, v62
	v_mov_b32_e32 v76, v63
	v_pk_add_f32 v[62:63], v[56:57], v[80:81] op_sel:[0,1] op_sel_hi:[1,0] neg_hi:[0,1]
	v_pk_add_f32 v[56:57], v[56:57], v[80:81] op_sel:[0,1] op_sel_hi:[1,0] neg_lo:[0,1]
	v_pk_add_f32 v[80:81], v[58:59], v[64:65]
	v_pk_add_f32 v[58:59], v[58:59], v[64:65] neg_lo:[0,1] neg_hi:[0,1]
	v_cvt_f32_f16_e32 v173, v29
	v_xor_b32_e32 v65, 0x80000000, v58
	v_mov_b32_e32 v64, v59
	v_pk_add_f32 v[58:59], v[82:83], v[70:71]
	v_pk_add_f32 v[70:71], v[82:83], v[70:71] neg_lo:[0,1] neg_hi:[0,1]
	v_pk_add_f32 v[82:83], v[78:79], v[52:53]
	v_pk_add_f32 v[52:53], v[78:79], v[52:53] neg_lo:[0,1] neg_hi:[0,1]
	v_pk_add_f32 v[118:119], v[58:59], v[82:83]
	v_pk_add_f32 v[134:135], v[58:59], v[82:83] neg_lo:[0,1] neg_hi:[0,1]
	v_cos_f32_e32 v83, v18
	v_sin_f32_e32 v82, v18
	v_cvt_f32_f16_sdwa v181, v29 dst_sel:DWORD dst_unused:UNUSED_PAD src0_sel:WORD_1
	v_cvt_f32_f16_e32 v180, v28
	v_cvt_f32_f16_sdwa v167, v13 dst_sel:DWORD dst_unused:UNUSED_PAD src0_sel:WORD_1
	v_cvt_f32_f16_e32 v166, v12
	v_cvt_f32_f16_e32 v154, v6
	v_cvt_f32_f16_e32 v155, v7
	v_cvt_f32_f16_sdwa v157, v7 dst_sel:DWORD dst_unused:UNUSED_PAD src0_sel:WORD_1
	v_cvt_f32_f16_sdwa v156, v6 dst_sel:DWORD dst_unused:UNUSED_PAD src0_sel:WORD_1
	v_cvt_f32_f16_sdwa v140, v4 dst_sel:DWORD dst_unused:UNUSED_PAD src0_sel:WORD_1
	v_cvt_f32_f16_e32 v141, v5
	v_cvt_f32_f16_sdwa v143, v5 dst_sel:DWORD dst_unused:UNUSED_PAD src0_sel:WORD_1
	v_cvt_f32_f16_e32 v142, v4
	v_cvt_f32_f16_e32 v124, v16
	v_cvt_f32_f16_e32 v125, v17
	v_cvt_f32_f16_sdwa v127, v17 dst_sel:DWORD dst_unused:UNUSED_PAD src0_sel:WORD_1
	v_cvt_f32_f16_sdwa v126, v16 dst_sel:DWORD dst_unused:UNUSED_PAD src0_sel:WORD_1
	v_cvt_f32_f16_sdwa v114, v122 dst_sel:DWORD dst_unused:UNUSED_PAD src0_sel:WORD_1
	v_cvt_f32_f16_e32 v115, v123
	v_cvt_f32_f16_sdwa v117, v123 dst_sel:DWORD dst_unused:UNUSED_PAD src0_sel:WORD_1
	v_cvt_f32_f16_e32 v116, v122
	v_xor_b32_e32 v79, 0x80000000, v52
	v_mov_b32_e32 v78, v53
	v_pk_add_f32 v[52:53], v[48:49], v[72:73] op_sel:[0,1] op_sel_hi:[1,0] neg_hi:[0,1]
	v_pk_add_f32 v[48:49], v[48:49], v[72:73] op_sel:[0,1] op_sel_hi:[1,0] neg_lo:[0,1]
	v_pk_add_f32 v[72:73], v[50:51], v[54:55]
	v_pk_add_f32 v[50:51], v[50:51], v[54:55] neg_lo:[0,1] neg_hi:[0,1]
	v_pk_fma_f32 v[160:161], v[82:83], 0, v[82:83] op_sel:[0,0,1] op_sel_hi:[1,0,0] neg_lo:[1,0,0] neg_hi:[1,0,0]
	v_xor_b32_e32 v55, 0x80000000, v50
	v_mov_b32_e32 v54, v51
	v_pk_fma_f32 v[198:199], v[82:83], 0, v[82:83] op_sel:[0,0,1] op_sel_hi:[1,0,0]
	v_pk_add_f32 v[42:43], v[112:113], v[22:23]
	v_pk_add_f32 v[22:23], v[112:113], v[22:23] neg_lo:[0,1] neg_hi:[0,1]
	v_pk_add_f32 v[98:99], v[74:75], v[90:91]
	v_pk_add_f32 v[100:101], v[74:75], v[90:91] neg_lo:[0,1] neg_hi:[0,1]
	v_pk_add_f32 v[102:103], v[68:69], v[76:77]
	v_pk_add_f32 v[106:107], v[68:69], v[76:77] neg_lo:[0,1] neg_hi:[0,1]
	v_pk_add_f32 v[104:105], v[62:63], v[80:81]
	v_pk_add_f32 v[108:109], v[62:63], v[80:81] neg_lo:[0,1] neg_hi:[0,1]
	v_pk_add_f32 v[110:111], v[56:57], v[64:65]
	v_pk_add_f32 v[112:113], v[56:57], v[64:65] neg_lo:[0,1] neg_hi:[0,1]
	v_pk_add_f32 v[152:153], v[70:71], v[78:79]
	v_pk_add_f32 v[162:163], v[70:71], v[78:79] neg_lo:[0,1] neg_hi:[0,1]
	v_pk_add_f32 v[178:179], v[52:53], v[72:73]
	v_pk_add_f32 v[182:183], v[52:53], v[72:73] neg_lo:[0,1] neg_hi:[0,1]
	v_pk_add_f32 v[188:189], v[48:49], v[54:55]
	v_pk_add_f32 v[196:197], v[48:49], v[54:55] neg_lo:[0,1] neg_hi:[0,1]
	v_pk_mul_f32 v[186:187], v[82:83], 0 op_sel_hi:[1,0]
	v_mov_b32_e32 v190, v160
	v_mov_b32_e32 v191, v199
	v_mul_f32_e32 v18, 0x3f3504f3, v83
	v_mul_f32_e32 v158, 0xbec3ef15, v83
	v_mul_f32_e32 v132, 0xbf6c835e, v83
	s_and_saveexec_b64 s[0:1], vcc
	s_xor_b64 s[0:1], exec, s[0:1]
	s_cbranch_execz .LBB0_501
	v_pk_add_f32 v[4:5], v[148:149], v[196:197]
	v_pk_add_f32 v[6:7], v[148:149], v[196:197] neg_lo:[0,1] neg_hi:[0,1]
	v_mul_f32_e32 v4, 0.5, v4
	v_mul_f32_e32 v12, 0.5, v7
	v_mov_b32_e32 v7, v5
	v_pk_mul_f32 v[6:7], v[6:7], s[44:45]
	v_pk_mov_b32 v[16:17], v[198:199], v[160:161] op_sel:[1,0]
	v_pk_mul_f32 v[24:25], v[190:191], v[6:7] op_sel:[0,1] op_sel_hi:[1,0]
	v_pk_mul_f32 v[6:7], v[190:191], v[6:7]
	v_pk_add_f32 v[24:25], v[24:25], v[24:25] op_sel:[0,1] op_sel_hi:[0,1]
	v_pk_add_f32 v[28:29], v[4:5], v[24:25]
	v_pk_add_f32 v[4:5], v[4:5], v[24:25] op_sel_hi:[0,1] neg_lo:[0,1] neg_hi:[0,1]
	v_mov_b32_e32 v29, v5
	v_pk_add_f32 v[4:5], v[6:7], v[6:7] op_sel:[0,1] op_sel_hi:[0,1] neg_lo:[0,1] neg_hi:[0,1]
	v_pk_add_f32 v[6:7], v[12:13], v[4:5]
	v_pk_add_f32 v[4:5], v[12:13], v[4:5] op_sel_hi:[0,1] neg_lo:[0,1] neg_hi:[0,1]
	v_mov_b32_e32 v7, v5
	v_pk_mul_f32 v[4:5], v[6:7], v[194:195]
	v_pk_mul_f32 v[6:7], v[6:7], v[192:193]
	v_pk_fma_f32 v[4:5], v[28:29], v[192:193], v[4:5]
	v_pk_fma_f32 v[6:7], v[28:29], v[194:195], v[6:7] neg_lo:[0,0,1] neg_hi:[0,0,1]
	s_mov_b32 s78, s19
	v_pk_add_f32 v[12:13], v[6:7], v[4:5] op_sel:[0,1] op_sel_hi:[1,0] neg_lo:[0,1] neg_hi:[0,1]
	v_pk_add_f32 v[28:29], v[6:7], v[4:5] op_sel:[0,1] op_sel_hi:[1,0]
	v_pk_add_f32 v[4:5], v[4:5], v[6:7] op_sel:[1,0] op_sel_hi:[0,1] neg_lo:[0,1] neg_hi:[0,1]
	v_mov_b32_e32 v13, v29
	v_pk_mul_f32 v[12:13], v[12:13], 0.5 op_sel_hi:[1,0]
	v_mov_b32_e32 v29, v5
	v_mul_f32_e32 v24, v190, v12
	v_pk_fma_f32 v[30:31], v[190:191], v[12:13], v[24:25] op_sel_hi:[1,1,0] neg_lo:[1,0,0] neg_hi:[1,0,0]
	v_mul_f32_e32 v24, v160, v13
	v_pk_fma_f32 v[12:13], v[16:17], v[12:13], v[24:25] op_sel_hi:[1,1,0]
	v_mov_b32_e32 v16, v83
	v_mov_b32_e32 v30, v12
	v_pk_fma_f32 v[4:5], v[28:29], 0.5, v[12:13] op_sel_hi:[1,0,1] neg_lo:[0,0,1] neg_hi:[0,0,1]
	v_pk_fma_f32 v[122:123], v[28:29], 0.5, v[30:31] op_sel_hi:[1,0,1]
	v_pk_fma_f32 v[6:7], v[28:29], 0.5, v[30:31] op_sel_hi:[1,0,1] neg_lo:[1,0,0] neg_hi:[1,0,0]
	v_mov_b32_e32 v5, v123
	v_pk_mul_f32 v[24:25], v[4:5], s[6:7] op_sel_hi:[1,0]
	v_pk_add_f32 v[4:5], v[138:139], v[188:189]
	v_pk_add_f32 v[12:13], v[138:139], v[188:189] neg_lo:[0,1] neg_hi:[0,1]
	v_mov_b32_e32 v17, v82
	v_mul_f32_e32 v6, 0.5, v13
	v_pk_add_f32 v[28:29], v[186:187], v[16:17] neg_lo:[0,1] neg_hi:[0,1]
	v_pk_add_f32 v[30:31], v[186:187], v[16:17]
	v_mov_b32_e32 v13, v5
	v_pk_mov_b32 v[32:33], v[28:29], v[30:31] op_sel:[1,0]
	v_pk_mul_f32 v[12:13], v[12:13], s[44:45]
	v_mul_f32_e32 v4, 0.5, v4
	v_pk_mul_f32 v[48:49], v[32:33], v[12:13] op_sel:[0,1] op_sel_hi:[1,0]
	v_pk_mul_f32 v[12:13], v[32:33], v[12:13]
	v_pk_add_f32 v[48:49], v[48:49], v[48:49] op_sel:[0,1] op_sel_hi:[0,1]
	v_pk_add_f32 v[50:51], v[4:5], v[48:49]
	v_pk_add_f32 v[4:5], v[4:5], v[48:49] op_sel_hi:[0,1] neg_lo:[0,1] neg_hi:[0,1]
	v_mov_b32_e32 v51, v5
	v_pk_add_f32 v[4:5], v[12:13], v[12:13] op_sel:[0,1] op_sel_hi:[0,1] neg_lo:[0,1] neg_hi:[0,1]
	v_pk_add_f32 v[12:13], v[6:7], v[4:5]
	v_pk_add_f32 v[4:5], v[6:7], v[4:5] op_sel_hi:[0,1] neg_lo:[0,1] neg_hi:[0,1]
	v_mov_b32_e32 v13, v5
	v_pk_mul_f32 v[4:5], v[12:13], v[184:185]
	v_pk_mul_f32 v[12:13], v[12:13], v[170:171]
	v_pk_fma_f32 v[4:5], v[50:51], v[170:171], v[4:5]
	v_pk_fma_f32 v[12:13], v[50:51], v[184:185], v[12:13] neg_lo:[0,0,1] neg_hi:[0,0,1]
	v_mov_b32_e32 v31, v29
	v_pk_add_f32 v[48:49], v[12:13], v[4:5] op_sel:[0,1] op_sel_hi:[1,0] neg_lo:[0,1] neg_hi:[0,1]
	v_pk_add_f32 v[50:51], v[12:13], v[4:5] op_sel:[0,1] op_sel_hi:[1,0]
	v_pk_add_f32 v[4:5], v[4:5], v[12:13] op_sel:[1,0] op_sel_hi:[0,1] neg_lo:[0,1] neg_hi:[0,1]
	v_mov_b32_e32 v49, v51
	v_pk_mul_f32 v[48:49], v[48:49], 0.5 op_sel_hi:[1,0]
	v_mov_b32_e32 v51, v5
	v_mul_f32_e32 v6, v29, v48
	v_pk_fma_f32 v[32:33], v[32:33], v[48:49], v[6:7] op_sel_hi:[1,1,0] neg_lo:[1,0,0] neg_hi:[1,0,0]
	v_mul_f32_e32 v6, v29, v49
	v_pk_fma_f32 v[28:29], v[30:31], v[48:49], v[6:7] op_sel_hi:[1,1,0]
	v_pk_mul_f32 v[12:13], v[16:17], s[36:37]
	v_mov_b32_e32 v32, v28
	v_pk_fma_f32 v[4:5], v[50:51], 0.5, v[28:29] op_sel_hi:[1,0,1] neg_lo:[0,0,1] neg_hi:[0,0,1]
	v_pk_fma_f32 v[138:139], v[50:51], 0.5, v[32:33] op_sel_hi:[1,0,1]
	v_pk_add_f32 v[16:17], v[92:93], v[182:183]
	v_mov_b32_e32 v5, v139
	v_pk_add_f32 v[28:29], v[92:93], v[182:183] neg_lo:[0,1] neg_hi:[0,1]
	v_pk_mul_f32 v[30:31], v[4:5], s[6:7] op_sel_hi:[1,0]
	v_pk_fma_f32 v[4:5], v[50:51], 0.5, v[32:33] op_sel_hi:[1,0,1] neg_lo:[1,0,0] neg_hi:[1,0,0]
	v_mul_f32_e32 v6, 0.5, v29
	v_pk_add_f32 v[32:33], v[18:19], v[12:13] op_sel:[0,1] op_sel_hi:[0,1] neg_lo:[0,1] neg_hi:[0,1]
	v_pk_add_f32 v[48:49], v[18:19], v[12:13] op_sel:[0,1] op_sel_hi:[0,1]
	v_mov_b32_e32 v29, v17
	v_mul_f32_e32 v4, 0.5, v16
	v_mov_b32_e32 v50, v32
	v_mov_b32_e32 v51, v49
	v_pk_mul_f32 v[16:17], v[28:29], s[44:45]
	v_pk_mov_b32 v[48:49], v[48:49], v[32:33] op_sel:[1,0]
	v_pk_mul_f32 v[28:29], v[50:51], v[16:17] op_sel:[0,1] op_sel_hi:[1,0]
	v_pk_mul_f32 v[16:17], v[50:51], v[16:17]
	v_pk_add_f32 v[28:29], v[28:29], v[28:29] op_sel:[0,1] op_sel_hi:[0,1]
	v_pk_add_f32 v[52:53], v[4:5], v[28:29]
	v_pk_add_f32 v[28:29], v[4:5], v[28:29] op_sel_hi:[0,1] neg_lo:[0,1] neg_hi:[0,1]
	v_pk_add_f32 v[16:17], v[16:17], v[16:17] op_sel:[0,1] op_sel_hi:[0,1] neg_lo:[0,1] neg_hi:[0,1]
	v_mov_b32_e32 v53, v29
	v_pk_add_f32 v[28:29], v[6:7], v[16:17]
	v_pk_add_f32 v[16:17], v[6:7], v[16:17] op_sel_hi:[0,1] neg_lo:[0,1] neg_hi:[0,1]
	v_mov_b32_e32 v29, v17
	v_pk_mul_f32 v[16:17], v[28:29], v[180:181]
	v_pk_mul_f32 v[28:29], v[28:29], v[172:173]
	v_pk_fma_f32 v[16:17], v[52:53], v[172:173], v[16:17]
	v_pk_fma_f32 v[28:29], v[52:53], v[180:181], v[28:29] neg_lo:[0,0,1] neg_hi:[0,0,1]
	v_sub_f32_e32 v6, v89, v179
	v_pk_add_f32 v[52:53], v[28:29], v[16:17] op_sel:[0,1] op_sel_hi:[1,0] neg_lo:[0,1] neg_hi:[0,1]
	v_pk_add_f32 v[54:55], v[28:29], v[16:17] op_sel:[0,1] op_sel_hi:[1,0]
	v_pk_add_f32 v[16:17], v[16:17], v[28:29] op_sel:[1,0] op_sel_hi:[0,1] neg_lo:[0,1] neg_hi:[0,1]
	v_mov_b32_e32 v53, v55
	v_pk_mul_f32 v[52:53], v[52:53], 0.5 op_sel_hi:[1,0]
	v_mov_b32_e32 v55, v17
	v_mul_f32_e32 v4, v32, v52
	v_pk_fma_f32 v[56:57], v[50:51], v[52:53], v[4:5] op_sel_hi:[1,1,0] neg_lo:[1,0,0] neg_hi:[1,0,0]
	v_mul_f32_e32 v4, v32, v53
	v_pk_fma_f32 v[48:49], v[48:49], v[52:53], v[4:5] op_sel_hi:[1,1,0]
	v_pk_add_f32 v[28:29], v[88:89], v[178:179]
	v_mov_b32_e32 v56, v48
	v_pk_fma_f32 v[16:17], v[54:55], 0.5, v[48:49] op_sel_hi:[1,0,1] neg_lo:[0,0,1] neg_hi:[0,0,1]
	v_mov_b32_e32 v48, v12
	v_mov_b32_e32 v49, v88
	v_pk_mov_b32 v[12:13], v[12:13], v[178:179] op_sel:[1,0]
	v_mul_f32_e32 v18, 0.5, v29
	v_pk_add_f32 v[12:13], v[48:49], v[12:13] neg_lo:[0,1] neg_hi:[0,1]
	v_mul_f32_e32 v4, 0.5, v28
	v_pk_mul_f32 v[48:49], v[12:13], v[18:19]
	v_mov_b32_e32 v13, v32
	v_pk_fma_f32 v[50:51], v[50:51], v[48:49], v[48:49] op_sel:[0,1,0] op_sel_hi:[1,0,1]
	v_mov_b32_e32 v48, v49
	v_mov_b32_e32 v49, v18
	v_pk_mul_f32 v[48:49], v[12:13], v[48:49]
	v_pk_add_f32 v[52:53], v[4:5], v[50:51]
	v_mul_f32_e32 v6, 0.5, v6
	v_fma_f32 v53, v28, 0.5, -v50
	v_pk_add_f32 v[28:29], v[48:49], v[48:49] op_sel:[0,1] op_sel_hi:[0,1] neg_lo:[0,1] neg_hi:[0,1]
	v_pk_add_f32 v[48:49], v[6:7], v[28:29]
	v_pk_add_f32 v[28:29], v[6:7], v[28:29] op_sel_hi:[0,1] neg_lo:[0,1] neg_hi:[0,1]
	v_mov_b32_e32 v49, v29
	v_pk_mul_f32 v[28:29], v[48:49], v[176:177]
	v_pk_mul_f32 v[48:49], v[48:49], v[174:175]
	v_pk_fma_f32 v[28:29], v[52:53], v[174:175], v[28:29]
	v_pk_fma_f32 v[48:49], v[52:53], v[176:177], v[48:49] neg_lo:[0,0,1] neg_hi:[0,0,1]
	v_pk_fma_f32 v[92:93], v[54:55], 0.5, v[56:57] op_sel_hi:[1,0,1]
	v_pk_add_f32 v[50:51], v[48:49], v[28:29] op_sel:[0,1] op_sel_hi:[1,0] neg_lo:[0,1] neg_hi:[0,1]
	v_pk_add_f32 v[52:53], v[48:49], v[28:29] op_sel:[0,1] op_sel_hi:[1,0]
	v_mov_b32_e32 v17, v93
	v_mov_b32_e32 v51, v53
	v_pk_mul_f32 v[50:51], v[50:51], 0.5 op_sel_hi:[1,0]
	v_pk_mul_f32 v[64:65], v[16:17], s[6:7] op_sel_hi:[1,0]
	v_mul_f32_e32 v4, v12, v50
	v_pk_fma_f32 v[16:17], v[54:55], 0.5, v[56:57] op_sel_hi:[1,0,1] neg_lo:[1,0,0] neg_hi:[1,0,0]
	v_pk_fma_f32 v[54:55], v[12:13], v[50:51], v[4:5] op_sel_hi:[1,1,0] neg_lo:[1,0,0] neg_hi:[1,0,0]
	v_mov_b32_e32 v33, v12
	v_mul_f32_e32 v4, v12, v51
	v_pk_fma_f32 v[12:13], v[32:33], v[50:51], v[4:5] op_sel_hi:[1,1,0]
	v_pk_add_f32 v[28:29], v[28:29], v[48:49] op_sel:[1,0] op_sel_hi:[0,1] neg_lo:[0,1] neg_hi:[0,1]
	v_mov_b32_e32 v53, v29
	v_mov_b32_e32 v54, v12
	v_pk_fma_f32 v[12:13], v[52:53], 0.5, v[12:13] op_sel_hi:[1,0,1] neg_lo:[0,0,1] neg_hi:[0,0,1]
	v_pk_fma_f32 v[88:89], v[52:53], 0.5, v[54:55] op_sel_hi:[1,0,1]
	s_mov_b32 s79, s16
	v_mov_b32_e32 v13, v89
	v_pk_mul_f32 v[68:69], v[12:13], s[6:7] op_sel_hi:[1,0]
	v_pk_fma_f32 v[12:13], v[52:53], 0.5, v[54:55] op_sel_hi:[1,0,1] neg_lo:[1,0,0] neg_hi:[1,0,0]
	v_mov_b32_e32 v4, v83
	s_mov_b32 s17, s19
	v_pk_mul_f32 v[48:49], v[82:83], s[78:79] op_sel_hi:[0,1]
	v_pk_add_f32 v[28:29], v[96:97], v[162:163]
	v_pk_add_f32 v[32:33], v[96:97], v[162:163] neg_lo:[0,1] neg_hi:[0,1]
	v_pk_fma_f32 v[52:53], v[4:5], s[16:17], v[48:49] op_sel_hi:[0,1,1] neg_lo:[0,0,1] neg_hi:[0,0,1]
	v_mul_f32_e32 v12, 0.5, v33
	v_pk_fma_f32 v[50:51], v[4:5], s[16:17], v[48:49] op_sel_hi:[0,1,1]
	v_mov_b32_e32 v33, v29
	v_mul_f32_e32 v6, 0.5, v28
	v_mov_b32_e32 v54, v52
	v_mov_b32_e32 v55, v51
	v_pk_mul_f32 v[28:29], v[32:33], s[44:45]
	v_pk_mov_b32 v[56:57], v[50:51], v[52:53] op_sel:[1,0]
	v_pk_mul_f32 v[32:33], v[54:55], v[28:29] op_sel:[0,1] op_sel_hi:[1,0]
	v_pk_mul_f32 v[28:29], v[54:55], v[28:29]
	v_pk_add_f32 v[32:33], v[32:33], v[32:33] op_sel:[0,1] op_sel_hi:[0,1]
	v_pk_add_f32 v[58:59], v[6:7], v[32:33]
	v_pk_add_f32 v[32:33], v[6:7], v[32:33] op_sel_hi:[0,1] neg_lo:[0,1] neg_hi:[0,1]
	v_pk_add_f32 v[28:29], v[28:29], v[28:29] op_sel:[0,1] op_sel_hi:[0,1] neg_lo:[0,1] neg_hi:[0,1]
	v_mov_b32_e32 v59, v33
	v_pk_add_f32 v[32:33], v[12:13], v[28:29]
	v_pk_add_f32 v[28:29], v[12:13], v[28:29] op_sel_hi:[0,1] neg_lo:[0,1] neg_hi:[0,1]
	v_mov_b32_e32 v33, v29
	v_pk_mul_f32 v[28:29], v[32:33], v[166:167]
	v_pk_mul_f32 v[32:33], v[32:33], v[164:165]
	v_pk_fma_f32 v[28:29], v[58:59], v[164:165], v[28:29]
	v_pk_fma_f32 v[32:33], v[58:59], v[166:167], v[32:33] neg_lo:[0,0,1] neg_hi:[0,0,1]
	v_mov_b32_e32 v159, v66
	v_pk_add_f32 v[58:59], v[32:33], v[28:29] op_sel:[0,1] op_sel_hi:[1,0] neg_lo:[0,1] neg_hi:[0,1]
	v_pk_add_f32 v[70:71], v[32:33], v[28:29] op_sel:[0,1] op_sel_hi:[1,0]
	v_pk_add_f32 v[28:29], v[28:29], v[32:33] op_sel:[1,0] op_sel_hi:[0,1] neg_lo:[0,1] neg_hi:[0,1]
	v_mov_b32_e32 v59, v71
	v_pk_mul_f32 v[58:59], v[58:59], 0.5 op_sel_hi:[1,0]
	v_mov_b32_e32 v71, v29
	v_mul_f32_e32 v6, v52, v58
	v_pk_fma_f32 v[72:73], v[54:55], v[58:59], v[6:7] op_sel_hi:[1,1,0] neg_lo:[1,0,0] neg_hi:[1,0,0]
	v_mul_f32_e32 v6, v52, v59
	v_pk_fma_f32 v[56:57], v[56:57], v[58:59], v[6:7] op_sel_hi:[1,1,0]
	v_sub_f32_e32 v12, v67, v153
	v_mov_b32_e32 v72, v56
	v_pk_fma_f32 v[28:29], v[70:71], 0.5, v[56:57] op_sel_hi:[1,0,1] neg_lo:[0,0,1] neg_hi:[0,0,1]
	v_pk_fma_f32 v[96:97], v[70:71], 0.5, v[72:73] op_sel_hi:[1,0,1]
	v_pk_mov_b32 v[56:57], v[48:49], v[152:153] op_sel:[1,0]
	v_mov_b32_e32 v29, v97
	v_pk_mul_f32 v[62:63], v[28:29], s[6:7] op_sel_hi:[1,0]
	v_pk_add_f32 v[28:29], v[66:67], v[152:153]
	v_pk_add_f32 v[56:57], v[158:159], v[56:57] neg_lo:[0,1] neg_hi:[0,1]
	v_mul_f32_e32 v18, 0.5, v29
	v_pk_mul_f32 v[58:59], v[56:57], v[18:19]
	v_mul_f32_e32 v6, 0.5, v28
	v_pk_fma_f32 v[54:55], v[54:55], v[58:59], v[58:59] op_sel:[0,1,0] op_sel_hi:[1,0,1]
	v_mov_b32_e32 v66, v56
	v_mov_b32_e32 v67, v52
	v_mov_b32_e32 v58, v59
	v_mov_b32_e32 v59, v18
	v_pk_mul_f32 v[58:59], v[66:67], v[58:59]
	v_pk_add_f32 v[66:67], v[6:7], v[54:55]
	v_mul_f32_e32 v12, 0.5, v12
	v_fma_f32 v67, v28, 0.5, -v54
	v_pk_add_f32 v[28:29], v[58:59], v[58:59] op_sel:[0,1] op_sel_hi:[0,1] neg_lo:[0,1] neg_hi:[0,1]
	v_pk_add_f32 v[54:55], v[12:13], v[28:29]
	v_pk_add_f32 v[28:29], v[12:13], v[28:29] op_sel_hi:[0,1] neg_lo:[0,1] neg_hi:[0,1]
	v_mov_b32_e32 v55, v29
	v_pk_mul_f32 v[28:29], v[54:55], v[156:157]
	v_pk_mul_f32 v[54:55], v[54:55], v[154:155]
	v_pk_fma_f32 v[32:33], v[70:71], 0.5, v[72:73] op_sel_hi:[1,0,1] neg_lo:[1,0,0] neg_hi:[1,0,0]
	v_pk_fma_f32 v[58:59], v[66:67], v[154:155], v[28:29] neg_lo:[0,0,1] neg_hi:[0,0,1]
	v_pk_fma_f32 v[28:29], v[66:67], v[154:155], v[28:29]
	v_pk_fma_f32 v[70:71], v[66:67], v[156:157], v[54:55]
	v_pk_fma_f32 v[54:55], v[66:67], v[156:157], v[54:55] neg_lo:[0,0,1] neg_hi:[0,0,1]
	v_pk_add_f32 v[72:73], v[58:59], v[28:29] op_sel:[0,1] op_sel_hi:[1,0]
	v_pk_add_f32 v[66:67], v[70:71], v[54:55] op_sel_hi:[0,1] neg_lo:[0,1] neg_hi:[0,1]
	v_pk_add_f32 v[28:29], v[58:59], v[28:29] op_sel_hi:[0,1] neg_lo:[0,1] neg_hi:[0,1]
	v_pk_add_f32 v[54:55], v[70:71], v[54:55] op_sel:[0,1] op_sel_hi:[1,0]
	v_mov_b32_e32 v73, v67
	v_mov_b32_e32 v55, v29
	v_pk_mul_f32 v[28:29], v[54:55], 0.5 op_sel_hi:[1,0]
	v_mov_b32_e32 v133, v84
	v_pk_mul_f32 v[54:55], v[52:53], v[28:29] op_sel:[0,1] op_sel_hi:[0,0]
	v_pk_fma_f32 v[58:59], v[56:57], v[28:29], v[54:55] op_sel_hi:[0,1,1]
	v_pk_fma_f32 v[28:29], v[56:57], v[28:29], v[54:55] op_sel_hi:[0,1,1] neg_lo:[0,0,1] neg_hi:[0,0,1]
	v_mov_b32_e32 v28, v58
	v_pk_fma_f32 v[54:55], v[72:73], 0.5, v[58:59] op_sel_hi:[1,0,1] neg_lo:[0,0,1] neg_hi:[0,0,1]
	v_pk_fma_f32 v[66:67], v[72:73], 0.5, v[28:29] op_sel_hi:[1,0,1]
	v_pk_add_f32 v[56:57], v[60:61], v[134:135] neg_lo:[0,1] neg_hi:[0,1]
	v_mov_b32_e32 v55, v67
	v_pk_mul_f32 v[90:91], v[54:55], s[6:7] op_sel_hi:[1,0]
	v_pk_add_f32 v[54:55], v[134:135], v[60:61]
	v_mul_f32_e32 v12, 0.5, v57
	v_mov_b32_e32 v57, v55
	v_mul_f32_e32 v6, 0.5, v54
	v_pk_mov_b32 v[58:59], v[52:53], v[50:51] op_sel:[1,0]
	v_pk_mul_f32 v[54:55], v[56:57], s[44:45]
	v_pk_fma_f32 v[28:29], v[72:73], 0.5, v[28:29] op_sel_hi:[1,0,1] neg_lo:[1,0,0] neg_hi:[1,0,0]
	v_pk_mul_f32 v[56:57], v[58:59], v[54:55] op_sel:[0,1] op_sel_hi:[1,0]
	v_pk_mul_f32 v[54:55], v[58:59], v[54:55]
	v_pk_add_f32 v[56:57], v[56:57], v[56:57] op_sel:[0,1] op_sel_hi:[0,1]
	v_pk_add_f32 v[60:61], v[6:7], v[56:57]
	v_pk_add_f32 v[56:57], v[6:7], v[56:57] op_sel_hi:[0,1] neg_lo:[0,1] neg_hi:[0,1]
	v_pk_add_f32 v[54:55], v[54:55], v[54:55] op_sel:[0,1] op_sel_hi:[0,1] neg_lo:[0,1] neg_hi:[0,1]
	v_mov_b32_e32 v61, v57
	v_pk_add_f32 v[56:57], v[12:13], v[54:55]
	v_pk_add_f32 v[54:55], v[12:13], v[54:55] op_sel_hi:[0,1] neg_lo:[0,1] neg_hi:[0,1]
	v_mov_b32_e32 v57, v55
	v_pk_mul_f32 v[54:55], v[56:57], v[142:143]
	v_pk_mul_f32 v[56:57], v[56:57], v[140:141]
	v_pk_fma_f32 v[54:55], v[60:61], v[140:141], v[54:55]
	v_pk_fma_f32 v[56:57], v[60:61], v[142:143], v[56:57] neg_lo:[0,0,1] neg_hi:[0,0,1]
	v_mov_b32_e32 v51, v53
	v_pk_add_f32 v[60:61], v[56:57], v[54:55] op_sel:[0,1] op_sel_hi:[1,0] neg_lo:[0,1] neg_hi:[0,1]
	v_pk_add_f32 v[70:71], v[56:57], v[54:55] op_sel:[0,1] op_sel_hi:[1,0]
	v_pk_add_f32 v[54:55], v[54:55], v[56:57] op_sel:[1,0] op_sel_hi:[0,1] neg_lo:[0,1] neg_hi:[0,1]
	v_mov_b32_e32 v61, v71
	v_pk_mul_f32 v[60:61], v[60:61], 0.5 op_sel_hi:[1,0]
	v_mov_b32_e32 v71, v55
	v_mul_f32_e32 v6, v53, v60
	v_pk_fma_f32 v[72:73], v[58:59], v[60:61], v[6:7] op_sel_hi:[1,1,0] neg_lo:[1,0,0] neg_hi:[1,0,0]
	v_mul_f32_e32 v6, v53, v61
	v_pk_fma_f32 v[50:51], v[50:51], v[60:61], v[6:7] op_sel_hi:[1,1,0]
	v_pk_add_f32 v[54:55], v[118:119], v[84:85]
	v_mov_b32_e32 v72, v50
	v_mov_b32_e32 v49, v118
	v_pk_fma_f32 v[50:51], v[70:71], 0.5, v[50:51] op_sel_hi:[1,0,1] neg_lo:[0,0,1] neg_hi:[0,0,1]
	v_pk_fma_f32 v[60:61], v[70:71], 0.5, v[72:73] op_sel_hi:[1,0,1]
	v_mul_f32_e32 v18, 0.5, v55
	v_pk_add_f32 v[48:49], v[132:133], v[48:49] neg_lo:[0,1] neg_hi:[0,1]
	v_mov_b32_e32 v51, v61
	v_pk_mul_f32 v[56:57], v[48:49], v[18:19]
	v_pk_mul_f32 v[94:95], v[50:51], s[6:7] op_sel_hi:[1,0]
	v_pk_fma_f32 v[50:51], v[70:71], 0.5, v[72:73] op_sel_hi:[1,0,1] neg_lo:[1,0,0] neg_hi:[1,0,0]
	v_mul_f32_e32 v6, 0.5, v54
	v_pk_fma_f32 v[58:59], v[58:59], v[56:57], v[56:57] op_sel:[0,1,0] op_sel_hi:[1,0,1]
	v_mov_b32_e32 v70, v48
	v_mov_b32_e32 v71, v53
	v_mov_b32_e32 v56, v57
	v_mov_b32_e32 v57, v18
	v_sub_f32_e32 v12, v85, v119
	v_pk_mul_f32 v[56:57], v[70:71], v[56:57]
	v_pk_add_f32 v[70:71], v[6:7], v[58:59]
	v_mul_f32_e32 v12, 0.5, v12
	v_fma_f32 v71, v54, 0.5, -v58
	v_pk_add_f32 v[54:55], v[56:57], v[56:57] op_sel:[0,1] op_sel_hi:[0,1] neg_lo:[0,1] neg_hi:[0,1]
	v_pk_add_f32 v[56:57], v[12:13], v[54:55]
	v_pk_add_f32 v[54:55], v[12:13], v[54:55] op_sel_hi:[0,1] neg_lo:[0,1] neg_hi:[0,1]
	v_mov_b32_e32 v57, v55
	v_pk_mul_f32 v[54:55], v[56:57], v[126:127]
	v_pk_mul_f32 v[56:57], v[56:57], v[124:125]
	v_pk_fma_f32 v[58:59], v[70:71], v[124:125], v[54:55] neg_lo:[0,0,1] neg_hi:[0,0,1]
	v_pk_fma_f32 v[54:55], v[70:71], v[124:125], v[54:55]
	v_pk_fma_f32 v[72:73], v[70:71], v[126:127], v[56:57]
	v_pk_fma_f32 v[56:57], v[70:71], v[126:127], v[56:57] neg_lo:[0,0,1] neg_hi:[0,0,1]
	v_pk_add_f32 v[70:71], v[58:59], v[54:55] op_sel:[0,1] op_sel_hi:[1,0]
	v_pk_add_f32 v[74:75], v[72:73], v[56:57] op_sel_hi:[0,1] neg_lo:[0,1] neg_hi:[0,1]
	v_pk_add_f32 v[54:55], v[58:59], v[54:55] op_sel_hi:[0,1] neg_lo:[0,1] neg_hi:[0,1]
	v_pk_add_f32 v[56:57], v[72:73], v[56:57] op_sel:[0,1] op_sel_hi:[1,0]
	v_mov_b32_e32 v71, v75
	v_mov_b32_e32 v57, v55
	v_pk_mul_f32 v[54:55], v[56:57], 0.5 op_sel_hi:[1,0]
	s_mov_b32 s78, s11
	v_pk_mul_f32 v[52:53], v[52:53], v[54:55] op_sel:[1,1] op_sel_hi:[1,0]
	s_mov_b32 s79, s8
	v_pk_fma_f32 v[56:57], v[48:49], v[54:55], v[52:53] op_sel_hi:[0,1,1]
	v_pk_fma_f32 v[48:49], v[48:49], v[54:55], v[52:53] op_sel_hi:[0,1,1] neg_lo:[0,0,1] neg_hi:[0,0,1]
	v_mov_b32_e32 v48, v56
	v_pk_fma_f32 v[52:53], v[70:71], 0.5, v[56:57] op_sel_hi:[1,0,1] neg_lo:[0,0,1] neg_hi:[0,0,1]
	v_pk_fma_f32 v[84:85], v[70:71], 0.5, v[48:49] op_sel_hi:[1,0,1]
	s_mov_b32 s9, s11
	v_mov_b32_e32 v53, v85
	v_pk_mul_f32 v[80:81], v[52:53], s[6:7] op_sel_hi:[1,0]
	v_pk_mul_f32 v[118:119], v[82:83], s[78:79] op_sel_hi:[0,1]
	v_pk_add_f32 v[52:53], v[86:87], v[112:113]
	v_pk_add_f32 v[54:55], v[86:87], v[112:113] neg_lo:[0,1] neg_hi:[0,1]
	v_pk_fma_f32 v[58:59], v[4:5], s[8:9], v[118:119] op_sel_hi:[0,1,1] neg_lo:[0,0,1] neg_hi:[0,0,1]
	v_mul_f32_e32 v12, 0.5, v55
	v_pk_fma_f32 v[72:73], v[4:5], s[8:9], v[118:119] op_sel_hi:[0,1,1]
	v_mov_b32_e32 v55, v53
	v_mul_f32_e32 v6, 0.5, v52
	v_mov_b32_e32 v56, v58
	v_mov_b32_e32 v57, v73
	v_pk_mul_f32 v[52:53], v[54:55], s[44:45]
	v_pk_fma_f32 v[48:49], v[70:71], 0.5, v[48:49] op_sel_hi:[1,0,1] neg_lo:[1,0,0] neg_hi:[1,0,0]
	v_pk_mul_f32 v[54:55], v[56:57], v[52:53] op_sel:[0,1] op_sel_hi:[1,0]
	v_pk_mul_f32 v[52:53], v[56:57], v[52:53]
	v_pk_add_f32 v[54:55], v[54:55], v[54:55] op_sel:[0,1] op_sel_hi:[0,1]
	v_pk_add_f32 v[74:75], v[6:7], v[54:55]
	v_pk_add_f32 v[54:55], v[6:7], v[54:55] op_sel_hi:[0,1] neg_lo:[0,1] neg_hi:[0,1]
	v_pk_add_f32 v[52:53], v[52:53], v[52:53] op_sel:[0,1] op_sel_hi:[0,1] neg_lo:[0,1] neg_hi:[0,1]
	v_mov_b32_e32 v75, v55
	v_pk_add_f32 v[54:55], v[12:13], v[52:53]
	v_pk_add_f32 v[52:53], v[12:13], v[52:53] op_sel_hi:[0,1] neg_lo:[0,1] neg_hi:[0,1]
	v_mov_b32_e32 v55, v53
	v_pk_mul_f32 v[52:53], v[54:55], v[116:117]
	v_pk_mul_f32 v[54:55], v[54:55], v[114:115]
	v_pk_fma_f32 v[52:53], v[74:75], v[114:115], v[52:53]
	v_pk_fma_f32 v[54:55], v[74:75], v[116:117], v[54:55] neg_lo:[0,0,1] neg_hi:[0,0,1]
	v_pk_mov_b32 v[70:71], v[72:73], v[58:59] op_sel:[1,0]
	v_pk_add_f32 v[74:75], v[54:55], v[52:53] op_sel:[0,1] op_sel_hi:[1,0] neg_lo:[0,1] neg_hi:[0,1]
	v_pk_add_f32 v[76:77], v[54:55], v[52:53] op_sel:[0,1] op_sel_hi:[1,0]
	v_pk_add_f32 v[52:53], v[52:53], v[54:55] op_sel:[1,0] op_sel_hi:[0,1] neg_lo:[0,1] neg_hi:[0,1]
	v_mov_b32_e32 v75, v77
	v_pk_mul_f32 v[74:75], v[74:75], 0.5 op_sel_hi:[1,0]
	v_mov_b32_e32 v77, v53
	v_mul_f32_e32 v6, v58, v74
	v_pk_fma_f32 v[112:113], v[56:57], v[74:75], v[6:7] op_sel_hi:[1,1,0] neg_lo:[1,0,0] neg_hi:[1,0,0]
	v_mul_f32_e32 v6, v58, v75
	v_pk_fma_f32 v[70:71], v[70:71], v[74:75], v[6:7] op_sel_hi:[1,1,0]
	v_pk_add_f32 v[54:55], v[34:35], v[110:111]
	v_mov_b32_e32 v112, v70
	v_pk_fma_f32 v[52:53], v[76:77], 0.5, v[70:71] op_sel_hi:[1,0,1] neg_lo:[0,0,1] neg_hi:[0,0,1]
	v_pk_fma_f32 v[86:87], v[76:77], 0.5, v[112:113] op_sel_hi:[1,0,1]
	v_sub_f32_e32 v12, v35, v111
	v_mov_b32_e32 v53, v87
	v_pk_mul_f32 v[78:79], v[52:53], s[6:7] op_sel_hi:[1,0]
	v_mul_f32_e32 v52, 0xbe47c5c2, v83
	v_mov_b32_e32 v53, v34
	v_pk_mov_b32 v[34:35], v[118:119], v[110:111] op_sel:[1,0]
	v_mul_f32_e32 v18, 0.5, v55
	v_pk_add_f32 v[34:35], v[52:53], v[34:35] neg_lo:[0,1] neg_hi:[0,1]
	v_mov_b32_e32 v71, v58
	v_pk_mul_f32 v[52:53], v[34:35], v[18:19]
	v_mov_b32_e32 v70, v34
	v_pk_fma_f32 v[56:57], v[56:57], v[52:53], v[52:53] op_sel:[0,1,0] op_sel_hi:[1,0,1]
	v_mov_b32_e32 v52, v53
	v_mov_b32_e32 v53, v18
	v_mul_f32_e32 v6, 0.5, v54
	v_pk_mul_f32 v[52:53], v[70:71], v[52:53]
	v_cvt_f32_f16_e32 v70, v46
	v_cvt_f32_f16_e32 v71, v47
	v_cvt_f32_f16_sdwa v47, v47 dst_sel:DWORD dst_unused:UNUSED_PAD src0_sel:WORD_1
	v_cvt_f32_f16_sdwa v46, v46 dst_sel:DWORD dst_unused:UNUSED_PAD src0_sel:WORD_1
	v_pk_fma_f32 v[74:75], v[76:77], 0.5, v[112:113] op_sel_hi:[1,0,1] neg_lo:[1,0,0] neg_hi:[1,0,0]
	v_mul_f32_e32 v12, 0.5, v12
	v_pk_add_f32 v[76:77], v[6:7], v[56:57]
	v_pk_add_f32 v[52:53], v[52:53], v[52:53] op_sel:[0,1] op_sel_hi:[0,1] neg_lo:[0,1] neg_hi:[0,1]
	v_fma_f32 v77, v54, 0.5, -v56
	v_pk_add_f32 v[54:55], v[12:13], v[52:53]
	v_pk_add_f32 v[52:53], v[12:13], v[52:53] op_sel_hi:[0,1] neg_lo:[0,1] neg_hi:[0,1]
	v_mov_b32_e32 v55, v53
	v_pk_mul_f32 v[52:53], v[54:55], v[46:47]
	v_pk_mul_f32 v[54:55], v[54:55], v[70:71]
	v_pk_fma_f32 v[56:57], v[76:77], v[70:71], v[52:53] neg_lo:[0,0,1] neg_hi:[0,0,1]
	v_pk_fma_f32 v[52:53], v[76:77], v[70:71], v[52:53]
	v_pk_fma_f32 v[70:71], v[76:77], v[46:47], v[54:55]
	v_pk_fma_f32 v[46:47], v[76:77], v[46:47], v[54:55] neg_lo:[0,0,1] neg_hi:[0,0,1]
	v_pk_add_f32 v[54:55], v[56:57], v[52:53] op_sel:[0,1] op_sel_hi:[1,0]
	v_pk_add_f32 v[76:77], v[70:71], v[46:47] op_sel_hi:[0,1] neg_lo:[0,1] neg_hi:[0,1]
	v_pk_add_f32 v[52:53], v[56:57], v[52:53] op_sel_hi:[0,1] neg_lo:[0,1] neg_hi:[0,1]
	v_pk_add_f32 v[46:47], v[70:71], v[46:47] op_sel:[0,1] op_sel_hi:[1,0]
	v_mov_b32_e32 v55, v77
	v_mov_b32_e32 v47, v53
	v_pk_mul_f32 v[46:47], v[46:47], 0.5 op_sel_hi:[1,0]
	s_mov_b32 s25, s27
	v_pk_mul_f32 v[52:53], v[58:59], v[46:47] op_sel:[0,1] op_sel_hi:[0,0]
	v_pk_fma_f32 v[56:57], v[34:35], v[46:47], v[52:53] op_sel_hi:[0,1,1]
	v_pk_fma_f32 v[46:47], v[34:35], v[46:47], v[52:53] op_sel_hi:[0,1,1] neg_lo:[0,0,1] neg_hi:[0,0,1]
	v_mov_b32_e32 v46, v56
	v_pk_fma_f32 v[52:53], v[54:55], 0.5, v[56:57] op_sel_hi:[1,0,1] neg_lo:[0,0,1] neg_hi:[0,0,1]
	v_pk_fma_f32 v[34:35], v[54:55], 0.5, v[46:47] op_sel_hi:[1,0,1]
	s_mov_b32 s78, s27
	v_mov_b32_e32 v53, v35
	v_pk_mul_f32 v[136:137], v[52:53], s[6:7] op_sel_hi:[1,0]
	v_pk_fma_f32 v[52:53], v[54:55], 0.5, v[46:47] op_sel_hi:[1,0,1] neg_lo:[1,0,0] neg_hi:[1,0,0]
	s_mov_b32 s79, s24
	v_pk_mul_f32 v[46:47], v[82:83], s[24:25] op_sel_hi:[0,1]
	v_pk_add_f32 v[54:55], v[108:109], v[40:41]
	v_pk_add_f32 v[40:41], v[40:41], v[108:109] neg_lo:[0,1] neg_hi:[0,1]
	v_pk_fma_f32 v[108:109], v[4:5], s[78:79], v[46:47] op_sel_hi:[0,1,1] neg_lo:[0,0,1] neg_hi:[0,0,1]
	v_mul_f32_e32 v12, 0.5, v41
	v_pk_fma_f32 v[70:71], v[4:5], s[78:79], v[46:47] op_sel_hi:[0,1,1]
	v_mov_b32_e32 v41, v55
	v_mov_b32_e32 v56, v108
	v_mov_b32_e32 v57, v71
	v_pk_mul_f32 v[40:41], v[40:41], s[44:45]
	v_mul_f32_e32 v6, 0.5, v54
	v_pk_mul_f32 v[54:55], v[56:57], v[40:41] op_sel:[0,1] op_sel_hi:[1,0]
	v_cvt_f32_f16_sdwa v76, v36 dst_sel:DWORD dst_unused:UNUSED_PAD src0_sel:WORD_1
	v_cvt_f32_f16_e32 v77, v37
	v_cvt_f32_f16_sdwa v37, v37 dst_sel:DWORD dst_unused:UNUSED_PAD src0_sel:WORD_1
	v_cvt_f32_f16_e32 v36, v36
	v_pk_mul_f32 v[40:41], v[56:57], v[40:41]
	v_pk_add_f32 v[54:55], v[54:55], v[54:55] op_sel:[0,1] op_sel_hi:[0,1]
	v_pk_add_f32 v[112:113], v[6:7], v[54:55]
	v_pk_add_f32 v[54:55], v[6:7], v[54:55] op_sel_hi:[0,1] neg_lo:[0,1] neg_hi:[0,1]
	v_pk_add_f32 v[40:41], v[40:41], v[40:41] op_sel:[0,1] op_sel_hi:[0,1] neg_lo:[0,1] neg_hi:[0,1]
	v_mov_b32_e32 v113, v55
	v_pk_add_f32 v[54:55], v[12:13], v[40:41]
	v_pk_add_f32 v[40:41], v[12:13], v[40:41] op_sel_hi:[0,1] neg_lo:[0,1] neg_hi:[0,1]
	v_mov_b32_e32 v55, v41
	v_pk_mul_f32 v[40:41], v[54:55], v[36:37]
	v_pk_mul_f32 v[54:55], v[54:55], v[76:77]
	v_pk_fma_f32 v[40:41], v[112:113], v[76:77], v[40:41]
	v_pk_fma_f32 v[36:37], v[112:113], v[36:37], v[54:55] neg_lo:[0,0,1] neg_hi:[0,0,1]
	v_pk_mov_b32 v[110:111], v[70:71], v[108:109] op_sel:[1,0]
	v_pk_add_f32 v[54:55], v[36:37], v[40:41] op_sel:[0,1] op_sel_hi:[1,0] neg_lo:[0,1] neg_hi:[0,1]
	v_pk_add_f32 v[76:77], v[36:37], v[40:41] op_sel:[0,1] op_sel_hi:[1,0]
	v_pk_add_f32 v[36:37], v[40:41], v[36:37] op_sel:[1,0] op_sel_hi:[0,1] neg_lo:[0,1] neg_hi:[0,1]
	v_mov_b32_e32 v55, v77
	v_pk_mul_f32 v[54:55], v[54:55], 0.5 op_sel_hi:[1,0]
	v_mov_b32_e32 v77, v37
	v_mul_f32_e32 v4, v108, v54
	v_pk_fma_f32 v[112:113], v[56:57], v[54:55], v[4:5] op_sel_hi:[1,1,0] neg_lo:[1,0,0] neg_hi:[1,0,0]
	v_mul_f32_e32 v4, v108, v55
	v_pk_fma_f32 v[54:55], v[110:111], v[54:55], v[4:5] op_sel_hi:[1,1,0]
	v_sub_f32_e32 v6, v45, v105
	v_mov_b32_e32 v112, v54
	v_pk_fma_f32 v[40:41], v[76:77], 0.5, v[54:55] op_sel_hi:[1,0,1] neg_lo:[0,0,1] neg_hi:[0,0,1]
	v_pk_fma_f32 v[36:37], v[76:77], 0.5, v[112:113] op_sel_hi:[1,0,1]
	v_pk_add_f32 v[54:55], v[104:105], v[44:45]
	v_mov_b32_e32 v41, v37
	v_pk_mul_f32 v[130:131], v[40:41], s[6:7] op_sel_hi:[1,0]
	v_mul_f32_e32 v40, 0xbf54db31, v83
	v_mov_b32_e32 v41, v44
	v_pk_mov_b32 v[44:45], v[46:47], v[104:105] op_sel:[1,0]
	v_mul_f32_e32 v18, 0.5, v55
	v_pk_add_f32 v[40:41], v[40:41], v[44:45] neg_lo:[0,1] neg_hi:[0,1]
	v_mov_b32_e32 v105, v108
	v_pk_mul_f32 v[44:45], v[40:41], v[18:19]
	v_mov_b32_e32 v104, v40
	v_pk_fma_f32 v[56:57], v[56:57], v[44:45], v[44:45] op_sel:[0,1,0] op_sel_hi:[1,0,1]
	v_mov_b32_e32 v44, v45
	v_mov_b32_e32 v45, v18
	v_mul_f32_e32 v4, 0.5, v54
	v_pk_mul_f32 v[44:45], v[104:105], v[44:45]
	v_cvt_f32_f16_e32 v104, v26
	v_cvt_f32_f16_e32 v105, v27
	v_cvt_f32_f16_sdwa v27, v27 dst_sel:DWORD dst_unused:UNUSED_PAD src0_sel:WORD_1
	v_cvt_f32_f16_sdwa v26, v26 dst_sel:DWORD dst_unused:UNUSED_PAD src0_sel:WORD_1
	v_mul_f32_e32 v6, 0.5, v6
	v_pk_add_f32 v[110:111], v[4:5], v[56:57]
	v_pk_add_f32 v[44:45], v[44:45], v[44:45] op_sel:[0,1] op_sel_hi:[0,1] neg_lo:[0,1] neg_hi:[0,1]
	v_fma_f32 v111, v54, 0.5, -v56
	v_pk_add_f32 v[54:55], v[6:7], v[44:45]
	v_pk_add_f32 v[44:45], v[6:7], v[44:45] op_sel_hi:[0,1] neg_lo:[0,1] neg_hi:[0,1]
	v_mov_b32_e32 v55, v45
	v_pk_mul_f32 v[44:45], v[54:55], v[26:27]
	v_pk_mul_f32 v[54:55], v[54:55], v[104:105]
	v_pk_fma_f32 v[56:57], v[110:111], v[104:105], v[44:45] neg_lo:[0,0,1] neg_hi:[0,0,1]
	v_pk_fma_f32 v[44:45], v[110:111], v[104:105], v[44:45]
	v_pk_fma_f32 v[104:105], v[110:111], v[26:27], v[54:55]
	v_pk_fma_f32 v[26:27], v[110:111], v[26:27], v[54:55] neg_lo:[0,0,1] neg_hi:[0,0,1]
	v_pk_add_f32 v[54:55], v[56:57], v[44:45] op_sel:[0,1] op_sel_hi:[1,0]
	v_pk_add_f32 v[110:111], v[104:105], v[26:27] op_sel_hi:[0,1] neg_lo:[0,1] neg_hi:[0,1]
	v_pk_add_f32 v[44:45], v[56:57], v[44:45] op_sel_hi:[0,1] neg_lo:[0,1] neg_hi:[0,1]
	v_pk_add_f32 v[26:27], v[104:105], v[26:27] op_sel:[0,1] op_sel_hi:[1,0]
	v_mov_b32_e32 v55, v111
	v_mov_b32_e32 v27, v45
	v_pk_mul_f32 v[26:27], v[26:27], 0.5 op_sel_hi:[1,0]
	v_mov_b32_e32 v47, v102
	v_pk_mul_f32 v[44:45], v[108:109], v[26:27] op_sel:[0,1] op_sel_hi:[0,0]
	v_pk_fma_f32 v[56:57], v[40:41], v[26:27], v[44:45] op_sel_hi:[0,1,1]
	v_pk_fma_f32 v[40:41], v[40:41], v[26:27], v[44:45] op_sel_hi:[0,1,1] neg_lo:[0,0,1] neg_hi:[0,0,1]
	v_mov_b32_e32 v40, v56
	v_pk_fma_f32 v[44:45], v[54:55], 0.5, v[56:57] op_sel_hi:[1,0,1] neg_lo:[0,0,1] neg_hi:[0,0,1]
	v_pk_fma_f32 v[26:27], v[54:55], 0.5, v[40:41] op_sel_hi:[1,0,1]
	v_pk_fma_f32 v[56:57], v[54:55], 0.5, v[40:41] op_sel_hi:[1,0,1] neg_lo:[1,0,0] neg_hi:[1,0,0]
	v_pk_add_f32 v[40:41], v[106:107], v[42:43]
	v_pk_add_f32 v[42:43], v[42:43], v[106:107] neg_lo:[0,1] neg_hi:[0,1]
	v_mov_b32_e32 v45, v27
	v_mul_f32_e32 v6, 0.5, v43
	v_mov_b32_e32 v43, v41
	v_pk_mul_f32 v[120:121], v[44:45], s[6:7] op_sel_hi:[1,0]
	v_mul_f32_e32 v4, 0.5, v40
	v_pk_mov_b32 v[44:45], v[108:109], v[70:71] op_sel:[1,0]
	v_pk_mul_f32 v[40:41], v[42:43], s[44:45]
	v_cvt_f32_f16_sdwa v54, v20 dst_sel:DWORD dst_unused:UNUSED_PAD src0_sel:WORD_1
	v_pk_mul_f32 v[42:43], v[44:45], v[40:41] op_sel:[0,1] op_sel_hi:[1,0]
	v_cvt_f32_f16_e32 v55, v21
	v_cvt_f32_f16_sdwa v21, v21 dst_sel:DWORD dst_unused:UNUSED_PAD src0_sel:WORD_1
	v_cvt_f32_f16_e32 v20, v20
	v_pk_mul_f32 v[40:41], v[44:45], v[40:41]
	v_pk_add_f32 v[42:43], v[42:43], v[42:43] op_sel:[0,1] op_sel_hi:[0,1]
	v_pk_add_f32 v[104:105], v[4:5], v[42:43]
	v_pk_add_f32 v[42:43], v[4:5], v[42:43] op_sel_hi:[0,1] neg_lo:[0,1] neg_hi:[0,1]
	v_pk_add_f32 v[40:41], v[40:41], v[40:41] op_sel:[0,1] op_sel_hi:[0,1] neg_lo:[0,1] neg_hi:[0,1]
	v_mov_b32_e32 v105, v43
	v_pk_add_f32 v[42:43], v[6:7], v[40:41]
	v_pk_add_f32 v[40:41], v[6:7], v[40:41] op_sel_hi:[0,1] neg_lo:[0,1] neg_hi:[0,1]
	v_mov_b32_e32 v43, v41
	v_pk_mul_f32 v[40:41], v[42:43], v[20:21]
	v_pk_mul_f32 v[42:43], v[42:43], v[54:55]
	v_pk_fma_f32 v[40:41], v[104:105], v[54:55], v[40:41]
	v_pk_fma_f32 v[20:21], v[104:105], v[20:21], v[42:43] neg_lo:[0,0,1] neg_hi:[0,0,1]
	v_mov_b32_e32 v71, v109
	v_pk_add_f32 v[42:43], v[20:21], v[40:41] op_sel:[0,1] op_sel_hi:[1,0] neg_lo:[0,1] neg_hi:[0,1]
	v_pk_add_f32 v[54:55], v[20:21], v[40:41] op_sel:[0,1] op_sel_hi:[1,0]
	v_pk_add_f32 v[20:21], v[40:41], v[20:21] op_sel:[1,0] op_sel_hi:[0,1] neg_lo:[0,1] neg_hi:[0,1]
	v_mov_b32_e32 v43, v55
	v_pk_mul_f32 v[42:43], v[42:43], 0.5 op_sel_hi:[1,0]
	v_mov_b32_e32 v55, v21
	v_mul_f32_e32 v4, v109, v42
	v_pk_fma_f32 v[104:105], v[44:45], v[42:43], v[4:5] op_sel_hi:[1,1,0] neg_lo:[1,0,0] neg_hi:[1,0,0]
	v_mul_f32_e32 v4, v109, v43
	v_pk_fma_f32 v[42:43], v[70:71], v[42:43], v[4:5] op_sel_hi:[1,1,0]
	v_sub_f32_e32 v6, v23, v103
	v_mov_b32_e32 v104, v42
	v_pk_fma_f32 v[40:41], v[54:55], 0.5, v[42:43] op_sel_hi:[1,0,1] neg_lo:[0,0,1] neg_hi:[0,0,1]
	v_pk_fma_f32 v[20:21], v[54:55], 0.5, v[104:105] op_sel_hi:[1,0,1]
	v_pk_add_f32 v[42:43], v[102:103], v[22:23]
	v_mov_b32_e32 v41, v21
	v_pk_mul_f32 v[128:129], v[40:41], s[6:7] op_sel_hi:[1,0]
	v_mul_f32_e32 v40, 0xbf0e39da, v83
	v_mov_b32_e32 v41, v22
	v_mul_f32_e32 v18, 0.5, v43
	v_pk_add_f32 v[22:23], v[40:41], v[46:47] neg_lo:[0,1] neg_hi:[0,1]
	v_mov_b32_e32 v47, v109
	v_pk_mul_f32 v[40:41], v[22:23], v[18:19]
	v_mov_b32_e32 v46, v22
	v_pk_fma_f32 v[44:45], v[44:45], v[40:41], v[40:41] op_sel:[0,1,0] op_sel_hi:[1,0,1]
	v_mov_b32_e32 v40, v41
	v_mov_b32_e32 v41, v18
	v_mul_f32_e32 v4, 0.5, v42
	v_pk_mul_f32 v[40:41], v[46:47], v[40:41]
	v_cvt_f32_f16_e32 v46, v10
	v_cvt_f32_f16_e32 v47, v11
	v_cvt_f32_f16_sdwa v11, v11 dst_sel:DWORD dst_unused:UNUSED_PAD src0_sel:WORD_1
	v_cvt_f32_f16_sdwa v10, v10 dst_sel:DWORD dst_unused:UNUSED_PAD src0_sel:WORD_1
	v_pk_fma_f32 v[70:71], v[54:55], 0.5, v[104:105] op_sel_hi:[1,0,1] neg_lo:[1,0,0] neg_hi:[1,0,0]
	v_mul_f32_e32 v6, 0.5, v6
	v_pk_add_f32 v[54:55], v[4:5], v[44:45]
	v_pk_add_f32 v[40:41], v[40:41], v[40:41] op_sel:[0,1] op_sel_hi:[0,1] neg_lo:[0,1] neg_hi:[0,1]
	v_fma_f32 v55, v42, 0.5, -v44
	v_pk_add_f32 v[42:43], v[6:7], v[40:41]
	v_pk_add_f32 v[40:41], v[6:7], v[40:41] op_sel_hi:[0,1] neg_lo:[0,1] neg_hi:[0,1]
	v_mov_b32_e32 v43, v41
	v_pk_mul_f32 v[40:41], v[42:43], v[10:11]
	v_pk_mul_f32 v[42:43], v[42:43], v[46:47]
	v_pk_fma_f32 v[44:45], v[54:55], v[46:47], v[40:41] neg_lo:[0,0,1] neg_hi:[0,0,1]
	v_pk_fma_f32 v[40:41], v[54:55], v[46:47], v[40:41]
	v_pk_fma_f32 v[46:47], v[54:55], v[10:11], v[42:43]
	v_pk_fma_f32 v[10:11], v[54:55], v[10:11], v[42:43] neg_lo:[0,0,1] neg_hi:[0,0,1]
	v_pk_add_f32 v[42:43], v[44:45], v[40:41] op_sel:[0,1] op_sel_hi:[1,0]
	v_pk_add_f32 v[54:55], v[46:47], v[10:11] op_sel_hi:[0,1] neg_lo:[0,1] neg_hi:[0,1]
	v_pk_add_f32 v[40:41], v[44:45], v[40:41] op_sel_hi:[0,1] neg_lo:[0,1] neg_hi:[0,1]
	v_pk_add_f32 v[10:11], v[46:47], v[10:11] op_sel:[0,1] op_sel_hi:[1,0]
	v_mov_b32_e32 v43, v55
	v_mov_b32_e32 v11, v41
	v_pk_mul_f32 v[10:11], v[10:11], 0.5 op_sel_hi:[1,0]
	v_mov_b32_e32 v119, v98
	v_pk_mul_f32 v[40:41], v[108:109], v[10:11] op_sel:[1,1] op_sel_hi:[1,0]
	v_pk_fma_f32 v[76:77], v[76:77], 0.5, v[112:113] op_sel_hi:[1,0,1] neg_lo:[1,0,0] neg_hi:[1,0,0]
	v_pk_fma_f32 v[44:45], v[22:23], v[10:11], v[40:41] op_sel_hi:[0,1,1]
	v_pk_fma_f32 v[10:11], v[22:23], v[10:11], v[40:41] op_sel_hi:[0,1,1] neg_lo:[0,0,1] neg_hi:[0,0,1]
	v_mov_b32_e32 v10, v44
	v_pk_fma_f32 v[22:23], v[42:43], 0.5, v[44:45] op_sel_hi:[1,0,1] neg_lo:[0,0,1] neg_hi:[0,0,1]
	v_pk_fma_f32 v[40:41], v[42:43], 0.5, v[10:11] op_sel_hi:[1,0,1]
	v_pk_fma_f32 v[54:55], v[42:43], 0.5, v[10:11] op_sel_hi:[1,0,1] neg_lo:[1,0,0] neg_hi:[1,0,0]
	v_pk_add_f32 v[10:11], v[100:101], v[14:15]
	v_pk_add_f32 v[14:15], v[14:15], v[100:101] neg_lo:[0,1] neg_hi:[0,1]
	v_mov_b32_e32 v23, v41
	v_mul_f32_e32 v6, 0.5, v15
	v_mov_b32_e32 v15, v11
	v_pk_mul_f32 v[150:151], v[22:23], s[6:7] op_sel_hi:[1,0]
	v_mul_f32_e32 v4, 0.5, v10
	v_pk_mov_b32 v[22:23], v[58:59], v[72:73] op_sel:[1,0]
	v_pk_mul_f32 v[10:11], v[14:15], s[44:45]
	v_cvt_f32_f16_sdwa v42, v8 dst_sel:DWORD dst_unused:UNUSED_PAD src0_sel:WORD_1
	v_pk_mul_f32 v[14:15], v[22:23], v[10:11] op_sel:[0,1] op_sel_hi:[1,0]
	v_cvt_f32_f16_e32 v43, v9
	v_cvt_f32_f16_sdwa v9, v9 dst_sel:DWORD dst_unused:UNUSED_PAD src0_sel:WORD_1
	v_cvt_f32_f16_e32 v8, v8
	v_pk_mul_f32 v[10:11], v[22:23], v[10:11]
	v_pk_add_f32 v[14:15], v[14:15], v[14:15] op_sel:[0,1] op_sel_hi:[0,1]
	v_pk_add_f32 v[44:45], v[4:5], v[14:15]
	v_pk_add_f32 v[14:15], v[4:5], v[14:15] op_sel_hi:[0,1] neg_lo:[0,1] neg_hi:[0,1]
	v_pk_add_f32 v[10:11], v[10:11], v[10:11] op_sel:[0,1] op_sel_hi:[0,1] neg_lo:[0,1] neg_hi:[0,1]
	v_mov_b32_e32 v45, v15
	v_pk_add_f32 v[14:15], v[6:7], v[10:11]
	v_pk_add_f32 v[10:11], v[6:7], v[10:11] op_sel_hi:[0,1] neg_lo:[0,1] neg_hi:[0,1]
	v_mov_b32_e32 v15, v11
	v_pk_mul_f32 v[10:11], v[14:15], v[8:9]
	v_pk_mul_f32 v[14:15], v[14:15], v[42:43]
	v_pk_fma_f32 v[10:11], v[44:45], v[42:43], v[10:11]
	v_pk_fma_f32 v[8:9], v[44:45], v[8:9], v[14:15] neg_lo:[0,0,1] neg_hi:[0,0,1]
	v_mov_b32_e32 v73, v59
	v_pk_add_f32 v[14:15], v[8:9], v[10:11] op_sel:[0,1] op_sel_hi:[1,0] neg_lo:[0,1] neg_hi:[0,1]
	v_pk_add_f32 v[42:43], v[8:9], v[10:11] op_sel:[0,1] op_sel_hi:[1,0]
	v_pk_add_f32 v[8:9], v[10:11], v[8:9] op_sel:[1,0] op_sel_hi:[0,1] neg_lo:[0,1] neg_hi:[0,1]
	v_mov_b32_e32 v15, v43
	v_pk_mul_f32 v[14:15], v[14:15], 0.5 op_sel_hi:[1,0]
	v_mov_b32_e32 v43, v9
	v_mul_f32_e32 v4, v59, v14
	v_pk_fma_f32 v[44:45], v[22:23], v[14:15], v[4:5] op_sel_hi:[1,1,0] neg_lo:[1,0,0] neg_hi:[1,0,0]
	v_mul_f32_e32 v4, v59, v15
	v_pk_fma_f32 v[14:15], v[72:73], v[14:15], v[4:5] op_sel_hi:[1,1,0]
	v_sub_f32_e32 v6, v39, v99
	v_mov_b32_e32 v44, v14
	v_pk_fma_f32 v[8:9], v[42:43], 0.5, v[14:15] op_sel_hi:[1,0,1] neg_lo:[0,0,1] neg_hi:[0,0,1]
	v_pk_fma_f32 v[10:11], v[42:43], 0.5, v[44:45] op_sel_hi:[1,0,1]
	v_pk_add_f32 v[14:15], v[98:99], v[38:39]
	v_mov_b32_e32 v9, v11
	v_pk_mul_f32 v[168:169], v[8:9], s[6:7] op_sel_hi:[1,0]
	v_mul_f32_e32 v8, 0xbf7b14be, v83
	v_mov_b32_e32 v9, v38
	v_mul_f32_e32 v18, 0.5, v15
	v_pk_add_f32 v[8:9], v[8:9], v[118:119] neg_lo:[0,1] neg_hi:[0,1]
	v_pk_fma_f32 v[72:73], v[42:43], 0.5, v[44:45] op_sel_hi:[1,0,1] neg_lo:[1,0,0] neg_hi:[1,0,0]
	v_pk_mul_f32 v[38:39], v[8:9], v[18:19]
	v_mov_b32_e32 v42, v8
	v_pk_fma_f32 v[22:23], v[22:23], v[38:39], v[38:39] op_sel:[0,1,0] op_sel_hi:[1,0,1]
	v_mov_b32_e32 v43, v59
	v_mov_b32_e32 v38, v39
	v_mov_b32_e32 v39, v18
	v_mul_f32_e32 v4, 0.5, v14
	v_pk_mul_f32 v[38:39], v[42:43], v[38:39]
	v_cvt_f32_f16_e32 v44, v2
	v_cvt_f32_f16_e32 v45, v3
	v_cvt_f32_f16_sdwa v3, v3 dst_sel:DWORD dst_unused:UNUSED_PAD src0_sel:WORD_1
	v_cvt_f32_f16_sdwa v2, v2 dst_sel:DWORD dst_unused:UNUSED_PAD src0_sel:WORD_1
	v_mul_f32_e32 v6, 0.5, v6
	v_pk_add_f32 v[46:47], v[4:5], v[22:23]
	v_fma_f32 v4, v14, 0.5, -v22
	v_pk_add_f32 v[22:23], v[38:39], v[38:39] op_sel:[0,1] op_sel_hi:[0,1] neg_lo:[0,1] neg_hi:[0,1]
	v_pk_add_f32 v[38:39], v[6:7], v[22:23]
	v_pk_add_f32 v[22:23], v[6:7], v[22:23] op_sel_hi:[0,1] neg_lo:[0,1] neg_hi:[0,1]
	v_mov_b32_e32 v39, v23
	v_mov_b32_e32 v14, v46
	v_mov_b32_e32 v15, v4
	v_pk_mul_f32 v[22:23], v[4:5], v[44:45] op_sel_hi:[0,1]
	v_pk_mul_f32 v[82:83], v[38:39], v[2:3]
	v_pk_mul_f32 v[46:47], v[46:47], v[2:3]
	v_pk_mul_f32 v[38:39], v[38:39], v[44:45]
	v_pk_fma_f32 v[98:99], v[14:15], v[44:45], v[82:83] neg_lo:[0,0,1] neg_hi:[0,0,1]
	v_pk_fma_f32 v[2:3], v[14:15], v[2:3], v[38:39] neg_lo:[0,0,1] neg_hi:[0,0,1]
	v_add_f32_e32 v4, v23, v83
	v_add_f32_e32 v6, v46, v38
	v_pk_add_f32 v[22:23], v[6:7], v[2:3] op_sel_hi:[0,1] neg_lo:[0,1] neg_hi:[0,1]
	v_pk_add_f32 v[38:39], v[98:99], v[4:5] op_sel_hi:[1,0] neg_lo:[0,1] neg_hi:[0,1]
	v_pk_add_f32 v[2:3], v[6:7], v[2:3] op_sel_hi:[0,1]
	v_mov_b32_e32 v39, v3
	v_pk_mul_f32 v[2:3], v[38:39], 0.5 op_sel_hi:[1,0]
	v_pk_add_f32 v[14:15], v[98:99], v[4:5] op_sel_hi:[1,0]
	v_mul_f32_e32 v4, v59, v3
	v_pk_fma_f32 v[38:39], v[42:43], v[2:3], v[4:5] op_sel_hi:[1,1,0] neg_lo:[0,0,1] neg_hi:[0,0,1]
	v_pk_mov_b32 v[42:43], v[58:59], v[8:9] op_sel:[1,0]
	v_mul_f32_e32 v4, v8, v3
	v_pk_fma_f32 v[2:3], v[42:43], v[2:3], v[4:5] op_sel_hi:[1,1,0]
	v_mov_b32_e32 v15, v23
	v_pk_fma_f32 v[8:9], v[14:15], 0.5, v[2:3] op_sel_hi:[1,0,1] neg_lo:[0,0,1] neg_hi:[0,0,1]
	v_pk_fma_f32 v[42:43], v[14:15], 0.5, v[38:39] op_sel_hi:[1,0,0]
	v_pk_fma_f32 v[2:3], v[14:15], 0.5, v[2:3] op_sel_hi:[1,0,1]
	v_mov_b32_e32 v9, v43
	v_pk_fma_f32 v[58:59], v[22:23], 0.5, v[38:39] op_sel_hi:[1,0,0] neg_lo:[1,0,0] neg_hi:[1,0,0]
	v_pk_mul_f32 v[144:145], v[8:9], s[6:7] op_sel_hi:[1,0]
	v_mov_b32_e32 v58, v2
	v_mov_b32_e32 v72, v10
	v_mov_b32_e32 v54, v40
	v_mov_b32_e32 v70, v20
	v_mov_b32_e32 v56, v26
	v_mov_b32_e32 v76, v36
	v_mov_b32_e32 v52, v34
	v_mov_b32_e32 v74, v86
	v_mov_b32_e32 v48, v84
	v_mov_b32_e32 v50, v60
	v_mov_b32_e32 v28, v66
	v_mov_b32_e32 v32, v96
	v_mov_b32_e32 v12, v88
	v_mov_b32_e32 v16, v92
	v_mov_b32_e32 v4, v138
	v_mov_b32_e32 v6, v122

.LBB0_503:
	s_or_b64 exec, exec, s[0:1]
	v_pk_mul_f32 v[22:23], v[32:33], s[6:7] op_sel_hi:[1,0]
	v_pk_add_f32 v[26:27], v[24:25], v[30:31]
	v_pk_add_f32 v[24:25], v[24:25], v[30:31] neg_lo:[0,1] neg_hi:[0,1]
	v_pk_add_f32 v[30:31], v[64:65], v[68:69]
	v_pk_add_f32 v[32:33], v[64:65], v[68:69] neg_lo:[0,1] neg_hi:[0,1]
	v_pk_add_f32 v[34:35], v[62:63], v[90:91]
	v_pk_add_f32 v[38:39], v[94:95], v[80:81]
	v_pk_add_f32 v[40:41], v[94:95], v[80:81] neg_lo:[0,1] neg_hi:[0,1]
	v_pk_add_f32 v[68:69], v[26:27], v[30:31]
	v_pk_add_f32 v[26:27], v[26:27], v[30:31] neg_lo:[0,1] neg_hi:[0,1]
	v_xor_b32_e32 v30, 0x80000000, v33
	v_mov_b32_e32 v31, v32
	v_pk_mul_f32 v[20:21], v[50:51], s[6:7] op_sel_hi:[1,0]
	v_pk_add_f32 v[36:37], v[62:63], v[90:91] neg_lo:[0,1] neg_hi:[0,1]
	v_pk_add_f32 v[42:43], v[78:79], v[136:137]
	v_pk_add_f32 v[46:47], v[130:131], v[120:121]
	v_pk_add_f32 v[50:51], v[130:131], v[120:121] neg_lo:[0,1] neg_hi:[0,1]
	v_pk_add_f32 v[32:33], v[24:25], v[30:31]
	v_pk_add_f32 v[24:25], v[24:25], v[30:31] neg_lo:[0,1] neg_hi:[0,1]
	v_pk_add_f32 v[30:31], v[34:35], v[38:39]
	v_pk_add_f32 v[34:35], v[34:35], v[38:39] neg_lo:[0,1] neg_hi:[0,1]
	v_xor_b32_e32 v38, 0x80000000, v41
	v_mov_b32_e32 v39, v40
	v_pk_add_f32 v[44:45], v[78:79], v[136:137] neg_lo:[0,1] neg_hi:[0,1]
	v_pk_add_f32 v[60:61], v[128:129], v[150:151]
	v_pk_add_f32 v[64:65], v[168:169], v[144:145]
	v_pk_add_f32 v[66:67], v[168:169], v[144:145] neg_lo:[0,1] neg_hi:[0,1]
	v_pk_add_f32 v[40:41], v[36:37], v[38:39]
	v_pk_add_f32 v[36:37], v[36:37], v[38:39] neg_lo:[0,1] neg_hi:[0,1]
	v_pk_add_f32 v[38:39], v[42:43], v[46:47]
	v_pk_add_f32 v[42:43], v[42:43], v[46:47] neg_lo:[0,1] neg_hi:[0,1]
	v_xor_b32_e32 v46, 0x80000000, v51
	v_mov_b32_e32 v47, v50
	v_pk_add_f32 v[62:63], v[128:129], v[150:151] neg_lo:[0,1] neg_hi:[0,1]
	v_pk_add_f32 v[50:51], v[44:45], v[46:47]
	v_pk_add_f32 v[44:45], v[44:45], v[46:47] neg_lo:[0,1] neg_hi:[0,1]
	v_pk_add_f32 v[46:47], v[60:61], v[64:65]
	v_pk_add_f32 v[60:61], v[60:61], v[64:65] neg_lo:[0,1] neg_hi:[0,1]
	v_xor_b32_e32 v64, 0x80000000, v67
	v_mov_b32_e32 v65, v66
	s_mov_b32 s78, s37
	s_mov_b32 s79, s36
	v_pk_add_f32 v[66:67], v[62:63], v[64:65]
	v_pk_add_f32 v[62:63], v[62:63], v[64:65] neg_lo:[0,1] neg_hi:[0,1]
	v_pk_add_f32 v[64:65], v[68:69], v[30:31]
	v_pk_add_f32 v[30:31], v[68:69], v[30:31] neg_lo:[0,1] neg_hi:[0,1]
	s_mov_b32 s0, s37
	v_pk_mul_f32 v[68:69], v[40:41], s[78:79]
	s_mov_b32 s80, s19
	v_pk_fma_f32 v[40:41], v[40:41], s[0:1], v[68:69] op_sel:[0,0,1] op_sel_hi:[1,0,0]
	s_mov_b32 s81, s18
	v_pk_add_f32 v[68:69], v[32:33], v[40:41]
	v_pk_add_f32 v[32:33], v[32:33], v[40:41] neg_lo:[0,1] neg_hi:[0,1]
	v_xor_b32_e32 v40, 0x80000000, v35
	v_mov_b32_e32 v41, v34
	v_pk_add_f32 v[34:35], v[26:27], v[40:41]
	v_pk_add_f32 v[26:27], v[26:27], v[40:41] neg_lo:[0,1] neg_hi:[0,1]
	v_pk_mul_f32 v[40:41], v[36:37], s[78:79]
	s_mov_b32 s82, s19
	v_pk_fma_f32 v[36:37], v[36:37], s[0:1], v[40:41] op_sel:[0,0,1] op_sel_hi:[1,0,0] neg_lo:[1,0,0] neg_hi:[1,0,0]
	v_pk_mul_f32 v[2:3], v[72:73], s[6:7] op_sel_hi:[1,0]
	v_pk_add_f32 v[40:41], v[24:25], v[36:37]
	v_pk_add_f32 v[24:25], v[24:25], v[36:37] neg_lo:[0,1] neg_hi:[0,1]
	v_pk_add_f32 v[36:37], v[38:39], v[46:47]
	v_pk_add_f32 v[38:39], v[38:39], v[46:47] neg_lo:[0,1] neg_hi:[0,1]
	v_pk_mul_f32 v[46:47], v[66:67], s[78:79]
	v_pk_mul_f32 v[8:9], v[70:71], s[6:7] op_sel_hi:[1,0]
	v_pk_fma_f32 v[46:47], v[66:67], s[0:1], v[46:47] op_sel:[0,0,1] op_sel_hi:[1,0,0]
	v_pk_mul_f32 v[10:11], v[76:77], s[6:7] op_sel_hi:[1,0]
	v_pk_add_f32 v[66:67], v[50:51], v[46:47]
	v_pk_add_f32 v[46:47], v[50:51], v[46:47] neg_lo:[0,1] neg_hi:[0,1]
	v_xor_b32_e32 v50, 0x80000000, v61
	v_mov_b32_e32 v51, v60
	v_pk_add_f32 v[60:61], v[42:43], v[50:51]
	v_pk_add_f32 v[42:43], v[42:43], v[50:51] neg_lo:[0,1] neg_hi:[0,1]
	v_pk_mul_f32 v[50:51], v[62:63], s[78:79]
	v_pk_mul_f32 v[14:15], v[74:75], s[6:7] op_sel_hi:[1,0]
	v_pk_fma_f32 v[50:51], v[62:63], s[0:1], v[50:51] op_sel:[0,0,1] op_sel_hi:[1,0,0] neg_lo:[1,0,0] neg_hi:[1,0,0]
	v_pk_mul_f32 v[16:17], v[16:17], s[6:7] op_sel_hi:[1,0]
	v_pk_add_f32 v[62:63], v[44:45], v[50:51]
	v_pk_add_f32 v[44:45], v[44:45], v[50:51] neg_lo:[0,1] neg_hi:[0,1]
	v_pk_add_f32 v[50:51], v[64:65], v[36:37]
	v_pk_add_f32 v[36:37], v[64:65], v[36:37] neg_lo:[0,1] neg_hi:[0,1]
	v_pk_mul_f32 v[64:65], v[66:67], s[80:81]
	v_pk_mul_f32 v[6:7], v[6:7], s[6:7] op_sel_hi:[1,0]
	v_pk_fma_f32 v[64:65], v[66:67], s[16:17], v[64:65] op_sel:[0,0,1] op_sel_hi:[1,0,0]
	s_mov_b32 s17, s40
	v_pk_add_f32 v[66:67], v[68:69], v[64:65]
	v_pk_add_f32 v[64:65], v[68:69], v[64:65] neg_lo:[0,1] neg_hi:[0,1]
	v_pk_mul_f32 v[68:69], v[60:61], s[78:79]
	s_mov_b32 s88, s11
	v_pk_fma_f32 v[60:61], v[60:61], s[0:1], v[68:69] op_sel:[0,0,1] op_sel_hi:[1,0,0]
	s_mov_b32 s89, s10
	v_pk_add_f32 v[68:69], v[34:35], v[60:61]
	v_pk_add_f32 v[34:35], v[34:35], v[60:61] neg_lo:[0,1] neg_hi:[0,1]
	v_pk_mul_f32 v[60:61], v[62:63], s[16:17]
	s_mov_b32 s62, s27
	v_pk_fma_f32 v[60:61], v[62:63], s[82:83], v[60:61] op_sel:[0,0,1] op_sel_hi:[1,0,0]
	s_mov_b32 s63, s26
	v_pk_add_f32 v[62:63], v[40:41], v[60:61]
	v_pk_add_f32 v[40:41], v[40:41], v[60:61] neg_lo:[0,1] neg_hi:[0,1]
	v_xor_b32_e32 v60, 0x80000000, v39
	v_mov_b32_e32 v61, v38
	v_pk_add_f32 v[38:39], v[30:31], v[60:61]
	v_pk_add_f32 v[30:31], v[30:31], v[60:61] neg_lo:[0,1] neg_hi:[0,1]
	v_pk_mul_f32 v[60:61], v[46:47], s[16:17]
	s_mov_b32 s84, s27
	v_pk_fma_f32 v[46:47], v[46:47], s[82:83], v[60:61] op_sel:[0,0,1] op_sel_hi:[1,0,0] neg_lo:[1,0,0] neg_hi:[1,0,0]
	s_mov_b32 s86, s11
	v_pk_add_f32 v[60:61], v[32:33], v[46:47]
	v_pk_add_f32 v[32:33], v[32:33], v[46:47] neg_lo:[0,1] neg_hi:[0,1]
	v_pk_mul_f32 v[46:47], v[42:43], s[78:79]
	s_ashr_i32 s73, s72, 31
	v_pk_fma_f32 v[42:43], v[42:43], s[0:1], v[46:47] op_sel:[0,0,1] op_sel_hi:[1,0,0] neg_lo:[1,0,0] neg_hi:[1,0,0]
	s_nop 0
	v_pk_add_f32 v[46:47], v[26:27], v[42:43]
	v_pk_add_f32 v[26:27], v[26:27], v[42:43] neg_lo:[0,1] neg_hi:[0,1]
	v_pk_mul_f32 v[42:43], v[44:45], s[80:81]
	s_nop 0
	v_pk_fma_f32 v[42:43], v[44:45], s[16:17], v[42:43] op_sel:[0,0,1] op_sel_hi:[1,0,0] neg_lo:[1,0,0] neg_hi:[1,0,0]
	s_nop 0
	v_pk_add_f32 v[44:45], v[24:25], v[42:43]
	v_pk_add_f32 v[24:25], v[24:25], v[42:43] neg_lo:[0,1] neg_hi:[0,1]
	v_pk_fma_f32 v[42:43], v[58:59], s[6:7], v[2:3] op_sel_hi:[1,0,1]
	v_pk_fma_f32 v[2:3], v[58:59], s[6:7], v[2:3] op_sel_hi:[1,0,1] neg_lo:[0,0,1] neg_hi:[0,0,1]
	v_pk_fma_f32 v[58:59], v[54:55], s[6:7], v[8:9] op_sel_hi:[1,0,1]
	v_pk_fma_f32 v[8:9], v[54:55], s[6:7], v[8:9] op_sel_hi:[1,0,1] neg_lo:[0,0,1] neg_hi:[0,0,1]
	v_pk_fma_f32 v[54:55], v[56:57], s[6:7], v[10:11] op_sel_hi:[1,0,1]
	v_pk_fma_f32 v[10:11], v[56:57], s[6:7], v[10:11] op_sel_hi:[1,0,1] neg_lo:[0,0,1] neg_hi:[0,0,1]
	v_pk_fma_f32 v[56:57], v[52:53], s[6:7], v[14:15] op_sel_hi:[1,0,1]
	v_pk_fma_f32 v[14:15], v[52:53], s[6:7], v[14:15] op_sel_hi:[1,0,1] neg_lo:[0,0,1] neg_hi:[0,0,1]
	v_pk_fma_f32 v[52:53], v[48:49], s[6:7], v[20:21] op_sel_hi:[1,0,1]
	v_pk_fma_f32 v[20:21], v[48:49], s[6:7], v[20:21] op_sel_hi:[1,0,1] neg_lo:[0,0,1] neg_hi:[0,0,1]
	v_pk_fma_f32 v[48:49], v[28:29], s[6:7], v[22:23] op_sel_hi:[1,0,1]
	v_pk_fma_f32 v[22:23], v[28:29], s[6:7], v[22:23] op_sel_hi:[1,0,1] neg_lo:[0,0,1] neg_hi:[0,0,1]
	v_pk_fma_f32 v[28:29], v[12:13], s[6:7], v[16:17] op_sel_hi:[1,0,1]
	v_pk_fma_f32 v[12:13], v[12:13], s[6:7], v[16:17] op_sel_hi:[1,0,1] neg_lo:[0,0,1] neg_hi:[0,0,1]
	v_pk_fma_f32 v[16:17], v[4:5], s[6:7], v[6:7] op_sel_hi:[1,0,1]
	v_pk_fma_f32 v[4:5], v[4:5], s[6:7], v[6:7] op_sel_hi:[1,0,1] neg_lo:[0,0,1] neg_hi:[0,0,1]
	v_pk_add_f32 v[6:7], v[58:59], v[42:43]
	v_pk_add_f32 v[42:43], v[42:43], v[58:59] neg_lo:[0,1] neg_hi:[0,1]
	v_xor_b32_e32 v58, 0x80000000, v9
	v_mov_b32_e32 v59, v8
	v_pk_add_f32 v[8:9], v[2:3], v[58:59]
	v_pk_add_f32 v[2:3], v[2:3], v[58:59] neg_lo:[0,1] neg_hi:[0,1]
	v_pk_add_f32 v[58:59], v[56:57], v[54:55]
	v_pk_add_f32 v[54:55], v[54:55], v[56:57] neg_lo:[0,1] neg_hi:[0,1]
	v_xor_b32_e32 v56, 0x80000000, v15
	v_mov_b32_e32 v57, v14
	v_pk_add_f32 v[14:15], v[10:11], v[56:57]
	v_pk_add_f32 v[10:11], v[10:11], v[56:57] neg_lo:[0,1] neg_hi:[0,1]
	v_pk_add_f32 v[56:57], v[48:49], v[52:53]
	v_pk_add_f32 v[48:49], v[52:53], v[48:49] neg_lo:[0,1] neg_hi:[0,1]
	v_xor_b32_e32 v52, 0x80000000, v23
	v_mov_b32_e32 v53, v22
	v_pk_add_f32 v[22:23], v[20:21], v[52:53]
	v_pk_add_f32 v[20:21], v[20:21], v[52:53] neg_lo:[0,1] neg_hi:[0,1]
	v_pk_add_f32 v[52:53], v[16:17], v[28:29]
	v_pk_add_f32 v[16:17], v[28:29], v[16:17] neg_lo:[0,1] neg_hi:[0,1]
	v_xor_b32_e32 v28, 0x80000000, v5
	v_mov_b32_e32 v29, v4
	v_pk_add_f32 v[4:5], v[12:13], v[28:29]
	v_pk_add_f32 v[12:13], v[12:13], v[28:29] neg_lo:[0,1] neg_hi:[0,1]
	v_pk_add_f32 v[28:29], v[58:59], v[6:7]
	v_pk_add_f32 v[6:7], v[6:7], v[58:59] neg_lo:[0,1] neg_hi:[0,1]
	v_pk_mul_f32 v[58:59], v[14:15], s[78:79]
	s_nop 0
	v_pk_fma_f32 v[14:15], v[14:15], s[0:1], v[58:59] op_sel:[0,0,1] op_sel_hi:[1,0,0]
	s_nop 0
	v_pk_add_f32 v[58:59], v[14:15], v[8:9]
	v_pk_add_f32 v[8:9], v[8:9], v[14:15] neg_lo:[0,1] neg_hi:[0,1]
	v_xor_b32_e32 v14, 0x80000000, v55
	v_mov_b32_e32 v15, v54
	v_pk_add_f32 v[54:55], v[14:15], v[42:43]
	v_pk_add_f32 v[14:15], v[42:43], v[14:15] neg_lo:[0,1] neg_hi:[0,1]
	v_pk_mul_f32 v[42:43], v[10:11], s[78:79]
	s_nop 0
	v_pk_fma_f32 v[10:11], v[10:11], s[0:1], v[42:43] op_sel:[0,0,1] op_sel_hi:[1,0,0] neg_lo:[1,0,0] neg_hi:[1,0,0]
	s_nop 0
	v_pk_add_f32 v[42:43], v[10:11], v[2:3]
	v_pk_add_f32 v[2:3], v[2:3], v[10:11] neg_lo:[0,1] neg_hi:[0,1]
	v_pk_add_f32 v[10:11], v[52:53], v[56:57]
	v_pk_add_f32 v[52:53], v[56:57], v[52:53] neg_lo:[0,1] neg_hi:[0,1]
	v_pk_mul_f32 v[56:57], v[4:5], s[78:79]
	s_nop 0
	v_pk_fma_f32 v[4:5], v[4:5], s[0:1], v[56:57] op_sel:[0,0,1] op_sel_hi:[1,0,0]
	s_nop 0
	v_pk_add_f32 v[56:57], v[4:5], v[22:23]
	v_pk_add_f32 v[4:5], v[22:23], v[4:5] neg_lo:[0,1] neg_hi:[0,1]
	v_xor_b32_e32 v22, 0x80000000, v17
	v_mov_b32_e32 v23, v16
	v_pk_add_f32 v[16:17], v[22:23], v[48:49]
	v_pk_add_f32 v[22:23], v[48:49], v[22:23] neg_lo:[0,1] neg_hi:[0,1]
	v_pk_mul_f32 v[48:49], v[12:13], s[78:79]
	s_nop 0
	v_pk_fma_f32 v[12:13], v[12:13], s[0:1], v[48:49] op_sel:[0,0,1] op_sel_hi:[1,0,0] neg_lo:[1,0,0] neg_hi:[1,0,0]
	s_nop 0
	v_pk_add_f32 v[48:49], v[12:13], v[20:21]
	v_pk_add_f32 v[12:13], v[20:21], v[12:13] neg_lo:[0,1] neg_hi:[0,1]
	v_pk_add_f32 v[20:21], v[10:11], v[28:29]
	v_pk_add_f32 v[10:11], v[28:29], v[10:11] neg_lo:[0,1] neg_hi:[0,1]
	v_pk_mul_f32 v[28:29], v[56:57], s[80:81]
	s_nop 0
	v_pk_fma_f32 v[28:29], v[56:57], s[16:17], v[28:29] op_sel:[0,0,1] op_sel_hi:[1,0,0]
	s_nop 0
	v_pk_add_f32 v[56:57], v[28:29], v[58:59]
	v_pk_add_f32 v[28:29], v[58:59], v[28:29] neg_lo:[0,1] neg_hi:[0,1]
	v_pk_mul_f32 v[58:59], v[16:17], s[78:79]
	s_nop 0
	v_pk_fma_f32 v[16:17], v[16:17], s[0:1], v[58:59] op_sel:[0,0,1] op_sel_hi:[1,0,0]
	s_nop 0
	v_pk_add_f32 v[58:59], v[16:17], v[54:55]
	v_pk_add_f32 v[16:17], v[54:55], v[16:17] neg_lo:[0,1] neg_hi:[0,1]
	v_pk_mul_f32 v[54:55], v[48:49], s[16:17]
	s_nop 0
	v_pk_fma_f32 v[48:49], v[48:49], s[82:83], v[54:55] op_sel:[0,0,1] op_sel_hi:[1,0,0]
	s_nop 0
	v_pk_add_f32 v[54:55], v[48:49], v[42:43]
	v_pk_add_f32 v[42:43], v[42:43], v[48:49] neg_lo:[0,1] neg_hi:[0,1]
	v_xor_b32_e32 v48, 0x80000000, v53
	v_mov_b32_e32 v49, v52
	v_pk_add_f32 v[52:53], v[48:49], v[6:7]
	v_pk_add_f32 v[6:7], v[6:7], v[48:49] neg_lo:[0,1] neg_hi:[0,1]
	v_pk_mul_f32 v[48:49], v[4:5], s[16:17]
	s_nop 0
	v_pk_fma_f32 v[4:5], v[4:5], s[82:83], v[48:49] op_sel:[0,0,1] op_sel_hi:[1,0,0] neg_lo:[1,0,0] neg_hi:[1,0,0]
	s_nop 0
	v_pk_add_f32 v[48:49], v[4:5], v[8:9]
	v_pk_add_f32 v[4:5], v[8:9], v[4:5] neg_lo:[0,1] neg_hi:[0,1]
	v_pk_mul_f32 v[8:9], v[22:23], s[78:79]
	s_nop 0
	v_pk_fma_f32 v[8:9], v[22:23], s[0:1], v[8:9] op_sel:[0,0,1] op_sel_hi:[1,0,0] neg_lo:[1,0,0] neg_hi:[1,0,0]
	s_nop 0
	v_pk_add_f32 v[22:23], v[8:9], v[14:15]
	v_pk_add_f32 v[8:9], v[14:15], v[8:9] neg_lo:[0,1] neg_hi:[0,1]
	v_pk_mul_f32 v[14:15], v[12:13], s[80:81]
	s_nop 0
	v_pk_fma_f32 v[12:13], v[12:13], s[16:17], v[14:15] op_sel:[0,0,1] op_sel_hi:[1,0,0] neg_lo:[1,0,0] neg_hi:[1,0,0]
	s_nop 0
	v_pk_add_f32 v[14:15], v[12:13], v[2:3]
	v_pk_add_f32 v[2:3], v[2:3], v[12:13] neg_lo:[0,1] neg_hi:[0,1]
	ds_write_b64 v211, v[50:51]
	ds_write_b64 v212, v[20:21]
	ds_write_b64 v211, v[66:67] offset:8
	ds_write_b64 v212, v[56:57] offset:8
	ds_write_b64 v211, v[68:69] offset:16
	ds_write_b64 v212, v[58:59] offset:16
	ds_write_b64 v211, v[62:63] offset:24
	ds_write_b64 v212, v[54:55] offset:24
	ds_write_b64 v211, v[38:39] offset:32
	ds_write_b64 v212, v[52:53] offset:32
	ds_write_b64 v211, v[60:61] offset:40
	ds_write_b64 v212, v[48:49] offset:40
	ds_write_b64 v211, v[46:47] offset:48
	ds_write_b64 v212, v[22:23] offset:48
	ds_write_b64 v211, v[44:45] offset:56
	ds_write_b64 v212, v[14:15] offset:56
	ds_write_b64 v211, v[36:37] offset:64
	ds_write_b64 v212, v[10:11] offset:64
	ds_write_b64 v211, v[64:65] offset:72
	ds_write_b64 v212, v[28:29] offset:72
	ds_write_b64 v211, v[34:35] offset:80
	ds_write_b64 v212, v[16:17] offset:80
	ds_write_b64 v211, v[40:41] offset:88
	ds_write_b64 v212, v[42:43] offset:88
	ds_write_b64 v211, v[30:31] offset:96
	ds_write_b64 v212, v[6:7] offset:96
	ds_write_b64 v211, v[32:33] offset:104
	ds_write_b64 v212, v[4:5] offset:104
	ds_write_b64 v211, v[26:27] offset:112
	ds_write_b64 v212, v[8:9] offset:112
	ds_write_b64 v211, v[24:25] offset:120
	ds_write_b64 v212, v[2:3] offset:120
	v_mov_b32_e32 v2, v210
	s_waitcnt lgkmcnt(0)
	s_barrier
	s_nop 0
	v_and_b32_e32 v3, 15, v2
	v_lshlrev_b32_e32 v5, 3, v3
	v_cvt_f32_ubyte0_e32 v3, v3
	v_mul_f32_e32 v3, 0x3b000000, v3
	v_sin_f32_e32 v17, v3
	v_cos_f32_e32 v16, v3
	v_lshlrev_b32_e32 v2, 5, v2
	v_and_b32_e32 v2, 0xfffffe00, v2
	v_lshl_add_u32 v4, v2, 3, 0
	v_ashrrev_i32_e32 v2, 2, v2
	s_nop 0
	v_add3_u32 v2, v4, v5, v2
	v_pk_mul_f32 v[4:5], v[16:17], v[16:17] op_sel:[1,1] op_sel_hi:[0,1] neg_lo:[0,1]
	v_pk_fma_f32 v[74:75], v[16:17], v[16:17], v[4:5] op_sel_hi:[1,0,1]
	v_add_u32_e32 v3, 0x800, v2
	v_pk_mul_f32 v[4:5], v[16:17], v[74:75] op_sel:[1,1] op_sel_hi:[1,0] neg_lo:[1,0]
	v_xor_b32_e32 v78, 0x80000000, v75
	v_mov_b32_e32 v79, v75
	v_pk_fma_f32 v[76:77], v[16:17], v[74:75], v[4:5] op_sel_hi:[0,1,1]
	v_pk_mul_f32 v[4:5], v[74:75], v[78:79] op_sel:[1,0] op_sel_hi:[0,1]
	v_pk_fma_f32 v[80:81], v[74:75], v[74:75], v[4:5] op_sel_hi:[1,0,1]
	v_xor_b32_e32 v84, 0x80000000, v77
	v_pk_mul_f32 v[4:5], v[16:17], v[80:81] op_sel:[1,1] op_sel_hi:[1,0] neg_lo:[1,0]
	v_mov_b32_e32 v85, v77
	v_pk_fma_f32 v[86:87], v[16:17], v[80:81], v[4:5] op_sel_hi:[0,1,1]
	v_pk_mul_f32 v[4:5], v[78:79], v[80:81] op_sel:[0,1] op_sel_hi:[1,0]
	v_xor_b32_e32 v82, 0x80000000, v81
	v_mov_b32_e32 v83, v81
	v_pk_fma_f32 v[90:91], v[74:75], v[80:81], v[4:5] op_sel_hi:[0,1,1]
	v_pk_mul_f32 v[4:5], v[80:81], v[84:85] op_sel:[1,0] op_sel_hi:[0,1]
	v_pk_fma_f32 v[94:95], v[80:81], v[76:77], v[4:5] op_sel_hi:[1,0,1]
	v_pk_mul_f32 v[4:5], v[80:81], v[82:83] op_sel:[1,0] op_sel_hi:[0,1]
	v_pk_fma_f32 v[98:99], v[80:81], v[80:81], v[4:5] op_sel_hi:[1,0,1]
	v_xor_b32_e32 v88, 0x80000000, v87
	v_pk_mul_f32 v[4:5], v[16:17], v[98:99] op_sel:[1,1] op_sel_hi:[1,0] neg_lo:[1,0]
	v_mov_b32_e32 v89, v87
	v_pk_fma_f32 v[102:103], v[16:17], v[98:99], v[4:5] op_sel_hi:[0,1,1]
	v_pk_mul_f32 v[4:5], v[78:79], v[98:99] op_sel:[0,1] op_sel_hi:[1,0]
	v_xor_b32_e32 v92, 0x80000000, v91
	v_pk_fma_f32 v[106:107], v[74:75], v[98:99], v[4:5] op_sel_hi:[0,1,1]
	v_pk_mul_f32 v[4:5], v[84:85], v[98:99] op_sel:[0,1] op_sel_hi:[1,0]
	v_mov_b32_e32 v93, v91
	v_pk_fma_f32 v[110:111], v[76:77], v[98:99], v[4:5] op_sel_hi:[0,1,1]
	v_pk_mul_f32 v[4:5], v[82:83], v[98:99] op_sel:[0,1] op_sel_hi:[1,0]
	v_xor_b32_e32 v96, 0x80000000, v95
	v_pk_fma_f32 v[114:115], v[80:81], v[98:99], v[4:5] op_sel_hi:[0,1,1]
	v_pk_mul_f32 v[4:5], v[16:17], v[114:115] op_sel:[1,1] op_sel_hi:[1,0] neg_lo:[1,0]
	v_mov_b32_e32 v97, v95
	v_pk_fma_f32 v[118:119], v[16:17], v[114:115], v[4:5] op_sel_hi:[0,1,1]
	v_pk_mul_f32 v[4:5], v[78:79], v[114:115] op_sel:[0,1] op_sel_hi:[1,0]
	v_xor_b32_e32 v100, 0x80000000, v99
	v_pk_fma_f32 v[122:123], v[74:75], v[114:115], v[4:5] op_sel_hi:[0,1,1]
	v_pk_mul_f32 v[4:5], v[84:85], v[114:115] op_sel:[0,1] op_sel_hi:[1,0]
	v_mov_b32_e32 v101, v99
	v_pk_fma_f32 v[126:127], v[76:77], v[114:115], v[4:5] op_sel_hi:[0,1,1]
	v_pk_mul_f32 v[4:5], v[82:83], v[114:115] op_sel:[0,1] op_sel_hi:[1,0]
	v_xor_b32_e32 v104, 0x80000000, v103
	v_pk_fma_f32 v[130:131], v[80:81], v[114:115], v[4:5] op_sel_hi:[0,1,1]
	v_pk_mul_f32 v[4:5], v[16:17], v[130:131] op_sel:[1,1] op_sel_hi:[1,0] neg_lo:[1,0]
	v_mov_b32_e32 v105, v103
	v_pk_fma_f32 v[134:135], v[16:17], v[130:131], v[4:5] op_sel_hi:[0,1,1]
	v_pk_mul_f32 v[4:5], v[78:79], v[130:131] op_sel:[0,1] op_sel_hi:[1,0]
	v_xor_b32_e32 v108, 0x80000000, v107
	v_pk_fma_f32 v[138:139], v[74:75], v[130:131], v[4:5] op_sel_hi:[0,1,1]
	v_pk_mul_f32 v[4:5], v[84:85], v[130:131] op_sel:[0,1] op_sel_hi:[1,0]
	v_mov_b32_e32 v109, v107
	v_pk_fma_f32 v[142:143], v[76:77], v[130:131], v[4:5] op_sel_hi:[0,1,1]
	v_pk_mul_f32 v[4:5], v[82:83], v[130:131] op_sel:[0,1] op_sel_hi:[1,0]
	v_xor_b32_e32 v112, 0x80000000, v111
	v_pk_fma_f32 v[148:149], v[80:81], v[130:131], v[4:5] op_sel_hi:[0,1,1]
	v_pk_mul_f32 v[4:5], v[16:17], v[148:149] op_sel:[1,1] op_sel_hi:[1,0] neg_lo:[1,0]
	v_mov_b32_e32 v113, v111
	v_pk_fma_f32 v[152:153], v[16:17], v[148:149], v[4:5] op_sel_hi:[0,1,1]
	v_pk_mul_f32 v[4:5], v[78:79], v[148:149] op_sel:[0,1] op_sel_hi:[1,0]
	v_xor_b32_e32 v116, 0x80000000, v115
	v_pk_fma_f32 v[156:157], v[74:75], v[148:149], v[4:5] op_sel_hi:[0,1,1]
	v_pk_mul_f32 v[4:5], v[84:85], v[148:149] op_sel:[0,1] op_sel_hi:[1,0]
	v_mov_b32_e32 v117, v115
	v_pk_fma_f32 v[160:161], v[76:77], v[148:149], v[4:5] op_sel_hi:[0,1,1]
	v_pk_mul_f32 v[4:5], v[82:83], v[148:149] op_sel:[0,1] op_sel_hi:[1,0]
	v_xor_b32_e32 v120, 0x80000000, v119
	v_pk_fma_f32 v[164:165], v[80:81], v[148:149], v[4:5] op_sel_hi:[0,1,1]
	v_pk_mul_f32 v[4:5], v[16:17], v[164:165] op_sel:[1,1] op_sel_hi:[1,0] neg_lo:[1,0]
	v_mov_b32_e32 v121, v119
	v_pk_fma_f32 v[168:169], v[16:17], v[164:165], v[4:5] op_sel_hi:[0,1,1]
	v_pk_mul_f32 v[4:5], v[78:79], v[164:165] op_sel:[0,1] op_sel_hi:[1,0]
	v_xor_b32_e32 v124, 0x80000000, v123
	v_pk_fma_f32 v[172:173], v[74:75], v[164:165], v[4:5] op_sel_hi:[0,1,1]
	v_pk_mul_f32 v[4:5], v[84:85], v[164:165] op_sel:[0,1] op_sel_hi:[1,0]
	v_mov_b32_e32 v125, v123
	v_pk_fma_f32 v[176:177], v[76:77], v[164:165], v[4:5] op_sel_hi:[0,1,1]
	v_pk_mul_f32 v[4:5], v[82:83], v[164:165] op_sel:[0,1] op_sel_hi:[1,0]
	v_xor_b32_e32 v128, 0x80000000, v127
	v_pk_fma_f32 v[180:181], v[80:81], v[164:165], v[4:5] op_sel_hi:[0,1,1]
	v_pk_mul_f32 v[4:5], v[16:17], v[180:181] op_sel:[1,1] op_sel_hi:[1,0] neg_lo:[1,0]
	v_mov_b32_e32 v129, v127
	v_pk_fma_f32 v[184:185], v[16:17], v[180:181], v[4:5] op_sel_hi:[0,1,1]
	v_pk_mul_f32 v[4:5], v[78:79], v[180:181] op_sel:[0,1] op_sel_hi:[1,0]
	v_xor_b32_e32 v132, 0x80000000, v131
	v_pk_fma_f32 v[188:189], v[74:75], v[180:181], v[4:5] op_sel_hi:[0,1,1]
	v_pk_mul_f32 v[4:5], v[84:85], v[180:181] op_sel:[0,1] op_sel_hi:[1,0]
	v_mov_b32_e32 v133, v131
	v_pk_fma_f32 v[192:193], v[76:77], v[180:181], v[4:5] op_sel_hi:[0,1,1]
	ds_read2_b64 v[4:7], v2 offset1:16
	ds_read2_b64 v[8:11], v2 offset0:33 offset1:49
	ds_read2_b64 v[12:15], v2 offset0:66 offset1:82
	ds_read2_b64 v[20:23], v2 offset0:99 offset1:115
	ds_read2_b64 v[24:27], v2 offset0:132 offset1:148
	ds_read2_b64 v[28:31], v2 offset0:165 offset1:181
	ds_read2_b64 v[32:35], v2 offset0:198 offset1:214
	ds_read2_b64 v[36:39], v2 offset0:231 offset1:247
	ds_read2_b64 v[40:43], v3 offset0:8 offset1:24
	ds_read2_b64 v[44:47], v3 offset0:41 offset1:57
	ds_read2_b64 v[48:51], v3 offset0:74 offset1:90
	ds_read2_b64 v[52:55], v3 offset0:107 offset1:123
	ds_read2_b64 v[56:59], v3 offset0:140 offset1:156
	ds_read2_b64 v[60:63], v3 offset0:173 offset1:189
	ds_read2_b64 v[64:67], v3 offset0:206 offset1:222
	ds_read2_b64 v[68:71], v3 offset0:239 offset1:255
	s_waitcnt lgkmcnt(7)
	v_pk_mul_f32 v[72:73], v[16:17], v[40:41] op_sel:[1,1] op_sel_hi:[1,0] neg_lo:[1,0]
	v_xor_b32_e32 v136, 0x80000000, v135
	v_pk_fma_f32 v[16:17], v[16:17], v[40:41], v[72:73] op_sel_hi:[0,1,1]
	v_pk_mul_f32 v[40:41], v[24:25], v[78:79] op_sel:[1,0] op_sel_hi:[0,1]
	v_pk_fma_f32 v[24:25], v[24:25], v[74:75], v[40:41] op_sel_hi:[1,0,1]
	s_waitcnt lgkmcnt(3)
	v_pk_mul_f32 v[40:41], v[84:85], v[56:57] op_sel:[0,1] op_sel_hi:[1,0]
	v_mov_b32_e32 v137, v135
	v_pk_fma_f32 v[40:41], v[76:77], v[56:57], v[40:41] op_sel_hi:[0,1,1]
	v_pk_mul_f32 v[56:57], v[12:13], v[82:83] op_sel:[1,0] op_sel_hi:[0,1]
	v_pk_fma_f32 v[12:13], v[12:13], v[80:81], v[56:57] op_sel_hi:[1,0,1]
	v_pk_mul_f32 v[56:57], v[88:89], v[48:49] op_sel:[0,1] op_sel_hi:[1,0]
	v_xor_b32_e32 v140, 0x80000000, v139
	v_pk_fma_f32 v[48:49], v[86:87], v[48:49], v[56:57] op_sel_hi:[0,1,1]
	v_pk_mul_f32 v[56:57], v[32:33], v[92:93] op_sel:[1,0] op_sel_hi:[0,1]
	v_pk_fma_f32 v[32:33], v[32:33], v[90:91], v[56:57] op_sel_hi:[1,0,1]
	s_waitcnt lgkmcnt(1)
	v_pk_mul_f32 v[56:57], v[96:97], v[64:65] op_sel:[0,1] op_sel_hi:[1,0]
	v_mov_b32_e32 v141, v139
	v_pk_fma_f32 v[56:57], v[94:95], v[64:65], v[56:57] op_sel_hi:[0,1,1]
	v_pk_mul_f32 v[64:65], v[8:9], v[100:101] op_sel:[1,0] op_sel_hi:[0,1]
	v_pk_fma_f32 v[8:9], v[8:9], v[98:99], v[64:65] op_sel_hi:[1,0,1]
	v_pk_mul_f32 v[64:65], v[44:45], v[104:105] op_sel:[1,0] op_sel_hi:[0,1]
	v_pk_fma_f32 v[44:45], v[44:45], v[102:103], v[64:65] op_sel_hi:[1,0,1]
	v_pk_mul_f32 v[64:65], v[28:29], v[108:109] op_sel:[1,0] op_sel_hi:[0,1]
	v_pk_fma_f32 v[28:29], v[28:29], v[106:107], v[64:65] op_sel_hi:[1,0,1]
	v_pk_mul_f32 v[64:65], v[112:113], v[60:61] op_sel:[0,1] op_sel_hi:[1,0]
	v_xor_b32_e32 v144, 0x80000000, v143
	v_pk_fma_f32 v[60:61], v[110:111], v[60:61], v[64:65] op_sel_hi:[0,1,1]
	v_pk_mul_f32 v[64:65], v[20:21], v[116:117] op_sel:[1,0] op_sel_hi:[0,1]
	v_pk_fma_f32 v[20:21], v[20:21], v[114:115], v[64:65] op_sel_hi:[1,0,1]
	v_pk_mul_f32 v[64:65], v[52:53], v[120:121] op_sel:[1,0] op_sel_hi:[0,1]
	v_pk_fma_f32 v[52:53], v[52:53], v[118:119], v[64:65] op_sel_hi:[1,0,1]
	v_pk_mul_f32 v[64:65], v[36:37], v[124:125] op_sel:[1,0] op_sel_hi:[0,1]
	v_pk_fma_f32 v[36:37], v[36:37], v[122:123], v[64:65] op_sel_hi:[1,0,1]
	s_waitcnt lgkmcnt(0)
	v_pk_mul_f32 v[64:65], v[128:129], v[68:69] op_sel:[0,1] op_sel_hi:[1,0]
	v_mov_b32_e32 v145, v143
	v_pk_fma_f32 v[64:65], v[126:127], v[68:69], v[64:65] op_sel_hi:[0,1,1]
	v_pk_mul_f32 v[68:69], v[6:7], v[132:133] op_sel:[1,0] op_sel_hi:[0,1]
	v_pk_fma_f32 v[6:7], v[6:7], v[130:131], v[68:69] op_sel_hi:[1,0,1]
	v_pk_mul_f32 v[68:69], v[42:43], v[136:137] op_sel:[1,0] op_sel_hi:[0,1]
	v_pk_fma_f32 v[42:43], v[42:43], v[134:135], v[68:69] op_sel_hi:[1,0,1]
	v_pk_mul_f32 v[68:69], v[26:27], v[140:141] op_sel:[1,0] op_sel_hi:[0,1]
	v_xor_b32_e32 v150, 0x80000000, v149
	v_mov_b32_e32 v151, v149
	v_pk_fma_f32 v[26:27], v[26:27], v[138:139], v[68:69] op_sel_hi:[1,0,1]
	v_pk_mul_f32 v[68:69], v[58:59], v[144:145] op_sel:[1,0] op_sel_hi:[0,1]
	v_xor_b32_e32 v154, 0x80000000, v153
	v_mov_b32_e32 v155, v153
	v_pk_fma_f32 v[58:59], v[58:59], v[142:143], v[68:69] op_sel_hi:[1,0,1]
	v_pk_mul_f32 v[68:69], v[14:15], v[150:151] op_sel:[1,0] op_sel_hi:[0,1]
	v_xor_b32_e32 v158, 0x80000000, v157
	v_mov_b32_e32 v159, v157
	v_pk_fma_f32 v[14:15], v[14:15], v[148:149], v[68:69] op_sel_hi:[1,0,1]
	v_pk_mul_f32 v[68:69], v[50:51], v[154:155] op_sel:[1,0] op_sel_hi:[0,1]
	v_xor_b32_e32 v162, 0x80000000, v161
	v_mov_b32_e32 v163, v161
	v_pk_fma_f32 v[50:51], v[50:51], v[152:153], v[68:69] op_sel_hi:[1,0,1]
	v_pk_mul_f32 v[68:69], v[34:35], v[158:159] op_sel:[1,0] op_sel_hi:[0,1]
	v_xor_b32_e32 v166, 0x80000000, v165
	v_mov_b32_e32 v167, v165
	v_pk_fma_f32 v[34:35], v[34:35], v[156:157], v[68:69] op_sel_hi:[1,0,1]
	v_pk_mul_f32 v[68:69], v[162:163], v[66:67] op_sel:[0,1] op_sel_hi:[1,0]
	v_xor_b32_e32 v170, 0x80000000, v169
	v_mov_b32_e32 v171, v169
	v_pk_fma_f32 v[66:67], v[160:161], v[66:67], v[68:69] op_sel_hi:[0,1,1]
	v_pk_mul_f32 v[68:69], v[10:11], v[166:167] op_sel:[1,0] op_sel_hi:[0,1]
	v_xor_b32_e32 v174, 0x80000000, v173
	v_mov_b32_e32 v175, v173
	v_pk_fma_f32 v[10:11], v[10:11], v[164:165], v[68:69] op_sel_hi:[1,0,1]
	v_pk_mul_f32 v[68:69], v[46:47], v[170:171] op_sel:[1,0] op_sel_hi:[0,1]
	v_xor_b32_e32 v178, 0x80000000, v177
	v_mov_b32_e32 v179, v177
	v_pk_fma_f32 v[46:47], v[46:47], v[168:169], v[68:69] op_sel_hi:[1,0,1]
	v_pk_mul_f32 v[68:69], v[30:31], v[174:175] op_sel:[1,0] op_sel_hi:[0,1]
	v_xor_b32_e32 v182, 0x80000000, v181
	v_mov_b32_e32 v183, v181
	v_pk_fma_f32 v[30:31], v[30:31], v[172:173], v[68:69] op_sel_hi:[1,0,1]
	v_pk_mul_f32 v[68:69], v[62:63], v[178:179] op_sel:[1,0] op_sel_hi:[0,1]
	v_xor_b32_e32 v186, 0x80000000, v185
	v_mov_b32_e32 v187, v185
	v_pk_fma_f32 v[62:63], v[62:63], v[176:177], v[68:69] op_sel_hi:[1,0,1]
	v_pk_mul_f32 v[68:69], v[22:23], v[182:183] op_sel:[1,0] op_sel_hi:[0,1]
	v_xor_b32_e32 v190, 0x80000000, v189
	v_mov_b32_e32 v191, v189
	v_pk_fma_f32 v[22:23], v[22:23], v[180:181], v[68:69] op_sel_hi:[1,0,1]
	v_pk_mul_f32 v[68:69], v[54:55], v[186:187] op_sel:[1,0] op_sel_hi:[0,1]
	v_xor_b32_e32 v194, 0x80000000, v193
	v_mov_b32_e32 v195, v193
	v_pk_fma_f32 v[54:55], v[54:55], v[184:185], v[68:69] op_sel_hi:[1,0,1]
	v_pk_mul_f32 v[68:69], v[38:39], v[190:191] op_sel:[1,0] op_sel_hi:[0,1]
	v_pk_fma_f32 v[38:39], v[38:39], v[188:189], v[68:69] op_sel_hi:[1,0,1]
	v_pk_mul_f32 v[68:69], v[70:71], v[194:195] op_sel:[1,0] op_sel_hi:[0,1]
	v_pk_fma_f32 v[68:69], v[70:71], v[192:193], v[68:69] op_sel_hi:[1,0,1]
	v_pk_add_f32 v[70:71], v[4:5], v[6:7]
	v_pk_add_f32 v[4:5], v[4:5], v[6:7] neg_lo:[0,1] neg_hi:[0,1]
	v_pk_add_f32 v[6:7], v[8:9], v[10:11]
	v_pk_add_f32 v[8:9], v[8:9], v[10:11] neg_lo:[0,1] neg_hi:[0,1]
	v_pk_add_f32 v[10:11], v[12:13], v[14:15]
	v_pk_add_f32 v[12:13], v[12:13], v[14:15] neg_lo:[0,1] neg_hi:[0,1]
	v_pk_add_f32 v[14:15], v[20:21], v[22:23]
	v_pk_add_f32 v[20:21], v[20:21], v[22:23] neg_lo:[0,1] neg_hi:[0,1]
	v_pk_add_f32 v[22:23], v[24:25], v[26:27]
	v_pk_add_f32 v[24:25], v[24:25], v[26:27] neg_lo:[0,1] neg_hi:[0,1]
	v_pk_add_f32 v[26:27], v[28:29], v[30:31]
	v_pk_add_f32 v[28:29], v[28:29], v[30:31] neg_lo:[0,1] neg_hi:[0,1]
	v_pk_add_f32 v[30:31], v[32:33], v[34:35]
	v_pk_add_f32 v[32:33], v[32:33], v[34:35] neg_lo:[0,1] neg_hi:[0,1]
	v_pk_add_f32 v[34:35], v[36:37], v[38:39]
	v_pk_add_f32 v[36:37], v[36:37], v[38:39] neg_lo:[0,1] neg_hi:[0,1]
	v_pk_add_f32 v[38:39], v[16:17], v[42:43]
	v_pk_add_f32 v[16:17], v[16:17], v[42:43] neg_lo:[0,1] neg_hi:[0,1]
	v_pk_add_f32 v[42:43], v[44:45], v[46:47]
	v_pk_add_f32 v[44:45], v[44:45], v[46:47] neg_lo:[0,1] neg_hi:[0,1]
	v_pk_add_f32 v[46:47], v[48:49], v[50:51]
	v_pk_add_f32 v[48:49], v[48:49], v[50:51] neg_lo:[0,1] neg_hi:[0,1]
	v_pk_add_f32 v[50:51], v[52:53], v[54:55]
	v_pk_add_f32 v[52:53], v[52:53], v[54:55] neg_lo:[0,1] neg_hi:[0,1]
	v_pk_add_f32 v[54:55], v[40:41], v[58:59]
	v_pk_add_f32 v[40:41], v[40:41], v[58:59] neg_lo:[0,1] neg_hi:[0,1]
	v_pk_add_f32 v[58:59], v[60:61], v[62:63]
	v_pk_add_f32 v[60:61], v[60:61], v[62:63] neg_lo:[0,1] neg_hi:[0,1]
	v_pk_add_f32 v[62:63], v[56:57], v[66:67]
	v_pk_add_f32 v[56:57], v[56:57], v[66:67] neg_lo:[0,1] neg_hi:[0,1]
	v_pk_add_f32 v[66:67], v[64:65], v[68:69]
	v_pk_add_f32 v[64:65], v[64:65], v[68:69] neg_lo:[0,1] neg_hi:[0,1]
	v_pk_add_f32 v[68:69], v[70:71], v[6:7]
	v_pk_add_f32 v[6:7], v[70:71], v[6:7] neg_lo:[0,1] neg_hi:[0,1]
	v_xor_b32_e32 v70, 0x80000000, v9
	v_mov_b32_e32 v71, v8
	v_pk_add_f32 v[8:9], v[4:5], v[70:71]
	v_pk_add_f32 v[4:5], v[4:5], v[70:71] neg_lo:[0,1] neg_hi:[0,1]
	v_pk_add_f32 v[70:71], v[10:11], v[14:15]
	v_pk_add_f32 v[10:11], v[10:11], v[14:15] neg_lo:[0,1] neg_hi:[0,1]
	v_xor_b32_e32 v14, 0x80000000, v21
	v_mov_b32_e32 v15, v20
	v_pk_add_f32 v[20:21], v[12:13], v[14:15]
	v_pk_add_f32 v[12:13], v[12:13], v[14:15] neg_lo:[0,1] neg_hi:[0,1]
	v_pk_add_f32 v[14:15], v[22:23], v[26:27]
	v_pk_add_f32 v[22:23], v[22:23], v[26:27] neg_lo:[0,1] neg_hi:[0,1]
	v_xor_b32_e32 v26, 0x80000000, v29
	v_mov_b32_e32 v27, v28
	v_pk_add_f32 v[28:29], v[24:25], v[26:27]
	v_pk_add_f32 v[24:25], v[24:25], v[26:27] neg_lo:[0,1] neg_hi:[0,1]
	v_pk_add_f32 v[26:27], v[30:31], v[34:35]
	v_pk_add_f32 v[30:31], v[30:31], v[34:35] neg_lo:[0,1] neg_hi:[0,1]
	v_xor_b32_e32 v34, 0x80000000, v37
	v_mov_b32_e32 v35, v36
	v_pk_add_f32 v[36:37], v[32:33], v[34:35]
	v_pk_add_f32 v[32:33], v[32:33], v[34:35] neg_lo:[0,1] neg_hi:[0,1]
	v_pk_add_f32 v[34:35], v[38:39], v[42:43]
	v_pk_add_f32 v[38:39], v[38:39], v[42:43] neg_lo:[0,1] neg_hi:[0,1]
	v_xor_b32_e32 v42, 0x80000000, v45
	v_mov_b32_e32 v43, v44
	v_pk_add_f32 v[44:45], v[16:17], v[42:43]
	v_pk_add_f32 v[16:17], v[16:17], v[42:43] neg_lo:[0,1] neg_hi:[0,1]
	v_pk_add_f32 v[42:43], v[46:47], v[50:51]
	v_pk_add_f32 v[46:47], v[46:47], v[50:51] neg_lo:[0,1] neg_hi:[0,1]
	v_xor_b32_e32 v50, 0x80000000, v53
	v_mov_b32_e32 v51, v52
	v_pk_add_f32 v[52:53], v[48:49], v[50:51]
	v_pk_add_f32 v[48:49], v[48:49], v[50:51] neg_lo:[0,1] neg_hi:[0,1]
	v_pk_add_f32 v[50:51], v[54:55], v[58:59]
	v_pk_add_f32 v[54:55], v[54:55], v[58:59] neg_lo:[0,1] neg_hi:[0,1]
	v_xor_b32_e32 v58, 0x80000000, v61
	v_mov_b32_e32 v59, v60
	v_pk_add_f32 v[60:61], v[40:41], v[58:59]
	v_pk_add_f32 v[40:41], v[40:41], v[58:59] neg_lo:[0,1] neg_hi:[0,1]
	v_pk_add_f32 v[58:59], v[62:63], v[66:67]
	v_pk_add_f32 v[62:63], v[62:63], v[66:67] neg_lo:[0,1] neg_hi:[0,1]
	v_xor_b32_e32 v66, 0x80000000, v65
	v_mov_b32_e32 v67, v64
	v_pk_add_f32 v[64:65], v[56:57], v[66:67]
	v_pk_add_f32 v[56:57], v[56:57], v[66:67] neg_lo:[0,1] neg_hi:[0,1]
	v_pk_add_f32 v[66:67], v[68:69], v[70:71]
	v_pk_add_f32 v[68:69], v[68:69], v[70:71] neg_lo:[0,1] neg_hi:[0,1]
	v_pk_mul_f32 v[70:71], v[20:21], s[78:79]
	s_nop 0
	v_pk_fma_f32 v[20:21], v[20:21], s[0:1], v[70:71] op_sel:[0,0,1] op_sel_hi:[1,0,0]
	s_nop 0
	v_pk_add_f32 v[70:71], v[8:9], v[20:21]
	v_pk_add_f32 v[8:9], v[8:9], v[20:21] neg_lo:[0,1] neg_hi:[0,1]
	v_xor_b32_e32 v20, 0x80000000, v11
	v_mov_b32_e32 v21, v10
	v_pk_add_f32 v[10:11], v[6:7], v[20:21]
	v_pk_add_f32 v[6:7], v[6:7], v[20:21] neg_lo:[0,1] neg_hi:[0,1]
	v_pk_mul_f32 v[20:21], v[12:13], s[78:79]
	s_nop 0
	v_pk_fma_f32 v[12:13], v[12:13], s[0:1], v[20:21] op_sel:[0,0,1] op_sel_hi:[1,0,0] neg_lo:[1,0,0] neg_hi:[1,0,0]
	s_nop 0
	v_pk_add_f32 v[20:21], v[4:5], v[12:13]
	v_pk_add_f32 v[4:5], v[4:5], v[12:13] neg_lo:[0,1] neg_hi:[0,1]
	v_pk_add_f32 v[12:13], v[14:15], v[26:27]
	v_pk_add_f32 v[14:15], v[14:15], v[26:27] neg_lo:[0,1] neg_hi:[0,1]
	v_pk_mul_f32 v[26:27], v[36:37], s[78:79]
	s_nop 0
	v_pk_fma_f32 v[26:27], v[36:37], s[0:1], v[26:27] op_sel:[0,0,1] op_sel_hi:[1,0,0]
	s_nop 0
	v_pk_add_f32 v[36:37], v[28:29], v[26:27]
	v_pk_add_f32 v[26:27], v[28:29], v[26:27] neg_lo:[0,1] neg_hi:[0,1]
	v_xor_b32_e32 v28, 0x80000000, v31
	v_mov_b32_e32 v29, v30
	v_pk_add_f32 v[30:31], v[22:23], v[28:29]
	v_pk_add_f32 v[22:23], v[22:23], v[28:29] neg_lo:[0,1] neg_hi:[0,1]
	v_pk_mul_f32 v[28:29], v[32:33], s[78:79]
	s_nop 0
	v_pk_fma_f32 v[28:29], v[32:33], s[0:1], v[28:29] op_sel:[0,0,1] op_sel_hi:[1,0,0] neg_lo:[1,0,0] neg_hi:[1,0,0]
	s_nop 0
	v_pk_add_f32 v[32:33], v[24:25], v[28:29]
	v_pk_add_f32 v[24:25], v[24:25], v[28:29] neg_lo:[0,1] neg_hi:[0,1]
	v_pk_add_f32 v[28:29], v[34:35], v[42:43]
	v_pk_add_f32 v[34:35], v[34:35], v[42:43] neg_lo:[0,1] neg_hi:[0,1]
	v_pk_mul_f32 v[42:43], v[52:53], s[78:79]
	s_nop 0
	v_pk_fma_f32 v[42:43], v[52:53], s[0:1], v[42:43] op_sel:[0,0,1] op_sel_hi:[1,0,0]
	s_nop 0
	v_pk_add_f32 v[52:53], v[44:45], v[42:43]
	v_pk_add_f32 v[42:43], v[44:45], v[42:43] neg_lo:[0,1] neg_hi:[0,1]
	v_xor_b32_e32 v44, 0x80000000, v47
	v_mov_b32_e32 v45, v46
	v_pk_add_f32 v[46:47], v[38:39], v[44:45]
	v_pk_add_f32 v[38:39], v[38:39], v[44:45] neg_lo:[0,1] neg_hi:[0,1]
	v_pk_mul_f32 v[44:45], v[48:49], s[78:79]
	s_nop 0
	v_pk_fma_f32 v[44:45], v[48:49], s[0:1], v[44:45] op_sel:[0,0,1] op_sel_hi:[1,0,0] neg_lo:[1,0,0] neg_hi:[1,0,0]
	s_nop 0
	v_pk_add_f32 v[48:49], v[16:17], v[44:45]
	v_pk_add_f32 v[16:17], v[16:17], v[44:45] neg_lo:[0,1] neg_hi:[0,1]
	v_pk_add_f32 v[44:45], v[50:51], v[58:59]
	v_pk_add_f32 v[50:51], v[50:51], v[58:59] neg_lo:[0,1] neg_hi:[0,1]
	v_pk_mul_f32 v[58:59], v[64:65], s[78:79]
	s_nop 0
	v_pk_fma_f32 v[58:59], v[64:65], s[0:1], v[58:59] op_sel:[0,0,1] op_sel_hi:[1,0,0]
	s_nop 0
	v_pk_add_f32 v[64:65], v[60:61], v[58:59]
	v_pk_add_f32 v[58:59], v[60:61], v[58:59] neg_lo:[0,1] neg_hi:[0,1]
	v_xor_b32_e32 v60, 0x80000000, v63
	v_mov_b32_e32 v61, v62
	v_pk_add_f32 v[62:63], v[54:55], v[60:61]
	v_pk_add_f32 v[54:55], v[54:55], v[60:61] neg_lo:[0,1] neg_hi:[0,1]
	v_pk_mul_f32 v[60:61], v[56:57], s[78:79]
	s_nop 0
	v_pk_fma_f32 v[56:57], v[56:57], s[0:1], v[60:61] op_sel:[0,0,1] op_sel_hi:[1,0,0] neg_lo:[1,0,0] neg_hi:[1,0,0]
	s_nop 0
	v_pk_add_f32 v[60:61], v[40:41], v[56:57]
	v_pk_add_f32 v[40:41], v[40:41], v[56:57] neg_lo:[0,1] neg_hi:[0,1]
	v_pk_add_f32 v[56:57], v[66:67], v[12:13]
	v_pk_add_f32 v[12:13], v[66:67], v[12:13] neg_lo:[0,1] neg_hi:[0,1]
	v_pk_mul_f32 v[66:67], v[36:37], s[80:81]
	s_nop 0
	v_pk_fma_f32 v[36:37], v[36:37], s[16:17], v[66:67] op_sel:[0,0,1] op_sel_hi:[1,0,0]
	s_nop 0
	v_pk_add_f32 v[66:67], v[70:71], v[36:37]
	v_pk_add_f32 v[36:37], v[70:71], v[36:37] neg_lo:[0,1] neg_hi:[0,1]
	v_pk_mul_f32 v[70:71], v[30:31], s[78:79]
	s_nop 0
	v_pk_fma_f32 v[30:31], v[30:31], s[0:1], v[70:71] op_sel:[0,0,1] op_sel_hi:[1,0,0]
	s_nop 0
	v_pk_add_f32 v[70:71], v[10:11], v[30:31]
	v_pk_add_f32 v[10:11], v[10:11], v[30:31] neg_lo:[0,1] neg_hi:[0,1]
	v_pk_mul_f32 v[30:31], v[32:33], s[16:17]
	s_nop 0
	v_pk_fma_f32 v[30:31], v[32:33], s[82:83], v[30:31] op_sel:[0,0,1] op_sel_hi:[1,0,0]
	s_nop 0
	v_pk_add_f32 v[32:33], v[20:21], v[30:31]
	v_pk_add_f32 v[20:21], v[20:21], v[30:31] neg_lo:[0,1] neg_hi:[0,1]
	v_xor_b32_e32 v30, 0x80000000, v15
	v_mov_b32_e32 v31, v14
	v_pk_add_f32 v[14:15], v[68:69], v[30:31]
	v_pk_add_f32 v[30:31], v[68:69], v[30:31] neg_lo:[0,1] neg_hi:[0,1]
	v_pk_mul_f32 v[68:69], v[26:27], s[16:17]
	s_nop 0
	v_pk_fma_f32 v[26:27], v[26:27], s[82:83], v[68:69] op_sel:[0,0,1] op_sel_hi:[1,0,0] neg_lo:[1,0,0] neg_hi:[1,0,0]
	s_nop 0
	v_pk_add_f32 v[68:69], v[8:9], v[26:27]
	v_pk_add_f32 v[8:9], v[8:9], v[26:27] neg_lo:[0,1] neg_hi:[0,1]
	v_pk_mul_f32 v[26:27], v[22:23], s[78:79]
	s_nop 0
	v_pk_fma_f32 v[22:23], v[22:23], s[0:1], v[26:27] op_sel:[0,0,1] op_sel_hi:[1,0,0] neg_lo:[1,0,0] neg_hi:[1,0,0]
	s_nop 0
	v_pk_add_f32 v[26:27], v[6:7], v[22:23]
	v_pk_add_f32 v[6:7], v[6:7], v[22:23] neg_lo:[0,1] neg_hi:[0,1]
	v_pk_mul_f32 v[22:23], v[24:25], s[80:81]
	s_nop 0
	v_pk_fma_f32 v[22:23], v[24:25], s[16:17], v[22:23] op_sel:[0,0,1] op_sel_hi:[1,0,0] neg_lo:[1,0,0] neg_hi:[1,0,0]
	s_nop 0
	v_pk_add_f32 v[24:25], v[4:5], v[22:23]
	v_pk_add_f32 v[4:5], v[4:5], v[22:23] neg_lo:[0,1] neg_hi:[0,1]
	v_pk_add_f32 v[22:23], v[28:29], v[44:45]
	v_pk_add_f32 v[28:29], v[28:29], v[44:45] neg_lo:[0,1] neg_hi:[0,1]
	v_pk_mul_f32 v[44:45], v[64:65], s[80:81]
	s_nop 0
	v_pk_fma_f32 v[44:45], v[64:65], s[16:17], v[44:45] op_sel:[0,0,1] op_sel_hi:[1,0,0]
	s_nop 0
	v_pk_add_f32 v[64:65], v[52:53], v[44:45]
	v_pk_add_f32 v[44:45], v[52:53], v[44:45] neg_lo:[0,1] neg_hi:[0,1]
	v_pk_mul_f32 v[52:53], v[62:63], s[78:79]
	s_nop 0
	v_pk_fma_f32 v[52:53], v[62:63], s[0:1], v[52:53] op_sel:[0,0,1] op_sel_hi:[1,0,0]
	s_nop 0
	v_pk_add_f32 v[62:63], v[46:47], v[52:53]
	v_pk_add_f32 v[46:47], v[46:47], v[52:53] neg_lo:[0,1] neg_hi:[0,1]
	v_pk_mul_f32 v[52:53], v[60:61], s[16:17]
	s_nop 0
	v_pk_fma_f32 v[52:53], v[60:61], s[82:83], v[52:53] op_sel:[0,0,1] op_sel_hi:[1,0,0]
	s_nop 0
	v_pk_add_f32 v[60:61], v[48:49], v[52:53]
	v_pk_add_f32 v[48:49], v[48:49], v[52:53] neg_lo:[0,1] neg_hi:[0,1]
	v_xor_b32_e32 v52, 0x80000000, v51
	v_mov_b32_e32 v53, v50
	v_pk_add_f32 v[50:51], v[34:35], v[52:53]
	v_pk_add_f32 v[34:35], v[34:35], v[52:53] neg_lo:[0,1] neg_hi:[0,1]
	v_pk_mul_f32 v[52:53], v[58:59], s[16:17]
	s_nop 0
	v_pk_fma_f32 v[52:53], v[58:59], s[82:83], v[52:53] op_sel:[0,0,1] op_sel_hi:[1,0,0] neg_lo:[1,0,0] neg_hi:[1,0,0]
	s_nop 0
	v_pk_add_f32 v[58:59], v[42:43], v[52:53]
	v_pk_add_f32 v[42:43], v[42:43], v[52:53] neg_lo:[0,1] neg_hi:[0,1]
	v_pk_mul_f32 v[52:53], v[54:55], s[78:79]
	s_nop 0
	v_pk_fma_f32 v[52:53], v[54:55], s[0:1], v[52:53] op_sel:[0,0,1] op_sel_hi:[1,0,0] neg_lo:[1,0,0] neg_hi:[1,0,0]
	s_nop 0
	v_pk_add_f32 v[54:55], v[38:39], v[52:53]
	v_pk_add_f32 v[38:39], v[38:39], v[52:53] neg_lo:[0,1] neg_hi:[0,1]
	v_pk_mul_f32 v[52:53], v[40:41], s[80:81]
	s_nop 0
	v_pk_fma_f32 v[40:41], v[40:41], s[16:17], v[52:53] op_sel:[0,0,1] op_sel_hi:[1,0,0] neg_lo:[1,0,0] neg_hi:[1,0,0]
	s_nop 0
	v_pk_add_f32 v[52:53], v[16:17], v[40:41]
	v_pk_add_f32 v[16:17], v[16:17], v[40:41] neg_lo:[0,1] neg_hi:[0,1]
	v_pk_add_f32 v[40:41], v[56:57], v[22:23]
	v_pk_add_f32 v[22:23], v[56:57], v[22:23] neg_lo:[0,1] neg_hi:[0,1]
	v_pk_mul_f32 v[56:57], v[64:65], s[88:89]
	s_nop 0
	v_pk_fma_f32 v[56:57], v[64:65], s[8:9], v[56:57] op_sel:[0,0,1] op_sel_hi:[1,0,0]
	s_mov_b32 s9, s42
	v_pk_add_f32 v[64:65], v[66:67], v[56:57]
	v_pk_add_f32 v[56:57], v[66:67], v[56:57] neg_lo:[0,1] neg_hi:[0,1]
	v_pk_mul_f32 v[66:67], v[62:63], s[80:81]
	s_nop 0
	v_pk_fma_f32 v[62:63], v[62:63], s[16:17], v[66:67] op_sel:[0,0,1] op_sel_hi:[1,0,0]
	s_nop 0
	v_pk_add_f32 v[66:67], v[70:71], v[62:63]
	v_pk_add_f32 v[62:63], v[70:71], v[62:63] neg_lo:[0,1] neg_hi:[0,1]
	v_pk_mul_f32 v[70:71], v[60:61], s[62:63]
	s_nop 0
	v_pk_fma_f32 v[60:61], v[60:61], s[24:25], v[70:71] op_sel:[0,0,1] op_sel_hi:[1,0,0]
	s_mov_b32 s25, s38
	v_pk_add_f32 v[70:71], v[32:33], v[60:61]
	v_pk_add_f32 v[32:33], v[32:33], v[60:61] neg_lo:[0,1] neg_hi:[0,1]
	v_pk_mul_f32 v[60:61], v[50:51], s[78:79]
	s_nop 0
	v_pk_fma_f32 v[50:51], v[50:51], s[0:1], v[60:61] op_sel:[0,0,1] op_sel_hi:[1,0,0]
	s_nop 0
	v_pk_add_f32 v[60:61], v[14:15], v[50:51]
	v_pk_add_f32 v[14:15], v[14:15], v[50:51] neg_lo:[0,1] neg_hi:[0,1]
	v_pk_mul_f32 v[50:51], v[58:59], s[24:25]
	s_nop 0
	v_pk_fma_f32 v[50:51], v[58:59], s[84:85], v[50:51] op_sel:[0,0,1] op_sel_hi:[1,0,0]
	s_nop 0
	v_pk_add_f32 v[58:59], v[68:69], v[50:51]
	v_pk_add_f32 v[50:51], v[68:69], v[50:51] neg_lo:[0,1] neg_hi:[0,1]
	v_pk_mul_f32 v[68:69], v[54:55], s[16:17]
	s_nop 0
	v_pk_fma_f32 v[54:55], v[54:55], s[82:83], v[68:69] op_sel:[0,0,1] op_sel_hi:[1,0,0]
	s_nop 0
	v_pk_add_f32 v[68:69], v[26:27], v[54:55]
	v_pk_add_f32 v[26:27], v[26:27], v[54:55] neg_lo:[0,1] neg_hi:[0,1]
	v_pk_mul_f32 v[54:55], v[52:53], s[8:9]
	s_nop 0
	v_pk_fma_f32 v[52:53], v[52:53], s[86:87], v[54:55] op_sel:[0,0,1] op_sel_hi:[1,0,0]
	s_nop 0
	v_pk_add_f32 v[54:55], v[24:25], v[52:53]
	v_pk_add_f32 v[24:25], v[24:25], v[52:53] neg_lo:[0,1] neg_hi:[0,1]
	v_xor_b32_e32 v52, 0x80000000, v29
	v_mov_b32_e32 v53, v28
	v_pk_add_f32 v[28:29], v[12:13], v[52:53]
	v_pk_add_f32 v[12:13], v[12:13], v[52:53] neg_lo:[0,1] neg_hi:[0,1]
	v_pk_mul_f32 v[52:53], v[44:45], s[8:9]
	s_nop 0
	v_pk_fma_f32 v[44:45], v[44:45], s[86:87], v[52:53] op_sel:[0,0,1] op_sel_hi:[1,0,0] neg_lo:[1,0,0] neg_hi:[1,0,0]
	s_nop 0
	v_pk_add_f32 v[52:53], v[36:37], v[44:45]
	v_pk_add_f32 v[36:37], v[36:37], v[44:45] neg_lo:[0,1] neg_hi:[0,1]
	v_pk_mul_f32 v[44:45], v[46:47], s[16:17]
	s_nop 0
	v_pk_fma_f32 v[44:45], v[46:47], s[82:83], v[44:45] op_sel:[0,0,1] op_sel_hi:[1,0,0] neg_lo:[1,0,0] neg_hi:[1,0,0]
	s_nop 0
	v_pk_add_f32 v[46:47], v[10:11], v[44:45]
	v_pk_add_f32 v[10:11], v[10:11], v[44:45] neg_lo:[0,1] neg_hi:[0,1]
	v_pk_mul_f32 v[44:45], v[48:49], s[24:25]
	s_nop 0
	v_pk_fma_f32 v[44:45], v[48:49], s[84:85], v[44:45] op_sel:[0,0,1] op_sel_hi:[1,0,0] neg_lo:[1,0,0] neg_hi:[1,0,0]
	s_nop 0
	v_pk_add_f32 v[48:49], v[20:21], v[44:45]
	v_pk_add_f32 v[20:21], v[20:21], v[44:45] neg_lo:[0,1] neg_hi:[0,1]
	v_pk_mul_f32 v[44:45], v[34:35], s[78:79]
	s_nop 0
	v_pk_fma_f32 v[34:35], v[34:35], s[0:1], v[44:45] op_sel:[0,0,1] op_sel_hi:[1,0,0] neg_lo:[1,0,0] neg_hi:[1,0,0]
	s_lshl_b64 s[0:1], s[72:73], 2
	v_pk_add_f32 v[44:45], v[30:31], v[34:35]
	v_pk_add_f32 v[30:31], v[30:31], v[34:35] neg_lo:[0,1] neg_hi:[0,1]
	v_pk_mul_f32 v[34:35], v[42:43], s[62:63]
	s_add_u32 s0, s49, s0
	v_pk_fma_f32 v[34:35], v[42:43], s[24:25], v[34:35] op_sel:[0,0,1] op_sel_hi:[1,0,0] neg_lo:[1,0,0] neg_hi:[1,0,0]
	s_addc_u32 s1, s60, s1
	v_pk_add_f32 v[42:43], v[8:9], v[34:35]
	v_pk_add_f32 v[8:9], v[8:9], v[34:35] neg_lo:[0,1] neg_hi:[0,1]
	v_pk_mul_f32 v[34:35], v[38:39], s[80:81]
	s_lshl_b64 s[62:63], s[76:77], 2
	v_pk_fma_f32 v[34:35], v[38:39], s[16:17], v[34:35] op_sel:[0,0,1] op_sel_hi:[1,0,0] neg_lo:[1,0,0] neg_hi:[1,0,0]
	s_add_u32 s62, s22, s62
	v_pk_add_f32 v[38:39], v[6:7], v[34:35]
	v_pk_add_f32 v[6:7], v[6:7], v[34:35] neg_lo:[0,1] neg_hi:[0,1]
	v_pk_mul_f32 v[34:35], v[16:17], s[88:89]
	s_addc_u32 s63, s23, s63
	v_pk_fma_f32 v[16:17], v[16:17], s[8:9], v[34:35] op_sel:[0,0,1] op_sel_hi:[1,0,0] neg_lo:[1,0,0] neg_hi:[1,0,0]
	s_nop 0
	v_pk_add_f32 v[34:35], v[4:5], v[16:17]
	v_pk_add_f32 v[4:5], v[4:5], v[16:17] neg_lo:[0,1] neg_hi:[0,1]
	ds_write2_b64 v2, v[40:41], v[64:65] offset1:16
	ds_write2_b64 v2, v[66:67], v[70:71] offset0:33 offset1:49
	ds_write2_b64 v2, v[60:61], v[58:59] offset0:66 offset1:82
	ds_write2_b64 v2, v[68:69], v[54:55] offset0:99 offset1:115
	ds_write2_b64 v2, v[28:29], v[52:53] offset0:132 offset1:148
	ds_write2_b64 v2, v[46:47], v[48:49] offset0:165 offset1:181
	ds_write2_b64 v2, v[44:45], v[42:43] offset0:198 offset1:214
	ds_write2_b64 v2, v[38:39], v[34:35] offset0:231 offset1:247
	ds_write2_b64 v3, v[22:23], v[56:57] offset0:8 offset1:24
	ds_write2_b64 v3, v[62:63], v[32:33] offset0:41 offset1:57
	ds_write2_b64 v3, v[14:15], v[50:51] offset0:74 offset1:90
	ds_write2_b64 v3, v[26:27], v[24:25] offset0:107 offset1:123
	ds_write2_b64 v3, v[12:13], v[36:37] offset0:140 offset1:156
	ds_write2_b64 v3, v[10:11], v[20:21] offset0:173 offset1:189
	ds_write2_b64 v3, v[30:31], v[8:9] offset0:206 offset1:222
	ds_write2_b64 v3, v[6:7], v[4:5] offset0:239 offset1:255
	s_waitcnt lgkmcnt(0)
	s_barrier
	global_load_dword v30, v206, s[0:1]
	global_load_dword v20, v207, s[0:1]
	v_ashrrev_i32_e32 v2, 31, v210
	v_lshrrev_b32_e32 v2, 22, v2
	v_add_u32_e32 v2, v210, v2
	v_ashrrev_i32_e32 v2, 10, v2
	v_mul_i32_i24_e32 v3, 0x400, v2
	global_load_dword v31, v205, s[0:1]
	global_load_dword v24, v205, s[62:63]
	s_add_u32 s0, s87, s74
	v_sub_u32_e32 v21, v210, v3
	v_lshlrev_b32_e32 v36, 14, v2
	s_addc_u32 s1, s90, s75
	v_ashrrev_i32_e32 v37, 31, v36
	v_lshlrev_b32_e32 v32, 4, v21
	v_lshl_add_u64 v[2:3], v[36:37], 1, s[0:1]
	v_ashrrev_i32_e32 v33, 31, v32
	v_lshl_add_u64 v[2:3], v[32:33], 1, v[2:3]
	global_load_dwordx4 v[10:13], v[2:3], off offset:16 nt
	global_load_dwordx4 v[14:17], v[2:3], off nt
	v_cmp_lt_i32_e32 vcc, 0, v21
	v_mov_b32_e32 v39, 0
	v_mov_b32_e32 v41, 0
	s_and_saveexec_b64 s[72:73], vcc
	s_cbranch_execz .LBB0_505
	global_load_ushort v41, v[2:3], off offset:-2

.LBB0_511:
	s_or_b64 exec, exec, s[0:1]
	v_mov_b32_e32 v25, v210
	s_mov_b32 s72, s37
	v_and_b32_e32 v28, 0x1ff, v25
	v_cvt_f32_u32_e32 v34, v28
	v_lshlrev_b32_e32 v25, 5, v25
	v_and_or_b32 v25, v25, s94, v28
	v_ashrrev_i32_e32 v28, 5, v25
	v_mul_f32_e32 v34, 0x38800000, v34
	v_sin_f32_e32 v43, v34
	v_cos_f32_e32 v42, v34
	v_lshlrev_b32_e32 v25, 3, v25
	v_lshlrev_b32_e32 v28, 3, v28
	s_nop 0
	s_nop 0
	v_pk_mul_f32 v[46:47], v[42:43], v[42:43] op_sel:[1,1] op_sel_hi:[0,1] neg_lo:[0,1]
	v_pk_fma_f32 v[46:47], v[42:43], v[42:43], v[46:47] op_sel_hi:[1,0,1]
	v_add3_u32 v25, 0, v25, v28
	v_pk_mul_f32 v[52:53], v[46:47], v[46:47] op_sel:[1,1] op_sel_hi:[0,1] neg_lo:[0,1]
	v_pk_fma_f32 v[52:53], v[46:47], v[46:47], v[52:53] op_sel_hi:[1,0,1]
	v_add_u32_e32 v28, 0x10800, v25
	v_pk_mul_f32 v[70:71], v[52:53], v[52:53] op_sel:[1,1] op_sel_hi:[0,1] neg_lo:[0,1]
	v_pk_fma_f32 v[70:71], v[52:53], v[52:53], v[70:71] op_sel_hi:[1,0,1]
	v_pk_mul_f32 v[48:49], v[42:43], v[46:47] op_sel:[1,1] op_sel_hi:[1,0] neg_lo:[1,0]
	v_pk_mul_f32 v[86:87], v[52:53], v[70:71] op_sel:[1,1] op_sel_hi:[1,0] neg_lo:[1,0]
	ds_read_b64 v[168:169], v25
	ds_read_b64 v[170:171], v25 offset:4224
	ds_read_b64 v[172:173], v25 offset:8448
	ds_read_b64 v[174:175], v25 offset:12672
	ds_read_b64 v[176:177], v25 offset:16896
	ds_read_b64 v[178:179], v25 offset:21120
	ds_read_b64 v[180:181], v25 offset:25344
	ds_read_b64 v[182:183], v25 offset:29568
	ds_read_b64 v[184:185], v25 offset:33792
	ds_read_b64 v[186:187], v25 offset:38016
	ds_read_b64 v[188:189], v25 offset:42240
	ds_read_b64 v[190:191], v25 offset:46464
	ds_read_b64 v[192:193], v25 offset:50688
	ds_read_b64 v[194:195], v25 offset:54912
	ds_read_b64 v[196:197], v25 offset:59136
	ds_read_b64 v[198:199], v25 offset:63360
	v_pk_fma_f32 v[86:87], v[52:53], v[70:71], v[86:87] op_sel_hi:[0,1,1]
	v_pk_mul_f32 v[102:103], v[52:53], v[86:87] op_sel:[1,1] op_sel_hi:[1,0] neg_lo:[1,0]
	v_add_u32_e32 v34, 0x11880, v25
	v_pk_fma_f32 v[102:103], v[52:53], v[86:87], v[102:103] op_sel_hi:[0,1,1]
	v_pk_mul_f32 v[118:119], v[52:53], v[102:103] op_sel:[1,1] op_sel_hi:[1,0] neg_lo:[1,0]
	v_add_u32_e32 v38, 0x12900, v25
	v_pk_fma_f32 v[118:119], v[52:53], v[102:103], v[118:119] op_sel_hi:[0,1,1]
	v_pk_mul_f32 v[134:135], v[52:53], v[118:119] op_sel:[1,1] op_sel_hi:[1,0] neg_lo:[1,0]
	v_add_u32_e32 v40, 0x13980, v25
	v_pk_fma_f32 v[134:135], v[52:53], v[118:119], v[134:135] op_sel_hi:[0,1,1]
	v_pk_mul_f32 v[152:153], v[52:53], v[134:135] op_sel:[1,1] op_sel_hi:[1,0] neg_lo:[1,0]
	ds_read_b64 v[212:213], v28
	ds_read_b64 v[214:215], v34
	ds_read_b64 v[216:217], v38
	ds_read_b64 v[218:219], v40
	v_add_u32_e32 v28, 0x14a00, v25
	v_pk_fma_f32 v[48:49], v[42:43], v[46:47], v[48:49] op_sel_hi:[0,1,1]
	v_pk_fma_f32 v[152:153], v[52:53], v[134:135], v[152:153] op_sel_hi:[0,1,1]
	v_add_u32_e32 v34, 0x15a80, v25
	v_add_u32_e32 v38, 0x16b00, v25
	v_add_u32_e32 v40, 0x17b80, v25
	ds_read_b64 v[220:221], v28
	ds_read_b64 v[222:223], v34
	ds_read_b64 v[224:225], v38
	ds_read_b64 v[226:227], v40
	v_add_u32_e32 v28, 0x18c00, v25
	v_pk_mul_f32 v[58:59], v[42:43], v[52:53] op_sel:[1,1] op_sel_hi:[1,0] neg_lo:[1,0]
	v_pk_mul_f32 v[74:75], v[42:43], v[70:71] op_sel:[1,1] op_sel_hi:[1,0] neg_lo:[1,0]
	v_pk_mul_f32 v[90:91], v[42:43], v[86:87] op_sel:[1,1] op_sel_hi:[1,0] neg_lo:[1,0]
	v_pk_mul_f32 v[106:107], v[42:43], v[102:103] op_sel:[1,1] op_sel_hi:[1,0] neg_lo:[1,0]
	v_pk_mul_f32 v[122:123], v[42:43], v[118:119] op_sel:[1,1] op_sel_hi:[1,0] neg_lo:[1,0]
	v_pk_mul_f32 v[138:139], v[42:43], v[134:135] op_sel:[1,1] op_sel_hi:[1,0] neg_lo:[1,0]
	v_pk_mul_f32 v[156:157], v[42:43], v[152:153] op_sel:[1,1] op_sel_hi:[1,0] neg_lo:[1,0]
	v_add_u32_e32 v34, 0x19c80, v25
	v_add_u32_e32 v38, 0x1ad00, v25
	v_add_u32_e32 v40, 0x1bd80, v25
	ds_read_b64 v[228:229], v28
	ds_read_b64 v[230:231], v34
	ds_read_b64 v[232:233], v38
	ds_read_b64 v[234:235], v40
	v_add_u32_e32 v28, 0x1ce00, v25
	s_waitcnt lgkmcnt(11)
	v_pk_mul_f32 v[44:45], v[42:43], v[212:213] op_sel:[1,1] op_sel_hi:[1,0] neg_lo:[1,0]
	v_pk_fma_f32 v[58:59], v[42:43], v[52:53], v[58:59] op_sel_hi:[0,1,1]
	v_pk_mul_f32 v[62:63], v[46:47], v[52:53] op_sel:[1,1] op_sel_hi:[1,0] neg_lo:[1,0]
	v_pk_mul_f32 v[66:67], v[52:53], v[48:49] op_sel:[1,1] op_sel_hi:[0,1] neg_lo:[0,1]
	v_pk_fma_f32 v[74:75], v[42:43], v[70:71], v[74:75] op_sel_hi:[0,1,1]
	v_pk_mul_f32 v[78:79], v[46:47], v[70:71] op_sel:[1,1] op_sel_hi:[1,0] neg_lo:[1,0]
	v_pk_fma_f32 v[90:91], v[42:43], v[86:87], v[90:91] op_sel_hi:[0,1,1]
	v_pk_mul_f32 v[94:95], v[46:47], v[86:87] op_sel:[1,1] op_sel_hi:[1,0] neg_lo:[1,0]
	v_pk_fma_f32 v[106:107], v[42:43], v[102:103], v[106:107] op_sel_hi:[0,1,1]
	v_pk_mul_f32 v[110:111], v[46:47], v[102:103] op_sel:[1,1] op_sel_hi:[1,0] neg_lo:[1,0]
	v_pk_fma_f32 v[122:123], v[42:43], v[118:119], v[122:123] op_sel_hi:[0,1,1]
	v_pk_mul_f32 v[126:127], v[46:47], v[118:119] op_sel:[1,1] op_sel_hi:[1,0] neg_lo:[1,0]
	v_pk_fma_f32 v[138:139], v[42:43], v[134:135], v[138:139] op_sel_hi:[0,1,1]
	v_pk_mul_f32 v[142:143], v[46:47], v[134:135] op_sel:[1,1] op_sel_hi:[1,0] neg_lo:[1,0]
	v_pk_fma_f32 v[156:157], v[42:43], v[152:153], v[156:157] op_sel_hi:[0,1,1]
	v_pk_mul_f32 v[160:161], v[46:47], v[152:153] op_sel:[1,1] op_sel_hi:[1,0] neg_lo:[1,0]
	v_add_u32_e32 v34, 0x1de80, v25
	v_add_u32_e32 v38, 0x1ef00, v25
	v_add_u32_e32 v40, 0x1ff80, v25
	ds_read_b64 v[236:237], v28
	ds_read_b64 v[238:239], v34
	ds_read_b64 v[240:241], v38
	ds_read_b64 v[242:243], v40
	v_pk_fma_f32 v[42:43], v[42:43], v[212:213], v[44:45] op_sel_hi:[0,1,1]
	v_pk_mul_f32 v[44:45], v[184:185], v[46:47] op_sel:[1,1] op_sel_hi:[0,1] neg_lo:[0,1]
	v_pk_fma_f32 v[62:63], v[46:47], v[52:53], v[62:63] op_sel_hi:[0,1,1]
	v_pk_fma_f32 v[66:67], v[52:53], v[48:49], v[66:67] op_sel_hi:[1,0,1]
	v_pk_fma_f32 v[78:79], v[46:47], v[70:71], v[78:79] op_sel_hi:[0,1,1]
	v_pk_mul_f32 v[82:83], v[48:49], v[70:71] op_sel:[1,1] op_sel_hi:[1,0] neg_lo:[1,0]
	v_pk_fma_f32 v[94:95], v[46:47], v[86:87], v[94:95] op_sel_hi:[0,1,1]
	v_pk_mul_f32 v[98:99], v[48:49], v[86:87] op_sel:[1,1] op_sel_hi:[1,0] neg_lo:[1,0]
	v_pk_fma_f32 v[110:111], v[46:47], v[102:103], v[110:111] op_sel_hi:[0,1,1]
	v_pk_mul_f32 v[114:115], v[48:49], v[102:103] op_sel:[1,1] op_sel_hi:[1,0] neg_lo:[1,0]
	v_pk_fma_f32 v[126:127], v[46:47], v[118:119], v[126:127] op_sel_hi:[0,1,1]
	v_pk_mul_f32 v[130:131], v[48:49], v[118:119] op_sel:[1,1] op_sel_hi:[1,0] neg_lo:[1,0]
	v_pk_fma_f32 v[142:143], v[46:47], v[134:135], v[142:143] op_sel_hi:[0,1,1]
	v_pk_mul_f32 v[148:149], v[48:49], v[134:135] op_sel:[1,1] op_sel_hi:[1,0] neg_lo:[1,0]
	v_pk_fma_f32 v[160:161], v[46:47], v[152:153], v[160:161] op_sel_hi:[0,1,1]
	v_pk_mul_f32 v[164:165], v[48:49], v[152:153] op_sel:[1,1] op_sel_hi:[1,0] neg_lo:[1,0]
	v_pk_fma_f32 v[44:45], v[184:185], v[46:47], v[44:45] op_sel_hi:[1,0,1]
	s_waitcnt lgkmcnt(7)
	v_pk_mul_f32 v[46:47], v[48:49], v[228:229] op_sel:[1,1] op_sel_hi:[1,0] neg_lo:[1,0]
	v_xor_b32_e32 v60, 0x80000000, v59
	v_xor_b32_e32 v64, 0x80000000, v63
	v_xor_b32_e32 v68, 0x80000000, v67
	v_xor_b32_e32 v72, 0x80000000, v71
	v_pk_fma_f32 v[82:83], v[48:49], v[70:71], v[82:83] op_sel_hi:[0,1,1]
	v_pk_fma_f32 v[98:99], v[48:49], v[86:87], v[98:99] op_sel_hi:[0,1,1]
	v_pk_fma_f32 v[114:115], v[48:49], v[102:103], v[114:115] op_sel_hi:[0,1,1]
	v_pk_fma_f32 v[130:131], v[48:49], v[118:119], v[130:131] op_sel_hi:[0,1,1]
	v_pk_fma_f32 v[148:149], v[48:49], v[134:135], v[148:149] op_sel_hi:[0,1,1]
	v_pk_fma_f32 v[164:165], v[48:49], v[152:153], v[164:165] op_sel_hi:[0,1,1]
	v_mov_b32_e32 v61, v59
	v_mov_b32_e32 v65, v63
	v_mov_b32_e32 v69, v67
	v_mov_b32_e32 v73, v71
	v_pk_fma_f32 v[46:47], v[48:49], v[228:229], v[46:47] op_sel_hi:[0,1,1]
	v_pk_mul_f32 v[48:49], v[176:177], v[52:53] op_sel:[1,1] op_sel_hi:[0,1] neg_lo:[0,1]
	v_xor_b32_e32 v76, 0x80000000, v75
	v_xor_b32_e32 v80, 0x80000000, v79
	v_xor_b32_e32 v84, 0x80000000, v83
	v_xor_b32_e32 v88, 0x80000000, v87
	v_xor_b32_e32 v92, 0x80000000, v91
	v_xor_b32_e32 v96, 0x80000000, v95
	v_xor_b32_e32 v100, 0x80000000, v99
	v_xor_b32_e32 v104, 0x80000000, v103
	v_xor_b32_e32 v136, 0x80000000, v135
	v_mov_b32_e32 v77, v75
	v_mov_b32_e32 v81, v79
	v_mov_b32_e32 v85, v83
	v_mov_b32_e32 v89, v87
	v_mov_b32_e32 v93, v91
	v_mov_b32_e32 v97, v95
	v_mov_b32_e32 v101, v99
	v_mov_b32_e32 v105, v103
	v_mov_b32_e32 v137, v135
	v_pk_fma_f32 v[48:49], v[176:177], v[52:53], v[48:49] op_sel_hi:[1,0,1]
	v_pk_mul_f32 v[50:51], v[60:61], v[220:221] op_sel:[0,1] op_sel_hi:[1,0]
	v_pk_mul_f32 v[52:53], v[192:193], v[64:65] op_sel:[1,0] op_sel_hi:[0,1]
	s_waitcnt lgkmcnt(3)
	v_pk_mul_f32 v[54:55], v[68:69], v[236:237] op_sel:[0,1] op_sel_hi:[1,0]
	v_pk_mul_f32 v[56:57], v[172:173], v[72:73] op_sel:[1,0] op_sel_hi:[0,1]
	v_xor_b32_e32 v108, 0x80000000, v107
	v_xor_b32_e32 v112, 0x80000000, v111
	v_xor_b32_e32 v116, 0x80000000, v115
	v_xor_b32_e32 v120, 0x80000000, v119
	v_xor_b32_e32 v124, 0x80000000, v123
	v_xor_b32_e32 v128, 0x80000000, v127
	v_xor_b32_e32 v132, 0x80000000, v131
	v_xor_b32_e32 v140, 0x80000000, v139
	v_xor_b32_e32 v144, 0x80000000, v143
	v_xor_b32_e32 v150, 0x80000000, v149
	v_xor_b32_e32 v154, 0x80000000, v153
	v_xor_b32_e32 v158, 0x80000000, v157
	v_xor_b32_e32 v162, 0x80000000, v161
	v_xor_b32_e32 v166, 0x80000000, v165
	v_mov_b32_e32 v109, v107
	v_mov_b32_e32 v113, v111
	v_mov_b32_e32 v117, v115
	v_mov_b32_e32 v121, v119
	v_mov_b32_e32 v125, v123
	v_mov_b32_e32 v129, v127
	v_mov_b32_e32 v133, v131
	v_mov_b32_e32 v141, v139
	v_mov_b32_e32 v145, v143
	v_mov_b32_e32 v151, v149
	v_mov_b32_e32 v155, v153
	v_mov_b32_e32 v159, v157
	v_mov_b32_e32 v163, v161
	v_mov_b32_e32 v167, v165
	v_pk_fma_f32 v[50:51], v[58:59], v[220:221], v[50:51] op_sel_hi:[0,1,1]
	v_pk_fma_f32 v[52:53], v[192:193], v[62:63], v[52:53] op_sel_hi:[1,0,1]
	v_pk_fma_f32 v[54:55], v[66:67], v[236:237], v[54:55] op_sel_hi:[0,1,1]
	v_pk_fma_f32 v[56:57], v[172:173], v[70:71], v[56:57] op_sel_hi:[1,0,1]
	v_pk_mul_f32 v[58:59], v[216:217], v[76:77] op_sel:[1,0] op_sel_hi:[0,1]
	v_pk_mul_f32 v[60:61], v[188:189], v[80:81] op_sel:[1,0] op_sel_hi:[0,1]
	v_pk_mul_f32 v[62:63], v[84:85], v[232:233] op_sel:[0,1] op_sel_hi:[1,0]
	v_pk_mul_f32 v[64:65], v[180:181], v[88:89] op_sel:[1,0] op_sel_hi:[0,1]
	v_pk_mul_f32 v[66:67], v[224:225], v[92:93] op_sel:[1,0] op_sel_hi:[0,1]
	v_pk_mul_f32 v[68:69], v[196:197], v[96:97] op_sel:[1,0] op_sel_hi:[0,1]
	s_waitcnt lgkmcnt(1)
	v_pk_mul_f32 v[70:71], v[100:101], v[240:241] op_sel:[0,1] op_sel_hi:[1,0]
	v_pk_mul_f32 v[72:73], v[170:171], v[104:105] op_sel:[1,0] op_sel_hi:[0,1]
	v_pk_mul_f32 v[88:89], v[174:175], v[136:137] op_sel:[1,0] op_sel_hi:[0,1]
	v_pk_fma_f32 v[58:59], v[216:217], v[74:75], v[58:59] op_sel_hi:[1,0,1]
	v_pk_fma_f32 v[60:61], v[188:189], v[78:79], v[60:61] op_sel_hi:[1,0,1]
	v_pk_fma_f32 v[62:63], v[82:83], v[232:233], v[62:63] op_sel_hi:[0,1,1]
	v_pk_fma_f32 v[64:65], v[180:181], v[86:87], v[64:65] op_sel_hi:[1,0,1]
	v_pk_fma_f32 v[66:67], v[224:225], v[90:91], v[66:67] op_sel_hi:[1,0,1]
	v_pk_fma_f32 v[68:69], v[196:197], v[94:95], v[68:69] op_sel_hi:[1,0,1]
	v_pk_fma_f32 v[70:71], v[98:99], v[240:241], v[70:71] op_sel_hi:[0,1,1]
	v_pk_fma_f32 v[72:73], v[170:171], v[102:103], v[72:73] op_sel_hi:[1,0,1]
	v_pk_mul_f32 v[74:75], v[214:215], v[108:109] op_sel:[1,0] op_sel_hi:[0,1]
	v_pk_mul_f32 v[76:77], v[186:187], v[112:113] op_sel:[1,0] op_sel_hi:[0,1]
	v_pk_mul_f32 v[78:79], v[230:231], v[116:117] op_sel:[1,0] op_sel_hi:[0,1]
	v_pk_mul_f32 v[80:81], v[178:179], v[120:121] op_sel:[1,0] op_sel_hi:[0,1]
	v_pk_mul_f32 v[82:83], v[222:223], v[124:125] op_sel:[1,0] op_sel_hi:[0,1]
	v_pk_mul_f32 v[84:85], v[194:195], v[128:129] op_sel:[1,0] op_sel_hi:[0,1]
	v_pk_mul_f32 v[86:87], v[132:133], v[238:239] op_sel:[0,1] op_sel_hi:[1,0]
	v_pk_fma_f32 v[88:89], v[174:175], v[134:135], v[88:89] op_sel_hi:[1,0,1]
	v_pk_mul_f32 v[90:91], v[218:219], v[140:141] op_sel:[1,0] op_sel_hi:[0,1]
	v_pk_mul_f32 v[92:93], v[190:191], v[144:145] op_sel:[1,0] op_sel_hi:[0,1]
	v_pk_mul_f32 v[94:95], v[234:235], v[150:151] op_sel:[1,0] op_sel_hi:[0,1]
	v_pk_mul_f32 v[96:97], v[182:183], v[154:155] op_sel:[1,0] op_sel_hi:[0,1]
	v_pk_mul_f32 v[98:99], v[226:227], v[158:159] op_sel:[1,0] op_sel_hi:[0,1]
	v_pk_mul_f32 v[100:101], v[198:199], v[162:163] op_sel:[1,0] op_sel_hi:[0,1]
	s_waitcnt lgkmcnt(0)
	v_pk_mul_f32 v[102:103], v[242:243], v[166:167] op_sel:[1,0] op_sel_hi:[0,1]
	v_pk_fma_f32 v[74:75], v[214:215], v[106:107], v[74:75] op_sel_hi:[1,0,1]
	v_pk_fma_f32 v[76:77], v[186:187], v[110:111], v[76:77] op_sel_hi:[1,0,1]
	v_pk_fma_f32 v[78:79], v[230:231], v[114:115], v[78:79] op_sel_hi:[1,0,1]
	v_pk_fma_f32 v[80:81], v[178:179], v[118:119], v[80:81] op_sel_hi:[1,0,1]
	v_pk_fma_f32 v[82:83], v[222:223], v[122:123], v[82:83] op_sel_hi:[1,0,1]
	v_pk_fma_f32 v[84:85], v[194:195], v[126:127], v[84:85] op_sel_hi:[1,0,1]
	v_pk_fma_f32 v[86:87], v[130:131], v[238:239], v[86:87] op_sel_hi:[0,1,1]
	v_pk_fma_f32 v[90:91], v[218:219], v[138:139], v[90:91] op_sel_hi:[1,0,1]
	v_pk_fma_f32 v[92:93], v[190:191], v[142:143], v[92:93] op_sel_hi:[1,0,1]
	v_pk_fma_f32 v[94:95], v[234:235], v[148:149], v[94:95] op_sel_hi:[1,0,1]
	v_pk_fma_f32 v[96:97], v[182:183], v[152:153], v[96:97] op_sel_hi:[1,0,1]
	v_pk_fma_f32 v[98:99], v[226:227], v[156:157], v[98:99] op_sel_hi:[1,0,1]
	v_pk_fma_f32 v[100:101], v[198:199], v[160:161], v[100:101] op_sel_hi:[1,0,1]
	v_pk_fma_f32 v[102:103], v[242:243], v[164:165], v[102:103] op_sel_hi:[1,0,1]
	v_pk_add_f32 v[104:105], v[168:169], v[72:73]
	v_pk_add_f32 v[106:107], v[56:57], v[88:89]
	v_pk_add_f32 v[56:57], v[56:57], v[88:89] neg_lo:[0,1] neg_hi:[0,1]
	v_pk_add_f32 v[72:73], v[168:169], v[72:73] neg_lo:[0,1] neg_hi:[0,1]
	v_pk_add_f32 v[88:89], v[48:49], v[80:81]
	v_pk_add_f32 v[48:49], v[48:49], v[80:81] neg_lo:[0,1] neg_hi:[0,1]
	v_pk_add_f32 v[80:81], v[64:65], v[96:97]
	v_pk_add_f32 v[64:65], v[64:65], v[96:97] neg_lo:[0,1] neg_hi:[0,1]
	v_pk_add_f32 v[96:97], v[44:45], v[76:77]
	v_pk_add_f32 v[44:45], v[44:45], v[76:77] neg_lo:[0,1] neg_hi:[0,1]
	v_pk_add_f32 v[76:77], v[60:61], v[92:93]
	v_pk_add_f32 v[60:61], v[60:61], v[92:93] neg_lo:[0,1] neg_hi:[0,1]
	v_pk_add_f32 v[92:93], v[52:53], v[84:85]
	v_pk_add_f32 v[52:53], v[52:53], v[84:85] neg_lo:[0,1] neg_hi:[0,1]
	v_pk_add_f32 v[84:85], v[68:69], v[100:101]
	v_pk_add_f32 v[68:69], v[68:69], v[100:101] neg_lo:[0,1] neg_hi:[0,1]
	v_pk_add_f32 v[100:101], v[42:43], v[74:75]
	v_pk_add_f32 v[42:43], v[42:43], v[74:75] neg_lo:[0,1] neg_hi:[0,1]
	v_pk_add_f32 v[74:75], v[58:59], v[90:91]
	v_pk_add_f32 v[58:59], v[58:59], v[90:91] neg_lo:[0,1] neg_hi:[0,1]
	v_pk_add_f32 v[90:91], v[50:51], v[82:83]
	v_pk_add_f32 v[50:51], v[50:51], v[82:83] neg_lo:[0,1] neg_hi:[0,1]
	v_pk_add_f32 v[82:83], v[66:67], v[98:99]
	v_pk_add_f32 v[66:67], v[66:67], v[98:99] neg_lo:[0,1] neg_hi:[0,1]
	v_pk_add_f32 v[98:99], v[46:47], v[78:79]
	v_pk_add_f32 v[46:47], v[46:47], v[78:79] neg_lo:[0,1] neg_hi:[0,1]
	v_pk_add_f32 v[78:79], v[62:63], v[94:95]
	v_pk_add_f32 v[62:63], v[62:63], v[94:95] neg_lo:[0,1] neg_hi:[0,1]
	v_pk_add_f32 v[94:95], v[54:55], v[86:87]
	v_pk_add_f32 v[54:55], v[54:55], v[86:87] neg_lo:[0,1] neg_hi:[0,1]
	v_pk_add_f32 v[86:87], v[70:71], v[102:103]
	v_pk_add_f32 v[70:71], v[70:71], v[102:103] neg_lo:[0,1] neg_hi:[0,1]
	v_pk_add_f32 v[102:103], v[104:105], v[106:107]
	v_pk_add_f32 v[104:105], v[104:105], v[106:107] neg_lo:[0,1] neg_hi:[0,1]
	v_xor_b32_e32 v106, 0x80000000, v57
	v_mov_b32_e32 v107, v56
	v_pk_add_f32 v[56:57], v[72:73], v[106:107]
	v_pk_add_f32 v[72:73], v[72:73], v[106:107] neg_lo:[0,1] neg_hi:[0,1]
	v_pk_add_f32 v[106:107], v[88:89], v[80:81]
	v_pk_add_f32 v[80:81], v[88:89], v[80:81] neg_lo:[0,1] neg_hi:[0,1]
	v_xor_b32_e32 v88, 0x80000000, v65
	v_mov_b32_e32 v89, v64
	v_pk_add_f32 v[64:65], v[48:49], v[88:89]
	v_pk_add_f32 v[48:49], v[48:49], v[88:89] neg_lo:[0,1] neg_hi:[0,1]
	v_pk_add_f32 v[88:89], v[96:97], v[76:77]
	v_pk_add_f32 v[76:77], v[96:97], v[76:77] neg_lo:[0,1] neg_hi:[0,1]
	v_xor_b32_e32 v96, 0x80000000, v61
	v_mov_b32_e32 v97, v60
	v_pk_add_f32 v[60:61], v[44:45], v[96:97]
	v_pk_add_f32 v[44:45], v[44:45], v[96:97] neg_lo:[0,1] neg_hi:[0,1]
	v_pk_add_f32 v[96:97], v[92:93], v[84:85]
	v_pk_add_f32 v[84:85], v[92:93], v[84:85] neg_lo:[0,1] neg_hi:[0,1]
	v_xor_b32_e32 v92, 0x80000000, v69
	v_mov_b32_e32 v93, v68
	v_pk_add_f32 v[68:69], v[52:53], v[92:93]
	v_pk_add_f32 v[52:53], v[52:53], v[92:93] neg_lo:[0,1] neg_hi:[0,1]
	v_pk_add_f32 v[92:93], v[100:101], v[74:75]
	v_pk_add_f32 v[74:75], v[100:101], v[74:75] neg_lo:[0,1] neg_hi:[0,1]
	v_xor_b32_e32 v100, 0x80000000, v59
	v_mov_b32_e32 v101, v58
	v_pk_add_f32 v[58:59], v[42:43], v[100:101]
	v_pk_add_f32 v[42:43], v[42:43], v[100:101] neg_lo:[0,1] neg_hi:[0,1]
	v_pk_add_f32 v[100:101], v[90:91], v[82:83]
	v_pk_add_f32 v[82:83], v[90:91], v[82:83] neg_lo:[0,1] neg_hi:[0,1]
	v_xor_b32_e32 v90, 0x80000000, v67
	v_mov_b32_e32 v91, v66
	v_pk_add_f32 v[66:67], v[50:51], v[90:91]
	v_pk_add_f32 v[50:51], v[50:51], v[90:91] neg_lo:[0,1] neg_hi:[0,1]
	v_pk_add_f32 v[90:91], v[98:99], v[78:79]
	v_pk_add_f32 v[78:79], v[98:99], v[78:79] neg_lo:[0,1] neg_hi:[0,1]
	v_xor_b32_e32 v98, 0x80000000, v63
	v_mov_b32_e32 v99, v62
	v_pk_add_f32 v[62:63], v[46:47], v[98:99]
	v_pk_add_f32 v[46:47], v[46:47], v[98:99] neg_lo:[0,1] neg_hi:[0,1]
	v_pk_add_f32 v[98:99], v[94:95], v[86:87]
	v_pk_add_f32 v[86:87], v[94:95], v[86:87] neg_lo:[0,1] neg_hi:[0,1]
	v_xor_b32_e32 v94, 0x80000000, v71
	v_mov_b32_e32 v95, v70
	s_mov_b32 s73, s36
	v_pk_add_f32 v[70:71], v[54:55], v[94:95]
	v_pk_add_f32 v[54:55], v[54:55], v[94:95] neg_lo:[0,1] neg_hi:[0,1]
	v_pk_add_f32 v[94:95], v[102:103], v[106:107]
	v_pk_add_f32 v[102:103], v[102:103], v[106:107] neg_lo:[0,1] neg_hi:[0,1]
	s_mov_b32 s0, s37
	v_pk_mul_f32 v[106:107], v[64:65], s[72:73]
	s_mov_b32 s74, s19
	v_pk_fma_f32 v[64:65], v[64:65], s[0:1], v[106:107] op_sel:[0,0,1] op_sel_hi:[1,0,0]
	s_mov_b32 s75, s18
	v_pk_add_f32 v[106:107], v[56:57], v[64:65]
	v_pk_add_f32 v[56:57], v[56:57], v[64:65] neg_lo:[0,1] neg_hi:[0,1]
	v_xor_b32_e32 v64, 0x80000000, v81
	v_mov_b32_e32 v65, v80
	v_pk_add_f32 v[80:81], v[104:105], v[64:65]
	v_pk_add_f32 v[64:65], v[104:105], v[64:65] neg_lo:[0,1] neg_hi:[0,1]
	v_pk_mul_f32 v[104:105], v[48:49], s[72:73]
	s_mov_b32 s76, s19
	v_pk_fma_f32 v[48:49], v[48:49], s[0:1], v[104:105] op_sel:[0,0,1] op_sel_hi:[1,0,0] neg_lo:[1,0,0] neg_hi:[1,0,0]
	s_mov_b32 s62, s11
	v_pk_add_f32 v[104:105], v[72:73], v[48:49]
	v_pk_add_f32 v[48:49], v[72:73], v[48:49] neg_lo:[0,1] neg_hi:[0,1]
	v_pk_add_f32 v[72:73], v[88:89], v[96:97]
	v_pk_add_f32 v[88:89], v[88:89], v[96:97] neg_lo:[0,1] neg_hi:[0,1]
	v_pk_mul_f32 v[96:97], v[68:69], s[72:73]
	s_mov_b32 s63, s10
	v_pk_fma_f32 v[68:69], v[68:69], s[0:1], v[96:97] op_sel:[0,0,1] op_sel_hi:[1,0,0]
	s_mov_b32 s78, s27
	v_pk_add_f32 v[96:97], v[60:61], v[68:69]
	v_pk_add_f32 v[60:61], v[60:61], v[68:69] neg_lo:[0,1] neg_hi:[0,1]
	v_xor_b32_e32 v68, 0x80000000, v85
	v_mov_b32_e32 v69, v84
	v_pk_add_f32 v[84:85], v[76:77], v[68:69]
	v_pk_add_f32 v[68:69], v[76:77], v[68:69] neg_lo:[0,1] neg_hi:[0,1]
	v_pk_mul_f32 v[76:77], v[52:53], s[72:73]
	v_pk_mul_f32 v[108:109], v[96:97], s[74:75]
	v_pk_fma_f32 v[52:53], v[52:53], s[0:1], v[76:77] op_sel:[0,0,1] op_sel_hi:[1,0,0] neg_lo:[1,0,0] neg_hi:[1,0,0]
	v_pk_fma_f32 v[96:97], v[96:97], s[16:17], v[108:109] op_sel:[0,0,1] op_sel_hi:[1,0,0]
	v_pk_add_f32 v[76:77], v[44:45], v[52:53]
	v_pk_add_f32 v[44:45], v[44:45], v[52:53] neg_lo:[0,1] neg_hi:[0,1]
	v_pk_add_f32 v[52:53], v[92:93], v[100:101]
	v_pk_add_f32 v[92:93], v[92:93], v[100:101] neg_lo:[0,1] neg_hi:[0,1]
	v_pk_mul_f32 v[100:101], v[66:67], s[72:73]
	s_mov_b32 s17, s40
	v_pk_fma_f32 v[66:67], v[66:67], s[0:1], v[100:101] op_sel:[0,0,1] op_sel_hi:[1,0,0]
	v_pk_add_f32 v[108:109], v[106:107], v[96:97]
	v_pk_add_f32 v[100:101], v[58:59], v[66:67]
	v_pk_add_f32 v[58:59], v[58:59], v[66:67] neg_lo:[0,1] neg_hi:[0,1]
	v_xor_b32_e32 v66, 0x80000000, v83
	v_mov_b32_e32 v67, v82
	v_pk_add_f32 v[82:83], v[74:75], v[66:67]
	v_pk_add_f32 v[66:67], v[74:75], v[66:67] neg_lo:[0,1] neg_hi:[0,1]
	v_pk_mul_f32 v[74:75], v[50:51], s[72:73]
	v_pk_add_f32 v[96:97], v[106:107], v[96:97] neg_lo:[0,1] neg_hi:[0,1]
	v_pk_fma_f32 v[50:51], v[50:51], s[0:1], v[74:75] op_sel:[0,0,1] op_sel_hi:[1,0,0] neg_lo:[1,0,0] neg_hi:[1,0,0]
	v_pk_mul_f32 v[106:107], v[84:85], s[72:73]
	v_pk_add_f32 v[74:75], v[42:43], v[50:51]
	v_pk_add_f32 v[42:43], v[42:43], v[50:51] neg_lo:[0,1] neg_hi:[0,1]
	v_pk_add_f32 v[50:51], v[90:91], v[98:99]
	v_pk_add_f32 v[90:91], v[90:91], v[98:99] neg_lo:[0,1] neg_hi:[0,1]
	v_pk_mul_f32 v[98:99], v[70:71], s[72:73]
	v_pk_fma_f32 v[84:85], v[84:85], s[0:1], v[106:107] op_sel:[0,0,1] op_sel_hi:[1,0,0]
	v_pk_fma_f32 v[70:71], v[70:71], s[0:1], v[98:99] op_sel:[0,0,1] op_sel_hi:[1,0,0]
	v_pk_add_f32 v[106:107], v[80:81], v[84:85]
	v_pk_add_f32 v[98:99], v[62:63], v[70:71]
	v_pk_add_f32 v[62:63], v[62:63], v[70:71] neg_lo:[0,1] neg_hi:[0,1]
	v_xor_b32_e32 v70, 0x80000000, v87
	v_mov_b32_e32 v71, v86
	v_pk_mul_f32 v[110:111], v[98:99], s[74:75]
	v_pk_add_f32 v[86:87], v[78:79], v[70:71]
	v_pk_add_f32 v[70:71], v[78:79], v[70:71] neg_lo:[0,1] neg_hi:[0,1]
	v_pk_mul_f32 v[78:79], v[54:55], s[72:73]
	v_pk_fma_f32 v[98:99], v[98:99], s[16:17], v[110:111] op_sel:[0,0,1] op_sel_hi:[1,0,0]
	v_pk_fma_f32 v[54:55], v[54:55], s[0:1], v[78:79] op_sel:[0,0,1] op_sel_hi:[1,0,0] neg_lo:[1,0,0] neg_hi:[1,0,0]
	v_pk_add_f32 v[110:111], v[100:101], v[98:99]
	v_pk_add_f32 v[98:99], v[100:101], v[98:99] neg_lo:[0,1] neg_hi:[0,1]
	v_pk_mul_f32 v[100:101], v[86:87], s[72:73]
	v_pk_add_f32 v[78:79], v[46:47], v[54:55]
	v_pk_fma_f32 v[86:87], v[86:87], s[0:1], v[100:101] op_sel:[0,0,1] op_sel_hi:[1,0,0]
	v_pk_add_f32 v[46:47], v[46:47], v[54:55] neg_lo:[0,1] neg_hi:[0,1]
	v_pk_add_f32 v[100:101], v[82:83], v[86:87]
	v_pk_add_f32 v[82:83], v[82:83], v[86:87] neg_lo:[0,1] neg_hi:[0,1]
	v_pk_mul_f32 v[86:87], v[78:79], s[16:17]
	v_pk_add_f32 v[80:81], v[80:81], v[84:85] neg_lo:[0,1] neg_hi:[0,1]
	v_pk_fma_f32 v[78:79], v[78:79], s[76:77], v[86:87] op_sel:[0,0,1] op_sel_hi:[1,0,0]
	v_pk_mul_f32 v[84:85], v[76:77], s[16:17]
	v_pk_add_f32 v[86:87], v[74:75], v[78:79]
	v_pk_add_f32 v[74:75], v[74:75], v[78:79] neg_lo:[0,1] neg_hi:[0,1]
	v_xor_b32_e32 v78, 0x80000000, v91
	v_mov_b32_e32 v79, v90
	v_pk_add_f32 v[90:91], v[92:93], v[78:79]
	v_pk_add_f32 v[78:79], v[92:93], v[78:79] neg_lo:[0,1] neg_hi:[0,1]
	v_pk_mul_f32 v[92:93], v[62:63], s[16:17]
	v_pk_fma_f32 v[76:77], v[76:77], s[76:77], v[84:85] op_sel:[0,0,1] op_sel_hi:[1,0,0]
	v_pk_fma_f32 v[62:63], v[62:63], s[76:77], v[92:93] op_sel:[0,0,1] op_sel_hi:[1,0,0] neg_lo:[1,0,0] neg_hi:[1,0,0]
	v_pk_add_f32 v[84:85], v[104:105], v[76:77]
	v_pk_add_f32 v[92:93], v[58:59], v[62:63]
	v_pk_add_f32 v[58:59], v[58:59], v[62:63] neg_lo:[0,1] neg_hi:[0,1]
	v_pk_mul_f32 v[62:63], v[70:71], s[72:73]
	v_pk_add_f32 v[76:77], v[104:105], v[76:77] neg_lo:[0,1] neg_hi:[0,1]
	v_pk_fma_f32 v[62:63], v[70:71], s[0:1], v[62:63] op_sel:[0,0,1] op_sel_hi:[1,0,0] neg_lo:[1,0,0] neg_hi:[1,0,0]
	v_xor_b32_e32 v104, 0x80000000, v89
	v_pk_add_f32 v[70:71], v[66:67], v[62:63]
	v_pk_add_f32 v[62:63], v[66:67], v[62:63] neg_lo:[0,1] neg_hi:[0,1]
	v_pk_mul_f32 v[66:67], v[46:47], s[74:75]
	v_mov_b32_e32 v105, v88
	v_pk_fma_f32 v[46:47], v[46:47], s[16:17], v[66:67] op_sel:[0,0,1] op_sel_hi:[1,0,0] neg_lo:[1,0,0] neg_hi:[1,0,0]
	s_mov_b32 s79, s26
	v_pk_add_f32 v[66:67], v[42:43], v[46:47]
	v_pk_add_f32 v[42:43], v[42:43], v[46:47] neg_lo:[0,1] neg_hi:[0,1]
	v_pk_mul_f32 v[46:47], v[110:111], s[62:63]
	v_pk_add_f32 v[88:89], v[102:103], v[104:105]
	v_pk_fma_f32 v[46:47], v[110:111], s[8:9], v[46:47] op_sel:[0,0,1] op_sel_hi:[1,0,0]
	v_pk_add_f32 v[102:103], v[102:103], v[104:105] neg_lo:[0,1] neg_hi:[0,1]
	v_pk_add_f32 v[46:47], v[108:109], v[46:47]
	v_pk_mul_f32 v[108:109], v[100:101], s[74:75]
	v_pk_mul_f32 v[104:105], v[60:61], s[16:17]
	v_pk_fma_f32 v[100:101], v[100:101], s[16:17], v[108:109] op_sel:[0,0,1] op_sel_hi:[1,0,0]
	v_pk_fma_f32 v[60:61], v[60:61], s[76:77], v[104:105] op_sel:[0,0,1] op_sel_hi:[1,0,0] neg_lo:[1,0,0] neg_hi:[1,0,0]
	v_pk_add_f32 v[100:101], v[106:107], v[100:101]
	v_pk_mul_f32 v[106:107], v[86:87], s[78:79]
	v_pk_add_f32 v[104:105], v[56:57], v[60:61]
	v_pk_fma_f32 v[86:87], v[86:87], s[24:25], v[106:107] op_sel:[0,0,1] op_sel_hi:[1,0,0]
	v_pk_add_f32 v[56:57], v[56:57], v[60:61] neg_lo:[0,1] neg_hi:[0,1]
	v_pk_mul_f32 v[60:61], v[68:69], s[72:73]
	v_pk_add_f32 v[84:85], v[84:85], v[86:87]
	v_pk_mul_f32 v[86:87], v[90:91], s[72:73]
	v_pk_fma_f32 v[60:61], v[68:69], s[0:1], v[60:61] op_sel:[0,0,1] op_sel_hi:[1,0,0] neg_lo:[1,0,0] neg_hi:[1,0,0]
	v_pk_fma_f32 v[86:87], v[90:91], s[0:1], v[86:87] op_sel:[0,0,1] op_sel_hi:[1,0,0]
	v_pk_mul_f32 v[90:91], v[70:71], s[16:17]
	v_pk_add_f32 v[68:69], v[64:65], v[60:61]
	v_pk_fma_f32 v[70:71], v[70:71], s[76:77], v[90:91] op_sel:[0,0,1] op_sel_hi:[1,0,0]
	s_mov_b32 s9, s42
	s_mov_b32 s25, s38
	v_pk_add_f32 v[68:69], v[68:69], v[70:71]
	s_mov_b32 s82, s11
	v_pk_mul_f32 v[70:71], v[66:67], s[8:9]
	s_mov_b32 s80, s27
	v_pk_fma_f32 v[66:67], v[66:67], s[82:83], v[70:71] op_sel:[0,0,1] op_sel_hi:[1,0,0]
	v_pk_mul_f32 v[70:71], v[74:75], s[24:25]
	v_pk_add_f32 v[60:61], v[64:65], v[60:61] neg_lo:[0,1] neg_hi:[0,1]
	v_pk_fma_f32 v[70:71], v[74:75], s[80:81], v[70:71] op_sel:[0,0,1] op_sel_hi:[1,0,0] neg_lo:[1,0,0] neg_hi:[1,0,0]
	v_pk_mul_f32 v[64:65], v[44:45], s[74:75]
	v_pk_add_f32 v[70:71], v[76:77], v[70:71]
	v_pk_mul_f32 v[76:77], v[58:59], s[78:79]
	v_pk_fma_f32 v[44:45], v[44:45], s[16:17], v[64:65] op_sel:[0,0,1] op_sel_hi:[1,0,0] neg_lo:[1,0,0] neg_hi:[1,0,0]
	v_pk_fma_f32 v[58:59], v[58:59], s[24:25], v[76:77] op_sel:[0,0,1] op_sel_hi:[1,0,0] neg_lo:[1,0,0] neg_hi:[1,0,0]
	v_pk_add_f32 v[64:65], v[48:49], v[44:45]
	v_pk_add_f32 v[56:57], v[56:57], v[58:59]
	v_pk_mul_f32 v[58:59], v[62:63], s[74:75]
	v_pk_add_f32 v[44:45], v[48:49], v[44:45] neg_lo:[0,1] neg_hi:[0,1]
	v_pk_fma_f32 v[58:59], v[62:63], s[16:17], v[58:59] op_sel:[0,0,1] op_sel_hi:[1,0,0] neg_lo:[1,0,0] neg_hi:[1,0,0]
	v_pk_add_f32 v[48:49], v[52:53], v[50:51] neg_lo:[0,1] neg_hi:[0,1]
	v_pk_add_f32 v[58:59], v[60:61], v[58:59]
	v_pk_mul_f32 v[60:61], v[42:43], s[62:63]
	v_pk_add_f32 v[54:55], v[94:95], v[72:73] neg_lo:[0,1] neg_hi:[0,1]
	v_pk_add_f32 v[64:65], v[64:65], v[66:67]
	v_xor_b32_e32 v66, 0x80000000, v49
	v_mov_b32_e32 v67, v48
	v_pk_fma_f32 v[42:43], v[42:43], s[8:9], v[60:61] op_sel:[0,0,1] op_sel_hi:[1,0,0] neg_lo:[1,0,0] neg_hi:[1,0,0]
	v_pk_add_f32 v[86:87], v[88:89], v[86:87]
	v_pk_mul_f32 v[88:89], v[92:93], s[24:25]
	v_pk_add_f32 v[48:49], v[54:55], v[66:67]
	v_pk_mul_f32 v[54:55], v[98:99], s[8:9]
	v_pk_mul_f32 v[66:67], v[82:83], s[16:17]
	v_pk_mul_f32 v[74:75], v[78:79], s[72:73]
	v_pk_add_f32 v[42:43], v[44:45], v[42:43]
	v_pk_add_f32 v[44:45], v[94:95], v[72:73]
	v_pk_add_f32 v[50:51], v[52:53], v[50:51]
	v_pk_fma_f32 v[88:89], v[92:93], s[80:81], v[88:89] op_sel:[0,0,1] op_sel_hi:[1,0,0]
	v_pk_fma_f32 v[54:55], v[98:99], s[82:83], v[54:55] op_sel:[0,0,1] op_sel_hi:[1,0,0] neg_lo:[1,0,0] neg_hi:[1,0,0]
	v_pk_fma_f32 v[66:67], v[82:83], s[76:77], v[66:67] op_sel:[0,0,1] op_sel_hi:[1,0,0] neg_lo:[1,0,0] neg_hi:[1,0,0]
	v_pk_fma_f32 v[74:75], v[78:79], s[0:1], v[74:75] op_sel:[0,0,1] op_sel_hi:[1,0,0] neg_lo:[1,0,0] neg_hi:[1,0,0]
	v_pk_add_f32 v[44:45], v[44:45], v[50:51]
	v_lshl_add_u32 v21, v21, 3, v36
	v_pk_add_f32 v[88:89], v[104:105], v[88:89]
	v_pk_add_f32 v[54:55], v[96:97], v[54:55]
	v_pk_add_f32 v[66:67], v[80:81], v[66:67]
	v_pk_add_f32 v[74:75], v[102:103], v[74:75]
	ds_write_b64 v25, v[44:45]
	ds_write_b64 v25, v[46:47] offset:4224
	ds_write_b64 v25, v[100:101] offset:8448
	ds_write_b64 v25, v[84:85] offset:12672
	ds_write_b64 v25, v[86:87] offset:16896
	ds_write_b64 v25, v[88:89] offset:21120
	ds_write_b64 v25, v[68:69] offset:25344
	ds_write_b64 v25, v[64:65] offset:29568
	ds_write_b64 v25, v[48:49] offset:33792
	ds_write_b64 v25, v[54:55] offset:38016
	ds_write_b64 v25, v[66:67] offset:42240
	ds_write_b64 v25, v[70:71] offset:46464
	ds_write_b64 v25, v[74:75] offset:50688
	ds_write_b64 v25, v[56:57] offset:54912
	ds_write_b64 v25, v[58:59] offset:59136
	ds_write_b64 v25, v[42:43] offset:63360
	v_ashrrev_i32_e32 v25, 5, v21
	v_lshlrev_b32_e32 v21, 3, v21
	v_lshlrev_b32_e32 v25, 3, v25
	s_waitcnt vmcnt(0)
	v_lshlrev_b32_e32 v41, 16, v41
	v_lshlrev_b32_e32 v39, 16, v39
	v_lshlrev_b32_e32 v35, 16, v35
	v_lshlrev_b32_e32 v29, 16, v29
	v_and_b32_e32 v48, 0xffff0000, v14
	v_add3_u32 v21, 0, v21, v25
	v_mov_b32_e32 v40, v48
	s_waitcnt lgkmcnt(0)
	s_barrier
	v_pk_mul_f32 v[44:45], v[30:31], v[40:41]
	ds_read2_b64 v[40:43], v21 offset1:1
	v_lshlrev_b32_e32 v28, 16, v14
	v_lshlrev_b32_e32 v49, 16, v15
	v_pk_fma_f32 v[44:45], v[30:31], v[28:29], v[44:45] op_sel:[0,0,1] op_sel_hi:[1,0,0]
	v_mov_b32_e32 v28, v31
	v_pk_fma_f32 v[44:45], v[20:21], v[48:49], v[44:45] op_sel_hi:[0,1,1]
	v_pk_add_f32 v[50:51], v[24:25], v[44:45] op_sel_hi:[0,1]
	ds_read2_b64 v[44:47], v21 offset0:2 offset1:3
	s_waitcnt lgkmcnt(1)
	v_pk_mul_f32 v[40:41], v[50:51], v[40:41]
	v_and_b32_e32 v51, 16, v16
	v_and_b32_e32 v50, 0xffff0000, v15
	v_pk_mov_b32 v[14:15], v[48:49], v[50:51] op_sel:[1,0]
	v_lshlrev_b32_e32 v53, 16, v16
	v_pk_mul_f32 v[14:15], v[30:31], v[14:15] op_sel_hi:[0,1]
	v_mov_b32_e32 v52, v50
	v_pk_fma_f32 v[14:15], v[28:29], v[48:49], v[14:15] op_sel_hi:[0,1,1]
	v_pk_fma_f32 v[14:15], v[20:21], v[52:53], v[14:15] op_sel_hi:[0,1,1]
	v_pk_add_f32 v[14:15], v[24:25], v[14:15] op_sel_hi:[0,1]
	v_pk_mul_f32 v[14:15], v[14:15], v[42:43]
	v_and_b32_e32 v43, 16, v17
	v_and_b32_e32 v42, 0xffff0000, v16
	v_lshlrev_b32_e32 v49, 16, v17
	v_mov_b32_e32 v48, v42
	v_pk_mov_b32 v[42:43], v[52:53], v[42:43] op_sel:[1,0]
	v_pk_mov_b32 v[16:17], v[16:17], v[10:11] op_sel:[1,0]
	v_pk_mul_f32 v[42:43], v[30:31], v[42:43] op_sel_hi:[0,1]
	v_and_b32_e32 v17, 16, v17
	v_and_b32_e32 v16, 0xffff0000, v16
	v_pk_fma_f32 v[42:43], v[28:29], v[52:53], v[42:43] op_sel_hi:[0,1,1]
	v_mov_b32_e32 v50, v16
	v_pk_mov_b32 v[16:17], v[48:49], v[16:17] op_sel:[1,0]
	v_pk_fma_f32 v[42:43], v[20:21], v[48:49], v[42:43] op_sel_hi:[0,1,1]
	v_pk_mul_f32 v[16:17], v[30:31], v[16:17] op_sel_hi:[0,1]
	v_pk_add_f32 v[42:43], v[24:25], v[42:43] op_sel_hi:[0,1]
	v_lshlrev_b32_e32 v51, 16, v10
	v_pk_fma_f32 v[16:17], v[28:29], v[48:49], v[16:17] op_sel_hi:[0,1,1]
	s_waitcnt lgkmcnt(0)
	v_pk_mul_f32 v[42:43], v[42:43], v[44:45]
	v_pk_fma_f32 v[16:17], v[20:21], v[50:51], v[16:17] op_sel_hi:[0,1,1]
	v_and_b32_e32 v45, 16, v11
	v_and_b32_e32 v44, 0xffff0000, v10
	v_pk_add_f32 v[16:17], v[24:25], v[16:17] op_sel_hi:[0,1]
	v_mov_b32_e32 v52, v44
	v_pk_mov_b32 v[44:45], v[50:51], v[44:45] op_sel:[1,0]
	v_pk_mul_f32 v[16:17], v[16:17], v[46:47]
	v_pk_mul_f32 v[48:49], v[30:31], v[44:45] op_sel_hi:[0,1]
	ds_read2_b64 v[44:47], v21 offset0:4 offset1:5
	v_lshlrev_b32_e32 v53, 16, v11
	v_pk_fma_f32 v[48:49], v[28:29], v[50:51], v[48:49] op_sel_hi:[0,1,1]
	v_pk_fma_f32 v[48:49], v[20:21], v[52:53], v[48:49] op_sel_hi:[0,1,1]
	v_pk_add_f32 v[54:55], v[24:25], v[48:49] op_sel_hi:[0,1]
	ds_read2_b64 v[48:51], v21 offset0:6 offset1:7
	s_waitcnt lgkmcnt(1)
	v_pk_mul_f32 v[44:45], v[54:55], v[44:45]
	v_and_b32_e32 v55, 16, v12
	v_and_b32_e32 v54, 0xffff0000, v11
	v_pk_mov_b32 v[10:11], v[52:53], v[54:55] op_sel:[1,0]
	v_lshlrev_b32_e32 v57, 16, v12
	v_pk_mul_f32 v[10:11], v[30:31], v[10:11] op_sel_hi:[0,1]
	v_mov_b32_e32 v56, v54
	v_pk_fma_f32 v[10:11], v[28:29], v[52:53], v[10:11] op_sel_hi:[0,1,1]
	v_pk_fma_f32 v[10:11], v[20:21], v[56:57], v[10:11] op_sel_hi:[0,1,1]
	v_pk_add_f32 v[10:11], v[24:25], v[10:11] op_sel_hi:[0,1]
	v_and_b32_e32 v38, 0xffff0000, v13
	v_pk_mul_f32 v[10:11], v[10:11], v[46:47]
	v_and_b32_e32 v47, 16, v13
	v_and_b32_e32 v46, 0xffff0000, v12
	v_lshlrev_b32_e32 v53, 16, v13
	v_mov_b32_e32 v52, v46
	v_pk_mov_b32 v[12:13], v[56:57], v[46:47] op_sel:[1,0]
	v_mov_b32_e32 v46, v53
	v_mov_b32_e32 v47, v38
	v_pk_mul_f32 v[12:13], v[30:31], v[12:13] op_sel_hi:[0,1]
	v_pk_mul_f32 v[46:47], v[30:31], v[46:47] op_sel_hi:[0,1]
	v_pk_fma_f32 v[12:13], v[28:29], v[56:57], v[12:13] op_sel_hi:[0,1,1]
	v_pk_fma_f32 v[46:47], v[28:29], v[52:53], v[46:47] op_sel_hi:[0,1,1]
	v_pk_fma_f32 v[12:13], v[20:21], v[52:53], v[12:13] op_sel_hi:[0,1,1]
	v_pk_fma_f32 v[38:39], v[20:21], v[38:39], v[46:47] op_sel_hi:[0,1,1]
	s_xor_b64 s[70:71], s[70:71], -1
	v_pk_add_f32 v[12:13], v[24:25], v[12:13] op_sel_hi:[0,1]
	v_pk_add_f32 v[38:39], v[24:25], v[38:39] op_sel_hi:[0,1]
	s_waitcnt lgkmcnt(0)
	v_pk_mul_f32 v[12:13], v[12:13], v[48:49]
	v_pk_mul_f32 v[38:39], v[38:39], v[50:51]
	s_mov_b64 s[0:1], -1
	s_and_b64 vcc, exec, s[70:71]
	s_cbranch_vccz .LBB0_513
	v_bfe_u32 v46, v15, 16, 1
	v_add3_u32 v47, v15, v46, s4
	v_bfe_u32 v46, v14, 16, 1
	v_bfe_u32 v48, v16, 16, 1
	v_bfe_u32 v50, v42, 16, 1
	v_bfe_u32 v34, v17, 16, 1
	v_bfe_u32 v49, v40, 16, 1
	v_add3_u32 v50, v42, v50, s4
	v_add3_u32 v48, v16, v48, s4
	v_add3_u32 v46, v14, v46, s4
	v_bfe_u32 v25, v43, 16, 1
	v_bfe_u32 v28, v41, 16, 1
	v_add3_u32 v34, v17, v34, s4
	v_add3_u32 v49, v40, v49, s4
	v_lshrrev_b32_e32 v51, 16, v46
	v_lshrrev_b32_e32 v52, 16, v48
	v_lshrrev_b32_e32 v48, 16, v50
	v_bfe_u32 v50, v11, 16, 1
	v_add3_u32 v28, v41, v28, s4
	v_add3_u32 v25, v43, v25, s4
	v_lshrrev_b32_e32 v46, 16, v49
	v_and_or_b32 v49, v34, s91, v52
	v_and_or_b32 v47, v47, s91, v51
	v_add3_u32 v51, v11, v50, s4
	v_bfe_u32 v50, v10, 16, 1
	v_bfe_u32 v52, v38, 16, 1
	v_bfe_u32 v53, v44, 16, 1
	v_bfe_u32 v54, v12, 16, 1
	v_lshl_add_u64 v[36:37], v[36:37], 1, s[50:51]
	v_and_or_b32 v48, v25, s91, v48
	v_and_or_b32 v46, v28, s91, v46
	v_bfe_u32 v25, v13, 16, 1
	v_bfe_u32 v28, v45, 16, 1
	v_bfe_u32 v34, v39, 16, 1
	v_add3_u32 v54, v12, v54, s4
	v_add3_u32 v53, v44, v53, s4
	v_add3_u32 v52, v38, v52, s4
	v_add3_u32 v50, v10, v50, s4
	v_add3_u32 v34, v39, v34, s4
	v_add3_u32 v28, v45, v28, s4
	v_add3_u32 v25, v13, v25, s4
	v_lshrrev_b32_e32 v55, 16, v50
	v_lshrrev_b32_e32 v56, 16, v52
	v_lshrrev_b32_e32 v50, 16, v53
	v_lshrrev_b32_e32 v52, 16, v54
	v_lshl_add_u64 v[32:33], v[32:33], 1, v[36:37]
	v_and_or_b32 v52, v25, s91, v52
	v_and_or_b32 v50, v28, s91, v50
	v_and_or_b32 v53, v34, s91, v56
	v_and_or_b32 v51, v51, s91, v55
	global_store_dwordx4 v[32:33], v[46:49], off
	global_store_dwordx4 v[32:33], v[50:53], off offset:16
	s_mov_b64 s[0:1], 0

.LBB0_534:
	v_mov_b32_e32 v2, v210
	s_mov_b32 s43, s8
	v_and_b32_e32 v3, 0xff, v2
	v_lshlrev_b32_e32 v4, 5, v2
	v_and_or_b32 v3, v4, s33, v3
	v_ashrrev_i32_e32 v4, 5, v3
	v_lshlrev_b32_e32 v3, 3, v3
	v_lshlrev_b32_e32 v4, 3, v4
	v_add3_u32 v18, 0, v3, v4
	ds_read_b64 v[128:129], v18
	ds_read_b64 v[132:133], v18 offset:2112
	ds_read_b64 v[134:135], v18 offset:4224
	ds_read_b64 v[136:137], v18 offset:6336
	ds_read_b64 v[138:139], v18 offset:8448
	ds_read_b64 v[140:141], v18 offset:10560
	ds_read_b64 v[142:143], v18 offset:12672
	ds_read_b64 v[130:131], v18 offset:14784
	ds_read_b64 v[144:145], v18 offset:16896
	ds_read_b64 v[148:149], v18 offset:19008
	ds_read_b64 v[150:151], v18 offset:21120
	ds_read_b64 v[152:153], v18 offset:23232
	s_waitcnt lgkmcnt(10)
	v_pk_mul_f32 v[162:163], v[132:133], s[10:11]
	s_mov_b32 s64, s11
	v_pk_fma_f32 v[162:163], v[132:133], s[8:9], v[162:163] op_sel:[0,0,1] op_sel_hi:[1,0,0]
	s_waitcnt lgkmcnt(2)
	v_pk_mul_f32 v[178:179], v[148:149], s[42:43]
	v_pk_add_f32 v[194:195], v[132:133], v[148:149]
	v_pk_add_f32 v[132:133], v[132:133], v[148:149] neg_lo:[0,1] neg_hi:[0,1]
	v_pk_mul_f32 v[164:165], v[134:135], s[18:19]
	s_mov_b32 s41, s16
	v_pk_fma_f32 v[178:179], v[148:149], s[64:65], v[178:179] op_sel:[0,0,1] op_sel_hi:[1,0,0] neg_lo:[1,0,0] neg_hi:[1,0,0]
	v_pk_mul_f32 v[148:149], v[132:133], s[18:19]
	v_pk_fma_f32 v[164:165], v[134:135], s[16:17], v[164:165] op_sel:[0,0,1] op_sel_hi:[1,0,0]
	s_mov_b32 s68, s19
	s_waitcnt lgkmcnt(1)
	v_pk_mul_f32 v[180:181], v[150:151], s[40:41]
	v_pk_fma_f32 v[132:133], v[132:133], s[16:17], v[148:149] op_sel:[0,0,1] op_sel_hi:[1,0,0]
	v_pk_add_f32 v[148:149], v[134:135], v[150:151]
	v_pk_add_f32 v[134:135], v[134:135], v[150:151] neg_lo:[0,1] neg_hi:[0,1]
	v_pk_mul_f32 v[166:167], v[136:137], s[26:27]
	s_mov_b32 s66, s37
	s_mov_b32 s39, s24
	v_pk_fma_f32 v[180:181], v[150:151], s[68:69], v[180:181] op_sel:[0,0,1] op_sel_hi:[1,0,0] neg_lo:[1,0,0] neg_hi:[1,0,0]
	v_pk_mul_f32 v[150:151], v[134:135], s[36:37]
	ds_read_b64 v[154:155], v18 offset:25344
	ds_read_b64 v[156:157], v18 offset:27456
	ds_read_b64 v[158:159], v18 offset:29568
	ds_read_b64 v[160:161], v18 offset:31680
	v_pk_fma_f32 v[166:167], v[136:137], s[24:25], v[166:167] op_sel:[0,0,1] op_sel_hi:[1,0,0]
	s_mov_b32 s0, s27
	s_waitcnt lgkmcnt(4)
	v_pk_mul_f32 v[182:183], v[152:153], s[38:39]
	v_pk_fma_f32 v[134:135], v[134:135], s[66:67], v[150:151] op_sel:[0,0,1] op_sel_hi:[1,0,0]
	v_pk_add_f32 v[150:151], v[136:137], v[152:153]
	v_pk_add_f32 v[136:137], v[136:137], v[152:153] neg_lo:[0,1] neg_hi:[0,1]
	v_pk_mul_f32 v[168:169], v[138:139], s[36:37]
	v_pk_fma_f32 v[182:183], v[152:153], s[0:1], v[182:183] op_sel:[0,0,1] op_sel_hi:[1,0,0] neg_lo:[1,0,0] neg_hi:[1,0,0]
	v_pk_mul_f32 v[152:153], v[136:137], s[40:41]
	v_pk_fma_f32 v[168:169], v[138:139], s[66:67], v[168:169] op_sel:[0,0,1] op_sel_hi:[1,0,0]
	v_pk_mul_f32 v[170:171], v[140:141], s[38:39]
	s_waitcnt lgkmcnt(3)
	v_pk_mul_f32 v[184:185], v[154:155], s[36:37]
	v_pk_fma_f32 v[136:137], v[136:137], s[68:69], v[152:153] op_sel:[0,0,1] op_sel_hi:[1,0,0]
	v_pk_add_f32 v[152:153], v[138:139], v[154:155]
	v_pk_add_f32 v[138:139], v[138:139], v[154:155] neg_lo:[0,1] neg_hi:[0,1]
	v_pk_fma_f32 v[170:171], v[140:141], s[0:1], v[170:171] op_sel:[0,0,1] op_sel_hi:[1,0,0]
	v_pk_fma_f32 v[184:185], v[154:155], s[66:67], v[184:185] op_sel:[0,0,1] op_sel_hi:[1,0,0] neg_lo:[1,0,0] neg_hi:[1,0,0]
	s_waitcnt lgkmcnt(2)
	v_pk_mul_f32 v[186:187], v[156:157], s[26:27]
	v_xor_b32_e32 v155, 0x80000000, v138
	v_mov_b32_e32 v154, v139
	v_pk_add_f32 v[138:139], v[140:141], v[156:157]
	v_pk_add_f32 v[140:141], v[140:141], v[156:157] neg_lo:[0,1] neg_hi:[0,1]
	v_pk_mul_f32 v[172:173], v[142:143], s[40:41]
	v_pk_fma_f32 v[186:187], v[156:157], s[24:25], v[186:187] op_sel:[0,0,1] op_sel_hi:[1,0,0] neg_lo:[1,0,0] neg_hi:[1,0,0]
	v_pk_mul_f32 v[156:157], v[140:141], s[40:41]
	v_pk_fma_f32 v[172:173], v[142:143], s[68:69], v[172:173] op_sel:[0,0,1] op_sel_hi:[1,0,0]
	s_waitcnt lgkmcnt(1)
	v_pk_mul_f32 v[188:189], v[158:159], s[18:19]
	v_pk_fma_f32 v[140:141], v[140:141], s[68:69], v[156:157] op_sel:[0,0,1] op_sel_hi:[1,0,0] neg_lo:[1,0,0] neg_hi:[1,0,0]
	v_pk_add_f32 v[156:157], v[142:143], v[158:159]
	v_pk_add_f32 v[142:143], v[142:143], v[158:159] neg_lo:[0,1] neg_hi:[0,1]
	v_pk_mul_f32 v[174:175], v[130:131], s[42:43]
	v_pk_fma_f32 v[188:189], v[158:159], s[16:17], v[188:189] op_sel:[0,0,1] op_sel_hi:[1,0,0] neg_lo:[1,0,0] neg_hi:[1,0,0]
	v_pk_mul_f32 v[158:159], v[142:143], s[36:37]
	v_pk_fma_f32 v[174:175], v[130:131], s[64:65], v[174:175] op_sel:[0,0,1] op_sel_hi:[1,0,0]
	s_waitcnt lgkmcnt(0)
	v_pk_mul_f32 v[190:191], v[160:161], s[10:11]
	v_pk_fma_f32 v[142:143], v[142:143], s[66:67], v[158:159] op_sel:[0,0,1] op_sel_hi:[1,0,0] neg_lo:[1,0,0] neg_hi:[1,0,0]
	v_pk_add_f32 v[158:159], v[130:131], v[160:161]
	v_pk_add_f32 v[130:131], v[130:131], v[160:161] neg_lo:[0,1] neg_hi:[0,1]
	v_xor_b32_e32 v177, 0x80000000, v144
	v_mov_b32_e32 v176, v145
	v_pk_fma_f32 v[190:191], v[160:161], s[8:9], v[190:191] op_sel:[0,0,1] op_sel_hi:[1,0,0] neg_lo:[1,0,0] neg_hi:[1,0,0]
	v_pk_mul_f32 v[160:161], v[130:131], s[18:19]
	v_pk_add_f32 v[192:193], v[128:129], v[144:145]
	v_pk_add_f32 v[144:145], v[128:129], v[144:145] neg_lo:[0,1] neg_hi:[0,1]
	v_pk_fma_f32 v[130:131], v[130:131], s[16:17], v[160:161] op_sel:[0,0,1] op_sel_hi:[1,0,0] neg_lo:[1,0,0] neg_hi:[1,0,0]
	v_pk_add_f32 v[160:161], v[128:129], v[176:177]
	v_pk_add_f32 v[128:129], v[128:129], v[176:177] neg_lo:[0,1] neg_hi:[0,1]
	v_pk_add_f32 v[176:177], v[162:163], v[178:179]
	v_pk_add_f32 v[162:163], v[162:163], v[178:179] neg_lo:[0,1] neg_hi:[0,1]
	v_cvt_f32_ubyte0_e32 v2, v2
	v_pk_mul_f32 v[178:179], v[162:163], s[18:19]
	v_mul_f32_e32 v2, 0x39000000, v2
	v_pk_fma_f32 v[162:163], v[162:163], s[16:17], v[178:179] op_sel:[0,0,1] op_sel_hi:[1,0,0]
	v_pk_add_f32 v[178:179], v[164:165], v[180:181]
	v_pk_add_f32 v[164:165], v[164:165], v[180:181] neg_lo:[0,1] neg_hi:[0,1]
	v_sin_f32_e32 v34, v2
	v_pk_mul_f32 v[180:181], v[164:165], s[36:37]
	v_cos_f32_e32 v30, v2
	v_pk_fma_f32 v[164:165], v[164:165], s[66:67], v[180:181] op_sel:[0,0,1] op_sel_hi:[1,0,0]
	v_pk_add_f32 v[180:181], v[166:167], v[182:183]
	v_pk_add_f32 v[166:167], v[166:167], v[182:183] neg_lo:[0,1] neg_hi:[0,1]
	v_xor_b32_e32 v31, 0x80000000, v34
	v_pk_mul_f32 v[182:183], v[166:167], s[40:41]
	v_mov_b32_e32 v35, v31
	v_pk_fma_f32 v[166:167], v[166:167], s[68:69], v[182:183] op_sel:[0,0,1] op_sel_hi:[1,0,0]
	v_pk_add_f32 v[182:183], v[168:169], v[184:185]
	v_pk_add_f32 v[184:185], v[168:169], v[184:185] neg_lo:[0,1] neg_hi:[0,1]
	v_pk_mul_f32 v[2:3], v[30:31], v[34:35] op_sel:[1,0] op_sel_hi:[0,1]
	v_pk_add_f32 v[168:169], v[170:171], v[186:187]
	v_pk_add_f32 v[170:171], v[170:171], v[186:187] neg_lo:[0,1] neg_hi:[0,1]
	v_pk_fma_f32 v[44:45], v[30:31], v[30:31], v[2:3] op_sel_hi:[1,0,1]
	v_pk_mul_f32 v[186:187], v[170:171], s[40:41]
	v_pk_mul_f32 v[2:3], v[34:35], v[44:45] op_sel:[0,1] op_sel_hi:[1,0]
	v_pk_fma_f32 v[170:171], v[170:171], s[68:69], v[186:187] op_sel:[0,0,1] op_sel_hi:[1,0,0] neg_lo:[1,0,0] neg_hi:[1,0,0]
	v_pk_add_f32 v[186:187], v[172:173], v[188:189]
	v_pk_add_f32 v[172:173], v[172:173], v[188:189] neg_lo:[0,1] neg_hi:[0,1]
	v_pk_mul_f32 v[188:189], v[172:173], s[36:37]
	v_pk_fma_f32 v[172:173], v[172:173], s[66:67], v[188:189] op_sel:[0,0,1] op_sel_hi:[1,0,0] neg_lo:[1,0,0] neg_hi:[1,0,0]
	v_pk_add_f32 v[188:189], v[174:175], v[190:191]
	v_pk_add_f32 v[174:175], v[174:175], v[190:191] neg_lo:[0,1] neg_hi:[0,1]
	v_pk_fma_f32 v[46:47], v[30:31], v[44:45], v[2:3] op_sel_hi:[0,1,1]
	v_pk_mul_f32 v[190:191], v[174:175], s[18:19]
	v_pk_mul_f32 v[2:3], v[44:45], v[44:45] op_sel:[1,1] op_sel_hi:[0,1] neg_lo:[0,1]
	v_pk_fma_f32 v[174:175], v[174:175], s[16:17], v[190:191] op_sel:[0,0,1] op_sel_hi:[1,0,0] neg_lo:[1,0,0] neg_hi:[1,0,0]
	v_pk_add_f32 v[190:191], v[192:193], v[152:153]
	v_pk_add_f32 v[152:153], v[192:193], v[152:153] neg_lo:[0,1] neg_hi:[0,1]
	v_pk_add_f32 v[192:193], v[194:195], v[138:139]
	v_pk_add_f32 v[138:139], v[194:195], v[138:139] neg_lo:[0,1] neg_hi:[0,1]
	v_pk_fma_f32 v[52:53], v[44:45], v[44:45], v[2:3] op_sel_hi:[1,0,1]
	v_pk_mul_f32 v[194:195], v[138:139], s[36:37]
	v_pk_fma_f32 v[138:139], v[138:139], s[66:67], v[194:195] op_sel:[0,0,1] op_sel_hi:[1,0,0]
	v_pk_add_f32 v[194:195], v[148:149], v[156:157]
	v_pk_add_f32 v[156:157], v[148:149], v[156:157] neg_lo:[0,1] neg_hi:[0,1]
	v_pk_add_f32 v[148:149], v[150:151], v[158:159]
	v_pk_add_f32 v[150:151], v[150:151], v[158:159] neg_lo:[0,1] neg_hi:[0,1]
	v_pk_mul_f32 v[2:3], v[52:53], v[52:53] op_sel:[1,1] op_sel_hi:[0,1] neg_lo:[0,1]
	v_pk_mul_f32 v[158:159], v[150:151], s[36:37]
	v_pk_fma_f32 v[48:49], v[52:53], v[52:53], v[2:3] op_sel_hi:[1,0,1]
	v_pk_fma_f32 v[150:151], v[150:151], s[66:67], v[158:159] op_sel:[0,0,1] op_sel_hi:[1,0,0] neg_lo:[1,0,0] neg_hi:[1,0,0]
	v_pk_add_f32 v[158:159], v[144:145], v[154:155]
	v_pk_add_f32 v[144:145], v[144:145], v[154:155] neg_lo:[0,1] neg_hi:[0,1]
	v_pk_add_f32 v[154:155], v[132:133], v[140:141]
	v_pk_add_f32 v[132:133], v[132:133], v[140:141] neg_lo:[0,1] neg_hi:[0,1]
	v_pk_mul_f32 v[2:3], v[52:53], v[48:49] op_sel:[1,1] op_sel_hi:[1,0] neg_lo:[1,0]
	v_pk_mul_f32 v[140:141], v[132:133], s[36:37]
	v_pk_fma_f32 v[36:37], v[52:53], v[48:49], v[2:3] op_sel_hi:[0,1,1]
	v_pk_fma_f32 v[132:133], v[132:133], s[66:67], v[140:141] op_sel:[0,0,1] op_sel_hi:[1,0,0]
	v_pk_add_f32 v[140:141], v[134:135], v[142:143]
	v_pk_add_f32 v[142:143], v[134:135], v[142:143] neg_lo:[0,1] neg_hi:[0,1]
	v_pk_mul_f32 v[2:3], v[52:53], v[36:37] op_sel:[1,1] op_sel_hi:[1,0] neg_lo:[1,0]
	v_pk_add_f32 v[134:135], v[136:137], v[130:131]
	v_pk_add_f32 v[130:131], v[136:137], v[130:131] neg_lo:[0,1] neg_hi:[0,1]
	v_pk_fma_f32 v[26:27], v[52:53], v[36:37], v[2:3] op_sel_hi:[0,1,1]
	v_pk_mul_f32 v[136:137], v[130:131], s[36:37]
	v_pk_mul_f32 v[2:3], v[52:53], v[26:27] op_sel:[1,1] op_sel_hi:[1,0] neg_lo:[1,0]
	v_pk_fma_f32 v[130:131], v[130:131], s[66:67], v[136:137] op_sel:[0,0,1] op_sel_hi:[1,0,0] neg_lo:[1,0,0] neg_hi:[1,0,0]
	v_pk_add_f32 v[136:137], v[160:161], v[182:183]
	v_pk_add_f32 v[160:161], v[160:161], v[182:183] neg_lo:[0,1] neg_hi:[0,1]
	v_pk_add_f32 v[182:183], v[176:177], v[168:169]
	v_pk_add_f32 v[168:169], v[176:177], v[168:169] neg_lo:[0,1] neg_hi:[0,1]
	v_pk_fma_f32 v[20:21], v[52:53], v[26:27], v[2:3] op_sel_hi:[0,1,1]
	v_pk_mul_f32 v[176:177], v[168:169], s[36:37]
	v_pk_mul_f32 v[2:3], v[52:53], v[20:21] op_sel:[1,1] op_sel_hi:[1,0] neg_lo:[1,0]
	v_pk_fma_f32 v[168:169], v[168:169], s[66:67], v[176:177] op_sel:[0,0,1] op_sel_hi:[1,0,0]
	v_pk_add_f32 v[176:177], v[178:179], v[186:187]
	v_pk_add_f32 v[186:187], v[178:179], v[186:187] neg_lo:[0,1] neg_hi:[0,1]
	v_pk_fma_f32 v[10:11], v[52:53], v[20:21], v[2:3] op_sel_hi:[0,1,1]
	v_pk_add_f32 v[178:179], v[180:181], v[188:189]
	v_pk_add_f32 v[180:181], v[180:181], v[188:189] neg_lo:[0,1] neg_hi:[0,1]
	v_pk_mul_f32 v[2:3], v[52:53], v[10:11] op_sel:[1,1] op_sel_hi:[1,0] neg_lo:[1,0]
	v_pk_mul_f32 v[188:189], v[180:181], s[36:37]
	v_pk_fma_f32 v[4:5], v[52:53], v[10:11], v[2:3] op_sel_hi:[0,1,1]
	v_pk_fma_f32 v[180:181], v[180:181], s[66:67], v[188:189] op_sel:[0,0,1] op_sel_hi:[1,0,0] neg_lo:[1,0,0] neg_hi:[1,0,0]
	v_pk_add_f32 v[188:189], v[128:129], v[184:185] op_sel:[0,1] op_sel_hi:[1,0] neg_hi:[0,1]
	v_pk_add_f32 v[128:129], v[128:129], v[184:185] op_sel:[0,1] op_sel_hi:[1,0] neg_lo:[0,1]
	v_pk_add_f32 v[184:185], v[162:163], v[170:171]
	v_pk_add_f32 v[162:163], v[162:163], v[170:171] neg_lo:[0,1] neg_hi:[0,1]
	v_pk_mul_f32 v[170:171], v[162:163], s[36:37]
	v_pk_fma_f32 v[162:163], v[162:163], s[66:67], v[170:171] op_sel:[0,0,1] op_sel_hi:[1,0,0]
	v_pk_add_f32 v[170:171], v[164:165], v[172:173]
	v_pk_add_f32 v[172:173], v[164:165], v[172:173] neg_lo:[0,1] neg_hi:[0,1]
	v_pk_mul_f32 v[2:3], v[46:47], v[4:5] op_sel:[1,1] op_sel_hi:[1,0] neg_lo:[1,0]
	v_pk_add_f32 v[164:165], v[166:167], v[174:175]
	v_pk_add_f32 v[166:167], v[166:167], v[174:175] neg_lo:[0,1] neg_hi:[0,1]
	v_pk_mul_f32 v[14:15], v[34:35], v[4:5] op_sel:[0,1] op_sel_hi:[1,0]
	v_pk_mul_f32 v[174:175], v[166:167], s[36:37]
	v_pk_mul_f32 v[40:41], v[34:35], v[10:11] op_sel:[0,1] op_sel_hi:[1,0]
	v_pk_fma_f32 v[166:167], v[166:167], s[66:67], v[174:175] op_sel:[0,0,1] op_sel_hi:[1,0,0] neg_lo:[1,0,0] neg_hi:[1,0,0]
	v_pk_add_f32 v[174:175], v[190:191], v[194:195]
	v_pk_add_f32 v[190:191], v[190:191], v[194:195] neg_lo:[0,1] neg_hi:[0,1]
	v_pk_add_f32 v[194:195], v[192:193], v[148:149]
	v_pk_add_f32 v[192:193], v[192:193], v[148:149] neg_lo:[0,1] neg_hi:[0,1]
	v_pk_mul_f32 v[66:67], v[34:35], v[20:21] op_sel:[0,1] op_sel_hi:[1,0]
	v_pk_add_f32 v[148:149], v[152:153], v[156:157] op_sel:[0,1] op_sel_hi:[1,0] neg_hi:[0,1]
	v_pk_add_f32 v[152:153], v[152:153], v[156:157] op_sel:[0,1] op_sel_hi:[1,0] neg_lo:[0,1]
	v_pk_add_f32 v[156:157], v[138:139], v[150:151]
	v_pk_add_f32 v[150:151], v[138:139], v[150:151] neg_lo:[0,1] neg_hi:[0,1]
	v_pk_mul_f32 v[82:83], v[34:35], v[26:27] op_sel:[0,1] op_sel_hi:[1,0]
	v_pk_add_f32 v[138:139], v[158:159], v[140:141]
	v_pk_add_f32 v[140:141], v[158:159], v[140:141] neg_lo:[0,1] neg_hi:[0,1]
	v_pk_add_f32 v[158:159], v[154:155], v[134:135]
	v_pk_add_f32 v[154:155], v[154:155], v[134:135] neg_lo:[0,1] neg_hi:[0,1]
	v_pk_mul_f32 v[96:97], v[34:35], v[36:37] op_sel:[0,1] op_sel_hi:[1,0]
	v_pk_add_f32 v[134:135], v[144:145], v[142:143] op_sel:[0,1] op_sel_hi:[1,0] neg_hi:[0,1]
	v_pk_add_f32 v[142:143], v[144:145], v[142:143] op_sel:[0,1] op_sel_hi:[1,0] neg_lo:[0,1]
	v_pk_add_f32 v[144:145], v[132:133], v[130:131]
	v_pk_add_f32 v[132:133], v[132:133], v[130:131] neg_lo:[0,1] neg_hi:[0,1]
	v_pk_mul_f32 v[110:111], v[34:35], v[48:49] op_sel:[0,1] op_sel_hi:[1,0]
	v_pk_add_f32 v[130:131], v[136:137], v[176:177]
	v_pk_add_f32 v[136:137], v[136:137], v[176:177] neg_lo:[0,1] neg_hi:[0,1]
	v_pk_add_f32 v[176:177], v[182:183], v[178:179]
	v_pk_add_f32 v[182:183], v[182:183], v[178:179] neg_lo:[0,1] neg_hi:[0,1]
	v_pk_mul_f32 v[124:125], v[34:35], v[52:53] op_sel:[0,1] op_sel_hi:[1,0]
	v_pk_add_f32 v[178:179], v[160:161], v[186:187] op_sel:[0,1] op_sel_hi:[1,0] neg_hi:[0,1]
	v_pk_add_f32 v[160:161], v[160:161], v[186:187] op_sel:[0,1] op_sel_hi:[1,0] neg_lo:[0,1]
	v_pk_add_f32 v[186:187], v[168:169], v[180:181]
	v_pk_add_f32 v[180:181], v[168:169], v[180:181] neg_lo:[0,1] neg_hi:[0,1]
	v_pk_fma_f32 v[2:3], v[46:47], v[4:5], v[2:3] op_sel_hi:[0,1,1]
	v_pk_add_f32 v[168:169], v[188:189], v[170:171]
	v_pk_add_f32 v[170:171], v[188:189], v[170:171] neg_lo:[0,1] neg_hi:[0,1]
	v_pk_add_f32 v[188:189], v[184:185], v[164:165]
	v_pk_add_f32 v[184:185], v[184:185], v[164:165] neg_lo:[0,1] neg_hi:[0,1]
	v_pk_mul_f32 v[8:9], v[44:45], v[4:5] op_sel:[1,1] op_sel_hi:[1,0] neg_lo:[1,0]
	v_pk_add_f32 v[164:165], v[128:129], v[172:173] op_sel:[0,1] op_sel_hi:[1,0] neg_hi:[0,1]
	v_pk_add_f32 v[128:129], v[128:129], v[172:173] op_sel:[0,1] op_sel_hi:[1,0] neg_lo:[0,1]
	v_pk_add_f32 v[172:173], v[162:163], v[166:167]
	v_pk_add_f32 v[166:167], v[162:163], v[166:167] neg_lo:[0,1] neg_hi:[0,1]
	v_pk_fma_f32 v[14:15], v[30:31], v[4:5], v[14:15] op_sel_hi:[0,1,1]
	v_pk_add_f32 v[162:163], v[174:175], v[194:195]
	v_pk_add_f32 v[174:175], v[174:175], v[194:195] neg_lo:[0,1] neg_hi:[0,1]
	v_pk_add_f32 v[194:195], v[190:191], v[192:193] op_sel:[0,1] op_sel_hi:[1,0] neg_hi:[0,1]
	v_pk_add_f32 v[190:191], v[190:191], v[192:193] op_sel:[0,1] op_sel_hi:[1,0] neg_lo:[0,1]
	v_pk_add_f32 v[192:193], v[148:149], v[156:157]
	v_pk_add_f32 v[148:149], v[148:149], v[156:157] neg_lo:[0,1] neg_hi:[0,1]
	v_pk_add_f32 v[156:157], v[152:153], v[150:151] op_sel:[0,1] op_sel_hi:[1,0] neg_hi:[0,1]
	v_pk_add_f32 v[150:151], v[152:153], v[150:151] op_sel:[0,1] op_sel_hi:[1,0] neg_lo:[0,1]
	v_pk_add_f32 v[152:153], v[138:139], v[158:159]
	v_pk_add_f32 v[138:139], v[138:139], v[158:159] neg_lo:[0,1] neg_hi:[0,1]
	v_pk_add_f32 v[158:159], v[140:141], v[154:155] op_sel:[0,1] op_sel_hi:[1,0] neg_hi:[0,1]
	v_pk_add_f32 v[140:141], v[140:141], v[154:155] op_sel:[0,1] op_sel_hi:[1,0] neg_lo:[0,1]
	v_pk_add_f32 v[154:155], v[134:135], v[144:145]
	v_pk_add_f32 v[134:135], v[134:135], v[144:145] neg_lo:[0,1] neg_hi:[0,1]
	v_pk_add_f32 v[144:145], v[142:143], v[132:133] op_sel:[0,1] op_sel_hi:[1,0] neg_hi:[0,1]
	v_pk_add_f32 v[132:133], v[142:143], v[132:133] op_sel:[0,1] op_sel_hi:[1,0] neg_lo:[0,1]
	v_pk_add_f32 v[142:143], v[130:131], v[176:177]
	v_pk_mul_f32 v[24:25], v[46:47], v[10:11] op_sel:[1,1] op_sel_hi:[1,0] neg_lo:[1,0]
	v_pk_mul_f32 v[34:35], v[34:35], v[142:143] op_sel:[0,1] op_sel_hi:[1,0]
	v_pk_mul_f32 v[32:33], v[44:45], v[10:11] op_sel:[1,1] op_sel_hi:[1,0] neg_lo:[1,0]
	v_pk_fma_f32 v[40:41], v[30:31], v[10:11], v[40:41] op_sel_hi:[0,1,1]
	v_pk_mul_f32 v[56:57], v[46:47], v[20:21] op_sel:[1,1] op_sel_hi:[1,0] neg_lo:[1,0]
	v_pk_mul_f32 v[62:63], v[44:45], v[20:21] op_sel:[1,1] op_sel_hi:[1,0] neg_lo:[1,0]
	v_pk_fma_f32 v[66:67], v[30:31], v[20:21], v[66:67] op_sel_hi:[0,1,1]
	v_pk_mul_f32 v[74:75], v[46:47], v[26:27] op_sel:[1,1] op_sel_hi:[1,0] neg_lo:[1,0]
	v_pk_mul_f32 v[78:79], v[44:45], v[26:27] op_sel:[1,1] op_sel_hi:[1,0] neg_lo:[1,0]
	v_pk_fma_f32 v[82:83], v[30:31], v[26:27], v[82:83] op_sel_hi:[0,1,1]
	v_pk_mul_f32 v[88:89], v[46:47], v[36:37] op_sel:[1,1] op_sel_hi:[1,0] neg_lo:[1,0]
	v_pk_mul_f32 v[92:93], v[44:45], v[36:37] op_sel:[1,1] op_sel_hi:[1,0] neg_lo:[1,0]
	v_pk_fma_f32 v[96:97], v[30:31], v[36:37], v[96:97] op_sel_hi:[0,1,1]
	v_pk_mul_f32 v[102:103], v[46:47], v[48:49] op_sel:[1,1] op_sel_hi:[1,0] neg_lo:[1,0]
	v_pk_mul_f32 v[106:107], v[44:45], v[48:49] op_sel:[1,1] op_sel_hi:[1,0] neg_lo:[1,0]
	v_pk_fma_f32 v[110:111], v[30:31], v[48:49], v[110:111] op_sel_hi:[0,1,1]
	v_pk_mul_f32 v[116:117], v[52:53], v[46:47] op_sel:[1,1] op_sel_hi:[0,1] neg_lo:[0,1]
	v_pk_mul_f32 v[120:121], v[44:45], v[52:53] op_sel:[1,1] op_sel_hi:[1,0] neg_lo:[1,0]
	v_pk_fma_f32 v[124:125], v[30:31], v[52:53], v[124:125] op_sel_hi:[0,1,1]
	v_pk_add_f32 v[130:131], v[130:131], v[176:177] neg_lo:[0,1] neg_hi:[0,1]
	v_pk_add_f32 v[176:177], v[136:137], v[182:183] op_sel:[0,1] op_sel_hi:[1,0] neg_hi:[0,1]
	v_pk_add_f32 v[136:137], v[136:137], v[182:183] op_sel:[0,1] op_sel_hi:[1,0] neg_lo:[0,1]
	v_pk_add_f32 v[182:183], v[178:179], v[186:187]
	v_pk_add_f32 v[178:179], v[178:179], v[186:187] neg_lo:[0,1] neg_hi:[0,1]
	v_pk_add_f32 v[186:187], v[160:161], v[180:181] op_sel:[0,1] op_sel_hi:[1,0] neg_hi:[0,1]
	v_pk_add_f32 v[160:161], v[160:161], v[180:181] op_sel:[0,1] op_sel_hi:[1,0] neg_lo:[0,1]
	v_pk_add_f32 v[180:181], v[168:169], v[188:189]
	v_pk_fma_f32 v[30:31], v[30:31], v[142:143], v[34:35] op_sel_hi:[0,1,1]
	v_pk_mul_f32 v[34:35], v[44:45], v[152:153] op_sel:[1,1] op_sel_hi:[1,0] neg_lo:[1,0]
	v_xor_b32_e32 v6, 0x80000000, v3
	v_pk_fma_f32 v[8:9], v[44:45], v[4:5], v[8:9] op_sel_hi:[0,1,1]
	v_pk_fma_f32 v[24:25], v[46:47], v[10:11], v[24:25] op_sel_hi:[0,1,1]
	v_pk_fma_f32 v[32:33], v[44:45], v[10:11], v[32:33] op_sel_hi:[0,1,1]
	v_pk_fma_f32 v[56:57], v[46:47], v[20:21], v[56:57] op_sel_hi:[0,1,1]
	v_pk_fma_f32 v[62:63], v[44:45], v[20:21], v[62:63] op_sel_hi:[0,1,1]
	v_pk_fma_f32 v[74:75], v[46:47], v[26:27], v[74:75] op_sel_hi:[0,1,1]
	v_pk_fma_f32 v[78:79], v[44:45], v[26:27], v[78:79] op_sel_hi:[0,1,1]
	v_pk_fma_f32 v[88:89], v[46:47], v[36:37], v[88:89] op_sel_hi:[0,1,1]
	v_pk_fma_f32 v[92:93], v[44:45], v[36:37], v[92:93] op_sel_hi:[0,1,1]
	v_pk_fma_f32 v[102:103], v[46:47], v[48:49], v[102:103] op_sel_hi:[0,1,1]
	v_pk_fma_f32 v[106:107], v[44:45], v[48:49], v[106:107] op_sel_hi:[0,1,1]
	v_pk_fma_f32 v[116:117], v[52:53], v[46:47], v[116:117] op_sel_hi:[1,0,1]
	v_pk_fma_f32 v[120:121], v[44:45], v[52:53], v[120:121] op_sel_hi:[0,1,1]
	v_mov_b32_e32 v7, v3
	v_pk_add_f32 v[168:169], v[168:169], v[188:189] neg_lo:[0,1] neg_hi:[0,1]
	v_pk_add_f32 v[188:189], v[170:171], v[184:185] op_sel:[0,1] op_sel_hi:[1,0] neg_hi:[0,1]
	v_pk_add_f32 v[170:171], v[170:171], v[184:185] op_sel:[0,1] op_sel_hi:[1,0] neg_lo:[0,1]
	v_pk_add_f32 v[184:185], v[164:165], v[172:173]
	v_pk_add_f32 v[164:165], v[164:165], v[172:173] neg_lo:[0,1] neg_hi:[0,1]
	v_pk_add_f32 v[172:173], v[128:129], v[166:167] op_sel:[0,1] op_sel_hi:[1,0] neg_hi:[0,1]
	v_pk_add_f32 v[128:129], v[128:129], v[166:167] op_sel:[0,1] op_sel_hi:[1,0] neg_lo:[0,1]
	v_pk_fma_f32 v[34:35], v[44:45], v[152:153], v[34:35] op_sel_hi:[0,1,1]
	v_pk_mul_f32 v[44:45], v[46:47], v[180:181] op_sel:[1,1] op_sel_hi:[1,0] neg_lo:[1,0]
	v_xor_b32_e32 v12, 0x80000000, v9
	v_xor_b32_e32 v16, 0x80000000, v15
	v_xor_b32_e32 v22, 0x80000000, v5
	v_xor_b32_e32 v28, 0x80000000, v25
	v_xor_b32_e32 v38, 0x80000000, v33
	v_xor_b32_e32 v42, 0x80000000, v41
	v_xor_b32_e32 v50, 0x80000000, v11
	v_xor_b32_e32 v60, 0x80000000, v57
	v_xor_b32_e32 v64, 0x80000000, v63
	v_xor_b32_e32 v68, 0x80000000, v67
	v_xor_b32_e32 v70, 0x80000000, v21
	v_xor_b32_e32 v76, 0x80000000, v75
	v_xor_b32_e32 v80, 0x80000000, v79
	v_xor_b32_e32 v84, 0x80000000, v83
	v_xor_b32_e32 v86, 0x80000000, v27
	v_xor_b32_e32 v90, 0x80000000, v89
	v_xor_b32_e32 v94, 0x80000000, v93
	v_xor_b32_e32 v98, 0x80000000, v97
	v_xor_b32_e32 v100, 0x80000000, v37
	v_xor_b32_e32 v104, 0x80000000, v103
	v_xor_b32_e32 v108, 0x80000000, v107
	v_mov_b32_e32 v109, v107
	v_mov_b32_e32 v105, v103
	v_mov_b32_e32 v101, v37
	v_mov_b32_e32 v99, v97
	v_mov_b32_e32 v95, v93
	v_mov_b32_e32 v91, v89
	v_mov_b32_e32 v87, v27
	v_mov_b32_e32 v85, v83
	v_mov_b32_e32 v81, v79
	v_mov_b32_e32 v77, v75
	v_mov_b32_e32 v71, v21
	v_mov_b32_e32 v69, v67
	v_mov_b32_e32 v65, v63
	v_mov_b32_e32 v61, v57
	v_mov_b32_e32 v51, v11
	v_mov_b32_e32 v43, v41
	v_mov_b32_e32 v39, v33
	v_mov_b32_e32 v29, v25
	v_mov_b32_e32 v23, v5
	v_mov_b32_e32 v17, v15
	v_mov_b32_e32 v13, v9
	v_pk_fma_f32 v[44:45], v[46:47], v[180:181], v[44:45] op_sel_hi:[0,1,1]
	v_pk_mul_f32 v[46:47], v[52:53], v[192:193] op_sel:[1,1] op_sel_hi:[1,0] neg_lo:[1,0]
	v_pk_mul_f32 v[72:73], v[48:49], v[194:195] op_sel:[1,1] op_sel_hi:[1,0] neg_lo:[1,0]
	v_pk_mul_f32 v[6:7], v[128:129], v[6:7] op_sel:[1,0] op_sel_hi:[0,1]
	v_pk_fma_f32 v[46:47], v[52:53], v[192:193], v[46:47] op_sel_hi:[0,1,1]
	v_pk_mul_f32 v[52:53], v[124:125], v[182:183] op_sel:[1,1] op_sel_hi:[1,0] neg_lo:[1,0]
	v_pk_mul_f32 v[54:55], v[120:121], v[154:155] op_sel:[1,1] op_sel_hi:[1,0] neg_lo:[1,0]
	v_pk_mul_f32 v[58:59], v[116:117], v[184:185] op_sel:[1,1] op_sel_hi:[1,0] neg_lo:[1,0]
	v_pk_fma_f32 v[48:49], v[48:49], v[194:195], v[72:73] op_sel_hi:[0,1,1]
	v_pk_mul_f32 v[72:73], v[110:111], v[176:177] op_sel:[1,1] op_sel_hi:[1,0] neg_lo:[1,0]
	v_pk_mul_f32 v[108:109], v[108:109], v[158:159] op_sel:[0,1] op_sel_hi:[1,0]
	v_pk_mul_f32 v[104:105], v[104:105], v[188:189] op_sel:[0,1] op_sel_hi:[1,0]
	v_pk_mul_f32 v[100:101], v[100:101], v[156:157] op_sel:[0,1] op_sel_hi:[1,0]
	v_pk_mul_f32 v[98:99], v[98:99], v[186:187] op_sel:[0,1] op_sel_hi:[1,0]
	v_pk_mul_f32 v[94:95], v[94:95], v[144:145] op_sel:[0,1] op_sel_hi:[1,0]
	v_pk_mul_f32 v[90:91], v[90:91], v[172:173] op_sel:[0,1] op_sel_hi:[1,0]
	v_pk_mul_f32 v[86:87], v[174:175], v[86:87] op_sel:[1,0] op_sel_hi:[0,1]
	v_pk_mul_f32 v[84:85], v[130:131], v[84:85] op_sel:[1,0] op_sel_hi:[0,1]
	v_pk_mul_f32 v[80:81], v[138:139], v[80:81] op_sel:[1,0] op_sel_hi:[0,1]
	v_pk_mul_f32 v[76:77], v[168:169], v[76:77] op_sel:[1,0] op_sel_hi:[0,1]
	v_pk_mul_f32 v[70:71], v[148:149], v[70:71] op_sel:[1,0] op_sel_hi:[0,1]
	v_pk_mul_f32 v[68:69], v[178:179], v[68:69] op_sel:[1,0] op_sel_hi:[0,1]
	v_pk_mul_f32 v[64:65], v[134:135], v[64:65] op_sel:[1,0] op_sel_hi:[0,1]
	v_pk_mul_f32 v[60:61], v[164:165], v[60:61] op_sel:[1,0] op_sel_hi:[0,1]
	v_pk_mul_f32 v[50:51], v[190:191], v[50:51] op_sel:[1,0] op_sel_hi:[0,1]
	v_pk_mul_f32 v[42:43], v[136:137], v[42:43] op_sel:[1,0] op_sel_hi:[0,1]
	v_pk_mul_f32 v[38:39], v[140:141], v[38:39] op_sel:[1,0] op_sel_hi:[0,1]
	v_pk_mul_f32 v[28:29], v[170:171], v[28:29] op_sel:[1,0] op_sel_hi:[0,1]
	v_pk_mul_f32 v[22:23], v[150:151], v[22:23] op_sel:[1,0] op_sel_hi:[0,1]
	v_pk_mul_f32 v[16:17], v[160:161], v[16:17] op_sel:[1,0] op_sel_hi:[0,1]
	v_pk_mul_f32 v[12:13], v[132:133], v[12:13] op_sel:[1,0] op_sel_hi:[0,1]
	v_pk_fma_f32 v[2:3], v[128:129], v[2:3], v[6:7] op_sel_hi:[1,0,1]
	v_pk_fma_f32 v[52:53], v[124:125], v[182:183], v[52:53] op_sel_hi:[0,1,1]
	v_pk_fma_f32 v[54:55], v[120:121], v[154:155], v[54:55] op_sel_hi:[0,1,1]
	v_pk_fma_f32 v[58:59], v[116:117], v[184:185], v[58:59] op_sel_hi:[0,1,1]
	v_pk_fma_f32 v[72:73], v[110:111], v[176:177], v[72:73] op_sel_hi:[0,1,1]
	v_pk_fma_f32 v[106:107], v[106:107], v[158:159], v[108:109] op_sel_hi:[0,1,1]
	v_pk_fma_f32 v[102:103], v[102:103], v[188:189], v[104:105] op_sel_hi:[0,1,1]
	v_pk_fma_f32 v[36:37], v[36:37], v[156:157], v[100:101] op_sel_hi:[0,1,1]
	v_pk_fma_f32 v[96:97], v[96:97], v[186:187], v[98:99] op_sel_hi:[0,1,1]
	v_pk_fma_f32 v[92:93], v[92:93], v[144:145], v[94:95] op_sel_hi:[0,1,1]
	v_pk_fma_f32 v[88:89], v[88:89], v[172:173], v[90:91] op_sel_hi:[0,1,1]
	v_pk_fma_f32 v[26:27], v[174:175], v[26:27], v[86:87] op_sel_hi:[1,0,1]
	v_pk_fma_f32 v[82:83], v[130:131], v[82:83], v[84:85] op_sel_hi:[1,0,1]
	v_pk_fma_f32 v[78:79], v[138:139], v[78:79], v[80:81] op_sel_hi:[1,0,1]
	v_pk_fma_f32 v[74:75], v[168:169], v[74:75], v[76:77] op_sel_hi:[1,0,1]
	v_pk_fma_f32 v[20:21], v[148:149], v[20:21], v[70:71] op_sel_hi:[1,0,1]
	v_pk_fma_f32 v[66:67], v[178:179], v[66:67], v[68:69] op_sel_hi:[1,0,1]
	v_pk_fma_f32 v[62:63], v[134:135], v[62:63], v[64:65] op_sel_hi:[1,0,1]
	v_pk_fma_f32 v[56:57], v[164:165], v[56:57], v[60:61] op_sel_hi:[1,0,1]
	v_pk_fma_f32 v[10:11], v[190:191], v[10:11], v[50:51] op_sel_hi:[1,0,1]
	v_pk_fma_f32 v[40:41], v[136:137], v[40:41], v[42:43] op_sel_hi:[1,0,1]
	v_pk_fma_f32 v[32:33], v[140:141], v[32:33], v[38:39] op_sel_hi:[1,0,1]
	v_pk_fma_f32 v[24:25], v[170:171], v[24:25], v[28:29] op_sel_hi:[1,0,1]
	v_pk_fma_f32 v[4:5], v[150:151], v[4:5], v[22:23] op_sel_hi:[1,0,1]
	v_pk_fma_f32 v[14:15], v[160:161], v[14:15], v[16:17] op_sel_hi:[1,0,1]
	v_pk_fma_f32 v[8:9], v[132:133], v[8:9], v[12:13] op_sel_hi:[1,0,1]
	ds_write_b64 v18, v[162:163]
	ds_write_b64 v18, v[26:27] offset:2112
	ds_write_b64 v18, v[48:49] offset:4224
	ds_write_b64 v18, v[10:11] offset:6336
	ds_write_b64 v18, v[46:47] offset:8448
	ds_write_b64 v18, v[20:21] offset:10560
	ds_write_b64 v18, v[36:37] offset:12672
	ds_write_b64 v18, v[4:5] offset:14784
	ds_write_b64 v18, v[34:35] offset:16896
	ds_write_b64 v18, v[78:79] offset:19008
	ds_write_b64 v18, v[106:107] offset:21120
	ds_write_b64 v18, v[32:33] offset:23232
	ds_write_b64 v18, v[54:55] offset:25344
	ds_write_b64 v18, v[62:63] offset:27456
	ds_write_b64 v18, v[92:93] offset:29568
	ds_write_b64 v18, v[8:9] offset:31680
	ds_write_b64 v18, v[30:31] offset:33792
	ds_write_b64 v18, v[82:83] offset:35904
	ds_write_b64 v18, v[72:73] offset:38016
	ds_write_b64 v18, v[40:41] offset:40128
	ds_write_b64 v18, v[52:53] offset:42240
	ds_write_b64 v18, v[66:67] offset:44352
	ds_write_b64 v18, v[96:97] offset:46464
	ds_write_b64 v18, v[14:15] offset:48576
	ds_write_b64 v18, v[44:45] offset:50688
	ds_write_b64 v18, v[74:75] offset:52800
	ds_write_b64 v18, v[102:103] offset:54912
	ds_write_b64 v18, v[24:25] offset:57024
	ds_write_b64 v18, v[58:59] offset:59136
	ds_write_b64 v18, v[56:57] offset:61248
	ds_write_b64 v18, v[88:89] offset:63360
	ds_write_b64 v18, v[2:3] offset:65472
	v_mov_b32_e32 v3, v210
	s_waitcnt lgkmcnt(0)
	s_barrier
	s_add_i32 s64, s62, s48
	v_and_b32_e32 v5, 15, v3
	v_cvt_f32_ubyte0_e32 v2, v5
	v_mul_f32_e32 v4, 0x3b800000, v2
	v_sin_f32_e32 v2, v4
	v_cos_f32_e32 v4, v4
	v_lshlrev_b32_e32 v64, 3, v5
	v_lshlrev_b32_e32 v18, 4, v3
	v_xor_b32_e32 v5, 0x80000000, v2
	v_mov_b32_e32 v3, v5
	v_pk_mul_f32 v[6:7], v[4:5], v[2:3] op_sel:[1,0] op_sel_hi:[0,1]
	v_pk_fma_f32 v[6:7], v[4:5], v[4:5], v[6:7] op_sel_hi:[1,0,1]
	s_ashr_i32 s65, s64, 31
	s_nop 0
	s_nop 0
	v_pk_mul_f32 v[10:11], v[6:7], v[6:7] op_sel:[1,1] op_sel_hi:[0,1] neg_lo:[0,1]
	v_pk_fma_f32 v[10:11], v[6:7], v[6:7], v[10:11] op_sel_hi:[1,0,1]
	v_pk_mul_f32 v[8:9], v[2:3], v[6:7] op_sel:[0,1] op_sel_hi:[1,0]
	v_pk_mul_f32 v[32:33], v[10:11], v[10:11] op_sel:[1,1] op_sel_hi:[0,1] neg_lo:[0,1]
	v_pk_fma_f32 v[32:33], v[10:11], v[10:11], v[32:33] op_sel_hi:[1,0,1]
	v_pk_mul_f32 v[16:17], v[2:3], v[10:11] op_sel:[0,1] op_sel_hi:[1,0]
	v_pk_mul_f32 v[48:49], v[10:11], v[32:33] op_sel:[1,1] op_sel_hi:[1,0] neg_lo:[1,0]
	v_pk_mul_f32 v[36:37], v[2:3], v[32:33] op_sel:[0,1] op_sel_hi:[1,0]
	v_pk_fma_f32 v[48:49], v[10:11], v[32:33], v[48:49] op_sel_hi:[0,1,1]
	v_pk_mul_f32 v[52:53], v[2:3], v[48:49] op_sel:[0,1] op_sel_hi:[1,0]
	v_pk_fma_f32 v[8:9], v[4:5], v[6:7], v[8:9] op_sel_hi:[0,1,1]
	v_pk_fma_f32 v[16:17], v[4:5], v[10:11], v[16:17] op_sel_hi:[0,1,1]
	v_pk_fma_f32 v[36:37], v[4:5], v[32:33], v[36:37] op_sel_hi:[0,1,1]
	v_pk_fma_f32 v[52:53], v[4:5], v[48:49], v[52:53] op_sel_hi:[0,1,1]
	v_and_b32_e32 v5, 0xffffff00, v18
	v_lshlrev_b32_e32 v18, 3, v5
	v_add3_u32 v18, 0, v64, v18
	v_ashrrev_i32_e32 v64, 2, v5
	v_add_u32_e32 v106, v18, v64
	ds_read2_b64 v[64:67], v106 offset1:16
	ds_read2_b64 v[68:71], v106 offset0:33 offset1:49
	ds_read2_b64 v[72:75], v106 offset0:66 offset1:82
	ds_read2_b64 v[76:79], v106 offset0:132 offset1:148
	ds_read2_b64 v[80:83], v106 offset0:99 offset1:115
	ds_read2_b64 v[84:87], v106 offset0:165 offset1:181
	ds_read2_b64 v[88:91], v106 offset0:198 offset1:214
	ds_read2_b64 v[92:95], v106 offset0:231 offset1:247
	s_waitcnt lgkmcnt(4)
	v_pk_add_f32 v[96:97], v[64:65], v[76:77]
	v_pk_add_f32 v[64:65], v[64:65], v[76:77] neg_lo:[0,1] neg_hi:[0,1]
	v_pk_add_f32 v[76:77], v[66:67], v[78:79]
	v_pk_add_f32 v[66:67], v[66:67], v[78:79] neg_lo:[0,1] neg_hi:[0,1]
	s_waitcnt lgkmcnt(1)
	v_pk_add_f32 v[98:99], v[74:75], v[90:91]
	v_pk_mul_f32 v[78:79], v[66:67], s[18:19]
	v_pk_add_f32 v[74:75], v[74:75], v[90:91] neg_lo:[0,1] neg_hi:[0,1]
	v_pk_fma_f32 v[66:67], v[66:67], s[16:17], v[78:79] op_sel:[0,0,1] op_sel_hi:[1,0,0]
	v_pk_add_f32 v[78:79], v[68:69], v[84:85]
	v_pk_add_f32 v[68:69], v[68:69], v[84:85] neg_lo:[0,1] neg_hi:[0,1]
	v_pk_mul_f32 v[90:91], v[74:75], s[40:41]
	v_pk_mul_f32 v[84:85], v[68:69], s[36:37]
	v_pk_fma_f32 v[74:75], v[74:75], s[68:69], v[90:91] op_sel:[0,0,1] op_sel_hi:[1,0,0] neg_lo:[1,0,0] neg_hi:[1,0,0]
	v_pk_fma_f32 v[68:69], v[68:69], s[66:67], v[84:85] op_sel:[0,0,1] op_sel_hi:[1,0,0]
	v_pk_add_f32 v[84:85], v[70:71], v[86:87]
	v_pk_add_f32 v[70:71], v[70:71], v[86:87] neg_lo:[0,1] neg_hi:[0,1]
	s_waitcnt lgkmcnt(0)
	v_pk_add_f32 v[90:91], v[80:81], v[92:93]
	v_pk_add_f32 v[80:81], v[80:81], v[92:93] neg_lo:[0,1] neg_hi:[0,1]
	v_pk_mul_f32 v[86:87], v[70:71], s[40:41]
	v_pk_mul_f32 v[92:93], v[80:81], s[36:37]
	v_pk_fma_f32 v[70:71], v[70:71], s[68:69], v[86:87] op_sel:[0,0,1] op_sel_hi:[1,0,0]
	v_pk_add_f32 v[86:87], v[72:73], v[88:89]
	v_pk_add_f32 v[88:89], v[72:73], v[88:89] neg_lo:[0,1] neg_hi:[0,1]
	v_pk_fma_f32 v[80:81], v[80:81], s[66:67], v[92:93] op_sel:[0,0,1] op_sel_hi:[1,0,0] neg_lo:[1,0,0] neg_hi:[1,0,0]
	v_pk_add_f32 v[92:93], v[82:83], v[94:95]
	v_pk_add_f32 v[82:83], v[82:83], v[94:95] neg_lo:[0,1] neg_hi:[0,1]
	v_pk_mul_f32 v[94:95], v[82:83], s[18:19]
	v_pk_fma_f32 v[82:83], v[82:83], s[16:17], v[94:95] op_sel:[0,0,1] op_sel_hi:[1,0,0] neg_lo:[1,0,0] neg_hi:[1,0,0]
	v_pk_add_f32 v[94:95], v[96:97], v[86:87]
	v_pk_add_f32 v[86:87], v[96:97], v[86:87] neg_lo:[0,1] neg_hi:[0,1]
	v_pk_add_f32 v[96:97], v[76:77], v[98:99]
	v_pk_add_f32 v[76:77], v[76:77], v[98:99] neg_lo:[0,1] neg_hi:[0,1]
	v_pk_add_f32 v[100:101], v[84:85], v[92:93]
	v_pk_add_f32 v[84:85], v[84:85], v[92:93] neg_lo:[0,1] neg_hi:[0,1]
	v_pk_add_f32 v[72:73], v[64:65], v[88:89] op_sel:[0,1] op_sel_hi:[1,0] neg_hi:[0,1]
	v_pk_add_f32 v[64:65], v[64:65], v[88:89] op_sel:[0,1] op_sel_hi:[1,0] neg_lo:[0,1]
	v_pk_add_f32 v[88:89], v[66:67], v[74:75]
	v_pk_add_f32 v[66:67], v[66:67], v[74:75] neg_lo:[0,1] neg_hi:[0,1]
	v_pk_mul_f32 v[98:99], v[76:77], s[36:37]
	v_pk_mul_f32 v[92:93], v[84:85], s[36:37]
	v_pk_mul_f32 v[74:75], v[66:67], s[36:37]
	v_pk_fma_f32 v[76:77], v[76:77], s[66:67], v[98:99] op_sel:[0,0,1] op_sel_hi:[1,0,0]
	v_pk_add_f32 v[98:99], v[78:79], v[90:91]
	v_pk_add_f32 v[90:91], v[78:79], v[90:91] neg_lo:[0,1] neg_hi:[0,1]
	v_pk_fma_f32 v[84:85], v[84:85], s[66:67], v[92:93] op_sel:[0,0,1] op_sel_hi:[1,0,0] neg_lo:[1,0,0] neg_hi:[1,0,0]
	v_pk_fma_f32 v[66:67], v[66:67], s[66:67], v[74:75] op_sel:[0,0,1] op_sel_hi:[1,0,0]
	v_pk_add_f32 v[74:75], v[68:69], v[80:81]
	v_pk_add_f32 v[92:93], v[70:71], v[82:83]
	v_pk_add_f32 v[70:71], v[70:71], v[82:83] neg_lo:[0,1] neg_hi:[0,1]
	v_pk_add_f32 v[68:69], v[68:69], v[80:81] neg_lo:[0,1] neg_hi:[0,1]
	v_pk_mul_f32 v[82:83], v[70:71], s[36:37]
	v_pk_add_f32 v[102:103], v[72:73], v[74:75]
	v_pk_add_f32 v[72:73], v[72:73], v[74:75] neg_lo:[0,1] neg_hi:[0,1]
	v_pk_add_f32 v[74:75], v[88:89], v[92:93]
	v_pk_add_f32 v[92:93], v[88:89], v[92:93] neg_lo:[0,1] neg_hi:[0,1]
	v_pk_mul_f32 v[24:25], v[6:7], v[10:11] op_sel:[1,1] op_sel_hi:[1,0] neg_lo:[1,0]
	v_xor_b32_e32 v81, 0x80000000, v68
	v_pk_fma_f32 v[70:71], v[70:71], s[66:67], v[82:83] op_sel:[0,0,1] op_sel_hi:[1,0,0] neg_lo:[1,0,0] neg_hi:[1,0,0]
	v_pk_add_f32 v[78:79], v[86:87], v[90:91] op_sel:[0,1] op_sel_hi:[1,0] neg_hi:[0,1]
	v_pk_add_f32 v[86:87], v[86:87], v[90:91] op_sel:[0,1] op_sel_hi:[1,0] neg_lo:[0,1]
	v_pk_add_f32 v[90:91], v[76:77], v[84:85]
	v_pk_add_f32 v[84:85], v[76:77], v[84:85] neg_lo:[0,1] neg_hi:[0,1]
	v_mov_b32_e32 v80, v69
	v_pk_fma_f32 v[24:25], v[6:7], v[10:11], v[24:25] op_sel_hi:[0,1,1]
	v_pk_mul_f32 v[28:29], v[10:11], v[8:9] op_sel:[1,1] op_sel_hi:[0,1] neg_lo:[0,1]
	v_pk_add_f32 v[68:69], v[64:65], v[80:81]
	v_pk_add_f32 v[64:65], v[64:65], v[80:81] neg_lo:[0,1] neg_hi:[0,1]
	v_pk_add_f32 v[80:81], v[66:67], v[70:71]
	v_pk_add_f32 v[70:71], v[66:67], v[70:71] neg_lo:[0,1] neg_hi:[0,1]
	v_pk_add_f32 v[88:89], v[72:73], v[92:93] op_sel:[0,1] op_sel_hi:[1,0] neg_hi:[0,1]
	v_pk_fma_f32 v[28:29], v[10:11], v[8:9], v[28:29] op_sel_hi:[1,0,1]
	v_pk_add_f32 v[76:77], v[86:87], v[84:85] op_sel:[0,1] op_sel_hi:[1,0] neg_hi:[0,1]
	v_pk_add_f32 v[72:73], v[72:73], v[92:93] op_sel:[0,1] op_sel_hi:[1,0] neg_lo:[0,1]
	v_pk_mul_f32 v[92:93], v[16:17], v[88:89] op_sel:[1,1] op_sel_hi:[1,0] neg_lo:[1,0]
	v_pk_add_f32 v[82:83], v[94:95], v[98:99]
	v_pk_add_f32 v[94:95], v[94:95], v[98:99] neg_lo:[0,1] neg_hi:[0,1]
	v_pk_add_f32 v[98:99], v[96:97], v[100:101]
	v_pk_add_f32 v[66:67], v[64:65], v[70:71] op_sel:[0,1] op_sel_hi:[1,0] neg_hi:[0,1]
	v_pk_fma_f32 v[88:89], v[16:17], v[88:89], v[92:93] op_sel_hi:[0,1,1]
	v_pk_mul_f32 v[92:93], v[24:25], v[76:77] op_sel:[1,1] op_sel_hi:[1,0] neg_lo:[1,0]
	v_pk_mul_f32 v[40:41], v[6:7], v[32:33] op_sel:[1,1] op_sel_hi:[1,0] neg_lo:[1,0]
	v_pk_add_f32 v[104:105], v[82:83], v[98:99]
	v_pk_add_f32 v[82:83], v[82:83], v[98:99] neg_lo:[0,1] neg_hi:[0,1]
	v_pk_fma_f32 v[76:77], v[24:25], v[76:77], v[92:93] op_sel_hi:[0,1,1]
	v_pk_mul_f32 v[92:93], v[28:29], v[66:67] op_sel:[1,1] op_sel_hi:[1,0] neg_lo:[1,0]
	v_pk_fma_f32 v[40:41], v[6:7], v[32:33], v[40:41] op_sel_hi:[0,1,1]
	v_pk_mul_f32 v[44:45], v[8:9], v[32:33] op_sel:[1,1] op_sel_hi:[1,0] neg_lo:[1,0]
	v_pk_add_f32 v[84:85], v[86:87], v[84:85] op_sel:[0,1] op_sel_hi:[1,0] neg_lo:[0,1]
	v_pk_add_f32 v[86:87], v[102:103], v[74:75]
	v_pk_add_f32 v[74:75], v[102:103], v[74:75] neg_lo:[0,1] neg_hi:[0,1]
	v_pk_fma_f32 v[66:67], v[28:29], v[66:67], v[92:93] op_sel_hi:[0,1,1]
	v_pk_mul_f32 v[92:93], v[32:33], v[82:83] op_sel:[1,1] op_sel_hi:[1,0] neg_lo:[1,0]
	v_pk_fma_f32 v[44:45], v[8:9], v[32:33], v[44:45] op_sel_hi:[0,1,1]
	v_pk_add_f32 v[100:101], v[96:97], v[100:101] neg_lo:[0,1] neg_hi:[0,1]
	v_pk_add_f32 v[98:99], v[78:79], v[90:91]
	v_pk_add_f32 v[78:79], v[78:79], v[90:91] neg_lo:[0,1] neg_hi:[0,1]
	v_pk_fma_f32 v[82:83], v[32:33], v[82:83], v[92:93] op_sel_hi:[0,1,1]
	v_pk_mul_f32 v[92:93], v[36:37], v[74:75] op_sel:[1,1] op_sel_hi:[1,0] neg_lo:[1,0]
	v_pk_add_f32 v[90:91], v[68:69], v[80:81]
	v_pk_add_f32 v[68:69], v[68:69], v[80:81] neg_lo:[0,1] neg_hi:[0,1]
	v_pk_fma_f32 v[74:75], v[36:37], v[74:75], v[92:93] op_sel_hi:[0,1,1]
	v_pk_mul_f32 v[92:93], v[40:41], v[78:79] op_sel:[1,1] op_sel_hi:[1,0] neg_lo:[1,0]
	v_pk_mul_f32 v[56:57], v[6:7], v[48:49] op_sel:[1,1] op_sel_hi:[1,0] neg_lo:[1,0]
	v_pk_add_f32 v[96:97], v[94:95], v[100:101] op_sel:[0,1] op_sel_hi:[1,0] neg_hi:[0,1]
	v_pk_add_f32 v[94:95], v[94:95], v[100:101] op_sel:[0,1] op_sel_hi:[1,0] neg_lo:[0,1]
	v_pk_fma_f32 v[78:79], v[40:41], v[78:79], v[92:93] op_sel_hi:[0,1,1]
	v_pk_mul_f32 v[92:93], v[44:45], v[68:69] op_sel:[1,1] op_sel_hi:[1,0] neg_lo:[1,0]
	v_pk_fma_f32 v[56:57], v[6:7], v[48:49], v[56:57] op_sel_hi:[0,1,1]
	v_pk_mul_f32 v[60:61], v[8:9], v[48:49] op_sel:[1,1] op_sel_hi:[1,0] neg_lo:[1,0]
	v_pk_fma_f32 v[68:69], v[44:45], v[68:69], v[92:93] op_sel_hi:[0,1,1]
	v_pk_mul_f32 v[92:93], v[48:49], v[94:95] op_sel:[1,1] op_sel_hi:[1,0] neg_lo:[1,0]
	v_pk_fma_f32 v[60:61], v[8:9], v[48:49], v[60:61] op_sel_hi:[0,1,1]
	v_pk_add_f32 v[64:65], v[64:65], v[70:71] op_sel:[0,1] op_sel_hi:[1,0] neg_lo:[0,1]
	v_pk_mul_f32 v[70:71], v[2:3], v[86:87] op_sel:[0,1] op_sel_hi:[1,0]
	v_pk_fma_f32 v[92:93], v[48:49], v[94:95], v[92:93] op_sel_hi:[0,1,1]
	v_pk_mul_f32 v[94:95], v[52:53], v[72:73] op_sel:[1,1] op_sel_hi:[1,0] neg_lo:[1,0]
	v_pk_fma_f32 v[70:71], v[4:5], v[86:87], v[70:71] op_sel_hi:[0,1,1]
	v_pk_mul_f32 v[86:87], v[8:9], v[90:91] op_sel:[1,1] op_sel_hi:[1,0] neg_lo:[1,0]
	v_pk_fma_f32 v[72:73], v[52:53], v[72:73], v[94:95] op_sel_hi:[0,1,1]
	v_pk_mul_f32 v[94:95], v[56:57], v[84:85] op_sel:[1,1] op_sel_hi:[1,0] neg_lo:[1,0]
	v_add_u32_e32 v5, 0x2000, v5
	v_pk_mul_f32 v[80:81], v[6:7], v[98:99] op_sel:[1,1] op_sel_hi:[1,0] neg_lo:[1,0]
	v_pk_fma_f32 v[86:87], v[8:9], v[90:91], v[86:87] op_sel_hi:[0,1,1]
	v_pk_mul_f32 v[90:91], v[10:11], v[96:97] op_sel:[1,1] op_sel_hi:[1,0] neg_lo:[1,0]
	v_pk_fma_f32 v[84:85], v[56:57], v[84:85], v[94:95] op_sel_hi:[0,1,1]
	v_pk_mul_f32 v[94:95], v[60:61], v[64:65] op_sel:[1,1] op_sel_hi:[1,0] neg_lo:[1,0]
	v_ashrrev_i32_e32 v5, 2, v5
	v_pk_fma_f32 v[80:81], v[6:7], v[98:99], v[80:81] op_sel_hi:[0,1,1]
	v_pk_fma_f32 v[90:91], v[10:11], v[96:97], v[90:91] op_sel_hi:[0,1,1]
	v_pk_fma_f32 v[64:65], v[60:61], v[64:65], v[94:95] op_sel_hi:[0,1,1]
	ds_write2_b64 v106, v[104:105], v[82:83] offset1:16
	ds_write2_b64 v106, v[90:91], v[92:93] offset0:33 offset1:49
	ds_write2_b64 v106, v[80:81], v[78:79] offset0:66 offset1:82
	ds_write2_b64 v106, v[76:77], v[84:85] offset0:99 offset1:115
	ds_write2_b64 v106, v[70:71], v[74:75] offset0:132 offset1:148
	ds_write2_b64 v106, v[88:89], v[72:73] offset0:165 offset1:181
	ds_write2_b64 v106, v[86:87], v[68:69] offset0:198 offset1:214
	ds_write2_b64 v106, v[66:67], v[64:65] offset0:231 offset1:247
	v_add3_u32 v18, v18, v5, s5
	ds_read2_b64 v[64:67], v18 offset1:16
	ds_read2_b64 v[68:71], v18 offset0:33 offset1:49
	ds_read2_b64 v[72:75], v18 offset0:66 offset1:82
	ds_read2_b64 v[76:79], v18 offset0:132 offset1:148
	ds_read2_b64 v[80:83], v18 offset0:99 offset1:115
	ds_read2_b64 v[84:87], v18 offset0:165 offset1:181
	ds_read2_b64 v[88:91], v18 offset0:198 offset1:214
	ds_read2_b64 v[92:95], v18 offset0:231 offset1:247
	s_waitcnt lgkmcnt(4)
	v_pk_add_f32 v[96:97], v[64:65], v[76:77]
	v_pk_add_f32 v[64:65], v[64:65], v[76:77] neg_lo:[0,1] neg_hi:[0,1]
	v_pk_add_f32 v[76:77], v[66:67], v[78:79]
	v_pk_add_f32 v[66:67], v[66:67], v[78:79] neg_lo:[0,1] neg_hi:[0,1]
	s_waitcnt lgkmcnt(1)
	v_pk_add_f32 v[98:99], v[74:75], v[90:91]
	v_pk_mul_f32 v[78:79], v[66:67], s[18:19]
	v_pk_add_f32 v[74:75], v[74:75], v[90:91] neg_lo:[0,1] neg_hi:[0,1]
	v_pk_fma_f32 v[66:67], v[66:67], s[16:17], v[78:79] op_sel:[0,0,1] op_sel_hi:[1,0,0]
	v_pk_add_f32 v[78:79], v[68:69], v[84:85]
	v_pk_add_f32 v[68:69], v[68:69], v[84:85] neg_lo:[0,1] neg_hi:[0,1]
	v_pk_mul_f32 v[90:91], v[74:75], s[40:41]
	v_pk_mul_f32 v[84:85], v[68:69], s[36:37]
	v_pk_fma_f32 v[74:75], v[74:75], s[68:69], v[90:91] op_sel:[0,0,1] op_sel_hi:[1,0,0] neg_lo:[1,0,0] neg_hi:[1,0,0]
	s_waitcnt lgkmcnt(0)
	v_pk_add_f32 v[90:91], v[80:81], v[92:93]
	v_pk_add_f32 v[80:81], v[80:81], v[92:93] neg_lo:[0,1] neg_hi:[0,1]
	v_pk_fma_f32 v[68:69], v[68:69], s[66:67], v[84:85] op_sel:[0,0,1] op_sel_hi:[1,0,0]
	v_pk_add_f32 v[84:85], v[70:71], v[86:87]
	v_pk_add_f32 v[70:71], v[70:71], v[86:87] neg_lo:[0,1] neg_hi:[0,1]
	v_pk_mul_f32 v[92:93], v[80:81], s[36:37]
	v_pk_mul_f32 v[86:87], v[70:71], s[40:41]
	v_pk_fma_f32 v[80:81], v[80:81], s[66:67], v[92:93] op_sel:[0,0,1] op_sel_hi:[1,0,0] neg_lo:[1,0,0] neg_hi:[1,0,0]
	v_pk_add_f32 v[92:93], v[82:83], v[94:95]
	v_pk_add_f32 v[82:83], v[82:83], v[94:95] neg_lo:[0,1] neg_hi:[0,1]
	v_pk_fma_f32 v[70:71], v[70:71], s[68:69], v[86:87] op_sel:[0,0,1] op_sel_hi:[1,0,0]
	v_pk_add_f32 v[86:87], v[72:73], v[88:89]
	v_pk_mul_f32 v[94:95], v[82:83], s[18:19]
	v_pk_add_f32 v[88:89], v[72:73], v[88:89] neg_lo:[0,1] neg_hi:[0,1]
	v_pk_fma_f32 v[82:83], v[82:83], s[16:17], v[94:95] op_sel:[0,0,1] op_sel_hi:[1,0,0] neg_lo:[1,0,0] neg_hi:[1,0,0]
	v_pk_add_f32 v[94:95], v[96:97], v[86:87]
	v_pk_add_f32 v[86:87], v[96:97], v[86:87] neg_lo:[0,1] neg_hi:[0,1]
	v_pk_add_f32 v[96:97], v[76:77], v[98:99]
	v_pk_add_f32 v[76:77], v[76:77], v[98:99] neg_lo:[0,1] neg_hi:[0,1]
	v_pk_mul_f32 v[98:99], v[76:77], s[36:37]
	v_pk_add_f32 v[100:101], v[84:85], v[92:93]
	v_pk_add_f32 v[84:85], v[84:85], v[92:93] neg_lo:[0,1] neg_hi:[0,1]
	v_pk_fma_f32 v[76:77], v[76:77], s[66:67], v[98:99] op_sel:[0,0,1] op_sel_hi:[1,0,0]
	v_pk_add_f32 v[98:99], v[78:79], v[90:91]
	v_pk_add_f32 v[90:91], v[78:79], v[90:91] neg_lo:[0,1] neg_hi:[0,1]
	v_pk_mul_f32 v[92:93], v[84:85], s[36:37]
	v_pk_add_f32 v[72:73], v[64:65], v[88:89] op_sel:[0,1] op_sel_hi:[1,0] neg_hi:[0,1]
	v_pk_add_f32 v[64:65], v[64:65], v[88:89] op_sel:[0,1] op_sel_hi:[1,0] neg_lo:[0,1]
	v_pk_add_f32 v[88:89], v[66:67], v[74:75]
	v_pk_add_f32 v[66:67], v[66:67], v[74:75] neg_lo:[0,1] neg_hi:[0,1]
	v_pk_fma_f32 v[84:85], v[84:85], s[66:67], v[92:93] op_sel:[0,0,1] op_sel_hi:[1,0,0] neg_lo:[1,0,0] neg_hi:[1,0,0]
	v_pk_mul_f32 v[74:75], v[66:67], s[36:37]
	v_pk_fma_f32 v[66:67], v[66:67], s[66:67], v[74:75] op_sel:[0,0,1] op_sel_hi:[1,0,0]
	v_pk_add_f32 v[74:75], v[68:69], v[80:81]
	v_pk_add_f32 v[92:93], v[70:71], v[82:83]
	v_pk_add_f32 v[70:71], v[70:71], v[82:83] neg_lo:[0,1] neg_hi:[0,1]
	v_pk_add_f32 v[78:79], v[86:87], v[90:91] op_sel:[0,1] op_sel_hi:[1,0] neg_hi:[0,1]
	v_pk_add_f32 v[86:87], v[86:87], v[90:91] op_sel:[0,1] op_sel_hi:[1,0] neg_lo:[0,1]
	v_pk_add_f32 v[90:91], v[76:77], v[84:85]
	v_pk_add_f32 v[84:85], v[76:77], v[84:85] neg_lo:[0,1] neg_hi:[0,1]
	v_pk_add_f32 v[80:81], v[68:69], v[80:81] neg_lo:[0,1] neg_hi:[0,1]
	v_pk_mul_f32 v[82:83], v[70:71], s[36:37]
	v_pk_add_f32 v[102:103], v[72:73], v[74:75]
	v_pk_add_f32 v[72:73], v[72:73], v[74:75] neg_lo:[0,1] neg_hi:[0,1]
	v_pk_add_f32 v[74:75], v[88:89], v[92:93]
	v_pk_fma_f32 v[70:71], v[70:71], s[66:67], v[82:83] op_sel:[0,0,1] op_sel_hi:[1,0,0] neg_lo:[1,0,0] neg_hi:[1,0,0]
	v_pk_add_f32 v[82:83], v[94:95], v[98:99]
	v_pk_add_f32 v[94:95], v[94:95], v[98:99] neg_lo:[0,1] neg_hi:[0,1]
	v_pk_add_f32 v[98:99], v[96:97], v[100:101]
	v_pk_add_f32 v[76:77], v[86:87], v[84:85] op_sel:[0,1] op_sel_hi:[1,0] neg_hi:[0,1]
	v_pk_add_f32 v[84:85], v[86:87], v[84:85] op_sel:[0,1] op_sel_hi:[1,0] neg_lo:[0,1]
	v_pk_add_f32 v[86:87], v[102:103], v[74:75]
	v_pk_add_f32 v[100:101], v[96:97], v[100:101] neg_lo:[0,1] neg_hi:[0,1]
	v_pk_add_f32 v[68:69], v[64:65], v[80:81] op_sel:[0,1] op_sel_hi:[1,0] neg_hi:[0,1]
	v_pk_add_f32 v[64:65], v[64:65], v[80:81] op_sel:[0,1] op_sel_hi:[1,0] neg_lo:[0,1]
	v_pk_add_f32 v[80:81], v[66:67], v[70:71]
	v_pk_add_f32 v[104:105], v[82:83], v[98:99]
	v_pk_add_f32 v[82:83], v[82:83], v[98:99] neg_lo:[0,1] neg_hi:[0,1]
	v_pk_add_f32 v[98:99], v[78:79], v[90:91]
	v_pk_mul_f32 v[2:3], v[2:3], v[86:87] op_sel:[0,1] op_sel_hi:[1,0]
	v_pk_add_f32 v[92:93], v[88:89], v[92:93] neg_lo:[0,1] neg_hi:[0,1]
	v_pk_add_f32 v[78:79], v[78:79], v[90:91] neg_lo:[0,1] neg_hi:[0,1]
	v_pk_add_f32 v[90:91], v[68:69], v[80:81]
	v_pk_fma_f32 v[2:3], v[4:5], v[86:87], v[2:3] op_sel_hi:[0,1,1]
	v_pk_mul_f32 v[4:5], v[6:7], v[98:99] op_sel:[1,1] op_sel_hi:[1,0] neg_lo:[1,0]
	v_pk_add_f32 v[70:71], v[66:67], v[70:71] neg_lo:[0,1] neg_hi:[0,1]
	v_pk_add_f32 v[96:97], v[94:95], v[100:101] op_sel:[0,1] op_sel_hi:[1,0] neg_hi:[0,1]
	v_pk_fma_f32 v[4:5], v[6:7], v[98:99], v[4:5] op_sel_hi:[0,1,1]
	v_pk_mul_f32 v[6:7], v[8:9], v[90:91] op_sel:[1,1] op_sel_hi:[1,0] neg_lo:[1,0]
	v_pk_add_f32 v[88:89], v[72:73], v[92:93] op_sel:[0,1] op_sel_hi:[1,0] neg_hi:[0,1]
	v_pk_fma_f32 v[6:7], v[8:9], v[90:91], v[6:7] op_sel_hi:[0,1,1]
	v_pk_mul_f32 v[8:9], v[10:11], v[96:97] op_sel:[1,1] op_sel_hi:[1,0] neg_lo:[1,0]
	v_pk_add_f32 v[66:67], v[64:65], v[70:71] op_sel:[0,1] op_sel_hi:[1,0] neg_hi:[0,1]
	v_pk_fma_f32 v[8:9], v[10:11], v[96:97], v[8:9] op_sel_hi:[0,1,1]
	v_pk_mul_f32 v[10:11], v[16:17], v[88:89] op_sel:[1,1] op_sel_hi:[1,0] neg_lo:[1,0]
	v_pk_add_f32 v[94:95], v[94:95], v[100:101] op_sel:[0,1] op_sel_hi:[1,0] neg_lo:[0,1]
	v_pk_add_f32 v[74:75], v[102:103], v[74:75] neg_lo:[0,1] neg_hi:[0,1]
	v_pk_add_f32 v[72:73], v[72:73], v[92:93] op_sel:[0,1] op_sel_hi:[1,0] neg_lo:[0,1]
	v_pk_add_f32 v[68:69], v[68:69], v[80:81] neg_lo:[0,1] neg_hi:[0,1]
	v_pk_add_f32 v[64:65], v[64:65], v[70:71] op_sel:[0,1] op_sel_hi:[1,0] neg_lo:[0,1]
	v_pk_fma_f32 v[10:11], v[16:17], v[88:89], v[10:11] op_sel_hi:[0,1,1]
	v_pk_mul_f32 v[12:13], v[24:25], v[76:77] op_sel:[1,1] op_sel_hi:[1,0] neg_lo:[1,0]
	v_pk_mul_f32 v[14:15], v[28:29], v[66:67] op_sel:[1,1] op_sel_hi:[1,0] neg_lo:[1,0]
	v_pk_mul_f32 v[16:17], v[32:33], v[82:83] op_sel:[1,1] op_sel_hi:[1,0] neg_lo:[1,0]
	v_pk_fma_f32 v[12:13], v[24:25], v[76:77], v[12:13] op_sel_hi:[0,1,1]
	v_pk_fma_f32 v[14:15], v[28:29], v[66:67], v[14:15] op_sel_hi:[0,1,1]
	v_pk_fma_f32 v[16:17], v[32:33], v[82:83], v[16:17] op_sel_hi:[0,1,1]
	v_pk_mul_f32 v[20:21], v[36:37], v[74:75] op_sel:[1,1] op_sel_hi:[1,0] neg_lo:[1,0]
	v_pk_mul_f32 v[22:23], v[40:41], v[78:79] op_sel:[1,1] op_sel_hi:[1,0] neg_lo:[1,0]
	v_pk_mul_f32 v[24:25], v[44:45], v[68:69] op_sel:[1,1] op_sel_hi:[1,0] neg_lo:[1,0]
	v_pk_mul_f32 v[26:27], v[48:49], v[94:95] op_sel:[1,1] op_sel_hi:[1,0] neg_lo:[1,0]
	v_pk_mul_f32 v[28:29], v[52:53], v[72:73] op_sel:[1,1] op_sel_hi:[1,0] neg_lo:[1,0]
	v_pk_mul_f32 v[30:31], v[56:57], v[84:85] op_sel:[1,1] op_sel_hi:[1,0] neg_lo:[1,0]
	v_pk_mul_f32 v[32:33], v[60:61], v[64:65] op_sel:[1,1] op_sel_hi:[1,0] neg_lo:[1,0]
	v_pk_fma_f32 v[20:21], v[36:37], v[74:75], v[20:21] op_sel_hi:[0,1,1]
	v_pk_fma_f32 v[22:23], v[40:41], v[78:79], v[22:23] op_sel_hi:[0,1,1]
	v_pk_fma_f32 v[24:25], v[44:45], v[68:69], v[24:25] op_sel_hi:[0,1,1]
	v_pk_fma_f32 v[26:27], v[48:49], v[94:95], v[26:27] op_sel_hi:[0,1,1]
	v_pk_fma_f32 v[28:29], v[52:53], v[72:73], v[28:29] op_sel_hi:[0,1,1]
	v_pk_fma_f32 v[30:31], v[56:57], v[84:85], v[30:31] op_sel_hi:[0,1,1]
	v_pk_fma_f32 v[32:33], v[60:61], v[64:65], v[32:33] op_sel_hi:[0,1,1]
	ds_write2_b64 v18, v[104:105], v[16:17] offset1:16
	ds_write2_b64 v18, v[8:9], v[26:27] offset0:33 offset1:49
	ds_write2_b64 v18, v[4:5], v[22:23] offset0:66 offset1:82
	ds_write2_b64 v18, v[12:13], v[30:31] offset0:99 offset1:115
	ds_write2_b64 v18, v[2:3], v[20:21] offset0:132 offset1:148
	ds_write2_b64 v18, v[10:11], v[28:29] offset0:165 offset1:181
	ds_write2_b64 v18, v[6:7], v[24:25] offset0:198 offset1:214
	ds_write2_b64 v18, v[14:15], v[32:33] offset0:231 offset1:247
	v_ashrrev_i32_e32 v2, 31, v210
	v_add_u32_sdwa v2, v210, v2 dst_sel:DWORD dst_unused:UNUSED_PAD src0_sel:DWORD src1_sel:BYTE_3
	s_lshl_b64 s[0:1], s[64:65], 15
	v_and_b32_e32 v2, 0xffffff00, v2
	s_add_u32 s0, s29, s0
	v_sub_u32_e32 v2, v210, v2
	s_addc_u32 s1, s85, s1
	v_ashrrev_i32_e32 v3, 31, v2
	v_lshl_add_u64 v[14:15], v[2:3], 3, s[0:1]
	s_movk_i32 s0, 0x1000
	v_add_co_u32_e32 v16, vcc, s0, v14
	s_movk_i32 s0, 0x3000
	s_nop 0
	v_addc_co_u32_e32 v17, vcc, 0, v15, vcc
	v_add_co_u32_e32 v2, vcc, s92, v14
	s_waitcnt lgkmcnt(0)
	s_nop 0
	v_addc_co_u32_e32 v3, vcc, 0, v15, vcc
	v_add_co_u32_e32 v22, vcc, s0, v14
	s_movk_i32 s0, 0x5000
	s_nop 0
	v_addc_co_u32_e32 v23, vcc, 0, v15, vcc
	v_add_co_u32_e32 v8, vcc, s95, v14
	s_barrier
	s_nop 0
	v_addc_co_u32_e32 v9, vcc, 0, v15, vcc
	v_add_co_u32_e32 v26, vcc, s0, v14
	s_nop 1
	v_addc_co_u32_e32 v27, vcc, 0, v15, vcc
	v_add_co_u32_e32 v10, vcc, s96, v14
	global_load_dwordx2 v[12:13], v[2:3], off nt
	global_load_dwordx2 v[6:7], v[2:3], off offset:2048 nt
	global_load_dwordx2 v[4:5], v[8:9], off offset:-4096 nt
	global_load_dwordx2 v[122:123], v[8:9], off nt
	v_addc_co_u32_e32 v11, vcc, 0, v15, vcc
	v_add_co_u32_e32 v28, vcc, s97, v14
	global_load_dwordx2 v[46:47], v[8:9], off offset:2048 nt
	global_load_dwordx2 v[38:39], v[10:11], off offset:-4096 nt
	global_load_dwordx2 v[20:21], v[10:11], off nt
	s_nop 0
	global_load_dwordx2 v[10:11], v[10:11], off offset:2048 nt
	v_addc_co_u32_e32 v29, vcc, 0, v15, vcc
	global_load_dwordx2 v[24:25], v[2:3], off offset:-4096 nt
	s_nop 0
	global_load_dwordx2 v[26:27], v[26:27], off offset:2048 nt
	s_nop 0
	global_load_dwordx2 v[8:9], v[28:29], off nt
	global_load_dwordx2 v[2:3], v[28:29], off offset:2048 nt
	global_load_dwordx2 v[30:31], v[14:15], off offset:2048 nt
	s_nop 0
	global_load_dwordx2 v[28:29], v[16:17], off offset:2048 nt
	s_nop 0
	global_load_dwordx2 v[16:17], v[22:23], off offset:2048 nt
	global_load_dwordx2 v[32:33], v[14:15], off nt
	v_mov_b32_e32 v14, v210
	s_waitcnt vmcnt(15)
	v_cvt_f32_f16_sdwa v164, v12 dst_sel:DWORD dst_unused:UNUSED_PAD src0_sel:WORD_1
	v_ashrrev_i32_e32 v15, 31, v14
	v_add_u32_sdwa v15, v14, v15 dst_sel:DWORD dst_unused:UNUSED_PAD src0_sel:DWORD src1_sel:BYTE_3
	v_ashrrev_i32_e32 v15, 8, v15
	v_mul_i32_i24_e32 v18, 0x100, v15
	v_sub_u32_e32 v18, v14, v18
	v_lshlrev_b32_e32 v14, 13, v15
	v_lshlrev_b32_e32 v15, 1, v18
	v_bfrev_b32_e32 v15, v15
	v_lshrrev_b32_e32 v15, 23, v15
	v_sub_u32_e32 v15, 0x200, v15
	v_bfrev_b32_e32 v15, v15
	v_lshrrev_b32_e32 v15, 19, v15
	v_and_b32_e32 v15, 0x1ff0, v15
	v_cmp_eq_u32_e64 s[0:1], 0, v18
	v_lshl_add_u32 v22, v18, 5, v14
	v_lshl_add_u32 v23, v22, 3, 0
	v_cndmask_b32_e64 v15, v15, 16, s[0:1]
	v_or_b32_e32 v14, v15, v14
	v_ashrrev_i32_e32 v22, 2, v22
	v_ashrrev_i32_e32 v15, 5, v14
	v_add_u32_e32 v211, v23, v22
	v_lshlrev_b32_e32 v14, 3, v14
	v_lshlrev_b32_e32 v15, 3, v15
	v_add3_u32 v212, 0, v14, v15
	ds_read2_b64 v[34:37], v211 offset1:1
	ds_read2_b64 v[40:43], v211 offset0:2 offset1:3
	ds_read2_b64 v[48:51], v212 offset1:1
	ds_read2_b64 v[52:55], v212 offset0:2 offset1:3
	ds_read2_b64 v[56:59], v211 offset0:4 offset1:5
	ds_read2_b64 v[60:63], v211 offset0:6 offset1:7
	ds_read2_b64 v[68:71], v212 offset0:4 offset1:5
	ds_read2_b64 v[72:75], v212 offset0:6 offset1:7
	ds_read2_b64 v[64:67], v211 offset0:8 offset1:9
	ds_read2_b64 v[76:79], v211 offset0:10 offset1:11
	ds_read2_b64 v[80:83], v212 offset0:8 offset1:9
	ds_read2_b64 v[98:101], v212 offset0:10 offset1:11
	ds_read2_b64 v[84:87], v211 offset0:12 offset1:13
	ds_read2_b64 v[88:91], v211 offset0:14 offset1:15
	ds_read2_b64 v[102:105], v212 offset0:12 offset1:13
	ds_read2_b64 v[106:109], v212 offset0:14 offset1:15
	s_waitcnt lgkmcnt(7)
	v_pk_add_f32 v[14:15], v[34:35], v[64:65]
	v_pk_add_f32 v[22:23], v[34:35], v[64:65] neg_lo:[0,1] neg_hi:[0,1]
	v_pk_add_f32 v[34:35], v[36:37], v[66:67]
	v_pk_add_f32 v[36:37], v[36:37], v[66:67] neg_lo:[0,1] neg_hi:[0,1]
	v_cmp_ne_u32_e32 vcc, 0, v18
	v_pk_mul_f32 v[44:45], v[36:37], s[18:19]
	v_bfrev_b32_e32 v18, v18
	v_pk_fma_f32 v[36:37], v[36:37], s[16:17], v[44:45] op_sel:[0,0,1] op_sel_hi:[1,0,0]
	s_waitcnt lgkmcnt(6)
	v_pk_add_f32 v[44:45], v[40:41], v[76:77]
	v_pk_add_f32 v[40:41], v[40:41], v[76:77] neg_lo:[0,1] neg_hi:[0,1]
	v_cvt_f32_ubyte3_e32 v18, v18
	v_pk_mul_f32 v[64:65], v[40:41], s[36:37]
	v_mul_f32_e32 v18, 0x38800000, v18
	v_pk_fma_f32 v[40:41], v[40:41], s[66:67], v[64:65] op_sel:[0,0,1] op_sel_hi:[1,0,0]
	v_pk_add_f32 v[64:65], v[42:43], v[78:79]
	v_pk_add_f32 v[42:43], v[42:43], v[78:79] neg_lo:[0,1] neg_hi:[0,1]
	s_waitcnt lgkmcnt(3)
	v_pk_add_f32 v[78:79], v[58:59], v[86:87]
	v_pk_mul_f32 v[66:67], v[42:43], s[40:41]
	v_pk_add_f32 v[58:59], v[58:59], v[86:87] neg_lo:[0,1] neg_hi:[0,1]
	v_pk_fma_f32 v[42:43], v[42:43], s[68:69], v[66:67] op_sel:[0,0,1] op_sel_hi:[1,0,0]
	v_pk_add_f32 v[66:67], v[56:57], v[84:85]
	v_pk_add_f32 v[76:77], v[56:57], v[84:85] neg_lo:[0,1] neg_hi:[0,1]
	v_pk_mul_f32 v[84:85], v[58:59], s[40:41]
	v_pk_fma_f32 v[58:59], v[58:59], s[68:69], v[84:85] op_sel:[0,0,1] op_sel_hi:[1,0,0] neg_lo:[1,0,0] neg_hi:[1,0,0]
	s_waitcnt lgkmcnt(2)
	v_pk_add_f32 v[84:85], v[60:61], v[88:89]
	v_pk_add_f32 v[60:61], v[60:61], v[88:89] neg_lo:[0,1] neg_hi:[0,1]
	v_pk_mul_f32 v[86:87], v[60:61], s[36:37]
	v_pk_add_f32 v[56:57], v[22:23], v[76:77] op_sel:[0,1] op_sel_hi:[1,0] neg_hi:[0,1]
	v_pk_fma_f32 v[60:61], v[60:61], s[66:67], v[86:87] op_sel:[0,0,1] op_sel_hi:[1,0,0] neg_lo:[1,0,0] neg_hi:[1,0,0]
	v_pk_add_f32 v[86:87], v[62:63], v[90:91]
	v_pk_add_f32 v[62:63], v[62:63], v[90:91] neg_lo:[0,1] neg_hi:[0,1]
	v_pk_add_f32 v[90:91], v[64:65], v[86:87]
	v_pk_mul_f32 v[88:89], v[62:63], s[18:19]
	v_pk_add_f32 v[64:65], v[64:65], v[86:87] neg_lo:[0,1] neg_hi:[0,1]
	v_pk_fma_f32 v[62:63], v[62:63], s[16:17], v[88:89] op_sel:[0,0,1] op_sel_hi:[1,0,0] neg_lo:[1,0,0] neg_hi:[1,0,0]
	v_pk_add_f32 v[88:89], v[14:15], v[66:67]
	v_pk_add_f32 v[14:15], v[14:15], v[66:67] neg_lo:[0,1] neg_hi:[0,1]
	v_pk_add_f32 v[66:67], v[34:35], v[78:79]
	v_pk_add_f32 v[34:35], v[34:35], v[78:79] neg_lo:[0,1] neg_hi:[0,1]
	v_pk_add_f32 v[22:23], v[22:23], v[76:77] op_sel:[0,1] op_sel_hi:[1,0] neg_lo:[0,1]
	v_pk_mul_f32 v[78:79], v[34:35], s[36:37]
	v_pk_add_f32 v[76:77], v[36:37], v[58:59]
	v_pk_add_f32 v[36:37], v[36:37], v[58:59] neg_lo:[0,1] neg_hi:[0,1]
	v_pk_fma_f32 v[34:35], v[34:35], s[66:67], v[78:79] op_sel:[0,0,1] op_sel_hi:[1,0,0]
	v_pk_add_f32 v[78:79], v[44:45], v[84:85]
	v_pk_add_f32 v[84:85], v[44:45], v[84:85] neg_lo:[0,1] neg_hi:[0,1]
	v_pk_mul_f32 v[86:87], v[64:65], s[36:37]
	v_pk_mul_f32 v[58:59], v[36:37], s[36:37]
	v_pk_fma_f32 v[64:65], v[64:65], s[66:67], v[86:87] op_sel:[0,0,1] op_sel_hi:[1,0,0] neg_lo:[1,0,0] neg_hi:[1,0,0]
	v_pk_fma_f32 v[36:37], v[36:37], s[66:67], v[58:59] op_sel:[0,0,1] op_sel_hi:[1,0,0]
	v_pk_add_f32 v[58:59], v[40:41], v[60:61]
	v_pk_add_f32 v[86:87], v[42:43], v[62:63]
	v_pk_add_f32 v[42:43], v[42:43], v[62:63] neg_lo:[0,1] neg_hi:[0,1]
	v_pk_mul_f32 v[62:63], v[42:43], s[36:37]
	v_pk_add_f32 v[44:45], v[14:15], v[84:85] op_sel:[0,1] op_sel_hi:[1,0] neg_hi:[0,1]
	v_pk_add_f32 v[14:15], v[14:15], v[84:85] op_sel:[0,1] op_sel_hi:[1,0] neg_lo:[0,1]
	v_pk_add_f32 v[84:85], v[34:35], v[64:65]
	v_pk_add_f32 v[64:65], v[34:35], v[64:65] neg_lo:[0,1] neg_hi:[0,1]
	v_pk_add_f32 v[94:95], v[56:57], v[58:59]
	v_pk_add_f32 v[56:57], v[56:57], v[58:59] neg_lo:[0,1] neg_hi:[0,1]
	v_pk_add_f32 v[58:59], v[76:77], v[86:87]
	v_pk_fma_f32 v[42:43], v[42:43], s[66:67], v[62:63] op_sel:[0,0,1] op_sel_hi:[1,0,0] neg_lo:[1,0,0] neg_hi:[1,0,0]
	v_pk_add_f32 v[62:63], v[88:89], v[78:79]
	v_pk_add_f32 v[78:79], v[88:89], v[78:79] neg_lo:[0,1] neg_hi:[0,1]
	v_pk_add_f32 v[88:89], v[66:67], v[90:91]
	v_pk_add_f32 v[110:111], v[76:77], v[86:87] neg_lo:[0,1] neg_hi:[0,1]
	v_pk_add_f32 v[86:87], v[94:95], v[58:59]
	v_pk_add_f32 v[34:35], v[94:95], v[58:59] neg_lo:[0,1] neg_hi:[0,1]
	v_pk_add_f32 v[58:59], v[50:51], v[82:83]
	v_pk_add_f32 v[50:51], v[50:51], v[82:83] neg_lo:[0,1] neg_hi:[0,1]
	v_pk_add_f32 v[60:61], v[40:41], v[60:61] neg_lo:[0,1] neg_hi:[0,1]
	v_pk_add_f32 v[148:149], v[62:63], v[88:89]
	v_pk_add_f32 v[138:139], v[62:63], v[88:89] neg_lo:[0,1] neg_hi:[0,1]
	v_pk_mul_f32 v[62:63], v[50:51], s[18:19]
	v_pk_add_f32 v[90:91], v[66:67], v[90:91] neg_lo:[0,1] neg_hi:[0,1]
	v_pk_fma_f32 v[50:51], v[50:51], s[16:17], v[62:63] op_sel:[0,0,1] op_sel_hi:[1,0,0]
	v_pk_add_f32 v[62:63], v[52:53], v[98:99]
	v_pk_add_f32 v[52:53], v[52:53], v[98:99] neg_lo:[0,1] neg_hi:[0,1]
	v_pk_add_f32 v[112:113], v[22:23], v[60:61] op_sel:[0,1] op_sel_hi:[1,0] neg_hi:[0,1]
	v_pk_add_f32 v[114:115], v[22:23], v[60:61] op_sel:[0,1] op_sel_hi:[1,0] neg_lo:[0,1]
	v_pk_add_f32 v[96:97], v[44:45], v[84:85]
	v_pk_add_f32 v[66:67], v[44:45], v[84:85] neg_lo:[0,1] neg_hi:[0,1]
	v_pk_add_f32 v[60:61], v[14:15], v[64:65] op_sel:[0,1] op_sel_hi:[1,0] neg_hi:[0,1]
	v_pk_add_f32 v[84:85], v[14:15], v[64:65] op_sel:[0,1] op_sel_hi:[1,0] neg_lo:[0,1]
	v_pk_mul_f32 v[64:65], v[52:53], s[36:37]
	v_pk_fma_f32 v[52:53], v[52:53], s[66:67], v[64:65] op_sel:[0,0,1] op_sel_hi:[1,0,0]
	v_pk_add_f32 v[64:65], v[54:55], v[100:101]
	v_pk_add_f32 v[54:55], v[54:55], v[100:101] neg_lo:[0,1] neg_hi:[0,1]
	v_pk_mul_f32 v[76:77], v[54:55], s[40:41]
	v_pk_add_f32 v[92:93], v[78:79], v[90:91] op_sel:[0,1] op_sel_hi:[1,0] neg_hi:[0,1]
	v_pk_fma_f32 v[54:55], v[54:55], s[68:69], v[76:77] op_sel:[0,0,1] op_sel_hi:[1,0,0]
	s_waitcnt lgkmcnt(1)
	v_pk_add_f32 v[76:77], v[68:69], v[102:103]
	v_pk_add_f32 v[68:69], v[68:69], v[102:103] neg_lo:[0,1] neg_hi:[0,1]
	v_pk_add_f32 v[88:89], v[78:79], v[90:91] op_sel:[0,1] op_sel_hi:[1,0] neg_lo:[0,1]
	v_xor_b32_e32 v79, 0x80000000, v68
	v_mov_b32_e32 v78, v69
	v_pk_add_f32 v[68:69], v[70:71], v[104:105]
	v_pk_add_f32 v[70:71], v[70:71], v[104:105] neg_lo:[0,1] neg_hi:[0,1]
	v_pk_add_f32 v[40:41], v[56:57], v[110:111] op_sel:[0,1] op_sel_hi:[1,0] neg_hi:[0,1]
	v_pk_add_f32 v[44:45], v[56:57], v[110:111] op_sel:[0,1] op_sel_hi:[1,0] neg_lo:[0,1]
	v_pk_add_f32 v[56:57], v[48:49], v[80:81]
	v_pk_add_f32 v[48:49], v[48:49], v[80:81] neg_lo:[0,1] neg_hi:[0,1]
	v_pk_mul_f32 v[80:81], v[70:71], s[40:41]
	v_cndmask_b32_e64 v18, v18, v208, s[0:1]
	v_pk_fma_f32 v[70:71], v[70:71], s[68:69], v[80:81] op_sel:[0,0,1] op_sel_hi:[1,0,0] neg_lo:[1,0,0] neg_hi:[1,0,0]
	s_waitcnt lgkmcnt(0)
	v_pk_add_f32 v[80:81], v[72:73], v[106:107]
	v_pk_add_f32 v[72:73], v[72:73], v[106:107] neg_lo:[0,1] neg_hi:[0,1]
	v_pk_add_f32 v[22:23], v[36:37], v[42:43]
	v_pk_mul_f32 v[82:83], v[72:73], s[36:37]
	v_pk_add_f32 v[116:117], v[36:37], v[42:43] neg_lo:[0,1] neg_hi:[0,1]
	v_pk_fma_f32 v[72:73], v[72:73], s[66:67], v[82:83] op_sel:[0,0,1] op_sel_hi:[1,0,0] neg_lo:[1,0,0] neg_hi:[1,0,0]
	v_pk_add_f32 v[82:83], v[74:75], v[108:109]
	v_pk_add_f32 v[74:75], v[74:75], v[108:109] neg_lo:[0,1] neg_hi:[0,1]
	v_pk_mul_f32 v[90:91], v[74:75], s[18:19]
	v_pk_fma_f32 v[74:75], v[74:75], s[16:17], v[90:91] op_sel:[0,0,1] op_sel_hi:[1,0,0] neg_lo:[1,0,0] neg_hi:[1,0,0]
	v_pk_add_f32 v[90:91], v[56:57], v[76:77]
	v_pk_add_f32 v[56:57], v[56:57], v[76:77] neg_lo:[0,1] neg_hi:[0,1]
	v_pk_add_f32 v[76:77], v[58:59], v[68:69]
	v_pk_add_f32 v[58:59], v[58:59], v[68:69] neg_lo:[0,1] neg_hi:[0,1]
	v_pk_add_f32 v[14:15], v[114:115], v[116:117] op_sel:[0,1] op_sel_hi:[1,0] neg_hi:[0,1]
	v_pk_mul_f32 v[68:69], v[58:59], s[36:37]
	v_pk_add_f32 v[36:37], v[114:115], v[116:117] op_sel:[0,1] op_sel_hi:[1,0] neg_lo:[0,1]
	v_pk_fma_f32 v[58:59], v[58:59], s[66:67], v[68:69] op_sel:[0,0,1] op_sel_hi:[1,0,0]
	v_pk_add_f32 v[68:69], v[62:63], v[80:81]
	v_pk_add_f32 v[80:81], v[62:63], v[80:81] neg_lo:[0,1] neg_hi:[0,1]
	s_waitcnt vmcnt(0)
	v_cvt_f32_f16_e32 v193, v33
	s_nop 0
	s_nop 0
	v_pk_add_f32 v[62:63], v[64:65], v[82:83]
	v_pk_add_f32 v[64:65], v[64:65], v[82:83] neg_lo:[0,1] neg_hi:[0,1]
	v_cvt_f32_f16_sdwa v192, v32 dst_sel:DWORD dst_unused:UNUSED_PAD src0_sel:WORD_1
	v_pk_mul_f32 v[82:83], v[64:65], s[36:37]
	v_cvt_f32_f16_e32 v194, v32
	v_pk_fma_f32 v[64:65], v[64:65], s[66:67], v[82:83] op_sel:[0,0,1] op_sel_hi:[1,0,0] neg_lo:[1,0,0] neg_hi:[1,0,0]
	v_pk_add_f32 v[82:83], v[48:49], v[78:79]
	v_pk_add_f32 v[48:49], v[48:49], v[78:79] neg_lo:[0,1] neg_hi:[0,1]
	v_pk_add_f32 v[78:79], v[50:51], v[70:71]
	v_pk_add_f32 v[50:51], v[50:51], v[70:71] neg_lo:[0,1] neg_hi:[0,1]
	v_cvt_f32_f16_sdwa v195, v33 dst_sel:DWORD dst_unused:UNUSED_PAD src0_sel:WORD_1
	v_pk_mul_f32 v[70:71], v[50:51], s[36:37]
	v_cvt_f32_f16_sdwa v170, v30 dst_sel:DWORD dst_unused:UNUSED_PAD src0_sel:WORD_1
	v_pk_fma_f32 v[50:51], v[50:51], s[66:67], v[70:71] op_sel:[0,0,1] op_sel_hi:[1,0,0]
	v_pk_add_f32 v[70:71], v[52:53], v[72:73]
	v_pk_add_f32 v[72:73], v[52:53], v[72:73] neg_lo:[0,1] neg_hi:[0,1]
	v_cvt_f32_f16_e32 v171, v31
	s_nop 0
	s_nop 0
	v_pk_add_f32 v[52:53], v[54:55], v[74:75]
	v_pk_add_f32 v[54:55], v[54:55], v[74:75] neg_lo:[0,1] neg_hi:[0,1]
	v_cvt_f32_f16_sdwa v185, v31 dst_sel:DWORD dst_unused:UNUSED_PAD src0_sel:WORD_1
	v_pk_mul_f32 v[74:75], v[54:55], s[36:37]
	v_cvt_f32_f16_e32 v184, v30
	v_pk_fma_f32 v[54:55], v[54:55], s[66:67], v[74:75] op_sel:[0,0,1] op_sel_hi:[1,0,0] neg_lo:[1,0,0] neg_hi:[1,0,0]
	v_pk_add_f32 v[74:75], v[90:91], v[68:69]
	v_pk_add_f32 v[68:69], v[90:91], v[68:69] neg_lo:[0,1] neg_hi:[0,1]
	v_pk_add_f32 v[90:91], v[76:77], v[62:63]
	v_pk_add_f32 v[62:63], v[76:77], v[62:63] neg_lo:[0,1] neg_hi:[0,1]
	v_cvt_f32_f16_sdwa v172, v24 dst_sel:DWORD dst_unused:UNUSED_PAD src0_sel:WORD_1
	v_xor_b32_e32 v77, 0x80000000, v62
	v_mov_b32_e32 v76, v63
	v_pk_add_f32 v[62:63], v[56:57], v[80:81] op_sel:[0,1] op_sel_hi:[1,0] neg_hi:[0,1]
	v_pk_add_f32 v[56:57], v[56:57], v[80:81] op_sel:[0,1] op_sel_hi:[1,0] neg_lo:[0,1]
	v_pk_add_f32 v[80:81], v[58:59], v[64:65]
	v_pk_add_f32 v[58:59], v[58:59], v[64:65] neg_lo:[0,1] neg_hi:[0,1]
	v_cvt_f32_f16_e32 v173, v25
	v_xor_b32_e32 v65, 0x80000000, v58
	v_mov_b32_e32 v64, v59
	v_pk_add_f32 v[58:59], v[82:83], v[70:71]
	v_pk_add_f32 v[70:71], v[82:83], v[70:71] neg_lo:[0,1] neg_hi:[0,1]
	v_pk_add_f32 v[82:83], v[78:79], v[52:53]
	v_pk_add_f32 v[52:53], v[78:79], v[52:53] neg_lo:[0,1] neg_hi:[0,1]
	v_pk_add_f32 v[118:119], v[58:59], v[82:83]
	v_pk_add_f32 v[134:135], v[58:59], v[82:83] neg_lo:[0,1] neg_hi:[0,1]
	v_cos_f32_e32 v83, v18
	v_sin_f32_e32 v82, v18
	v_cvt_f32_f16_sdwa v181, v25 dst_sel:DWORD dst_unused:UNUSED_PAD src0_sel:WORD_1
	v_cvt_f32_f16_e32 v180, v24
	v_cvt_f32_f16_sdwa v174, v28 dst_sel:DWORD dst_unused:UNUSED_PAD src0_sel:WORD_1
	v_cvt_f32_f16_e32 v175, v29
	v_cvt_f32_f16_sdwa v179, v29 dst_sel:DWORD dst_unused:UNUSED_PAD src0_sel:WORD_1
	v_cvt_f32_f16_e32 v178, v28
	v_cvt_f32_f16_e32 v165, v13
	v_cvt_f32_f16_sdwa v167, v13 dst_sel:DWORD dst_unused:UNUSED_PAD src0_sel:WORD_1
	v_cvt_f32_f16_e32 v166, v12
	v_cvt_f32_f16_e32 v154, v6
	v_cvt_f32_f16_e32 v155, v7
	v_cvt_f32_f16_sdwa v157, v7 dst_sel:DWORD dst_unused:UNUSED_PAD src0_sel:WORD_1
	v_cvt_f32_f16_sdwa v156, v6 dst_sel:DWORD dst_unused:UNUSED_PAD src0_sel:WORD_1
	v_cvt_f32_f16_sdwa v140, v4 dst_sel:DWORD dst_unused:UNUSED_PAD src0_sel:WORD_1
	v_cvt_f32_f16_e32 v141, v5
	v_cvt_f32_f16_sdwa v143, v5 dst_sel:DWORD dst_unused:UNUSED_PAD src0_sel:WORD_1
	v_cvt_f32_f16_e32 v142, v4
	v_cvt_f32_f16_e32 v124, v16
	v_cvt_f32_f16_e32 v125, v17
	v_cvt_f32_f16_sdwa v127, v17 dst_sel:DWORD dst_unused:UNUSED_PAD src0_sel:WORD_1
	v_cvt_f32_f16_sdwa v126, v16 dst_sel:DWORD dst_unused:UNUSED_PAD src0_sel:WORD_1
	v_cvt_f32_f16_sdwa v114, v122 dst_sel:DWORD dst_unused:UNUSED_PAD src0_sel:WORD_1
	v_cvt_f32_f16_e32 v115, v123
	v_cvt_f32_f16_sdwa v117, v123 dst_sel:DWORD dst_unused:UNUSED_PAD src0_sel:WORD_1
	v_cvt_f32_f16_e32 v116, v122
	v_xor_b32_e32 v79, 0x80000000, v52
	v_mov_b32_e32 v78, v53
	v_pk_add_f32 v[52:53], v[48:49], v[72:73] op_sel:[0,1] op_sel_hi:[1,0] neg_hi:[0,1]
	v_pk_add_f32 v[48:49], v[48:49], v[72:73] op_sel:[0,1] op_sel_hi:[1,0] neg_lo:[0,1]
	v_pk_add_f32 v[72:73], v[50:51], v[54:55]
	v_pk_add_f32 v[50:51], v[50:51], v[54:55] neg_lo:[0,1] neg_hi:[0,1]
	v_pk_fma_f32 v[160:161], v[82:83], 0, v[82:83] op_sel:[0,0,1] op_sel_hi:[1,0,0] neg_lo:[1,0,0] neg_hi:[1,0,0]
	v_xor_b32_e32 v55, 0x80000000, v50
	v_mov_b32_e32 v54, v51
	v_pk_fma_f32 v[198:199], v[82:83], 0, v[82:83] op_sel:[0,0,1] op_sel_hi:[1,0,0]
	v_pk_add_f32 v[42:43], v[112:113], v[22:23]
	v_pk_add_f32 v[22:23], v[112:113], v[22:23] neg_lo:[0,1] neg_hi:[0,1]
	v_pk_add_f32 v[98:99], v[74:75], v[90:91]
	v_pk_add_f32 v[100:101], v[74:75], v[90:91] neg_lo:[0,1] neg_hi:[0,1]
	v_pk_add_f32 v[102:103], v[68:69], v[76:77]
	v_pk_add_f32 v[106:107], v[68:69], v[76:77] neg_lo:[0,1] neg_hi:[0,1]
	v_pk_add_f32 v[104:105], v[62:63], v[80:81]
	v_pk_add_f32 v[108:109], v[62:63], v[80:81] neg_lo:[0,1] neg_hi:[0,1]
	v_pk_add_f32 v[110:111], v[56:57], v[64:65]
	v_pk_add_f32 v[112:113], v[56:57], v[64:65] neg_lo:[0,1] neg_hi:[0,1]
	v_pk_add_f32 v[152:153], v[70:71], v[78:79]
	v_pk_add_f32 v[162:163], v[70:71], v[78:79] neg_lo:[0,1] neg_hi:[0,1]
	v_pk_add_f32 v[176:177], v[52:53], v[72:73]
	v_pk_add_f32 v[182:183], v[52:53], v[72:73] neg_lo:[0,1] neg_hi:[0,1]
	v_pk_add_f32 v[188:189], v[48:49], v[54:55]
	v_pk_add_f32 v[196:197], v[48:49], v[54:55] neg_lo:[0,1] neg_hi:[0,1]
	v_pk_mul_f32 v[186:187], v[82:83], 0 op_sel_hi:[1,0]
	v_mov_b32_e32 v190, v160
	v_mov_b32_e32 v191, v199
	v_mul_f32_e32 v18, 0x3f3504f3, v83
	v_mul_f32_e32 v158, 0xbec3ef15, v83
	v_mul_f32_e32 v132, 0xbf6c835e, v83
	s_and_saveexec_b64 s[0:1], vcc
	s_xor_b64 s[0:1], exec, s[0:1]
	s_cbranch_execz .LBB0_536
	v_pk_add_f32 v[4:5], v[148:149], v[196:197]
	v_pk_add_f32 v[6:7], v[148:149], v[196:197] neg_lo:[0,1] neg_hi:[0,1]
	v_mul_f32_e32 v4, 0.5, v4
	v_mul_f32_e32 v12, 0.5, v7
	v_mov_b32_e32 v7, v5
	v_pk_mul_f32 v[6:7], v[6:7], s[44:45]
	v_pk_mov_b32 v[16:17], v[198:199], v[160:161] op_sel:[1,0]
	v_pk_mul_f32 v[24:25], v[190:191], v[6:7] op_sel:[0,1] op_sel_hi:[1,0]
	v_pk_mul_f32 v[6:7], v[190:191], v[6:7]
	v_pk_add_f32 v[24:25], v[24:25], v[24:25] op_sel:[0,1] op_sel_hi:[0,1]
	v_pk_add_f32 v[28:29], v[4:5], v[24:25]
	v_pk_add_f32 v[4:5], v[4:5], v[24:25] op_sel_hi:[0,1] neg_lo:[0,1] neg_hi:[0,1]
	v_mov_b32_e32 v29, v5
	v_pk_add_f32 v[4:5], v[6:7], v[6:7] op_sel:[0,1] op_sel_hi:[0,1] neg_lo:[0,1] neg_hi:[0,1]
	v_pk_add_f32 v[6:7], v[12:13], v[4:5]
	v_pk_add_f32 v[4:5], v[12:13], v[4:5] op_sel_hi:[0,1] neg_lo:[0,1] neg_hi:[0,1]
	v_mov_b32_e32 v7, v5
	v_pk_mul_f32 v[4:5], v[6:7], v[194:195]
	v_pk_mul_f32 v[6:7], v[6:7], v[192:193]
	v_pk_fma_f32 v[4:5], v[28:29], v[192:193], v[4:5]
	v_pk_fma_f32 v[6:7], v[28:29], v[194:195], v[6:7] neg_lo:[0,0,1] neg_hi:[0,0,1]
	s_mov_b32 s66, s19
	v_pk_add_f32 v[12:13], v[6:7], v[4:5] op_sel:[0,1] op_sel_hi:[1,0] neg_lo:[0,1] neg_hi:[0,1]
	v_pk_add_f32 v[28:29], v[6:7], v[4:5] op_sel:[0,1] op_sel_hi:[1,0]
	v_pk_add_f32 v[4:5], v[4:5], v[6:7] op_sel:[1,0] op_sel_hi:[0,1] neg_lo:[0,1] neg_hi:[0,1]
	v_mov_b32_e32 v13, v29
	v_pk_mul_f32 v[12:13], v[12:13], 0.5 op_sel_hi:[1,0]
	v_mov_b32_e32 v29, v5
	v_mul_f32_e32 v24, v190, v12
	v_pk_fma_f32 v[30:31], v[190:191], v[12:13], v[24:25] op_sel_hi:[1,1,0] neg_lo:[1,0,0] neg_hi:[1,0,0]
	v_mul_f32_e32 v24, v160, v13
	v_pk_fma_f32 v[12:13], v[16:17], v[12:13], v[24:25] op_sel_hi:[1,1,0]
	v_mov_b32_e32 v16, v83
	v_mov_b32_e32 v30, v12
	v_pk_fma_f32 v[4:5], v[28:29], 0.5, v[12:13] op_sel_hi:[1,0,1] neg_lo:[0,0,1] neg_hi:[0,0,1]
	v_pk_fma_f32 v[122:123], v[28:29], 0.5, v[30:31] op_sel_hi:[1,0,1]
	v_pk_fma_f32 v[6:7], v[28:29], 0.5, v[30:31] op_sel_hi:[1,0,1] neg_lo:[1,0,0] neg_hi:[1,0,0]
	v_mov_b32_e32 v5, v123
	v_pk_mul_f32 v[24:25], v[4:5], s[46:47] op_sel_hi:[1,0]
	v_pk_add_f32 v[4:5], v[138:139], v[188:189]
	v_pk_add_f32 v[12:13], v[138:139], v[188:189] neg_lo:[0,1] neg_hi:[0,1]
	v_mov_b32_e32 v17, v82
	v_mul_f32_e32 v6, 0.5, v13
	v_pk_add_f32 v[28:29], v[186:187], v[16:17] neg_lo:[0,1] neg_hi:[0,1]
	v_pk_add_f32 v[30:31], v[186:187], v[16:17]
	v_mov_b32_e32 v13, v5
	v_pk_mov_b32 v[32:33], v[28:29], v[30:31] op_sel:[1,0]
	v_pk_mul_f32 v[12:13], v[12:13], s[44:45]
	v_mul_f32_e32 v4, 0.5, v4
	v_pk_mul_f32 v[48:49], v[32:33], v[12:13] op_sel:[0,1] op_sel_hi:[1,0]
	v_pk_mul_f32 v[12:13], v[32:33], v[12:13]
	v_pk_add_f32 v[48:49], v[48:49], v[48:49] op_sel:[0,1] op_sel_hi:[0,1]
	v_pk_add_f32 v[50:51], v[4:5], v[48:49]
	v_pk_add_f32 v[4:5], v[4:5], v[48:49] op_sel_hi:[0,1] neg_lo:[0,1] neg_hi:[0,1]
	v_mov_b32_e32 v51, v5
	v_pk_add_f32 v[4:5], v[12:13], v[12:13] op_sel:[0,1] op_sel_hi:[0,1] neg_lo:[0,1] neg_hi:[0,1]
	v_pk_add_f32 v[12:13], v[6:7], v[4:5]
	v_pk_add_f32 v[4:5], v[6:7], v[4:5] op_sel_hi:[0,1] neg_lo:[0,1] neg_hi:[0,1]
	v_mov_b32_e32 v13, v5
	v_pk_mul_f32 v[4:5], v[12:13], v[184:185]
	v_pk_mul_f32 v[12:13], v[12:13], v[170:171]
	v_pk_fma_f32 v[4:5], v[50:51], v[170:171], v[4:5]
	v_pk_fma_f32 v[12:13], v[50:51], v[184:185], v[12:13] neg_lo:[0,0,1] neg_hi:[0,0,1]
	v_mov_b32_e32 v31, v29
	v_pk_add_f32 v[48:49], v[12:13], v[4:5] op_sel:[0,1] op_sel_hi:[1,0] neg_lo:[0,1] neg_hi:[0,1]
	v_pk_add_f32 v[50:51], v[12:13], v[4:5] op_sel:[0,1] op_sel_hi:[1,0]
	v_pk_add_f32 v[4:5], v[4:5], v[12:13] op_sel:[1,0] op_sel_hi:[0,1] neg_lo:[0,1] neg_hi:[0,1]
	v_mov_b32_e32 v49, v51
	v_pk_mul_f32 v[48:49], v[48:49], 0.5 op_sel_hi:[1,0]
	v_mov_b32_e32 v51, v5
	v_mul_f32_e32 v6, v29, v48
	v_pk_fma_f32 v[32:33], v[32:33], v[48:49], v[6:7] op_sel_hi:[1,1,0] neg_lo:[1,0,0] neg_hi:[1,0,0]
	v_mul_f32_e32 v6, v29, v49
	v_pk_fma_f32 v[28:29], v[30:31], v[48:49], v[6:7] op_sel_hi:[1,1,0]
	v_pk_mul_f32 v[12:13], v[16:17], s[36:37]
	v_mov_b32_e32 v32, v28
	v_pk_fma_f32 v[4:5], v[50:51], 0.5, v[28:29] op_sel_hi:[1,0,1] neg_lo:[0,0,1] neg_hi:[0,0,1]
	v_pk_fma_f32 v[138:139], v[50:51], 0.5, v[32:33] op_sel_hi:[1,0,1]
	v_pk_add_f32 v[16:17], v[92:93], v[182:183]
	v_mov_b32_e32 v5, v139
	v_pk_add_f32 v[28:29], v[92:93], v[182:183] neg_lo:[0,1] neg_hi:[0,1]
	v_pk_mul_f32 v[30:31], v[4:5], s[46:47] op_sel_hi:[1,0]
	v_pk_fma_f32 v[4:5], v[50:51], 0.5, v[32:33] op_sel_hi:[1,0,1] neg_lo:[1,0,0] neg_hi:[1,0,0]
	v_mul_f32_e32 v6, 0.5, v29
	v_pk_add_f32 v[32:33], v[18:19], v[12:13] op_sel:[0,1] op_sel_hi:[0,1] neg_lo:[0,1] neg_hi:[0,1]
	v_pk_add_f32 v[48:49], v[18:19], v[12:13] op_sel:[0,1] op_sel_hi:[0,1]
	v_mov_b32_e32 v29, v17
	v_mul_f32_e32 v4, 0.5, v16
	v_mov_b32_e32 v50, v32
	v_mov_b32_e32 v51, v49
	v_pk_mul_f32 v[16:17], v[28:29], s[44:45]
	v_pk_mov_b32 v[48:49], v[48:49], v[32:33] op_sel:[1,0]
	v_pk_mul_f32 v[28:29], v[50:51], v[16:17] op_sel:[0,1] op_sel_hi:[1,0]
	v_pk_mul_f32 v[16:17], v[50:51], v[16:17]
	v_pk_add_f32 v[28:29], v[28:29], v[28:29] op_sel:[0,1] op_sel_hi:[0,1]
	v_pk_add_f32 v[52:53], v[4:5], v[28:29]
	v_pk_add_f32 v[28:29], v[4:5], v[28:29] op_sel_hi:[0,1] neg_lo:[0,1] neg_hi:[0,1]
	v_pk_add_f32 v[16:17], v[16:17], v[16:17] op_sel:[0,1] op_sel_hi:[0,1] neg_lo:[0,1] neg_hi:[0,1]
	v_mov_b32_e32 v53, v29
	v_pk_add_f32 v[28:29], v[6:7], v[16:17]
	v_pk_add_f32 v[16:17], v[6:7], v[16:17] op_sel_hi:[0,1] neg_lo:[0,1] neg_hi:[0,1]
	v_mov_b32_e32 v29, v17
	v_pk_mul_f32 v[16:17], v[28:29], v[180:181]
	v_pk_mul_f32 v[28:29], v[28:29], v[172:173]
	v_pk_fma_f32 v[16:17], v[52:53], v[172:173], v[16:17]
	v_pk_fma_f32 v[28:29], v[52:53], v[180:181], v[28:29] neg_lo:[0,0,1] neg_hi:[0,0,1]
	v_sub_f32_e32 v6, v89, v177
	v_pk_add_f32 v[52:53], v[28:29], v[16:17] op_sel:[0,1] op_sel_hi:[1,0] neg_lo:[0,1] neg_hi:[0,1]
	v_pk_add_f32 v[54:55], v[28:29], v[16:17] op_sel:[0,1] op_sel_hi:[1,0]
	v_pk_add_f32 v[16:17], v[16:17], v[28:29] op_sel:[1,0] op_sel_hi:[0,1] neg_lo:[0,1] neg_hi:[0,1]
	v_mov_b32_e32 v53, v55
	v_pk_mul_f32 v[52:53], v[52:53], 0.5 op_sel_hi:[1,0]
	v_mov_b32_e32 v55, v17
	v_mul_f32_e32 v4, v32, v52
	v_pk_fma_f32 v[56:57], v[50:51], v[52:53], v[4:5] op_sel_hi:[1,1,0] neg_lo:[1,0,0] neg_hi:[1,0,0]
	v_mul_f32_e32 v4, v32, v53
	v_pk_fma_f32 v[48:49], v[48:49], v[52:53], v[4:5] op_sel_hi:[1,1,0]
	v_pk_add_f32 v[28:29], v[88:89], v[176:177]
	v_mov_b32_e32 v56, v48
	v_pk_fma_f32 v[16:17], v[54:55], 0.5, v[48:49] op_sel_hi:[1,0,1] neg_lo:[0,0,1] neg_hi:[0,0,1]
	v_mov_b32_e32 v48, v12
	v_mov_b32_e32 v49, v88
	v_pk_mov_b32 v[12:13], v[12:13], v[176:177] op_sel:[1,0]
	v_mul_f32_e32 v18, 0.5, v29
	v_pk_add_f32 v[12:13], v[48:49], v[12:13] neg_lo:[0,1] neg_hi:[0,1]
	v_mul_f32_e32 v4, 0.5, v28
	v_pk_mul_f32 v[48:49], v[12:13], v[18:19]
	v_mov_b32_e32 v13, v32
	v_pk_fma_f32 v[50:51], v[50:51], v[48:49], v[48:49] op_sel:[0,1,0] op_sel_hi:[1,0,1]
	v_mov_b32_e32 v48, v49
	v_mov_b32_e32 v49, v18
	v_pk_mul_f32 v[48:49], v[12:13], v[48:49]
	v_pk_add_f32 v[52:53], v[4:5], v[50:51]
	v_mul_f32_e32 v6, 0.5, v6
	v_fma_f32 v53, v28, 0.5, -v50
	v_pk_add_f32 v[28:29], v[48:49], v[48:49] op_sel:[0,1] op_sel_hi:[0,1] neg_lo:[0,1] neg_hi:[0,1]
	v_pk_add_f32 v[48:49], v[6:7], v[28:29]
	v_pk_add_f32 v[28:29], v[6:7], v[28:29] op_sel_hi:[0,1] neg_lo:[0,1] neg_hi:[0,1]
	v_mov_b32_e32 v49, v29
	v_pk_mul_f32 v[28:29], v[48:49], v[178:179]
	v_pk_mul_f32 v[48:49], v[48:49], v[174:175]
	v_pk_fma_f32 v[28:29], v[52:53], v[174:175], v[28:29]
	v_pk_fma_f32 v[48:49], v[52:53], v[178:179], v[48:49] neg_lo:[0,0,1] neg_hi:[0,0,1]
	v_pk_fma_f32 v[92:93], v[54:55], 0.5, v[56:57] op_sel_hi:[1,0,1]
	v_pk_add_f32 v[50:51], v[48:49], v[28:29] op_sel:[0,1] op_sel_hi:[1,0] neg_lo:[0,1] neg_hi:[0,1]
	v_pk_add_f32 v[52:53], v[48:49], v[28:29] op_sel:[0,1] op_sel_hi:[1,0]
	v_mov_b32_e32 v17, v93
	v_mov_b32_e32 v51, v53
	v_pk_mul_f32 v[50:51], v[50:51], 0.5 op_sel_hi:[1,0]
	v_pk_mul_f32 v[64:65], v[16:17], s[46:47] op_sel_hi:[1,0]
	v_mul_f32_e32 v4, v12, v50
	v_pk_fma_f32 v[16:17], v[54:55], 0.5, v[56:57] op_sel_hi:[1,0,1] neg_lo:[1,0,0] neg_hi:[1,0,0]
	v_pk_fma_f32 v[54:55], v[12:13], v[50:51], v[4:5] op_sel_hi:[1,1,0] neg_lo:[1,0,0] neg_hi:[1,0,0]
	v_mov_b32_e32 v33, v12
	v_mul_f32_e32 v4, v12, v51
	v_pk_fma_f32 v[12:13], v[32:33], v[50:51], v[4:5] op_sel_hi:[1,1,0]
	v_pk_add_f32 v[28:29], v[28:29], v[48:49] op_sel:[1,0] op_sel_hi:[0,1] neg_lo:[0,1] neg_hi:[0,1]
	v_mov_b32_e32 v53, v29
	v_mov_b32_e32 v54, v12
	v_pk_fma_f32 v[12:13], v[52:53], 0.5, v[12:13] op_sel_hi:[1,0,1] neg_lo:[0,0,1] neg_hi:[0,0,1]
	v_pk_fma_f32 v[88:89], v[52:53], 0.5, v[54:55] op_sel_hi:[1,0,1]
	s_mov_b32 s67, s16
	v_mov_b32_e32 v13, v89
	v_pk_mul_f32 v[68:69], v[12:13], s[46:47] op_sel_hi:[1,0]
	v_pk_fma_f32 v[12:13], v[52:53], 0.5, v[54:55] op_sel_hi:[1,0,1] neg_lo:[1,0,0] neg_hi:[1,0,0]
	v_mov_b32_e32 v4, v83
	s_mov_b32 s17, s19
	v_pk_mul_f32 v[48:49], v[82:83], s[66:67] op_sel_hi:[0,1]
	v_pk_add_f32 v[28:29], v[96:97], v[162:163]
	v_pk_add_f32 v[32:33], v[96:97], v[162:163] neg_lo:[0,1] neg_hi:[0,1]
	v_pk_fma_f32 v[52:53], v[4:5], s[16:17], v[48:49] op_sel_hi:[0,1,1] neg_lo:[0,0,1] neg_hi:[0,0,1]
	v_mul_f32_e32 v12, 0.5, v33
	v_pk_fma_f32 v[50:51], v[4:5], s[16:17], v[48:49] op_sel_hi:[0,1,1]
	v_mov_b32_e32 v33, v29
	v_mul_f32_e32 v6, 0.5, v28
	v_mov_b32_e32 v54, v52
	v_mov_b32_e32 v55, v51
	v_pk_mul_f32 v[28:29], v[32:33], s[44:45]
	v_pk_mov_b32 v[56:57], v[50:51], v[52:53] op_sel:[1,0]
	v_pk_mul_f32 v[32:33], v[54:55], v[28:29] op_sel:[0,1] op_sel_hi:[1,0]
	v_pk_mul_f32 v[28:29], v[54:55], v[28:29]
	v_pk_add_f32 v[32:33], v[32:33], v[32:33] op_sel:[0,1] op_sel_hi:[0,1]
	v_pk_add_f32 v[58:59], v[6:7], v[32:33]
	v_pk_add_f32 v[32:33], v[6:7], v[32:33] op_sel_hi:[0,1] neg_lo:[0,1] neg_hi:[0,1]
	v_pk_add_f32 v[28:29], v[28:29], v[28:29] op_sel:[0,1] op_sel_hi:[0,1] neg_lo:[0,1] neg_hi:[0,1]
	v_mov_b32_e32 v59, v33
	v_pk_add_f32 v[32:33], v[12:13], v[28:29]
	v_pk_add_f32 v[28:29], v[12:13], v[28:29] op_sel_hi:[0,1] neg_lo:[0,1] neg_hi:[0,1]
	v_mov_b32_e32 v33, v29
	v_pk_mul_f32 v[28:29], v[32:33], v[166:167]
	v_pk_mul_f32 v[32:33], v[32:33], v[164:165]
	v_pk_fma_f32 v[28:29], v[58:59], v[164:165], v[28:29]
	v_pk_fma_f32 v[32:33], v[58:59], v[166:167], v[32:33] neg_lo:[0,0,1] neg_hi:[0,0,1]
	v_mov_b32_e32 v159, v66
	v_pk_add_f32 v[58:59], v[32:33], v[28:29] op_sel:[0,1] op_sel_hi:[1,0] neg_lo:[0,1] neg_hi:[0,1]
	v_pk_add_f32 v[70:71], v[32:33], v[28:29] op_sel:[0,1] op_sel_hi:[1,0]
	v_pk_add_f32 v[28:29], v[28:29], v[32:33] op_sel:[1,0] op_sel_hi:[0,1] neg_lo:[0,1] neg_hi:[0,1]
	v_mov_b32_e32 v59, v71
	v_pk_mul_f32 v[58:59], v[58:59], 0.5 op_sel_hi:[1,0]
	v_mov_b32_e32 v71, v29
	v_mul_f32_e32 v6, v52, v58
	v_pk_fma_f32 v[72:73], v[54:55], v[58:59], v[6:7] op_sel_hi:[1,1,0] neg_lo:[1,0,0] neg_hi:[1,0,0]
	v_mul_f32_e32 v6, v52, v59
	v_pk_fma_f32 v[56:57], v[56:57], v[58:59], v[6:7] op_sel_hi:[1,1,0]
	v_sub_f32_e32 v12, v67, v153
	v_mov_b32_e32 v72, v56
	v_pk_fma_f32 v[28:29], v[70:71], 0.5, v[56:57] op_sel_hi:[1,0,1] neg_lo:[0,0,1] neg_hi:[0,0,1]
	v_pk_fma_f32 v[96:97], v[70:71], 0.5, v[72:73] op_sel_hi:[1,0,1]
	v_pk_mov_b32 v[56:57], v[48:49], v[152:153] op_sel:[1,0]
	v_mov_b32_e32 v29, v97
	v_pk_mul_f32 v[62:63], v[28:29], s[46:47] op_sel_hi:[1,0]
	v_pk_add_f32 v[28:29], v[66:67], v[152:153]
	v_pk_add_f32 v[56:57], v[158:159], v[56:57] neg_lo:[0,1] neg_hi:[0,1]
	v_mul_f32_e32 v18, 0.5, v29
	v_pk_mul_f32 v[58:59], v[56:57], v[18:19]
	v_mul_f32_e32 v6, 0.5, v28
	v_pk_fma_f32 v[54:55], v[54:55], v[58:59], v[58:59] op_sel:[0,1,0] op_sel_hi:[1,0,1]
	v_mov_b32_e32 v66, v56
	v_mov_b32_e32 v67, v52
	v_mov_b32_e32 v58, v59
	v_mov_b32_e32 v59, v18
	v_pk_mul_f32 v[58:59], v[66:67], v[58:59]
	v_pk_add_f32 v[66:67], v[6:7], v[54:55]
	v_mul_f32_e32 v12, 0.5, v12
	v_fma_f32 v67, v28, 0.5, -v54
	v_pk_add_f32 v[28:29], v[58:59], v[58:59] op_sel:[0,1] op_sel_hi:[0,1] neg_lo:[0,1] neg_hi:[0,1]
	v_pk_add_f32 v[54:55], v[12:13], v[28:29]
	v_pk_add_f32 v[28:29], v[12:13], v[28:29] op_sel_hi:[0,1] neg_lo:[0,1] neg_hi:[0,1]
	v_mov_b32_e32 v55, v29
	v_pk_mul_f32 v[28:29], v[54:55], v[156:157]
	v_pk_mul_f32 v[54:55], v[54:55], v[154:155]
	v_pk_fma_f32 v[32:33], v[70:71], 0.5, v[72:73] op_sel_hi:[1,0,1] neg_lo:[1,0,0] neg_hi:[1,0,0]
	v_pk_fma_f32 v[58:59], v[66:67], v[154:155], v[28:29] neg_lo:[0,0,1] neg_hi:[0,0,1]
	v_pk_fma_f32 v[28:29], v[66:67], v[154:155], v[28:29]
	v_pk_fma_f32 v[70:71], v[66:67], v[156:157], v[54:55]
	v_pk_fma_f32 v[54:55], v[66:67], v[156:157], v[54:55] neg_lo:[0,0,1] neg_hi:[0,0,1]
	v_pk_add_f32 v[72:73], v[58:59], v[28:29] op_sel:[0,1] op_sel_hi:[1,0]
	v_pk_add_f32 v[66:67], v[70:71], v[54:55] op_sel_hi:[0,1] neg_lo:[0,1] neg_hi:[0,1]
	v_pk_add_f32 v[28:29], v[58:59], v[28:29] op_sel_hi:[0,1] neg_lo:[0,1] neg_hi:[0,1]
	v_pk_add_f32 v[54:55], v[70:71], v[54:55] op_sel:[0,1] op_sel_hi:[1,0]
	v_mov_b32_e32 v73, v67
	v_mov_b32_e32 v55, v29
	v_pk_mul_f32 v[28:29], v[54:55], 0.5 op_sel_hi:[1,0]
	v_mov_b32_e32 v133, v84
	v_pk_mul_f32 v[54:55], v[52:53], v[28:29] op_sel:[0,1] op_sel_hi:[0,0]
	v_pk_fma_f32 v[58:59], v[56:57], v[28:29], v[54:55] op_sel_hi:[0,1,1]
	v_pk_fma_f32 v[28:29], v[56:57], v[28:29], v[54:55] op_sel_hi:[0,1,1] neg_lo:[0,0,1] neg_hi:[0,0,1]
	v_mov_b32_e32 v28, v58
	v_pk_fma_f32 v[54:55], v[72:73], 0.5, v[58:59] op_sel_hi:[1,0,1] neg_lo:[0,0,1] neg_hi:[0,0,1]
	v_pk_fma_f32 v[66:67], v[72:73], 0.5, v[28:29] op_sel_hi:[1,0,1]
	v_pk_add_f32 v[56:57], v[60:61], v[134:135] neg_lo:[0,1] neg_hi:[0,1]
	v_mov_b32_e32 v55, v67
	v_pk_mul_f32 v[90:91], v[54:55], s[46:47] op_sel_hi:[1,0]
	v_pk_add_f32 v[54:55], v[134:135], v[60:61]
	v_mul_f32_e32 v12, 0.5, v57
	v_mov_b32_e32 v57, v55
	v_mul_f32_e32 v6, 0.5, v54
	v_pk_mov_b32 v[58:59], v[52:53], v[50:51] op_sel:[1,0]
	v_pk_mul_f32 v[54:55], v[56:57], s[44:45]
	v_pk_fma_f32 v[28:29], v[72:73], 0.5, v[28:29] op_sel_hi:[1,0,1] neg_lo:[1,0,0] neg_hi:[1,0,0]
	v_pk_mul_f32 v[56:57], v[58:59], v[54:55] op_sel:[0,1] op_sel_hi:[1,0]
	v_pk_mul_f32 v[54:55], v[58:59], v[54:55]
	v_pk_add_f32 v[56:57], v[56:57], v[56:57] op_sel:[0,1] op_sel_hi:[0,1]
	v_pk_add_f32 v[60:61], v[6:7], v[56:57]
	v_pk_add_f32 v[56:57], v[6:7], v[56:57] op_sel_hi:[0,1] neg_lo:[0,1] neg_hi:[0,1]
	v_pk_add_f32 v[54:55], v[54:55], v[54:55] op_sel:[0,1] op_sel_hi:[0,1] neg_lo:[0,1] neg_hi:[0,1]
	v_mov_b32_e32 v61, v57
	v_pk_add_f32 v[56:57], v[12:13], v[54:55]
	v_pk_add_f32 v[54:55], v[12:13], v[54:55] op_sel_hi:[0,1] neg_lo:[0,1] neg_hi:[0,1]
	v_mov_b32_e32 v57, v55
	v_pk_mul_f32 v[54:55], v[56:57], v[142:143]
	v_pk_mul_f32 v[56:57], v[56:57], v[140:141]
	v_pk_fma_f32 v[54:55], v[60:61], v[140:141], v[54:55]
	v_pk_fma_f32 v[56:57], v[60:61], v[142:143], v[56:57] neg_lo:[0,0,1] neg_hi:[0,0,1]
	v_mov_b32_e32 v51, v53
	v_pk_add_f32 v[60:61], v[56:57], v[54:55] op_sel:[0,1] op_sel_hi:[1,0] neg_lo:[0,1] neg_hi:[0,1]
	v_pk_add_f32 v[70:71], v[56:57], v[54:55] op_sel:[0,1] op_sel_hi:[1,0]
	v_pk_add_f32 v[54:55], v[54:55], v[56:57] op_sel:[1,0] op_sel_hi:[0,1] neg_lo:[0,1] neg_hi:[0,1]
	v_mov_b32_e32 v61, v71
	v_pk_mul_f32 v[60:61], v[60:61], 0.5 op_sel_hi:[1,0]
	v_mov_b32_e32 v71, v55
	v_mul_f32_e32 v6, v53, v60
	v_pk_fma_f32 v[72:73], v[58:59], v[60:61], v[6:7] op_sel_hi:[1,1,0] neg_lo:[1,0,0] neg_hi:[1,0,0]
	v_mul_f32_e32 v6, v53, v61
	v_pk_fma_f32 v[50:51], v[50:51], v[60:61], v[6:7] op_sel_hi:[1,1,0]
	v_pk_add_f32 v[54:55], v[118:119], v[84:85]
	v_mov_b32_e32 v72, v50
	v_mov_b32_e32 v49, v118
	v_pk_fma_f32 v[50:51], v[70:71], 0.5, v[50:51] op_sel_hi:[1,0,1] neg_lo:[0,0,1] neg_hi:[0,0,1]
	v_pk_fma_f32 v[60:61], v[70:71], 0.5, v[72:73] op_sel_hi:[1,0,1]
	v_mul_f32_e32 v18, 0.5, v55
	v_pk_add_f32 v[48:49], v[132:133], v[48:49] neg_lo:[0,1] neg_hi:[0,1]
	v_mov_b32_e32 v51, v61
	v_pk_mul_f32 v[56:57], v[48:49], v[18:19]
	v_pk_mul_f32 v[94:95], v[50:51], s[46:47] op_sel_hi:[1,0]
	v_pk_fma_f32 v[50:51], v[70:71], 0.5, v[72:73] op_sel_hi:[1,0,1] neg_lo:[1,0,0] neg_hi:[1,0,0]
	v_mul_f32_e32 v6, 0.5, v54
	v_pk_fma_f32 v[58:59], v[58:59], v[56:57], v[56:57] op_sel:[0,1,0] op_sel_hi:[1,0,1]
	v_mov_b32_e32 v70, v48
	v_mov_b32_e32 v71, v53
	v_mov_b32_e32 v56, v57
	v_mov_b32_e32 v57, v18
	v_sub_f32_e32 v12, v85, v119
	v_pk_mul_f32 v[56:57], v[70:71], v[56:57]
	v_pk_add_f32 v[70:71], v[6:7], v[58:59]
	v_mul_f32_e32 v12, 0.5, v12
	v_fma_f32 v71, v54, 0.5, -v58
	v_pk_add_f32 v[54:55], v[56:57], v[56:57] op_sel:[0,1] op_sel_hi:[0,1] neg_lo:[0,1] neg_hi:[0,1]
	v_pk_add_f32 v[56:57], v[12:13], v[54:55]
	v_pk_add_f32 v[54:55], v[12:13], v[54:55] op_sel_hi:[0,1] neg_lo:[0,1] neg_hi:[0,1]
	v_mov_b32_e32 v57, v55
	v_pk_mul_f32 v[54:55], v[56:57], v[126:127]
	v_pk_mul_f32 v[56:57], v[56:57], v[124:125]
	v_pk_fma_f32 v[58:59], v[70:71], v[124:125], v[54:55] neg_lo:[0,0,1] neg_hi:[0,0,1]
	v_pk_fma_f32 v[54:55], v[70:71], v[124:125], v[54:55]
	v_pk_fma_f32 v[72:73], v[70:71], v[126:127], v[56:57]
	v_pk_fma_f32 v[56:57], v[70:71], v[126:127], v[56:57] neg_lo:[0,0,1] neg_hi:[0,0,1]
	v_pk_add_f32 v[70:71], v[58:59], v[54:55] op_sel:[0,1] op_sel_hi:[1,0]
	v_pk_add_f32 v[74:75], v[72:73], v[56:57] op_sel_hi:[0,1] neg_lo:[0,1] neg_hi:[0,1]
	v_pk_add_f32 v[54:55], v[58:59], v[54:55] op_sel_hi:[0,1] neg_lo:[0,1] neg_hi:[0,1]
	v_pk_add_f32 v[56:57], v[72:73], v[56:57] op_sel:[0,1] op_sel_hi:[1,0]
	v_mov_b32_e32 v71, v75
	v_mov_b32_e32 v57, v55
	v_pk_mul_f32 v[54:55], v[56:57], 0.5 op_sel_hi:[1,0]
	s_mov_b32 s66, s11
	v_pk_mul_f32 v[52:53], v[52:53], v[54:55] op_sel:[1,1] op_sel_hi:[1,0]
	s_mov_b32 s67, s8
	v_pk_fma_f32 v[56:57], v[48:49], v[54:55], v[52:53] op_sel_hi:[0,1,1]
	v_pk_fma_f32 v[48:49], v[48:49], v[54:55], v[52:53] op_sel_hi:[0,1,1] neg_lo:[0,0,1] neg_hi:[0,0,1]
	v_mov_b32_e32 v48, v56
	v_pk_fma_f32 v[52:53], v[70:71], 0.5, v[56:57] op_sel_hi:[1,0,1] neg_lo:[0,0,1] neg_hi:[0,0,1]
	v_pk_fma_f32 v[84:85], v[70:71], 0.5, v[48:49] op_sel_hi:[1,0,1]
	s_mov_b32 s9, s11
	v_mov_b32_e32 v53, v85
	v_pk_mul_f32 v[80:81], v[52:53], s[46:47] op_sel_hi:[1,0]
	v_pk_mul_f32 v[118:119], v[82:83], s[66:67] op_sel_hi:[0,1]
	v_pk_add_f32 v[52:53], v[86:87], v[112:113]
	v_pk_add_f32 v[54:55], v[86:87], v[112:113] neg_lo:[0,1] neg_hi:[0,1]
	v_pk_fma_f32 v[58:59], v[4:5], s[8:9], v[118:119] op_sel_hi:[0,1,1] neg_lo:[0,0,1] neg_hi:[0,0,1]
	v_mul_f32_e32 v12, 0.5, v55
	v_pk_fma_f32 v[72:73], v[4:5], s[8:9], v[118:119] op_sel_hi:[0,1,1]
	v_mov_b32_e32 v55, v53
	v_mul_f32_e32 v6, 0.5, v52
	v_mov_b32_e32 v56, v58
	v_mov_b32_e32 v57, v73
	v_pk_mul_f32 v[52:53], v[54:55], s[44:45]
	v_pk_fma_f32 v[48:49], v[70:71], 0.5, v[48:49] op_sel_hi:[1,0,1] neg_lo:[1,0,0] neg_hi:[1,0,0]
	v_pk_mul_f32 v[54:55], v[56:57], v[52:53] op_sel:[0,1] op_sel_hi:[1,0]
	v_pk_mul_f32 v[52:53], v[56:57], v[52:53]
	v_pk_add_f32 v[54:55], v[54:55], v[54:55] op_sel:[0,1] op_sel_hi:[0,1]
	v_pk_add_f32 v[74:75], v[6:7], v[54:55]
	v_pk_add_f32 v[54:55], v[6:7], v[54:55] op_sel_hi:[0,1] neg_lo:[0,1] neg_hi:[0,1]
	v_pk_add_f32 v[52:53], v[52:53], v[52:53] op_sel:[0,1] op_sel_hi:[0,1] neg_lo:[0,1] neg_hi:[0,1]
	v_mov_b32_e32 v75, v55
	v_pk_add_f32 v[54:55], v[12:13], v[52:53]
	v_pk_add_f32 v[52:53], v[12:13], v[52:53] op_sel_hi:[0,1] neg_lo:[0,1] neg_hi:[0,1]
	v_mov_b32_e32 v55, v53
	v_pk_mul_f32 v[52:53], v[54:55], v[116:117]
	v_pk_mul_f32 v[54:55], v[54:55], v[114:115]
	v_pk_fma_f32 v[52:53], v[74:75], v[114:115], v[52:53]
	v_pk_fma_f32 v[54:55], v[74:75], v[116:117], v[54:55] neg_lo:[0,0,1] neg_hi:[0,0,1]
	v_pk_mov_b32 v[70:71], v[72:73], v[58:59] op_sel:[1,0]
	v_pk_add_f32 v[74:75], v[54:55], v[52:53] op_sel:[0,1] op_sel_hi:[1,0] neg_lo:[0,1] neg_hi:[0,1]
	v_pk_add_f32 v[76:77], v[54:55], v[52:53] op_sel:[0,1] op_sel_hi:[1,0]
	v_pk_add_f32 v[52:53], v[52:53], v[54:55] op_sel:[1,0] op_sel_hi:[0,1] neg_lo:[0,1] neg_hi:[0,1]
	v_mov_b32_e32 v75, v77
	v_pk_mul_f32 v[74:75], v[74:75], 0.5 op_sel_hi:[1,0]
	v_mov_b32_e32 v77, v53
	v_mul_f32_e32 v6, v58, v74
	v_pk_fma_f32 v[112:113], v[56:57], v[74:75], v[6:7] op_sel_hi:[1,1,0] neg_lo:[1,0,0] neg_hi:[1,0,0]
	v_mul_f32_e32 v6, v58, v75
	v_pk_fma_f32 v[70:71], v[70:71], v[74:75], v[6:7] op_sel_hi:[1,1,0]
	v_pk_add_f32 v[54:55], v[34:35], v[110:111]
	v_mov_b32_e32 v112, v70
	v_pk_fma_f32 v[52:53], v[76:77], 0.5, v[70:71] op_sel_hi:[1,0,1] neg_lo:[0,0,1] neg_hi:[0,0,1]
	v_pk_fma_f32 v[86:87], v[76:77], 0.5, v[112:113] op_sel_hi:[1,0,1]
	v_sub_f32_e32 v12, v35, v111
	v_mov_b32_e32 v53, v87
	v_pk_mul_f32 v[78:79], v[52:53], s[46:47] op_sel_hi:[1,0]
	v_mul_f32_e32 v52, 0xbe47c5c2, v83
	v_mov_b32_e32 v53, v34
	v_pk_mov_b32 v[34:35], v[118:119], v[110:111] op_sel:[1,0]
	v_mul_f32_e32 v18, 0.5, v55
	v_pk_add_f32 v[34:35], v[52:53], v[34:35] neg_lo:[0,1] neg_hi:[0,1]
	v_mov_b32_e32 v71, v58
	v_pk_mul_f32 v[52:53], v[34:35], v[18:19]
	v_mov_b32_e32 v70, v34
	v_pk_fma_f32 v[56:57], v[56:57], v[52:53], v[52:53] op_sel:[0,1,0] op_sel_hi:[1,0,1]
	v_mov_b32_e32 v52, v53
	v_mov_b32_e32 v53, v18
	v_mul_f32_e32 v6, 0.5, v54
	v_pk_mul_f32 v[52:53], v[70:71], v[52:53]
	v_cvt_f32_f16_e32 v70, v46
	v_cvt_f32_f16_e32 v71, v47
	v_cvt_f32_f16_sdwa v47, v47 dst_sel:DWORD dst_unused:UNUSED_PAD src0_sel:WORD_1
	v_cvt_f32_f16_sdwa v46, v46 dst_sel:DWORD dst_unused:UNUSED_PAD src0_sel:WORD_1
	v_pk_fma_f32 v[74:75], v[76:77], 0.5, v[112:113] op_sel_hi:[1,0,1] neg_lo:[1,0,0] neg_hi:[1,0,0]
	v_mul_f32_e32 v12, 0.5, v12
	v_pk_add_f32 v[76:77], v[6:7], v[56:57]
	v_pk_add_f32 v[52:53], v[52:53], v[52:53] op_sel:[0,1] op_sel_hi:[0,1] neg_lo:[0,1] neg_hi:[0,1]
	v_fma_f32 v77, v54, 0.5, -v56
	v_pk_add_f32 v[54:55], v[12:13], v[52:53]
	v_pk_add_f32 v[52:53], v[12:13], v[52:53] op_sel_hi:[0,1] neg_lo:[0,1] neg_hi:[0,1]
	v_mov_b32_e32 v55, v53
	v_pk_mul_f32 v[52:53], v[54:55], v[46:47]
	v_pk_mul_f32 v[54:55], v[54:55], v[70:71]
	v_pk_fma_f32 v[56:57], v[76:77], v[70:71], v[52:53] neg_lo:[0,0,1] neg_hi:[0,0,1]
	v_pk_fma_f32 v[52:53], v[76:77], v[70:71], v[52:53]
	v_pk_fma_f32 v[70:71], v[76:77], v[46:47], v[54:55]
	v_pk_fma_f32 v[46:47], v[76:77], v[46:47], v[54:55] neg_lo:[0,0,1] neg_hi:[0,0,1]
	v_pk_add_f32 v[54:55], v[56:57], v[52:53] op_sel:[0,1] op_sel_hi:[1,0]
	v_pk_add_f32 v[76:77], v[70:71], v[46:47] op_sel_hi:[0,1] neg_lo:[0,1] neg_hi:[0,1]
	v_pk_add_f32 v[52:53], v[56:57], v[52:53] op_sel_hi:[0,1] neg_lo:[0,1] neg_hi:[0,1]
	v_pk_add_f32 v[46:47], v[70:71], v[46:47] op_sel:[0,1] op_sel_hi:[1,0]
	v_mov_b32_e32 v55, v77
	v_mov_b32_e32 v47, v53
	v_pk_mul_f32 v[46:47], v[46:47], 0.5 op_sel_hi:[1,0]
	s_mov_b32 s25, s27
	v_pk_mul_f32 v[52:53], v[58:59], v[46:47] op_sel:[0,1] op_sel_hi:[0,0]
	v_pk_fma_f32 v[56:57], v[34:35], v[46:47], v[52:53] op_sel_hi:[0,1,1]
	v_pk_fma_f32 v[46:47], v[34:35], v[46:47], v[52:53] op_sel_hi:[0,1,1] neg_lo:[0,0,1] neg_hi:[0,0,1]
	v_mov_b32_e32 v46, v56
	v_pk_fma_f32 v[52:53], v[54:55], 0.5, v[56:57] op_sel_hi:[1,0,1] neg_lo:[0,0,1] neg_hi:[0,0,1]
	v_pk_fma_f32 v[34:35], v[54:55], 0.5, v[46:47] op_sel_hi:[1,0,1]
	s_mov_b32 s66, s27
	v_mov_b32_e32 v53, v35
	v_pk_mul_f32 v[136:137], v[52:53], s[46:47] op_sel_hi:[1,0]
	v_pk_fma_f32 v[52:53], v[54:55], 0.5, v[46:47] op_sel_hi:[1,0,1] neg_lo:[1,0,0] neg_hi:[1,0,0]
	s_mov_b32 s67, s24
	v_pk_mul_f32 v[46:47], v[82:83], s[24:25] op_sel_hi:[0,1]
	v_pk_add_f32 v[54:55], v[108:109], v[40:41]
	v_pk_add_f32 v[40:41], v[40:41], v[108:109] neg_lo:[0,1] neg_hi:[0,1]
	v_pk_fma_f32 v[108:109], v[4:5], s[66:67], v[46:47] op_sel_hi:[0,1,1] neg_lo:[0,0,1] neg_hi:[0,0,1]
	v_mul_f32_e32 v12, 0.5, v41
	v_pk_fma_f32 v[70:71], v[4:5], s[66:67], v[46:47] op_sel_hi:[0,1,1]
	v_mov_b32_e32 v41, v55
	v_mov_b32_e32 v56, v108
	v_mov_b32_e32 v57, v71
	v_pk_mul_f32 v[40:41], v[40:41], s[44:45]
	v_mul_f32_e32 v6, 0.5, v54
	v_pk_mul_f32 v[54:55], v[56:57], v[40:41] op_sel:[0,1] op_sel_hi:[1,0]
	v_cvt_f32_f16_sdwa v76, v38 dst_sel:DWORD dst_unused:UNUSED_PAD src0_sel:WORD_1
	v_cvt_f32_f16_e32 v77, v39
	v_cvt_f32_f16_sdwa v39, v39 dst_sel:DWORD dst_unused:UNUSED_PAD src0_sel:WORD_1
	v_cvt_f32_f16_e32 v38, v38
	v_pk_mul_f32 v[40:41], v[56:57], v[40:41]
	v_pk_add_f32 v[54:55], v[54:55], v[54:55] op_sel:[0,1] op_sel_hi:[0,1]
	v_pk_add_f32 v[112:113], v[6:7], v[54:55]
	v_pk_add_f32 v[54:55], v[6:7], v[54:55] op_sel_hi:[0,1] neg_lo:[0,1] neg_hi:[0,1]
	v_pk_add_f32 v[40:41], v[40:41], v[40:41] op_sel:[0,1] op_sel_hi:[0,1] neg_lo:[0,1] neg_hi:[0,1]
	v_mov_b32_e32 v113, v55
	v_pk_add_f32 v[54:55], v[12:13], v[40:41]
	v_pk_add_f32 v[40:41], v[12:13], v[40:41] op_sel_hi:[0,1] neg_lo:[0,1] neg_hi:[0,1]
	v_mov_b32_e32 v55, v41
	v_pk_mul_f32 v[40:41], v[54:55], v[38:39]
	v_pk_mul_f32 v[54:55], v[54:55], v[76:77]
	v_pk_fma_f32 v[40:41], v[112:113], v[76:77], v[40:41]
	v_pk_fma_f32 v[38:39], v[112:113], v[38:39], v[54:55] neg_lo:[0,0,1] neg_hi:[0,0,1]
	v_pk_mov_b32 v[110:111], v[70:71], v[108:109] op_sel:[1,0]
	v_pk_add_f32 v[54:55], v[38:39], v[40:41] op_sel:[0,1] op_sel_hi:[1,0] neg_lo:[0,1] neg_hi:[0,1]
	v_pk_add_f32 v[76:77], v[38:39], v[40:41] op_sel:[0,1] op_sel_hi:[1,0]
	v_pk_add_f32 v[38:39], v[40:41], v[38:39] op_sel:[1,0] op_sel_hi:[0,1] neg_lo:[0,1] neg_hi:[0,1]
	v_mov_b32_e32 v55, v77
	v_pk_mul_f32 v[54:55], v[54:55], 0.5 op_sel_hi:[1,0]
	v_mov_b32_e32 v77, v39
	v_mul_f32_e32 v4, v108, v54
	v_pk_fma_f32 v[112:113], v[56:57], v[54:55], v[4:5] op_sel_hi:[1,1,0] neg_lo:[1,0,0] neg_hi:[1,0,0]
	v_mul_f32_e32 v4, v108, v55
	v_pk_fma_f32 v[54:55], v[110:111], v[54:55], v[4:5] op_sel_hi:[1,1,0]
	v_sub_f32_e32 v6, v45, v105
	v_mov_b32_e32 v112, v54
	v_pk_fma_f32 v[40:41], v[76:77], 0.5, v[54:55] op_sel_hi:[1,0,1] neg_lo:[0,0,1] neg_hi:[0,0,1]
	v_pk_fma_f32 v[38:39], v[76:77], 0.5, v[112:113] op_sel_hi:[1,0,1]
	v_pk_add_f32 v[54:55], v[104:105], v[44:45]
	v_mov_b32_e32 v41, v39
	v_pk_mul_f32 v[130:131], v[40:41], s[46:47] op_sel_hi:[1,0]
	v_mul_f32_e32 v40, 0xbf54db31, v83
	v_mov_b32_e32 v41, v44
	v_pk_mov_b32 v[44:45], v[46:47], v[104:105] op_sel:[1,0]
	v_mul_f32_e32 v18, 0.5, v55
	v_pk_add_f32 v[40:41], v[40:41], v[44:45] neg_lo:[0,1] neg_hi:[0,1]
	v_mov_b32_e32 v105, v108
	v_pk_mul_f32 v[44:45], v[40:41], v[18:19]
	v_mov_b32_e32 v104, v40
	v_pk_fma_f32 v[56:57], v[56:57], v[44:45], v[44:45] op_sel:[0,1,0] op_sel_hi:[1,0,1]
	v_mov_b32_e32 v44, v45
	v_mov_b32_e32 v45, v18
	v_mul_f32_e32 v4, 0.5, v54
	v_pk_mul_f32 v[44:45], v[104:105], v[44:45]
	v_cvt_f32_f16_e32 v104, v26
	v_cvt_f32_f16_e32 v105, v27
	v_cvt_f32_f16_sdwa v27, v27 dst_sel:DWORD dst_unused:UNUSED_PAD src0_sel:WORD_1
	v_cvt_f32_f16_sdwa v26, v26 dst_sel:DWORD dst_unused:UNUSED_PAD src0_sel:WORD_1
	v_mul_f32_e32 v6, 0.5, v6
	v_pk_add_f32 v[110:111], v[4:5], v[56:57]
	v_pk_add_f32 v[44:45], v[44:45], v[44:45] op_sel:[0,1] op_sel_hi:[0,1] neg_lo:[0,1] neg_hi:[0,1]
	v_fma_f32 v111, v54, 0.5, -v56
	v_pk_add_f32 v[54:55], v[6:7], v[44:45]
	v_pk_add_f32 v[44:45], v[6:7], v[44:45] op_sel_hi:[0,1] neg_lo:[0,1] neg_hi:[0,1]
	v_mov_b32_e32 v55, v45
	v_pk_mul_f32 v[44:45], v[54:55], v[26:27]
	v_pk_mul_f32 v[54:55], v[54:55], v[104:105]
	v_pk_fma_f32 v[56:57], v[110:111], v[104:105], v[44:45] neg_lo:[0,0,1] neg_hi:[0,0,1]
	v_pk_fma_f32 v[44:45], v[110:111], v[104:105], v[44:45]
	v_pk_fma_f32 v[104:105], v[110:111], v[26:27], v[54:55]
	v_pk_fma_f32 v[26:27], v[110:111], v[26:27], v[54:55] neg_lo:[0,0,1] neg_hi:[0,0,1]
	v_pk_add_f32 v[54:55], v[56:57], v[44:45] op_sel:[0,1] op_sel_hi:[1,0]
	v_pk_add_f32 v[110:111], v[104:105], v[26:27] op_sel_hi:[0,1] neg_lo:[0,1] neg_hi:[0,1]
	v_pk_add_f32 v[44:45], v[56:57], v[44:45] op_sel_hi:[0,1] neg_lo:[0,1] neg_hi:[0,1]
	v_pk_add_f32 v[26:27], v[104:105], v[26:27] op_sel:[0,1] op_sel_hi:[1,0]
	v_mov_b32_e32 v55, v111
	v_mov_b32_e32 v27, v45
	v_pk_mul_f32 v[26:27], v[26:27], 0.5 op_sel_hi:[1,0]
	v_mov_b32_e32 v47, v102
	v_pk_mul_f32 v[44:45], v[108:109], v[26:27] op_sel:[0,1] op_sel_hi:[0,0]
	v_pk_fma_f32 v[56:57], v[40:41], v[26:27], v[44:45] op_sel_hi:[0,1,1]
	v_pk_fma_f32 v[40:41], v[40:41], v[26:27], v[44:45] op_sel_hi:[0,1,1] neg_lo:[0,0,1] neg_hi:[0,0,1]
	v_mov_b32_e32 v40, v56
	v_pk_fma_f32 v[44:45], v[54:55], 0.5, v[56:57] op_sel_hi:[1,0,1] neg_lo:[0,0,1] neg_hi:[0,0,1]
	v_pk_fma_f32 v[26:27], v[54:55], 0.5, v[40:41] op_sel_hi:[1,0,1]
	v_pk_fma_f32 v[56:57], v[54:55], 0.5, v[40:41] op_sel_hi:[1,0,1] neg_lo:[1,0,0] neg_hi:[1,0,0]
	v_pk_add_f32 v[40:41], v[106:107], v[42:43]
	v_pk_add_f32 v[42:43], v[42:43], v[106:107] neg_lo:[0,1] neg_hi:[0,1]
	v_mov_b32_e32 v45, v27
	v_mul_f32_e32 v6, 0.5, v43
	v_mov_b32_e32 v43, v41
	v_pk_mul_f32 v[120:121], v[44:45], s[46:47] op_sel_hi:[1,0]
	v_mul_f32_e32 v4, 0.5, v40
	v_pk_mov_b32 v[44:45], v[108:109], v[70:71] op_sel:[1,0]
	v_pk_mul_f32 v[40:41], v[42:43], s[44:45]
	v_cvt_f32_f16_sdwa v54, v20 dst_sel:DWORD dst_unused:UNUSED_PAD src0_sel:WORD_1
	v_pk_mul_f32 v[42:43], v[44:45], v[40:41] op_sel:[0,1] op_sel_hi:[1,0]
	v_cvt_f32_f16_e32 v55, v21
	v_cvt_f32_f16_sdwa v21, v21 dst_sel:DWORD dst_unused:UNUSED_PAD src0_sel:WORD_1
	v_cvt_f32_f16_e32 v20, v20
	v_pk_mul_f32 v[40:41], v[44:45], v[40:41]
	v_pk_add_f32 v[42:43], v[42:43], v[42:43] op_sel:[0,1] op_sel_hi:[0,1]
	v_pk_add_f32 v[104:105], v[4:5], v[42:43]
	v_pk_add_f32 v[42:43], v[4:5], v[42:43] op_sel_hi:[0,1] neg_lo:[0,1] neg_hi:[0,1]
	v_pk_add_f32 v[40:41], v[40:41], v[40:41] op_sel:[0,1] op_sel_hi:[0,1] neg_lo:[0,1] neg_hi:[0,1]
	v_mov_b32_e32 v105, v43
	v_pk_add_f32 v[42:43], v[6:7], v[40:41]
	v_pk_add_f32 v[40:41], v[6:7], v[40:41] op_sel_hi:[0,1] neg_lo:[0,1] neg_hi:[0,1]
	v_mov_b32_e32 v43, v41
	v_pk_mul_f32 v[40:41], v[42:43], v[20:21]
	v_pk_mul_f32 v[42:43], v[42:43], v[54:55]
	v_pk_fma_f32 v[40:41], v[104:105], v[54:55], v[40:41]
	v_pk_fma_f32 v[20:21], v[104:105], v[20:21], v[42:43] neg_lo:[0,0,1] neg_hi:[0,0,1]
	v_mov_b32_e32 v71, v109
	v_pk_add_f32 v[42:43], v[20:21], v[40:41] op_sel:[0,1] op_sel_hi:[1,0] neg_lo:[0,1] neg_hi:[0,1]
	v_pk_add_f32 v[54:55], v[20:21], v[40:41] op_sel:[0,1] op_sel_hi:[1,0]
	v_pk_add_f32 v[20:21], v[40:41], v[20:21] op_sel:[1,0] op_sel_hi:[0,1] neg_lo:[0,1] neg_hi:[0,1]
	v_mov_b32_e32 v43, v55
	v_pk_mul_f32 v[42:43], v[42:43], 0.5 op_sel_hi:[1,0]
	v_mov_b32_e32 v55, v21
	v_mul_f32_e32 v4, v109, v42
	v_pk_fma_f32 v[104:105], v[44:45], v[42:43], v[4:5] op_sel_hi:[1,1,0] neg_lo:[1,0,0] neg_hi:[1,0,0]
	v_mul_f32_e32 v4, v109, v43
	v_pk_fma_f32 v[42:43], v[70:71], v[42:43], v[4:5] op_sel_hi:[1,1,0]
	v_sub_f32_e32 v6, v23, v103
	v_mov_b32_e32 v104, v42
	v_pk_fma_f32 v[40:41], v[54:55], 0.5, v[42:43] op_sel_hi:[1,0,1] neg_lo:[0,0,1] neg_hi:[0,0,1]
	v_pk_fma_f32 v[20:21], v[54:55], 0.5, v[104:105] op_sel_hi:[1,0,1]
	v_pk_add_f32 v[42:43], v[102:103], v[22:23]
	v_mov_b32_e32 v41, v21
	v_pk_mul_f32 v[128:129], v[40:41], s[46:47] op_sel_hi:[1,0]
	v_mul_f32_e32 v40, 0xbf0e39da, v83
	v_mov_b32_e32 v41, v22
	v_mul_f32_e32 v18, 0.5, v43
	v_pk_add_f32 v[22:23], v[40:41], v[46:47] neg_lo:[0,1] neg_hi:[0,1]
	v_mov_b32_e32 v47, v109
	v_pk_mul_f32 v[40:41], v[22:23], v[18:19]
	v_mov_b32_e32 v46, v22
	v_pk_fma_f32 v[44:45], v[44:45], v[40:41], v[40:41] op_sel:[0,1,0] op_sel_hi:[1,0,1]
	v_mov_b32_e32 v40, v41
	v_mov_b32_e32 v41, v18
	v_mul_f32_e32 v4, 0.5, v42
	v_pk_mul_f32 v[40:41], v[46:47], v[40:41]
	v_cvt_f32_f16_e32 v46, v10
	v_cvt_f32_f16_e32 v47, v11
	v_cvt_f32_f16_sdwa v11, v11 dst_sel:DWORD dst_unused:UNUSED_PAD src0_sel:WORD_1
	v_cvt_f32_f16_sdwa v10, v10 dst_sel:DWORD dst_unused:UNUSED_PAD src0_sel:WORD_1
	v_pk_fma_f32 v[70:71], v[54:55], 0.5, v[104:105] op_sel_hi:[1,0,1] neg_lo:[1,0,0] neg_hi:[1,0,0]
	v_mul_f32_e32 v6, 0.5, v6
	v_pk_add_f32 v[54:55], v[4:5], v[44:45]
	v_pk_add_f32 v[40:41], v[40:41], v[40:41] op_sel:[0,1] op_sel_hi:[0,1] neg_lo:[0,1] neg_hi:[0,1]
	v_fma_f32 v55, v42, 0.5, -v44
	v_pk_add_f32 v[42:43], v[6:7], v[40:41]
	v_pk_add_f32 v[40:41], v[6:7], v[40:41] op_sel_hi:[0,1] neg_lo:[0,1] neg_hi:[0,1]
	v_mov_b32_e32 v43, v41
	v_pk_mul_f32 v[40:41], v[42:43], v[10:11]
	v_pk_mul_f32 v[42:43], v[42:43], v[46:47]
	v_pk_fma_f32 v[44:45], v[54:55], v[46:47], v[40:41] neg_lo:[0,0,1] neg_hi:[0,0,1]
	v_pk_fma_f32 v[40:41], v[54:55], v[46:47], v[40:41]
	v_pk_fma_f32 v[46:47], v[54:55], v[10:11], v[42:43]
	v_pk_fma_f32 v[10:11], v[54:55], v[10:11], v[42:43] neg_lo:[0,0,1] neg_hi:[0,0,1]
	v_pk_add_f32 v[42:43], v[44:45], v[40:41] op_sel:[0,1] op_sel_hi:[1,0]
	v_pk_add_f32 v[54:55], v[46:47], v[10:11] op_sel_hi:[0,1] neg_lo:[0,1] neg_hi:[0,1]
	v_pk_add_f32 v[40:41], v[44:45], v[40:41] op_sel_hi:[0,1] neg_lo:[0,1] neg_hi:[0,1]
	v_pk_add_f32 v[10:11], v[46:47], v[10:11] op_sel:[0,1] op_sel_hi:[1,0]
	v_mov_b32_e32 v43, v55
	v_mov_b32_e32 v11, v41
	v_pk_mul_f32 v[10:11], v[10:11], 0.5 op_sel_hi:[1,0]
	v_mov_b32_e32 v119, v98
	v_pk_mul_f32 v[40:41], v[108:109], v[10:11] op_sel:[1,1] op_sel_hi:[1,0]
	v_pk_fma_f32 v[76:77], v[76:77], 0.5, v[112:113] op_sel_hi:[1,0,1] neg_lo:[1,0,0] neg_hi:[1,0,0]
	v_pk_fma_f32 v[44:45], v[22:23], v[10:11], v[40:41] op_sel_hi:[0,1,1]
	v_pk_fma_f32 v[10:11], v[22:23], v[10:11], v[40:41] op_sel_hi:[0,1,1] neg_lo:[0,0,1] neg_hi:[0,0,1]
	v_mov_b32_e32 v10, v44
	v_pk_fma_f32 v[22:23], v[42:43], 0.5, v[44:45] op_sel_hi:[1,0,1] neg_lo:[0,0,1] neg_hi:[0,0,1]
	v_pk_fma_f32 v[40:41], v[42:43], 0.5, v[10:11] op_sel_hi:[1,0,1]
	v_pk_fma_f32 v[54:55], v[42:43], 0.5, v[10:11] op_sel_hi:[1,0,1] neg_lo:[1,0,0] neg_hi:[1,0,0]
	v_pk_add_f32 v[10:11], v[100:101], v[14:15]
	v_pk_add_f32 v[14:15], v[14:15], v[100:101] neg_lo:[0,1] neg_hi:[0,1]
	v_mov_b32_e32 v23, v41
	v_mul_f32_e32 v6, 0.5, v15
	v_mov_b32_e32 v15, v11
	v_pk_mul_f32 v[150:151], v[22:23], s[46:47] op_sel_hi:[1,0]
	v_mul_f32_e32 v4, 0.5, v10
	v_pk_mov_b32 v[22:23], v[58:59], v[72:73] op_sel:[1,0]
	v_pk_mul_f32 v[10:11], v[14:15], s[44:45]
	v_cvt_f32_f16_sdwa v42, v8 dst_sel:DWORD dst_unused:UNUSED_PAD src0_sel:WORD_1
	v_pk_mul_f32 v[14:15], v[22:23], v[10:11] op_sel:[0,1] op_sel_hi:[1,0]
	v_cvt_f32_f16_e32 v43, v9
	v_cvt_f32_f16_sdwa v9, v9 dst_sel:DWORD dst_unused:UNUSED_PAD src0_sel:WORD_1
	v_cvt_f32_f16_e32 v8, v8
	v_pk_mul_f32 v[10:11], v[22:23], v[10:11]
	v_pk_add_f32 v[14:15], v[14:15], v[14:15] op_sel:[0,1] op_sel_hi:[0,1]
	v_pk_add_f32 v[44:45], v[4:5], v[14:15]
	v_pk_add_f32 v[14:15], v[4:5], v[14:15] op_sel_hi:[0,1] neg_lo:[0,1] neg_hi:[0,1]
	v_pk_add_f32 v[10:11], v[10:11], v[10:11] op_sel:[0,1] op_sel_hi:[0,1] neg_lo:[0,1] neg_hi:[0,1]
	v_mov_b32_e32 v45, v15
	v_pk_add_f32 v[14:15], v[6:7], v[10:11]
	v_pk_add_f32 v[10:11], v[6:7], v[10:11] op_sel_hi:[0,1] neg_lo:[0,1] neg_hi:[0,1]
	v_mov_b32_e32 v15, v11
	v_pk_mul_f32 v[10:11], v[14:15], v[8:9]
	v_pk_mul_f32 v[14:15], v[14:15], v[42:43]
	v_pk_fma_f32 v[10:11], v[44:45], v[42:43], v[10:11]
	v_pk_fma_f32 v[8:9], v[44:45], v[8:9], v[14:15] neg_lo:[0,0,1] neg_hi:[0,0,1]
	v_mov_b32_e32 v73, v59
	v_pk_add_f32 v[14:15], v[8:9], v[10:11] op_sel:[0,1] op_sel_hi:[1,0] neg_lo:[0,1] neg_hi:[0,1]
	v_pk_add_f32 v[42:43], v[8:9], v[10:11] op_sel:[0,1] op_sel_hi:[1,0]
	v_pk_add_f32 v[8:9], v[10:11], v[8:9] op_sel:[1,0] op_sel_hi:[0,1] neg_lo:[0,1] neg_hi:[0,1]
	v_mov_b32_e32 v15, v43
	v_pk_mul_f32 v[14:15], v[14:15], 0.5 op_sel_hi:[1,0]
	v_mov_b32_e32 v43, v9
	v_mul_f32_e32 v4, v59, v14
	v_pk_fma_f32 v[44:45], v[22:23], v[14:15], v[4:5] op_sel_hi:[1,1,0] neg_lo:[1,0,0] neg_hi:[1,0,0]
	v_mul_f32_e32 v4, v59, v15
	v_pk_fma_f32 v[14:15], v[72:73], v[14:15], v[4:5] op_sel_hi:[1,1,0]
	v_sub_f32_e32 v6, v37, v99
	v_mov_b32_e32 v44, v14
	v_pk_fma_f32 v[8:9], v[42:43], 0.5, v[14:15] op_sel_hi:[1,0,1] neg_lo:[0,0,1] neg_hi:[0,0,1]
	v_pk_fma_f32 v[10:11], v[42:43], 0.5, v[44:45] op_sel_hi:[1,0,1]
	v_pk_add_f32 v[14:15], v[98:99], v[36:37]
	v_mov_b32_e32 v9, v11
	v_pk_mul_f32 v[168:169], v[8:9], s[46:47] op_sel_hi:[1,0]
	v_mul_f32_e32 v8, 0xbf7b14be, v83
	v_mov_b32_e32 v9, v36
	v_mul_f32_e32 v18, 0.5, v15
	v_pk_add_f32 v[8:9], v[8:9], v[118:119] neg_lo:[0,1] neg_hi:[0,1]
	v_pk_fma_f32 v[72:73], v[42:43], 0.5, v[44:45] op_sel_hi:[1,0,1] neg_lo:[1,0,0] neg_hi:[1,0,0]
	v_pk_mul_f32 v[36:37], v[8:9], v[18:19]
	v_mov_b32_e32 v42, v8
	v_pk_fma_f32 v[22:23], v[22:23], v[36:37], v[36:37] op_sel:[0,1,0] op_sel_hi:[1,0,1]
	v_mov_b32_e32 v43, v59
	v_mov_b32_e32 v36, v37
	v_mov_b32_e32 v37, v18
	v_mul_f32_e32 v4, 0.5, v14
	v_pk_mul_f32 v[36:37], v[42:43], v[36:37]
	v_cvt_f32_f16_e32 v44, v2
	v_cvt_f32_f16_e32 v45, v3
	v_cvt_f32_f16_sdwa v3, v3 dst_sel:DWORD dst_unused:UNUSED_PAD src0_sel:WORD_1
	v_cvt_f32_f16_sdwa v2, v2 dst_sel:DWORD dst_unused:UNUSED_PAD src0_sel:WORD_1
	v_mul_f32_e32 v6, 0.5, v6
	v_pk_add_f32 v[46:47], v[4:5], v[22:23]
	v_fma_f32 v4, v14, 0.5, -v22
	v_pk_add_f32 v[22:23], v[36:37], v[36:37] op_sel:[0,1] op_sel_hi:[0,1] neg_lo:[0,1] neg_hi:[0,1]
	v_pk_add_f32 v[36:37], v[6:7], v[22:23]
	v_pk_add_f32 v[22:23], v[6:7], v[22:23] op_sel_hi:[0,1] neg_lo:[0,1] neg_hi:[0,1]
	v_mov_b32_e32 v37, v23
	v_mov_b32_e32 v14, v46
	v_mov_b32_e32 v15, v4
	v_pk_mul_f32 v[22:23], v[4:5], v[44:45] op_sel_hi:[0,1]
	v_pk_mul_f32 v[82:83], v[36:37], v[2:3]
	v_pk_mul_f32 v[46:47], v[46:47], v[2:3]
	v_pk_mul_f32 v[36:37], v[36:37], v[44:45]
	v_pk_fma_f32 v[98:99], v[14:15], v[44:45], v[82:83] neg_lo:[0,0,1] neg_hi:[0,0,1]
	v_pk_fma_f32 v[2:3], v[14:15], v[2:3], v[36:37] neg_lo:[0,0,1] neg_hi:[0,0,1]
	v_add_f32_e32 v4, v23, v83
	v_add_f32_e32 v6, v46, v36
	v_pk_add_f32 v[22:23], v[6:7], v[2:3] op_sel_hi:[0,1] neg_lo:[0,1] neg_hi:[0,1]
	v_pk_add_f32 v[36:37], v[98:99], v[4:5] op_sel_hi:[1,0] neg_lo:[0,1] neg_hi:[0,1]
	v_pk_add_f32 v[2:3], v[6:7], v[2:3] op_sel_hi:[0,1]
	v_mov_b32_e32 v37, v3
	v_pk_mul_f32 v[2:3], v[36:37], 0.5 op_sel_hi:[1,0]
	v_pk_add_f32 v[14:15], v[98:99], v[4:5] op_sel_hi:[1,0]
	v_mul_f32_e32 v4, v59, v3
	v_pk_fma_f32 v[36:37], v[42:43], v[2:3], v[4:5] op_sel_hi:[1,1,0] neg_lo:[0,0,1] neg_hi:[0,0,1]
	v_pk_mov_b32 v[42:43], v[58:59], v[8:9] op_sel:[1,0]
	v_mul_f32_e32 v4, v8, v3
	v_pk_fma_f32 v[2:3], v[42:43], v[2:3], v[4:5] op_sel_hi:[1,1,0]
	v_mov_b32_e32 v15, v23
	v_pk_fma_f32 v[8:9], v[14:15], 0.5, v[2:3] op_sel_hi:[1,0,1] neg_lo:[0,0,1] neg_hi:[0,0,1]
	v_pk_fma_f32 v[42:43], v[14:15], 0.5, v[36:37] op_sel_hi:[1,0,0]
	v_pk_fma_f32 v[2:3], v[14:15], 0.5, v[2:3] op_sel_hi:[1,0,1]
	v_mov_b32_e32 v9, v43
	v_pk_fma_f32 v[58:59], v[22:23], 0.5, v[36:37] op_sel_hi:[1,0,0] neg_lo:[1,0,0] neg_hi:[1,0,0]
	v_pk_mul_f32 v[144:145], v[8:9], s[46:47] op_sel_hi:[1,0]
	v_mov_b32_e32 v58, v2
	v_mov_b32_e32 v72, v10
	v_mov_b32_e32 v54, v40
	v_mov_b32_e32 v70, v20
	v_mov_b32_e32 v56, v26
	v_mov_b32_e32 v76, v38
	v_mov_b32_e32 v52, v34
	v_mov_b32_e32 v74, v86
	v_mov_b32_e32 v48, v84
	v_mov_b32_e32 v50, v60
	v_mov_b32_e32 v28, v66
	v_mov_b32_e32 v32, v96
	v_mov_b32_e32 v12, v88
	v_mov_b32_e32 v16, v92
	v_mov_b32_e32 v4, v138
	v_mov_b32_e32 v6, v122

.LBB0_546:
	s_or_b64 exec, exec, s[0:1]
	v_mov_b32_e32 v25, v210
	s_mov_b32 s62, s37
	v_and_b32_e32 v28, 0xff, v25
	v_lshlrev_b32_e32 v34, 5, v25
	v_cvt_f32_ubyte0_e32 v25, v25
	v_mul_f32_e32 v25, 0x39000000, v25
	v_sin_f32_e32 v43, v25
	v_cos_f32_e32 v42, v25
	v_and_or_b32 v28, v34, s33, v28
	v_ashrrev_i32_e32 v34, 5, v28
	s_nop 0
	s_nop 0
	v_pk_mul_f32 v[46:47], v[42:43], v[42:43] op_sel:[1,1] op_sel_hi:[0,1] neg_lo:[0,1]
	v_pk_fma_f32 v[46:47], v[42:43], v[42:43], v[46:47] op_sel_hi:[1,0,1]
	v_lshlrev_b32_e32 v28, 3, v28
	v_pk_mul_f32 v[52:53], v[46:47], v[46:47] op_sel:[1,1] op_sel_hi:[0,1] neg_lo:[0,1]
	v_pk_fma_f32 v[52:53], v[46:47], v[46:47], v[52:53] op_sel_hi:[1,0,1]
	v_lshlrev_b32_e32 v34, 3, v34
	v_pk_mul_f32 v[70:71], v[52:53], v[52:53] op_sel:[1,1] op_sel_hi:[0,1] neg_lo:[0,1]
	v_pk_fma_f32 v[70:71], v[52:53], v[52:53], v[70:71] op_sel_hi:[1,0,1]
	v_pk_mul_f32 v[48:49], v[42:43], v[46:47] op_sel:[1,1] op_sel_hi:[1,0] neg_lo:[1,0]
	v_pk_mul_f32 v[86:87], v[52:53], v[70:71] op_sel:[1,1] op_sel_hi:[1,0] neg_lo:[1,0]
	v_add3_u32 v25, 0, v28, v34
	v_pk_fma_f32 v[86:87], v[52:53], v[70:71], v[86:87] op_sel_hi:[0,1,1]
	v_pk_mul_f32 v[102:103], v[52:53], v[86:87] op_sel:[1,1] op_sel_hi:[1,0] neg_lo:[1,0]
	v_pk_fma_f32 v[48:49], v[42:43], v[46:47], v[48:49] op_sel_hi:[0,1,1]
	v_pk_fma_f32 v[102:103], v[52:53], v[86:87], v[102:103] op_sel_hi:[0,1,1]
	v_pk_mul_f32 v[118:119], v[52:53], v[102:103] op_sel:[1,1] op_sel_hi:[1,0] neg_lo:[1,0]
	v_pk_fma_f32 v[118:119], v[52:53], v[102:103], v[118:119] op_sel_hi:[0,1,1]
	v_pk_mul_f32 v[134:135], v[52:53], v[118:119] op_sel:[1,1] op_sel_hi:[1,0] neg_lo:[1,0]
	v_pk_fma_f32 v[134:135], v[52:53], v[118:119], v[134:135] op_sel_hi:[0,1,1]
	v_pk_mul_f32 v[152:153], v[52:53], v[134:135] op_sel:[1,1] op_sel_hi:[1,0] neg_lo:[1,0]
	v_pk_mul_f32 v[58:59], v[42:43], v[52:53] op_sel:[1,1] op_sel_hi:[1,0] neg_lo:[1,0]
	v_pk_fma_f32 v[152:153], v[52:53], v[134:135], v[152:153] op_sel_hi:[0,1,1]
	v_pk_mul_f32 v[74:75], v[42:43], v[70:71] op_sel:[1,1] op_sel_hi:[1,0] neg_lo:[1,0]
	v_pk_mul_f32 v[90:91], v[42:43], v[86:87] op_sel:[1,1] op_sel_hi:[1,0] neg_lo:[1,0]
	v_pk_mul_f32 v[106:107], v[42:43], v[102:103] op_sel:[1,1] op_sel_hi:[1,0] neg_lo:[1,0]
	v_pk_mul_f32 v[122:123], v[42:43], v[118:119] op_sel:[1,1] op_sel_hi:[1,0] neg_lo:[1,0]
	v_pk_mul_f32 v[138:139], v[42:43], v[134:135] op_sel:[1,1] op_sel_hi:[1,0] neg_lo:[1,0]
	v_pk_mul_f32 v[156:157], v[42:43], v[152:153] op_sel:[1,1] op_sel_hi:[1,0] neg_lo:[1,0]
	ds_read_b64 v[168:169], v25
	ds_read_b64 v[170:171], v25 offset:2112
	ds_read_b64 v[172:173], v25 offset:4224
	ds_read_b64 v[174:175], v25 offset:6336
	ds_read_b64 v[176:177], v25 offset:8448
	ds_read_b64 v[178:179], v25 offset:10560
	ds_read_b64 v[180:181], v25 offset:12672
	ds_read_b64 v[182:183], v25 offset:14784
	ds_read_b64 v[184:185], v25 offset:16896
	ds_read_b64 v[186:187], v25 offset:19008
	ds_read_b64 v[188:189], v25 offset:21120
	ds_read_b64 v[190:191], v25 offset:23232
	ds_read_b64 v[192:193], v25 offset:25344
	ds_read_b64 v[194:195], v25 offset:27456
	ds_read_b64 v[196:197], v25 offset:29568
	ds_read_b64 v[198:199], v25 offset:31680
	ds_read_b64 v[212:213], v25 offset:33792
	ds_read_b64 v[214:215], v25 offset:35904
	ds_read_b64 v[216:217], v25 offset:38016
	ds_read_b64 v[218:219], v25 offset:40128
	ds_read_b64 v[220:221], v25 offset:42240
	ds_read_b64 v[222:223], v25 offset:44352
	ds_read_b64 v[224:225], v25 offset:46464
	ds_read_b64 v[226:227], v25 offset:48576
	ds_read_b64 v[228:229], v25 offset:50688
	ds_read_b64 v[230:231], v25 offset:52800
	ds_read_b64 v[232:233], v25 offset:54912
	ds_read_b64 v[234:235], v25 offset:57024
	ds_read_b64 v[236:237], v25 offset:59136
	ds_read_b64 v[238:239], v25 offset:61248
	ds_read_b64 v[240:241], v25 offset:63360
	ds_read_b64 v[242:243], v25 offset:65472
	s_waitcnt lgkmcnt(14)
	v_pk_mul_f32 v[44:45], v[42:43], v[212:213] op_sel:[1,1] op_sel_hi:[1,0] neg_lo:[1,0]
	v_pk_fma_f32 v[58:59], v[42:43], v[52:53], v[58:59] op_sel_hi:[0,1,1]
	v_pk_mul_f32 v[62:63], v[46:47], v[52:53] op_sel:[1,1] op_sel_hi:[1,0] neg_lo:[1,0]
	v_pk_mul_f32 v[66:67], v[52:53], v[48:49] op_sel:[1,1] op_sel_hi:[0,1] neg_lo:[0,1]
	v_pk_fma_f32 v[74:75], v[42:43], v[70:71], v[74:75] op_sel_hi:[0,1,1]
	v_pk_mul_f32 v[78:79], v[46:47], v[70:71] op_sel:[1,1] op_sel_hi:[1,0] neg_lo:[1,0]
	v_pk_fma_f32 v[90:91], v[42:43], v[86:87], v[90:91] op_sel_hi:[0,1,1]
	v_pk_mul_f32 v[94:95], v[46:47], v[86:87] op_sel:[1,1] op_sel_hi:[1,0] neg_lo:[1,0]
	v_pk_fma_f32 v[106:107], v[42:43], v[102:103], v[106:107] op_sel_hi:[0,1,1]
	v_pk_mul_f32 v[110:111], v[46:47], v[102:103] op_sel:[1,1] op_sel_hi:[1,0] neg_lo:[1,0]
	v_pk_fma_f32 v[122:123], v[42:43], v[118:119], v[122:123] op_sel_hi:[0,1,1]
	v_pk_mul_f32 v[126:127], v[46:47], v[118:119] op_sel:[1,1] op_sel_hi:[1,0] neg_lo:[1,0]
	v_pk_fma_f32 v[138:139], v[42:43], v[134:135], v[138:139] op_sel_hi:[0,1,1]
	v_pk_mul_f32 v[142:143], v[46:47], v[134:135] op_sel:[1,1] op_sel_hi:[1,0] neg_lo:[1,0]
	v_pk_fma_f32 v[156:157], v[42:43], v[152:153], v[156:157] op_sel_hi:[0,1,1]
	v_pk_mul_f32 v[160:161], v[46:47], v[152:153] op_sel:[1,1] op_sel_hi:[1,0] neg_lo:[1,0]
	v_pk_fma_f32 v[42:43], v[42:43], v[212:213], v[44:45] op_sel_hi:[0,1,1]
	v_pk_mul_f32 v[44:45], v[184:185], v[46:47] op_sel:[1,1] op_sel_hi:[0,1] neg_lo:[0,1]
	v_pk_fma_f32 v[62:63], v[46:47], v[52:53], v[62:63] op_sel_hi:[0,1,1]
	v_pk_fma_f32 v[66:67], v[52:53], v[48:49], v[66:67] op_sel_hi:[1,0,1]
	v_pk_fma_f32 v[78:79], v[46:47], v[70:71], v[78:79] op_sel_hi:[0,1,1]
	v_pk_mul_f32 v[82:83], v[48:49], v[70:71] op_sel:[1,1] op_sel_hi:[1,0] neg_lo:[1,0]
	v_pk_fma_f32 v[94:95], v[46:47], v[86:87], v[94:95] op_sel_hi:[0,1,1]
	v_pk_mul_f32 v[98:99], v[48:49], v[86:87] op_sel:[1,1] op_sel_hi:[1,0] neg_lo:[1,0]
	v_pk_fma_f32 v[110:111], v[46:47], v[102:103], v[110:111] op_sel_hi:[0,1,1]
	v_pk_mul_f32 v[114:115], v[48:49], v[102:103] op_sel:[1,1] op_sel_hi:[1,0] neg_lo:[1,0]
	v_pk_fma_f32 v[126:127], v[46:47], v[118:119], v[126:127] op_sel_hi:[0,1,1]
	v_pk_mul_f32 v[130:131], v[48:49], v[118:119] op_sel:[1,1] op_sel_hi:[1,0] neg_lo:[1,0]
	v_pk_fma_f32 v[142:143], v[46:47], v[134:135], v[142:143] op_sel_hi:[0,1,1]
	v_pk_mul_f32 v[148:149], v[48:49], v[134:135] op_sel:[1,1] op_sel_hi:[1,0] neg_lo:[1,0]
	v_pk_fma_f32 v[160:161], v[46:47], v[152:153], v[160:161] op_sel_hi:[0,1,1]
	v_pk_mul_f32 v[164:165], v[48:49], v[152:153] op_sel:[1,1] op_sel_hi:[1,0] neg_lo:[1,0]
	v_pk_fma_f32 v[44:45], v[184:185], v[46:47], v[44:45] op_sel_hi:[1,0,1]
	s_waitcnt lgkmcnt(7)
	v_pk_mul_f32 v[46:47], v[48:49], v[228:229] op_sel:[1,1] op_sel_hi:[1,0] neg_lo:[1,0]
	v_xor_b32_e32 v60, 0x80000000, v59
	v_xor_b32_e32 v64, 0x80000000, v63
	v_xor_b32_e32 v68, 0x80000000, v67
	v_xor_b32_e32 v72, 0x80000000, v71
	v_pk_fma_f32 v[82:83], v[48:49], v[70:71], v[82:83] op_sel_hi:[0,1,1]
	v_pk_fma_f32 v[98:99], v[48:49], v[86:87], v[98:99] op_sel_hi:[0,1,1]
	v_pk_fma_f32 v[114:115], v[48:49], v[102:103], v[114:115] op_sel_hi:[0,1,1]
	v_pk_fma_f32 v[130:131], v[48:49], v[118:119], v[130:131] op_sel_hi:[0,1,1]
	v_pk_fma_f32 v[148:149], v[48:49], v[134:135], v[148:149] op_sel_hi:[0,1,1]
	v_pk_fma_f32 v[164:165], v[48:49], v[152:153], v[164:165] op_sel_hi:[0,1,1]
	v_mov_b32_e32 v61, v59
	v_mov_b32_e32 v65, v63
	v_mov_b32_e32 v69, v67
	v_mov_b32_e32 v73, v71
	v_pk_fma_f32 v[46:47], v[48:49], v[228:229], v[46:47] op_sel_hi:[0,1,1]
	v_pk_mul_f32 v[48:49], v[176:177], v[52:53] op_sel:[1,1] op_sel_hi:[0,1] neg_lo:[0,1]
	v_xor_b32_e32 v76, 0x80000000, v75
	v_xor_b32_e32 v80, 0x80000000, v79
	v_xor_b32_e32 v84, 0x80000000, v83
	v_xor_b32_e32 v88, 0x80000000, v87
	v_xor_b32_e32 v92, 0x80000000, v91
	v_xor_b32_e32 v96, 0x80000000, v95
	v_xor_b32_e32 v100, 0x80000000, v99
	v_xor_b32_e32 v104, 0x80000000, v103
	v_xor_b32_e32 v136, 0x80000000, v135
	v_mov_b32_e32 v77, v75
	v_mov_b32_e32 v81, v79
	v_mov_b32_e32 v85, v83
	v_mov_b32_e32 v89, v87
	v_mov_b32_e32 v93, v91
	v_mov_b32_e32 v97, v95
	v_mov_b32_e32 v101, v99
	v_mov_b32_e32 v105, v103
	v_mov_b32_e32 v137, v135
	v_pk_fma_f32 v[48:49], v[176:177], v[52:53], v[48:49] op_sel_hi:[1,0,1]
	v_pk_mul_f32 v[50:51], v[60:61], v[220:221] op_sel:[0,1] op_sel_hi:[1,0]
	v_pk_mul_f32 v[52:53], v[192:193], v[64:65] op_sel:[1,0] op_sel_hi:[0,1]
	s_waitcnt lgkmcnt(3)
	v_pk_mul_f32 v[54:55], v[68:69], v[236:237] op_sel:[0,1] op_sel_hi:[1,0]
	v_pk_mul_f32 v[56:57], v[172:173], v[72:73] op_sel:[1,0] op_sel_hi:[0,1]
	v_xor_b32_e32 v108, 0x80000000, v107
	v_xor_b32_e32 v112, 0x80000000, v111
	v_xor_b32_e32 v116, 0x80000000, v115
	v_xor_b32_e32 v120, 0x80000000, v119
	v_xor_b32_e32 v124, 0x80000000, v123
	v_xor_b32_e32 v128, 0x80000000, v127
	v_xor_b32_e32 v132, 0x80000000, v131
	v_xor_b32_e32 v140, 0x80000000, v139
	v_xor_b32_e32 v144, 0x80000000, v143
	v_xor_b32_e32 v150, 0x80000000, v149
	v_xor_b32_e32 v154, 0x80000000, v153
	v_xor_b32_e32 v158, 0x80000000, v157
	v_xor_b32_e32 v162, 0x80000000, v161
	v_xor_b32_e32 v166, 0x80000000, v165
	v_mov_b32_e32 v109, v107
	v_mov_b32_e32 v113, v111
	v_mov_b32_e32 v117, v115
	v_mov_b32_e32 v121, v119
	v_mov_b32_e32 v125, v123
	v_mov_b32_e32 v129, v127
	v_mov_b32_e32 v133, v131
	v_mov_b32_e32 v141, v139
	v_mov_b32_e32 v145, v143
	v_mov_b32_e32 v151, v149
	v_mov_b32_e32 v155, v153
	v_mov_b32_e32 v159, v157
	v_mov_b32_e32 v163, v161
	v_mov_b32_e32 v167, v165
	v_pk_fma_f32 v[50:51], v[58:59], v[220:221], v[50:51] op_sel_hi:[0,1,1]
	v_pk_fma_f32 v[52:53], v[192:193], v[62:63], v[52:53] op_sel_hi:[1,0,1]
	v_pk_fma_f32 v[54:55], v[66:67], v[236:237], v[54:55] op_sel_hi:[0,1,1]
	v_pk_fma_f32 v[56:57], v[172:173], v[70:71], v[56:57] op_sel_hi:[1,0,1]
	v_pk_mul_f32 v[58:59], v[216:217], v[76:77] op_sel:[1,0] op_sel_hi:[0,1]
	v_pk_mul_f32 v[60:61], v[188:189], v[80:81] op_sel:[1,0] op_sel_hi:[0,1]
	v_pk_mul_f32 v[62:63], v[84:85], v[232:233] op_sel:[0,1] op_sel_hi:[1,0]
	v_pk_mul_f32 v[64:65], v[180:181], v[88:89] op_sel:[1,0] op_sel_hi:[0,1]
	v_pk_mul_f32 v[66:67], v[224:225], v[92:93] op_sel:[1,0] op_sel_hi:[0,1]
	v_pk_mul_f32 v[68:69], v[196:197], v[96:97] op_sel:[1,0] op_sel_hi:[0,1]
	s_waitcnt lgkmcnt(1)
	v_pk_mul_f32 v[70:71], v[100:101], v[240:241] op_sel:[0,1] op_sel_hi:[1,0]
	v_pk_mul_f32 v[72:73], v[170:171], v[104:105] op_sel:[1,0] op_sel_hi:[0,1]
	v_pk_mul_f32 v[88:89], v[174:175], v[136:137] op_sel:[1,0] op_sel_hi:[0,1]
	v_pk_fma_f32 v[58:59], v[216:217], v[74:75], v[58:59] op_sel_hi:[1,0,1]
	v_pk_fma_f32 v[60:61], v[188:189], v[78:79], v[60:61] op_sel_hi:[1,0,1]
	v_pk_fma_f32 v[62:63], v[82:83], v[232:233], v[62:63] op_sel_hi:[0,1,1]
	v_pk_fma_f32 v[64:65], v[180:181], v[86:87], v[64:65] op_sel_hi:[1,0,1]
	v_pk_fma_f32 v[66:67], v[224:225], v[90:91], v[66:67] op_sel_hi:[1,0,1]
	v_pk_fma_f32 v[68:69], v[196:197], v[94:95], v[68:69] op_sel_hi:[1,0,1]
	v_pk_fma_f32 v[70:71], v[98:99], v[240:241], v[70:71] op_sel_hi:[0,1,1]
	v_pk_fma_f32 v[72:73], v[170:171], v[102:103], v[72:73] op_sel_hi:[1,0,1]
	v_pk_mul_f32 v[74:75], v[214:215], v[108:109] op_sel:[1,0] op_sel_hi:[0,1]
	v_pk_mul_f32 v[76:77], v[186:187], v[112:113] op_sel:[1,0] op_sel_hi:[0,1]
	v_pk_mul_f32 v[78:79], v[230:231], v[116:117] op_sel:[1,0] op_sel_hi:[0,1]
	v_pk_mul_f32 v[80:81], v[178:179], v[120:121] op_sel:[1,0] op_sel_hi:[0,1]
	v_pk_mul_f32 v[82:83], v[222:223], v[124:125] op_sel:[1,0] op_sel_hi:[0,1]
	v_pk_mul_f32 v[84:85], v[194:195], v[128:129] op_sel:[1,0] op_sel_hi:[0,1]
	v_pk_mul_f32 v[86:87], v[132:133], v[238:239] op_sel:[0,1] op_sel_hi:[1,0]
	v_pk_fma_f32 v[88:89], v[174:175], v[134:135], v[88:89] op_sel_hi:[1,0,1]
	v_pk_mul_f32 v[90:91], v[218:219], v[140:141] op_sel:[1,0] op_sel_hi:[0,1]
	v_pk_mul_f32 v[92:93], v[190:191], v[144:145] op_sel:[1,0] op_sel_hi:[0,1]
	v_pk_mul_f32 v[94:95], v[234:235], v[150:151] op_sel:[1,0] op_sel_hi:[0,1]
	v_pk_mul_f32 v[96:97], v[182:183], v[154:155] op_sel:[1,0] op_sel_hi:[0,1]
	v_pk_mul_f32 v[98:99], v[226:227], v[158:159] op_sel:[1,0] op_sel_hi:[0,1]
	v_pk_mul_f32 v[100:101], v[198:199], v[162:163] op_sel:[1,0] op_sel_hi:[0,1]
	s_waitcnt lgkmcnt(0)
	v_pk_mul_f32 v[102:103], v[242:243], v[166:167] op_sel:[1,0] op_sel_hi:[0,1]
	v_pk_fma_f32 v[74:75], v[214:215], v[106:107], v[74:75] op_sel_hi:[1,0,1]
	v_pk_fma_f32 v[76:77], v[186:187], v[110:111], v[76:77] op_sel_hi:[1,0,1]
	v_pk_fma_f32 v[78:79], v[230:231], v[114:115], v[78:79] op_sel_hi:[1,0,1]
	v_pk_fma_f32 v[80:81], v[178:179], v[118:119], v[80:81] op_sel_hi:[1,0,1]
	v_pk_fma_f32 v[82:83], v[222:223], v[122:123], v[82:83] op_sel_hi:[1,0,1]
	v_pk_fma_f32 v[84:85], v[194:195], v[126:127], v[84:85] op_sel_hi:[1,0,1]
	v_pk_fma_f32 v[86:87], v[130:131], v[238:239], v[86:87] op_sel_hi:[0,1,1]
	v_pk_fma_f32 v[90:91], v[218:219], v[138:139], v[90:91] op_sel_hi:[1,0,1]
	v_pk_fma_f32 v[92:93], v[190:191], v[142:143], v[92:93] op_sel_hi:[1,0,1]
	v_pk_fma_f32 v[94:95], v[234:235], v[148:149], v[94:95] op_sel_hi:[1,0,1]
	v_pk_fma_f32 v[96:97], v[182:183], v[152:153], v[96:97] op_sel_hi:[1,0,1]
	v_pk_fma_f32 v[98:99], v[226:227], v[156:157], v[98:99] op_sel_hi:[1,0,1]
	v_pk_fma_f32 v[100:101], v[198:199], v[160:161], v[100:101] op_sel_hi:[1,0,1]
	v_pk_fma_f32 v[102:103], v[242:243], v[164:165], v[102:103] op_sel_hi:[1,0,1]
	v_pk_add_f32 v[104:105], v[168:169], v[72:73]
	v_pk_add_f32 v[106:107], v[56:57], v[88:89]
	v_pk_add_f32 v[56:57], v[56:57], v[88:89] neg_lo:[0,1] neg_hi:[0,1]
	v_pk_add_f32 v[72:73], v[168:169], v[72:73] neg_lo:[0,1] neg_hi:[0,1]
	v_pk_add_f32 v[88:89], v[48:49], v[80:81]
	v_pk_add_f32 v[48:49], v[48:49], v[80:81] neg_lo:[0,1] neg_hi:[0,1]
	v_pk_add_f32 v[80:81], v[64:65], v[96:97]
	v_pk_add_f32 v[64:65], v[64:65], v[96:97] neg_lo:[0,1] neg_hi:[0,1]
	v_pk_add_f32 v[96:97], v[44:45], v[76:77]
	v_pk_add_f32 v[44:45], v[44:45], v[76:77] neg_lo:[0,1] neg_hi:[0,1]
	v_pk_add_f32 v[76:77], v[60:61], v[92:93]
	v_pk_add_f32 v[60:61], v[60:61], v[92:93] neg_lo:[0,1] neg_hi:[0,1]
	v_pk_add_f32 v[92:93], v[52:53], v[84:85]
	v_pk_add_f32 v[52:53], v[52:53], v[84:85] neg_lo:[0,1] neg_hi:[0,1]
	v_pk_add_f32 v[84:85], v[68:69], v[100:101]
	v_pk_add_f32 v[68:69], v[68:69], v[100:101] neg_lo:[0,1] neg_hi:[0,1]
	v_pk_add_f32 v[100:101], v[42:43], v[74:75]
	v_pk_add_f32 v[42:43], v[42:43], v[74:75] neg_lo:[0,1] neg_hi:[0,1]
	v_pk_add_f32 v[74:75], v[58:59], v[90:91]
	v_pk_add_f32 v[58:59], v[58:59], v[90:91] neg_lo:[0,1] neg_hi:[0,1]
	v_pk_add_f32 v[90:91], v[50:51], v[82:83]
	v_pk_add_f32 v[50:51], v[50:51], v[82:83] neg_lo:[0,1] neg_hi:[0,1]
	v_pk_add_f32 v[82:83], v[66:67], v[98:99]
	v_pk_add_f32 v[66:67], v[66:67], v[98:99] neg_lo:[0,1] neg_hi:[0,1]
	v_pk_add_f32 v[98:99], v[46:47], v[78:79]
	v_pk_add_f32 v[46:47], v[46:47], v[78:79] neg_lo:[0,1] neg_hi:[0,1]
	v_pk_add_f32 v[78:79], v[62:63], v[94:95]
	v_pk_add_f32 v[62:63], v[62:63], v[94:95] neg_lo:[0,1] neg_hi:[0,1]
	v_pk_add_f32 v[94:95], v[54:55], v[86:87]
	v_pk_add_f32 v[54:55], v[54:55], v[86:87] neg_lo:[0,1] neg_hi:[0,1]
	v_pk_add_f32 v[86:87], v[70:71], v[102:103]
	v_pk_add_f32 v[70:71], v[70:71], v[102:103] neg_lo:[0,1] neg_hi:[0,1]
	v_pk_add_f32 v[102:103], v[104:105], v[106:107]
	v_pk_add_f32 v[104:105], v[104:105], v[106:107] neg_lo:[0,1] neg_hi:[0,1]
	v_xor_b32_e32 v106, 0x80000000, v57
	v_mov_b32_e32 v107, v56
	v_pk_add_f32 v[56:57], v[72:73], v[106:107]
	v_pk_add_f32 v[72:73], v[72:73], v[106:107] neg_lo:[0,1] neg_hi:[0,1]
	v_pk_add_f32 v[106:107], v[88:89], v[80:81]
	v_pk_add_f32 v[80:81], v[88:89], v[80:81] neg_lo:[0,1] neg_hi:[0,1]
	v_xor_b32_e32 v88, 0x80000000, v65
	v_mov_b32_e32 v89, v64
	v_pk_add_f32 v[64:65], v[48:49], v[88:89]
	v_pk_add_f32 v[48:49], v[48:49], v[88:89] neg_lo:[0,1] neg_hi:[0,1]
	v_pk_add_f32 v[88:89], v[96:97], v[76:77]
	v_pk_add_f32 v[76:77], v[96:97], v[76:77] neg_lo:[0,1] neg_hi:[0,1]
	v_xor_b32_e32 v96, 0x80000000, v61
	v_mov_b32_e32 v97, v60
	v_pk_add_f32 v[60:61], v[44:45], v[96:97]
	v_pk_add_f32 v[44:45], v[44:45], v[96:97] neg_lo:[0,1] neg_hi:[0,1]
	v_pk_add_f32 v[96:97], v[92:93], v[84:85]
	v_pk_add_f32 v[84:85], v[92:93], v[84:85] neg_lo:[0,1] neg_hi:[0,1]
	v_xor_b32_e32 v92, 0x80000000, v69
	v_mov_b32_e32 v93, v68
	v_pk_add_f32 v[68:69], v[52:53], v[92:93]
	v_pk_add_f32 v[52:53], v[52:53], v[92:93] neg_lo:[0,1] neg_hi:[0,1]
	v_pk_add_f32 v[92:93], v[100:101], v[74:75]
	v_pk_add_f32 v[74:75], v[100:101], v[74:75] neg_lo:[0,1] neg_hi:[0,1]
	v_xor_b32_e32 v100, 0x80000000, v59
	v_mov_b32_e32 v101, v58
	v_pk_add_f32 v[58:59], v[42:43], v[100:101]
	v_pk_add_f32 v[42:43], v[42:43], v[100:101] neg_lo:[0,1] neg_hi:[0,1]
	v_pk_add_f32 v[100:101], v[90:91], v[82:83]
	v_pk_add_f32 v[82:83], v[90:91], v[82:83] neg_lo:[0,1] neg_hi:[0,1]
	v_xor_b32_e32 v90, 0x80000000, v67
	v_mov_b32_e32 v91, v66
	v_pk_add_f32 v[66:67], v[50:51], v[90:91]
	v_pk_add_f32 v[50:51], v[50:51], v[90:91] neg_lo:[0,1] neg_hi:[0,1]
	v_pk_add_f32 v[90:91], v[98:99], v[78:79]
	v_pk_add_f32 v[78:79], v[98:99], v[78:79] neg_lo:[0,1] neg_hi:[0,1]
	v_xor_b32_e32 v98, 0x80000000, v63
	v_mov_b32_e32 v99, v62
	v_pk_add_f32 v[62:63], v[46:47], v[98:99]
	v_pk_add_f32 v[46:47], v[46:47], v[98:99] neg_lo:[0,1] neg_hi:[0,1]
	v_pk_add_f32 v[98:99], v[94:95], v[86:87]
	v_pk_add_f32 v[86:87], v[94:95], v[86:87] neg_lo:[0,1] neg_hi:[0,1]
	v_xor_b32_e32 v94, 0x80000000, v71
	v_mov_b32_e32 v95, v70
	s_mov_b32 s63, s36
	v_pk_add_f32 v[70:71], v[54:55], v[94:95]
	v_pk_add_f32 v[54:55], v[54:55], v[94:95] neg_lo:[0,1] neg_hi:[0,1]
	v_pk_add_f32 v[94:95], v[102:103], v[106:107]
	v_pk_add_f32 v[102:103], v[102:103], v[106:107] neg_lo:[0,1] neg_hi:[0,1]
	s_mov_b32 s0, s37
	v_pk_mul_f32 v[106:107], v[64:65], s[62:63]
	s_mov_b32 s64, s19
	v_pk_fma_f32 v[64:65], v[64:65], s[0:1], v[106:107] op_sel:[0,0,1] op_sel_hi:[1,0,0]
	s_mov_b32 s65, s18
	v_pk_add_f32 v[106:107], v[56:57], v[64:65]
	v_pk_add_f32 v[56:57], v[56:57], v[64:65] neg_lo:[0,1] neg_hi:[0,1]
	v_xor_b32_e32 v64, 0x80000000, v81
	v_mov_b32_e32 v65, v80
	v_pk_add_f32 v[80:81], v[104:105], v[64:65]
	v_pk_add_f32 v[64:65], v[104:105], v[64:65] neg_lo:[0,1] neg_hi:[0,1]
	v_pk_mul_f32 v[104:105], v[48:49], s[62:63]
	s_mov_b32 s66, s19
	v_pk_fma_f32 v[48:49], v[48:49], s[0:1], v[104:105] op_sel:[0,0,1] op_sel_hi:[1,0,0] neg_lo:[1,0,0] neg_hi:[1,0,0]
	s_mov_b32 s68, s11
	v_pk_add_f32 v[104:105], v[72:73], v[48:49]
	v_pk_add_f32 v[48:49], v[72:73], v[48:49] neg_lo:[0,1] neg_hi:[0,1]
	v_pk_add_f32 v[72:73], v[88:89], v[96:97]
	v_pk_add_f32 v[88:89], v[88:89], v[96:97] neg_lo:[0,1] neg_hi:[0,1]
	v_pk_mul_f32 v[96:97], v[68:69], s[62:63]
	s_mov_b32 s69, s10
	v_pk_fma_f32 v[68:69], v[68:69], s[0:1], v[96:97] op_sel:[0,0,1] op_sel_hi:[1,0,0]
	s_mov_b32 s72, s27
	v_pk_add_f32 v[96:97], v[60:61], v[68:69]
	v_pk_add_f32 v[60:61], v[60:61], v[68:69] neg_lo:[0,1] neg_hi:[0,1]
	v_xor_b32_e32 v68, 0x80000000, v85
	v_mov_b32_e32 v69, v84
	v_pk_add_f32 v[84:85], v[76:77], v[68:69]
	v_pk_add_f32 v[68:69], v[76:77], v[68:69] neg_lo:[0,1] neg_hi:[0,1]
	v_pk_mul_f32 v[76:77], v[52:53], s[62:63]
	v_pk_mul_f32 v[108:109], v[96:97], s[64:65]
	v_pk_fma_f32 v[52:53], v[52:53], s[0:1], v[76:77] op_sel:[0,0,1] op_sel_hi:[1,0,0] neg_lo:[1,0,0] neg_hi:[1,0,0]
	v_pk_fma_f32 v[96:97], v[96:97], s[16:17], v[108:109] op_sel:[0,0,1] op_sel_hi:[1,0,0]
	v_pk_add_f32 v[76:77], v[44:45], v[52:53]
	v_pk_add_f32 v[44:45], v[44:45], v[52:53] neg_lo:[0,1] neg_hi:[0,1]
	v_pk_add_f32 v[52:53], v[92:93], v[100:101]
	v_pk_add_f32 v[92:93], v[92:93], v[100:101] neg_lo:[0,1] neg_hi:[0,1]
	v_pk_mul_f32 v[100:101], v[66:67], s[62:63]
	s_mov_b32 s17, s40
	v_pk_fma_f32 v[66:67], v[66:67], s[0:1], v[100:101] op_sel:[0,0,1] op_sel_hi:[1,0,0]
	v_pk_add_f32 v[108:109], v[106:107], v[96:97]
	v_pk_add_f32 v[100:101], v[58:59], v[66:67]
	v_pk_add_f32 v[58:59], v[58:59], v[66:67] neg_lo:[0,1] neg_hi:[0,1]
	v_xor_b32_e32 v66, 0x80000000, v83
	v_mov_b32_e32 v67, v82
	v_pk_add_f32 v[82:83], v[74:75], v[66:67]
	v_pk_add_f32 v[66:67], v[74:75], v[66:67] neg_lo:[0,1] neg_hi:[0,1]
	v_pk_mul_f32 v[74:75], v[50:51], s[62:63]
	v_pk_add_f32 v[96:97], v[106:107], v[96:97] neg_lo:[0,1] neg_hi:[0,1]
	v_pk_fma_f32 v[50:51], v[50:51], s[0:1], v[74:75] op_sel:[0,0,1] op_sel_hi:[1,0,0] neg_lo:[1,0,0] neg_hi:[1,0,0]
	v_pk_mul_f32 v[106:107], v[84:85], s[62:63]
	v_pk_add_f32 v[74:75], v[42:43], v[50:51]
	v_pk_add_f32 v[42:43], v[42:43], v[50:51] neg_lo:[0,1] neg_hi:[0,1]
	v_pk_add_f32 v[50:51], v[90:91], v[98:99]
	v_pk_add_f32 v[90:91], v[90:91], v[98:99] neg_lo:[0,1] neg_hi:[0,1]
	v_pk_mul_f32 v[98:99], v[70:71], s[62:63]
	v_pk_fma_f32 v[84:85], v[84:85], s[0:1], v[106:107] op_sel:[0,0,1] op_sel_hi:[1,0,0]
	v_pk_fma_f32 v[70:71], v[70:71], s[0:1], v[98:99] op_sel:[0,0,1] op_sel_hi:[1,0,0]
	v_pk_add_f32 v[106:107], v[80:81], v[84:85]
	v_pk_add_f32 v[98:99], v[62:63], v[70:71]
	v_pk_add_f32 v[62:63], v[62:63], v[70:71] neg_lo:[0,1] neg_hi:[0,1]
	v_xor_b32_e32 v70, 0x80000000, v87
	v_mov_b32_e32 v71, v86
	v_pk_mul_f32 v[110:111], v[98:99], s[64:65]
	v_pk_add_f32 v[86:87], v[78:79], v[70:71]
	v_pk_add_f32 v[70:71], v[78:79], v[70:71] neg_lo:[0,1] neg_hi:[0,1]
	v_pk_mul_f32 v[78:79], v[54:55], s[62:63]
	v_pk_fma_f32 v[98:99], v[98:99], s[16:17], v[110:111] op_sel:[0,0,1] op_sel_hi:[1,0,0]
	v_pk_fma_f32 v[54:55], v[54:55], s[0:1], v[78:79] op_sel:[0,0,1] op_sel_hi:[1,0,0] neg_lo:[1,0,0] neg_hi:[1,0,0]
	v_pk_add_f32 v[110:111], v[100:101], v[98:99]
	v_pk_add_f32 v[98:99], v[100:101], v[98:99] neg_lo:[0,1] neg_hi:[0,1]
	v_pk_mul_f32 v[100:101], v[86:87], s[62:63]
	v_pk_add_f32 v[78:79], v[46:47], v[54:55]
	v_pk_fma_f32 v[86:87], v[86:87], s[0:1], v[100:101] op_sel:[0,0,1] op_sel_hi:[1,0,0]
	v_pk_add_f32 v[46:47], v[46:47], v[54:55] neg_lo:[0,1] neg_hi:[0,1]
	v_pk_add_f32 v[100:101], v[82:83], v[86:87]
	v_pk_add_f32 v[82:83], v[82:83], v[86:87] neg_lo:[0,1] neg_hi:[0,1]
	v_pk_mul_f32 v[86:87], v[78:79], s[16:17]
	v_pk_add_f32 v[80:81], v[80:81], v[84:85] neg_lo:[0,1] neg_hi:[0,1]
	v_pk_fma_f32 v[78:79], v[78:79], s[66:67], v[86:87] op_sel:[0,0,1] op_sel_hi:[1,0,0]
	v_pk_mul_f32 v[84:85], v[76:77], s[16:17]
	v_pk_add_f32 v[86:87], v[74:75], v[78:79]
	v_pk_add_f32 v[74:75], v[74:75], v[78:79] neg_lo:[0,1] neg_hi:[0,1]
	v_xor_b32_e32 v78, 0x80000000, v91
	v_mov_b32_e32 v79, v90
	v_pk_add_f32 v[90:91], v[92:93], v[78:79]
	v_pk_add_f32 v[78:79], v[92:93], v[78:79] neg_lo:[0,1] neg_hi:[0,1]
	v_pk_mul_f32 v[92:93], v[62:63], s[16:17]
	v_pk_fma_f32 v[76:77], v[76:77], s[66:67], v[84:85] op_sel:[0,0,1] op_sel_hi:[1,0,0]
	v_pk_fma_f32 v[62:63], v[62:63], s[66:67], v[92:93] op_sel:[0,0,1] op_sel_hi:[1,0,0] neg_lo:[1,0,0] neg_hi:[1,0,0]
	v_pk_add_f32 v[84:85], v[104:105], v[76:77]
	v_pk_add_f32 v[92:93], v[58:59], v[62:63]
	v_pk_add_f32 v[58:59], v[58:59], v[62:63] neg_lo:[0,1] neg_hi:[0,1]
	v_pk_mul_f32 v[62:63], v[70:71], s[62:63]
	v_pk_add_f32 v[76:77], v[104:105], v[76:77] neg_lo:[0,1] neg_hi:[0,1]
	v_pk_fma_f32 v[62:63], v[70:71], s[0:1], v[62:63] op_sel:[0,0,1] op_sel_hi:[1,0,0] neg_lo:[1,0,0] neg_hi:[1,0,0]
	v_xor_b32_e32 v104, 0x80000000, v89
	v_pk_add_f32 v[70:71], v[66:67], v[62:63]
	v_pk_add_f32 v[62:63], v[66:67], v[62:63] neg_lo:[0,1] neg_hi:[0,1]
	v_pk_mul_f32 v[66:67], v[46:47], s[64:65]
	v_mov_b32_e32 v105, v88
	v_pk_fma_f32 v[46:47], v[46:47], s[16:17], v[66:67] op_sel:[0,0,1] op_sel_hi:[1,0,0] neg_lo:[1,0,0] neg_hi:[1,0,0]
	s_mov_b32 s73, s26
	v_pk_add_f32 v[66:67], v[42:43], v[46:47]
	v_pk_add_f32 v[42:43], v[42:43], v[46:47] neg_lo:[0,1] neg_hi:[0,1]
	v_pk_mul_f32 v[46:47], v[110:111], s[68:69]
	v_pk_add_f32 v[88:89], v[102:103], v[104:105]
	v_pk_fma_f32 v[46:47], v[110:111], s[8:9], v[46:47] op_sel:[0,0,1] op_sel_hi:[1,0,0]
	v_pk_add_f32 v[102:103], v[102:103], v[104:105] neg_lo:[0,1] neg_hi:[0,1]
	v_pk_add_f32 v[46:47], v[108:109], v[46:47]
	v_pk_mul_f32 v[108:109], v[100:101], s[64:65]
	v_pk_mul_f32 v[104:105], v[60:61], s[16:17]
	v_pk_fma_f32 v[100:101], v[100:101], s[16:17], v[108:109] op_sel:[0,0,1] op_sel_hi:[1,0,0]
	v_pk_fma_f32 v[60:61], v[60:61], s[66:67], v[104:105] op_sel:[0,0,1] op_sel_hi:[1,0,0] neg_lo:[1,0,0] neg_hi:[1,0,0]
	v_pk_add_f32 v[100:101], v[106:107], v[100:101]
	v_pk_mul_f32 v[106:107], v[86:87], s[72:73]
	v_pk_add_f32 v[104:105], v[56:57], v[60:61]
	v_pk_fma_f32 v[86:87], v[86:87], s[24:25], v[106:107] op_sel:[0,0,1] op_sel_hi:[1,0,0]
	v_pk_add_f32 v[56:57], v[56:57], v[60:61] neg_lo:[0,1] neg_hi:[0,1]
	v_pk_mul_f32 v[60:61], v[68:69], s[62:63]
	v_pk_add_f32 v[84:85], v[84:85], v[86:87]
	v_pk_mul_f32 v[86:87], v[90:91], s[62:63]
	v_pk_fma_f32 v[60:61], v[68:69], s[0:1], v[60:61] op_sel:[0,0,1] op_sel_hi:[1,0,0] neg_lo:[1,0,0] neg_hi:[1,0,0]
	v_pk_fma_f32 v[86:87], v[90:91], s[0:1], v[86:87] op_sel:[0,0,1] op_sel_hi:[1,0,0]
	v_pk_mul_f32 v[90:91], v[70:71], s[16:17]
	v_pk_add_f32 v[68:69], v[64:65], v[60:61]
	v_pk_fma_f32 v[70:71], v[70:71], s[66:67], v[90:91] op_sel:[0,0,1] op_sel_hi:[1,0,0]
	s_mov_b32 s9, s42
	s_mov_b32 s25, s38
	v_pk_add_f32 v[68:69], v[68:69], v[70:71]
	s_mov_b32 s76, s11
	v_pk_mul_f32 v[70:71], v[66:67], s[8:9]
	s_mov_b32 s74, s27
	v_pk_fma_f32 v[66:67], v[66:67], s[76:77], v[70:71] op_sel:[0,0,1] op_sel_hi:[1,0,0]
	v_pk_mul_f32 v[70:71], v[74:75], s[24:25]
	v_pk_add_f32 v[60:61], v[64:65], v[60:61] neg_lo:[0,1] neg_hi:[0,1]
	v_pk_fma_f32 v[70:71], v[74:75], s[74:75], v[70:71] op_sel:[0,0,1] op_sel_hi:[1,0,0] neg_lo:[1,0,0] neg_hi:[1,0,0]
	v_pk_mul_f32 v[64:65], v[44:45], s[64:65]
	v_pk_add_f32 v[70:71], v[76:77], v[70:71]
	v_pk_mul_f32 v[76:77], v[58:59], s[72:73]
	v_pk_fma_f32 v[44:45], v[44:45], s[16:17], v[64:65] op_sel:[0,0,1] op_sel_hi:[1,0,0] neg_lo:[1,0,0] neg_hi:[1,0,0]
	v_pk_fma_f32 v[58:59], v[58:59], s[24:25], v[76:77] op_sel:[0,0,1] op_sel_hi:[1,0,0] neg_lo:[1,0,0] neg_hi:[1,0,0]
	v_pk_add_f32 v[64:65], v[48:49], v[44:45]
	v_pk_add_f32 v[56:57], v[56:57], v[58:59]
	v_pk_mul_f32 v[58:59], v[62:63], s[64:65]
	v_pk_add_f32 v[44:45], v[48:49], v[44:45] neg_lo:[0,1] neg_hi:[0,1]
	v_pk_fma_f32 v[58:59], v[62:63], s[16:17], v[58:59] op_sel:[0,0,1] op_sel_hi:[1,0,0] neg_lo:[1,0,0] neg_hi:[1,0,0]
	v_pk_add_f32 v[48:49], v[52:53], v[50:51] neg_lo:[0,1] neg_hi:[0,1]
	v_pk_add_f32 v[58:59], v[60:61], v[58:59]
	v_pk_mul_f32 v[60:61], v[42:43], s[68:69]
	v_pk_add_f32 v[54:55], v[94:95], v[72:73] neg_lo:[0,1] neg_hi:[0,1]
	v_pk_add_f32 v[64:65], v[64:65], v[66:67]
	v_xor_b32_e32 v66, 0x80000000, v49
	v_mov_b32_e32 v67, v48
	v_pk_fma_f32 v[42:43], v[42:43], s[8:9], v[60:61] op_sel:[0,0,1] op_sel_hi:[1,0,0] neg_lo:[1,0,0] neg_hi:[1,0,0]
	v_pk_add_f32 v[86:87], v[88:89], v[86:87]
	v_pk_mul_f32 v[88:89], v[92:93], s[24:25]
	v_pk_add_f32 v[48:49], v[54:55], v[66:67]
	v_pk_mul_f32 v[54:55], v[98:99], s[8:9]
	v_pk_mul_f32 v[66:67], v[82:83], s[16:17]
	v_pk_mul_f32 v[74:75], v[78:79], s[62:63]
	v_pk_add_f32 v[42:43], v[44:45], v[42:43]
	v_pk_add_f32 v[44:45], v[94:95], v[72:73]
	v_pk_add_f32 v[50:51], v[52:53], v[50:51]
	v_pk_fma_f32 v[88:89], v[92:93], s[74:75], v[88:89] op_sel:[0,0,1] op_sel_hi:[1,0,0]
	v_pk_fma_f32 v[54:55], v[98:99], s[76:77], v[54:55] op_sel:[0,0,1] op_sel_hi:[1,0,0] neg_lo:[1,0,0] neg_hi:[1,0,0]
	v_pk_fma_f32 v[66:67], v[82:83], s[66:67], v[66:67] op_sel:[0,0,1] op_sel_hi:[1,0,0] neg_lo:[1,0,0] neg_hi:[1,0,0]
	v_pk_fma_f32 v[74:75], v[78:79], s[0:1], v[74:75] op_sel:[0,0,1] op_sel_hi:[1,0,0] neg_lo:[1,0,0] neg_hi:[1,0,0]
	v_pk_add_f32 v[44:45], v[44:45], v[50:51]
	v_lshl_add_u32 v21, v21, 3, v36
	v_pk_add_f32 v[88:89], v[104:105], v[88:89]
	v_pk_add_f32 v[54:55], v[96:97], v[54:55]
	v_pk_add_f32 v[66:67], v[80:81], v[66:67]
	v_pk_add_f32 v[74:75], v[102:103], v[74:75]
	ds_write_b64 v25, v[44:45]
	ds_write_b64 v25, v[46:47] offset:2112
	ds_write_b64 v25, v[100:101] offset:4224
	ds_write_b64 v25, v[84:85] offset:6336
	ds_write_b64 v25, v[86:87] offset:8448
	ds_write_b64 v25, v[88:89] offset:10560
	ds_write_b64 v25, v[68:69] offset:12672
	ds_write_b64 v25, v[64:65] offset:14784
	ds_write_b64 v25, v[48:49] offset:16896
	ds_write_b64 v25, v[54:55] offset:19008
	ds_write_b64 v25, v[66:67] offset:21120
	ds_write_b64 v25, v[70:71] offset:23232
	ds_write_b64 v25, v[74:75] offset:25344
	ds_write_b64 v25, v[56:57] offset:27456
	ds_write_b64 v25, v[58:59] offset:29568
	ds_write_b64 v25, v[42:43] offset:31680
	v_ashrrev_i32_e32 v25, 5, v21
	v_lshlrev_b32_e32 v21, 3, v21
	v_lshlrev_b32_e32 v25, 3, v25
	s_waitcnt vmcnt(0)
	v_lshlrev_b32_e32 v41, 16, v41
	v_lshlrev_b32_e32 v39, 16, v39
	v_lshlrev_b32_e32 v35, 16, v35
	v_lshlrev_b32_e32 v29, 16, v29
	v_and_b32_e32 v48, 0xffff0000, v14
	v_add3_u32 v21, 0, v21, v25
	v_mov_b32_e32 v40, v48
	s_waitcnt lgkmcnt(0)
	s_barrier
	v_pk_mul_f32 v[44:45], v[30:31], v[40:41]
	ds_read2_b64 v[40:43], v21 offset1:1
	v_lshlrev_b32_e32 v28, 16, v14
	v_lshlrev_b32_e32 v49, 16, v15
	v_pk_fma_f32 v[44:45], v[30:31], v[28:29], v[44:45] op_sel:[0,0,1] op_sel_hi:[1,0,0]
	v_mov_b32_e32 v28, v31
	v_pk_fma_f32 v[44:45], v[20:21], v[48:49], v[44:45] op_sel_hi:[0,1,1]
	v_pk_add_f32 v[50:51], v[24:25], v[44:45] op_sel_hi:[0,1]
	ds_read2_b64 v[44:47], v21 offset0:2 offset1:3
	s_waitcnt lgkmcnt(1)
	v_pk_mul_f32 v[40:41], v[50:51], v[40:41]
	v_and_b32_e32 v51, 16, v16
	v_and_b32_e32 v50, 0xffff0000, v15
	v_pk_mov_b32 v[14:15], v[48:49], v[50:51] op_sel:[1,0]
	v_lshlrev_b32_e32 v53, 16, v16
	v_pk_mul_f32 v[14:15], v[30:31], v[14:15] op_sel_hi:[0,1]
	v_mov_b32_e32 v52, v50
	v_pk_fma_f32 v[14:15], v[28:29], v[48:49], v[14:15] op_sel_hi:[0,1,1]
	v_pk_fma_f32 v[14:15], v[20:21], v[52:53], v[14:15] op_sel_hi:[0,1,1]
	v_pk_add_f32 v[14:15], v[24:25], v[14:15] op_sel_hi:[0,1]
	v_pk_mul_f32 v[14:15], v[14:15], v[42:43]
	v_and_b32_e32 v43, 16, v17
	v_and_b32_e32 v42, 0xffff0000, v16
	v_lshlrev_b32_e32 v49, 16, v17
	v_mov_b32_e32 v48, v42
	v_pk_mov_b32 v[42:43], v[52:53], v[42:43] op_sel:[1,0]
	v_pk_mov_b32 v[16:17], v[16:17], v[10:11] op_sel:[1,0]
	v_pk_mul_f32 v[42:43], v[30:31], v[42:43] op_sel_hi:[0,1]
	v_and_b32_e32 v17, 16, v17
	v_and_b32_e32 v16, 0xffff0000, v16
	v_pk_fma_f32 v[42:43], v[28:29], v[52:53], v[42:43] op_sel_hi:[0,1,1]
	v_mov_b32_e32 v50, v16
	v_pk_mov_b32 v[16:17], v[48:49], v[16:17] op_sel:[1,0]
	v_pk_fma_f32 v[42:43], v[20:21], v[48:49], v[42:43] op_sel_hi:[0,1,1]
	v_pk_mul_f32 v[16:17], v[30:31], v[16:17] op_sel_hi:[0,1]
	v_pk_add_f32 v[42:43], v[24:25], v[42:43] op_sel_hi:[0,1]
	v_lshlrev_b32_e32 v51, 16, v10
	v_pk_fma_f32 v[16:17], v[28:29], v[48:49], v[16:17] op_sel_hi:[0,1,1]
	s_waitcnt lgkmcnt(0)
	v_pk_mul_f32 v[42:43], v[42:43], v[44:45]
	v_pk_fma_f32 v[16:17], v[20:21], v[50:51], v[16:17] op_sel_hi:[0,1,1]
	v_and_b32_e32 v45, 16, v11
	v_and_b32_e32 v44, 0xffff0000, v10
	v_pk_add_f32 v[16:17], v[24:25], v[16:17] op_sel_hi:[0,1]
	v_mov_b32_e32 v52, v44
	v_pk_mov_b32 v[44:45], v[50:51], v[44:45] op_sel:[1,0]
	v_pk_mul_f32 v[16:17], v[16:17], v[46:47]
	v_pk_mul_f32 v[48:49], v[30:31], v[44:45] op_sel_hi:[0,1]
	ds_read2_b64 v[44:47], v21 offset0:4 offset1:5
	v_lshlrev_b32_e32 v53, 16, v11
	v_pk_fma_f32 v[48:49], v[28:29], v[50:51], v[48:49] op_sel_hi:[0,1,1]
	v_pk_fma_f32 v[48:49], v[20:21], v[52:53], v[48:49] op_sel_hi:[0,1,1]
	v_pk_add_f32 v[54:55], v[24:25], v[48:49] op_sel_hi:[0,1]
	ds_read2_b64 v[48:51], v21 offset0:6 offset1:7
	s_waitcnt lgkmcnt(1)
	v_pk_mul_f32 v[44:45], v[54:55], v[44:45]
	v_and_b32_e32 v55, 16, v12
	v_and_b32_e32 v54, 0xffff0000, v11
	v_pk_mov_b32 v[10:11], v[52:53], v[54:55] op_sel:[1,0]
	v_lshlrev_b32_e32 v57, 16, v12
	v_pk_mul_f32 v[10:11], v[30:31], v[10:11] op_sel_hi:[0,1]
	v_mov_b32_e32 v56, v54
	v_pk_fma_f32 v[10:11], v[28:29], v[52:53], v[10:11] op_sel_hi:[0,1,1]
	v_pk_fma_f32 v[10:11], v[20:21], v[56:57], v[10:11] op_sel_hi:[0,1,1]
	v_pk_add_f32 v[10:11], v[24:25], v[10:11] op_sel_hi:[0,1]
	v_and_b32_e32 v38, 0xffff0000, v13
	v_pk_mul_f32 v[10:11], v[10:11], v[46:47]
	v_and_b32_e32 v47, 16, v13
	v_and_b32_e32 v46, 0xffff0000, v12
	v_lshlrev_b32_e32 v53, 16, v13
	v_mov_b32_e32 v52, v46
	v_pk_mov_b32 v[12:13], v[56:57], v[46:47] op_sel:[1,0]
	v_mov_b32_e32 v46, v53
	v_mov_b32_e32 v47, v38
	v_pk_mul_f32 v[12:13], v[30:31], v[12:13] op_sel_hi:[0,1]
	v_pk_mul_f32 v[46:47], v[30:31], v[46:47] op_sel_hi:[0,1]
	v_pk_fma_f32 v[12:13], v[28:29], v[56:57], v[12:13] op_sel_hi:[0,1,1]
	v_pk_fma_f32 v[46:47], v[28:29], v[52:53], v[46:47] op_sel_hi:[0,1,1]
	v_pk_fma_f32 v[12:13], v[20:21], v[52:53], v[12:13] op_sel_hi:[0,1,1]
	v_pk_fma_f32 v[38:39], v[20:21], v[38:39], v[46:47] op_sel_hi:[0,1,1]
	s_xor_b64 s[50:51], s[50:51], -1
	v_pk_add_f32 v[12:13], v[24:25], v[12:13] op_sel_hi:[0,1]
	v_pk_add_f32 v[38:39], v[24:25], v[38:39] op_sel_hi:[0,1]
	s_waitcnt lgkmcnt(0)
	v_pk_mul_f32 v[12:13], v[12:13], v[48:49]
	v_pk_mul_f32 v[38:39], v[38:39], v[50:51]
	s_mov_b64 s[0:1], -1
	s_and_b64 vcc, exec, s[50:51]
	s_cbranch_vccz .LBB0_548
	v_bfe_u32 v46, v15, 16, 1
	v_add3_u32 v47, v15, v46, s4
	v_bfe_u32 v46, v14, 16, 1
	v_bfe_u32 v48, v16, 16, 1
	v_bfe_u32 v50, v42, 16, 1
	v_bfe_u32 v34, v17, 16, 1
	v_bfe_u32 v49, v40, 16, 1
	v_add3_u32 v50, v42, v50, s4
	v_add3_u32 v48, v16, v48, s4
	v_add3_u32 v46, v14, v46, s4
	v_bfe_u32 v25, v43, 16, 1
	v_bfe_u32 v28, v41, 16, 1
	v_add3_u32 v34, v17, v34, s4
	v_add3_u32 v49, v40, v49, s4
	v_lshrrev_b32_e32 v51, 16, v46
	v_lshrrev_b32_e32 v52, 16, v48
	v_lshrrev_b32_e32 v48, 16, v50
	v_bfe_u32 v50, v11, 16, 1
	v_add3_u32 v28, v41, v28, s4
	v_add3_u32 v25, v43, v25, s4
	v_lshrrev_b32_e32 v46, 16, v49
	v_and_or_b32 v49, v34, s91, v52
	v_and_or_b32 v47, v47, s91, v51
	v_add3_u32 v51, v11, v50, s4
	v_bfe_u32 v50, v10, 16, 1
	v_bfe_u32 v52, v38, 16, 1
	v_bfe_u32 v53, v44, 16, 1
	v_bfe_u32 v54, v12, 16, 1
	v_lshl_add_u64 v[36:37], v[36:37], 1, s[70:71]
	v_and_or_b32 v48, v25, s91, v48
	v_and_or_b32 v46, v28, s91, v46
	v_bfe_u32 v25, v13, 16, 1
	v_bfe_u32 v28, v45, 16, 1
	v_bfe_u32 v34, v39, 16, 1
	v_add3_u32 v54, v12, v54, s4
	v_add3_u32 v53, v44, v53, s4
	v_add3_u32 v52, v38, v52, s4
	v_add3_u32 v50, v10, v50, s4
	v_add3_u32 v34, v39, v34, s4
	v_add3_u32 v28, v45, v28, s4
	v_add3_u32 v25, v13, v25, s4
	v_lshrrev_b32_e32 v55, 16, v50
	v_lshrrev_b32_e32 v56, 16, v52
	v_lshrrev_b32_e32 v50, 16, v53
	v_lshrrev_b32_e32 v52, 16, v54
	v_lshl_add_u64 v[32:33], v[32:33], 1, v[36:37]
	v_and_or_b32 v52, v25, s91, v52
	v_and_or_b32 v50, v28, s91, v50
	v_and_or_b32 v53, v34, s91, v56
	v_and_or_b32 v51, v51, s91, v55
	global_store_dwordx4 v[32:33], v[46:49], off
	global_store_dwordx4 v[32:33], v[50:53], off offset:16
	s_mov_b64 s[0:1], 0

.LBB0_560:
	s_or_b64 exec, exec, s[0:1]
	v_mov_b32_e32 v2, v142
	s_waitcnt lgkmcnt(0)
	s_barrier
	s_mov_b32 s41, s38
	v_and_b32_e32 v4, 0x1ff, v2
	v_lshlrev_b32_e32 v2, 5, v2
	v_and_or_b32 v2, v2, s34, v4
	v_ashrrev_i32_e32 v6, 5, v2
	v_lshlrev_b32_e32 v2, 3, v2
	v_lshlrev_b32_e32 v7, 3, v6
	v_add3_u32 v2, 0, v2, v7
	v_add_u32_e32 v143, 0x10800, v2
	ds_read_b64 v[128:129], v2
	ds_read_b64 v[130:131], v2 offset:4224
	ds_read_b64 v[144:145], v2 offset:8448
	ds_read_b64 v[148:149], v2 offset:12672
	ds_read_b64 v[150:151], v2 offset:16896
	ds_read_b64 v[152:153], v2 offset:21120
	ds_read_b64 v[154:155], v2 offset:25344
	ds_read_b64 v[156:157], v2 offset:29568
	ds_read_b64 v[158:159], v2 offset:33792
	ds_read_b64 v[160:161], v2 offset:38016
	ds_read_b64 v[162:163], v2 offset:42240
	ds_read_b64 v[164:165], v2 offset:46464
	ds_read_b64 v[166:167], v2 offset:50688
	ds_read_b64 v[168:169], v2 offset:54912
	ds_read_b64 v[170:171], v2 offset:59136
	ds_read_b64 v[172:173], v2 offset:63360
	v_add_u32_e32 v212, 0x11880, v2
	v_add_u32_e32 v213, 0x12900, v2
	v_add_u32_e32 v214, 0x13980, v2
	ds_read_b64 v[174:175], v143
	ds_read_b64 v[176:177], v212
	ds_read_b64 v[178:179], v213
	ds_read_b64 v[180:181], v214
	v_add_u32_e32 v215, 0x14a00, v2
	s_waitcnt lgkmcnt(3)
	v_pk_add_f32 v[210:211], v[128:129], v[174:175]
	v_pk_add_f32 v[128:129], v[128:129], v[174:175] neg_lo:[0,1] neg_hi:[0,1]
	s_waitcnt lgkmcnt(2)
	v_pk_add_f32 v[174:175], v[130:131], v[176:177]
	v_pk_add_f32 v[130:131], v[130:131], v[176:177] neg_lo:[0,1] neg_hi:[0,1]
	v_add_u32_e32 v216, 0x15a80, v2
	v_pk_mul_f32 v[176:177], v[130:131], s[20:21]
	v_add_u32_e32 v217, 0x16b00, v2
	v_pk_fma_f32 v[130:131], v[130:131], s[10:11], v[176:177] op_sel:[0,0,1] op_sel_hi:[1,0,0]
	s_waitcnt lgkmcnt(1)
	v_pk_add_f32 v[176:177], v[144:145], v[178:179]
	v_pk_add_f32 v[144:145], v[144:145], v[178:179] neg_lo:[0,1] neg_hi:[0,1]
	v_add_u32_e32 v218, 0x17b80, v2
	v_pk_mul_f32 v[178:179], v[144:145], s[24:25]
	ds_read_b64 v[182:183], v215
	ds_read_b64 v[184:185], v216
	ds_read_b64 v[186:187], v217
	ds_read_b64 v[188:189], v218
	v_pk_fma_f32 v[144:145], v[144:145], s[22:23], v[178:179] op_sel:[0,0,1] op_sel_hi:[1,0,0]
	s_waitcnt lgkmcnt(4)
	v_pk_add_f32 v[178:179], v[148:149], v[180:181]
	v_pk_add_f32 v[148:149], v[148:149], v[180:181] neg_lo:[0,1] neg_hi:[0,1]
	s_mov_b32 s43, s26
	v_pk_mul_f32 v[180:181], v[148:149], s[36:37]
	s_mov_b32 s0, s37
	v_pk_fma_f32 v[148:149], v[148:149], s[26:27], v[180:181] op_sel:[0,0,1] op_sel_hi:[1,0,0]
	s_waitcnt lgkmcnt(3)
	v_pk_add_f32 v[180:181], v[150:151], v[182:183]
	v_pk_add_f32 v[150:151], v[150:151], v[182:183] neg_lo:[0,1] neg_hi:[0,1]
	s_mov_b32 s45, s22
	v_pk_mul_f32 v[182:183], v[150:151], s[40:41]
	v_add_u32_e32 v219, 0x18c00, v2
	v_pk_fma_f32 v[150:151], v[150:151], s[38:39], v[182:183] op_sel:[0,0,1] op_sel_hi:[1,0,0]
	s_waitcnt lgkmcnt(2)
	v_pk_add_f32 v[182:183], v[152:153], v[184:185]
	v_pk_add_f32 v[152:153], v[152:153], v[184:185] neg_lo:[0,1] neg_hi:[0,1]
	s_mov_b32 s50, s25
	v_pk_mul_f32 v[184:185], v[152:153], s[42:43]
	v_add_u32_e32 v220, 0x19c80, v2
	v_pk_fma_f32 v[152:153], v[152:153], s[0:1], v[184:185] op_sel:[0,0,1] op_sel_hi:[1,0,0]
	s_waitcnt lgkmcnt(1)
	v_pk_add_f32 v[184:185], v[154:155], v[186:187]
	v_pk_add_f32 v[154:155], v[154:155], v[186:187] neg_lo:[0,1] neg_hi:[0,1]
	v_add_u32_e32 v221, 0x1ad00, v2
	v_pk_mul_f32 v[186:187], v[154:155], s[44:45]
	v_add_u32_e32 v222, 0x1bd80, v2
	ds_read_b64 v[190:191], v219
	ds_read_b64 v[192:193], v220
	ds_read_b64 v[194:195], v221
	ds_read_b64 v[196:197], v222
	v_pk_fma_f32 v[154:155], v[154:155], s[50:51], v[186:187] op_sel:[0,0,1] op_sel_hi:[1,0,0]
	s_waitcnt lgkmcnt(4)
	v_pk_add_f32 v[186:187], v[156:157], v[188:189]
	v_pk_add_f32 v[156:157], v[156:157], v[188:189] neg_lo:[0,1] neg_hi:[0,1]
	v_add_u32_e32 v223, 0x1ce00, v2
	v_pk_mul_f32 v[188:189], v[156:157], s[8:9]
	v_add_u32_e32 v224, 0x1de80, v2
	v_pk_fma_f32 v[156:157], v[156:157], s[16:17], v[188:189] op_sel:[0,0,1] op_sel_hi:[1,0,0]
	s_waitcnt lgkmcnt(3)
	v_pk_add_f32 v[188:189], v[158:159], v[190:191]
	v_pk_add_f32 v[190:191], v[158:159], v[190:191] neg_lo:[0,1] neg_hi:[0,1]
	v_add_u32_e32 v225, 0x1ef00, v2
	s_waitcnt lgkmcnt(2)
	v_pk_add_f32 v[158:159], v[160:161], v[192:193]
	v_pk_add_f32 v[160:161], v[160:161], v[192:193] neg_lo:[0,1] neg_hi:[0,1]
	v_add_u32_e32 v226, 0x1ff80, v2
	v_pk_mul_f32 v[192:193], v[160:161], s[8:9]
	ds_read_b64 v[198:199], v223
	ds_read_b64 v[204:205], v224
	ds_read_b64 v[206:207], v225
	ds_read_b64 v[208:209], v226
	v_pk_fma_f32 v[160:161], v[160:161], s[16:17], v[192:193] op_sel:[0,0,1] op_sel_hi:[1,0,0] neg_lo:[1,0,0] neg_hi:[1,0,0]
	s_waitcnt lgkmcnt(5)
	v_pk_add_f32 v[192:193], v[162:163], v[194:195]
	v_pk_add_f32 v[162:163], v[162:163], v[194:195] neg_lo:[0,1] neg_hi:[0,1]
	v_cvt_f32_u32_e32 v5, v4
	v_pk_mul_f32 v[194:195], v[162:163], s[44:45]
	v_mul_f32_e32 v5, 0x38800000, v5
	v_pk_fma_f32 v[162:163], v[162:163], s[50:51], v[194:195] op_sel:[0,0,1] op_sel_hi:[1,0,0] neg_lo:[1,0,0] neg_hi:[1,0,0]
	s_waitcnt lgkmcnt(4)
	v_pk_add_f32 v[194:195], v[164:165], v[196:197]
	v_pk_add_f32 v[164:165], v[164:165], v[196:197] neg_lo:[0,1] neg_hi:[0,1]
	v_sin_f32_e32 v4, v5
	v_pk_mul_f32 v[196:197], v[164:165], s[42:43]
	v_cos_f32_e32 v6, v5
	v_pk_fma_f32 v[164:165], v[164:165], s[0:1], v[196:197] op_sel:[0,0,1] op_sel_hi:[1,0,0] neg_lo:[1,0,0] neg_hi:[1,0,0]
	s_waitcnt lgkmcnt(3)
	v_pk_add_f32 v[196:197], v[166:167], v[198:199]
	v_pk_add_f32 v[166:167], v[166:167], v[198:199] neg_lo:[0,1] neg_hi:[0,1]
	v_xor_b32_e32 v7, 0x80000000, v4
	v_pk_mul_f32 v[198:199], v[166:167], s[40:41]
	v_mov_b32_e32 v5, v7
	v_pk_fma_f32 v[166:167], v[166:167], s[38:39], v[198:199] op_sel:[0,0,1] op_sel_hi:[1,0,0] neg_lo:[1,0,0] neg_hi:[1,0,0]
	s_waitcnt lgkmcnt(2)
	v_pk_add_f32 v[198:199], v[168:169], v[204:205]
	v_pk_add_f32 v[168:169], v[168:169], v[204:205] neg_lo:[0,1] neg_hi:[0,1]
	v_pk_mul_f32 v[8:9], v[6:7], v[4:5] op_sel:[1,0] op_sel_hi:[0,1]
	v_pk_mul_f32 v[204:205], v[168:169], s[36:37]
	v_pk_fma_f32 v[8:9], v[6:7], v[6:7], v[8:9] op_sel_hi:[1,0,1]
	v_pk_fma_f32 v[168:169], v[168:169], s[26:27], v[204:205] op_sel:[0,0,1] op_sel_hi:[1,0,0] neg_lo:[1,0,0] neg_hi:[1,0,0]
	s_waitcnt lgkmcnt(1)
	v_pk_add_f32 v[204:205], v[170:171], v[206:207]
	v_pk_add_f32 v[170:171], v[170:171], v[206:207] neg_lo:[0,1] neg_hi:[0,1]
	v_pk_mul_f32 v[206:207], v[170:171], s[24:25]
	v_pk_fma_f32 v[170:171], v[170:171], s[22:23], v[206:207] op_sel:[0,0,1] op_sel_hi:[1,0,0] neg_lo:[1,0,0] neg_hi:[1,0,0]
	s_waitcnt lgkmcnt(0)
	v_pk_add_f32 v[206:207], v[172:173], v[208:209]
	v_pk_add_f32 v[172:173], v[172:173], v[208:209] neg_lo:[0,1] neg_hi:[0,1]
	v_pk_mul_f32 v[12:13], v[8:9], v[8:9] op_sel:[1,1] op_sel_hi:[0,1] neg_lo:[0,1]
	v_pk_mul_f32 v[208:209], v[172:173], s[20:21]
	v_pk_fma_f32 v[12:13], v[8:9], v[8:9], v[12:13] op_sel_hi:[1,0,1]
	v_pk_fma_f32 v[172:173], v[172:173], s[10:11], v[208:209] op_sel:[0,0,1] op_sel_hi:[1,0,0] neg_lo:[1,0,0] neg_hi:[1,0,0]
	v_pk_add_f32 v[208:209], v[210:211], v[188:189]
	v_pk_add_f32 v[188:189], v[210:211], v[188:189] neg_lo:[0,1] neg_hi:[0,1]
	v_pk_add_f32 v[210:211], v[174:175], v[158:159]
	v_pk_add_f32 v[158:159], v[174:175], v[158:159] neg_lo:[0,1] neg_hi:[0,1]
	v_pk_mul_f32 v[174:175], v[158:159], s[24:25]
	v_pk_fma_f32 v[158:159], v[158:159], s[22:23], v[174:175] op_sel:[0,0,1] op_sel_hi:[1,0,0]
	v_pk_add_f32 v[174:175], v[176:177], v[192:193]
	v_pk_add_f32 v[176:177], v[176:177], v[192:193] neg_lo:[0,1] neg_hi:[0,1]
	v_pk_mul_f32 v[28:29], v[12:13], v[12:13] op_sel:[1,1] op_sel_hi:[0,1] neg_lo:[0,1]
	v_pk_mul_f32 v[192:193], v[176:177], s[40:41]
	v_pk_fma_f32 v[28:29], v[12:13], v[12:13], v[28:29] op_sel_hi:[1,0,1]
	v_pk_fma_f32 v[176:177], v[176:177], s[38:39], v[192:193] op_sel:[0,0,1] op_sel_hi:[1,0,0]
	v_pk_add_f32 v[192:193], v[178:179], v[194:195]
	v_pk_add_f32 v[178:179], v[178:179], v[194:195] neg_lo:[0,1] neg_hi:[0,1]
	v_pk_mul_f32 v[44:45], v[12:13], v[28:29] op_sel:[1,1] op_sel_hi:[1,0] neg_lo:[1,0]
	v_pk_mul_f32 v[194:195], v[178:179], s[44:45]
	v_pk_fma_f32 v[44:45], v[12:13], v[28:29], v[44:45] op_sel_hi:[0,1,1]
	v_pk_fma_f32 v[178:179], v[178:179], s[50:51], v[194:195] op_sel:[0,0,1] op_sel_hi:[1,0,0]
	v_pk_add_f32 v[194:195], v[180:181], v[196:197]
	v_pk_add_f32 v[196:197], v[180:181], v[196:197] neg_lo:[0,1] neg_hi:[0,1]
	v_pk_mul_f32 v[60:61], v[12:13], v[44:45] op_sel:[1,1] op_sel_hi:[1,0] neg_lo:[1,0]
	v_pk_add_f32 v[180:181], v[182:183], v[198:199]
	v_pk_add_f32 v[182:183], v[182:183], v[198:199] neg_lo:[0,1] neg_hi:[0,1]
	v_pk_fma_f32 v[60:61], v[12:13], v[44:45], v[60:61] op_sel_hi:[0,1,1]
	v_pk_mul_f32 v[198:199], v[182:183], s[44:45]
	v_pk_mul_f32 v[76:77], v[12:13], v[60:61] op_sel:[1,1] op_sel_hi:[1,0] neg_lo:[1,0]
	v_pk_fma_f32 v[182:183], v[182:183], s[50:51], v[198:199] op_sel:[0,0,1] op_sel_hi:[1,0,0] neg_lo:[1,0,0] neg_hi:[1,0,0]
	v_pk_add_f32 v[198:199], v[184:185], v[204:205]
	v_pk_add_f32 v[184:185], v[184:185], v[204:205] neg_lo:[0,1] neg_hi:[0,1]
	v_pk_fma_f32 v[76:77], v[12:13], v[60:61], v[76:77] op_sel_hi:[0,1,1]
	v_pk_mul_f32 v[204:205], v[184:185], s[40:41]
	v_pk_mul_f32 v[92:93], v[12:13], v[76:77] op_sel:[1,1] op_sel_hi:[1,0] neg_lo:[1,0]
	v_pk_fma_f32 v[184:185], v[184:185], s[38:39], v[204:205] op_sel:[0,0,1] op_sel_hi:[1,0,0] neg_lo:[1,0,0] neg_hi:[1,0,0]
	v_pk_add_f32 v[204:205], v[186:187], v[206:207]
	v_pk_add_f32 v[186:187], v[186:187], v[206:207] neg_lo:[0,1] neg_hi:[0,1]
	v_pk_fma_f32 v[92:93], v[12:13], v[76:77], v[92:93] op_sel_hi:[0,1,1]
	v_pk_mul_f32 v[206:207], v[186:187], s[24:25]
	v_pk_mul_f32 v[108:109], v[12:13], v[92:93] op_sel:[1,1] op_sel_hi:[1,0] neg_lo:[1,0]
	v_pk_fma_f32 v[186:187], v[186:187], s[22:23], v[206:207] op_sel:[0,0,1] op_sel_hi:[1,0,0] neg_lo:[1,0,0] neg_hi:[1,0,0]
	v_pk_add_f32 v[206:207], v[128:129], v[190:191] op_sel:[0,1] op_sel_hi:[1,0] neg_hi:[0,1]
	v_pk_add_f32 v[128:129], v[128:129], v[190:191] op_sel:[0,1] op_sel_hi:[1,0] neg_lo:[0,1]
	v_pk_add_f32 v[190:191], v[130:131], v[160:161]
	v_pk_add_f32 v[130:131], v[130:131], v[160:161] neg_lo:[0,1] neg_hi:[0,1]
	v_pk_mul_f32 v[10:11], v[4:5], v[8:9] op_sel:[0,1] op_sel_hi:[1,0]
	v_pk_mul_f32 v[160:161], v[130:131], s[24:25]
	v_pk_fma_f32 v[108:109], v[12:13], v[92:93], v[108:109] op_sel_hi:[0,1,1]
	v_pk_fma_f32 v[130:131], v[130:131], s[22:23], v[160:161] op_sel:[0,0,1] op_sel_hi:[1,0,0]
	v_pk_add_f32 v[160:161], v[144:145], v[162:163]
	v_pk_add_f32 v[144:145], v[144:145], v[162:163] neg_lo:[0,1] neg_hi:[0,1]
	v_pk_fma_f32 v[10:11], v[6:7], v[8:9], v[10:11] op_sel_hi:[0,1,1]
	v_pk_mul_f32 v[162:163], v[144:145], s[40:41]
	v_pk_mul_f32 v[18:19], v[4:5], v[12:13] op_sel:[0,1] op_sel_hi:[1,0]
	v_pk_fma_f32 v[144:145], v[144:145], s[38:39], v[162:163] op_sel:[0,0,1] op_sel_hi:[1,0,0]
	v_pk_add_f32 v[162:163], v[148:149], v[164:165]
	v_pk_add_f32 v[148:149], v[148:149], v[164:165] neg_lo:[0,1] neg_hi:[0,1]
	v_pk_mul_f32 v[32:33], v[4:5], v[28:29] op_sel:[0,1] op_sel_hi:[1,0]
	v_pk_mul_f32 v[164:165], v[148:149], s[44:45]
	v_pk_mul_f32 v[48:49], v[4:5], v[44:45] op_sel:[0,1] op_sel_hi:[1,0]
	v_pk_fma_f32 v[148:149], v[148:149], s[50:51], v[164:165] op_sel:[0,0,1] op_sel_hi:[1,0,0]
	v_pk_add_f32 v[164:165], v[150:151], v[166:167]
	v_pk_add_f32 v[166:167], v[150:151], v[166:167] neg_lo:[0,1] neg_hi:[0,1]
	v_pk_mul_f32 v[64:65], v[4:5], v[60:61] op_sel:[0,1] op_sel_hi:[1,0]
	v_pk_add_f32 v[150:151], v[152:153], v[168:169]
	v_pk_add_f32 v[152:153], v[152:153], v[168:169] neg_lo:[0,1] neg_hi:[0,1]
	v_pk_mul_f32 v[80:81], v[4:5], v[76:77] op_sel:[0,1] op_sel_hi:[1,0]
	v_pk_mul_f32 v[168:169], v[152:153], s[44:45]
	v_pk_mul_f32 v[96:97], v[4:5], v[92:93] op_sel:[0,1] op_sel_hi:[1,0]
	v_pk_fma_f32 v[152:153], v[152:153], s[50:51], v[168:169] op_sel:[0,0,1] op_sel_hi:[1,0,0] neg_lo:[1,0,0] neg_hi:[1,0,0]
	v_pk_add_f32 v[168:169], v[154:155], v[170:171]
	v_pk_add_f32 v[154:155], v[154:155], v[170:171] neg_lo:[0,1] neg_hi:[0,1]
	v_pk_mul_f32 v[112:113], v[4:5], v[108:109] op_sel:[0,1] op_sel_hi:[1,0]
	v_pk_mul_f32 v[170:171], v[154:155], s[40:41]
	v_pk_fma_f32 v[154:155], v[154:155], s[38:39], v[170:171] op_sel:[0,0,1] op_sel_hi:[1,0,0] neg_lo:[1,0,0] neg_hi:[1,0,0]
	v_pk_add_f32 v[170:171], v[156:157], v[172:173]
	v_pk_add_f32 v[156:157], v[156:157], v[172:173] neg_lo:[0,1] neg_hi:[0,1]
	v_pk_mul_f32 v[172:173], v[156:157], s[24:25]
	v_pk_fma_f32 v[18:19], v[6:7], v[12:13], v[18:19] op_sel_hi:[0,1,1]
	v_pk_fma_f32 v[156:157], v[156:157], s[22:23], v[172:173] op_sel:[0,0,1] op_sel_hi:[1,0,0] neg_lo:[1,0,0] neg_hi:[1,0,0]
	v_pk_add_f32 v[172:173], v[208:209], v[194:195]
	v_pk_add_f32 v[194:195], v[208:209], v[194:195] neg_lo:[0,1] neg_hi:[0,1]
	v_pk_add_f32 v[208:209], v[210:211], v[180:181]
	v_pk_add_f32 v[180:181], v[210:211], v[180:181] neg_lo:[0,1] neg_hi:[0,1]
	v_pk_mul_f32 v[20:21], v[8:9], v[12:13] op_sel:[1,1] op_sel_hi:[1,0] neg_lo:[1,0]
	v_pk_mul_f32 v[210:211], v[180:181], s[40:41]
	v_pk_fma_f32 v[32:33], v[6:7], v[28:29], v[32:33] op_sel_hi:[0,1,1]
	v_pk_fma_f32 v[180:181], v[180:181], s[38:39], v[210:211] op_sel:[0,0,1] op_sel_hi:[1,0,0]
	v_pk_add_f32 v[210:211], v[174:175], v[198:199]
	v_pk_add_f32 v[198:199], v[174:175], v[198:199] neg_lo:[0,1] neg_hi:[0,1]
	v_pk_mul_f32 v[36:37], v[8:9], v[28:29] op_sel:[1,1] op_sel_hi:[1,0] neg_lo:[1,0]
	v_pk_add_f32 v[174:175], v[192:193], v[204:205]
	v_pk_add_f32 v[192:193], v[192:193], v[204:205] neg_lo:[0,1] neg_hi:[0,1]
	v_pk_fma_f32 v[48:49], v[6:7], v[44:45], v[48:49] op_sel_hi:[0,1,1]
	v_pk_mul_f32 v[204:205], v[192:193], s[40:41]
	v_pk_mul_f32 v[52:53], v[8:9], v[44:45] op_sel:[1,1] op_sel_hi:[1,0] neg_lo:[1,0]
	v_pk_fma_f32 v[192:193], v[192:193], s[38:39], v[204:205] op_sel:[0,0,1] op_sel_hi:[1,0,0] neg_lo:[1,0,0] neg_hi:[1,0,0]
	v_pk_add_f32 v[204:205], v[188:189], v[196:197] op_sel:[0,1] op_sel_hi:[1,0] neg_hi:[0,1]
	v_pk_add_f32 v[188:189], v[188:189], v[196:197] op_sel:[0,1] op_sel_hi:[1,0] neg_lo:[0,1]
	v_pk_add_f32 v[196:197], v[158:159], v[182:183]
	v_pk_add_f32 v[158:159], v[158:159], v[182:183] neg_lo:[0,1] neg_hi:[0,1]
	v_pk_fma_f32 v[64:65], v[6:7], v[60:61], v[64:65] op_sel_hi:[0,1,1]
	v_pk_mul_f32 v[182:183], v[158:159], s[40:41]
	v_pk_mul_f32 v[68:69], v[8:9], v[60:61] op_sel:[1,1] op_sel_hi:[1,0] neg_lo:[1,0]
	v_pk_fma_f32 v[158:159], v[158:159], s[38:39], v[182:183] op_sel:[0,0,1] op_sel_hi:[1,0,0]
	v_pk_add_f32 v[182:183], v[176:177], v[184:185]
	v_pk_add_f32 v[184:185], v[176:177], v[184:185] neg_lo:[0,1] neg_hi:[0,1]
	v_pk_fma_f32 v[80:81], v[6:7], v[76:77], v[80:81] op_sel_hi:[0,1,1]
	v_pk_add_f32 v[176:177], v[178:179], v[186:187]
	v_pk_add_f32 v[178:179], v[178:179], v[186:187] neg_lo:[0,1] neg_hi:[0,1]
	v_pk_mul_f32 v[84:85], v[8:9], v[76:77] op_sel:[1,1] op_sel_hi:[1,0] neg_lo:[1,0]
	v_pk_mul_f32 v[186:187], v[178:179], s[40:41]
	v_pk_fma_f32 v[96:97], v[6:7], v[92:93], v[96:97] op_sel_hi:[0,1,1]
	v_pk_fma_f32 v[178:179], v[178:179], s[38:39], v[186:187] op_sel:[0,0,1] op_sel_hi:[1,0,0] neg_lo:[1,0,0] neg_hi:[1,0,0]
	v_pk_add_f32 v[186:187], v[206:207], v[164:165]
	v_pk_add_f32 v[164:165], v[206:207], v[164:165] neg_lo:[0,1] neg_hi:[0,1]
	v_pk_add_f32 v[206:207], v[190:191], v[150:151]
	v_pk_add_f32 v[150:151], v[190:191], v[150:151] neg_lo:[0,1] neg_hi:[0,1]
	v_pk_mul_f32 v[100:101], v[8:9], v[92:93] op_sel:[1,1] op_sel_hi:[1,0] neg_lo:[1,0]
	v_pk_mul_f32 v[190:191], v[150:151], s[40:41]
	v_pk_fma_f32 v[112:113], v[6:7], v[108:109], v[112:113] op_sel_hi:[0,1,1]
	v_pk_fma_f32 v[150:151], v[150:151], s[38:39], v[190:191] op_sel:[0,0,1] op_sel_hi:[1,0,0]
	v_pk_add_f32 v[190:191], v[160:161], v[168:169]
	v_pk_add_f32 v[168:169], v[160:161], v[168:169] neg_lo:[0,1] neg_hi:[0,1]
	v_pk_mul_f32 v[116:117], v[8:9], v[108:109] op_sel:[1,1] op_sel_hi:[1,0] neg_lo:[1,0]
	v_pk_add_f32 v[160:161], v[162:163], v[170:171]
	v_pk_add_f32 v[162:163], v[162:163], v[170:171] neg_lo:[0,1] neg_hi:[0,1]
	v_pk_fma_f32 v[20:21], v[8:9], v[12:13], v[20:21] op_sel_hi:[0,1,1]
	v_pk_mul_f32 v[170:171], v[162:163], s[40:41]
	v_pk_mul_f32 v[24:25], v[12:13], v[10:11] op_sel:[1,1] op_sel_hi:[0,1] neg_lo:[0,1]
	v_pk_fma_f32 v[162:163], v[162:163], s[38:39], v[170:171] op_sel:[0,0,1] op_sel_hi:[1,0,0] neg_lo:[1,0,0] neg_hi:[1,0,0]
	v_pk_add_f32 v[170:171], v[128:129], v[166:167] op_sel:[0,1] op_sel_hi:[1,0] neg_hi:[0,1]
	v_pk_add_f32 v[128:129], v[128:129], v[166:167] op_sel:[0,1] op_sel_hi:[1,0] neg_lo:[0,1]
	v_pk_add_f32 v[166:167], v[130:131], v[152:153]
	v_pk_add_f32 v[130:131], v[130:131], v[152:153] neg_lo:[0,1] neg_hi:[0,1]
	v_pk_fma_f32 v[36:37], v[8:9], v[28:29], v[36:37] op_sel_hi:[0,1,1]
	v_pk_mul_f32 v[152:153], v[130:131], s[40:41]
	v_pk_mul_f32 v[40:41], v[10:11], v[28:29] op_sel:[1,1] op_sel_hi:[1,0] neg_lo:[1,0]
	v_pk_fma_f32 v[130:131], v[130:131], s[38:39], v[152:153] op_sel:[0,0,1] op_sel_hi:[1,0,0]
	v_pk_add_f32 v[152:153], v[144:145], v[154:155]
	v_pk_add_f32 v[154:155], v[144:145], v[154:155] neg_lo:[0,1] neg_hi:[0,1]
	v_pk_fma_f32 v[52:53], v[8:9], v[44:45], v[52:53] op_sel_hi:[0,1,1]
	v_pk_add_f32 v[144:145], v[148:149], v[156:157]
	v_pk_add_f32 v[148:149], v[148:149], v[156:157] neg_lo:[0,1] neg_hi:[0,1]
	v_pk_mul_f32 v[56:57], v[10:11], v[44:45] op_sel:[1,1] op_sel_hi:[1,0] neg_lo:[1,0]
	v_pk_mul_f32 v[156:157], v[148:149], s[40:41]
	v_pk_fma_f32 v[68:69], v[8:9], v[60:61], v[68:69] op_sel_hi:[0,1,1]
	v_pk_fma_f32 v[148:149], v[148:149], s[38:39], v[156:157] op_sel:[0,0,1] op_sel_hi:[1,0,0] neg_lo:[1,0,0] neg_hi:[1,0,0]
	v_pk_add_f32 v[156:157], v[172:173], v[210:211]
	v_pk_add_f32 v[172:173], v[172:173], v[210:211] neg_lo:[0,1] neg_hi:[0,1]
	v_pk_add_f32 v[210:211], v[208:209], v[174:175]
	v_pk_add_f32 v[208:209], v[208:209], v[174:175] neg_lo:[0,1] neg_hi:[0,1]
	v_pk_mul_f32 v[72:73], v[10:11], v[60:61] op_sel:[1,1] op_sel_hi:[1,0] neg_lo:[1,0]
	v_pk_add_f32 v[174:175], v[194:195], v[198:199] op_sel:[0,1] op_sel_hi:[1,0] neg_hi:[0,1]
	v_pk_add_f32 v[194:195], v[194:195], v[198:199] op_sel:[0,1] op_sel_hi:[1,0] neg_lo:[0,1]
	v_pk_add_f32 v[198:199], v[180:181], v[192:193]
	v_pk_add_f32 v[192:193], v[180:181], v[192:193] neg_lo:[0,1] neg_hi:[0,1]
	v_pk_fma_f32 v[84:85], v[8:9], v[76:77], v[84:85] op_sel_hi:[0,1,1]
	v_pk_add_f32 v[180:181], v[204:205], v[182:183]
	v_pk_add_f32 v[182:183], v[204:205], v[182:183] neg_lo:[0,1] neg_hi:[0,1]
	v_pk_add_f32 v[204:205], v[196:197], v[176:177]
	v_pk_add_f32 v[196:197], v[196:197], v[176:177] neg_lo:[0,1] neg_hi:[0,1]
	v_pk_mul_f32 v[88:89], v[10:11], v[76:77] op_sel:[1,1] op_sel_hi:[1,0] neg_lo:[1,0]
	v_pk_add_f32 v[176:177], v[188:189], v[184:185] op_sel:[0,1] op_sel_hi:[1,0] neg_hi:[0,1]
	v_pk_add_f32 v[184:185], v[188:189], v[184:185] op_sel:[0,1] op_sel_hi:[1,0] neg_lo:[0,1]
	v_pk_add_f32 v[188:189], v[158:159], v[178:179]
	v_pk_add_f32 v[178:179], v[158:159], v[178:179] neg_lo:[0,1] neg_hi:[0,1]
	v_pk_fma_f32 v[100:101], v[8:9], v[92:93], v[100:101] op_sel_hi:[0,1,1]
	v_pk_add_f32 v[158:159], v[186:187], v[190:191]
	v_pk_add_f32 v[186:187], v[186:187], v[190:191] neg_lo:[0,1] neg_hi:[0,1]
	v_pk_add_f32 v[190:191], v[206:207], v[160:161]
	v_pk_add_f32 v[206:207], v[206:207], v[160:161] neg_lo:[0,1] neg_hi:[0,1]
	v_pk_mul_f32 v[104:105], v[10:11], v[92:93] op_sel:[1,1] op_sel_hi:[1,0] neg_lo:[1,0]
	v_pk_add_f32 v[160:161], v[164:165], v[168:169] op_sel:[0,1] op_sel_hi:[1,0] neg_hi:[0,1]
	v_pk_add_f32 v[164:165], v[164:165], v[168:169] op_sel:[0,1] op_sel_hi:[1,0] neg_lo:[0,1]
	v_pk_add_f32 v[168:169], v[150:151], v[162:163]
	v_pk_add_f32 v[162:163], v[150:151], v[162:163] neg_lo:[0,1] neg_hi:[0,1]
	v_pk_fma_f32 v[116:117], v[8:9], v[108:109], v[116:117] op_sel_hi:[0,1,1]
	v_pk_add_f32 v[150:151], v[170:171], v[152:153]
	v_pk_add_f32 v[152:153], v[170:171], v[152:153] neg_lo:[0,1] neg_hi:[0,1]
	v_pk_add_f32 v[170:171], v[166:167], v[144:145]
	v_pk_add_f32 v[166:167], v[166:167], v[144:145] neg_lo:[0,1] neg_hi:[0,1]
	v_pk_mul_f32 v[120:121], v[10:11], v[108:109] op_sel:[1,1] op_sel_hi:[1,0] neg_lo:[1,0]
	v_pk_add_f32 v[144:145], v[128:129], v[154:155] op_sel:[0,1] op_sel_hi:[1,0] neg_hi:[0,1]
	v_pk_add_f32 v[128:129], v[128:129], v[154:155] op_sel:[0,1] op_sel_hi:[1,0] neg_lo:[0,1]
	v_pk_add_f32 v[154:155], v[130:131], v[148:149]
	v_pk_add_f32 v[148:149], v[130:131], v[148:149] neg_lo:[0,1] neg_hi:[0,1]
	v_xor_b32_e32 v26, 0x80000000, v19
	v_pk_add_f32 v[130:131], v[156:157], v[210:211]
	v_pk_add_f32 v[156:157], v[156:157], v[210:211] neg_lo:[0,1] neg_hi:[0,1]
	v_pk_add_f32 v[210:211], v[172:173], v[208:209] op_sel:[0,1] op_sel_hi:[1,0] neg_hi:[0,1]
	v_pk_add_f32 v[172:173], v[172:173], v[208:209] op_sel:[0,1] op_sel_hi:[1,0] neg_lo:[0,1]
	v_pk_add_f32 v[208:209], v[174:175], v[198:199]
	v_pk_add_f32 v[174:175], v[174:175], v[198:199] neg_lo:[0,1] neg_hi:[0,1]
	v_pk_add_f32 v[198:199], v[194:195], v[192:193] op_sel:[0,1] op_sel_hi:[1,0] neg_hi:[0,1]
	v_pk_add_f32 v[192:193], v[194:195], v[192:193] op_sel:[0,1] op_sel_hi:[1,0] neg_lo:[0,1]
	v_pk_add_f32 v[194:195], v[180:181], v[204:205]
	v_pk_add_f32 v[180:181], v[180:181], v[204:205] neg_lo:[0,1] neg_hi:[0,1]
	v_pk_add_f32 v[204:205], v[182:183], v[196:197] op_sel:[0,1] op_sel_hi:[1,0] neg_hi:[0,1]
	v_pk_add_f32 v[182:183], v[182:183], v[196:197] op_sel:[0,1] op_sel_hi:[1,0] neg_lo:[0,1]
	v_pk_add_f32 v[196:197], v[176:177], v[188:189]
	v_pk_add_f32 v[176:177], v[176:177], v[188:189] neg_lo:[0,1] neg_hi:[0,1]
	v_pk_add_f32 v[188:189], v[184:185], v[178:179] op_sel:[0,1] op_sel_hi:[1,0] neg_hi:[0,1]
	v_pk_add_f32 v[178:179], v[184:185], v[178:179] op_sel:[0,1] op_sel_hi:[1,0] neg_lo:[0,1]
	v_pk_add_f32 v[184:185], v[158:159], v[190:191]
	v_pk_add_f32 v[158:159], v[158:159], v[190:191] neg_lo:[0,1] neg_hi:[0,1]
	v_pk_mul_f32 v[4:5], v[4:5], v[184:185] op_sel:[0,1] op_sel_hi:[1,0]
	v_pk_add_f32 v[190:191], v[186:187], v[206:207] op_sel:[0,1] op_sel_hi:[1,0] neg_hi:[0,1]
	v_pk_add_f32 v[186:187], v[186:187], v[206:207] op_sel:[0,1] op_sel_hi:[1,0] neg_lo:[0,1]
	v_pk_add_f32 v[206:207], v[160:161], v[168:169]
	v_pk_add_f32 v[160:161], v[160:161], v[168:169] neg_lo:[0,1] neg_hi:[0,1]
	v_pk_add_f32 v[168:169], v[164:165], v[162:163] op_sel:[0,1] op_sel_hi:[1,0] neg_hi:[0,1]
	v_pk_add_f32 v[162:163], v[164:165], v[162:163] op_sel:[0,1] op_sel_hi:[1,0] neg_lo:[0,1]
	v_pk_add_f32 v[164:165], v[150:151], v[170:171]
	v_pk_fma_f32 v[4:5], v[6:7], v[184:185], v[4:5] op_sel_hi:[0,1,1]
	v_pk_mul_f32 v[6:7], v[8:9], v[194:195] op_sel:[1,1] op_sel_hi:[1,0] neg_lo:[1,0]
	v_xor_b32_e32 v30, 0x80000000, v21
	v_pk_fma_f32 v[6:7], v[8:9], v[194:195], v[6:7] op_sel_hi:[0,1,1]
	v_pk_mul_f32 v[8:9], v[10:11], v[164:165] op_sel:[1,1] op_sel_hi:[1,0] neg_lo:[1,0]
	v_pk_fma_f32 v[24:25], v[12:13], v[10:11], v[24:25] op_sel_hi:[1,0,1]
	v_pk_fma_f32 v[40:41], v[10:11], v[28:29], v[40:41] op_sel_hi:[0,1,1]
	v_pk_fma_f32 v[56:57], v[10:11], v[44:45], v[56:57] op_sel_hi:[0,1,1]
	v_pk_fma_f32 v[72:73], v[10:11], v[60:61], v[72:73] op_sel_hi:[0,1,1]
	v_pk_fma_f32 v[88:89], v[10:11], v[76:77], v[88:89] op_sel_hi:[0,1,1]
	v_pk_fma_f32 v[104:105], v[10:11], v[92:93], v[104:105] op_sel_hi:[0,1,1]
	v_pk_fma_f32 v[120:121], v[10:11], v[108:109], v[120:121] op_sel_hi:[0,1,1]
	v_mov_b32_e32 v27, v19
	v_mov_b32_e32 v31, v21
	v_pk_fma_f32 v[8:9], v[10:11], v[164:165], v[8:9] op_sel_hi:[0,1,1]
	v_pk_mul_f32 v[10:11], v[12:13], v[208:209] op_sel:[1,1] op_sel_hi:[1,0] neg_lo:[1,0]
	v_pk_add_f32 v[150:151], v[150:151], v[170:171] neg_lo:[0,1] neg_hi:[0,1]
	v_pk_add_f32 v[170:171], v[152:153], v[166:167] op_sel:[0,1] op_sel_hi:[1,0] neg_hi:[0,1]
	v_pk_add_f32 v[152:153], v[152:153], v[166:167] op_sel:[0,1] op_sel_hi:[1,0] neg_lo:[0,1]
	v_pk_add_f32 v[166:167], v[144:145], v[154:155]
	v_pk_fma_f32 v[10:11], v[12:13], v[208:209], v[10:11] op_sel_hi:[0,1,1]
	v_pk_mul_f32 v[12:13], v[26:27], v[206:207] op_sel:[0,1] op_sel_hi:[1,0]
	v_pk_mul_f32 v[14:15], v[30:31], v[196:197] op_sel:[0,1] op_sel_hi:[1,0]
	v_pk_add_f32 v[144:145], v[144:145], v[154:155] neg_lo:[0,1] neg_hi:[0,1]
	v_pk_add_f32 v[154:155], v[128:129], v[148:149] op_sel:[0,1] op_sel_hi:[1,0] neg_hi:[0,1]
	v_pk_fma_f32 v[12:13], v[18:19], v[206:207], v[12:13] op_sel_hi:[0,1,1]
	v_pk_fma_f32 v[14:15], v[20:21], v[196:197], v[14:15] op_sel_hi:[0,1,1]
	v_pk_mul_f32 v[16:17], v[24:25], v[166:167] op_sel:[1,1] op_sel_hi:[1,0] neg_lo:[1,0]
	v_pk_mul_f32 v[18:19], v[28:29], v[210:211] op_sel:[1,1] op_sel_hi:[1,0] neg_lo:[1,0]
	v_pk_mul_f32 v[20:21], v[32:33], v[190:191] op_sel:[1,1] op_sel_hi:[1,0] neg_lo:[1,0]
	v_pk_mul_f32 v[22:23], v[36:37], v[204:205] op_sel:[1,1] op_sel_hi:[1,0] neg_lo:[1,0]
	v_xor_b32_e32 v78, 0x80000000, v69
	v_xor_b32_e32 v82, 0x80000000, v73
	v_xor_b32_e32 v86, 0x80000000, v77
	v_xor_b32_e32 v90, 0x80000000, v81
	v_xor_b32_e32 v94, 0x80000000, v85
	v_xor_b32_e32 v98, 0x80000000, v89
	v_xor_b32_e32 v102, 0x80000000, v93
	v_xor_b32_e32 v106, 0x80000000, v97
	v_xor_b32_e32 v110, 0x80000000, v101
	v_xor_b32_e32 v114, 0x80000000, v105
	v_xor_b32_e32 v118, 0x80000000, v109
	v_xor_b32_e32 v122, 0x80000000, v113
	v_xor_b32_e32 v124, 0x80000000, v117
	v_xor_b32_e32 v126, 0x80000000, v121
	v_mov_b32_e32 v79, v69
	v_mov_b32_e32 v83, v73
	v_mov_b32_e32 v87, v77
	v_mov_b32_e32 v91, v81
	v_mov_b32_e32 v95, v85
	v_mov_b32_e32 v99, v89
	v_mov_b32_e32 v103, v93
	v_mov_b32_e32 v107, v97
	v_mov_b32_e32 v111, v101
	v_mov_b32_e32 v115, v105
	v_mov_b32_e32 v119, v109
	v_mov_b32_e32 v123, v113
	v_mov_b32_e32 v125, v117
	v_mov_b32_e32 v127, v121
	v_pk_add_f32 v[128:129], v[128:129], v[148:149] op_sel:[0,1] op_sel_hi:[1,0] neg_lo:[0,1]
	v_pk_fma_f32 v[16:17], v[24:25], v[166:167], v[16:17] op_sel_hi:[0,1,1]
	v_pk_fma_f32 v[18:19], v[28:29], v[210:211], v[18:19] op_sel_hi:[0,1,1]
	v_pk_fma_f32 v[20:21], v[32:33], v[190:191], v[20:21] op_sel_hi:[0,1,1]
	v_pk_fma_f32 v[22:23], v[36:37], v[204:205], v[22:23] op_sel_hi:[0,1,1]
	v_pk_mul_f32 v[24:25], v[40:41], v[170:171] op_sel:[1,1] op_sel_hi:[1,0] neg_lo:[1,0]
	v_pk_mul_f32 v[26:27], v[44:45], v[198:199] op_sel:[1,1] op_sel_hi:[1,0] neg_lo:[1,0]
	v_pk_mul_f32 v[28:29], v[48:49], v[168:169] op_sel:[1,1] op_sel_hi:[1,0] neg_lo:[1,0]
	v_pk_mul_f32 v[30:31], v[52:53], v[188:189] op_sel:[1,1] op_sel_hi:[1,0] neg_lo:[1,0]
	v_pk_mul_f32 v[32:33], v[56:57], v[154:155] op_sel:[1,1] op_sel_hi:[1,0] neg_lo:[1,0]
	v_pk_mul_f32 v[34:35], v[60:61], v[156:157] op_sel:[1,1] op_sel_hi:[1,0] neg_lo:[1,0]
	v_pk_mul_f32 v[36:37], v[64:65], v[158:159] op_sel:[1,1] op_sel_hi:[1,0] neg_lo:[1,0]
	v_pk_fma_f32 v[24:25], v[40:41], v[170:171], v[24:25] op_sel_hi:[0,1,1]
	v_pk_fma_f32 v[26:27], v[44:45], v[198:199], v[26:27] op_sel_hi:[0,1,1]
	v_pk_fma_f32 v[28:29], v[48:49], v[168:169], v[28:29] op_sel_hi:[0,1,1]
	v_pk_fma_f32 v[30:31], v[52:53], v[188:189], v[30:31] op_sel_hi:[0,1,1]
	v_pk_fma_f32 v[32:33], v[56:57], v[154:155], v[32:33] op_sel_hi:[0,1,1]
	v_pk_fma_f32 v[34:35], v[60:61], v[156:157], v[34:35] op_sel_hi:[0,1,1]
	v_pk_fma_f32 v[36:37], v[64:65], v[158:159], v[36:37] op_sel_hi:[0,1,1]
	v_pk_mul_f32 v[38:39], v[78:79], v[180:181] op_sel:[0,1] op_sel_hi:[1,0]
	v_pk_mul_f32 v[40:41], v[82:83], v[150:151] op_sel:[0,1] op_sel_hi:[1,0]
	v_pk_mul_f32 v[42:43], v[86:87], v[174:175] op_sel:[0,1] op_sel_hi:[1,0]
	v_pk_mul_f32 v[44:45], v[90:91], v[160:161] op_sel:[0,1] op_sel_hi:[1,0]
	v_pk_mul_f32 v[46:47], v[94:95], v[176:177] op_sel:[0,1] op_sel_hi:[1,0]
	v_pk_mul_f32 v[48:49], v[98:99], v[144:145] op_sel:[0,1] op_sel_hi:[1,0]
	v_pk_mul_f32 v[50:51], v[102:103], v[172:173] op_sel:[0,1] op_sel_hi:[1,0]
	v_pk_mul_f32 v[52:53], v[106:107], v[186:187] op_sel:[0,1] op_sel_hi:[1,0]
	v_pk_mul_f32 v[54:55], v[110:111], v[182:183] op_sel:[0,1] op_sel_hi:[1,0]
	v_pk_mul_f32 v[56:57], v[114:115], v[152:153] op_sel:[0,1] op_sel_hi:[1,0]
	v_pk_mul_f32 v[58:59], v[118:119], v[192:193] op_sel:[0,1] op_sel_hi:[1,0]
	v_pk_mul_f32 v[60:61], v[122:123], v[162:163] op_sel:[0,1] op_sel_hi:[1,0]
	v_pk_mul_f32 v[62:63], v[124:125], v[178:179] op_sel:[0,1] op_sel_hi:[1,0]
	v_pk_mul_f32 v[64:65], v[126:127], v[128:129] op_sel:[0,1] op_sel_hi:[1,0]
	v_pk_fma_f32 v[38:39], v[68:69], v[180:181], v[38:39] op_sel_hi:[0,1,1]
	v_pk_fma_f32 v[40:41], v[72:73], v[150:151], v[40:41] op_sel_hi:[0,1,1]
	v_pk_fma_f32 v[42:43], v[76:77], v[174:175], v[42:43] op_sel_hi:[0,1,1]
	v_pk_fma_f32 v[44:45], v[80:81], v[160:161], v[44:45] op_sel_hi:[0,1,1]
	v_pk_fma_f32 v[46:47], v[84:85], v[176:177], v[46:47] op_sel_hi:[0,1,1]
	v_pk_fma_f32 v[48:49], v[88:89], v[144:145], v[48:49] op_sel_hi:[0,1,1]
	v_pk_fma_f32 v[50:51], v[92:93], v[172:173], v[50:51] op_sel_hi:[0,1,1]
	v_pk_fma_f32 v[52:53], v[96:97], v[186:187], v[52:53] op_sel_hi:[0,1,1]
	v_pk_fma_f32 v[54:55], v[100:101], v[182:183], v[54:55] op_sel_hi:[0,1,1]
	v_pk_fma_f32 v[56:57], v[104:105], v[152:153], v[56:57] op_sel_hi:[0,1,1]
	v_pk_fma_f32 v[58:59], v[108:109], v[192:193], v[58:59] op_sel_hi:[0,1,1]
	v_pk_fma_f32 v[60:61], v[112:113], v[162:163], v[60:61] op_sel_hi:[0,1,1]
	v_pk_fma_f32 v[62:63], v[116:117], v[178:179], v[62:63] op_sel_hi:[0,1,1]
	v_pk_fma_f32 v[64:65], v[120:121], v[128:129], v[64:65] op_sel_hi:[0,1,1]
	ds_write_b64 v2, v[130:131]
	ds_write_b64 v2, v[34:35] offset:4224
	ds_write_b64 v2, v[18:19] offset:8448
	ds_write_b64 v2, v[50:51] offset:12672
	ds_write_b64 v2, v[10:11] offset:16896
	ds_write_b64 v2, v[42:43] offset:21120
	ds_write_b64 v2, v[26:27] offset:25344
	ds_write_b64 v2, v[58:59] offset:29568
	ds_write_b64 v2, v[6:7] offset:33792
	ds_write_b64 v2, v[38:39] offset:38016
	ds_write_b64 v2, v[22:23] offset:42240
	ds_write_b64 v2, v[54:55] offset:46464
	ds_write_b64 v2, v[14:15] offset:50688
	ds_write_b64 v2, v[46:47] offset:54912
	ds_write_b64 v2, v[30:31] offset:59136
	ds_write_b64 v2, v[62:63] offset:63360
	ds_write_b64 v143, v[4:5]
	ds_write_b64 v212, v[36:37]
	ds_write_b64 v213, v[20:21]
	ds_write_b64 v214, v[52:53]
	ds_write_b64 v215, v[12:13]
	ds_write_b64 v216, v[44:45]
	ds_write_b64 v217, v[28:29]
	ds_write_b64 v218, v[60:61]
	ds_write_b64 v219, v[8:9]
	ds_write_b64 v220, v[40:41]
	ds_write_b64 v221, v[24:25]
	ds_write_b64 v222, v[56:57]
	ds_write_b64 v223, v[16:17]
	ds_write_b64 v224, v[48:49]
	ds_write_b64 v225, v[32:33]
	ds_write_b64 v226, v[64:65]
	v_mov_b32_e32 v2, v142
	s_waitcnt lgkmcnt(0)
	s_barrier
	s_nop 0
	v_and_b32_e32 v4, 15, v2
	v_lshlrev_b32_e32 v2, 5, v2
	v_and_b32_e32 v2, 0xfffffe00, v2
	v_lshl_add_u32 v5, v2, 3, 0
	v_lshlrev_b32_e32 v7, 3, v4
	v_ashrrev_i32_e32 v2, 2, v2
	v_add3_u32 v2, v5, v7, v2
	v_add_u32_e32 v143, 0x800, v2
	ds_read2_b64 v[128:131], v2 offset1:16
	ds_read2_b64 v[148:151], v2 offset0:33 offset1:49
	ds_read2_b64 v[152:155], v2 offset0:66 offset1:82
	ds_read2_b64 v[156:159], v2 offset0:99 offset1:115
	ds_read2_b64 v[160:163], v2 offset0:132 offset1:148
	ds_read2_b64 v[164:167], v2 offset0:165 offset1:181
	ds_read2_b64 v[168:171], v2 offset0:198 offset1:214
	ds_read2_b64 v[172:175], v2 offset0:231 offset1:247
	ds_read2_b64 v[176:179], v143 offset0:8 offset1:24
	ds_read2_b64 v[180:183], v143 offset0:41 offset1:57
	ds_read2_b64 v[184:187], v143 offset0:74 offset1:90
	ds_read2_b64 v[188:191], v143 offset0:107 offset1:123
	ds_read2_b64 v[192:195], v143 offset0:140 offset1:156
	ds_read2_b64 v[196:199], v143 offset0:173 offset1:189
	ds_read2_b64 v[204:207], v143 offset0:206 offset1:222
	ds_read2_b64 v[208:211], v143 offset0:239 offset1:255
	s_waitcnt lgkmcnt(7)
	v_pk_add_f32 v[144:145], v[128:129], v[176:177]
	v_pk_add_f32 v[128:129], v[128:129], v[176:177] neg_lo:[0,1] neg_hi:[0,1]
	v_pk_add_f32 v[176:177], v[130:131], v[178:179]
	v_pk_add_f32 v[130:131], v[130:131], v[178:179] neg_lo:[0,1] neg_hi:[0,1]
	v_cvt_f32_ubyte0_e32 v4, v4
	v_pk_mul_f32 v[178:179], v[130:131], s[20:21]
	v_mul_f32_e32 v6, 0x3b000000, v4
	v_pk_fma_f32 v[130:131], v[130:131], s[10:11], v[178:179] op_sel:[0,0,1] op_sel_hi:[1,0,0]
	s_waitcnt lgkmcnt(6)
	v_pk_add_f32 v[178:179], v[148:149], v[180:181]
	v_pk_add_f32 v[148:149], v[148:149], v[180:181] neg_lo:[0,1] neg_hi:[0,1]
	v_sin_f32_e32 v4, v6
	v_pk_mul_f32 v[180:181], v[148:149], s[24:25]
	v_cos_f32_e32 v6, v6
	v_pk_fma_f32 v[148:149], v[148:149], s[22:23], v[180:181] op_sel:[0,0,1] op_sel_hi:[1,0,0]
	v_pk_add_f32 v[180:181], v[150:151], v[182:183]
	v_pk_add_f32 v[150:151], v[150:151], v[182:183] neg_lo:[0,1] neg_hi:[0,1]
	v_xor_b32_e32 v7, 0x80000000, v4
	v_pk_mul_f32 v[182:183], v[150:151], s[36:37]
	v_mov_b32_e32 v5, v7
	v_pk_fma_f32 v[150:151], v[150:151], s[26:27], v[182:183] op_sel:[0,0,1] op_sel_hi:[1,0,0]
	s_waitcnt lgkmcnt(5)
	v_pk_add_f32 v[182:183], v[152:153], v[184:185]
	v_pk_add_f32 v[152:153], v[152:153], v[184:185] neg_lo:[0,1] neg_hi:[0,1]
	v_pk_mul_f32 v[8:9], v[6:7], v[4:5] op_sel:[1,0] op_sel_hi:[0,1]
	v_pk_mul_f32 v[184:185], v[152:153], s[40:41]
	v_pk_fma_f32 v[8:9], v[6:7], v[6:7], v[8:9] op_sel_hi:[1,0,1]
	v_pk_fma_f32 v[152:153], v[152:153], s[38:39], v[184:185] op_sel:[0,0,1] op_sel_hi:[1,0,0]
	v_pk_add_f32 v[184:185], v[154:155], v[186:187]
	v_pk_add_f32 v[154:155], v[154:155], v[186:187] neg_lo:[0,1] neg_hi:[0,1]
	v_pk_mul_f32 v[186:187], v[154:155], s[42:43]
	v_pk_fma_f32 v[154:155], v[154:155], s[0:1], v[186:187] op_sel:[0,0,1] op_sel_hi:[1,0,0]
	s_waitcnt lgkmcnt(4)
	v_pk_add_f32 v[186:187], v[156:157], v[188:189]
	v_pk_add_f32 v[156:157], v[156:157], v[188:189] neg_lo:[0,1] neg_hi:[0,1]
	v_pk_mul_f32 v[12:13], v[8:9], v[8:9] op_sel:[1,1] op_sel_hi:[0,1] neg_lo:[0,1]
	v_pk_mul_f32 v[188:189], v[156:157], s[44:45]
	v_pk_fma_f32 v[12:13], v[8:9], v[8:9], v[12:13] op_sel_hi:[1,0,1]
	v_pk_fma_f32 v[156:157], v[156:157], s[50:51], v[188:189] op_sel:[0,0,1] op_sel_hi:[1,0,0]
	v_pk_add_f32 v[188:189], v[158:159], v[190:191]
	v_pk_add_f32 v[158:159], v[158:159], v[190:191] neg_lo:[0,1] neg_hi:[0,1]
	v_pk_mul_f32 v[190:191], v[158:159], s[8:9]
	v_pk_fma_f32 v[158:159], v[158:159], s[16:17], v[190:191] op_sel:[0,0,1] op_sel_hi:[1,0,0]
	s_waitcnt lgkmcnt(3)
	v_pk_add_f32 v[190:191], v[160:161], v[192:193]
	v_pk_add_f32 v[192:193], v[160:161], v[192:193] neg_lo:[0,1] neg_hi:[0,1]
	v_pk_mul_f32 v[28:29], v[12:13], v[12:13] op_sel:[1,1] op_sel_hi:[0,1] neg_lo:[0,1]
	v_pk_add_f32 v[160:161], v[162:163], v[194:195]
	v_pk_add_f32 v[162:163], v[162:163], v[194:195] neg_lo:[0,1] neg_hi:[0,1]
	v_pk_fma_f32 v[28:29], v[12:13], v[12:13], v[28:29] op_sel_hi:[1,0,1]
	v_pk_mul_f32 v[194:195], v[162:163], s[8:9]
	v_pk_mul_f32 v[44:45], v[12:13], v[28:29] op_sel:[1,1] op_sel_hi:[1,0] neg_lo:[1,0]
	v_pk_fma_f32 v[162:163], v[162:163], s[16:17], v[194:195] op_sel:[0,0,1] op_sel_hi:[1,0,0] neg_lo:[1,0,0] neg_hi:[1,0,0]
	s_waitcnt lgkmcnt(2)
	v_pk_add_f32 v[194:195], v[164:165], v[196:197]
	v_pk_add_f32 v[164:165], v[164:165], v[196:197] neg_lo:[0,1] neg_hi:[0,1]
	v_pk_fma_f32 v[44:45], v[12:13], v[28:29], v[44:45] op_sel_hi:[0,1,1]
	v_pk_mul_f32 v[196:197], v[164:165], s[44:45]
	v_pk_mul_f32 v[60:61], v[12:13], v[44:45] op_sel:[1,1] op_sel_hi:[1,0] neg_lo:[1,0]
	v_pk_fma_f32 v[164:165], v[164:165], s[50:51], v[196:197] op_sel:[0,0,1] op_sel_hi:[1,0,0] neg_lo:[1,0,0] neg_hi:[1,0,0]
	v_pk_add_f32 v[196:197], v[166:167], v[198:199]
	v_pk_add_f32 v[166:167], v[166:167], v[198:199] neg_lo:[0,1] neg_hi:[0,1]
	v_pk_fma_f32 v[60:61], v[12:13], v[44:45], v[60:61] op_sel_hi:[0,1,1]
	v_pk_mul_f32 v[198:199], v[166:167], s[42:43]
	v_pk_mul_f32 v[76:77], v[12:13], v[60:61] op_sel:[1,1] op_sel_hi:[1,0] neg_lo:[1,0]
	v_pk_fma_f32 v[166:167], v[166:167], s[0:1], v[198:199] op_sel:[0,0,1] op_sel_hi:[1,0,0] neg_lo:[1,0,0] neg_hi:[1,0,0]
	s_waitcnt lgkmcnt(1)
	v_pk_add_f32 v[198:199], v[168:169], v[204:205]
	v_pk_add_f32 v[168:169], v[168:169], v[204:205] neg_lo:[0,1] neg_hi:[0,1]
	v_pk_fma_f32 v[76:77], v[12:13], v[60:61], v[76:77] op_sel_hi:[0,1,1]
	v_pk_mul_f32 v[204:205], v[168:169], s[40:41]
	v_pk_mul_f32 v[92:93], v[12:13], v[76:77] op_sel:[1,1] op_sel_hi:[1,0] neg_lo:[1,0]
	v_pk_fma_f32 v[168:169], v[168:169], s[38:39], v[204:205] op_sel:[0,0,1] op_sel_hi:[1,0,0] neg_lo:[1,0,0] neg_hi:[1,0,0]
	v_pk_add_f32 v[204:205], v[170:171], v[206:207]
	v_pk_add_f32 v[170:171], v[170:171], v[206:207] neg_lo:[0,1] neg_hi:[0,1]
	v_pk_fma_f32 v[92:93], v[12:13], v[76:77], v[92:93] op_sel_hi:[0,1,1]
	v_pk_mul_f32 v[206:207], v[170:171], s[36:37]
	v_pk_mul_f32 v[108:109], v[12:13], v[92:93] op_sel:[1,1] op_sel_hi:[1,0] neg_lo:[1,0]
	v_pk_fma_f32 v[170:171], v[170:171], s[26:27], v[206:207] op_sel:[0,0,1] op_sel_hi:[1,0,0] neg_lo:[1,0,0] neg_hi:[1,0,0]
	s_waitcnt lgkmcnt(0)
	v_pk_add_f32 v[206:207], v[172:173], v[208:209]
	v_pk_add_f32 v[172:173], v[172:173], v[208:209] neg_lo:[0,1] neg_hi:[0,1]
	v_pk_mul_f32 v[10:11], v[4:5], v[8:9] op_sel:[0,1] op_sel_hi:[1,0]
	v_pk_mul_f32 v[208:209], v[172:173], s[24:25]
	v_pk_fma_f32 v[108:109], v[12:13], v[92:93], v[108:109] op_sel_hi:[0,1,1]
	v_pk_fma_f32 v[172:173], v[172:173], s[22:23], v[208:209] op_sel:[0,0,1] op_sel_hi:[1,0,0] neg_lo:[1,0,0] neg_hi:[1,0,0]
	v_pk_add_f32 v[208:209], v[174:175], v[210:211]
	v_pk_add_f32 v[174:175], v[174:175], v[210:211] neg_lo:[0,1] neg_hi:[0,1]
	v_pk_fma_f32 v[10:11], v[6:7], v[8:9], v[10:11] op_sel_hi:[0,1,1]
	v_pk_mul_f32 v[210:211], v[174:175], s[20:21]
	v_pk_mul_f32 v[18:19], v[4:5], v[12:13] op_sel:[0,1] op_sel_hi:[1,0]
	v_pk_fma_f32 v[174:175], v[174:175], s[10:11], v[210:211] op_sel:[0,0,1] op_sel_hi:[1,0,0] neg_lo:[1,0,0] neg_hi:[1,0,0]
	v_pk_add_f32 v[210:211], v[144:145], v[190:191]
	v_pk_add_f32 v[144:145], v[144:145], v[190:191] neg_lo:[0,1] neg_hi:[0,1]
	v_pk_add_f32 v[190:191], v[176:177], v[160:161]
	v_pk_add_f32 v[160:161], v[176:177], v[160:161] neg_lo:[0,1] neg_hi:[0,1]
	v_pk_mul_f32 v[32:33], v[4:5], v[28:29] op_sel:[0,1] op_sel_hi:[1,0]
	v_pk_mul_f32 v[176:177], v[160:161], s[24:25]
	v_pk_mul_f32 v[48:49], v[4:5], v[44:45] op_sel:[0,1] op_sel_hi:[1,0]
	v_pk_fma_f32 v[160:161], v[160:161], s[22:23], v[176:177] op_sel:[0,0,1] op_sel_hi:[1,0,0]
	v_pk_add_f32 v[176:177], v[178:179], v[194:195]
	v_pk_add_f32 v[178:179], v[178:179], v[194:195] neg_lo:[0,1] neg_hi:[0,1]
	v_pk_mul_f32 v[64:65], v[4:5], v[60:61] op_sel:[0,1] op_sel_hi:[1,0]
	v_pk_mul_f32 v[194:195], v[178:179], s[40:41]
	v_pk_mul_f32 v[80:81], v[4:5], v[76:77] op_sel:[0,1] op_sel_hi:[1,0]
	v_pk_fma_f32 v[178:179], v[178:179], s[38:39], v[194:195] op_sel:[0,0,1] op_sel_hi:[1,0,0]
	v_pk_add_f32 v[194:195], v[180:181], v[196:197]
	v_pk_add_f32 v[180:181], v[180:181], v[196:197] neg_lo:[0,1] neg_hi:[0,1]
	v_pk_mul_f32 v[96:97], v[4:5], v[92:93] op_sel:[0,1] op_sel_hi:[1,0]
	v_pk_mul_f32 v[196:197], v[180:181], s[44:45]
	v_pk_mul_f32 v[112:113], v[4:5], v[108:109] op_sel:[0,1] op_sel_hi:[1,0]
	v_pk_fma_f32 v[180:181], v[180:181], s[50:51], v[196:197] op_sel:[0,0,1] op_sel_hi:[1,0,0]
	v_pk_add_f32 v[196:197], v[182:183], v[198:199]
	v_pk_add_f32 v[198:199], v[182:183], v[198:199] neg_lo:[0,1] neg_hi:[0,1]
	v_pk_add_f32 v[182:183], v[184:185], v[204:205]
	v_pk_add_f32 v[184:185], v[184:185], v[204:205] neg_lo:[0,1] neg_hi:[0,1]
	v_pk_mul_f32 v[204:205], v[184:185], s[44:45]
	v_pk_fma_f32 v[18:19], v[6:7], v[12:13], v[18:19] op_sel_hi:[0,1,1]
	v_pk_fma_f32 v[184:185], v[184:185], s[50:51], v[204:205] op_sel:[0,0,1] op_sel_hi:[1,0,0] neg_lo:[1,0,0] neg_hi:[1,0,0]
	v_pk_add_f32 v[204:205], v[186:187], v[206:207]
	v_pk_add_f32 v[186:187], v[186:187], v[206:207] neg_lo:[0,1] neg_hi:[0,1]
	v_pk_mul_f32 v[20:21], v[8:9], v[12:13] op_sel:[1,1] op_sel_hi:[1,0] neg_lo:[1,0]
	v_pk_mul_f32 v[206:207], v[186:187], s[40:41]
	v_pk_fma_f32 v[32:33], v[6:7], v[28:29], v[32:33] op_sel_hi:[0,1,1]
	v_pk_fma_f32 v[186:187], v[186:187], s[38:39], v[206:207] op_sel:[0,0,1] op_sel_hi:[1,0,0] neg_lo:[1,0,0] neg_hi:[1,0,0]
	v_pk_add_f32 v[206:207], v[188:189], v[208:209]
	v_pk_add_f32 v[188:189], v[188:189], v[208:209] neg_lo:[0,1] neg_hi:[0,1]
	v_pk_mul_f32 v[36:37], v[8:9], v[28:29] op_sel:[1,1] op_sel_hi:[1,0] neg_lo:[1,0]
	v_pk_mul_f32 v[208:209], v[188:189], s[24:25]
	v_pk_fma_f32 v[48:49], v[6:7], v[44:45], v[48:49] op_sel_hi:[0,1,1]
	v_pk_fma_f32 v[188:189], v[188:189], s[22:23], v[208:209] op_sel:[0,0,1] op_sel_hi:[1,0,0] neg_lo:[1,0,0] neg_hi:[1,0,0]
	v_pk_add_f32 v[208:209], v[128:129], v[192:193] op_sel:[0,1] op_sel_hi:[1,0] neg_hi:[0,1]
	v_pk_add_f32 v[128:129], v[128:129], v[192:193] op_sel:[0,1] op_sel_hi:[1,0] neg_lo:[0,1]
	v_pk_add_f32 v[192:193], v[130:131], v[162:163]
	v_pk_add_f32 v[130:131], v[130:131], v[162:163] neg_lo:[0,1] neg_hi:[0,1]
	v_pk_mul_f32 v[52:53], v[8:9], v[44:45] op_sel:[1,1] op_sel_hi:[1,0] neg_lo:[1,0]
	v_pk_mul_f32 v[162:163], v[130:131], s[24:25]
	v_pk_fma_f32 v[64:65], v[6:7], v[60:61], v[64:65] op_sel_hi:[0,1,1]
	v_pk_fma_f32 v[130:131], v[130:131], s[22:23], v[162:163] op_sel:[0,0,1] op_sel_hi:[1,0,0]
	v_pk_add_f32 v[162:163], v[148:149], v[164:165]
	v_pk_add_f32 v[148:149], v[148:149], v[164:165] neg_lo:[0,1] neg_hi:[0,1]
	v_pk_mul_f32 v[68:69], v[8:9], v[60:61] op_sel:[1,1] op_sel_hi:[1,0] neg_lo:[1,0]
	v_pk_mul_f32 v[164:165], v[148:149], s[40:41]
	v_pk_fma_f32 v[80:81], v[6:7], v[76:77], v[80:81] op_sel_hi:[0,1,1]
	v_pk_fma_f32 v[148:149], v[148:149], s[38:39], v[164:165] op_sel:[0,0,1] op_sel_hi:[1,0,0]
	v_pk_add_f32 v[164:165], v[150:151], v[166:167]
	v_pk_add_f32 v[150:151], v[150:151], v[166:167] neg_lo:[0,1] neg_hi:[0,1]
	v_pk_mul_f32 v[84:85], v[8:9], v[76:77] op_sel:[1,1] op_sel_hi:[1,0] neg_lo:[1,0]
	v_pk_mul_f32 v[166:167], v[150:151], s[44:45]
	v_pk_fma_f32 v[96:97], v[6:7], v[92:93], v[96:97] op_sel_hi:[0,1,1]
	v_pk_fma_f32 v[150:151], v[150:151], s[50:51], v[166:167] op_sel:[0,0,1] op_sel_hi:[1,0,0]
	v_pk_add_f32 v[166:167], v[152:153], v[168:169]
	v_pk_add_f32 v[168:169], v[152:153], v[168:169] neg_lo:[0,1] neg_hi:[0,1]
	v_pk_mul_f32 v[100:101], v[8:9], v[92:93] op_sel:[1,1] op_sel_hi:[1,0] neg_lo:[1,0]
	v_pk_add_f32 v[152:153], v[154:155], v[170:171]
	v_pk_add_f32 v[154:155], v[154:155], v[170:171] neg_lo:[0,1] neg_hi:[0,1]
	v_pk_fma_f32 v[112:113], v[6:7], v[108:109], v[112:113] op_sel_hi:[0,1,1]
	v_pk_mul_f32 v[170:171], v[154:155], s[44:45]
	v_pk_mul_f32 v[116:117], v[8:9], v[108:109] op_sel:[1,1] op_sel_hi:[1,0] neg_lo:[1,0]
	v_pk_fma_f32 v[154:155], v[154:155], s[50:51], v[170:171] op_sel:[0,0,1] op_sel_hi:[1,0,0] neg_lo:[1,0,0] neg_hi:[1,0,0]
	v_pk_add_f32 v[170:171], v[156:157], v[172:173]
	v_pk_add_f32 v[156:157], v[156:157], v[172:173] neg_lo:[0,1] neg_hi:[0,1]
	v_pk_fma_f32 v[20:21], v[8:9], v[12:13], v[20:21] op_sel_hi:[0,1,1]
	v_pk_mul_f32 v[172:173], v[156:157], s[40:41]
	v_pk_mul_f32 v[24:25], v[12:13], v[10:11] op_sel:[1,1] op_sel_hi:[0,1] neg_lo:[0,1]
	v_pk_fma_f32 v[156:157], v[156:157], s[38:39], v[172:173] op_sel:[0,0,1] op_sel_hi:[1,0,0] neg_lo:[1,0,0] neg_hi:[1,0,0]
	v_pk_add_f32 v[172:173], v[158:159], v[174:175]
	v_pk_add_f32 v[158:159], v[158:159], v[174:175] neg_lo:[0,1] neg_hi:[0,1]
	v_pk_fma_f32 v[36:37], v[8:9], v[28:29], v[36:37] op_sel_hi:[0,1,1]
	v_pk_mul_f32 v[174:175], v[158:159], s[24:25]
	v_pk_mul_f32 v[40:41], v[10:11], v[28:29] op_sel:[1,1] op_sel_hi:[1,0] neg_lo:[1,0]
	v_pk_fma_f32 v[158:159], v[158:159], s[22:23], v[174:175] op_sel:[0,0,1] op_sel_hi:[1,0,0] neg_lo:[1,0,0] neg_hi:[1,0,0]
	v_pk_add_f32 v[174:175], v[210:211], v[196:197]
	v_pk_add_f32 v[196:197], v[210:211], v[196:197] neg_lo:[0,1] neg_hi:[0,1]
	v_pk_add_f32 v[210:211], v[190:191], v[182:183]
	v_pk_add_f32 v[182:183], v[190:191], v[182:183] neg_lo:[0,1] neg_hi:[0,1]
	v_pk_fma_f32 v[52:53], v[8:9], v[44:45], v[52:53] op_sel_hi:[0,1,1]
	v_pk_mul_f32 v[190:191], v[182:183], s[40:41]
	v_pk_mul_f32 v[56:57], v[10:11], v[44:45] op_sel:[1,1] op_sel_hi:[1,0] neg_lo:[1,0]
	v_pk_fma_f32 v[182:183], v[182:183], s[38:39], v[190:191] op_sel:[0,0,1] op_sel_hi:[1,0,0]
	v_pk_add_f32 v[190:191], v[176:177], v[204:205]
	v_pk_add_f32 v[204:205], v[176:177], v[204:205] neg_lo:[0,1] neg_hi:[0,1]
	v_pk_fma_f32 v[68:69], v[8:9], v[60:61], v[68:69] op_sel_hi:[0,1,1]
	v_pk_add_f32 v[176:177], v[194:195], v[206:207]
	v_pk_add_f32 v[194:195], v[194:195], v[206:207] neg_lo:[0,1] neg_hi:[0,1]
	v_pk_mul_f32 v[72:73], v[10:11], v[60:61] op_sel:[1,1] op_sel_hi:[1,0] neg_lo:[1,0]
	v_pk_mul_f32 v[206:207], v[194:195], s[40:41]
	v_pk_fma_f32 v[84:85], v[8:9], v[76:77], v[84:85] op_sel_hi:[0,1,1]
	v_pk_fma_f32 v[194:195], v[194:195], s[38:39], v[206:207] op_sel:[0,0,1] op_sel_hi:[1,0,0] neg_lo:[1,0,0] neg_hi:[1,0,0]
	v_pk_add_f32 v[206:207], v[144:145], v[198:199] op_sel:[0,1] op_sel_hi:[1,0] neg_hi:[0,1]
	v_pk_add_f32 v[144:145], v[144:145], v[198:199] op_sel:[0,1] op_sel_hi:[1,0] neg_lo:[0,1]
	v_pk_add_f32 v[198:199], v[160:161], v[184:185]
	v_pk_add_f32 v[160:161], v[160:161], v[184:185] neg_lo:[0,1] neg_hi:[0,1]
	v_pk_mul_f32 v[88:89], v[10:11], v[76:77] op_sel:[1,1] op_sel_hi:[1,0] neg_lo:[1,0]
	v_pk_mul_f32 v[184:185], v[160:161], s[40:41]
	v_pk_fma_f32 v[100:101], v[8:9], v[92:93], v[100:101] op_sel_hi:[0,1,1]
	v_pk_fma_f32 v[160:161], v[160:161], s[38:39], v[184:185] op_sel:[0,0,1] op_sel_hi:[1,0,0]
	v_pk_add_f32 v[184:185], v[178:179], v[186:187]
	v_pk_add_f32 v[186:187], v[178:179], v[186:187] neg_lo:[0,1] neg_hi:[0,1]
	v_pk_mul_f32 v[104:105], v[10:11], v[92:93] op_sel:[1,1] op_sel_hi:[1,0] neg_lo:[1,0]
	v_pk_add_f32 v[178:179], v[180:181], v[188:189]
	v_pk_add_f32 v[180:181], v[180:181], v[188:189] neg_lo:[0,1] neg_hi:[0,1]
	v_pk_fma_f32 v[116:117], v[8:9], v[108:109], v[116:117] op_sel_hi:[0,1,1]
	v_pk_mul_f32 v[188:189], v[180:181], s[40:41]
	v_pk_mul_f32 v[120:121], v[10:11], v[108:109] op_sel:[1,1] op_sel_hi:[1,0] neg_lo:[1,0]
	v_pk_fma_f32 v[180:181], v[180:181], s[38:39], v[188:189] op_sel:[0,0,1] op_sel_hi:[1,0,0] neg_lo:[1,0,0] neg_hi:[1,0,0]
	v_pk_add_f32 v[188:189], v[208:209], v[166:167]
	v_pk_add_f32 v[166:167], v[208:209], v[166:167] neg_lo:[0,1] neg_hi:[0,1]
	v_pk_add_f32 v[208:209], v[192:193], v[152:153]
	v_pk_add_f32 v[152:153], v[192:193], v[152:153] neg_lo:[0,1] neg_hi:[0,1]
	v_xor_b32_e32 v26, 0x80000000, v19
	v_pk_mul_f32 v[192:193], v[152:153], s[40:41]
	v_xor_b32_e32 v30, 0x80000000, v21
	v_pk_fma_f32 v[152:153], v[152:153], s[38:39], v[192:193] op_sel:[0,0,1] op_sel_hi:[1,0,0]
	v_pk_add_f32 v[192:193], v[162:163], v[170:171]
	v_pk_add_f32 v[170:171], v[162:163], v[170:171] neg_lo:[0,1] neg_hi:[0,1]
	v_pk_fma_f32 v[24:25], v[12:13], v[10:11], v[24:25] op_sel_hi:[1,0,1]
	v_pk_add_f32 v[162:163], v[164:165], v[172:173]
	v_pk_add_f32 v[164:165], v[164:165], v[172:173] neg_lo:[0,1] neg_hi:[0,1]
	v_pk_fma_f32 v[40:41], v[10:11], v[28:29], v[40:41] op_sel_hi:[0,1,1]
	v_pk_mul_f32 v[172:173], v[164:165], s[40:41]
	v_pk_fma_f32 v[56:57], v[10:11], v[44:45], v[56:57] op_sel_hi:[0,1,1]
	v_pk_fma_f32 v[164:165], v[164:165], s[38:39], v[172:173] op_sel:[0,0,1] op_sel_hi:[1,0,0] neg_lo:[1,0,0] neg_hi:[1,0,0]
	v_pk_add_f32 v[172:173], v[128:129], v[168:169] op_sel:[0,1] op_sel_hi:[1,0] neg_hi:[0,1]
	v_pk_add_f32 v[128:129], v[128:129], v[168:169] op_sel:[0,1] op_sel_hi:[1,0] neg_lo:[0,1]
	v_pk_add_f32 v[168:169], v[130:131], v[154:155]
	v_pk_add_f32 v[130:131], v[130:131], v[154:155] neg_lo:[0,1] neg_hi:[0,1]
	v_pk_fma_f32 v[72:73], v[10:11], v[60:61], v[72:73] op_sel_hi:[0,1,1]
	v_pk_mul_f32 v[154:155], v[130:131], s[40:41]
	v_pk_fma_f32 v[88:89], v[10:11], v[76:77], v[88:89] op_sel_hi:[0,1,1]
	v_pk_fma_f32 v[130:131], v[130:131], s[38:39], v[154:155] op_sel:[0,0,1] op_sel_hi:[1,0,0]
	v_pk_add_f32 v[154:155], v[148:149], v[156:157]
	v_pk_add_f32 v[156:157], v[148:149], v[156:157] neg_lo:[0,1] neg_hi:[0,1]
	v_pk_fma_f32 v[104:105], v[10:11], v[92:93], v[104:105] op_sel_hi:[0,1,1]
	v_pk_add_f32 v[148:149], v[150:151], v[158:159]
	v_pk_add_f32 v[150:151], v[150:151], v[158:159] neg_lo:[0,1] neg_hi:[0,1]
	v_pk_fma_f32 v[120:121], v[10:11], v[108:109], v[120:121] op_sel_hi:[0,1,1]
	v_pk_mul_f32 v[158:159], v[150:151], s[40:41]
	v_mov_b32_e32 v27, v19
	v_pk_fma_f32 v[150:151], v[150:151], s[38:39], v[158:159] op_sel:[0,0,1] op_sel_hi:[1,0,0] neg_lo:[1,0,0] neg_hi:[1,0,0]
	v_pk_add_f32 v[158:159], v[174:175], v[190:191]
	v_pk_add_f32 v[174:175], v[174:175], v[190:191] neg_lo:[0,1] neg_hi:[0,1]
	v_pk_add_f32 v[190:191], v[210:211], v[176:177]
	v_pk_add_f32 v[210:211], v[210:211], v[176:177] neg_lo:[0,1] neg_hi:[0,1]
	v_mov_b32_e32 v31, v21
	v_pk_add_f32 v[176:177], v[196:197], v[204:205] op_sel:[0,1] op_sel_hi:[1,0] neg_hi:[0,1]
	v_pk_add_f32 v[196:197], v[196:197], v[204:205] op_sel:[0,1] op_sel_hi:[1,0] neg_lo:[0,1]
	v_pk_add_f32 v[204:205], v[182:183], v[194:195]
	v_pk_add_f32 v[194:195], v[182:183], v[194:195] neg_lo:[0,1] neg_hi:[0,1]
	v_xor_b32_e32 v34, 0x80000000, v25
	v_pk_add_f32 v[182:183], v[206:207], v[184:185]
	v_pk_add_f32 v[184:185], v[206:207], v[184:185] neg_lo:[0,1] neg_hi:[0,1]
	v_pk_add_f32 v[206:207], v[198:199], v[178:179]
	v_pk_add_f32 v[198:199], v[198:199], v[178:179] neg_lo:[0,1] neg_hi:[0,1]
	v_xor_b32_e32 v38, 0x80000000, v29
	v_pk_add_f32 v[178:179], v[144:145], v[186:187] op_sel:[0,1] op_sel_hi:[1,0] neg_hi:[0,1]
	v_pk_add_f32 v[144:145], v[144:145], v[186:187] op_sel:[0,1] op_sel_hi:[1,0] neg_lo:[0,1]
	v_pk_add_f32 v[186:187], v[160:161], v[180:181]
	v_pk_add_f32 v[180:181], v[160:161], v[180:181] neg_lo:[0,1] neg_hi:[0,1]
	v_xor_b32_e32 v42, 0x80000000, v33
	v_pk_add_f32 v[160:161], v[188:189], v[192:193]
	v_pk_add_f32 v[188:189], v[188:189], v[192:193] neg_lo:[0,1] neg_hi:[0,1]
	v_pk_add_f32 v[192:193], v[208:209], v[162:163]
	v_pk_add_f32 v[208:209], v[208:209], v[162:163] neg_lo:[0,1] neg_hi:[0,1]
	v_xor_b32_e32 v46, 0x80000000, v37
	v_pk_add_f32 v[162:163], v[166:167], v[170:171] op_sel:[0,1] op_sel_hi:[1,0] neg_hi:[0,1]
	v_pk_add_f32 v[166:167], v[166:167], v[170:171] op_sel:[0,1] op_sel_hi:[1,0] neg_lo:[0,1]
	v_pk_add_f32 v[170:171], v[152:153], v[164:165]
	v_pk_add_f32 v[164:165], v[152:153], v[164:165] neg_lo:[0,1] neg_hi:[0,1]
	v_mov_b32_e32 v35, v25
	v_pk_add_f32 v[152:153], v[172:173], v[154:155]
	v_pk_add_f32 v[154:155], v[172:173], v[154:155] neg_lo:[0,1] neg_hi:[0,1]
	v_pk_add_f32 v[172:173], v[168:169], v[148:149]
	v_pk_add_f32 v[168:169], v[168:169], v[148:149] neg_lo:[0,1] neg_hi:[0,1]
	v_mov_b32_e32 v39, v29
	v_pk_add_f32 v[148:149], v[128:129], v[156:157] op_sel:[0,1] op_sel_hi:[1,0] neg_hi:[0,1]
	v_pk_add_f32 v[128:129], v[128:129], v[156:157] op_sel:[0,1] op_sel_hi:[1,0] neg_lo:[0,1]
	v_pk_add_f32 v[156:157], v[130:131], v[150:151]
	v_pk_add_f32 v[130:131], v[130:131], v[150:151] neg_lo:[0,1] neg_hi:[0,1]
	v_mov_b32_e32 v43, v33
	v_xor_b32_e32 v151, 0x80000000, v130
	v_mov_b32_e32 v150, v131
	v_pk_add_f32 v[130:131], v[158:159], v[190:191]
	v_pk_add_f32 v[158:159], v[158:159], v[190:191] neg_lo:[0,1] neg_hi:[0,1]
	v_pk_add_f32 v[190:191], v[174:175], v[210:211] op_sel:[0,1] op_sel_hi:[1,0] neg_hi:[0,1]
	v_pk_add_f32 v[174:175], v[174:175], v[210:211] op_sel:[0,1] op_sel_hi:[1,0] neg_lo:[0,1]
	v_pk_add_f32 v[210:211], v[176:177], v[204:205]
	v_pk_add_f32 v[176:177], v[176:177], v[204:205] neg_lo:[0,1] neg_hi:[0,1]
	v_pk_add_f32 v[204:205], v[196:197], v[194:195] op_sel:[0,1] op_sel_hi:[1,0] neg_hi:[0,1]
	v_pk_add_f32 v[194:195], v[196:197], v[194:195] op_sel:[0,1] op_sel_hi:[1,0] neg_lo:[0,1]
	v_pk_add_f32 v[196:197], v[182:183], v[206:207]
	v_pk_add_f32 v[182:183], v[182:183], v[206:207] neg_lo:[0,1] neg_hi:[0,1]
	v_pk_add_f32 v[206:207], v[184:185], v[198:199] op_sel:[0,1] op_sel_hi:[1,0] neg_hi:[0,1]
	v_pk_add_f32 v[184:185], v[184:185], v[198:199] op_sel:[0,1] op_sel_hi:[1,0] neg_lo:[0,1]
	v_pk_add_f32 v[198:199], v[178:179], v[186:187]
	v_pk_add_f32 v[178:179], v[178:179], v[186:187] neg_lo:[0,1] neg_hi:[0,1]
	v_pk_add_f32 v[186:187], v[144:145], v[180:181] op_sel:[0,1] op_sel_hi:[1,0] neg_hi:[0,1]
	v_pk_add_f32 v[144:145], v[144:145], v[180:181] op_sel:[0,1] op_sel_hi:[1,0] neg_lo:[0,1]
	v_pk_add_f32 v[180:181], v[160:161], v[192:193]
	v_pk_add_f32 v[160:161], v[160:161], v[192:193] neg_lo:[0,1] neg_hi:[0,1]
	v_pk_mul_f32 v[4:5], v[4:5], v[180:181] op_sel:[0,1] op_sel_hi:[1,0]
	v_pk_add_f32 v[192:193], v[188:189], v[208:209] op_sel:[0,1] op_sel_hi:[1,0] neg_hi:[0,1]
	v_pk_add_f32 v[188:189], v[188:189], v[208:209] op_sel:[0,1] op_sel_hi:[1,0] neg_lo:[0,1]
	v_pk_add_f32 v[208:209], v[162:163], v[170:171]
	v_pk_add_f32 v[162:163], v[162:163], v[170:171] neg_lo:[0,1] neg_hi:[0,1]
	v_pk_add_f32 v[170:171], v[166:167], v[164:165] op_sel:[0,1] op_sel_hi:[1,0] neg_hi:[0,1]
	v_pk_add_f32 v[164:165], v[166:167], v[164:165] op_sel:[0,1] op_sel_hi:[1,0] neg_lo:[0,1]
	v_pk_add_f32 v[166:167], v[152:153], v[172:173]
	v_pk_fma_f32 v[4:5], v[6:7], v[180:181], v[4:5] op_sel_hi:[0,1,1]
	v_pk_mul_f32 v[6:7], v[8:9], v[196:197] op_sel:[1,1] op_sel_hi:[1,0] neg_lo:[1,0]
	v_mov_b32_e32 v47, v37
	v_pk_fma_f32 v[6:7], v[8:9], v[196:197], v[6:7] op_sel_hi:[0,1,1]
	v_pk_mul_f32 v[8:9], v[10:11], v[166:167] op_sel:[1,1] op_sel_hi:[1,0] neg_lo:[1,0]
	v_pk_add_f32 v[152:153], v[152:153], v[172:173] neg_lo:[0,1] neg_hi:[0,1]
	v_pk_fma_f32 v[8:9], v[10:11], v[166:167], v[8:9] op_sel_hi:[0,1,1]
	v_pk_mul_f32 v[10:11], v[12:13], v[210:211] op_sel:[1,1] op_sel_hi:[1,0] neg_lo:[1,0]
	v_pk_add_f32 v[172:173], v[154:155], v[168:169] op_sel:[0,1] op_sel_hi:[1,0] neg_hi:[0,1]
	v_pk_add_f32 v[154:155], v[154:155], v[168:169] op_sel:[0,1] op_sel_hi:[1,0] neg_lo:[0,1]
	v_pk_add_f32 v[168:169], v[148:149], v[156:157]
	v_pk_fma_f32 v[10:11], v[12:13], v[210:211], v[10:11] op_sel_hi:[0,1,1]
	v_pk_mul_f32 v[12:13], v[26:27], v[208:209] op_sel:[0,1] op_sel_hi:[1,0]
	v_pk_mul_f32 v[14:15], v[30:31], v[198:199] op_sel:[0,1] op_sel_hi:[1,0]
	v_pk_add_f32 v[148:149], v[148:149], v[156:157] neg_lo:[0,1] neg_hi:[0,1]
	v_pk_add_f32 v[156:157], v[128:129], v[150:151]
	v_pk_fma_f32 v[12:13], v[18:19], v[208:209], v[12:13] op_sel_hi:[0,1,1]
	v_pk_fma_f32 v[14:15], v[20:21], v[198:199], v[14:15] op_sel_hi:[0,1,1]
	v_pk_mul_f32 v[16:17], v[34:35], v[168:169] op_sel:[0,1] op_sel_hi:[1,0]
	v_pk_mul_f32 v[18:19], v[38:39], v[190:191] op_sel:[0,1] op_sel_hi:[1,0]
	v_pk_mul_f32 v[20:21], v[42:43], v[192:193] op_sel:[0,1] op_sel_hi:[1,0]
	v_pk_mul_f32 v[22:23], v[46:47], v[206:207] op_sel:[0,1] op_sel_hi:[1,0]
	v_xor_b32_e32 v78, 0x80000000, v69
	v_xor_b32_e32 v82, 0x80000000, v73
	v_xor_b32_e32 v86, 0x80000000, v77
	v_xor_b32_e32 v90, 0x80000000, v81
	v_xor_b32_e32 v94, 0x80000000, v85
	v_xor_b32_e32 v98, 0x80000000, v89
	v_xor_b32_e32 v102, 0x80000000, v93
	v_xor_b32_e32 v106, 0x80000000, v97
	v_xor_b32_e32 v110, 0x80000000, v101
	v_xor_b32_e32 v114, 0x80000000, v105
	v_xor_b32_e32 v118, 0x80000000, v109
	v_xor_b32_e32 v122, 0x80000000, v113
	v_xor_b32_e32 v124, 0x80000000, v117
	v_xor_b32_e32 v126, 0x80000000, v121
	v_mov_b32_e32 v79, v69
	v_mov_b32_e32 v83, v73
	v_mov_b32_e32 v87, v77
	v_mov_b32_e32 v91, v81
	v_mov_b32_e32 v95, v85
	v_mov_b32_e32 v99, v89
	v_mov_b32_e32 v103, v93
	v_mov_b32_e32 v107, v97
	v_mov_b32_e32 v111, v101
	v_mov_b32_e32 v115, v105
	v_mov_b32_e32 v119, v109
	v_mov_b32_e32 v123, v113
	v_mov_b32_e32 v125, v117
	v_mov_b32_e32 v127, v121
	v_pk_add_f32 v[128:129], v[128:129], v[150:151] neg_lo:[0,1] neg_hi:[0,1]
	v_pk_fma_f32 v[16:17], v[24:25], v[168:169], v[16:17] op_sel_hi:[0,1,1]
	v_pk_fma_f32 v[18:19], v[28:29], v[190:191], v[18:19] op_sel_hi:[0,1,1]
	v_pk_fma_f32 v[20:21], v[32:33], v[192:193], v[20:21] op_sel_hi:[0,1,1]
	v_pk_fma_f32 v[22:23], v[36:37], v[206:207], v[22:23] op_sel_hi:[0,1,1]
	v_pk_mul_f32 v[24:25], v[40:41], v[172:173] op_sel:[1,1] op_sel_hi:[1,0] neg_lo:[1,0]
	v_pk_mul_f32 v[26:27], v[44:45], v[204:205] op_sel:[1,1] op_sel_hi:[1,0] neg_lo:[1,0]
	v_pk_mul_f32 v[28:29], v[48:49], v[170:171] op_sel:[1,1] op_sel_hi:[1,0] neg_lo:[1,0]
	v_pk_mul_f32 v[30:31], v[52:53], v[186:187] op_sel:[1,1] op_sel_hi:[1,0] neg_lo:[1,0]
	v_pk_mul_f32 v[32:33], v[56:57], v[156:157] op_sel:[1,1] op_sel_hi:[1,0] neg_lo:[1,0]
	v_pk_mul_f32 v[34:35], v[60:61], v[158:159] op_sel:[1,1] op_sel_hi:[1,0] neg_lo:[1,0]
	v_pk_mul_f32 v[36:37], v[64:65], v[160:161] op_sel:[1,1] op_sel_hi:[1,0] neg_lo:[1,0]
	v_pk_fma_f32 v[24:25], v[40:41], v[172:173], v[24:25] op_sel_hi:[0,1,1]
	v_pk_fma_f32 v[26:27], v[44:45], v[204:205], v[26:27] op_sel_hi:[0,1,1]
	v_pk_fma_f32 v[28:29], v[48:49], v[170:171], v[28:29] op_sel_hi:[0,1,1]
	v_pk_fma_f32 v[30:31], v[52:53], v[186:187], v[30:31] op_sel_hi:[0,1,1]
	v_pk_fma_f32 v[32:33], v[56:57], v[156:157], v[32:33] op_sel_hi:[0,1,1]
	v_pk_fma_f32 v[34:35], v[60:61], v[158:159], v[34:35] op_sel_hi:[0,1,1]
	v_pk_fma_f32 v[36:37], v[64:65], v[160:161], v[36:37] op_sel_hi:[0,1,1]
	v_pk_mul_f32 v[38:39], v[78:79], v[182:183] op_sel:[0,1] op_sel_hi:[1,0]
	v_pk_mul_f32 v[40:41], v[82:83], v[152:153] op_sel:[0,1] op_sel_hi:[1,0]
	v_pk_mul_f32 v[42:43], v[86:87], v[176:177] op_sel:[0,1] op_sel_hi:[1,0]
	v_pk_mul_f32 v[44:45], v[90:91], v[162:163] op_sel:[0,1] op_sel_hi:[1,0]
	v_pk_mul_f32 v[46:47], v[94:95], v[178:179] op_sel:[0,1] op_sel_hi:[1,0]
	v_pk_mul_f32 v[48:49], v[98:99], v[148:149] op_sel:[0,1] op_sel_hi:[1,0]
	v_pk_mul_f32 v[50:51], v[102:103], v[174:175] op_sel:[0,1] op_sel_hi:[1,0]
	v_pk_mul_f32 v[52:53], v[106:107], v[188:189] op_sel:[0,1] op_sel_hi:[1,0]
	v_pk_mul_f32 v[54:55], v[110:111], v[184:185] op_sel:[0,1] op_sel_hi:[1,0]
	v_pk_mul_f32 v[56:57], v[114:115], v[154:155] op_sel:[0,1] op_sel_hi:[1,0]
	v_pk_mul_f32 v[58:59], v[118:119], v[194:195] op_sel:[0,1] op_sel_hi:[1,0]
	v_pk_mul_f32 v[60:61], v[122:123], v[164:165] op_sel:[0,1] op_sel_hi:[1,0]
	v_pk_mul_f32 v[62:63], v[124:125], v[144:145] op_sel:[0,1] op_sel_hi:[1,0]
	v_pk_mul_f32 v[64:65], v[126:127], v[128:129] op_sel:[0,1] op_sel_hi:[1,0]
	v_pk_fma_f32 v[38:39], v[68:69], v[182:183], v[38:39] op_sel_hi:[0,1,1]
	v_pk_fma_f32 v[40:41], v[72:73], v[152:153], v[40:41] op_sel_hi:[0,1,1]
	v_pk_fma_f32 v[42:43], v[76:77], v[176:177], v[42:43] op_sel_hi:[0,1,1]
	v_pk_fma_f32 v[44:45], v[80:81], v[162:163], v[44:45] op_sel_hi:[0,1,1]
	v_pk_fma_f32 v[46:47], v[84:85], v[178:179], v[46:47] op_sel_hi:[0,1,1]
	v_pk_fma_f32 v[48:49], v[88:89], v[148:149], v[48:49] op_sel_hi:[0,1,1]
	v_pk_fma_f32 v[50:51], v[92:93], v[174:175], v[50:51] op_sel_hi:[0,1,1]
	v_pk_fma_f32 v[52:53], v[96:97], v[188:189], v[52:53] op_sel_hi:[0,1,1]
	v_pk_fma_f32 v[54:55], v[100:101], v[184:185], v[54:55] op_sel_hi:[0,1,1]
	v_pk_fma_f32 v[56:57], v[104:105], v[154:155], v[56:57] op_sel_hi:[0,1,1]
	v_pk_fma_f32 v[58:59], v[108:109], v[194:195], v[58:59] op_sel_hi:[0,1,1]
	v_pk_fma_f32 v[60:61], v[112:113], v[164:165], v[60:61] op_sel_hi:[0,1,1]
	v_pk_fma_f32 v[62:63], v[116:117], v[144:145], v[62:63] op_sel_hi:[0,1,1]
	v_pk_fma_f32 v[64:65], v[120:121], v[128:129], v[64:65] op_sel_hi:[0,1,1]
	ds_write2_b64 v2, v[130:131], v[34:35] offset1:16
	ds_write2_b64 v2, v[18:19], v[50:51] offset0:33 offset1:49
	ds_write2_b64 v2, v[10:11], v[42:43] offset0:66 offset1:82
	ds_write2_b64 v2, v[26:27], v[58:59] offset0:99 offset1:115
	ds_write2_b64 v2, v[6:7], v[38:39] offset0:132 offset1:148
	ds_write2_b64 v2, v[22:23], v[54:55] offset0:165 offset1:181
	ds_write2_b64 v2, v[14:15], v[46:47] offset0:198 offset1:214
	ds_write2_b64 v2, v[30:31], v[62:63] offset0:231 offset1:247
	ds_write2_b64 v143, v[4:5], v[36:37] offset0:8 offset1:24
	ds_write2_b64 v143, v[20:21], v[52:53] offset0:41 offset1:57
	ds_write2_b64 v143, v[12:13], v[44:45] offset0:74 offset1:90
	ds_write2_b64 v143, v[28:29], v[60:61] offset0:107 offset1:123
	ds_write2_b64 v143, v[8:9], v[40:41] offset0:140 offset1:156
	ds_write2_b64 v143, v[24:25], v[56:57] offset0:173 offset1:189
	ds_write2_b64 v143, v[16:17], v[48:49] offset0:206 offset1:222
	ds_write2_b64 v143, v[32:33], v[64:65] offset0:239 offset1:255
	s_waitcnt lgkmcnt(0)
	s_barrier
	s_nop 0
	v_ashrrev_i32_e32 v2, 31, v142
	v_lshrrev_b32_e32 v2, 23, v2
	v_add_u32_e32 v2, v142, v2
	v_ashrrev_i32_e32 v2, 9, v2
	v_mul_i32_i24_e32 v4, 0x200, v2
	v_sub_u32_e32 v144, v142, v4
	v_lshlrev_b32_e32 v143, 14, v2
	v_lshlrev_b32_e32 v2, 1, v144
	v_bfrev_b32_e32 v2, v2
	v_lshrrev_b32_e32 v2, 22, v2
	v_sub_u32_e32 v2, 0x400, v2
	v_bfrev_b32_e32 v2, v2
	v_lshrrev_b32_e32 v2, 18, v2
	v_and_b32_e32 v2, 0x3ff0, v2
	v_cmp_eq_u32_e32 vcc, 0, v144
	v_lshl_add_u32 v4, v144, 5, v143
	v_lshlrev_b32_e32 v5, 3, v4
	v_cndmask_b32_e64 v2, v2, 16, vcc
	v_ashrrev_i32_e32 v4, 2, v4
	v_or_b32_e32 v2, v2, v143
	v_add3_u32 v56, 0, v5, v4
	v_ashrrev_i32_e32 v4, 5, v2
	v_lshlrev_b32_e32 v2, 3, v2
	v_lshlrev_b32_e32 v4, 3, v4
	v_add3_u32 v2, 0, v2, v4
	ds_read2_b64 v[4:7], v56 offset1:1
	ds_read2_b64 v[8:11], v56 offset0:2 offset1:3
	ds_read2_b64 v[12:15], v2 offset1:1
	ds_read2_b64 v[16:19], v2 offset0:2 offset1:3
	ds_read2_b64 v[20:23], v56 offset0:4 offset1:5
	ds_read2_b64 v[24:27], v56 offset0:6 offset1:7
	ds_read2_b64 v[28:31], v2 offset0:4 offset1:5
	ds_read2_b64 v[32:35], v2 offset0:6 offset1:7
	ds_read2_b64 v[36:39], v56 offset0:8 offset1:9
	ds_read2_b64 v[40:43], v56 offset0:10 offset1:11
	ds_read2_b64 v[48:51], v2 offset0:8 offset1:9
	ds_read2_b64 v[52:55], v2 offset0:10 offset1:11
	ds_read2_b64 v[44:47], v56 offset0:12 offset1:13
	ds_read2_b64 v[56:59], v56 offset0:14 offset1:15
	ds_read2_b64 v[70:73], v2 offset0:12 offset1:13
	ds_read2_b64 v[98:101], v2 offset0:14 offset1:15
	s_waitcnt lgkmcnt(7)
	v_pk_add_f32 v[60:61], v[4:5], v[36:37]
	v_pk_add_f32 v[4:5], v[4:5], v[36:37] neg_lo:[0,1] neg_hi:[0,1]
	v_pk_add_f32 v[36:37], v[6:7], v[38:39]
	v_pk_add_f32 v[6:7], v[6:7], v[38:39] neg_lo:[0,1] neg_hi:[0,1]
	s_waitcnt lgkmcnt(3)
	v_pk_add_f32 v[62:63], v[22:23], v[46:47]
	v_pk_mul_f32 v[38:39], v[6:7], s[24:25]
	v_pk_add_f32 v[22:23], v[22:23], v[46:47] neg_lo:[0,1] neg_hi:[0,1]
	v_pk_fma_f32 v[6:7], v[6:7], s[22:23], v[38:39] op_sel:[0,0,1] op_sel_hi:[1,0,0]
	v_pk_add_f32 v[38:39], v[8:9], v[40:41]
	v_pk_add_f32 v[8:9], v[8:9], v[40:41] neg_lo:[0,1] neg_hi:[0,1]
	v_pk_mul_f32 v[46:47], v[22:23], s[44:45]
	v_pk_mul_f32 v[40:41], v[8:9], s[40:41]
	v_pk_fma_f32 v[22:23], v[22:23], s[50:51], v[46:47] op_sel:[0,0,1] op_sel_hi:[1,0,0] neg_lo:[1,0,0] neg_hi:[1,0,0]
	v_pk_fma_f32 v[8:9], v[8:9], s[38:39], v[40:41] op_sel:[0,0,1] op_sel_hi:[1,0,0]
	v_pk_add_f32 v[40:41], v[10:11], v[42:43]
	v_pk_add_f32 v[10:11], v[10:11], v[42:43] neg_lo:[0,1] neg_hi:[0,1]
	s_waitcnt lgkmcnt(2)
	v_pk_add_f32 v[46:47], v[24:25], v[56:57]
	v_pk_add_f32 v[24:25], v[24:25], v[56:57] neg_lo:[0,1] neg_hi:[0,1]
	v_pk_mul_f32 v[42:43], v[10:11], s[44:45]
	v_pk_mul_f32 v[56:57], v[24:25], s[40:41]
	v_pk_fma_f32 v[10:11], v[10:11], s[50:51], v[42:43] op_sel:[0,0,1] op_sel_hi:[1,0,0]
	v_pk_add_f32 v[42:43], v[20:21], v[44:45]
	v_pk_add_f32 v[44:45], v[20:21], v[44:45] neg_lo:[0,1] neg_hi:[0,1]
	v_pk_fma_f32 v[24:25], v[24:25], s[38:39], v[56:57] op_sel:[0,0,1] op_sel_hi:[1,0,0] neg_lo:[1,0,0] neg_hi:[1,0,0]
	v_pk_add_f32 v[56:57], v[26:27], v[58:59]
	v_pk_add_f32 v[26:27], v[26:27], v[58:59] neg_lo:[0,1] neg_hi:[0,1]
	v_pk_mul_f32 v[58:59], v[26:27], s[24:25]
	v_pk_add_f32 v[64:65], v[40:41], v[56:57]
	v_pk_add_f32 v[40:41], v[40:41], v[56:57] neg_lo:[0,1] neg_hi:[0,1]
	v_pk_fma_f32 v[26:27], v[26:27], s[22:23], v[58:59] op_sel:[0,0,1] op_sel_hi:[1,0,0] neg_lo:[1,0,0] neg_hi:[1,0,0]
	v_pk_mul_f32 v[56:57], v[40:41], s[40:41]
	v_pk_add_f32 v[20:21], v[4:5], v[44:45] op_sel:[0,1] op_sel_hi:[1,0] neg_hi:[0,1]
	v_pk_add_f32 v[4:5], v[4:5], v[44:45] op_sel:[0,1] op_sel_hi:[1,0] neg_lo:[0,1]
	v_pk_add_f32 v[44:45], v[6:7], v[22:23]
	v_pk_add_f32 v[6:7], v[6:7], v[22:23] neg_lo:[0,1] neg_hi:[0,1]
	v_pk_fma_f32 v[40:41], v[40:41], s[38:39], v[56:57] op_sel:[0,0,1] op_sel_hi:[1,0,0] neg_lo:[1,0,0] neg_hi:[1,0,0]
	v_pk_mul_f32 v[22:23], v[6:7], s[40:41]
	v_pk_add_f32 v[56:57], v[10:11], v[26:27]
	v_pk_add_f32 v[10:11], v[10:11], v[26:27] neg_lo:[0,1] neg_hi:[0,1]
	v_pk_add_f32 v[58:59], v[60:61], v[42:43]
	v_pk_add_f32 v[42:43], v[60:61], v[42:43] neg_lo:[0,1] neg_hi:[0,1]
	v_pk_add_f32 v[60:61], v[36:37], v[62:63]
	v_pk_add_f32 v[36:37], v[36:37], v[62:63] neg_lo:[0,1] neg_hi:[0,1]
	v_pk_fma_f32 v[6:7], v[6:7], s[38:39], v[22:23] op_sel:[0,0,1] op_sel_hi:[1,0,0]
	v_pk_add_f32 v[22:23], v[8:9], v[24:25]
	v_pk_add_f32 v[24:25], v[8:9], v[24:25] neg_lo:[0,1] neg_hi:[0,1]
	v_pk_mul_f32 v[26:27], v[10:11], s[40:41]
	v_pk_mul_f32 v[62:63], v[36:37], s[40:41]
	v_pk_fma_f32 v[10:11], v[10:11], s[38:39], v[26:27] op_sel:[0,0,1] op_sel_hi:[1,0,0] neg_lo:[1,0,0] neg_hi:[1,0,0]
	v_pk_fma_f32 v[36:37], v[36:37], s[38:39], v[62:63] op_sel:[0,0,1] op_sel_hi:[1,0,0]
	v_pk_add_f32 v[62:63], v[38:39], v[46:47]
	v_pk_add_f32 v[66:67], v[20:21], v[22:23]
	v_pk_add_f32 v[20:21], v[20:21], v[22:23] neg_lo:[0,1] neg_hi:[0,1]
	v_pk_add_f32 v[22:23], v[44:45], v[56:57]
	v_pk_add_f32 v[44:45], v[44:45], v[56:57] neg_lo:[0,1] neg_hi:[0,1]
	v_pk_add_f32 v[8:9], v[4:5], v[24:25] op_sel:[0,1] op_sel_hi:[1,0] neg_hi:[0,1]
	v_pk_add_f32 v[4:5], v[4:5], v[24:25] op_sel:[0,1] op_sel_hi:[1,0] neg_lo:[0,1]
	v_pk_add_f32 v[24:25], v[6:7], v[10:11]
	v_pk_add_f32 v[10:11], v[6:7], v[10:11] neg_lo:[0,1] neg_hi:[0,1]
	v_pk_add_f32 v[26:27], v[58:59], v[62:63]
	v_pk_add_f32 v[58:59], v[58:59], v[62:63] neg_lo:[0,1] neg_hi:[0,1]
	v_pk_add_f32 v[62:63], v[60:61], v[64:65]
	v_pk_add_f32 v[60:61], v[60:61], v[64:65] neg_lo:[0,1] neg_hi:[0,1]
	v_xor_b32_e32 v57, 0x80000000, v44
	v_mov_b32_e32 v56, v45
	v_xor_b32_e32 v65, 0x80000000, v60
	v_pk_add_f32 v[130:131], v[26:27], v[62:63]
	v_pk_add_f32 v[92:93], v[26:27], v[62:63] neg_lo:[0,1] neg_hi:[0,1]
	v_mov_b32_e32 v64, v61
	v_pk_add_f32 v[62:63], v[20:21], v[56:57]
	v_pk_add_f32 v[78:79], v[20:21], v[56:57] neg_lo:[0,1] neg_hi:[0,1]
	v_pk_add_f32 v[56:57], v[4:5], v[10:11] op_sel:[0,1] op_sel_hi:[1,0] neg_hi:[0,1]
	v_pk_add_f32 v[90:91], v[4:5], v[10:11] op_sel:[0,1] op_sel_hi:[1,0] neg_lo:[0,1]
	v_pk_add_f32 v[10:11], v[14:15], v[50:51] neg_lo:[0,1] neg_hi:[0,1]
	v_pk_add_f32 v[46:47], v[38:39], v[46:47] neg_lo:[0,1] neg_hi:[0,1]
	v_pk_add_f32 v[84:85], v[58:59], v[64:65]
	v_pk_add_f32 v[86:87], v[58:59], v[64:65] neg_lo:[0,1] neg_hi:[0,1]
	v_pk_add_f32 v[80:81], v[8:9], v[24:25]
	v_pk_add_f32 v[64:65], v[8:9], v[24:25] neg_lo:[0,1] neg_hi:[0,1]
	v_pk_add_f32 v[4:5], v[12:13], v[48:49]
	v_pk_add_f32 v[6:7], v[12:13], v[48:49] neg_lo:[0,1] neg_hi:[0,1]
	v_pk_add_f32 v[8:9], v[14:15], v[50:51]
	v_pk_mul_f32 v[12:13], v[10:11], s[24:25]
	v_pk_add_f32 v[14:15], v[16:17], v[52:53] neg_lo:[0,1] neg_hi:[0,1]
	v_pk_fma_f32 v[10:11], v[10:11], s[22:23], v[12:13] op_sel:[0,0,1] op_sel_hi:[1,0,0]
	v_pk_add_f32 v[12:13], v[16:17], v[52:53]
	v_pk_mul_f32 v[16:17], v[14:15], s[40:41]
	v_pk_add_f32 v[38:39], v[42:43], v[46:47] op_sel:[0,1] op_sel_hi:[1,0] neg_hi:[0,1]
	v_pk_add_f32 v[42:43], v[42:43], v[46:47] op_sel:[0,1] op_sel_hi:[1,0] neg_lo:[0,1]
	v_pk_add_f32 v[46:47], v[36:37], v[40:41]
	v_pk_fma_f32 v[14:15], v[14:15], s[38:39], v[16:17] op_sel:[0,0,1] op_sel_hi:[1,0,0]
	v_pk_add_f32 v[16:17], v[18:19], v[54:55]
	v_pk_add_f32 v[18:19], v[18:19], v[54:55] neg_lo:[0,1] neg_hi:[0,1]
	v_pk_add_f32 v[88:89], v[38:39], v[46:47]
	v_pk_add_f32 v[68:69], v[38:39], v[46:47] neg_lo:[0,1] neg_hi:[0,1]
	v_pk_add_f32 v[96:97], v[66:67], v[22:23]
	v_pk_add_f32 v[46:47], v[66:67], v[22:23] neg_lo:[0,1] neg_hi:[0,1]
	v_pk_mul_f32 v[20:21], v[18:19], s[44:45]
	s_waitcnt lgkmcnt(1)
	v_pk_add_f32 v[24:25], v[28:29], v[70:71] neg_lo:[0,1] neg_hi:[0,1]
	v_pk_add_f32 v[26:27], v[30:31], v[72:73] neg_lo:[0,1] neg_hi:[0,1]
	v_pk_fma_f32 v[18:19], v[18:19], s[50:51], v[20:21] op_sel:[0,0,1] op_sel_hi:[1,0,0]
	v_pk_add_f32 v[20:21], v[28:29], v[70:71]
	v_pk_add_f32 v[22:23], v[30:31], v[72:73]
	v_pk_mul_f32 v[28:29], v[26:27], s[44:45]
	s_waitcnt lgkmcnt(0)
	v_pk_add_f32 v[30:31], v[32:33], v[98:99] neg_lo:[0,1] neg_hi:[0,1]
	v_pk_fma_f32 v[26:27], v[26:27], s[50:51], v[28:29] op_sel:[0,0,1] op_sel_hi:[1,0,0] neg_lo:[1,0,0] neg_hi:[1,0,0]
	v_pk_add_f32 v[28:29], v[32:33], v[98:99]
	v_pk_mul_f32 v[32:33], v[30:31], s[40:41]
	v_pk_add_f32 v[36:37], v[36:37], v[40:41] neg_lo:[0,1] neg_hi:[0,1]
	v_pk_fma_f32 v[30:31], v[30:31], s[38:39], v[32:33] op_sel:[0,0,1] op_sel_hi:[1,0,0] neg_lo:[1,0,0] neg_hi:[1,0,0]
	v_pk_add_f32 v[32:33], v[34:35], v[100:101]
	v_pk_add_f32 v[34:35], v[34:35], v[100:101] neg_lo:[0,1] neg_hi:[0,1]
	v_xor_b32_e32 v41, 0x80000000, v36
	v_mov_b32_e32 v40, v37
	v_pk_mul_f32 v[36:37], v[34:35], s[24:25]
	v_mov_b32_e32 v2, v130
	v_pk_fma_f32 v[34:35], v[34:35], s[22:23], v[36:37] op_sel:[0,0,1] op_sel_hi:[1,0,0] neg_lo:[1,0,0] neg_hi:[1,0,0]
	v_pk_add_f32 v[36:37], v[4:5], v[20:21]
	v_pk_add_f32 v[4:5], v[4:5], v[20:21] neg_lo:[0,1] neg_hi:[0,1]
	v_pk_add_f32 v[20:21], v[8:9], v[22:23]
	v_pk_add_f32 v[8:9], v[8:9], v[22:23] neg_lo:[0,1] neg_hi:[0,1]
	v_cmp_ne_u32_e64 s[0:1], 0, v144
	v_pk_mul_f32 v[22:23], v[8:9], s[40:41]
	v_pk_add_f32 v[74:75], v[42:43], v[40:41]
	v_pk_fma_f32 v[8:9], v[8:9], s[38:39], v[22:23] op_sel:[0,0,1] op_sel_hi:[1,0,0]
	v_pk_add_f32 v[22:23], v[12:13], v[28:29]
	v_pk_add_f32 v[28:29], v[12:13], v[28:29] neg_lo:[0,1] neg_hi:[0,1]
	v_pk_add_f32 v[94:95], v[42:43], v[40:41] neg_lo:[0,1] neg_hi:[0,1]
	v_pk_add_f32 v[12:13], v[16:17], v[32:33]
	v_pk_add_f32 v[16:17], v[16:17], v[32:33] neg_lo:[0,1] neg_hi:[0,1]
	s_nop 0
	v_pk_mul_f32 v[32:33], v[16:17], s[40:41]
	s_nop 0
	v_pk_fma_f32 v[16:17], v[16:17], s[38:39], v[32:33] op_sel:[0,0,1] op_sel_hi:[1,0,0] neg_lo:[1,0,0] neg_hi:[1,0,0]
	v_pk_add_f32 v[32:33], v[6:7], v[24:25] op_sel:[0,1] op_sel_hi:[1,0] neg_hi:[0,1]
	v_pk_add_f32 v[6:7], v[6:7], v[24:25] op_sel:[0,1] op_sel_hi:[1,0] neg_lo:[0,1]
	v_pk_add_f32 v[24:25], v[10:11], v[26:27]
	v_pk_add_f32 v[10:11], v[10:11], v[26:27] neg_lo:[0,1] neg_hi:[0,1]
	s_nop 0
	v_pk_mul_f32 v[26:27], v[10:11], s[40:41]
	s_nop 0
	v_pk_fma_f32 v[10:11], v[10:11], s[38:39], v[26:27] op_sel:[0,0,1] op_sel_hi:[1,0,0]
	v_pk_add_f32 v[26:27], v[14:15], v[30:31]
	v_pk_add_f32 v[30:31], v[14:15], v[30:31] neg_lo:[0,1] neg_hi:[0,1]
	s_nop 0
	v_pk_add_f32 v[14:15], v[18:19], v[34:35]
	v_pk_add_f32 v[18:19], v[18:19], v[34:35] neg_lo:[0,1] neg_hi:[0,1]
	s_nop 0
	v_pk_mul_f32 v[34:35], v[18:19], s[40:41]
	s_nop 0
	v_pk_fma_f32 v[18:19], v[18:19], s[38:39], v[34:35] op_sel:[0,0,1] op_sel_hi:[1,0,0] neg_lo:[1,0,0] neg_hi:[1,0,0]
	v_pk_add_f32 v[34:35], v[36:37], v[22:23]
	v_pk_add_f32 v[22:23], v[36:37], v[22:23] neg_lo:[0,1] neg_hi:[0,1]
	v_pk_add_f32 v[36:37], v[20:21], v[12:13]
	v_pk_add_f32 v[12:13], v[20:21], v[12:13] neg_lo:[0,1] neg_hi:[0,1]
	v_pk_add_f32 v[98:99], v[34:35], v[36:37]
	v_xor_b32_e32 v21, 0x80000000, v12
	v_mov_b32_e32 v20, v13
	v_pk_add_f32 v[12:13], v[4:5], v[28:29] op_sel:[0,1] op_sel_hi:[1,0] neg_hi:[0,1]
	v_pk_add_f32 v[4:5], v[4:5], v[28:29] op_sel:[0,1] op_sel_hi:[1,0] neg_lo:[0,1]
	v_pk_add_f32 v[28:29], v[8:9], v[16:17]
	v_pk_add_f32 v[8:9], v[8:9], v[16:17] neg_lo:[0,1] neg_hi:[0,1]
	v_pk_add_f32 v[100:101], v[34:35], v[36:37] neg_lo:[0,1] neg_hi:[0,1]
	v_xor_b32_e32 v17, 0x80000000, v8
	v_mov_b32_e32 v16, v9
	v_pk_add_f32 v[8:9], v[32:33], v[26:27]
	v_pk_add_f32 v[26:27], v[32:33], v[26:27] neg_lo:[0,1] neg_hi:[0,1]
	v_pk_add_f32 v[32:33], v[24:25], v[14:15]
	v_pk_add_f32 v[14:15], v[24:25], v[14:15] neg_lo:[0,1] neg_hi:[0,1]
	v_pk_add_f32 v[102:103], v[22:23], v[20:21]
	v_xor_b32_e32 v25, 0x80000000, v14
	v_mov_b32_e32 v24, v15
	v_pk_add_f32 v[14:15], v[6:7], v[30:31] op_sel:[0,1] op_sel_hi:[1,0] neg_hi:[0,1]
	v_pk_add_f32 v[6:7], v[6:7], v[30:31] op_sel:[0,1] op_sel_hi:[1,0] neg_lo:[0,1]
	v_pk_add_f32 v[30:31], v[10:11], v[18:19]
	v_pk_add_f32 v[10:11], v[10:11], v[18:19] neg_lo:[0,1] neg_hi:[0,1]
	v_pk_add_f32 v[104:105], v[22:23], v[20:21] neg_lo:[0,1] neg_hi:[0,1]
	v_xor_b32_e32 v19, 0x80000000, v10
	v_mov_b32_e32 v18, v11
	v_pk_add_f32 v[106:107], v[12:13], v[28:29]
	v_pk_add_f32 v[108:109], v[12:13], v[28:29] neg_lo:[0,1] neg_hi:[0,1]
	v_pk_add_f32 v[110:111], v[4:5], v[16:17]
	v_pk_add_f32 v[112:113], v[4:5], v[16:17] neg_lo:[0,1] neg_hi:[0,1]
	v_pk_add_f32 v[114:115], v[8:9], v[32:33]
	v_pk_add_f32 v[116:117], v[8:9], v[32:33] neg_lo:[0,1] neg_hi:[0,1]
	v_pk_add_f32 v[118:119], v[26:27], v[24:25]
	v_pk_add_f32 v[120:121], v[26:27], v[24:25] neg_lo:[0,1] neg_hi:[0,1]
	v_pk_add_f32 v[122:123], v[14:15], v[30:31]
	v_pk_add_f32 v[124:125], v[14:15], v[30:31] neg_lo:[0,1] neg_hi:[0,1]
	v_pk_add_f32 v[126:127], v[6:7], v[18:19]
	v_pk_add_f32 v[128:129], v[6:7], v[18:19] neg_lo:[0,1] neg_hi:[0,1]
	v_mov_b32_e32 v4, v131
	v_mov_b32_e32 v5, v3
	v_mov_b64_e32 v[6:7], v[2:3]
	s_and_saveexec_b64 s[50:51], s[0:1]
	s_xor_b64 s[0:1], exec, s[50:51]
	s_cbranch_execz .LBB0_562
	v_pk_add_f32 v[4:5], v[96:97], v[112:113]
	v_pk_add_f32 v[24:25], v[96:97], v[112:113] neg_lo:[0,1] neg_hi:[0,1]
	v_pk_add_f32 v[148:149], v[130:131], v[128:129]
	v_pk_add_f32 v[8:9], v[130:131], v[128:129] neg_lo:[0,1] neg_hi:[0,1]
	v_pk_add_f32 v[128:129], v[126:127], v[92:93]
	v_pk_add_f32 v[10:11], v[126:127], v[92:93] neg_lo:[0,1] neg_hi:[0,1]
	v_pk_add_f32 v[92:93], v[84:85], v[124:125]
	v_pk_add_f32 v[12:13], v[84:85], v[124:125] neg_lo:[0,1] neg_hi:[0,1]
	v_pk_add_f32 v[84:85], v[122:123], v[86:87]
	v_pk_add_f32 v[14:15], v[122:123], v[86:87] neg_lo:[0,1] neg_hi:[0,1]
	v_pk_add_f32 v[86:87], v[88:89], v[120:121]
	v_pk_add_f32 v[16:17], v[88:89], v[120:121] neg_lo:[0,1] neg_hi:[0,1]
	v_pk_add_f32 v[88:89], v[118:119], v[68:69]
	v_pk_add_f32 v[18:19], v[118:119], v[68:69] neg_lo:[0,1] neg_hi:[0,1]
	v_pk_add_f32 v[68:69], v[74:75], v[116:117]
	v_pk_add_f32 v[20:21], v[74:75], v[116:117] neg_lo:[0,1] neg_hi:[0,1]
	v_pk_add_f32 v[74:75], v[114:115], v[94:95]
	v_pk_add_f32 v[22:23], v[114:115], v[94:95] neg_lo:[0,1] neg_hi:[0,1]
	v_mov_b32_e32 v6, v4
	v_mov_b32_e32 v7, v25
	v_pk_mov_b32 v[4:5], v[4:5], v[24:25] op_sel:[1,0]
	v_pk_add_f32 v[94:95], v[110:111], v[46:47]
	v_pk_add_f32 v[24:25], v[110:111], v[46:47] neg_lo:[0,1] neg_hi:[0,1]
	v_pk_add_f32 v[46:47], v[62:63], v[108:109]
	v_pk_add_f32 v[26:27], v[62:63], v[108:109] neg_lo:[0,1] neg_hi:[0,1]
	v_pk_add_f32 v[62:63], v[106:107], v[78:79]
	v_pk_add_f32 v[28:29], v[106:107], v[78:79] neg_lo:[0,1] neg_hi:[0,1]
	v_pk_add_f32 v[78:79], v[80:81], v[104:105]
	v_pk_add_f32 v[30:31], v[80:81], v[104:105] neg_lo:[0,1] neg_hi:[0,1]
	v_pk_add_f32 v[80:81], v[102:103], v[64:65]
	v_pk_add_f32 v[32:33], v[102:103], v[64:65] neg_lo:[0,1] neg_hi:[0,1]
	v_pk_add_f32 v[64:65], v[56:57], v[100:101]
	v_pk_add_f32 v[34:35], v[56:57], v[100:101] neg_lo:[0,1] neg_hi:[0,1]
	v_pk_add_f32 v[56:57], v[98:99], v[90:91]
	v_pk_add_f32 v[36:37], v[98:99], v[90:91] neg_lo:[0,1] neg_hi:[0,1]
	v_pk_mul_f32 v[6:7], v[6:7], 0.5 op_sel_hi:[1,0]
	v_pk_mul_f32 v[4:5], v[4:5], s[46:47]
	v_mov_b32_e32 v39, v8
	v_mov_b32_e32 v38, v149
	v_mov_b32_e32 v41, v10
	v_mov_b32_e32 v40, v129
	v_mov_b32_e32 v43, v12
	v_mov_b32_e32 v42, v93
	v_mov_b32_e32 v45, v14
	v_mov_b32_e32 v44, v85
	v_mov_b32_e32 v49, v16
	v_mov_b32_e32 v48, v87
	v_mov_b32_e32 v51, v18
	v_mov_b32_e32 v50, v89
	v_mov_b32_e32 v53, v20
	v_mov_b32_e32 v52, v69
	v_mov_b32_e32 v55, v22
	v_mov_b32_e32 v54, v75
	v_mov_b32_e32 v59, v24
	v_mov_b32_e32 v58, v95
	v_mov_b32_e32 v61, v26
	v_mov_b32_e32 v60, v47
	v_mov_b32_e32 v67, v28
	v_mov_b32_e32 v66, v63
	v_mov_b32_e32 v71, v30
	v_mov_b32_e32 v70, v79
	v_mov_b32_e32 v73, v32
	v_mov_b32_e32 v72, v81
	v_mov_b32_e32 v77, v34
	v_mov_b32_e32 v76, v65
	v_mov_b32_e32 v83, v36
	v_mov_b32_e32 v82, v57
	v_mov_b32_e32 v8, v148
	v_mov_b32_e32 v10, v128
	v_mov_b32_e32 v12, v92
	v_mov_b32_e32 v14, v84
	v_mov_b32_e32 v16, v86
	v_mov_b32_e32 v18, v88
	v_mov_b32_e32 v20, v68
	v_mov_b32_e32 v22, v74
	v_mov_b32_e32 v24, v94
	v_mov_b32_e32 v26, v46
	v_mov_b32_e32 v28, v62
	v_mov_b32_e32 v30, v78
	v_mov_b32_e32 v32, v80
	v_mov_b32_e32 v34, v64
	v_mov_b32_e32 v36, v56

.LBB0_574:
	s_or_b64 exec, exec, s[0:1]
	v_mov_b32_e32 v2, v142
	s_waitcnt lgkmcnt(0)
	s_barrier
	s_mov_b32 s19, s16
	v_and_b32_e32 v4, 0xff, v2
	v_lshlrev_b32_e32 v5, 5, v2
	v_and_or_b32 v4, v5, s68, v4
	v_ashrrev_i32_e32 v5, 5, v4
	v_cvt_f32_ubyte0_e32 v2, v2
	v_lshlrev_b32_e32 v7, 3, v4
	v_mul_f32_e32 v2, 0x39000000, v2
	v_lshlrev_b32_e32 v5, 3, v5
	v_sin_f32_e32 v4, v2
	v_cos_f32_e32 v6, v2
	v_add3_u32 v2, 0, v7, v5
	ds_read_b64 v[128:129], v2
	ds_read_b64 v[130:131], v2 offset:2112
	ds_read_b64 v[144:145], v2 offset:4224
	ds_read_b64 v[148:149], v2 offset:6336
	ds_read_b64 v[150:151], v2 offset:8448
	ds_read_b64 v[152:153], v2 offset:10560
	ds_read_b64 v[154:155], v2 offset:12672
	ds_read_b64 v[156:157], v2 offset:14784
	ds_read_b64 v[158:159], v2 offset:16896
	ds_read_b64 v[160:161], v2 offset:19008
	ds_read_b64 v[162:163], v2 offset:21120
	ds_read_b64 v[164:165], v2 offset:23232
	ds_read_b64 v[166:167], v2 offset:25344
	ds_read_b64 v[168:169], v2 offset:27456
	ds_read_b64 v[170:171], v2 offset:29568
	ds_read_b64 v[172:173], v2 offset:31680
	ds_read_b64 v[174:175], v2 offset:33792
	ds_read_b64 v[176:177], v2 offset:35904
	ds_read_b64 v[178:179], v2 offset:38016
	ds_read_b64 v[180:181], v2 offset:40128
	ds_read_b64 v[182:183], v2 offset:42240
	ds_read_b64 v[184:185], v2 offset:44352
	ds_read_b64 v[186:187], v2 offset:46464
	ds_read_b64 v[188:189], v2 offset:48576
	ds_read_b64 v[190:191], v2 offset:50688
	ds_read_b64 v[192:193], v2 offset:52800
	ds_read_b64 v[194:195], v2 offset:54912
	ds_read_b64 v[196:197], v2 offset:57024
	ds_read_b64 v[198:199], v2 offset:59136
	ds_read_b64 v[204:205], v2 offset:61248
	ds_read_b64 v[206:207], v2 offset:63360
	ds_read_b64 v[208:209], v2 offset:65472
	s_waitcnt lgkmcnt(14)
	v_pk_add_f32 v[210:211], v[128:129], v[174:175]
	v_pk_add_f32 v[128:129], v[128:129], v[174:175] neg_lo:[0,1] neg_hi:[0,1]
	v_pk_add_f32 v[174:175], v[130:131], v[176:177]
	v_pk_add_f32 v[130:131], v[130:131], v[176:177] neg_lo:[0,1] neg_hi:[0,1]
	s_mov_b32 s0, s9
	v_pk_mul_f32 v[176:177], v[130:131], s[18:19]
	s_mov_b32 s41, s38
	v_pk_fma_f32 v[130:131], v[130:131], s[0:1], v[176:177] op_sel:[0,0,1] op_sel_hi:[1,0,0]
	s_waitcnt lgkmcnt(13)
	v_pk_add_f32 v[176:177], v[144:145], v[178:179]
	v_pk_add_f32 v[144:145], v[144:145], v[178:179] neg_lo:[0,1] neg_hi:[0,1]
	s_mov_b32 s43, s26
	v_pk_mul_f32 v[178:179], v[144:145], s[24:25]
	s_mov_b32 s62, s37
	v_pk_fma_f32 v[144:145], v[144:145], s[22:23], v[178:179] op_sel:[0,0,1] op_sel_hi:[1,0,0]
	s_waitcnt lgkmcnt(12)
	v_pk_add_f32 v[178:179], v[148:149], v[180:181]
	v_pk_add_f32 v[148:149], v[148:149], v[180:181] neg_lo:[0,1] neg_hi:[0,1]
	s_mov_b32 s45, s22
	v_pk_mul_f32 v[180:181], v[148:149], s[36:37]
	s_mov_b32 s50, s25
	v_pk_fma_f32 v[148:149], v[148:149], s[26:27], v[180:181] op_sel:[0,0,1] op_sel_hi:[1,0,0]
	s_waitcnt lgkmcnt(11)
	v_pk_add_f32 v[180:181], v[150:151], v[182:183]
	v_pk_add_f32 v[150:151], v[150:151], v[182:183] neg_lo:[0,1] neg_hi:[0,1]
	v_xor_b32_e32 v7, 0x80000000, v4
	v_pk_mul_f32 v[182:183], v[150:151], s[40:41]
	v_mov_b32_e32 v5, v7
	v_pk_fma_f32 v[150:151], v[150:151], s[38:39], v[182:183] op_sel:[0,0,1] op_sel_hi:[1,0,0]
	s_waitcnt lgkmcnt(10)
	v_pk_add_f32 v[182:183], v[152:153], v[184:185]
	v_pk_add_f32 v[152:153], v[152:153], v[184:185] neg_lo:[0,1] neg_hi:[0,1]
	v_pk_mul_f32 v[8:9], v[6:7], v[4:5] op_sel:[1,0] op_sel_hi:[0,1]
	v_pk_mul_f32 v[184:185], v[152:153], s[42:43]
	v_pk_fma_f32 v[8:9], v[6:7], v[6:7], v[8:9] op_sel_hi:[1,0,1]
	v_pk_fma_f32 v[152:153], v[152:153], s[62:63], v[184:185] op_sel:[0,0,1] op_sel_hi:[1,0,0]
	s_waitcnt lgkmcnt(9)
	v_pk_add_f32 v[184:185], v[154:155], v[186:187]
	v_pk_add_f32 v[154:155], v[154:155], v[186:187] neg_lo:[0,1] neg_hi:[0,1]
	v_pk_mul_f32 v[186:187], v[154:155], s[44:45]
	v_pk_fma_f32 v[154:155], v[154:155], s[50:51], v[186:187] op_sel:[0,0,1] op_sel_hi:[1,0,0]
	s_waitcnt lgkmcnt(8)
	v_pk_add_f32 v[186:187], v[156:157], v[188:189]
	v_pk_add_f32 v[156:157], v[156:157], v[188:189] neg_lo:[0,1] neg_hi:[0,1]
	v_pk_mul_f32 v[12:13], v[8:9], v[8:9] op_sel:[1,1] op_sel_hi:[0,1] neg_lo:[0,1]
	v_pk_mul_f32 v[188:189], v[156:157], s[8:9]
	v_pk_fma_f32 v[12:13], v[8:9], v[8:9], v[12:13] op_sel_hi:[1,0,1]
	v_pk_fma_f32 v[156:157], v[156:157], s[16:17], v[188:189] op_sel:[0,0,1] op_sel_hi:[1,0,0]
	s_waitcnt lgkmcnt(7)
	v_pk_add_f32 v[188:189], v[158:159], v[190:191]
	v_pk_add_f32 v[190:191], v[158:159], v[190:191] neg_lo:[0,1] neg_hi:[0,1]
	s_waitcnt lgkmcnt(6)
	v_pk_add_f32 v[158:159], v[160:161], v[192:193]
	v_pk_add_f32 v[160:161], v[160:161], v[192:193] neg_lo:[0,1] neg_hi:[0,1]
	v_pk_mul_f32 v[192:193], v[160:161], s[8:9]
	v_pk_mul_f32 v[28:29], v[12:13], v[12:13] op_sel:[1,1] op_sel_hi:[0,1] neg_lo:[0,1]
	v_pk_fma_f32 v[160:161], v[160:161], s[16:17], v[192:193] op_sel:[0,0,1] op_sel_hi:[1,0,0] neg_lo:[1,0,0] neg_hi:[1,0,0]
	s_waitcnt lgkmcnt(5)
	v_pk_add_f32 v[192:193], v[162:163], v[194:195]
	v_pk_add_f32 v[162:163], v[162:163], v[194:195] neg_lo:[0,1] neg_hi:[0,1]
	v_pk_fma_f32 v[28:29], v[12:13], v[12:13], v[28:29] op_sel_hi:[1,0,1]
	v_pk_mul_f32 v[194:195], v[162:163], s[44:45]
	v_pk_mul_f32 v[44:45], v[12:13], v[28:29] op_sel:[1,1] op_sel_hi:[1,0] neg_lo:[1,0]
	v_pk_fma_f32 v[162:163], v[162:163], s[50:51], v[194:195] op_sel:[0,0,1] op_sel_hi:[1,0,0] neg_lo:[1,0,0] neg_hi:[1,0,0]
	s_waitcnt lgkmcnt(4)
	v_pk_add_f32 v[194:195], v[164:165], v[196:197]
	v_pk_add_f32 v[164:165], v[164:165], v[196:197] neg_lo:[0,1] neg_hi:[0,1]
	v_pk_fma_f32 v[44:45], v[12:13], v[28:29], v[44:45] op_sel_hi:[0,1,1]
	v_pk_mul_f32 v[196:197], v[164:165], s[42:43]
	v_pk_mul_f32 v[60:61], v[12:13], v[44:45] op_sel:[1,1] op_sel_hi:[1,0] neg_lo:[1,0]
	v_pk_fma_f32 v[164:165], v[164:165], s[62:63], v[196:197] op_sel:[0,0,1] op_sel_hi:[1,0,0] neg_lo:[1,0,0] neg_hi:[1,0,0]
	s_waitcnt lgkmcnt(3)
	v_pk_add_f32 v[196:197], v[166:167], v[198:199]
	v_pk_add_f32 v[166:167], v[166:167], v[198:199] neg_lo:[0,1] neg_hi:[0,1]
	v_pk_fma_f32 v[60:61], v[12:13], v[44:45], v[60:61] op_sel_hi:[0,1,1]
	v_pk_mul_f32 v[198:199], v[166:167], s[40:41]
	v_pk_mul_f32 v[76:77], v[12:13], v[60:61] op_sel:[1,1] op_sel_hi:[1,0] neg_lo:[1,0]
	v_pk_fma_f32 v[166:167], v[166:167], s[38:39], v[198:199] op_sel:[0,0,1] op_sel_hi:[1,0,0] neg_lo:[1,0,0] neg_hi:[1,0,0]
	s_waitcnt lgkmcnt(2)
	v_pk_add_f32 v[198:199], v[168:169], v[204:205]
	v_pk_add_f32 v[168:169], v[168:169], v[204:205] neg_lo:[0,1] neg_hi:[0,1]
	v_pk_fma_f32 v[76:77], v[12:13], v[60:61], v[76:77] op_sel_hi:[0,1,1]
	v_pk_mul_f32 v[204:205], v[168:169], s[36:37]
	v_pk_mul_f32 v[92:93], v[12:13], v[76:77] op_sel:[1,1] op_sel_hi:[1,0] neg_lo:[1,0]
	v_pk_fma_f32 v[168:169], v[168:169], s[26:27], v[204:205] op_sel:[0,0,1] op_sel_hi:[1,0,0] neg_lo:[1,0,0] neg_hi:[1,0,0]
	s_waitcnt lgkmcnt(1)
	v_pk_add_f32 v[204:205], v[170:171], v[206:207]
	v_pk_add_f32 v[170:171], v[170:171], v[206:207] neg_lo:[0,1] neg_hi:[0,1]
	v_pk_fma_f32 v[92:93], v[12:13], v[76:77], v[92:93] op_sel_hi:[0,1,1]
	v_pk_mul_f32 v[206:207], v[170:171], s[24:25]
	v_pk_mul_f32 v[108:109], v[12:13], v[92:93] op_sel:[1,1] op_sel_hi:[1,0] neg_lo:[1,0]
	v_pk_fma_f32 v[170:171], v[170:171], s[22:23], v[206:207] op_sel:[0,0,1] op_sel_hi:[1,0,0] neg_lo:[1,0,0] neg_hi:[1,0,0]
	s_waitcnt lgkmcnt(0)
	v_pk_add_f32 v[206:207], v[172:173], v[208:209]
	v_pk_add_f32 v[172:173], v[172:173], v[208:209] neg_lo:[0,1] neg_hi:[0,1]
	v_pk_mul_f32 v[10:11], v[4:5], v[8:9] op_sel:[0,1] op_sel_hi:[1,0]
	v_pk_mul_f32 v[208:209], v[172:173], s[18:19]
	v_pk_fma_f32 v[108:109], v[12:13], v[92:93], v[108:109] op_sel_hi:[0,1,1]
	v_pk_fma_f32 v[172:173], v[172:173], s[0:1], v[208:209] op_sel:[0,0,1] op_sel_hi:[1,0,0] neg_lo:[1,0,0] neg_hi:[1,0,0]
	v_pk_add_f32 v[208:209], v[210:211], v[188:189]
	v_pk_add_f32 v[188:189], v[210:211], v[188:189] neg_lo:[0,1] neg_hi:[0,1]
	v_pk_add_f32 v[210:211], v[174:175], v[158:159]
	v_pk_add_f32 v[158:159], v[174:175], v[158:159] neg_lo:[0,1] neg_hi:[0,1]
	v_pk_fma_f32 v[10:11], v[6:7], v[8:9], v[10:11] op_sel_hi:[0,1,1]
	v_pk_mul_f32 v[174:175], v[158:159], s[24:25]
	v_pk_mul_f32 v[18:19], v[4:5], v[12:13] op_sel:[0,1] op_sel_hi:[1,0]
	v_pk_fma_f32 v[158:159], v[158:159], s[22:23], v[174:175] op_sel:[0,0,1] op_sel_hi:[1,0,0]
	v_pk_add_f32 v[174:175], v[176:177], v[192:193]
	v_pk_add_f32 v[176:177], v[176:177], v[192:193] neg_lo:[0,1] neg_hi:[0,1]
	v_pk_mul_f32 v[32:33], v[4:5], v[28:29] op_sel:[0,1] op_sel_hi:[1,0]
	v_pk_mul_f32 v[192:193], v[176:177], s[40:41]
	v_pk_mul_f32 v[48:49], v[4:5], v[44:45] op_sel:[0,1] op_sel_hi:[1,0]
	v_pk_fma_f32 v[176:177], v[176:177], s[38:39], v[192:193] op_sel:[0,0,1] op_sel_hi:[1,0,0]
	v_pk_add_f32 v[192:193], v[178:179], v[194:195]
	v_pk_add_f32 v[178:179], v[178:179], v[194:195] neg_lo:[0,1] neg_hi:[0,1]
	v_pk_mul_f32 v[64:65], v[4:5], v[60:61] op_sel:[0,1] op_sel_hi:[1,0]
	v_pk_mul_f32 v[194:195], v[178:179], s[44:45]
	v_pk_mul_f32 v[80:81], v[4:5], v[76:77] op_sel:[0,1] op_sel_hi:[1,0]
	v_pk_fma_f32 v[178:179], v[178:179], s[50:51], v[194:195] op_sel:[0,0,1] op_sel_hi:[1,0,0]
	v_pk_add_f32 v[194:195], v[180:181], v[196:197]
	v_pk_add_f32 v[196:197], v[180:181], v[196:197] neg_lo:[0,1] neg_hi:[0,1]
	v_pk_mul_f32 v[96:97], v[4:5], v[92:93] op_sel:[0,1] op_sel_hi:[1,0]
	v_pk_add_f32 v[180:181], v[182:183], v[198:199]
	v_pk_add_f32 v[182:183], v[182:183], v[198:199] neg_lo:[0,1] neg_hi:[0,1]
	v_pk_mul_f32 v[112:113], v[4:5], v[108:109] op_sel:[0,1] op_sel_hi:[1,0]
	v_pk_mul_f32 v[198:199], v[182:183], s[44:45]
	v_pk_fma_f32 v[182:183], v[182:183], s[50:51], v[198:199] op_sel:[0,0,1] op_sel_hi:[1,0,0] neg_lo:[1,0,0] neg_hi:[1,0,0]
	v_pk_add_f32 v[198:199], v[184:185], v[204:205]
	v_pk_add_f32 v[184:185], v[184:185], v[204:205] neg_lo:[0,1] neg_hi:[0,1]
	v_pk_mul_f32 v[204:205], v[184:185], s[40:41]
	v_pk_fma_f32 v[18:19], v[6:7], v[12:13], v[18:19] op_sel_hi:[0,1,1]
	v_pk_fma_f32 v[184:185], v[184:185], s[38:39], v[204:205] op_sel:[0,0,1] op_sel_hi:[1,0,0] neg_lo:[1,0,0] neg_hi:[1,0,0]
	v_pk_add_f32 v[204:205], v[186:187], v[206:207]
	v_pk_add_f32 v[186:187], v[186:187], v[206:207] neg_lo:[0,1] neg_hi:[0,1]
	v_pk_mul_f32 v[20:21], v[8:9], v[12:13] op_sel:[1,1] op_sel_hi:[1,0] neg_lo:[1,0]
	v_pk_mul_f32 v[206:207], v[186:187], s[24:25]
	v_pk_fma_f32 v[32:33], v[6:7], v[28:29], v[32:33] op_sel_hi:[0,1,1]
	v_pk_fma_f32 v[186:187], v[186:187], s[22:23], v[206:207] op_sel:[0,0,1] op_sel_hi:[1,0,0] neg_lo:[1,0,0] neg_hi:[1,0,0]
	v_pk_add_f32 v[206:207], v[128:129], v[190:191] op_sel:[0,1] op_sel_hi:[1,0] neg_hi:[0,1]
	v_pk_add_f32 v[128:129], v[128:129], v[190:191] op_sel:[0,1] op_sel_hi:[1,0] neg_lo:[0,1]
	v_pk_add_f32 v[190:191], v[130:131], v[160:161]
	v_pk_add_f32 v[130:131], v[130:131], v[160:161] neg_lo:[0,1] neg_hi:[0,1]
	v_pk_mul_f32 v[36:37], v[8:9], v[28:29] op_sel:[1,1] op_sel_hi:[1,0] neg_lo:[1,0]
	v_pk_mul_f32 v[160:161], v[130:131], s[24:25]
	v_pk_fma_f32 v[48:49], v[6:7], v[44:45], v[48:49] op_sel_hi:[0,1,1]
	v_pk_fma_f32 v[130:131], v[130:131], s[22:23], v[160:161] op_sel:[0,0,1] op_sel_hi:[1,0,0]
	v_pk_add_f32 v[160:161], v[144:145], v[162:163]
	v_pk_add_f32 v[144:145], v[144:145], v[162:163] neg_lo:[0,1] neg_hi:[0,1]
	v_pk_mul_f32 v[52:53], v[8:9], v[44:45] op_sel:[1,1] op_sel_hi:[1,0] neg_lo:[1,0]
	v_pk_mul_f32 v[162:163], v[144:145], s[40:41]
	v_pk_fma_f32 v[64:65], v[6:7], v[60:61], v[64:65] op_sel_hi:[0,1,1]
	v_pk_fma_f32 v[144:145], v[144:145], s[38:39], v[162:163] op_sel:[0,0,1] op_sel_hi:[1,0,0]
	v_pk_add_f32 v[162:163], v[148:149], v[164:165]
	v_pk_add_f32 v[148:149], v[148:149], v[164:165] neg_lo:[0,1] neg_hi:[0,1]
	v_pk_mul_f32 v[68:69], v[8:9], v[60:61] op_sel:[1,1] op_sel_hi:[1,0] neg_lo:[1,0]
	v_pk_mul_f32 v[164:165], v[148:149], s[44:45]
	v_pk_fma_f32 v[80:81], v[6:7], v[76:77], v[80:81] op_sel_hi:[0,1,1]
	v_pk_fma_f32 v[148:149], v[148:149], s[50:51], v[164:165] op_sel:[0,0,1] op_sel_hi:[1,0,0]
	v_pk_add_f32 v[164:165], v[150:151], v[166:167]
	v_pk_add_f32 v[166:167], v[150:151], v[166:167] neg_lo:[0,1] neg_hi:[0,1]
	v_pk_mul_f32 v[84:85], v[8:9], v[76:77] op_sel:[1,1] op_sel_hi:[1,0] neg_lo:[1,0]
	v_pk_add_f32 v[150:151], v[152:153], v[168:169]
	v_pk_add_f32 v[152:153], v[152:153], v[168:169] neg_lo:[0,1] neg_hi:[0,1]
	v_pk_fma_f32 v[96:97], v[6:7], v[92:93], v[96:97] op_sel_hi:[0,1,1]
	v_pk_mul_f32 v[168:169], v[152:153], s[44:45]
	v_pk_mul_f32 v[100:101], v[8:9], v[92:93] op_sel:[1,1] op_sel_hi:[1,0] neg_lo:[1,0]
	v_pk_fma_f32 v[152:153], v[152:153], s[50:51], v[168:169] op_sel:[0,0,1] op_sel_hi:[1,0,0] neg_lo:[1,0,0] neg_hi:[1,0,0]
	v_pk_add_f32 v[168:169], v[154:155], v[170:171]
	v_pk_add_f32 v[154:155], v[154:155], v[170:171] neg_lo:[0,1] neg_hi:[0,1]
	v_pk_fma_f32 v[112:113], v[6:7], v[108:109], v[112:113] op_sel_hi:[0,1,1]
	v_pk_mul_f32 v[170:171], v[154:155], s[40:41]
	v_pk_mul_f32 v[116:117], v[8:9], v[108:109] op_sel:[1,1] op_sel_hi:[1,0] neg_lo:[1,0]
	v_pk_fma_f32 v[154:155], v[154:155], s[38:39], v[170:171] op_sel:[0,0,1] op_sel_hi:[1,0,0] neg_lo:[1,0,0] neg_hi:[1,0,0]
	v_pk_add_f32 v[170:171], v[156:157], v[172:173]
	v_pk_add_f32 v[156:157], v[156:157], v[172:173] neg_lo:[0,1] neg_hi:[0,1]
	v_pk_fma_f32 v[20:21], v[8:9], v[12:13], v[20:21] op_sel_hi:[0,1,1]
	v_pk_mul_f32 v[172:173], v[156:157], s[24:25]
	v_pk_mul_f32 v[24:25], v[12:13], v[10:11] op_sel:[1,1] op_sel_hi:[0,1] neg_lo:[0,1]
	v_pk_fma_f32 v[156:157], v[156:157], s[22:23], v[172:173] op_sel:[0,0,1] op_sel_hi:[1,0,0] neg_lo:[1,0,0] neg_hi:[1,0,0]
	v_pk_add_f32 v[172:173], v[208:209], v[194:195]
	v_pk_add_f32 v[194:195], v[208:209], v[194:195] neg_lo:[0,1] neg_hi:[0,1]
	v_pk_add_f32 v[208:209], v[210:211], v[180:181]
	v_pk_add_f32 v[180:181], v[210:211], v[180:181] neg_lo:[0,1] neg_hi:[0,1]
	v_pk_fma_f32 v[36:37], v[8:9], v[28:29], v[36:37] op_sel_hi:[0,1,1]
	v_pk_mul_f32 v[210:211], v[180:181], s[40:41]
	v_pk_mul_f32 v[40:41], v[10:11], v[28:29] op_sel:[1,1] op_sel_hi:[1,0] neg_lo:[1,0]
	v_pk_fma_f32 v[180:181], v[180:181], s[38:39], v[210:211] op_sel:[0,0,1] op_sel_hi:[1,0,0]
	v_pk_add_f32 v[210:211], v[174:175], v[198:199]
	v_pk_add_f32 v[198:199], v[174:175], v[198:199] neg_lo:[0,1] neg_hi:[0,1]
	v_pk_fma_f32 v[52:53], v[8:9], v[44:45], v[52:53] op_sel_hi:[0,1,1]
	v_pk_add_f32 v[174:175], v[192:193], v[204:205]
	v_pk_add_f32 v[192:193], v[192:193], v[204:205] neg_lo:[0,1] neg_hi:[0,1]
	v_pk_mul_f32 v[56:57], v[10:11], v[44:45] op_sel:[1,1] op_sel_hi:[1,0] neg_lo:[1,0]
	v_pk_mul_f32 v[204:205], v[192:193], s[40:41]
	v_pk_fma_f32 v[68:69], v[8:9], v[60:61], v[68:69] op_sel_hi:[0,1,1]
	v_pk_fma_f32 v[192:193], v[192:193], s[38:39], v[204:205] op_sel:[0,0,1] op_sel_hi:[1,0,0] neg_lo:[1,0,0] neg_hi:[1,0,0]
	v_pk_add_f32 v[204:205], v[188:189], v[196:197] op_sel:[0,1] op_sel_hi:[1,0] neg_hi:[0,1]
	v_pk_add_f32 v[188:189], v[188:189], v[196:197] op_sel:[0,1] op_sel_hi:[1,0] neg_lo:[0,1]
	v_pk_add_f32 v[196:197], v[158:159], v[182:183]
	v_pk_add_f32 v[158:159], v[158:159], v[182:183] neg_lo:[0,1] neg_hi:[0,1]
	v_pk_mul_f32 v[72:73], v[10:11], v[60:61] op_sel:[1,1] op_sel_hi:[1,0] neg_lo:[1,0]
	v_pk_mul_f32 v[182:183], v[158:159], s[40:41]
	v_pk_fma_f32 v[84:85], v[8:9], v[76:77], v[84:85] op_sel_hi:[0,1,1]
	v_pk_fma_f32 v[158:159], v[158:159], s[38:39], v[182:183] op_sel:[0,0,1] op_sel_hi:[1,0,0]
	v_pk_add_f32 v[182:183], v[176:177], v[184:185]
	v_pk_add_f32 v[184:185], v[176:177], v[184:185] neg_lo:[0,1] neg_hi:[0,1]
	v_pk_mul_f32 v[88:89], v[10:11], v[76:77] op_sel:[1,1] op_sel_hi:[1,0] neg_lo:[1,0]
	v_pk_add_f32 v[176:177], v[178:179], v[186:187]
	v_pk_add_f32 v[178:179], v[178:179], v[186:187] neg_lo:[0,1] neg_hi:[0,1]
	v_pk_fma_f32 v[100:101], v[8:9], v[92:93], v[100:101] op_sel_hi:[0,1,1]
	v_pk_mul_f32 v[186:187], v[178:179], s[40:41]
	v_pk_mul_f32 v[104:105], v[10:11], v[92:93] op_sel:[1,1] op_sel_hi:[1,0] neg_lo:[1,0]
	v_pk_fma_f32 v[178:179], v[178:179], s[38:39], v[186:187] op_sel:[0,0,1] op_sel_hi:[1,0,0] neg_lo:[1,0,0] neg_hi:[1,0,0]
	v_pk_add_f32 v[186:187], v[206:207], v[164:165]
	v_pk_add_f32 v[164:165], v[206:207], v[164:165] neg_lo:[0,1] neg_hi:[0,1]
	v_pk_add_f32 v[206:207], v[190:191], v[150:151]
	v_pk_add_f32 v[150:151], v[190:191], v[150:151] neg_lo:[0,1] neg_hi:[0,1]
	v_pk_fma_f32 v[116:117], v[8:9], v[108:109], v[116:117] op_sel_hi:[0,1,1]
	v_pk_mul_f32 v[190:191], v[150:151], s[40:41]
	v_pk_mul_f32 v[120:121], v[10:11], v[108:109] op_sel:[1,1] op_sel_hi:[1,0] neg_lo:[1,0]
	v_pk_fma_f32 v[150:151], v[150:151], s[38:39], v[190:191] op_sel:[0,0,1] op_sel_hi:[1,0,0]
	v_pk_add_f32 v[190:191], v[160:161], v[168:169]
	v_pk_add_f32 v[168:169], v[160:161], v[168:169] neg_lo:[0,1] neg_hi:[0,1]
	v_xor_b32_e32 v26, 0x80000000, v19
	v_pk_add_f32 v[160:161], v[162:163], v[170:171]
	v_pk_add_f32 v[162:163], v[162:163], v[170:171] neg_lo:[0,1] neg_hi:[0,1]
	v_xor_b32_e32 v30, 0x80000000, v21
	v_pk_mul_f32 v[170:171], v[162:163], s[40:41]
	v_pk_fma_f32 v[24:25], v[12:13], v[10:11], v[24:25] op_sel_hi:[1,0,1]
	v_pk_fma_f32 v[162:163], v[162:163], s[38:39], v[170:171] op_sel:[0,0,1] op_sel_hi:[1,0,0] neg_lo:[1,0,0] neg_hi:[1,0,0]
	v_pk_add_f32 v[170:171], v[128:129], v[166:167] op_sel:[0,1] op_sel_hi:[1,0] neg_hi:[0,1]
	v_pk_add_f32 v[128:129], v[128:129], v[166:167] op_sel:[0,1] op_sel_hi:[1,0] neg_lo:[0,1]
	v_pk_add_f32 v[166:167], v[130:131], v[152:153]
	v_pk_add_f32 v[130:131], v[130:131], v[152:153] neg_lo:[0,1] neg_hi:[0,1]
	v_pk_fma_f32 v[40:41], v[10:11], v[28:29], v[40:41] op_sel_hi:[0,1,1]
	v_pk_mul_f32 v[152:153], v[130:131], s[40:41]
	v_pk_fma_f32 v[56:57], v[10:11], v[44:45], v[56:57] op_sel_hi:[0,1,1]
	v_pk_fma_f32 v[130:131], v[130:131], s[38:39], v[152:153] op_sel:[0,0,1] op_sel_hi:[1,0,0]
	v_pk_add_f32 v[152:153], v[144:145], v[154:155]
	v_pk_add_f32 v[154:155], v[144:145], v[154:155] neg_lo:[0,1] neg_hi:[0,1]
	v_pk_fma_f32 v[72:73], v[10:11], v[60:61], v[72:73] op_sel_hi:[0,1,1]
	v_pk_add_f32 v[144:145], v[148:149], v[156:157]
	v_pk_add_f32 v[148:149], v[148:149], v[156:157] neg_lo:[0,1] neg_hi:[0,1]
	v_pk_fma_f32 v[88:89], v[10:11], v[76:77], v[88:89] op_sel_hi:[0,1,1]
	v_pk_mul_f32 v[156:157], v[148:149], s[40:41]
	v_pk_fma_f32 v[104:105], v[10:11], v[92:93], v[104:105] op_sel_hi:[0,1,1]
	v_pk_fma_f32 v[148:149], v[148:149], s[38:39], v[156:157] op_sel:[0,0,1] op_sel_hi:[1,0,0] neg_lo:[1,0,0] neg_hi:[1,0,0]
	v_pk_add_f32 v[156:157], v[172:173], v[210:211]
	v_pk_add_f32 v[172:173], v[172:173], v[210:211] neg_lo:[0,1] neg_hi:[0,1]
	v_pk_add_f32 v[210:211], v[208:209], v[174:175]
	v_pk_add_f32 v[208:209], v[208:209], v[174:175] neg_lo:[0,1] neg_hi:[0,1]
	v_pk_fma_f32 v[120:121], v[10:11], v[108:109], v[120:121] op_sel_hi:[0,1,1]
	v_pk_add_f32 v[174:175], v[194:195], v[198:199] op_sel:[0,1] op_sel_hi:[1,0] neg_hi:[0,1]
	v_pk_add_f32 v[194:195], v[194:195], v[198:199] op_sel:[0,1] op_sel_hi:[1,0] neg_lo:[0,1]
	v_pk_add_f32 v[198:199], v[180:181], v[192:193]
	v_pk_add_f32 v[192:193], v[180:181], v[192:193] neg_lo:[0,1] neg_hi:[0,1]
	v_mov_b32_e32 v27, v19
	v_pk_add_f32 v[180:181], v[204:205], v[182:183]
	v_pk_add_f32 v[182:183], v[204:205], v[182:183] neg_lo:[0,1] neg_hi:[0,1]
	v_pk_add_f32 v[204:205], v[196:197], v[176:177]
	v_pk_add_f32 v[196:197], v[196:197], v[176:177] neg_lo:[0,1] neg_hi:[0,1]
	v_mov_b32_e32 v31, v21
	v_pk_add_f32 v[176:177], v[188:189], v[184:185] op_sel:[0,1] op_sel_hi:[1,0] neg_hi:[0,1]
	v_pk_add_f32 v[184:185], v[188:189], v[184:185] op_sel:[0,1] op_sel_hi:[1,0] neg_lo:[0,1]
	v_pk_add_f32 v[188:189], v[158:159], v[178:179]
	v_pk_add_f32 v[178:179], v[158:159], v[178:179] neg_lo:[0,1] neg_hi:[0,1]
	v_xor_b32_e32 v34, 0x80000000, v25
	v_pk_add_f32 v[158:159], v[186:187], v[190:191]
	v_pk_add_f32 v[186:187], v[186:187], v[190:191] neg_lo:[0,1] neg_hi:[0,1]
	v_pk_add_f32 v[190:191], v[206:207], v[160:161]
	v_pk_add_f32 v[206:207], v[206:207], v[160:161] neg_lo:[0,1] neg_hi:[0,1]
	v_xor_b32_e32 v38, 0x80000000, v29
	v_pk_add_f32 v[160:161], v[164:165], v[168:169] op_sel:[0,1] op_sel_hi:[1,0] neg_hi:[0,1]
	v_pk_add_f32 v[164:165], v[164:165], v[168:169] op_sel:[0,1] op_sel_hi:[1,0] neg_lo:[0,1]
	v_pk_add_f32 v[168:169], v[150:151], v[162:163]
	v_pk_add_f32 v[162:163], v[150:151], v[162:163] neg_lo:[0,1] neg_hi:[0,1]
	v_xor_b32_e32 v42, 0x80000000, v33
	v_pk_add_f32 v[150:151], v[170:171], v[152:153]
	v_pk_add_f32 v[152:153], v[170:171], v[152:153] neg_lo:[0,1] neg_hi:[0,1]
	v_pk_add_f32 v[170:171], v[166:167], v[144:145]
	v_pk_add_f32 v[166:167], v[166:167], v[144:145] neg_lo:[0,1] neg_hi:[0,1]
	v_xor_b32_e32 v46, 0x80000000, v37
	v_pk_add_f32 v[144:145], v[128:129], v[154:155] op_sel:[0,1] op_sel_hi:[1,0] neg_hi:[0,1]
	v_pk_add_f32 v[128:129], v[128:129], v[154:155] op_sel:[0,1] op_sel_hi:[1,0] neg_lo:[0,1]
	v_pk_add_f32 v[154:155], v[130:131], v[148:149]
	v_pk_add_f32 v[130:131], v[130:131], v[148:149] neg_lo:[0,1] neg_hi:[0,1]
	v_mov_b32_e32 v35, v25
	v_xor_b32_e32 v149, 0x80000000, v130
	v_mov_b32_e32 v148, v131
	v_pk_add_f32 v[130:131], v[156:157], v[210:211]
	v_pk_add_f32 v[156:157], v[156:157], v[210:211] neg_lo:[0,1] neg_hi:[0,1]
	v_pk_add_f32 v[210:211], v[172:173], v[208:209] op_sel:[0,1] op_sel_hi:[1,0] neg_hi:[0,1]
	v_pk_add_f32 v[172:173], v[172:173], v[208:209] op_sel:[0,1] op_sel_hi:[1,0] neg_lo:[0,1]
	v_pk_add_f32 v[208:209], v[174:175], v[198:199]
	v_pk_add_f32 v[174:175], v[174:175], v[198:199] neg_lo:[0,1] neg_hi:[0,1]
	v_pk_add_f32 v[198:199], v[194:195], v[192:193] op_sel:[0,1] op_sel_hi:[1,0] neg_hi:[0,1]
	v_pk_add_f32 v[192:193], v[194:195], v[192:193] op_sel:[0,1] op_sel_hi:[1,0] neg_lo:[0,1]
	v_pk_add_f32 v[194:195], v[180:181], v[204:205]
	v_pk_add_f32 v[180:181], v[180:181], v[204:205] neg_lo:[0,1] neg_hi:[0,1]
	v_pk_add_f32 v[204:205], v[182:183], v[196:197] op_sel:[0,1] op_sel_hi:[1,0] neg_hi:[0,1]
	v_pk_add_f32 v[182:183], v[182:183], v[196:197] op_sel:[0,1] op_sel_hi:[1,0] neg_lo:[0,1]
	v_pk_add_f32 v[196:197], v[176:177], v[188:189]
	v_pk_add_f32 v[176:177], v[176:177], v[188:189] neg_lo:[0,1] neg_hi:[0,1]
	v_pk_add_f32 v[188:189], v[184:185], v[178:179] op_sel:[0,1] op_sel_hi:[1,0] neg_hi:[0,1]
	v_pk_add_f32 v[178:179], v[184:185], v[178:179] op_sel:[0,1] op_sel_hi:[1,0] neg_lo:[0,1]
	v_pk_add_f32 v[184:185], v[158:159], v[190:191]
	v_pk_add_f32 v[158:159], v[158:159], v[190:191] neg_lo:[0,1] neg_hi:[0,1]
	v_pk_mul_f32 v[4:5], v[4:5], v[184:185] op_sel:[0,1] op_sel_hi:[1,0]
	v_pk_add_f32 v[190:191], v[186:187], v[206:207] op_sel:[0,1] op_sel_hi:[1,0] neg_hi:[0,1]
	v_pk_add_f32 v[186:187], v[186:187], v[206:207] op_sel:[0,1] op_sel_hi:[1,0] neg_lo:[0,1]
	v_pk_add_f32 v[206:207], v[160:161], v[168:169]
	v_pk_add_f32 v[160:161], v[160:161], v[168:169] neg_lo:[0,1] neg_hi:[0,1]
	v_pk_add_f32 v[168:169], v[164:165], v[162:163] op_sel:[0,1] op_sel_hi:[1,0] neg_hi:[0,1]
	v_pk_add_f32 v[162:163], v[164:165], v[162:163] op_sel:[0,1] op_sel_hi:[1,0] neg_lo:[0,1]
	v_pk_add_f32 v[164:165], v[150:151], v[170:171]
	v_pk_fma_f32 v[4:5], v[6:7], v[184:185], v[4:5] op_sel_hi:[0,1,1]
	v_pk_mul_f32 v[6:7], v[8:9], v[194:195] op_sel:[1,1] op_sel_hi:[1,0] neg_lo:[1,0]
	v_mov_b32_e32 v39, v29
	v_pk_fma_f32 v[6:7], v[8:9], v[194:195], v[6:7] op_sel_hi:[0,1,1]
	v_pk_mul_f32 v[8:9], v[10:11], v[164:165] op_sel:[1,1] op_sel_hi:[1,0] neg_lo:[1,0]
	v_mov_b32_e32 v43, v33
	v_pk_fma_f32 v[8:9], v[10:11], v[164:165], v[8:9] op_sel_hi:[0,1,1]
	v_pk_mul_f32 v[10:11], v[12:13], v[208:209] op_sel:[1,1] op_sel_hi:[1,0] neg_lo:[1,0]
	v_mov_b32_e32 v47, v37
	v_pk_add_f32 v[150:151], v[150:151], v[170:171] neg_lo:[0,1] neg_hi:[0,1]
	v_pk_add_f32 v[170:171], v[152:153], v[166:167] op_sel:[0,1] op_sel_hi:[1,0] neg_hi:[0,1]
	v_pk_add_f32 v[152:153], v[152:153], v[166:167] op_sel:[0,1] op_sel_hi:[1,0] neg_lo:[0,1]
	v_pk_add_f32 v[166:167], v[144:145], v[154:155]
	v_pk_fma_f32 v[10:11], v[12:13], v[208:209], v[10:11] op_sel_hi:[0,1,1]
	v_pk_mul_f32 v[12:13], v[26:27], v[206:207] op_sel:[0,1] op_sel_hi:[1,0]
	v_pk_mul_f32 v[14:15], v[30:31], v[196:197] op_sel:[0,1] op_sel_hi:[1,0]
	v_pk_add_f32 v[144:145], v[144:145], v[154:155] neg_lo:[0,1] neg_hi:[0,1]
	v_pk_add_f32 v[154:155], v[128:129], v[148:149]
	v_pk_fma_f32 v[12:13], v[18:19], v[206:207], v[12:13] op_sel_hi:[0,1,1]
	v_pk_fma_f32 v[14:15], v[20:21], v[196:197], v[14:15] op_sel_hi:[0,1,1]
	v_pk_mul_f32 v[16:17], v[34:35], v[166:167] op_sel:[0,1] op_sel_hi:[1,0]
	v_pk_mul_f32 v[18:19], v[38:39], v[210:211] op_sel:[0,1] op_sel_hi:[1,0]
	v_pk_mul_f32 v[20:21], v[42:43], v[190:191] op_sel:[0,1] op_sel_hi:[1,0]
	v_pk_mul_f32 v[22:23], v[46:47], v[204:205] op_sel:[0,1] op_sel_hi:[1,0]
	v_xor_b32_e32 v78, 0x80000000, v69
	v_xor_b32_e32 v82, 0x80000000, v73
	v_xor_b32_e32 v86, 0x80000000, v77
	v_xor_b32_e32 v90, 0x80000000, v81
	v_xor_b32_e32 v94, 0x80000000, v85
	v_xor_b32_e32 v98, 0x80000000, v89
	v_xor_b32_e32 v102, 0x80000000, v93
	v_xor_b32_e32 v106, 0x80000000, v97
	v_xor_b32_e32 v110, 0x80000000, v101
	v_xor_b32_e32 v114, 0x80000000, v105
	v_xor_b32_e32 v118, 0x80000000, v109
	v_xor_b32_e32 v122, 0x80000000, v113
	v_xor_b32_e32 v124, 0x80000000, v117
	v_xor_b32_e32 v126, 0x80000000, v121
	v_mov_b32_e32 v79, v69
	v_mov_b32_e32 v83, v73
	v_mov_b32_e32 v87, v77
	v_mov_b32_e32 v91, v81
	v_mov_b32_e32 v95, v85
	v_mov_b32_e32 v99, v89
	v_mov_b32_e32 v103, v93
	v_mov_b32_e32 v107, v97
	v_mov_b32_e32 v111, v101
	v_mov_b32_e32 v115, v105
	v_mov_b32_e32 v119, v109
	v_mov_b32_e32 v123, v113
	v_mov_b32_e32 v125, v117
	v_mov_b32_e32 v127, v121
	v_pk_add_f32 v[128:129], v[128:129], v[148:149] neg_lo:[0,1] neg_hi:[0,1]
	v_pk_fma_f32 v[16:17], v[24:25], v[166:167], v[16:17] op_sel_hi:[0,1,1]
	v_pk_fma_f32 v[18:19], v[28:29], v[210:211], v[18:19] op_sel_hi:[0,1,1]
	v_pk_fma_f32 v[20:21], v[32:33], v[190:191], v[20:21] op_sel_hi:[0,1,1]
	v_pk_fma_f32 v[22:23], v[36:37], v[204:205], v[22:23] op_sel_hi:[0,1,1]
	v_pk_mul_f32 v[24:25], v[40:41], v[170:171] op_sel:[1,1] op_sel_hi:[1,0] neg_lo:[1,0]
	v_pk_mul_f32 v[26:27], v[44:45], v[198:199] op_sel:[1,1] op_sel_hi:[1,0] neg_lo:[1,0]
	v_pk_mul_f32 v[28:29], v[48:49], v[168:169] op_sel:[1,1] op_sel_hi:[1,0] neg_lo:[1,0]
	v_pk_mul_f32 v[30:31], v[52:53], v[188:189] op_sel:[1,1] op_sel_hi:[1,0] neg_lo:[1,0]
	v_pk_mul_f32 v[32:33], v[56:57], v[154:155] op_sel:[1,1] op_sel_hi:[1,0] neg_lo:[1,0]
	v_pk_mul_f32 v[34:35], v[60:61], v[156:157] op_sel:[1,1] op_sel_hi:[1,0] neg_lo:[1,0]
	v_pk_mul_f32 v[36:37], v[64:65], v[158:159] op_sel:[1,1] op_sel_hi:[1,0] neg_lo:[1,0]
	v_pk_fma_f32 v[24:25], v[40:41], v[170:171], v[24:25] op_sel_hi:[0,1,1]
	v_pk_fma_f32 v[26:27], v[44:45], v[198:199], v[26:27] op_sel_hi:[0,1,1]
	v_pk_fma_f32 v[28:29], v[48:49], v[168:169], v[28:29] op_sel_hi:[0,1,1]
	v_pk_fma_f32 v[30:31], v[52:53], v[188:189], v[30:31] op_sel_hi:[0,1,1]
	v_pk_fma_f32 v[32:33], v[56:57], v[154:155], v[32:33] op_sel_hi:[0,1,1]
	v_pk_fma_f32 v[34:35], v[60:61], v[156:157], v[34:35] op_sel_hi:[0,1,1]
	v_pk_fma_f32 v[36:37], v[64:65], v[158:159], v[36:37] op_sel_hi:[0,1,1]
	v_pk_mul_f32 v[38:39], v[78:79], v[180:181] op_sel:[0,1] op_sel_hi:[1,0]
	v_pk_mul_f32 v[40:41], v[82:83], v[150:151] op_sel:[0,1] op_sel_hi:[1,0]
	v_pk_mul_f32 v[42:43], v[86:87], v[174:175] op_sel:[0,1] op_sel_hi:[1,0]
	v_pk_mul_f32 v[44:45], v[90:91], v[160:161] op_sel:[0,1] op_sel_hi:[1,0]
	v_pk_mul_f32 v[46:47], v[94:95], v[176:177] op_sel:[0,1] op_sel_hi:[1,0]
	v_pk_mul_f32 v[48:49], v[98:99], v[144:145] op_sel:[0,1] op_sel_hi:[1,0]
	v_pk_mul_f32 v[50:51], v[102:103], v[172:173] op_sel:[0,1] op_sel_hi:[1,0]
	v_pk_mul_f32 v[52:53], v[106:107], v[186:187] op_sel:[0,1] op_sel_hi:[1,0]
	v_pk_mul_f32 v[54:55], v[110:111], v[182:183] op_sel:[0,1] op_sel_hi:[1,0]
	v_pk_mul_f32 v[56:57], v[114:115], v[152:153] op_sel:[0,1] op_sel_hi:[1,0]
	v_pk_mul_f32 v[58:59], v[118:119], v[192:193] op_sel:[0,1] op_sel_hi:[1,0]
	v_pk_mul_f32 v[60:61], v[122:123], v[162:163] op_sel:[0,1] op_sel_hi:[1,0]
	v_pk_mul_f32 v[62:63], v[124:125], v[178:179] op_sel:[0,1] op_sel_hi:[1,0]
	v_pk_mul_f32 v[64:65], v[126:127], v[128:129] op_sel:[0,1] op_sel_hi:[1,0]
	v_pk_fma_f32 v[38:39], v[68:69], v[180:181], v[38:39] op_sel_hi:[0,1,1]
	v_pk_fma_f32 v[40:41], v[72:73], v[150:151], v[40:41] op_sel_hi:[0,1,1]
	v_pk_fma_f32 v[42:43], v[76:77], v[174:175], v[42:43] op_sel_hi:[0,1,1]
	v_pk_fma_f32 v[44:45], v[80:81], v[160:161], v[44:45] op_sel_hi:[0,1,1]
	v_pk_fma_f32 v[46:47], v[84:85], v[176:177], v[46:47] op_sel_hi:[0,1,1]
	v_pk_fma_f32 v[48:49], v[88:89], v[144:145], v[48:49] op_sel_hi:[0,1,1]
	v_pk_fma_f32 v[50:51], v[92:93], v[172:173], v[50:51] op_sel_hi:[0,1,1]
	v_pk_fma_f32 v[52:53], v[96:97], v[186:187], v[52:53] op_sel_hi:[0,1,1]
	v_pk_fma_f32 v[54:55], v[100:101], v[182:183], v[54:55] op_sel_hi:[0,1,1]
	v_pk_fma_f32 v[56:57], v[104:105], v[152:153], v[56:57] op_sel_hi:[0,1,1]
	v_pk_fma_f32 v[58:59], v[108:109], v[192:193], v[58:59] op_sel_hi:[0,1,1]
	v_pk_fma_f32 v[60:61], v[112:113], v[162:163], v[60:61] op_sel_hi:[0,1,1]
	v_pk_fma_f32 v[62:63], v[116:117], v[178:179], v[62:63] op_sel_hi:[0,1,1]
	v_pk_fma_f32 v[64:65], v[120:121], v[128:129], v[64:65] op_sel_hi:[0,1,1]
	ds_write_b64 v2, v[130:131]
	ds_write_b64 v2, v[34:35] offset:2112
	ds_write_b64 v2, v[18:19] offset:4224
	ds_write_b64 v2, v[50:51] offset:6336
	ds_write_b64 v2, v[10:11] offset:8448
	ds_write_b64 v2, v[42:43] offset:10560
	ds_write_b64 v2, v[26:27] offset:12672
	ds_write_b64 v2, v[58:59] offset:14784
	ds_write_b64 v2, v[6:7] offset:16896
	ds_write_b64 v2, v[38:39] offset:19008
	ds_write_b64 v2, v[22:23] offset:21120
	ds_write_b64 v2, v[54:55] offset:23232
	ds_write_b64 v2, v[14:15] offset:25344
	ds_write_b64 v2, v[46:47] offset:27456
	ds_write_b64 v2, v[30:31] offset:29568
	ds_write_b64 v2, v[62:63] offset:31680
	ds_write_b64 v2, v[4:5] offset:33792
	ds_write_b64 v2, v[36:37] offset:35904
	ds_write_b64 v2, v[20:21] offset:38016
	ds_write_b64 v2, v[52:53] offset:40128
	ds_write_b64 v2, v[12:13] offset:42240
	ds_write_b64 v2, v[44:45] offset:44352
	ds_write_b64 v2, v[28:29] offset:46464
	ds_write_b64 v2, v[60:61] offset:48576
	ds_write_b64 v2, v[8:9] offset:50688
	ds_write_b64 v2, v[40:41] offset:52800
	ds_write_b64 v2, v[24:25] offset:54912
	ds_write_b64 v2, v[56:57] offset:57024
	ds_write_b64 v2, v[16:17] offset:59136
	ds_write_b64 v2, v[48:49] offset:61248
	ds_write_b64 v2, v[32:33] offset:63360
	ds_write_b64 v2, v[64:65] offset:65472
	v_mov_b32_e32 v2, v142
	s_waitcnt lgkmcnt(0)
	s_barrier
	s_nop 0
	v_and_b32_e32 v5, 15, v2
	v_cvt_f32_ubyte0_e32 v4, v5
	v_mul_f32_e32 v6, 0x3b800000, v4
	v_sin_f32_e32 v4, v6
	v_cos_f32_e32 v6, v6
	v_lshlrev_b32_e32 v64, 3, v5
	v_lshlrev_b32_e32 v2, 4, v2
	v_xor_b32_e32 v7, 0x80000000, v4
	v_mov_b32_e32 v5, v7
	v_pk_mul_f32 v[8:9], v[6:7], v[4:5] op_sel:[1,0] op_sel_hi:[0,1]
	v_pk_fma_f32 v[8:9], v[6:7], v[6:7], v[8:9] op_sel_hi:[1,0,1]
	v_and_b32_e32 v2, 0xffffff00, v2
	v_pk_mul_f32 v[12:13], v[8:9], v[8:9] op_sel:[1,1] op_sel_hi:[0,1] neg_lo:[0,1]
	v_pk_fma_f32 v[12:13], v[8:9], v[8:9], v[12:13] op_sel_hi:[1,0,1]
	v_pk_mul_f32 v[10:11], v[4:5], v[8:9] op_sel:[0,1] op_sel_hi:[1,0]
	v_pk_mul_f32 v[32:33], v[12:13], v[12:13] op_sel:[1,1] op_sel_hi:[0,1] neg_lo:[0,1]
	v_pk_fma_f32 v[32:33], v[12:13], v[12:13], v[32:33] op_sel_hi:[1,0,1]
	v_pk_mul_f32 v[18:19], v[4:5], v[12:13] op_sel:[0,1] op_sel_hi:[1,0]
	v_pk_mul_f32 v[48:49], v[12:13], v[32:33] op_sel:[1,1] op_sel_hi:[1,0] neg_lo:[1,0]
	v_pk_mul_f32 v[36:37], v[4:5], v[32:33] op_sel:[0,1] op_sel_hi:[1,0]
	v_pk_fma_f32 v[48:49], v[12:13], v[32:33], v[48:49] op_sel_hi:[0,1,1]
	v_pk_mul_f32 v[52:53], v[4:5], v[48:49] op_sel:[0,1] op_sel_hi:[1,0]
	v_pk_fma_f32 v[10:11], v[6:7], v[8:9], v[10:11] op_sel_hi:[0,1,1]
	v_pk_fma_f32 v[18:19], v[6:7], v[12:13], v[18:19] op_sel_hi:[0,1,1]
	v_pk_fma_f32 v[36:37], v[6:7], v[32:33], v[36:37] op_sel_hi:[0,1,1]
	v_pk_fma_f32 v[52:53], v[6:7], v[48:49], v[52:53] op_sel_hi:[0,1,1]
	v_lshlrev_b32_e32 v7, 3, v2
	v_add3_u32 v7, 0, v64, v7
	v_ashrrev_i32_e32 v64, 2, v2
	v_add_u32_e32 v106, v7, v64
	ds_read2_b64 v[64:67], v106 offset1:16
	ds_read2_b64 v[68:71], v106 offset0:33 offset1:49
	ds_read2_b64 v[72:75], v106 offset0:66 offset1:82
	ds_read2_b64 v[76:79], v106 offset0:132 offset1:148
	ds_read2_b64 v[80:83], v106 offset0:99 offset1:115
	ds_read2_b64 v[84:87], v106 offset0:165 offset1:181
	ds_read2_b64 v[88:91], v106 offset0:198 offset1:214
	ds_read2_b64 v[92:95], v106 offset0:231 offset1:247
	s_waitcnt lgkmcnt(4)
	v_pk_add_f32 v[96:97], v[64:65], v[76:77]
	v_pk_add_f32 v[64:65], v[64:65], v[76:77] neg_lo:[0,1] neg_hi:[0,1]
	v_pk_add_f32 v[76:77], v[66:67], v[78:79]
	v_pk_add_f32 v[66:67], v[66:67], v[78:79] neg_lo:[0,1] neg_hi:[0,1]
	s_waitcnt lgkmcnt(1)
	v_pk_add_f32 v[98:99], v[74:75], v[90:91]
	v_pk_mul_f32 v[78:79], v[66:67], s[24:25]
	v_pk_add_f32 v[74:75], v[74:75], v[90:91] neg_lo:[0,1] neg_hi:[0,1]
	v_pk_fma_f32 v[66:67], v[66:67], s[22:23], v[78:79] op_sel:[0,0,1] op_sel_hi:[1,0,0]
	v_pk_add_f32 v[78:79], v[68:69], v[84:85]
	v_pk_add_f32 v[68:69], v[68:69], v[84:85] neg_lo:[0,1] neg_hi:[0,1]
	v_pk_mul_f32 v[90:91], v[74:75], s[44:45]
	v_pk_mul_f32 v[84:85], v[68:69], s[40:41]
	v_pk_fma_f32 v[74:75], v[74:75], s[50:51], v[90:91] op_sel:[0,0,1] op_sel_hi:[1,0,0] neg_lo:[1,0,0] neg_hi:[1,0,0]
	v_pk_fma_f32 v[68:69], v[68:69], s[38:39], v[84:85] op_sel:[0,0,1] op_sel_hi:[1,0,0]
	v_pk_add_f32 v[84:85], v[70:71], v[86:87]
	v_pk_add_f32 v[70:71], v[70:71], v[86:87] neg_lo:[0,1] neg_hi:[0,1]
	s_waitcnt lgkmcnt(0)
	v_pk_add_f32 v[90:91], v[80:81], v[92:93]
	v_pk_add_f32 v[80:81], v[80:81], v[92:93] neg_lo:[0,1] neg_hi:[0,1]
	v_pk_mul_f32 v[86:87], v[70:71], s[44:45]
	v_pk_mul_f32 v[92:93], v[80:81], s[40:41]
	v_pk_fma_f32 v[70:71], v[70:71], s[50:51], v[86:87] op_sel:[0,0,1] op_sel_hi:[1,0,0]
	v_pk_add_f32 v[86:87], v[72:73], v[88:89]
	v_pk_add_f32 v[88:89], v[72:73], v[88:89] neg_lo:[0,1] neg_hi:[0,1]
	v_pk_fma_f32 v[80:81], v[80:81], s[38:39], v[92:93] op_sel:[0,0,1] op_sel_hi:[1,0,0] neg_lo:[1,0,0] neg_hi:[1,0,0]
	v_pk_add_f32 v[92:93], v[82:83], v[94:95]
	v_pk_add_f32 v[82:83], v[82:83], v[94:95] neg_lo:[0,1] neg_hi:[0,1]
	v_pk_mul_f32 v[94:95], v[82:83], s[24:25]
	v_pk_fma_f32 v[82:83], v[82:83], s[22:23], v[94:95] op_sel:[0,0,1] op_sel_hi:[1,0,0] neg_lo:[1,0,0] neg_hi:[1,0,0]
	v_pk_add_f32 v[94:95], v[96:97], v[86:87]
	v_pk_add_f32 v[86:87], v[96:97], v[86:87] neg_lo:[0,1] neg_hi:[0,1]
	v_pk_add_f32 v[96:97], v[76:77], v[98:99]
	v_pk_add_f32 v[76:77], v[76:77], v[98:99] neg_lo:[0,1] neg_hi:[0,1]
	v_pk_add_f32 v[100:101], v[84:85], v[92:93]
	v_pk_add_f32 v[84:85], v[84:85], v[92:93] neg_lo:[0,1] neg_hi:[0,1]
	v_pk_add_f32 v[72:73], v[64:65], v[88:89] op_sel:[0,1] op_sel_hi:[1,0] neg_hi:[0,1]
	v_pk_add_f32 v[64:65], v[64:65], v[88:89] op_sel:[0,1] op_sel_hi:[1,0] neg_lo:[0,1]
	v_pk_add_f32 v[88:89], v[66:67], v[74:75]
	v_pk_add_f32 v[66:67], v[66:67], v[74:75] neg_lo:[0,1] neg_hi:[0,1]
	v_pk_mul_f32 v[98:99], v[76:77], s[40:41]
	v_pk_mul_f32 v[92:93], v[84:85], s[40:41]
	v_pk_mul_f32 v[74:75], v[66:67], s[40:41]
	v_pk_fma_f32 v[76:77], v[76:77], s[38:39], v[98:99] op_sel:[0,0,1] op_sel_hi:[1,0,0]
	v_pk_add_f32 v[98:99], v[78:79], v[90:91]
	v_pk_add_f32 v[90:91], v[78:79], v[90:91] neg_lo:[0,1] neg_hi:[0,1]
	v_pk_fma_f32 v[84:85], v[84:85], s[38:39], v[92:93] op_sel:[0,0,1] op_sel_hi:[1,0,0] neg_lo:[1,0,0] neg_hi:[1,0,0]
	v_pk_fma_f32 v[66:67], v[66:67], s[38:39], v[74:75] op_sel:[0,0,1] op_sel_hi:[1,0,0]
	v_pk_add_f32 v[74:75], v[68:69], v[80:81]
	v_pk_add_f32 v[92:93], v[70:71], v[82:83]
	v_pk_add_f32 v[70:71], v[70:71], v[82:83] neg_lo:[0,1] neg_hi:[0,1]
	v_pk_add_f32 v[68:69], v[68:69], v[80:81] neg_lo:[0,1] neg_hi:[0,1]
	v_pk_mul_f32 v[82:83], v[70:71], s[40:41]
	v_pk_add_f32 v[102:103], v[72:73], v[74:75]
	v_pk_add_f32 v[72:73], v[72:73], v[74:75] neg_lo:[0,1] neg_hi:[0,1]
	v_pk_add_f32 v[74:75], v[88:89], v[92:93]
	v_pk_add_f32 v[92:93], v[88:89], v[92:93] neg_lo:[0,1] neg_hi:[0,1]
	v_pk_mul_f32 v[24:25], v[8:9], v[12:13] op_sel:[1,1] op_sel_hi:[1,0] neg_lo:[1,0]
	v_xor_b32_e32 v81, 0x80000000, v68
	v_pk_fma_f32 v[70:71], v[70:71], s[38:39], v[82:83] op_sel:[0,0,1] op_sel_hi:[1,0,0] neg_lo:[1,0,0] neg_hi:[1,0,0]
	v_pk_add_f32 v[78:79], v[86:87], v[90:91] op_sel:[0,1] op_sel_hi:[1,0] neg_hi:[0,1]
	v_pk_add_f32 v[86:87], v[86:87], v[90:91] op_sel:[0,1] op_sel_hi:[1,0] neg_lo:[0,1]
	v_pk_add_f32 v[90:91], v[76:77], v[84:85]
	v_pk_add_f32 v[84:85], v[76:77], v[84:85] neg_lo:[0,1] neg_hi:[0,1]
	v_mov_b32_e32 v80, v69
	v_pk_fma_f32 v[24:25], v[8:9], v[12:13], v[24:25] op_sel_hi:[0,1,1]
	v_pk_mul_f32 v[28:29], v[12:13], v[10:11] op_sel:[1,1] op_sel_hi:[0,1] neg_lo:[0,1]
	v_pk_add_f32 v[68:69], v[64:65], v[80:81]
	v_pk_add_f32 v[64:65], v[64:65], v[80:81] neg_lo:[0,1] neg_hi:[0,1]
	v_pk_add_f32 v[80:81], v[66:67], v[70:71]
	v_pk_add_f32 v[70:71], v[66:67], v[70:71] neg_lo:[0,1] neg_hi:[0,1]
	v_pk_add_f32 v[88:89], v[72:73], v[92:93] op_sel:[0,1] op_sel_hi:[1,0] neg_hi:[0,1]
	v_pk_fma_f32 v[28:29], v[12:13], v[10:11], v[28:29] op_sel_hi:[1,0,1]
	v_pk_add_f32 v[76:77], v[86:87], v[84:85] op_sel:[0,1] op_sel_hi:[1,0] neg_hi:[0,1]
	v_pk_add_f32 v[72:73], v[72:73], v[92:93] op_sel:[0,1] op_sel_hi:[1,0] neg_lo:[0,1]
	v_pk_mul_f32 v[92:93], v[18:19], v[88:89] op_sel:[1,1] op_sel_hi:[1,0] neg_lo:[1,0]
	v_pk_add_f32 v[82:83], v[94:95], v[98:99]
	v_pk_add_f32 v[94:95], v[94:95], v[98:99] neg_lo:[0,1] neg_hi:[0,1]
	v_pk_add_f32 v[98:99], v[96:97], v[100:101]
	v_pk_add_f32 v[66:67], v[64:65], v[70:71] op_sel:[0,1] op_sel_hi:[1,0] neg_hi:[0,1]
	v_pk_fma_f32 v[88:89], v[18:19], v[88:89], v[92:93] op_sel_hi:[0,1,1]
	v_pk_mul_f32 v[92:93], v[24:25], v[76:77] op_sel:[1,1] op_sel_hi:[1,0] neg_lo:[1,0]
	v_pk_mul_f32 v[40:41], v[8:9], v[32:33] op_sel:[1,1] op_sel_hi:[1,0] neg_lo:[1,0]
	v_pk_add_f32 v[104:105], v[82:83], v[98:99]
	v_pk_add_f32 v[82:83], v[82:83], v[98:99] neg_lo:[0,1] neg_hi:[0,1]
	v_pk_fma_f32 v[76:77], v[24:25], v[76:77], v[92:93] op_sel_hi:[0,1,1]
	v_pk_mul_f32 v[92:93], v[28:29], v[66:67] op_sel:[1,1] op_sel_hi:[1,0] neg_lo:[1,0]
	v_pk_fma_f32 v[40:41], v[8:9], v[32:33], v[40:41] op_sel_hi:[0,1,1]
	v_pk_mul_f32 v[44:45], v[10:11], v[32:33] op_sel:[1,1] op_sel_hi:[1,0] neg_lo:[1,0]
	v_pk_add_f32 v[84:85], v[86:87], v[84:85] op_sel:[0,1] op_sel_hi:[1,0] neg_lo:[0,1]
	v_pk_add_f32 v[86:87], v[102:103], v[74:75]
	v_pk_add_f32 v[74:75], v[102:103], v[74:75] neg_lo:[0,1] neg_hi:[0,1]
	v_pk_fma_f32 v[66:67], v[28:29], v[66:67], v[92:93] op_sel_hi:[0,1,1]
	v_pk_mul_f32 v[92:93], v[32:33], v[82:83] op_sel:[1,1] op_sel_hi:[1,0] neg_lo:[1,0]
	v_pk_fma_f32 v[44:45], v[10:11], v[32:33], v[44:45] op_sel_hi:[0,1,1]
	v_pk_add_f32 v[100:101], v[96:97], v[100:101] neg_lo:[0,1] neg_hi:[0,1]
	v_pk_add_f32 v[98:99], v[78:79], v[90:91]
	v_pk_add_f32 v[78:79], v[78:79], v[90:91] neg_lo:[0,1] neg_hi:[0,1]
	v_pk_fma_f32 v[82:83], v[32:33], v[82:83], v[92:93] op_sel_hi:[0,1,1]
	v_pk_mul_f32 v[92:93], v[36:37], v[74:75] op_sel:[1,1] op_sel_hi:[1,0] neg_lo:[1,0]
	v_pk_add_f32 v[90:91], v[68:69], v[80:81]
	v_pk_add_f32 v[68:69], v[68:69], v[80:81] neg_lo:[0,1] neg_hi:[0,1]
	v_pk_fma_f32 v[74:75], v[36:37], v[74:75], v[92:93] op_sel_hi:[0,1,1]
	v_pk_mul_f32 v[92:93], v[40:41], v[78:79] op_sel:[1,1] op_sel_hi:[1,0] neg_lo:[1,0]
	v_pk_mul_f32 v[56:57], v[8:9], v[48:49] op_sel:[1,1] op_sel_hi:[1,0] neg_lo:[1,0]
	v_pk_add_f32 v[96:97], v[94:95], v[100:101] op_sel:[0,1] op_sel_hi:[1,0] neg_hi:[0,1]
	v_pk_add_f32 v[94:95], v[94:95], v[100:101] op_sel:[0,1] op_sel_hi:[1,0] neg_lo:[0,1]
	v_pk_fma_f32 v[78:79], v[40:41], v[78:79], v[92:93] op_sel_hi:[0,1,1]
	v_pk_mul_f32 v[92:93], v[44:45], v[68:69] op_sel:[1,1] op_sel_hi:[1,0] neg_lo:[1,0]
	v_pk_fma_f32 v[56:57], v[8:9], v[48:49], v[56:57] op_sel_hi:[0,1,1]
	v_pk_mul_f32 v[60:61], v[10:11], v[48:49] op_sel:[1,1] op_sel_hi:[1,0] neg_lo:[1,0]
	v_pk_fma_f32 v[68:69], v[44:45], v[68:69], v[92:93] op_sel_hi:[0,1,1]
	v_pk_mul_f32 v[92:93], v[48:49], v[94:95] op_sel:[1,1] op_sel_hi:[1,0] neg_lo:[1,0]
	v_pk_fma_f32 v[60:61], v[10:11], v[48:49], v[60:61] op_sel_hi:[0,1,1]
	v_pk_add_f32 v[64:65], v[64:65], v[70:71] op_sel:[0,1] op_sel_hi:[1,0] neg_lo:[0,1]
	v_pk_mul_f32 v[70:71], v[4:5], v[86:87] op_sel:[0,1] op_sel_hi:[1,0]
	v_pk_fma_f32 v[92:93], v[48:49], v[94:95], v[92:93] op_sel_hi:[0,1,1]
	v_pk_mul_f32 v[94:95], v[52:53], v[72:73] op_sel:[1,1] op_sel_hi:[1,0] neg_lo:[1,0]
	v_pk_fma_f32 v[70:71], v[6:7], v[86:87], v[70:71] op_sel_hi:[0,1,1]
	v_pk_mul_f32 v[86:87], v[10:11], v[90:91] op_sel:[1,1] op_sel_hi:[1,0] neg_lo:[1,0]
	v_pk_fma_f32 v[72:73], v[52:53], v[72:73], v[94:95] op_sel_hi:[0,1,1]
	v_pk_mul_f32 v[94:95], v[56:57], v[84:85] op_sel:[1,1] op_sel_hi:[1,0] neg_lo:[1,0]
	v_add_u32_e32 v2, 0x2000, v2
	v_pk_mul_f32 v[80:81], v[8:9], v[98:99] op_sel:[1,1] op_sel_hi:[1,0] neg_lo:[1,0]
	v_pk_fma_f32 v[86:87], v[10:11], v[90:91], v[86:87] op_sel_hi:[0,1,1]
	v_pk_mul_f32 v[90:91], v[12:13], v[96:97] op_sel:[1,1] op_sel_hi:[1,0] neg_lo:[1,0]
	v_pk_fma_f32 v[84:85], v[56:57], v[84:85], v[94:95] op_sel_hi:[0,1,1]
	v_pk_mul_f32 v[94:95], v[60:61], v[64:65] op_sel:[1,1] op_sel_hi:[1,0] neg_lo:[1,0]
	v_ashrrev_i32_e32 v2, 2, v2
	v_pk_fma_f32 v[80:81], v[8:9], v[98:99], v[80:81] op_sel_hi:[0,1,1]
	v_pk_fma_f32 v[90:91], v[12:13], v[96:97], v[90:91] op_sel_hi:[0,1,1]
	v_pk_fma_f32 v[64:65], v[60:61], v[64:65], v[94:95] op_sel_hi:[0,1,1]
	ds_write2_b64 v106, v[104:105], v[82:83] offset1:16
	ds_write2_b64 v106, v[90:91], v[92:93] offset0:33 offset1:49
	ds_write2_b64 v106, v[80:81], v[78:79] offset0:66 offset1:82
	ds_write2_b64 v106, v[76:77], v[84:85] offset0:99 offset1:115
	ds_write2_b64 v106, v[70:71], v[74:75] offset0:132 offset1:148
	ds_write2_b64 v106, v[88:89], v[72:73] offset0:165 offset1:181
	ds_write2_b64 v106, v[86:87], v[68:69] offset0:198 offset1:214
	ds_write2_b64 v106, v[66:67], v[64:65] offset0:231 offset1:247
	v_add3_u32 v2, v7, v2, s60
	ds_read2_b64 v[64:67], v2 offset1:16
	ds_read2_b64 v[68:71], v2 offset0:33 offset1:49
	ds_read2_b64 v[72:75], v2 offset0:66 offset1:82
	ds_read2_b64 v[76:79], v2 offset0:132 offset1:148
	ds_read2_b64 v[80:83], v2 offset0:99 offset1:115
	ds_read2_b64 v[84:87], v2 offset0:165 offset1:181
	ds_read2_b64 v[88:91], v2 offset0:198 offset1:214
	ds_read2_b64 v[92:95], v2 offset0:231 offset1:247
	s_waitcnt lgkmcnt(4)
	v_pk_add_f32 v[96:97], v[64:65], v[76:77]
	v_pk_add_f32 v[64:65], v[64:65], v[76:77] neg_lo:[0,1] neg_hi:[0,1]
	v_pk_add_f32 v[76:77], v[66:67], v[78:79]
	v_pk_add_f32 v[66:67], v[66:67], v[78:79] neg_lo:[0,1] neg_hi:[0,1]
	s_waitcnt lgkmcnt(1)
	v_pk_add_f32 v[98:99], v[74:75], v[90:91]
	v_pk_mul_f32 v[78:79], v[66:67], s[24:25]
	v_pk_add_f32 v[74:75], v[74:75], v[90:91] neg_lo:[0,1] neg_hi:[0,1]
	v_pk_fma_f32 v[66:67], v[66:67], s[22:23], v[78:79] op_sel:[0,0,1] op_sel_hi:[1,0,0]
	v_pk_add_f32 v[78:79], v[68:69], v[84:85]
	v_pk_add_f32 v[68:69], v[68:69], v[84:85] neg_lo:[0,1] neg_hi:[0,1]
	v_pk_mul_f32 v[90:91], v[74:75], s[44:45]
	v_pk_mul_f32 v[84:85], v[68:69], s[40:41]
	v_pk_fma_f32 v[74:75], v[74:75], s[50:51], v[90:91] op_sel:[0,0,1] op_sel_hi:[1,0,0] neg_lo:[1,0,0] neg_hi:[1,0,0]
	s_waitcnt lgkmcnt(0)
	v_pk_add_f32 v[90:91], v[80:81], v[92:93]
	v_pk_add_f32 v[80:81], v[80:81], v[92:93] neg_lo:[0,1] neg_hi:[0,1]
	v_pk_fma_f32 v[68:69], v[68:69], s[38:39], v[84:85] op_sel:[0,0,1] op_sel_hi:[1,0,0]
	v_pk_add_f32 v[84:85], v[70:71], v[86:87]
	v_pk_add_f32 v[70:71], v[70:71], v[86:87] neg_lo:[0,1] neg_hi:[0,1]
	v_pk_mul_f32 v[92:93], v[80:81], s[40:41]
	v_pk_mul_f32 v[86:87], v[70:71], s[44:45]
	v_pk_fma_f32 v[80:81], v[80:81], s[38:39], v[92:93] op_sel:[0,0,1] op_sel_hi:[1,0,0] neg_lo:[1,0,0] neg_hi:[1,0,0]
	v_pk_add_f32 v[92:93], v[82:83], v[94:95]
	v_pk_add_f32 v[82:83], v[82:83], v[94:95] neg_lo:[0,1] neg_hi:[0,1]
	v_pk_fma_f32 v[70:71], v[70:71], s[50:51], v[86:87] op_sel:[0,0,1] op_sel_hi:[1,0,0]
	v_pk_add_f32 v[86:87], v[72:73], v[88:89]
	v_pk_mul_f32 v[94:95], v[82:83], s[24:25]
	v_pk_add_f32 v[88:89], v[72:73], v[88:89] neg_lo:[0,1] neg_hi:[0,1]
	v_pk_fma_f32 v[82:83], v[82:83], s[22:23], v[94:95] op_sel:[0,0,1] op_sel_hi:[1,0,0] neg_lo:[1,0,0] neg_hi:[1,0,0]
	v_pk_add_f32 v[94:95], v[96:97], v[86:87]
	v_pk_add_f32 v[86:87], v[96:97], v[86:87] neg_lo:[0,1] neg_hi:[0,1]
	v_pk_add_f32 v[96:97], v[76:77], v[98:99]
	v_pk_add_f32 v[76:77], v[76:77], v[98:99] neg_lo:[0,1] neg_hi:[0,1]
	v_pk_mul_f32 v[98:99], v[76:77], s[40:41]
	v_pk_add_f32 v[100:101], v[84:85], v[92:93]
	v_pk_add_f32 v[84:85], v[84:85], v[92:93] neg_lo:[0,1] neg_hi:[0,1]
	v_pk_fma_f32 v[76:77], v[76:77], s[38:39], v[98:99] op_sel:[0,0,1] op_sel_hi:[1,0,0]
	v_pk_add_f32 v[98:99], v[78:79], v[90:91]
	v_pk_add_f32 v[90:91], v[78:79], v[90:91] neg_lo:[0,1] neg_hi:[0,1]
	v_pk_mul_f32 v[92:93], v[84:85], s[40:41]
	v_pk_add_f32 v[72:73], v[64:65], v[88:89] op_sel:[0,1] op_sel_hi:[1,0] neg_hi:[0,1]
	v_pk_add_f32 v[64:65], v[64:65], v[88:89] op_sel:[0,1] op_sel_hi:[1,0] neg_lo:[0,1]
	v_pk_add_f32 v[88:89], v[66:67], v[74:75]
	v_pk_add_f32 v[66:67], v[66:67], v[74:75] neg_lo:[0,1] neg_hi:[0,1]
	v_pk_fma_f32 v[84:85], v[84:85], s[38:39], v[92:93] op_sel:[0,0,1] op_sel_hi:[1,0,0] neg_lo:[1,0,0] neg_hi:[1,0,0]
	v_pk_mul_f32 v[74:75], v[66:67], s[40:41]
	v_pk_fma_f32 v[66:67], v[66:67], s[38:39], v[74:75] op_sel:[0,0,1] op_sel_hi:[1,0,0]
	v_pk_add_f32 v[74:75], v[68:69], v[80:81]
	v_pk_add_f32 v[92:93], v[70:71], v[82:83]
	v_pk_add_f32 v[70:71], v[70:71], v[82:83] neg_lo:[0,1] neg_hi:[0,1]
	v_pk_add_f32 v[78:79], v[86:87], v[90:91] op_sel:[0,1] op_sel_hi:[1,0] neg_hi:[0,1]
	v_pk_add_f32 v[86:87], v[86:87], v[90:91] op_sel:[0,1] op_sel_hi:[1,0] neg_lo:[0,1]
	v_pk_add_f32 v[90:91], v[76:77], v[84:85]
	v_pk_add_f32 v[84:85], v[76:77], v[84:85] neg_lo:[0,1] neg_hi:[0,1]
	v_pk_add_f32 v[80:81], v[68:69], v[80:81] neg_lo:[0,1] neg_hi:[0,1]
	v_pk_mul_f32 v[82:83], v[70:71], s[40:41]
	v_pk_add_f32 v[102:103], v[72:73], v[74:75]
	v_pk_add_f32 v[72:73], v[72:73], v[74:75] neg_lo:[0,1] neg_hi:[0,1]
	v_pk_add_f32 v[74:75], v[88:89], v[92:93]
	v_pk_fma_f32 v[70:71], v[70:71], s[38:39], v[82:83] op_sel:[0,0,1] op_sel_hi:[1,0,0] neg_lo:[1,0,0] neg_hi:[1,0,0]
	v_pk_add_f32 v[82:83], v[94:95], v[98:99]
	v_pk_add_f32 v[94:95], v[94:95], v[98:99] neg_lo:[0,1] neg_hi:[0,1]
	v_pk_add_f32 v[98:99], v[96:97], v[100:101]
	v_pk_add_f32 v[76:77], v[86:87], v[84:85] op_sel:[0,1] op_sel_hi:[1,0] neg_hi:[0,1]
	v_pk_add_f32 v[84:85], v[86:87], v[84:85] op_sel:[0,1] op_sel_hi:[1,0] neg_lo:[0,1]
	v_pk_add_f32 v[86:87], v[102:103], v[74:75]
	v_pk_add_f32 v[100:101], v[96:97], v[100:101] neg_lo:[0,1] neg_hi:[0,1]
	v_pk_add_f32 v[68:69], v[64:65], v[80:81] op_sel:[0,1] op_sel_hi:[1,0] neg_hi:[0,1]
	v_pk_add_f32 v[64:65], v[64:65], v[80:81] op_sel:[0,1] op_sel_hi:[1,0] neg_lo:[0,1]
	v_pk_add_f32 v[80:81], v[66:67], v[70:71]
	v_pk_add_f32 v[104:105], v[82:83], v[98:99]
	v_pk_add_f32 v[82:83], v[82:83], v[98:99] neg_lo:[0,1] neg_hi:[0,1]
	v_pk_add_f32 v[98:99], v[78:79], v[90:91]
	v_pk_mul_f32 v[4:5], v[4:5], v[86:87] op_sel:[0,1] op_sel_hi:[1,0]
	v_pk_add_f32 v[92:93], v[88:89], v[92:93] neg_lo:[0,1] neg_hi:[0,1]
	v_pk_add_f32 v[78:79], v[78:79], v[90:91] neg_lo:[0,1] neg_hi:[0,1]
	v_pk_add_f32 v[90:91], v[68:69], v[80:81]
	v_pk_fma_f32 v[4:5], v[6:7], v[86:87], v[4:5] op_sel_hi:[0,1,1]
	v_pk_mul_f32 v[6:7], v[8:9], v[98:99] op_sel:[1,1] op_sel_hi:[1,0] neg_lo:[1,0]
	v_pk_add_f32 v[70:71], v[66:67], v[70:71] neg_lo:[0,1] neg_hi:[0,1]
	v_pk_add_f32 v[96:97], v[94:95], v[100:101] op_sel:[0,1] op_sel_hi:[1,0] neg_hi:[0,1]
	v_pk_fma_f32 v[6:7], v[8:9], v[98:99], v[6:7] op_sel_hi:[0,1,1]
	v_pk_mul_f32 v[8:9], v[10:11], v[90:91] op_sel:[1,1] op_sel_hi:[1,0] neg_lo:[1,0]
	v_pk_add_f32 v[88:89], v[72:73], v[92:93] op_sel:[0,1] op_sel_hi:[1,0] neg_hi:[0,1]
	v_pk_fma_f32 v[8:9], v[10:11], v[90:91], v[8:9] op_sel_hi:[0,1,1]
	v_pk_mul_f32 v[10:11], v[12:13], v[96:97] op_sel:[1,1] op_sel_hi:[1,0] neg_lo:[1,0]
	v_pk_add_f32 v[66:67], v[64:65], v[70:71] op_sel:[0,1] op_sel_hi:[1,0] neg_hi:[0,1]
	v_pk_fma_f32 v[10:11], v[12:13], v[96:97], v[10:11] op_sel_hi:[0,1,1]
	v_pk_mul_f32 v[12:13], v[18:19], v[88:89] op_sel:[1,1] op_sel_hi:[1,0] neg_lo:[1,0]
	v_pk_add_f32 v[94:95], v[94:95], v[100:101] op_sel:[0,1] op_sel_hi:[1,0] neg_lo:[0,1]
	v_pk_add_f32 v[74:75], v[102:103], v[74:75] neg_lo:[0,1] neg_hi:[0,1]
	v_pk_add_f32 v[72:73], v[72:73], v[92:93] op_sel:[0,1] op_sel_hi:[1,0] neg_lo:[0,1]
	v_pk_add_f32 v[68:69], v[68:69], v[80:81] neg_lo:[0,1] neg_hi:[0,1]
	v_pk_add_f32 v[64:65], v[64:65], v[70:71] op_sel:[0,1] op_sel_hi:[1,0] neg_lo:[0,1]
	v_pk_fma_f32 v[12:13], v[18:19], v[88:89], v[12:13] op_sel_hi:[0,1,1]
	v_pk_mul_f32 v[14:15], v[24:25], v[76:77] op_sel:[1,1] op_sel_hi:[1,0] neg_lo:[1,0]
	v_pk_mul_f32 v[16:17], v[28:29], v[66:67] op_sel:[1,1] op_sel_hi:[1,0] neg_lo:[1,0]
	v_pk_mul_f32 v[18:19], v[32:33], v[82:83] op_sel:[1,1] op_sel_hi:[1,0] neg_lo:[1,0]
	v_pk_fma_f32 v[14:15], v[24:25], v[76:77], v[14:15] op_sel_hi:[0,1,1]
	v_pk_fma_f32 v[16:17], v[28:29], v[66:67], v[16:17] op_sel_hi:[0,1,1]
	v_pk_fma_f32 v[18:19], v[32:33], v[82:83], v[18:19] op_sel_hi:[0,1,1]
	v_pk_mul_f32 v[20:21], v[36:37], v[74:75] op_sel:[1,1] op_sel_hi:[1,0] neg_lo:[1,0]
	v_pk_mul_f32 v[22:23], v[40:41], v[78:79] op_sel:[1,1] op_sel_hi:[1,0] neg_lo:[1,0]
	v_pk_mul_f32 v[24:25], v[44:45], v[68:69] op_sel:[1,1] op_sel_hi:[1,0] neg_lo:[1,0]
	v_pk_mul_f32 v[26:27], v[48:49], v[94:95] op_sel:[1,1] op_sel_hi:[1,0] neg_lo:[1,0]
	v_pk_mul_f32 v[28:29], v[52:53], v[72:73] op_sel:[1,1] op_sel_hi:[1,0] neg_lo:[1,0]
	v_pk_mul_f32 v[30:31], v[56:57], v[84:85] op_sel:[1,1] op_sel_hi:[1,0] neg_lo:[1,0]
	v_pk_mul_f32 v[32:33], v[60:61], v[64:65] op_sel:[1,1] op_sel_hi:[1,0] neg_lo:[1,0]
	v_pk_fma_f32 v[20:21], v[36:37], v[74:75], v[20:21] op_sel_hi:[0,1,1]
	v_pk_fma_f32 v[22:23], v[40:41], v[78:79], v[22:23] op_sel_hi:[0,1,1]
	v_pk_fma_f32 v[24:25], v[44:45], v[68:69], v[24:25] op_sel_hi:[0,1,1]
	v_pk_fma_f32 v[26:27], v[48:49], v[94:95], v[26:27] op_sel_hi:[0,1,1]
	v_pk_fma_f32 v[28:29], v[52:53], v[72:73], v[28:29] op_sel_hi:[0,1,1]
	v_pk_fma_f32 v[30:31], v[56:57], v[84:85], v[30:31] op_sel_hi:[0,1,1]
	v_pk_fma_f32 v[32:33], v[60:61], v[64:65], v[32:33] op_sel_hi:[0,1,1]
	ds_write2_b64 v2, v[104:105], v[18:19] offset1:16
	ds_write2_b64 v2, v[10:11], v[26:27] offset0:33 offset1:49
	ds_write2_b64 v2, v[6:7], v[22:23] offset0:66 offset1:82
	ds_write2_b64 v2, v[14:15], v[30:31] offset0:99 offset1:115
	ds_write2_b64 v2, v[4:5], v[20:21] offset0:132 offset1:148
	ds_write2_b64 v2, v[12:13], v[28:29] offset0:165 offset1:181
	ds_write2_b64 v2, v[8:9], v[24:25] offset0:198 offset1:214
	ds_write2_b64 v2, v[16:17], v[32:33] offset0:231 offset1:247
	s_waitcnt lgkmcnt(0)
	s_barrier
	s_nop 0
	v_ashrrev_i32_e32 v2, 31, v142
	v_add_u32_sdwa v2, v142, v2 dst_sel:DWORD dst_unused:UNUSED_PAD src0_sel:DWORD src1_sel:BYTE_3
	v_ashrrev_i32_e32 v145, 8, v2
	v_mul_i32_i24_e32 v2, 0x100, v145
	v_sub_u32_e32 v144, v142, v2
	v_lshlrev_b32_e32 v2, 1, v144
	v_bfrev_b32_e32 v2, v2
	v_lshrrev_b32_e32 v2, 23, v2
	v_sub_u32_e32 v2, 0x200, v2
	v_bfrev_b32_e32 v2, v2
	v_lshrrev_b32_e32 v2, 19, v2
	v_lshlrev_b32_e32 v143, 13, v145
	v_and_b32_e32 v2, 0x1ff0, v2
	v_cmp_eq_u32_e32 vcc, 0, v144
	v_lshl_add_u32 v4, v144, 5, v143
	v_lshlrev_b32_e32 v5, 3, v4
	v_cndmask_b32_e64 v2, v2, 16, vcc
	v_ashrrev_i32_e32 v4, 2, v4
	v_or_b32_e32 v2, v2, v143
	v_add3_u32 v56, 0, v5, v4
	v_ashrrev_i32_e32 v4, 5, v2
	v_lshlrev_b32_e32 v2, 3, v2
	v_lshlrev_b32_e32 v4, 3, v4
	v_add3_u32 v2, 0, v2, v4
	ds_read2_b64 v[4:7], v56 offset1:1
	ds_read2_b64 v[8:11], v56 offset0:2 offset1:3
	ds_read2_b64 v[12:15], v2 offset1:1
	ds_read2_b64 v[16:19], v2 offset0:2 offset1:3
	ds_read2_b64 v[20:23], v56 offset0:4 offset1:5
	ds_read2_b64 v[24:27], v56 offset0:6 offset1:7
	ds_read2_b64 v[28:31], v2 offset0:4 offset1:5
	ds_read2_b64 v[32:35], v2 offset0:6 offset1:7
	ds_read2_b64 v[36:39], v56 offset0:8 offset1:9
	ds_read2_b64 v[40:43], v56 offset0:10 offset1:11
	ds_read2_b64 v[44:47], v2 offset0:8 offset1:9
	ds_read2_b64 v[52:55], v2 offset0:10 offset1:11
	ds_read2_b64 v[48:51], v56 offset0:12 offset1:13
	ds_read2_b64 v[56:59], v56 offset0:14 offset1:15
	ds_read2_b64 v[62:65], v2 offset0:12 offset1:13
	ds_read2_b64 v[74:77], v2 offset0:14 offset1:15
	s_waitcnt lgkmcnt(7)
	v_pk_add_f32 v[60:61], v[4:5], v[36:37]
	v_pk_add_f32 v[4:5], v[4:5], v[36:37] neg_lo:[0,1] neg_hi:[0,1]
	v_pk_add_f32 v[36:37], v[6:7], v[38:39]
	v_pk_add_f32 v[6:7], v[6:7], v[38:39] neg_lo:[0,1] neg_hi:[0,1]
	s_waitcnt lgkmcnt(3)
	v_pk_add_f32 v[66:67], v[22:23], v[50:51]
	v_pk_mul_f32 v[38:39], v[6:7], s[24:25]
	v_pk_add_f32 v[22:23], v[22:23], v[50:51] neg_lo:[0,1] neg_hi:[0,1]
	v_pk_fma_f32 v[6:7], v[6:7], s[22:23], v[38:39] op_sel:[0,0,1] op_sel_hi:[1,0,0]
	v_pk_add_f32 v[38:39], v[8:9], v[40:41]
	v_pk_add_f32 v[8:9], v[8:9], v[40:41] neg_lo:[0,1] neg_hi:[0,1]
	v_pk_mul_f32 v[50:51], v[22:23], s[44:45]
	v_pk_mul_f32 v[40:41], v[8:9], s[40:41]
	v_pk_fma_f32 v[22:23], v[22:23], s[50:51], v[50:51] op_sel:[0,0,1] op_sel_hi:[1,0,0] neg_lo:[1,0,0] neg_hi:[1,0,0]
	v_pk_fma_f32 v[8:9], v[8:9], s[38:39], v[40:41] op_sel:[0,0,1] op_sel_hi:[1,0,0]
	v_pk_add_f32 v[40:41], v[10:11], v[42:43]
	v_pk_add_f32 v[10:11], v[10:11], v[42:43] neg_lo:[0,1] neg_hi:[0,1]
	s_waitcnt lgkmcnt(2)
	v_pk_add_f32 v[50:51], v[24:25], v[56:57]
	v_pk_add_f32 v[24:25], v[24:25], v[56:57] neg_lo:[0,1] neg_hi:[0,1]
	v_pk_mul_f32 v[42:43], v[10:11], s[44:45]
	v_pk_mul_f32 v[56:57], v[24:25], s[40:41]
	v_pk_fma_f32 v[10:11], v[10:11], s[50:51], v[42:43] op_sel:[0,0,1] op_sel_hi:[1,0,0]
	v_pk_add_f32 v[42:43], v[20:21], v[48:49]
	v_pk_add_f32 v[48:49], v[20:21], v[48:49] neg_lo:[0,1] neg_hi:[0,1]
	v_pk_fma_f32 v[24:25], v[24:25], s[38:39], v[56:57] op_sel:[0,0,1] op_sel_hi:[1,0,0] neg_lo:[1,0,0] neg_hi:[1,0,0]
	v_pk_add_f32 v[56:57], v[26:27], v[58:59]
	v_pk_add_f32 v[26:27], v[26:27], v[58:59] neg_lo:[0,1] neg_hi:[0,1]
	v_pk_mul_f32 v[58:59], v[26:27], s[24:25]
	v_pk_add_f32 v[68:69], v[40:41], v[56:57]
	v_pk_add_f32 v[40:41], v[40:41], v[56:57] neg_lo:[0,1] neg_hi:[0,1]
	v_pk_fma_f32 v[26:27], v[26:27], s[22:23], v[58:59] op_sel:[0,0,1] op_sel_hi:[1,0,0] neg_lo:[1,0,0] neg_hi:[1,0,0]
	v_pk_mul_f32 v[56:57], v[40:41], s[40:41]
	v_pk_add_f32 v[20:21], v[4:5], v[48:49] op_sel:[0,1] op_sel_hi:[1,0] neg_hi:[0,1]
	v_pk_add_f32 v[4:5], v[4:5], v[48:49] op_sel:[0,1] op_sel_hi:[1,0] neg_lo:[0,1]
	v_pk_add_f32 v[48:49], v[6:7], v[22:23]
	v_pk_add_f32 v[6:7], v[6:7], v[22:23] neg_lo:[0,1] neg_hi:[0,1]
	v_pk_fma_f32 v[40:41], v[40:41], s[38:39], v[56:57] op_sel:[0,0,1] op_sel_hi:[1,0,0] neg_lo:[1,0,0] neg_hi:[1,0,0]
	v_pk_mul_f32 v[22:23], v[6:7], s[40:41]
	v_pk_add_f32 v[56:57], v[10:11], v[26:27]
	v_pk_add_f32 v[10:11], v[10:11], v[26:27] neg_lo:[0,1] neg_hi:[0,1]
	v_pk_add_f32 v[58:59], v[60:61], v[42:43]
	v_pk_add_f32 v[42:43], v[60:61], v[42:43] neg_lo:[0,1] neg_hi:[0,1]
	v_pk_add_f32 v[60:61], v[36:37], v[66:67]
	v_pk_add_f32 v[36:37], v[36:37], v[66:67] neg_lo:[0,1] neg_hi:[0,1]
	v_pk_fma_f32 v[6:7], v[6:7], s[38:39], v[22:23] op_sel:[0,0,1] op_sel_hi:[1,0,0]
	v_pk_add_f32 v[22:23], v[8:9], v[24:25]
	v_pk_add_f32 v[24:25], v[8:9], v[24:25] neg_lo:[0,1] neg_hi:[0,1]
	v_pk_mul_f32 v[26:27], v[10:11], s[40:41]
	v_pk_mul_f32 v[66:67], v[36:37], s[40:41]
	v_pk_fma_f32 v[10:11], v[10:11], s[38:39], v[26:27] op_sel:[0,0,1] op_sel_hi:[1,0,0] neg_lo:[1,0,0] neg_hi:[1,0,0]
	v_pk_fma_f32 v[36:37], v[36:37], s[38:39], v[66:67] op_sel:[0,0,1] op_sel_hi:[1,0,0]
	v_pk_add_f32 v[66:67], v[38:39], v[50:51]
	v_pk_add_f32 v[8:9], v[4:5], v[24:25] op_sel:[0,1] op_sel_hi:[1,0] neg_hi:[0,1]
	v_pk_add_f32 v[4:5], v[4:5], v[24:25] op_sel:[0,1] op_sel_hi:[1,0] neg_lo:[0,1]
	v_pk_add_f32 v[24:25], v[6:7], v[10:11]
	v_pk_add_f32 v[10:11], v[6:7], v[10:11] neg_lo:[0,1] neg_hi:[0,1]
	v_pk_add_f32 v[26:27], v[58:59], v[66:67]
	v_pk_add_f32 v[58:59], v[58:59], v[66:67] neg_lo:[0,1] neg_hi:[0,1]
	v_pk_add_f32 v[66:67], v[60:61], v[68:69]
	v_pk_add_f32 v[68:69], v[60:61], v[68:69] neg_lo:[0,1] neg_hi:[0,1]
	v_pk_add_f32 v[60:61], v[4:5], v[10:11] op_sel:[0,1] op_sel_hi:[1,0] neg_hi:[0,1]
	v_pk_add_f32 v[90:91], v[4:5], v[10:11] op_sel:[0,1] op_sel_hi:[1,0] neg_lo:[0,1]
	v_pk_add_f32 v[10:11], v[14:15], v[46:47] neg_lo:[0,1] neg_hi:[0,1]
	v_pk_add_f32 v[50:51], v[38:39], v[50:51] neg_lo:[0,1] neg_hi:[0,1]
	v_pk_add_f32 v[84:85], v[58:59], v[68:69] op_sel:[0,1] op_sel_hi:[1,0] neg_hi:[0,1]
	v_pk_add_f32 v[86:87], v[58:59], v[68:69] op_sel:[0,1] op_sel_hi:[1,0] neg_lo:[0,1]
	v_pk_add_f32 v[82:83], v[8:9], v[24:25]
	v_pk_add_f32 v[68:69], v[8:9], v[24:25] neg_lo:[0,1] neg_hi:[0,1]
	v_pk_add_f32 v[4:5], v[12:13], v[44:45]
	v_pk_add_f32 v[6:7], v[12:13], v[44:45] neg_lo:[0,1] neg_hi:[0,1]
	v_pk_add_f32 v[8:9], v[14:15], v[46:47]
	v_pk_mul_f32 v[12:13], v[10:11], s[24:25]
	v_pk_add_f32 v[14:15], v[16:17], v[52:53] neg_lo:[0,1] neg_hi:[0,1]
	v_pk_add_f32 v[70:71], v[20:21], v[22:23]
	v_pk_add_f32 v[20:21], v[20:21], v[22:23] neg_lo:[0,1] neg_hi:[0,1]
	v_pk_add_f32 v[22:23], v[48:49], v[56:57]
	v_pk_add_f32 v[48:49], v[48:49], v[56:57] neg_lo:[0,1] neg_hi:[0,1]
	v_pk_fma_f32 v[10:11], v[10:11], s[22:23], v[12:13] op_sel:[0,0,1] op_sel_hi:[1,0,0]
	v_pk_add_f32 v[12:13], v[16:17], v[52:53]
	v_pk_mul_f32 v[16:17], v[14:15], s[40:41]
	v_pk_add_f32 v[38:39], v[42:43], v[50:51] op_sel:[0,1] op_sel_hi:[1,0] neg_hi:[0,1]
	v_pk_add_f32 v[42:43], v[42:43], v[50:51] op_sel:[0,1] op_sel_hi:[1,0] neg_lo:[0,1]
	v_pk_add_f32 v[50:51], v[36:37], v[40:41]
	v_xor_b32_e32 v57, 0x80000000, v48
	v_mov_b32_e32 v56, v49
	v_pk_fma_f32 v[14:15], v[14:15], s[38:39], v[16:17] op_sel:[0,0,1] op_sel_hi:[1,0,0]
	v_pk_add_f32 v[16:17], v[18:19], v[54:55]
	v_pk_add_f32 v[18:19], v[18:19], v[54:55] neg_lo:[0,1] neg_hi:[0,1]
	v_pk_add_f32 v[130:131], v[26:27], v[66:67]
	v_pk_add_f32 v[92:93], v[26:27], v[66:67] neg_lo:[0,1] neg_hi:[0,1]
	v_pk_add_f32 v[88:89], v[38:39], v[50:51]
	v_pk_add_f32 v[72:73], v[38:39], v[50:51] neg_lo:[0,1] neg_hi:[0,1]
	v_pk_add_f32 v[96:97], v[70:71], v[22:23]
	v_pk_add_f32 v[50:51], v[70:71], v[22:23] neg_lo:[0,1] neg_hi:[0,1]
	v_pk_add_f32 v[66:67], v[20:21], v[56:57]
	v_pk_add_f32 v[80:81], v[20:21], v[56:57] neg_lo:[0,1] neg_hi:[0,1]
	v_pk_mul_f32 v[20:21], v[18:19], s[44:45]
	s_waitcnt lgkmcnt(1)
	v_pk_add_f32 v[24:25], v[28:29], v[62:63] neg_lo:[0,1] neg_hi:[0,1]
	v_pk_add_f32 v[26:27], v[30:31], v[64:65] neg_lo:[0,1] neg_hi:[0,1]
	v_pk_fma_f32 v[18:19], v[18:19], s[50:51], v[20:21] op_sel:[0,0,1] op_sel_hi:[1,0,0]
	v_pk_add_f32 v[20:21], v[28:29], v[62:63]
	v_pk_add_f32 v[22:23], v[30:31], v[64:65]
	v_pk_mul_f32 v[28:29], v[26:27], s[44:45]
	s_waitcnt lgkmcnt(0)
	v_pk_add_f32 v[30:31], v[32:33], v[74:75] neg_lo:[0,1] neg_hi:[0,1]
	v_pk_fma_f32 v[26:27], v[26:27], s[50:51], v[28:29] op_sel:[0,0,1] op_sel_hi:[1,0,0] neg_lo:[1,0,0] neg_hi:[1,0,0]
	v_pk_add_f32 v[28:29], v[32:33], v[74:75]
	v_pk_mul_f32 v[32:33], v[30:31], s[40:41]
	v_pk_add_f32 v[36:37], v[36:37], v[40:41] neg_lo:[0,1] neg_hi:[0,1]
	v_pk_fma_f32 v[30:31], v[30:31], s[38:39], v[32:33] op_sel:[0,0,1] op_sel_hi:[1,0,0] neg_lo:[1,0,0] neg_hi:[1,0,0]
	v_pk_add_f32 v[32:33], v[34:35], v[76:77]
	v_pk_add_f32 v[34:35], v[34:35], v[76:77] neg_lo:[0,1] neg_hi:[0,1]
	v_xor_b32_e32 v41, 0x80000000, v36
	v_mov_b32_e32 v40, v37
	v_pk_mul_f32 v[36:37], v[34:35], s[24:25]
	v_mov_b32_e32 v2, v130
	v_pk_fma_f32 v[34:35], v[34:35], s[22:23], v[36:37] op_sel:[0,0,1] op_sel_hi:[1,0,0] neg_lo:[1,0,0] neg_hi:[1,0,0]
	v_pk_add_f32 v[36:37], v[4:5], v[20:21]
	v_pk_add_f32 v[4:5], v[4:5], v[20:21] neg_lo:[0,1] neg_hi:[0,1]
	v_pk_add_f32 v[20:21], v[8:9], v[22:23]
	v_pk_add_f32 v[8:9], v[8:9], v[22:23] neg_lo:[0,1] neg_hi:[0,1]
	v_cmp_ne_u32_e64 s[0:1], 0, v144
	v_pk_mul_f32 v[22:23], v[8:9], s[40:41]
	v_pk_add_f32 v[78:79], v[42:43], v[40:41]
	v_pk_fma_f32 v[8:9], v[8:9], s[38:39], v[22:23] op_sel:[0,0,1] op_sel_hi:[1,0,0]
	v_pk_add_f32 v[22:23], v[12:13], v[28:29]
	v_pk_add_f32 v[28:29], v[12:13], v[28:29] neg_lo:[0,1] neg_hi:[0,1]
	v_pk_add_f32 v[94:95], v[42:43], v[40:41] neg_lo:[0,1] neg_hi:[0,1]
	v_pk_add_f32 v[12:13], v[16:17], v[32:33]
	v_pk_add_f32 v[16:17], v[16:17], v[32:33] neg_lo:[0,1] neg_hi:[0,1]
	s_nop 0
	v_pk_mul_f32 v[32:33], v[16:17], s[40:41]
	s_nop 0
	v_pk_fma_f32 v[16:17], v[16:17], s[38:39], v[32:33] op_sel:[0,0,1] op_sel_hi:[1,0,0] neg_lo:[1,0,0] neg_hi:[1,0,0]
	v_pk_add_f32 v[32:33], v[6:7], v[24:25] op_sel:[0,1] op_sel_hi:[1,0] neg_hi:[0,1]
	v_pk_add_f32 v[6:7], v[6:7], v[24:25] op_sel:[0,1] op_sel_hi:[1,0] neg_lo:[0,1]
	v_pk_add_f32 v[24:25], v[10:11], v[26:27]
	v_pk_add_f32 v[10:11], v[10:11], v[26:27] neg_lo:[0,1] neg_hi:[0,1]
	s_nop 0
	v_pk_mul_f32 v[26:27], v[10:11], s[40:41]
	s_nop 0
	v_pk_fma_f32 v[10:11], v[10:11], s[38:39], v[26:27] op_sel:[0,0,1] op_sel_hi:[1,0,0]
	v_pk_add_f32 v[26:27], v[14:15], v[30:31]
	v_pk_add_f32 v[30:31], v[14:15], v[30:31] neg_lo:[0,1] neg_hi:[0,1]
	s_nop 0
	v_pk_add_f32 v[14:15], v[18:19], v[34:35]
	v_pk_add_f32 v[18:19], v[18:19], v[34:35] neg_lo:[0,1] neg_hi:[0,1]
	s_nop 0
	v_pk_mul_f32 v[34:35], v[18:19], s[40:41]
	s_nop 0
	v_pk_fma_f32 v[18:19], v[18:19], s[38:39], v[34:35] op_sel:[0,0,1] op_sel_hi:[1,0,0] neg_lo:[1,0,0] neg_hi:[1,0,0]
	v_pk_add_f32 v[34:35], v[36:37], v[22:23]
	v_pk_add_f32 v[22:23], v[36:37], v[22:23] neg_lo:[0,1] neg_hi:[0,1]
	v_pk_add_f32 v[36:37], v[20:21], v[12:13]
	v_pk_add_f32 v[12:13], v[20:21], v[12:13] neg_lo:[0,1] neg_hi:[0,1]
	v_pk_add_f32 v[98:99], v[34:35], v[36:37]
	v_xor_b32_e32 v21, 0x80000000, v12
	v_mov_b32_e32 v20, v13
	v_pk_add_f32 v[12:13], v[4:5], v[28:29] op_sel:[0,1] op_sel_hi:[1,0] neg_hi:[0,1]
	v_pk_add_f32 v[4:5], v[4:5], v[28:29] op_sel:[0,1] op_sel_hi:[1,0] neg_lo:[0,1]
	v_pk_add_f32 v[28:29], v[8:9], v[16:17]
	v_pk_add_f32 v[8:9], v[8:9], v[16:17] neg_lo:[0,1] neg_hi:[0,1]
	v_pk_add_f32 v[100:101], v[34:35], v[36:37] neg_lo:[0,1] neg_hi:[0,1]
	v_xor_b32_e32 v17, 0x80000000, v8
	v_mov_b32_e32 v16, v9
	v_pk_add_f32 v[8:9], v[32:33], v[26:27]
	v_pk_add_f32 v[26:27], v[32:33], v[26:27] neg_lo:[0,1] neg_hi:[0,1]
	v_pk_add_f32 v[32:33], v[24:25], v[14:15]
	v_pk_add_f32 v[14:15], v[24:25], v[14:15] neg_lo:[0,1] neg_hi:[0,1]
	v_pk_add_f32 v[102:103], v[22:23], v[20:21]
	v_xor_b32_e32 v25, 0x80000000, v14
	v_mov_b32_e32 v24, v15
	v_pk_add_f32 v[14:15], v[6:7], v[30:31] op_sel:[0,1] op_sel_hi:[1,0] neg_hi:[0,1]
	v_pk_add_f32 v[6:7], v[6:7], v[30:31] op_sel:[0,1] op_sel_hi:[1,0] neg_lo:[0,1]
	v_pk_add_f32 v[30:31], v[10:11], v[18:19]
	v_pk_add_f32 v[10:11], v[10:11], v[18:19] neg_lo:[0,1] neg_hi:[0,1]
	v_pk_add_f32 v[104:105], v[22:23], v[20:21] neg_lo:[0,1] neg_hi:[0,1]
	v_xor_b32_e32 v19, 0x80000000, v10
	v_mov_b32_e32 v18, v11
	v_pk_add_f32 v[106:107], v[12:13], v[28:29]
	v_pk_add_f32 v[108:109], v[12:13], v[28:29] neg_lo:[0,1] neg_hi:[0,1]
	v_pk_add_f32 v[110:111], v[4:5], v[16:17]
	v_pk_add_f32 v[112:113], v[4:5], v[16:17] neg_lo:[0,1] neg_hi:[0,1]
	v_pk_add_f32 v[114:115], v[8:9], v[32:33]
	v_pk_add_f32 v[116:117], v[8:9], v[32:33] neg_lo:[0,1] neg_hi:[0,1]
	v_pk_add_f32 v[118:119], v[26:27], v[24:25]
	v_pk_add_f32 v[120:121], v[26:27], v[24:25] neg_lo:[0,1] neg_hi:[0,1]
	v_pk_add_f32 v[122:123], v[14:15], v[30:31]
	v_pk_add_f32 v[124:125], v[14:15], v[30:31] neg_lo:[0,1] neg_hi:[0,1]
	v_pk_add_f32 v[126:127], v[6:7], v[18:19]
	v_pk_add_f32 v[128:129], v[6:7], v[18:19] neg_lo:[0,1] neg_hi:[0,1]
	v_mov_b32_e32 v4, v131
	v_mov_b32_e32 v5, v3
	v_mov_b64_e32 v[6:7], v[2:3]
	s_and_saveexec_b64 s[50:51], s[0:1]
	s_xor_b64 s[0:1], exec, s[50:51]
	s_cbranch_execz .LBB0_576
	v_pk_add_f32 v[4:5], v[96:97], v[112:113]
	v_pk_add_f32 v[24:25], v[96:97], v[112:113] neg_lo:[0,1] neg_hi:[0,1]
	v_pk_add_f32 v[148:149], v[130:131], v[128:129]
	v_pk_add_f32 v[8:9], v[130:131], v[128:129] neg_lo:[0,1] neg_hi:[0,1]
	v_pk_add_f32 v[128:129], v[126:127], v[92:93]
	v_pk_add_f32 v[10:11], v[126:127], v[92:93] neg_lo:[0,1] neg_hi:[0,1]
	v_pk_add_f32 v[92:93], v[84:85], v[124:125]
	v_pk_add_f32 v[12:13], v[84:85], v[124:125] neg_lo:[0,1] neg_hi:[0,1]
	v_pk_add_f32 v[84:85], v[122:123], v[86:87]
	v_pk_add_f32 v[14:15], v[122:123], v[86:87] neg_lo:[0,1] neg_hi:[0,1]
	v_pk_add_f32 v[86:87], v[88:89], v[120:121]
	v_pk_add_f32 v[16:17], v[88:89], v[120:121] neg_lo:[0,1] neg_hi:[0,1]
	v_pk_add_f32 v[88:89], v[118:119], v[72:73]
	v_pk_add_f32 v[18:19], v[118:119], v[72:73] neg_lo:[0,1] neg_hi:[0,1]
	v_pk_add_f32 v[72:73], v[78:79], v[116:117]
	v_pk_add_f32 v[20:21], v[78:79], v[116:117] neg_lo:[0,1] neg_hi:[0,1]
	v_pk_add_f32 v[78:79], v[114:115], v[94:95]
	v_pk_add_f32 v[22:23], v[114:115], v[94:95] neg_lo:[0,1] neg_hi:[0,1]
	v_mov_b32_e32 v6, v4
	v_mov_b32_e32 v7, v25
	v_pk_mov_b32 v[4:5], v[4:5], v[24:25] op_sel:[1,0]
	v_pk_add_f32 v[94:95], v[110:111], v[50:51]
	v_pk_add_f32 v[24:25], v[110:111], v[50:51] neg_lo:[0,1] neg_hi:[0,1]
	v_pk_add_f32 v[50:51], v[66:67], v[108:109]
	v_pk_add_f32 v[26:27], v[66:67], v[108:109] neg_lo:[0,1] neg_hi:[0,1]
	v_pk_add_f32 v[66:67], v[106:107], v[80:81]
	v_pk_add_f32 v[28:29], v[106:107], v[80:81] neg_lo:[0,1] neg_hi:[0,1]
	v_pk_add_f32 v[80:81], v[82:83], v[104:105]
	v_pk_add_f32 v[30:31], v[82:83], v[104:105] neg_lo:[0,1] neg_hi:[0,1]
	v_pk_add_f32 v[82:83], v[102:103], v[68:69]
	v_pk_add_f32 v[32:33], v[102:103], v[68:69] neg_lo:[0,1] neg_hi:[0,1]
	v_pk_add_f32 v[68:69], v[60:61], v[100:101]
	v_pk_add_f32 v[34:35], v[60:61], v[100:101] neg_lo:[0,1] neg_hi:[0,1]
	v_pk_add_f32 v[60:61], v[98:99], v[90:91]
	v_pk_add_f32 v[36:37], v[98:99], v[90:91] neg_lo:[0,1] neg_hi:[0,1]
	v_pk_mul_f32 v[6:7], v[6:7], 0.5 op_sel_hi:[1,0]
	v_pk_mul_f32 v[4:5], v[4:5], s[46:47]
	v_mov_b32_e32 v39, v8
	v_mov_b32_e32 v38, v149
	v_mov_b32_e32 v41, v10
	v_mov_b32_e32 v40, v129
	v_mov_b32_e32 v43, v12
	v_mov_b32_e32 v42, v93
	v_mov_b32_e32 v45, v14
	v_mov_b32_e32 v44, v85
	v_mov_b32_e32 v47, v16
	v_mov_b32_e32 v46, v87
	v_mov_b32_e32 v49, v18
	v_mov_b32_e32 v48, v89
	v_mov_b32_e32 v53, v20
	v_mov_b32_e32 v52, v73
	v_mov_b32_e32 v55, v22
	v_mov_b32_e32 v54, v79
	v_mov_b32_e32 v57, v24
	v_mov_b32_e32 v56, v95
	v_mov_b32_e32 v59, v26
	v_mov_b32_e32 v58, v51
	v_mov_b32_e32 v63, v28
	v_mov_b32_e32 v62, v67
	v_mov_b32_e32 v65, v30
	v_mov_b32_e32 v64, v81
	v_mov_b32_e32 v71, v32
	v_mov_b32_e32 v70, v83
	v_mov_b32_e32 v75, v34
	v_mov_b32_e32 v74, v69
	v_mov_b32_e32 v77, v36
	v_mov_b32_e32 v76, v61
	v_mov_b32_e32 v8, v148
	v_mov_b32_e32 v10, v128
	v_mov_b32_e32 v12, v92
	v_mov_b32_e32 v14, v84
	v_mov_b32_e32 v16, v86
	v_mov_b32_e32 v18, v88
	v_mov_b32_e32 v20, v72
	v_mov_b32_e32 v22, v78
	v_mov_b32_e32 v24, v94
	v_mov_b32_e32 v26, v50
	v_mov_b32_e32 v28, v66
	v_mov_b32_e32 v30, v80
	v_mov_b32_e32 v32, v82
	v_mov_b32_e32 v34, v68
	v_mov_b32_e32 v36, v60
